# v70 + every packed f32 VALU op (v_pk_mul/add/fma_f32) replaced by its scalar pair (instruction selection)
# baseline (speedup 1.0000x reference)
; DI void conv_item(int lane, LAS unsigned char* wl, const float* src, const float* src2, const float* gain, bf16_t* dst, int ld, int K, int mode, int coff, int item) {
;     ...
;         if (gain) {
; #pragma unroll
;             for (int j = 0; j < 64; ++j) v[j] *= gain[k0 + kb + j];
;         }
.LBB0_221:
	global_load_dwordx4 v[232:235], v9, s[76:77] offset:48
	global_load_dwordx4 v[236:239], v9, s[76:77] offset:32
	global_load_dwordx4 v[240:243], v9, s[76:77] offset:16
	global_load_dwordx4 v[244:247], v9, s[76:77]
	s_waitcnt vmcnt(3)
	v_mul_f32_e32 v168, v168, v232
	v_mul_f32_e32 v169, v169, v233
	s_waitcnt vmcnt(2)
	v_mul_f32_e32 v164, v164, v236
	v_mul_f32_e32 v165, v165, v237
	s_waitcnt vmcnt(1)
	v_mul_f32_e32 v160, v160, v240
	v_mul_f32_e32 v161, v161, v241
	s_waitcnt vmcnt(0)
	v_mul_f32_e32 v156, v156, v244
	v_mul_f32_e32 v157, v157, v245
	v_mul_f32_e32 v158, v158, v246
	v_mul_f32_e32 v159, v159, v247
	v_mul_f32_e32 v162, v162, v242
	v_mul_f32_e32 v163, v163, v243
	v_mul_f32_e32 v166, v166, v238
	v_mul_f32_e32 v167, v167, v239
	v_mul_f32_e32 v170, v170, v234
	v_mul_f32_e32 v171, v171, v235
	global_load_dwordx4 v[232:235], v9, s[76:77] offset:112
	global_load_dwordx4 v[236:239], v9, s[76:77] offset:96
	global_load_dwordx4 v[240:243], v9, s[76:77] offset:80
	global_load_dwordx4 v[244:247], v9, s[76:77] offset:64
	s_waitcnt vmcnt(3)
	v_mul_f32_e32 v184, v184, v232
	v_mul_f32_e32 v185, v185, v233
	s_waitcnt vmcnt(2)
	v_mul_f32_e32 v180, v180, v236
	v_mul_f32_e32 v181, v181, v237
	s_waitcnt vmcnt(1)
	v_mul_f32_e32 v176, v176, v240
	v_mul_f32_e32 v177, v177, v241
	s_waitcnt vmcnt(0)
	v_mul_f32_e32 v172, v172, v244
	v_mul_f32_e32 v173, v173, v245
	v_mul_f32_e32 v174, v174, v246
	v_mul_f32_e32 v175, v175, v247
	v_mul_f32_e32 v178, v178, v242
	v_mul_f32_e32 v179, v179, v243
	v_mul_f32_e32 v182, v182, v238
	v_mul_f32_e32 v183, v183, v239
	v_mul_f32_e32 v186, v186, v234
	v_mul_f32_e32 v187, v187, v235
	global_load_dwordx4 v[232:235], v9, s[76:77] offset:176
	global_load_dwordx4 v[236:239], v9, s[76:77] offset:160
	global_load_dwordx4 v[240:243], v9, s[76:77] offset:144
	global_load_dwordx4 v[244:247], v9, s[76:77] offset:128
	s_waitcnt vmcnt(3)
	v_mul_f32_e32 v200, v200, v232
	v_mul_f32_e32 v201, v201, v233
	s_waitcnt vmcnt(2)
	v_mul_f32_e32 v196, v196, v236
	v_mul_f32_e32 v197, v197, v237
	s_waitcnt vmcnt(1)
	v_mul_f32_e32 v192, v192, v240
	v_mul_f32_e32 v193, v193, v241
	s_waitcnt vmcnt(0)
	v_mul_f32_e32 v188, v188, v244
	v_mul_f32_e32 v189, v189, v245
	v_mul_f32_e32 v190, v190, v246
	v_mul_f32_e32 v191, v191, v247
	v_mul_f32_e32 v194, v194, v242
	v_mul_f32_e32 v195, v195, v243
	v_mul_f32_e32 v198, v198, v238
	v_mul_f32_e32 v199, v199, v239
	v_mul_f32_e32 v202, v202, v234
	v_mul_f32_e32 v203, v203, v235
	global_load_dwordx4 v[232:235], v9, s[76:77] offset:240
	global_load_dwordx4 v[236:239], v9, s[76:77] offset:224
	global_load_dwordx4 v[240:243], v9, s[76:77] offset:208
	global_load_dwordx4 v[244:247], v9, s[76:77] offset:192
	s_waitcnt vmcnt(3)
	v_mul_f32_e32 v216, v216, v232
	v_mul_f32_e32 v217, v217, v233
	s_waitcnt vmcnt(2)
	v_mul_f32_e32 v212, v212, v236
	v_mul_f32_e32 v213, v213, v237
	s_waitcnt vmcnt(1)
	v_mul_f32_e32 v208, v208, v240
	v_mul_f32_e32 v209, v209, v241
	s_waitcnt vmcnt(0)
	v_mul_f32_e32 v204, v204, v244
	v_mul_f32_e32 v205, v205, v245
	v_mul_f32_e32 v206, v206, v246
	v_mul_f32_e32 v207, v207, v247
	v_mul_f32_e32 v210, v210, v242
	v_mul_f32_e32 v211, v211, v243
	v_mul_f32_e32 v214, v214, v238
	v_mul_f32_e32 v215, v215, v239
	v_mul_f32_e32 v218, v218, v234
	v_mul_f32_e32 v219, v219, v235
	s_branch .LBB0_91

; #define PG8_STAGE(bufoff, gbase, voff) do { _Pragma("unroll") for (int _i = 0; _i < 2; ++_i) \
;         __builtin_amdgcn_global_load_lds((const unsigned*)((const char*)(gbase) + (voff)[_i]), (LAS unsigned*)(lds + (bufoff) + ldsw + _i * 8192), 16, 0, 0); } while (0)
; #define PG8_LDA(dst, b, h) do { _Pragma("unroll") for (int m = 0; m < 4; ++m) _Pragma("unroll") for (int k = 0; k < 2; ++k) dst[m][k] = *(const LAS bf16x8*)(lds + PG8_SA(b, h) + aoff + m * 2048 + k * 1024); } while (0)
; #define PG8_LDB(dst, b, h) do { _Pragma("unroll") for (int n = 0; n < 2; ++n) _Pragma("unroll") for (int k = 0; k < 2; ++k) dst[n][k] = *(const LAS bf16x8*)(lds + PG8_SB(b, h) + boff + n * 2048 + k * 1024); } while (0)
; #define PG8_MMA(ai, bj, At, Bt) do { __builtin_amdgcn_s_setprio(1); _Pragma("unroll") for (int m = 0; m < 4; ++m) _Pragma("unroll") for (int n = 0; n < 2; ++n) _Pragma("unroll") for (int k = 0; k < 2; ++k) \
;         acc[ai][bj][m][n] = __builtin_amdgcn_mfma_f32_16x16x32_bf16(Bt[n][k], At[m][k], acc[ai][bj][m][n], 0, 0, 0); __builtin_amdgcn_s_setprio(0); } while (0)
; #define PG8_WAIT_V(n) asm volatile("s_waitcnt vmcnt(" #n ")" ::: "memory")
; #define PG8_WAIT_L(n) asm volatile("s_waitcnt lgkmcnt(" #n ")" ::: "memory")
; #define PG8_BAR __builtin_amdgcn_s_barrier()
; #define PG8_SCHED __builtin_amdgcn_sched_barrier(0)
; template <class Epi>
; DI void gemm_phase(LAS unsigned char* lds, int wid, int K, int lda, int ldb, bool bperm, const Sched3& S, const Epi& E) {
;     ...
;             PG8_LDB(B0, 0, 0); PG8_SCHED; PG8_LDA(At, 0, 0); PG8_STAGE(PG8_SA(1, 1), a1 + hA, voffA);
;             PG8_WAIT_L(8); PG8_BAR; PG8_WAIT_L(0); PG8_MMA(0, 0, At, B0); PG8_BAR; PG8_SCHED;
;             PG8_LDB(B1, 0, 1); PG8_STAGE(PG8_SB(0, 0), b2, voffB);
;             PG8_BAR; PG8_WAIT_L(0); PG8_MMA(0, 1, At, B1); PG8_BAR;
;             PG8_LDA(At, 0, 1); PG8_STAGE(PG8_SA(0, 0), a2, voffA);
;             PG8_BAR; PG8_WAIT_L(0); if (full) PG8_MMA(1, 0, At, B0); PG8_BAR; PG8_SCHED;
;             PG8_STAGE(PG8_SB(0, 1), b2 + hstepB, voffB);
;             PG8_WAIT_V(6); PG8_BAR; if (full) PG8_MMA(1, 1, At, B1); PG8_BAR;
.LBB0_327:
	s_waitcnt lgkmcnt(0)
	ds_read_b128 v[128:131], v230
	ds_read_b128 v[132:135], v230 offset:1024
	ds_read_b128 v[136:139], v230 offset:2048
	ds_read_b128 v[156:159], v230 offset:3072
	s_add_u32 s48, s46, 0xfff80080
	s_addc_u32 s49, s47, -1
	s_cmp_eq_u32 s55, 28
	s_cselect_b32 s51, s5, s49
	s_cselect_b32 s50, s37, s48
	s_cselect_b32 s49, s39, s54
	s_cselect_b32 s48, s52, s53
	v_lshl_add_u64 v[192:193], s[46:47], 0, v[148:149]
	s_add_i32 m0, s58, 0xc000
	ds_read_b128 v[160:163], v231
	ds_read_b128 v[164:167], v231 offset:1024
	ds_read_b128 v[168:171], v231 offset:2048
	ds_read_b128 v[172:175], v231 offset:3072
	ds_read_b128 v[176:179], v231 offset:4096
	ds_read_b128 v[180:183], v231 offset:5120
	ds_read_b128 v[184:187], v231 offset:6144
	ds_read_b128 v[188:191], v231 offset:7168
	global_load_lds_dwordx4 v[192:193], off
	v_lshl_add_u64 v[192:193], s[46:47], 0, v[150:151]
	s_add_i32 m0, s58, 0xe000
	s_nop 0
	global_load_lds_dwordx4 v[192:193], off
	s_waitcnt lgkmcnt(8)
	s_barrier
	s_waitcnt lgkmcnt(0)
	s_setprio 1
	s_waitcnt lgkmcnt(0)
	v_mfma_f32_16x16x32_bf16 v[124:127], v[128:131], v[160:163], v[124:127]
	v_mfma_f32_16x16x32_bf16 v[120:123], v[136:139], v[160:163], v[120:123]
	v_mfma_f32_16x16x32_bf16 v[108:111], v[128:131], v[168:171], v[108:111]
	v_mfma_f32_16x16x32_bf16 v[104:107], v[136:139], v[168:171], v[104:107]
	v_mfma_f32_16x16x32_bf16 v[92:95], v[128:131], v[176:179], v[92:95]
	v_mfma_f32_16x16x32_bf16 v[88:91], v[136:139], v[176:179], v[88:91]
	v_mfma_f32_16x16x32_bf16 v[76:79], v[128:131], v[184:187], v[76:79]
	v_mfma_f32_16x16x32_bf16 v[72:75], v[136:139], v[184:187], v[72:75]
	v_mfma_f32_16x16x32_bf16 v[124:127], v[132:135], v[164:167], v[124:127]
	v_mfma_f32_16x16x32_bf16 v[120:123], v[156:159], v[164:167], v[120:123]
	v_mfma_f32_16x16x32_bf16 v[108:111], v[132:135], v[172:175], v[108:111]
	v_mfma_f32_16x16x32_bf16 v[104:107], v[156:159], v[172:175], v[104:107]
	v_mfma_f32_16x16x32_bf16 v[92:95], v[132:135], v[180:183], v[92:95]
	v_mfma_f32_16x16x32_bf16 v[88:91], v[156:159], v[180:183], v[88:91]
	v_mfma_f32_16x16x32_bf16 v[76:79], v[132:135], v[188:191], v[76:79]
	v_mfma_f32_16x16x32_bf16 v[72:75], v[156:159], v[188:191], v[72:75]
	s_setprio 0
	s_barrier
	s_add_i32 s75, s67, s57
	v_lshl_add_u64 v[208:209], s[48:49], 0, v[142:143]
	s_mov_b32 m0, s75
	ds_read_b128 v[192:195], v232
	ds_read_b128 v[196:199], v232 offset:1024
	ds_read_b128 v[200:203], v232 offset:2048
	ds_read_b128 v[204:207], v232 offset:3072
	global_load_lds_dwordx4 v[208:209], off
	v_lshl_add_u64 v[210:211], s[48:49], 0, v[146:147]
	s_add_i32 m0, s75, 0x2000
	s_nop 0
	global_load_lds_dwordx4 v[210:211], off
	s_barrier
	s_waitcnt lgkmcnt(0)
	s_setprio 1
	s_waitcnt lgkmcnt(0)
	v_mfma_f32_16x16x32_bf16 v[116:119], v[192:195], v[160:163], v[116:119]
	v_mfma_f32_16x16x32_bf16 v[112:115], v[200:203], v[160:163], v[112:115]
	v_mfma_f32_16x16x32_bf16 v[100:103], v[192:195], v[168:171], v[100:103]
	v_mfma_f32_16x16x32_bf16 v[96:99], v[200:203], v[168:171], v[96:99]
	v_mfma_f32_16x16x32_bf16 v[84:87], v[192:195], v[176:179], v[84:87]
	v_mfma_f32_16x16x32_bf16 v[80:83], v[200:203], v[176:179], v[80:83]
	v_mfma_f32_16x16x32_bf16 v[68:71], v[192:195], v[184:187], v[68:71]
	v_mfma_f32_16x16x32_bf16 v[64:67], v[200:203], v[184:187], v[64:67]
	v_mfma_f32_16x16x32_bf16 v[116:119], v[196:199], v[164:167], v[116:119]
	v_mfma_f32_16x16x32_bf16 v[112:115], v[204:207], v[164:167], v[112:115]
	v_mfma_f32_16x16x32_bf16 v[100:103], v[196:199], v[172:175], v[100:103]
	v_mfma_f32_16x16x32_bf16 v[96:99], v[204:207], v[172:175], v[96:99]
	v_mfma_f32_16x16x32_bf16 v[84:87], v[196:199], v[180:183], v[84:87]
	v_mfma_f32_16x16x32_bf16 v[80:83], v[204:207], v[180:183], v[80:83]
	v_mfma_f32_16x16x32_bf16 v[68:71], v[196:199], v[188:191], v[68:71]
	v_mfma_f32_16x16x32_bf16 v[64:67], v[204:207], v[188:191], v[64:67]
	s_setprio 0
	s_mov_b32 m0, s58
	v_lshl_add_u64 v[212:213], s[50:51], 0, v[140:141]
	s_barrier
	ds_read_b128 v[160:163], v231 offset:16384
	ds_read_b128 v[164:167], v231 offset:17408
	ds_read_b128 v[168:171], v231 offset:18432
	ds_read_b128 v[172:175], v231 offset:19456
	ds_read_b128 v[176:179], v231 offset:20480
	ds_read_b128 v[180:183], v231 offset:21504
	ds_read_b128 v[184:187], v231 offset:22528
	ds_read_b128 v[188:191], v231 offset:23552
	global_load_lds_dwordx4 v[212:213], off
	v_lshl_add_u64 v[214:215], s[50:51], 0, v[144:145]
	s_mov_b32 m0, s59
	s_nop 0
	global_load_lds_dwordx4 v[214:215], off
	s_barrier
	s_waitcnt lgkmcnt(0)
	s_setprio 1
	s_waitcnt lgkmcnt(0)
	v_mfma_f32_16x16x32_bf16 v[60:63], v[128:131], v[160:163], v[60:63]
	v_mfma_f32_16x16x32_bf16 v[56:59], v[136:139], v[160:163], v[56:59]
	v_mfma_f32_16x16x32_bf16 v[44:47], v[128:131], v[168:171], v[44:47]
	v_mfma_f32_16x16x32_bf16 v[40:43], v[136:139], v[168:171], v[40:43]
	v_mfma_f32_16x16x32_bf16 v[28:31], v[128:131], v[176:179], v[28:31]
	v_mfma_f32_16x16x32_bf16 v[24:27], v[136:139], v[176:179], v[24:27]
	v_mfma_f32_16x16x32_bf16 v[12:15], v[128:131], v[184:187], v[12:15]
	v_mfma_f32_16x16x32_bf16 v[8:11], v[136:139], v[184:187], v[8:11]
	v_mfma_f32_16x16x32_bf16 v[60:63], v[132:135], v[164:167], v[60:63]
	v_mfma_f32_16x16x32_bf16 v[56:59], v[156:159], v[164:167], v[56:59]
	v_mfma_f32_16x16x32_bf16 v[44:47], v[132:135], v[172:175], v[44:47]
	v_mfma_f32_16x16x32_bf16 v[40:43], v[156:159], v[172:175], v[40:43]
	v_mfma_f32_16x16x32_bf16 v[28:31], v[132:135], v[180:183], v[28:31]
	v_mfma_f32_16x16x32_bf16 v[24:27], v[156:159], v[180:183], v[24:27]
	v_mfma_f32_16x16x32_bf16 v[12:15], v[132:135], v[188:191], v[12:15]
	v_mfma_f32_16x16x32_bf16 v[8:11], v[156:159], v[188:191], v[8:11]
	s_setprio 0
	s_barrier
; #define PG8_STAGE(bufoff, gbase, voff) do { _Pragma("unroll") for (int _i = 0; _i < 2; ++_i) \
;         __builtin_amdgcn_global_load_lds((const unsigned*)((const char*)(gbase) + (voff)[_i]), (LAS unsigned*)(lds + (bufoff) + ldsw + _i * 8192), 16, 0, 0); } while (0)
; #define PG8_LDA(dst, b, h) do { _Pragma("unroll") for (int m = 0; m < 4; ++m) _Pragma("unroll") for (int k = 0; k < 2; ++k) dst[m][k] = *(const LAS bf16x8*)(lds + PG8_SA(b, h) + aoff + m * 2048 + k * 1024); } while (0)
; #define PG8_LDB(dst, b, h) do { _Pragma("unroll") for (int n = 0; n < 2; ++n) _Pragma("unroll") for (int k = 0; k < 2; ++k) dst[n][k] = *(const LAS bf16x8*)(lds + PG8_SB(b, h) + boff + n * 2048 + k * 1024); } while (0)
; #define PG8_MMA(ai, bj, At, Bt) do { __builtin_amdgcn_s_setprio(1); _Pragma("unroll") for (int m = 0; m < 4; ++m) _Pragma("unroll") for (int n = 0; n < 2; ++n) _Pragma("unroll") for (int k = 0; k < 2; ++k) \
;         acc[ai][bj][m][n] = __builtin_amdgcn_mfma_f32_16x16x32_bf16(Bt[n][k], At[m][k], acc[ai][bj][m][n], 0, 0, 0); __builtin_amdgcn_s_setprio(0); } while (0)
; #define PG8_WAIT_V(n) asm volatile("s_waitcnt vmcnt(" #n ")" ::: "memory")
; #define PG8_WAIT_L(n) asm volatile("s_waitcnt lgkmcnt(" #n ")" ::: "memory")
; #define PG8_BAR __builtin_amdgcn_s_barrier()
; #define PG8_SCHED __builtin_amdgcn_sched_barrier(0)
; template <class Epi>
; DI void gemm_phase(LAS unsigned char* lds, int wid, int K, int lda, int ldb, bool bperm, const Sched3& S, const Epi& E) {
;     ...
;             PG8_STAGE(PG8_SB(0, 1), b2 + hstepB, voffB);
;             PG8_WAIT_V(6); PG8_BAR; if (full) PG8_MMA(1, 1, At, B1); PG8_BAR;
;             PG8_LDB(B0, 1, 0); PG8_SCHED; PG8_LDA(At, 1, 0); PG8_STAGE(PG8_SA(0, 1), a2 + h2, voffA);
;             PG8_WAIT_L(8); PG8_BAR; PG8_WAIT_L(0); PG8_MMA(0, 0, At, B0); PG8_BAR; PG8_SCHED;
;             PG8_LDB(B1, 1, 1); PG8_STAGE(PG8_SB(1, 0), b3, voffB);
;             PG8_BAR; PG8_WAIT_L(0); PG8_MMA(0, 1, At, B1); PG8_BAR;
;             PG8_LDA(At, 1, 1); PG8_STAGE(PG8_SA(1, 0), a3, voffA);
;             PG8_BAR; PG8_WAIT_L(0); if (full) PG8_MMA(1, 0, At, B0); PG8_BAR; PG8_SCHED;
;             PG8_STAGE(PG8_SB(1, 1), b3 + hstepB, voffB);
	s_add_u32 s76, s48, 0x80000
	s_addc_u32 s77, s49, 0
	s_add_i32 s75, s68, s57
	v_lshl_add_u64 v[128:129], s[76:77], 0, v[142:143]
	s_mov_b32 m0, s75
	s_nop 0
	global_load_lds_dwordx4 v[128:129], off
	v_lshl_add_u64 v[128:129], s[76:77], 0, v[146:147]
	s_add_i32 m0, s75, 0x2000
	s_nop 0
	global_load_lds_dwordx4 v[128:129], off
	s_waitcnt vmcnt(6)
	s_barrier
	s_setprio 1
	v_mfma_f32_16x16x32_bf16 v[52:55], v[192:195], v[160:163], v[52:55]
	v_mfma_f32_16x16x32_bf16 v[48:51], v[200:203], v[160:163], v[48:51]
	v_mfma_f32_16x16x32_bf16 v[36:39], v[192:195], v[168:171], v[36:39]
	v_mfma_f32_16x16x32_bf16 v[32:35], v[200:203], v[168:171], v[32:35]
	v_mfma_f32_16x16x32_bf16 v[20:23], v[192:195], v[176:179], v[20:23]
	v_mfma_f32_16x16x32_bf16 v[16:19], v[200:203], v[176:179], v[16:19]
	v_mfma_f32_16x16x32_bf16 v[4:7], v[192:195], v[184:187], v[4:7]
	v_mfma_f32_16x16x32_bf16 v[0:3], v[200:203], v[184:187], v[0:3]
	v_mfma_f32_16x16x32_bf16 v[52:55], v[196:199], v[164:167], v[52:55]
	v_mfma_f32_16x16x32_bf16 v[48:51], v[204:207], v[164:167], v[48:51]
	v_mfma_f32_16x16x32_bf16 v[36:39], v[196:199], v[172:175], v[36:39]
	v_mfma_f32_16x16x32_bf16 v[32:35], v[204:207], v[172:175], v[32:35]
	v_mfma_f32_16x16x32_bf16 v[20:23], v[196:199], v[180:183], v[20:23]
	v_mfma_f32_16x16x32_bf16 v[16:19], v[204:207], v[180:183], v[16:19]
	v_mfma_f32_16x16x32_bf16 v[4:7], v[196:199], v[188:191], v[4:7]
	v_mfma_f32_16x16x32_bf16 v[0:3], v[204:207], v[188:191], v[0:3]
	s_setprio 0
	s_add_i32 s75, 0, 0x18000
	v_add_u32_e32 v156, s75, v224
	s_barrier
	ds_read_b128 v[128:131], v156
	ds_read_b128 v[132:135], v156 offset:1024
	ds_read_b128 v[136:139], v156 offset:2048
	ds_read_b128 v[156:159], v156 offset:3072
	s_add_u32 s50, s50, 0x80000
	s_addc_u32 s51, s51, 0
	s_mov_b32 m0, s60
	v_lshl_add_u64 v[192:193], s[50:51], 0, v[140:141]
	ds_read_b128 v[160:163], v231 offset:32768
	ds_read_b128 v[164:167], v231 offset:33792
	ds_read_b128 v[168:171], v231 offset:34816
	ds_read_b128 v[172:175], v231 offset:35840
	ds_read_b128 v[176:179], v231 offset:36864
	ds_read_b128 v[180:183], v231 offset:37888
	ds_read_b128 v[184:187], v231 offset:38912
	ds_read_b128 v[188:191], v231 offset:39936
	global_load_lds_dwordx4 v[192:193], off
	v_lshl_add_u64 v[192:193], s[50:51], 0, v[144:145]
	s_mov_b32 m0, s61
	s_nop 0
	global_load_lds_dwordx4 v[192:193], off
	s_waitcnt lgkmcnt(8)
	s_barrier
	s_waitcnt lgkmcnt(0)
	s_setprio 1
	s_waitcnt lgkmcnt(0)
	v_mfma_f32_16x16x32_bf16 v[124:127], v[128:131], v[160:163], v[124:127]
	v_mfma_f32_16x16x32_bf16 v[120:123], v[136:139], v[160:163], v[120:123]
	v_mfma_f32_16x16x32_bf16 v[108:111], v[128:131], v[168:171], v[108:111]
	v_mfma_f32_16x16x32_bf16 v[104:107], v[136:139], v[168:171], v[104:107]
	v_mfma_f32_16x16x32_bf16 v[92:95], v[128:131], v[176:179], v[92:95]
	v_mfma_f32_16x16x32_bf16 v[88:91], v[136:139], v[176:179], v[88:91]
	v_mfma_f32_16x16x32_bf16 v[76:79], v[128:131], v[184:187], v[76:79]
	v_mfma_f32_16x16x32_bf16 v[72:75], v[136:139], v[184:187], v[72:75]
	v_mfma_f32_16x16x32_bf16 v[124:127], v[132:135], v[164:167], v[124:127]
	v_mfma_f32_16x16x32_bf16 v[120:123], v[156:159], v[164:167], v[120:123]
	v_mfma_f32_16x16x32_bf16 v[108:111], v[132:135], v[172:175], v[108:111]
	v_mfma_f32_16x16x32_bf16 v[104:107], v[156:159], v[172:175], v[104:107]
	v_mfma_f32_16x16x32_bf16 v[92:95], v[132:135], v[180:183], v[92:95]
	v_mfma_f32_16x16x32_bf16 v[88:91], v[156:159], v[180:183], v[88:91]
	v_mfma_f32_16x16x32_bf16 v[76:79], v[132:135], v[188:191], v[76:79]
	v_mfma_f32_16x16x32_bf16 v[72:75], v[156:159], v[188:191], v[72:75]
	s_setprio 0
	s_barrier
	s_add_i32 s50, 0, 0x1c000
	s_add_i32 s51, s75, s57
	v_add_u32_e32 v204, s50, v224
	v_lshl_add_u64 v[208:209], v[208:209], 0, s[14:15]
	s_mov_b32 m0, s51
	ds_read_b128 v[192:195], v204
	ds_read_b128 v[196:199], v204 offset:1024
	ds_read_b128 v[200:203], v204 offset:2048
	ds_read_b128 v[204:207], v204 offset:3072
	global_load_lds_dwordx4 v[208:209], off
	v_lshl_add_u64 v[208:209], v[210:211], 0, s[14:15]
	s_add_i32 m0, s51, 0x2000
	s_nop 0
	global_load_lds_dwordx4 v[208:209], off
	s_barrier
	s_waitcnt lgkmcnt(0)
	s_setprio 1
	s_waitcnt lgkmcnt(0)
	v_mfma_f32_16x16x32_bf16 v[116:119], v[192:195], v[160:163], v[116:119]
	v_mfma_f32_16x16x32_bf16 v[112:115], v[200:203], v[160:163], v[112:115]
	v_mfma_f32_16x16x32_bf16 v[100:103], v[192:195], v[168:171], v[100:103]
	v_mfma_f32_16x16x32_bf16 v[96:99], v[200:203], v[168:171], v[96:99]
	v_mfma_f32_16x16x32_bf16 v[84:87], v[192:195], v[176:179], v[84:87]
	v_mfma_f32_16x16x32_bf16 v[80:83], v[200:203], v[176:179], v[80:83]
	v_mfma_f32_16x16x32_bf16 v[68:71], v[192:195], v[184:187], v[68:71]
	v_mfma_f32_16x16x32_bf16 v[64:67], v[200:203], v[184:187], v[64:67]
	v_mfma_f32_16x16x32_bf16 v[116:119], v[196:199], v[164:167], v[116:119]
	v_mfma_f32_16x16x32_bf16 v[112:115], v[204:207], v[164:167], v[112:115]
	v_mfma_f32_16x16x32_bf16 v[100:103], v[196:199], v[172:175], v[100:103]
	v_mfma_f32_16x16x32_bf16 v[96:99], v[204:207], v[172:175], v[96:99]
	v_mfma_f32_16x16x32_bf16 v[84:87], v[196:199], v[180:183], v[84:87]
	v_mfma_f32_16x16x32_bf16 v[80:83], v[204:207], v[180:183], v[80:83]
	v_mfma_f32_16x16x32_bf16 v[68:71], v[196:199], v[188:191], v[68:71]
	v_mfma_f32_16x16x32_bf16 v[64:67], v[204:207], v[188:191], v[64:67]
	s_setprio 0
	s_mov_b32 m0, s63
	v_lshl_add_u64 v[208:209], v[212:213], 0, s[14:15]
	s_barrier
	ds_read_b128 v[160:163], v231 offset:49152
	ds_read_b128 v[164:167], v231 offset:50176
	ds_read_b128 v[168:171], v231 offset:51200
	ds_read_b128 v[172:175], v231 offset:52224
	ds_read_b128 v[176:179], v231 offset:53248
	ds_read_b128 v[180:183], v231 offset:54272
	ds_read_b128 v[184:187], v231 offset:55296
	ds_read_b128 v[188:191], v231 offset:56320
	global_load_lds_dwordx4 v[208:209], off
	v_lshl_add_u64 v[208:209], v[214:215], 0, s[14:15]
	s_mov_b32 m0, s64
	s_nop 0
	global_load_lds_dwordx4 v[208:209], off
	s_barrier
; template <class Epi>
; DI void gemm_phase(LAS unsigned char* lds, int wid, int K, int lda, int ldb, bool bperm, const Sched3& S, const Epi& E) {
;     ...
;             PG8_BAR; PG8_WAIT_L(0); if (full) PG8_MMA(1, 0, At, B0); PG8_BAR; PG8_SCHED;
;             PG8_STAGE(PG8_SB(1, 1), b3 + hstepB, voffB);
;             PG8_WAIT_V(6); PG8_BAR; if (full) PG8_MMA(1, 1, At, B1); PG8_BAR;
;         }
;     DI void operator()(const Acc& acc, const Unit& u, int wr, int wc, int fr, int fq) const {
;     ...
;         if constexpr (PH == 1) {
;             if (u.kind == K_UZ) {
;                 LOAD_ROW_RS(rsv, SSQ(0), 1.f / 2048.f);
;                 ROWS8 { const int r = row0 + ai * HALF + m * 16; const float rs = rsv[ai][m];
;                     if (u.pn < 4) { bf16_t* dst = WSB(OFF_U) + (size_t)r * 1024 + colp;
; #pragma unroll
;                         for (int bj = 0; bj < 2; ++bj) { f32x4 v0 = acc[ai][bj][m][0] * rs, v1 = acc[ai][bj][m][1] * rs;
;                             v0[0] = gelu_tanh(v0[0]); v0[1] = gelu_tanh(v0[1]); v0[2] = gelu_tanh(v0[2]); v0[3] = gelu_tanh(v0[3]);
;                             v1[0] = gelu_tanh(v1[0]); v1[1] = gelu_tanh(v1[1]); v1[2] = gelu_tanh(v1[2]); v1[3] = gelu_tanh(v1[3]);
;                             *(u32x4*)(dst + bj * HALF) = PK8(v0, v1); }
;                     } else { float* dst = WSF(OFF_Z) + (size_t)r * 1024 + (colp - 1024);
;                         COLS4 *(f32x4*)(dst + bj * HALF + n * 4) = acc[ai][bj][m][n] * rs;
;                     }
;                 }
;             } else {
;                 float* ssqv = SSQ(1 + sqo);
;                 LOAD_COLP_RS(rsc, SSQ(0), 1.f / 2048.f);
; #pragma unroll
;                 for (int bj = 0; bj < 2; ++bj) { const int cc = colp + bj * HALF;
;                     f32x4 sq0 = {0.f, 0.f, 0.f, 0.f}, sq1 = {0.f, 0.f, 0.f, 0.f};
;                     ROWS8 { const int r = row0 + ai * HALF + m * 16; f32x4 v0 = acc[ai][bj][m][0] * rsc[bj][0], v1 = acc[ai][bj][m][1] * rsc[bj][1];
;                         v0[0] = gelu_tanh(v0[0]); v0[1] = gelu_tanh(v0[1]); v0[2] = gelu_tanh(v0[2]); v0[3] = gelu_tanh(v0[3]);
;                         v1[0] = gelu_tanh(v1[0]); v1[1] = gelu_tanh(v1[1]); v1[2] = gelu_tanh(v1[2]); v1[3] = gelu_tanh(v1[3]);
;                         sq0 += v0 * v0; sq1 += v1 * v1; *(u32x4*)(WSB(OFF_VT) + (size_t)r * 8192 + cc) = PK8(v0, v1); }
	s_waitcnt lgkmcnt(0)
	s_setprio 1
	s_waitcnt lgkmcnt(0)
	v_mfma_f32_16x16x32_bf16 v[60:63], v[128:131], v[160:163], v[60:63]
	v_mfma_f32_16x16x32_bf16 v[56:59], v[136:139], v[160:163], v[56:59]
	v_mfma_f32_16x16x32_bf16 v[44:47], v[128:131], v[168:171], v[44:47]
	v_mfma_f32_16x16x32_bf16 v[40:43], v[136:139], v[168:171], v[40:43]
	v_mfma_f32_16x16x32_bf16 v[28:31], v[128:131], v[176:179], v[28:31]
	v_mfma_f32_16x16x32_bf16 v[24:27], v[136:139], v[176:179], v[24:27]
	v_mfma_f32_16x16x32_bf16 v[12:15], v[128:131], v[184:187], v[12:15]
	v_mfma_f32_16x16x32_bf16 v[8:11], v[136:139], v[184:187], v[8:11]
	v_mfma_f32_16x16x32_bf16 v[60:63], v[132:135], v[164:167], v[60:63]
	v_mfma_f32_16x16x32_bf16 v[56:59], v[156:159], v[164:167], v[56:59]
	v_mfma_f32_16x16x32_bf16 v[44:47], v[132:135], v[172:175], v[44:47]
	v_mfma_f32_16x16x32_bf16 v[40:43], v[156:159], v[172:175], v[40:43]
	v_mfma_f32_16x16x32_bf16 v[28:31], v[132:135], v[180:183], v[28:31]
	v_mfma_f32_16x16x32_bf16 v[24:27], v[156:159], v[180:183], v[24:27]
	v_mfma_f32_16x16x32_bf16 v[12:15], v[132:135], v[188:191], v[12:15]
	v_mfma_f32_16x16x32_bf16 v[8:11], v[156:159], v[188:191], v[8:11]
	s_setprio 0
	s_barrier
	s_add_u32 s48, s48, 0x80080
	s_addc_u32 s49, s49, 0
	s_add_i32 s50, s50, s57
	v_lshl_add_u64 v[128:129], s[48:49], 0, v[142:143]
	s_mov_b32 m0, s50
	s_nop 0
	global_load_lds_dwordx4 v[128:129], off
	v_lshl_add_u64 v[128:129], s[48:49], 0, v[146:147]
	s_add_i32 m0, s50, 0x2000
	s_nop 0
	global_load_lds_dwordx4 v[128:129], off
	s_waitcnt vmcnt(6)
	s_barrier
	s_setprio 1
	v_mfma_f32_16x16x32_bf16 v[52:55], v[192:195], v[160:163], v[52:55]
	v_mfma_f32_16x16x32_bf16 v[48:51], v[200:203], v[160:163], v[48:51]
	v_mfma_f32_16x16x32_bf16 v[36:39], v[192:195], v[168:171], v[36:39]
	v_mfma_f32_16x16x32_bf16 v[32:35], v[200:203], v[168:171], v[32:35]
	v_mfma_f32_16x16x32_bf16 v[20:23], v[192:195], v[176:179], v[20:23]
	v_mfma_f32_16x16x32_bf16 v[16:19], v[200:203], v[176:179], v[16:19]
	v_mfma_f32_16x16x32_bf16 v[4:7], v[192:195], v[184:187], v[4:7]
	v_mfma_f32_16x16x32_bf16 v[0:3], v[200:203], v[184:187], v[0:3]
	v_mfma_f32_16x16x32_bf16 v[52:55], v[196:199], v[164:167], v[52:55]
	v_mfma_f32_16x16x32_bf16 v[48:51], v[204:207], v[164:167], v[48:51]
	v_mfma_f32_16x16x32_bf16 v[36:39], v[196:199], v[172:175], v[36:39]
	v_mfma_f32_16x16x32_bf16 v[32:35], v[204:207], v[172:175], v[32:35]
	v_mfma_f32_16x16x32_bf16 v[20:23], v[196:199], v[180:183], v[20:23]
	v_mfma_f32_16x16x32_bf16 v[16:19], v[204:207], v[180:183], v[16:19]
	v_mfma_f32_16x16x32_bf16 v[4:7], v[196:199], v[188:191], v[4:7]
	v_mfma_f32_16x16x32_bf16 v[0:3], v[204:207], v[188:191], v[0:3]
	s_setprio 0
	s_add_i32 s55, s55, 2
	s_add_u32 s46, s46, 0x100
	s_addc_u32 s47, s47, 0
	s_add_u32 s53, s53, 0x100
	s_addc_u32 s54, s54, 0
	s_cmp_gt_u32 s55, 29
	s_barrier
	s_cbranch_scc0 .LBB0_327
	v_lshl_add_u32 v158, s4, 8, v223
	v_lshl_add_u32 v156, s73, 8, v225
	v_or_b32_e32 v164, 16, v158
	v_or_b32_e32 v162, 32, v158
	v_or_b32_e32 v160, 48, v158
	s_cmp_lg_u32 s74, 0
	v_ashrrev_i32_e32 v157, 31, v156
	v_ashrrev_i32_e32 v159, 31, v158
	v_ashrrev_i32_e32 v165, 31, v164
	v_ashrrev_i32_e32 v163, 31, v162
	v_ashrrev_i32_e32 v161, 31, v160
	s_cbranch_scc0 .LBB0_362
	v_lshlrev_b64 v[136:137], 2, v[156:157]
	v_lshl_add_u64 v[132:133], s[16:17], 0, v[136:137]
	global_load_dwordx4 v[166:169], v[132:133], off
	global_load_dwordx4 v[172:175], v[132:133], off offset:16
	v_lshlrev_b64 v[128:129], 14, v[158:159]
	v_lshlrev_b64 v[170:171], 1, v[156:157]
	v_lshl_add_u64 v[138:139], s[20:21], 0, v[128:129]
	v_lshl_add_u64 v[138:139], v[138:139], 0, v[170:171]
	global_load_dwordx4 v[128:131], v[132:133], off offset:528
	s_nop 0
	global_load_dwordx4 v[132:135], v[132:133], off offset:512
	v_lshl_add_u64 v[136:137], s[18:19], 0, v[136:137]
	s_waitcnt vmcnt(0)
	v_fmamk_f32 v166, v166, 0x3a000000, v233
	v_fmamk_f32 v167, v167, 0x3a000000, v233
	v_fmamk_f32 v168, v168, 0x3a000000, v233
	v_fmamk_f32 v169, v169, 0x3a000000, v233
	v_rsq_f32_e32 v190, v166
	v_rsq_f32_e32 v191, v167
	v_rsq_f32_e32 v186, v168
	v_rsq_f32_e32 v187, v169
	v_fmamk_f32 v172, v172, 0x3a000000, v233
	v_fmamk_f32 v173, v173, 0x3a000000, v233
	v_fmamk_f32 v174, v174, 0x3a000000, v233
	v_fmamk_f32 v175, v175, 0x3a000000, v233
	v_rsq_f32_e32 v182, v172
	v_rsq_f32_e32 v184, v174
	v_rsq_f32_e32 v185, v175
	v_rsq_f32_e32 v183, v173
	v_mul_f32_e32 v168, v124, v190
	v_mul_f32_e32 v169, v125, v191
	v_mul_f32_e32 v166, v126, v186
	v_mul_f32_e32 v167, v127, v187
	v_mul_f32_e32 v178, 0x3d922279, v168
	v_mul_f32_e32 v179, 0x3d922279, v169
	v_mul_f32_e32 v192, 0x3d922279, v166
	v_mul_f32_e32 v193, 0x3d922279, v167
	v_fmaak_f32 v178, v168, v178, 0x3fcc422a
	v_fmaak_f32 v179, v169, v179, 0x3fcc422a
	v_mul_f32_e32 v172, v122, v184
	v_mul_f32_e32 v173, v123, v185
	v_mul_f32_e32 v174, v120, v182
	v_mul_f32_e32 v175, v121, v183
	v_fmaak_f32 v192, v166, v192, 0x3fcc422a
	v_fmaak_f32 v193, v167, v193, 0x3fcc422a
	v_mul_f32_e32 v178, v168, v178
	v_mul_f32_e32 v179, v169, v179
	v_mul_f32_e32 v196, 0x3d922279, v174
	v_mul_f32_e32 v197, 0x3d922279, v175
	v_mul_f32_e32 v198, 0x3d922279, v172
	v_mul_f32_e32 v199, 0x3d922279, v173
	v_mul_f32_e32 v192, v166, v192
	v_mul_f32_e32 v193, v167, v193
	v_mul_f32_e32 v178, 0xbfb8aa3b, v178
	v_mul_f32_e32 v179, 0xbfb8aa3b, v179
	v_fmaak_f32 v196, v174, v196, 0x3fcc422a
	v_fmaak_f32 v197, v175, v197, 0x3fcc422a
	v_fmaak_f32 v198, v172, v198, 0x3fcc422a
	v_fmaak_f32 v199, v173, v199, 0x3fcc422a
	v_mul_f32_e32 v192, 0xbfb8aa3b, v192
	v_mul_f32_e32 v193, 0xbfb8aa3b, v193
	v_exp_f32_e32 v178, v178
	v_exp_f32_e32 v179, v179
	v_mul_f32_e32 v196, v174, v196
	v_mul_f32_e32 v197, v175, v197
; DI float gelu_tanh(float x) { const float t = x * (1.5957691216f + 0.0713548163f * x * x); return x * __builtin_amdgcn_rcpf(1.f + __builtin_amdgcn_exp2f(-1.4426950409f * t)); }
; #define ROWS8 _Pragma("unroll") for (int ai = 0; ai < 2; ++ai) _Pragma("unroll") for (int m = 0; m < 4; ++m) if (ai == 0 || !hf)
; #define PK8(v0, v1) ({ const u32x2 h0_ = pk4(v0), h1_ = pk4(v1); (u32x4){h0_.x, h0_.y, h1_.x, h1_.y}; })
;     DI void operator()(const Acc& acc, const Unit& u, int wr, int wc, int fr, int fq) const {
;     ...
;                 for (int bj = 0; bj < 2; ++bj) { const int cc = colp + bj * HALF;
;                     f32x4 sq0 = {0.f, 0.f, 0.f, 0.f}, sq1 = {0.f, 0.f, 0.f, 0.f};
;                     ROWS8 { const int r = row0 + ai * HALF + m * 16; f32x4 v0 = acc[ai][bj][m][0] * rsc[bj][0], v1 = acc[ai][bj][m][1] * rsc[bj][1];
;                         v0[0] = gelu_tanh(v0[0]); v0[1] = gelu_tanh(v0[1]); v0[2] = gelu_tanh(v0[2]); v0[3] = gelu_tanh(v0[3]);
;                         v1[0] = gelu_tanh(v1[0]); v1[1] = gelu_tanh(v1[1]); v1[2] = gelu_tanh(v1[2]); v1[3] = gelu_tanh(v1[3]);
;                         sq0 += v0 * v0; sq1 += v1 * v1; *(u32x4*)(WSB(OFF_VT) + (size_t)r * 8192 + cc) = PK8(v0, v1); }
	v_mul_f32_e32 v198, v172, v198
	v_mul_f32_e32 v199, v173, v199
	v_exp_f32_e32 v192, v192
	v_exp_f32_e32 v193, v193
	v_mul_f32_e32 v196, 0xbfb8aa3b, v196
	v_mul_f32_e32 v197, 0xbfb8aa3b, v197
	v_mul_f32_e32 v198, 0xbfb8aa3b, v198
	v_mul_f32_e32 v199, 0xbfb8aa3b, v199
	v_exp_f32_e32 v196, v196
	v_exp_f32_e32 v197, v197
	v_exp_f32_e32 v198, v198
	v_exp_f32_e32 v199, v199
	v_add_f32_e32 v178, 1.0, v178
	v_add_f32_e32 v179, 1.0, v179
	v_add_f32_e32 v201, 1.0, v192
	v_add_f32_e32 v202, 1.0, v193
	v_rcp_f32_e32 v192, v178
	v_rcp_f32_e32 v193, v179
	v_add_f32_e32 v196, 1.0, v196
	v_add_f32_e32 v197, 1.0, v197
	v_add_f32_e32 v198, 1.0, v198
	v_add_f32_e32 v199, 1.0, v199
	v_mul_f32_e32 v194, v104, v182
	v_mul_f32_e32 v195, v105, v183
	v_rcp_f32_e32 v178, v201
	v_rcp_f32_e32 v179, v202
	v_rcp_f32_e32 v196, v196
	v_rcp_f32_e32 v198, v198
	v_rcp_f32_e32 v199, v199
	v_rcp_f32_e32 v197, v197
	v_mul_f32_e32 v202, v168, v192
	v_mul_f32_e32 v203, v169, v193
	v_mul_f32_e32 v192, 0x3d922279, v194
	v_fmaak_f32 v192, v194, v192, 0x3fcc422a
	v_mul_f32_e32 v192, v194, v192
	v_mul_f32_e32 v178, v166, v178
	v_mul_f32_e32 v179, v167, v179
	v_mul_f32_e32 v172, v172, v198
	v_mul_f32_e32 v173, v173, v199
	v_mul_f32_e32 v174, v174, v196
	v_mul_f32_e32 v175, v175, v197
	v_mul_f32_e32 v192, 0xbfb8aa3b, v192
	v_mul_f32_e32 v176, v110, v186
	v_mul_f32_e32 v177, v111, v187
	v_mul_f32_e32 v188, v106, v184
	v_mul_f32_e32 v189, v107, v185
	v_cvt_pk_bf16_f32 v166, v202, v203
	v_cvt_pk_bf16_f32 v167, v178, v179
	v_cvt_pk_bf16_f32 v168, v174, v175
	v_cvt_pk_bf16_f32 v169, v172, v173
	v_exp_f32_e32 v192, v192
	global_store_dwordx4 v[138:139], v[166:169], off
	v_mul_f32_e32 v193, 0x3d922279, v188
	v_fmaak_f32 v193, v188, v193, 0x3fcc422a
	v_mul_f32_e32 v168, 0x3d922279, v176
	v_mul_f32_e32 v169, 0x3d922279, v177
	v_fmaak_f32 v168, v176, v168, 0x3fcc422a
	v_fmaak_f32 v169, v177, v169, 0x3fcc422a
	v_mul_f32_e32 v197, 0x3d922279, v189
	v_mul_f32_e32 v168, v176, v168
	v_mul_f32_e32 v169, v177, v169
	v_mul_f32_e32 v193, v188, v193
	v_fmaak_f32 v197, v189, v197, 0x3fcc422a
	v_mul_f32_e32 v168, 0xbfb8aa3b, v168
	v_mul_f32_e32 v169, 0xbfb8aa3b, v169
	v_add_f32_e32 v192, 1.0, v192
	v_mul_f32_e32 v193, 0xbfb8aa3b, v193
	v_mul_f32_e32 v197, v189, v197
	v_exp_f32_e32 v168, v168
	v_exp_f32_e32 v169, v169
	v_rcp_f32_e32 v196, v192
	v_mul_f32_e32 v192, 0x3d922279, v195
	v_exp_f32_e32 v193, v193
	v_mul_f32_e32 v197, 0xbfb8aa3b, v197
	v_fmaak_f32 v192, v195, v192, 0x3fcc422a
	v_exp_f32_e32 v197, v197
	v_mul_f32_e32 v192, v195, v192
	v_mul_f32_e32 v192, 0xbfb8aa3b, v192
	v_add_f32_e32 v168, 1.0, v168
	v_add_f32_e32 v169, 1.0, v169
	v_exp_f32_e32 v192, v192
	v_add_f32_e32 v193, 1.0, v193
	v_mul_f32_e32 v180, v108, v190
	v_mul_f32_e32 v181, v109, v191
	v_rcp_f32_e32 v168, v168
	v_rcp_f32_e32 v169, v169
	v_rcp_f32_e32 v198, v193
	v_add_f32_e32 v193, 1.0, v197
	v_mul_f32_e32 v200, 0x3d922279, v180
	v_mul_f32_e32 v167, 0x3d922279, v181
	v_rcp_f32_e32 v199, v193
	v_fmaak_f32 v200, v180, v200, 0x3fcc422a
	v_fmaak_f32 v167, v181, v167, 0x3fcc422a
	v_mul_f32_e32 v200, v180, v200
	v_mul_f32_e32 v167, v181, v167
	v_add_f32_e32 v192, 1.0, v192
	v_mul_f32_e32 v200, 0xbfb8aa3b, v200
	v_mul_f32_e32 v167, 0xbfb8aa3b, v167
	v_rcp_f32_e32 v197, v192
	v_mul_f32_e32 v192, v176, v168
	v_mul_f32_e32 v193, v177, v169
	v_mul_f32_e32 v168, v92, v190
	v_mul_f32_e32 v169, v93, v191
	v_exp_f32_e32 v200, v200
	v_exp_f32_e32 v167, v167
	v_mul_f32_e32 v176, v188, v198
	v_mul_f32_e32 v177, v189, v199
	v_mul_f32_e32 v188, 0x3d922279, v168
	v_fmaak_f32 v188, v168, v188, 0x3fcc422a
	v_mul_f32_e32 v188, v168, v188
	v_mul_f32_e32 v188, 0xbfb8aa3b, v188
	v_add_f32_e32 v166, 1.0, v200
	v_add_f32_e32 v167, 1.0, v167
	v_exp_f32_e32 v198, v188
	v_mul_f32_e32 v188, v94, v186
	v_mul_f32_e32 v189, v95, v187
	v_mul_f32_e32 v199, 0x3d922279, v169
	v_rcp_f32_e32 v166, v166
	v_rcp_f32_e32 v167, v167
	v_fmaak_f32 v199, v169, v199, 0x3fcc422a
	v_mul_f32_e32 v200, 0x3d922279, v188
	v_mul_f32_e32 v199, v169, v199
	v_fmaak_f32 v200, v188, v200, 0x3fcc422a
	v_mul_f32_e32 v199, 0xbfb8aa3b, v199
	v_mul_f32_e32 v200, v188, v200
	v_exp_f32_e32 v199, v199
	v_mul_f32_e32 v200, 0xbfb8aa3b, v200
	v_mul_f32_e32 v210, v180, v166
	v_mul_f32_e32 v211, v181, v167
	v_lshlrev_b64 v[166:167], 14, v[164:165]
	v_exp_f32_e32 v204, v200
	v_mul_f32_e32 v180, v194, v196
	v_mul_f32_e32 v181, v195, v197
	v_lshl_add_u64 v[166:167], s[20:21], 0, v[166:167]
	v_cvt_pk_bf16_f32 v194, v210, v211
	v_cvt_pk_bf16_f32 v195, v192, v193
	v_cvt_pk_bf16_f32 v196, v180, v181
	v_cvt_pk_bf16_f32 v197, v176, v177
	v_lshl_add_u64 v[166:167], v[166:167], 0, v[170:171]
	v_add_f32_e32 v198, 1.0, v198
	global_store_dwordx4 v[166:167], v[194:197], off
	v_rcp_f32_e32 v200, v198
	v_add_f32_e32 v198, 1.0, v199
	v_mul_f32_e32 v194, v90, v184
	v_mul_f32_e32 v195, v91, v185
	v_mul_f32_e32 v196, v88, v182
	v_mul_f32_e32 v197, v89, v183
	v_rcp_f32_e32 v201, v198
	v_add_f32_e32 v198, 1.0, v204
	v_mul_f32_e32 v199, 0x3d922279, v189
	v_mul_f32_e32 v204, 0x3d922279, v196
	v_mul_f32_e32 v205, 0x3d922279, v197
	v_mul_f32_e32 v206, 0x3d922279, v194
	v_mul_f32_e32 v207, 0x3d922279, v195
	v_fmaak_f32 v199, v189, v199, 0x3fcc422a
	v_fmaak_f32 v204, v196, v204, 0x3fcc422a
	v_fmaak_f32 v205, v197, v205, 0x3fcc422a
	v_fmaak_f32 v206, v194, v206, 0x3fcc422a
	v_fmaak_f32 v207, v195, v207, 0x3fcc422a
	v_mul_f32_e32 v199, v189, v199
	v_mul_f32_e32 v204, v196, v204
	v_mul_f32_e32 v205, v197, v205
	v_mul_f32_e32 v206, v194, v206
	v_mul_f32_e32 v207, v195, v207
	v_mul_f32_e32 v199, 0xbfb8aa3b, v199
	v_mul_f32_e32 v204, 0xbfb8aa3b, v204
	v_mul_f32_e32 v205, 0xbfb8aa3b, v205
	v_mul_f32_e32 v206, 0xbfb8aa3b, v206
; DI float gelu_tanh(float x) { const float t = x * (1.5957691216f + 0.0713548163f * x * x); return x * __builtin_amdgcn_rcpf(1.f + __builtin_amdgcn_exp2f(-1.4426950409f * t)); }
; #define ROWS8 _Pragma("unroll") for (int ai = 0; ai < 2; ++ai) _Pragma("unroll") for (int m = 0; m < 4; ++m) if (ai == 0 || !hf)
; #define PK8(v0, v1) ({ const u32x2 h0_ = pk4(v0), h1_ = pk4(v1); (u32x4){h0_.x, h0_.y, h1_.x, h1_.y}; })
;     DI void operator()(const Acc& acc, const Unit& u, int wr, int wc, int fr, int fq) const {
;     ...
;                 for (int bj = 0; bj < 2; ++bj) { const int cc = colp + bj * HALF;
;                     f32x4 sq0 = {0.f, 0.f, 0.f, 0.f}, sq1 = {0.f, 0.f, 0.f, 0.f};
;                     ROWS8 { const int r = row0 + ai * HALF + m * 16; f32x4 v0 = acc[ai][bj][m][0] * rsc[bj][0], v1 = acc[ai][bj][m][1] * rsc[bj][1];
;                         v0[0] = gelu_tanh(v0[0]); v0[1] = gelu_tanh(v0[1]); v0[2] = gelu_tanh(v0[2]); v0[3] = gelu_tanh(v0[3]);
;                         v1[0] = gelu_tanh(v1[0]); v1[1] = gelu_tanh(v1[1]); v1[2] = gelu_tanh(v1[2]); v1[3] = gelu_tanh(v1[3]);
;                         sq0 += v0 * v0; sq1 += v1 * v1; *(u32x4*)(WSB(OFF_VT) + (size_t)r * 8192 + cc) = PK8(v0, v1); }
	v_mul_f32_e32 v207, 0xbfb8aa3b, v207
	v_exp_f32_e32 v199, v199
	v_exp_f32_e32 v204, v204
	v_exp_f32_e32 v205, v205
	v_exp_f32_e32 v206, v206
	v_exp_f32_e32 v207, v207
	v_add_f32_e32 v199, 1.0, v199
	v_add_f32_e32 v204, 1.0, v204
	v_add_f32_e32 v205, 1.0, v205
	v_add_f32_e32 v206, 1.0, v206
	v_add_f32_e32 v207, 1.0, v207
	v_rcp_f32_e32 v198, v198
	v_rcp_f32_e32 v199, v199
	v_rcp_f32_e32 v204, v204
	v_rcp_f32_e32 v206, v206
	v_rcp_f32_e32 v207, v207
	v_rcp_f32_e32 v205, v205
	v_mul_f32_e32 v198, v188, v198
	v_mul_f32_e32 v199, v189, v199
	v_mul_f32_e32 v212, v168, v200
	v_mul_f32_e32 v213, v169, v201
	v_mul_f32_e32 v188, v194, v206
	v_mul_f32_e32 v189, v195, v207
	v_mul_f32_e32 v194, v196, v204
	v_mul_f32_e32 v195, v197, v205
	v_mul_f32_e32 v196, v76, v190
	v_mul_f32_e32 v197, v77, v191
	v_lshlrev_b64 v[168:169], 14, v[162:163]
	v_mul_f32_e32 v200, 0x3d922279, v196
	v_fmaak_f32 v200, v196, v200, 0x3fcc422a
	v_lshl_add_u64 v[168:169], s[20:21], 0, v[168:169]
	v_mul_f32_e32 v200, v196, v200
	v_cvt_pk_bf16_f32 v204, v212, v213
	v_cvt_pk_bf16_f32 v205, v198, v199
	v_cvt_pk_bf16_f32 v206, v194, v195
	v_cvt_pk_bf16_f32 v207, v188, v189
	v_lshl_add_u64 v[168:169], v[168:169], 0, v[170:171]
	v_mul_f32_e32 v200, 0xbfb8aa3b, v200
	global_store_dwordx4 v[168:169], v[204:207], off
	v_mul_f32_e32 v208, v72, v182
	v_mul_f32_e32 v209, v73, v183
	s_nop 0
	v_exp_f32_e32 v204, v200
	v_mul_f32_e32 v200, v78, v186
	v_mul_f32_e32 v201, v79, v187
	v_mul_f32_e32 v205, 0x3d922279, v197
	v_fmaak_f32 v205, v197, v205, 0x3fcc422a
	v_mul_f32_e32 v214, 0x3d922279, v200
	v_mul_f32_e32 v205, v197, v205
	v_fmaak_f32 v214, v200, v214, 0x3fcc422a
	v_mul_f32_e32 v205, 0xbfb8aa3b, v205
	v_mul_f32_e32 v214, v200, v214
	v_exp_f32_e32 v205, v205
	v_mul_f32_e32 v214, 0xbfb8aa3b, v214
	v_exp_f32_e32 v216, v214
	v_add_f32_e32 v204, 1.0, v204
	v_rcp_f32_e32 v214, v204
	v_add_f32_e32 v204, 1.0, v205
	v_mul_f32_e32 v206, v74, v184
	v_mul_f32_e32 v207, v75, v185
	v_rcp_f32_e32 v215, v204
	v_add_f32_e32 v204, 1.0, v216
	v_mul_f32_e32 v205, 0x3d922279, v201
	v_mul_f32_e32 v216, 0x3d922279, v208
	v_mul_f32_e32 v217, 0x3d922279, v209
	v_fmaak_f32 v205, v201, v205, 0x3fcc422a
	v_fmaak_f32 v216, v208, v216, 0x3fcc422a
	v_fmaak_f32 v217, v209, v217, 0x3fcc422a
	v_mul_f32_e32 v218, 0x3d922279, v206
	v_mul_f32_e32 v219, 0x3d922279, v207
	v_mul_f32_e32 v205, v201, v205
	v_mul_f32_e32 v216, v208, v216
	v_mul_f32_e32 v217, v209, v217
	v_fmaak_f32 v218, v206, v218, 0x3fcc422a
	v_fmaak_f32 v219, v207, v219, 0x3fcc422a
	v_mul_f32_e32 v205, 0xbfb8aa3b, v205
	v_mul_f32_e32 v216, 0xbfb8aa3b, v216
	v_mul_f32_e32 v217, 0xbfb8aa3b, v217
	v_mul_f32_e32 v218, v206, v218
	v_mul_f32_e32 v219, v207, v219
	v_exp_f32_e32 v205, v205
	v_exp_f32_e32 v216, v216
	v_exp_f32_e32 v217, v217
	v_mul_f32_e32 v218, 0xbfb8aa3b, v218
	v_mul_f32_e32 v219, 0xbfb8aa3b, v219
	v_exp_f32_e32 v218, v218
	v_exp_f32_e32 v219, v219
	v_add_f32_e32 v205, 1.0, v205
	v_add_f32_e32 v216, 1.0, v216
	v_add_f32_e32 v217, 1.0, v217
	v_rcp_f32_e32 v204, v204
	v_rcp_f32_e32 v205, v205
	v_rcp_f32_e32 v216, v216
	v_add_f32_e32 v218, 1.0, v218
	v_add_f32_e32 v219, 1.0, v219
	v_rcp_f32_e32 v217, v217
	v_rcp_f32_e32 v218, v218
	v_rcp_f32_e32 v219, v219
	v_mul_f32_e32 v204, v200, v204
	v_mul_f32_e32 v205, v201, v205
	v_mul_f32_e32 v200, v208, v216
	v_mul_f32_e32 v201, v209, v217
	v_lshlrev_b64 v[216:217], 14, v[160:161]
	v_mul_f32_e32 v214, v196, v214
	v_mul_f32_e32 v215, v197, v215
	v_mul_f32_e32 v196, v206, v218
	v_mul_f32_e32 v197, v207, v219
	v_lshl_add_u64 v[216:217], s[20:21], 0, v[216:217]
	v_cvt_pk_bf16_f32 v206, v214, v215
	v_cvt_pk_bf16_f32 v207, v204, v205
	v_cvt_pk_bf16_f32 v208, v200, v201
	v_cvt_pk_bf16_f32 v209, v196, v197
	v_lshl_add_u64 v[170:171], v[216:217], 0, v[170:171]
	global_store_dwordx4 v[170:171], v[206:209], off
	s_nop 1
	v_mul_f32_e32 v206, v210, v210
	v_mul_f32_e32 v207, v211, v211
	s_nop 0
	v_fma_f32 v202, v202, v202, v206
	v_fma_f32 v203, v203, v203, v207
	s_nop 0
	v_fma_f32 v202, v212, v212, v202
	v_fma_f32 v203, v213, v213, v203
	v_mul_f32_e32 v212, v58, v184
	v_mul_f32_e32 v213, v59, v185
	v_fma_f32 v208, v214, v214, v202
	v_fma_f32 v209, v215, v215, v203
	v_mul_f32_e32 v202, v60, v190
	v_mul_f32_e32 v203, v61, v191
	v_mul_f32_e32 v214, v56, v182
	v_mul_f32_e32 v215, v57, v183
	v_mul_f32_e32 v206, 0x3d922279, v202
	v_fmaak_f32 v206, v202, v206, 0x3fcc422a
	v_mul_f32_e32 v206, v202, v206
	v_mul_f32_e32 v206, 0xbfb8aa3b, v206
	v_exp_f32_e32 v210, v206
	v_mul_f32_e32 v206, v62, v186
	v_mul_f32_e32 v207, v63, v187
	v_mul_f32_e32 v211, 0x3d922279, v203
	v_fmaak_f32 v211, v203, v211, 0x3fcc422a
	v_mul_f32_e32 v216, 0x3d922279, v206
	v_mul_f32_e32 v211, v203, v211
	v_fmaak_f32 v216, v206, v216, 0x3fcc422a
	v_mul_f32_e32 v211, 0xbfb8aa3b, v211
	v_mul_f32_e32 v216, v206, v216
	v_exp_f32_e32 v211, v211
	v_mul_f32_e32 v216, 0xbfb8aa3b, v216
	v_exp_f32_e32 v218, v216
	v_add_f32_e32 v210, 1.0, v210
	v_rcp_f32_e32 v216, v210
	v_add_f32_e32 v210, 1.0, v211
	v_rcp_f32_e32 v217, v210
	v_add_f32_e32 v210, 1.0, v218
	v_mul_f32_e32 v211, 0x3d922279, v207
	v_mul_f32_e32 v218, 0x3d922279, v214
	v_mul_f32_e32 v219, 0x3d922279, v215
	v_mul_f32_e32 v220, 0x3d922279, v212
	v_mul_f32_e32 v221, 0x3d922279, v213
	v_fmaak_f32 v211, v207, v211, 0x3fcc422a
	v_fmaak_f32 v218, v214, v218, 0x3fcc422a
	v_fmaak_f32 v219, v215, v219, 0x3fcc422a
	v_fmaak_f32 v220, v212, v220, 0x3fcc422a
	v_fmaak_f32 v221, v213, v221, 0x3fcc422a
	v_mul_f32_e32 v211, v207, v211
	v_mul_f32_e32 v218, v214, v218
	v_mul_f32_e32 v219, v215, v219
	v_mul_f32_e32 v220, v212, v220
	v_mul_f32_e32 v221, v213, v221
	v_mul_f32_e32 v211, 0xbfb8aa3b, v211
	v_mul_f32_e32 v218, 0xbfb8aa3b, v218
; DI float gelu_tanh(float x) { const float t = x * (1.5957691216f + 0.0713548163f * x * x); return x * __builtin_amdgcn_rcpf(1.f + __builtin_amdgcn_exp2f(-1.4426950409f * t)); }
; #define ROWS8 _Pragma("unroll") for (int ai = 0; ai < 2; ++ai) _Pragma("unroll") for (int m = 0; m < 4; ++m) if (ai == 0 || !hf)
; #define PK8(v0, v1) ({ const u32x2 h0_ = pk4(v0), h1_ = pk4(v1); (u32x4){h0_.x, h0_.y, h1_.x, h1_.y}; })
;     DI void operator()(const Acc& acc, const Unit& u, int wr, int wc, int fr, int fq) const {
;     ...
;                 for (int bj = 0; bj < 2; ++bj) { const int cc = colp + bj * HALF;
;                     f32x4 sq0 = {0.f, 0.f, 0.f, 0.f}, sq1 = {0.f, 0.f, 0.f, 0.f};
;                     ROWS8 { const int r = row0 + ai * HALF + m * 16; f32x4 v0 = acc[ai][bj][m][0] * rsc[bj][0], v1 = acc[ai][bj][m][1] * rsc[bj][1];
;                         v0[0] = gelu_tanh(v0[0]); v0[1] = gelu_tanh(v0[1]); v0[2] = gelu_tanh(v0[2]); v0[3] = gelu_tanh(v0[3]);
;                         v1[0] = gelu_tanh(v1[0]); v1[1] = gelu_tanh(v1[1]); v1[2] = gelu_tanh(v1[2]); v1[3] = gelu_tanh(v1[3]);
;                         sq0 += v0 * v0; sq1 += v1 * v1; *(u32x4*)(WSB(OFF_VT) + (size_t)r * 8192 + cc) = PK8(v0, v1); }
	v_mul_f32_e32 v219, 0xbfb8aa3b, v219
	v_mul_f32_e32 v220, 0xbfb8aa3b, v220
	v_mul_f32_e32 v221, 0xbfb8aa3b, v221
	v_exp_f32_e32 v211, v211
	v_exp_f32_e32 v218, v218
	v_exp_f32_e32 v219, v219
	v_exp_f32_e32 v220, v220
	v_exp_f32_e32 v221, v221
	v_add_f32_e32 v211, 1.0, v211
	v_add_f32_e32 v218, 1.0, v218
	v_add_f32_e32 v219, 1.0, v219
	v_add_f32_e32 v220, 1.0, v220
	v_add_f32_e32 v221, 1.0, v221
	v_rcp_f32_e32 v210, v210
	v_rcp_f32_e32 v211, v211
	v_rcp_f32_e32 v218, v218
	v_rcp_f32_e32 v220, v220
	v_rcp_f32_e32 v221, v221
	v_rcp_f32_e32 v219, v219
	v_mul_f32_e32 v216, v202, v216
	v_mul_f32_e32 v217, v203, v217
	v_mul_f32_e32 v210, v206, v210
	v_mul_f32_e32 v211, v207, v211
	v_mul_f32_e32 v202, v212, v220
	v_mul_f32_e32 v203, v213, v221
	v_mul_f32_e32 v206, v214, v218
	v_mul_f32_e32 v207, v215, v219
	v_fma_f32 v218, v216, v216, v208
	v_fma_f32 v219, v217, v217, v209
	v_add_co_u32_e32 v208, vcc, s69, v138
	v_cvt_pk_bf16_f32 v212, v216, v217
	v_cvt_pk_bf16_f32 v213, v210, v211
	v_cvt_pk_bf16_f32 v214, v206, v207
	v_cvt_pk_bf16_f32 v215, v202, v203
	v_addc_co_u32_e32 v209, vcc, 0, v139, vcc
	global_store_dwordx4 v[208:209], v[212:215], off
	v_mul_f32_e32 v208, v44, v190
	v_mul_f32_e32 v209, v45, v191
	v_mul_f32_e32 v220, v40, v182
	v_mul_f32_e32 v221, v41, v183
	v_mul_f32_e32 v212, 0x3d922279, v208
	v_fmaak_f32 v212, v208, v212, 0x3fcc422a
	v_mul_f32_e32 v212, v208, v212
	v_mul_f32_e32 v212, 0xbfb8aa3b, v212
	v_exp_f32_e32 v216, v212
	v_mul_f32_e32 v212, v46, v186
	v_mul_f32_e32 v213, v47, v187
	v_mul_f32_e32 v214, v42, v184
	v_mul_f32_e32 v215, v43, v185
	v_mul_f32_e32 v234, 0x3d922279, v213
	v_fmaak_f32 v234, v213, v234, 0x3fcc422a
	v_mul_f32_e32 v222, 0x3d922279, v212
	v_mul_f32_e32 v234, v213, v234
	v_fmaak_f32 v222, v212, v222, 0x3fcc422a
	v_mul_f32_e32 v234, 0xbfb8aa3b, v234
	v_mul_f32_e32 v222, v212, v222
	v_exp_f32_e32 v235, v234
	v_mul_f32_e32 v234, 0x3d922279, v220
	v_mul_f32_e32 v222, 0xbfb8aa3b, v222
	v_fmaak_f32 v234, v220, v234, 0x3fcc422a
	v_exp_f32_e32 v222, v222
	v_mul_f32_e32 v234, v220, v234
	v_mul_f32_e32 v234, 0xbfb8aa3b, v234
	v_exp_f32_e32 v236, v234
	v_add_f32_e32 v222, 1.0, v222
	v_rcp_f32_e32 v234, v222
	v_add_f32_e32 v222, 1.0, v235
	v_rcp_f32_e32 v235, v222
	v_add_f32_e32 v222, 1.0, v236
	v_mul_f32_e32 v237, 0x3d922279, v214
	v_mul_f32_e32 v217, 0x3d922279, v209
	v_rcp_f32_e32 v236, v222
	v_mul_f32_e32 v222, 0x3d922279, v221
	v_fmaak_f32 v237, v214, v237, 0x3fcc422a
	v_mul_f32_e32 v238, 0x3d922279, v215
	v_fmaak_f32 v217, v209, v217, 0x3fcc422a
	v_fmaak_f32 v222, v221, v222, 0x3fcc422a
	v_mul_f32_e32 v237, v214, v237
	v_fmaak_f32 v238, v215, v238, 0x3fcc422a
	v_mul_f32_e32 v217, v209, v217
	v_mul_f32_e32 v222, v221, v222
	v_mul_f32_e32 v237, 0xbfb8aa3b, v237
	v_mul_f32_e32 v238, v215, v238
	v_mul_f32_e32 v217, 0xbfb8aa3b, v217
	v_mul_f32_e32 v222, 0xbfb8aa3b, v222
	v_exp_f32_e32 v237, v237
	v_mul_f32_e32 v238, 0xbfb8aa3b, v238
	v_exp_f32_e32 v217, v217
	v_exp_f32_e32 v222, v222
	v_exp_f32_e32 v239, v238
	v_add_f32_e32 v237, 1.0, v237
	v_add_f32_e32 v216, 1.0, v216
	v_add_f32_e32 v217, 1.0, v217
	v_add_f32_e32 v222, 1.0, v222
	v_rcp_f32_e32 v238, v237
	v_add_f32_e32 v237, 1.0, v239
	v_rcp_f32_e32 v216, v216
	v_rcp_f32_e32 v217, v217
	v_rcp_f32_e32 v239, v237
	v_rcp_f32_e32 v237, v222
	v_mul_f32_e32 v240, v208, v216
	v_mul_f32_e32 v241, v209, v217
	v_mul_f32_e32 v216, v212, v234
	v_mul_f32_e32 v217, v213, v235
	v_mul_f32_e32 v208, v214, v238
	v_mul_f32_e32 v209, v215, v239
	v_mul_f32_e32 v212, v220, v236
	v_mul_f32_e32 v213, v221, v237
	v_add_co_u32_e32 v214, vcc, s70, v138
	v_fma_f32 v234, v240, v240, v218
	v_fma_f32 v235, v241, v241, v219
	v_cvt_pk_bf16_f32 v218, v240, v241
	v_cvt_pk_bf16_f32 v219, v216, v217
	v_cvt_pk_bf16_f32 v220, v212, v213
	v_cvt_pk_bf16_f32 v221, v208, v209
	v_addc_co_u32_e32 v215, vcc, 0, v139, vcc
	global_store_dwordx4 v[214:215], v[218:221], off
	v_mul_f32_e32 v214, v28, v190
	v_mul_f32_e32 v215, v29, v191
	v_mul_f32_e32 v238, v24, v182
	v_mul_f32_e32 v239, v25, v183
	v_mul_f32_e32 v218, 0x3d922279, v214
	v_fmaak_f32 v218, v214, v218, 0x3fcc422a
	v_mul_f32_e32 v218, v214, v218
	v_mul_f32_e32 v218, 0xbfb8aa3b, v218
	v_exp_f32_e32 v220, v218
	v_mul_f32_e32 v218, v30, v186
	v_mul_f32_e32 v219, v31, v187
	v_mul_f32_e32 v221, 0x3d922279, v215
	v_fmaak_f32 v221, v215, v221, 0x3fcc422a
	v_mul_f32_e32 v222, 0x3d922279, v218
	v_mul_f32_e32 v221, v215, v221
	v_fmaak_f32 v222, v218, v222, 0x3fcc422a
	v_mul_f32_e32 v221, 0xbfb8aa3b, v221
	v_mul_f32_e32 v222, v218, v222
	v_exp_f32_e32 v221, v221
	v_mul_f32_e32 v222, 0xbfb8aa3b, v222
	v_exp_f32_e32 v222, v222
	v_add_f32_e32 v220, 1.0, v220
	v_rcp_f32_e32 v240, v220
	v_add_f32_e32 v220, 1.0, v221
	v_rcp_f32_e32 v241, v220
	v_add_f32_e32 v220, 1.0, v222
	v_mul_f32_e32 v222, 0x3d922279, v238
	v_fmaak_f32 v222, v238, v222, 0x3fcc422a
	v_mul_f32_e32 v222, v238, v222
	v_mul_f32_e32 v222, 0xbfb8aa3b, v222
	v_exp_f32_e32 v222, v222
	v_mul_f32_e32 v236, v26, v184
	v_mul_f32_e32 v237, v27, v185
	v_mul_f32_e32 v221, 0x3d922279, v219
	v_mul_f32_e32 v243, 0x3d922279, v236
	v_add_f32_e32 v222, 1.0, v222
	v_rcp_f32_e32 v242, v222
	v_mul_f32_e32 v222, 0x3d922279, v239
	v_fmaak_f32 v243, v236, v243, 0x3fcc422a
	v_mul_f32_e32 v244, 0x3d922279, v237
	v_fmaak_f32 v221, v219, v221, 0x3fcc422a
	v_fmaak_f32 v222, v239, v222, 0x3fcc422a
	v_mul_f32_e32 v243, v236, v243
	v_fmaak_f32 v244, v237, v244, 0x3fcc422a
	v_mul_f32_e32 v221, v219, v221
	v_mul_f32_e32 v222, v239, v222
; DI float gelu_tanh(float x) { const float t = x * (1.5957691216f + 0.0713548163f * x * x); return x * __builtin_amdgcn_rcpf(1.f + __builtin_amdgcn_exp2f(-1.4426950409f * t)); }
; #define ROWS8 _Pragma("unroll") for (int ai = 0; ai < 2; ++ai) _Pragma("unroll") for (int m = 0; m < 4; ++m) if (ai == 0 || !hf)
; #define PK8(v0, v1) ({ const u32x2 h0_ = pk4(v0), h1_ = pk4(v1); (u32x4){h0_.x, h0_.y, h1_.x, h1_.y}; })
;     DI void operator()(const Acc& acc, const Unit& u, int wr, int wc, int fr, int fq) const {
;     ...
;                 for (int bj = 0; bj < 2; ++bj) { const int cc = colp + bj * HALF;
;                     f32x4 sq0 = {0.f, 0.f, 0.f, 0.f}, sq1 = {0.f, 0.f, 0.f, 0.f};
;                     ROWS8 { const int r = row0 + ai * HALF + m * 16; f32x4 v0 = acc[ai][bj][m][0] * rsc[bj][0], v1 = acc[ai][bj][m][1] * rsc[bj][1];
;                         v0[0] = gelu_tanh(v0[0]); v0[1] = gelu_tanh(v0[1]); v0[2] = gelu_tanh(v0[2]); v0[3] = gelu_tanh(v0[3]);
;                         v1[0] = gelu_tanh(v1[0]); v1[1] = gelu_tanh(v1[1]); v1[2] = gelu_tanh(v1[2]); v1[3] = gelu_tanh(v1[3]);
;                         sq0 += v0 * v0; sq1 += v1 * v1; *(u32x4*)(WSB(OFF_VT) + (size_t)r * 8192 + cc) = PK8(v0, v1); }
; #pragma unroll
;                     for (int j = 0; j < 8; ++j) { float t = j < 4 ? sq0[j & 3] : sq1[j & 3];
;                         t += __shfl_xor(t, 1); t += __shfl_xor(t, 2); t += __shfl_xor(t, 4); t += __shfl_xor(t, 8);
;                         if (fr == 0) unsafeAtomicAdd(ssqv + cc + j, t); }
	v_mul_f32_e32 v243, 0xbfb8aa3b, v243
	v_mul_f32_e32 v244, v237, v244
	v_mul_f32_e32 v221, 0xbfb8aa3b, v221
	v_mul_f32_e32 v222, 0xbfb8aa3b, v222
	v_exp_f32_e32 v243, v243
	v_mul_f32_e32 v244, 0xbfb8aa3b, v244
	v_exp_f32_e32 v221, v221
	v_exp_f32_e32 v222, v222
	v_exp_f32_e32 v245, v244
	v_add_f32_e32 v243, 1.0, v243
	v_add_f32_e32 v221, 1.0, v221
	v_add_f32_e32 v222, 1.0, v222
	v_rcp_f32_e32 v244, v243
	v_add_f32_e32 v243, 1.0, v245
	v_rcp_f32_e32 v220, v220
	v_rcp_f32_e32 v221, v221
	v_rcp_f32_e32 v245, v243
	v_rcp_f32_e32 v243, v222
	v_mul_f32_e32 v240, v214, v240
	v_mul_f32_e32 v241, v215, v241
	v_mul_f32_e32 v220, v218, v220
	v_mul_f32_e32 v221, v219, v221
	v_mul_f32_e32 v214, v236, v244
	v_mul_f32_e32 v215, v237, v245
	v_mul_f32_e32 v218, v238, v242
	v_mul_f32_e32 v219, v239, v243
	v_fma_f32 v238, v240, v240, v234
	v_fma_f32 v239, v241, v241, v235
	v_cvt_pk_bf16_f32 v234, v240, v241
	v_add_co_u32_e32 v240, vcc, s71, v138
	v_mul_f32_e32 v190, v12, v190
	v_mul_f32_e32 v191, v13, v191
	v_cvt_pk_bf16_f32 v235, v220, v221
	v_cvt_pk_bf16_f32 v236, v218, v219
	v_cvt_pk_bf16_f32 v237, v214, v215
	v_addc_co_u32_e32 v241, vcc, 0, v139, vcc
	v_mul_f32_e32 v222, 0x3d922279, v190
	global_store_dwordx4 v[240:241], v[234:237], off
	v_fmaak_f32 v222, v190, v222, 0x3fcc422a
	v_mul_f32_e32 v222, v190, v222
	v_mul_f32_e32 v234, 0x3d922279, v191
	v_fmaak_f32 v234, v191, v234, 0x3fcc422a
	v_mul_f32_e32 v222, 0xbfb8aa3b, v222
	v_mul_f32_e32 v234, v191, v234
	v_exp_f32_e32 v222, v222
	v_mul_f32_e32 v234, 0xbfb8aa3b, v234
	v_exp_f32_e32 v235, v234
	v_mul_f32_e32 v186, v14, v186
	v_mul_f32_e32 v187, v15, v187
	v_add_f32_e32 v222, 1.0, v222
	v_rcp_f32_e32 v234, v222
	v_add_f32_e32 v222, 1.0, v235
	v_mul_f32_e32 v235, 0x3d922279, v186
	v_fmaak_f32 v235, v186, v235, 0x3fcc422a
	v_mul_f32_e32 v235, v186, v235
	v_mul_f32_e32 v235, 0xbfb8aa3b, v235
	v_exp_f32_e32 v236, v235
	v_mul_f32_e32 v235, 0x3d922279, v187
	v_fmaak_f32 v235, v187, v235, 0x3fcc422a
	v_mul_f32_e32 v235, v187, v235
	v_mul_f32_e32 v235, 0xbfb8aa3b, v235
	v_exp_f32_e32 v237, v235
	v_rcp_f32_e32 v235, v222
	v_mul_f32_e32 v240, v8, v182
	v_mul_f32_e32 v241, v9, v183
	v_mul_f32_e32 v184, v10, v184
	v_mul_f32_e32 v185, v11, v185
	v_mul_f32_e32 v182, 0x3d922279, v240
	v_mul_f32_e32 v234, v190, v234
	v_mul_f32_e32 v235, v191, v235
	v_fmaak_f32 v182, v240, v182, 0x3fcc422a
	v_mul_f32_e32 v190, 0x3d922279, v184
	v_mul_f32_e32 v182, v240, v182
	v_fmaak_f32 v190, v184, v190, 0x3fcc422a
	v_add_f32_e32 v222, 1.0, v236
	v_mul_f32_e32 v182, 0xbfb8aa3b, v182
	v_mul_f32_e32 v190, v184, v190
	v_rcp_f32_e32 v236, v222
	v_add_f32_e32 v222, 1.0, v237
	v_exp_f32_e32 v182, v182
	v_mul_f32_e32 v190, 0xbfb8aa3b, v190
	v_rcp_f32_e32 v237, v222
	v_exp_f32_e32 v190, v190
	v_mul_f32_e32 v183, 0x3d922279, v241
	v_fmaak_f32 v183, v241, v183, 0x3fcc422a
	v_add_f32_e32 v182, 1.0, v182
	v_mul_f32_e32 v186, v186, v236
	v_mul_f32_e32 v187, v187, v237
	v_mul_f32_e32 v183, v241, v183
	v_rcp_f32_e32 v236, v182
	v_add_f32_e32 v182, 1.0, v190
	v_fma_f32 v190, v234, v234, v238
	v_fma_f32 v191, v235, v235, v239
	v_mul_f32_e32 v183, 0xbfb8aa3b, v183
	ds_bpermute_b32 v238, v226, v190
	v_exp_f32_e32 v183, v183
	v_rcp_f32_e32 v182, v182
	v_add_f32_e32 v222, 1.0, v183
	v_mul_f32_e32 v183, 0x3d922279, v185
	s_waitcnt lgkmcnt(0)
	v_add_f32_e32 v190, v190, v238
	v_fmaak_f32 v183, v185, v183, 0x3fcc422a
	v_rcp_f32_e32 v237, v222
	ds_bpermute_b32 v222, v227, v190
	v_mul_f32_e32 v183, v185, v183
	v_mul_f32_e32 v183, 0xbfb8aa3b, v183
	v_exp_f32_e32 v183, v183
	s_waitcnt lgkmcnt(0)
	v_add_f32_e32 v190, v190, v222
	ds_bpermute_b32 v222, v228, v190
	v_add_f32_e32 v183, 1.0, v183
	v_rcp_f32_e32 v183, v183
	s_waitcnt lgkmcnt(0)
	v_add_f32_e32 v190, v190, v222
	v_mul_f32_e32 v182, v184, v182
	v_mul_f32_e32 v183, v185, v183
	v_mul_f32_e32 v184, v240, v236
	v_mul_f32_e32 v185, v241, v237
	v_cvt_pk_bf16_f32 v236, v234, v235
	ds_bpermute_b32 v234, v229, v190
	v_add_co_u32_e32 v240, vcc, 0x2c0000, v138
	v_cvt_pk_bf16_f32 v237, v186, v187
	v_cvt_pk_bf16_f32 v238, v184, v185
	v_cvt_pk_bf16_f32 v239, v182, v183
	v_addc_co_u32_e32 v241, vcc, 0, v139, vcc
	global_store_dwordx4 v[240:241], v[236:239], off
	s_and_saveexec_b64 s[4:5], s[2:3]
	s_cbranch_execz .LBB0_331
	s_waitcnt lgkmcnt(0)
	v_add_f32_e32 v190, v190, v234
	global_atomic_add_f32 v[136:137], v190, off
.LBB0_331:
	s_or_b64 exec, exec, s[4:5]
	ds_bpermute_b32 v190, v226, v191
	s_waitcnt lgkmcnt(0)
	v_add_f32_e32 v190, v191, v190
	ds_bpermute_b32 v191, v227, v190
	s_waitcnt lgkmcnt(0)
	v_add_f32_e32 v222, v190, v191
	ds_bpermute_b32 v234, v228, v222
	v_mul_f32_e32 v190, v192, v192
	v_mul_f32_e32 v191, v193, v193
	s_nop 0
	v_fma_f32 v178, v178, v178, v190
	v_fma_f32 v179, v179, v179, v191
	s_waitcnt lgkmcnt(0)
	v_add_f32_e32 v190, v222, v234
	v_fma_f32 v178, v198, v198, v178
	v_fma_f32 v179, v199, v199, v179
	ds_bpermute_b32 v191, v229, v190
	v_fma_f32 v178, v204, v204, v178
	v_fma_f32 v179, v205, v205, v179
	s_nop 0
	v_fma_f32 v178, v210, v210, v178
	v_fma_f32 v179, v211, v211, v179
	s_nop 0
	v_fma_f32 v178, v216, v216, v178
	v_fma_f32 v179, v217, v217, v179
	s_nop 0
	v_fma_f32 v178, v220, v220, v178
	v_fma_f32 v179, v221, v221, v179
	s_nop 0
	v_fma_f32 v178, v186, v186, v178
	v_fma_f32 v179, v187, v187, v179
	s_and_saveexec_b64 s[4:5], s[2:3]
	s_cbranch_execz .LBB0_333
	s_waitcnt lgkmcnt(0)
	v_add_f32_e32 v186, v190, v191
	global_atomic_add_f32 v[136:137], v186, off offset:4

; DI float gelu_tanh(float x) { const float t = x * (1.5957691216f + 0.0713548163f * x * x); return x * __builtin_amdgcn_rcpf(1.f + __builtin_amdgcn_exp2f(-1.4426950409f * t)); }
; #define ROWS8 _Pragma("unroll") for (int ai = 0; ai < 2; ++ai) _Pragma("unroll") for (int m = 0; m < 4; ++m) if (ai == 0 || !hf)
; #define PK8(v0, v1) ({ const u32x2 h0_ = pk4(v0), h1_ = pk4(v1); (u32x4){h0_.x, h0_.y, h1_.x, h1_.y}; })
;     DI void operator()(const Acc& acc, const Unit& u, int wr, int wc, int fr, int fq) const {
;     ...
;                 for (int bj = 0; bj < 2; ++bj) { const int cc = colp + bj * HALF;
;                     f32x4 sq0 = {0.f, 0.f, 0.f, 0.f}, sq1 = {0.f, 0.f, 0.f, 0.f};
;                     ROWS8 { const int r = row0 + ai * HALF + m * 16; f32x4 v0 = acc[ai][bj][m][0] * rsc[bj][0], v1 = acc[ai][bj][m][1] * rsc[bj][1];
;                         v0[0] = gelu_tanh(v0[0]); v0[1] = gelu_tanh(v0[1]); v0[2] = gelu_tanh(v0[2]); v0[3] = gelu_tanh(v0[3]);
;                         v1[0] = gelu_tanh(v1[0]); v1[1] = gelu_tanh(v1[1]); v1[2] = gelu_tanh(v1[2]); v1[3] = gelu_tanh(v1[3]);
;                         sq0 += v0 * v0; sq1 += v1 * v1; *(u32x4*)(WSB(OFF_VT) + (size_t)r * 8192 + cc) = PK8(v0, v1); }
; #pragma unroll
;                     for (int j = 0; j < 8; ++j) { float t = j < 4 ? sq0[j & 3] : sq1[j & 3];
;                         t += __shfl_xor(t, 1); t += __shfl_xor(t, 2); t += __shfl_xor(t, 4); t += __shfl_xor(t, 8);
;                         if (fr == 0) unsafeAtomicAdd(ssqv + cc + j, t); }
.LBB0_337:
	s_or_b64 exec, exec, s[4:5]
	s_waitcnt lgkmcnt(0)
	v_mul_f32_e32 v178, v180, v180
	v_mul_f32_e32 v179, v181, v181
	s_nop 0
	v_fma_f32 v174, v174, v174, v178
	v_fma_f32 v175, v175, v175, v179
	s_nop 0
	v_fma_f32 v174, v194, v194, v174
	v_fma_f32 v175, v195, v195, v175
	s_nop 0
	v_fma_f32 v174, v200, v200, v174
	v_fma_f32 v175, v201, v201, v175
	s_nop 0
	v_fma_f32 v174, v206, v206, v174
	v_fma_f32 v175, v207, v207, v175
	s_nop 0
	v_fma_f32 v174, v212, v212, v174
	v_fma_f32 v175, v213, v213, v175
	s_nop 0
	v_fma_f32 v174, v218, v218, v174
	v_fma_f32 v175, v219, v219, v175
	s_nop 0
	v_fma_f32 v174, v184, v184, v174
	v_fma_f32 v175, v185, v185, v175
	ds_bpermute_b32 v178, v226, v174
	s_waitcnt lgkmcnt(0)
	v_add_f32_e32 v174, v174, v178
	ds_bpermute_b32 v178, v227, v174
	s_waitcnt lgkmcnt(0)
	v_add_f32_e32 v174, v174, v178
	ds_bpermute_b32 v178, v228, v174
	s_waitcnt lgkmcnt(0)
	v_add_f32_e32 v174, v174, v178
	ds_bpermute_b32 v178, v229, v174
	s_and_saveexec_b64 s[4:5], s[2:3]
	s_cbranch_execz .LBB0_339
	s_waitcnt lgkmcnt(0)
	v_add_f32_e32 v174, v174, v178
	global_atomic_add_f32 v[136:137], v174, off offset:16
.LBB0_339:
	s_or_b64 exec, exec, s[4:5]
	ds_bpermute_b32 v174, v226, v175
	s_waitcnt lgkmcnt(0)
	v_add_f32_e32 v174, v175, v174
	ds_bpermute_b32 v175, v227, v174
	s_waitcnt lgkmcnt(0)
	v_add_f32_e32 v178, v174, v175
	ds_bpermute_b32 v179, v228, v178
	v_mul_f32_e32 v174, v176, v176
	v_mul_f32_e32 v175, v177, v177
	s_nop 0
	v_fma_f32 v172, v172, v172, v174
	v_fma_f32 v173, v173, v173, v175
	s_waitcnt lgkmcnt(0)
	v_add_f32_e32 v174, v178, v179
	v_fma_f32 v172, v188, v188, v172
	v_fma_f32 v173, v189, v189, v173
	ds_bpermute_b32 v175, v229, v174
	v_fma_f32 v172, v196, v196, v172
	v_fma_f32 v173, v197, v197, v173
	s_nop 0
	v_fma_f32 v172, v202, v202, v172
	v_fma_f32 v173, v203, v203, v173
	s_nop 0
	v_fma_f32 v172, v208, v208, v172
	v_fma_f32 v173, v209, v209, v173
	s_nop 0
	v_fma_f32 v172, v214, v214, v172
	v_fma_f32 v173, v215, v215, v173
	s_nop 0
	v_fma_f32 v172, v182, v182, v172
	v_fma_f32 v173, v183, v183, v173
	s_and_saveexec_b64 s[4:5], s[2:3]
	s_cbranch_execz .LBB0_341
	s_waitcnt lgkmcnt(0)
	v_add_f32_e32 v174, v174, v175
	global_atomic_add_f32 v[136:137], v174, off offset:20

; DI float gelu_tanh(float x) { const float t = x * (1.5957691216f + 0.0713548163f * x * x); return x * __builtin_amdgcn_rcpf(1.f + __builtin_amdgcn_exp2f(-1.4426950409f * t)); }
; #define ROWS8 _Pragma("unroll") for (int ai = 0; ai < 2; ++ai) _Pragma("unroll") for (int m = 0; m < 4; ++m) if (ai == 0 || !hf)
; #define PK8(v0, v1) ({ const u32x2 h0_ = pk4(v0), h1_ = pk4(v1); (u32x4){h0_.x, h0_.y, h1_.x, h1_.y}; })
; #define LOAD_COLP_RS(rsc, ssqp, invn) f32x4 rsc[2][2]; COLS4 rsc[bj][n] = *(const f32x4*)((ssqp) + colp + bj * HALF + n * 4); \
;         COLS4 rsc[bj][n] = (f32x4){rstd_of(rsc[bj][n][0], invn), rstd_of(rsc[bj][n][1], invn), rstd_of(rsc[bj][n][2], invn), rstd_of(rsc[bj][n][3], invn)}
;     DI void operator()(const Acc& acc, const Unit& u, int wr, int wc, int fr, int fq) const {
;     ...
;                 float* ssqv = SSQ(1 + sqo);
;                 LOAD_COLP_RS(rsc, SSQ(0), 1.f / 2048.f);
; #pragma unroll
;                 for (int bj = 0; bj < 2; ++bj) { const int cc = colp + bj * HALF;
;                     f32x4 sq0 = {0.f, 0.f, 0.f, 0.f}, sq1 = {0.f, 0.f, 0.f, 0.f};
;                     ROWS8 { const int r = row0 + ai * HALF + m * 16; f32x4 v0 = acc[ai][bj][m][0] * rsc[bj][0], v1 = acc[ai][bj][m][1] * rsc[bj][1];
;                         v0[0] = gelu_tanh(v0[0]); v0[1] = gelu_tanh(v0[1]); v0[2] = gelu_tanh(v0[2]); v0[3] = gelu_tanh(v0[3]);
;                         v1[0] = gelu_tanh(v1[0]); v1[1] = gelu_tanh(v1[1]); v1[2] = gelu_tanh(v1[2]); v1[3] = gelu_tanh(v1[3]);
;                         sq0 += v0 * v0; sq1 += v1 * v1; *(u32x4*)(WSB(OFF_VT) + (size_t)r * 8192 + cc) = PK8(v0, v1); }
.LBB0_345:
	s_or_b64 exec, exec, s[4:5]
	v_fmamk_f32 v132, v132, 0x3a000000, v233
	v_rsq_f32_e32 v176, v132
	v_fmamk_f32 v132, v133, 0x3a000000, v233
	v_rsq_f32_e32 v177, v132
	v_fmamk_f32 v128, v128, 0x3a000000, v233
	v_rsq_f32_e32 v174, v128
	v_fmamk_f32 v128, v129, 0x3a000000, v233
	v_rsq_f32_e32 v175, v128
	v_fmamk_f32 v128, v130, 0x3a000000, v233
	v_fmamk_f32 v132, v134, 0x3a000000, v233
	v_rsq_f32_e32 v182, v128
	v_fmamk_f32 v128, v131, 0x3a000000, v233
	v_rsq_f32_e32 v180, v132
	v_fmamk_f32 v132, v135, 0x3a000000, v233
	v_rsq_f32_e32 v183, v128
	v_mul_f32_e32 v128, v116, v176
	v_mul_f32_e32 v129, v117, v177
	v_rsq_f32_e32 v181, v132
	v_mul_f32_e32 v130, 0x3d922279, v128
	v_fmaak_f32 v130, v128, v130, 0x3fcc422a
	v_mul_f32_e32 v130, v128, v130
	v_mul_f32_e32 v130, 0xbfb8aa3b, v130
	v_exp_f32_e32 v134, v130
	v_mul_f32_e32 v130, v118, v180
	v_mul_f32_e32 v131, v119, v181
	v_mul_f32_e32 v135, 0x3d922279, v129
	v_fmaak_f32 v135, v129, v135, 0x3fcc422a
	v_mul_f32_e32 v188, 0x3d922279, v130
	v_mul_f32_e32 v135, v129, v135
	v_fmaak_f32 v188, v130, v188, 0x3fcc422a
	v_mul_f32_e32 v135, 0xbfb8aa3b, v135
	v_mul_f32_e32 v188, v130, v188
	v_exp_f32_e32 v135, v135
	v_mul_f32_e32 v188, 0xbfb8aa3b, v188
	v_exp_f32_e32 v190, v188
	v_add_f32_e32 v134, 1.0, v134
	v_mul_f32_e32 v132, v114, v182
	v_mul_f32_e32 v133, v115, v183
	v_mul_f32_e32 v184, v112, v174
	v_mul_f32_e32 v185, v113, v175
	v_rcp_f32_e32 v188, v134
	v_add_f32_e32 v134, 1.0, v135
	v_rcp_f32_e32 v189, v134
	v_add_f32_e32 v134, 1.0, v190
	v_mul_f32_e32 v135, 0x3d922279, v131
	v_mul_f32_e32 v190, 0x3d922279, v184
	v_mul_f32_e32 v191, 0x3d922279, v185
	v_mul_f32_e32 v194, 0x3d922279, v132
	v_mul_f32_e32 v195, 0x3d922279, v133
	v_fmaak_f32 v135, v131, v135, 0x3fcc422a
	v_fmaak_f32 v190, v184, v190, 0x3fcc422a
	v_fmaak_f32 v191, v185, v191, 0x3fcc422a
	v_fmaak_f32 v194, v132, v194, 0x3fcc422a
	v_fmaak_f32 v195, v133, v195, 0x3fcc422a
	v_mul_f32_e32 v135, v131, v135
	v_mul_f32_e32 v190, v184, v190
	v_mul_f32_e32 v191, v185, v191
	v_mul_f32_e32 v194, v132, v194
	v_mul_f32_e32 v195, v133, v195
	v_mul_f32_e32 v135, 0xbfb8aa3b, v135
	v_mul_f32_e32 v190, 0xbfb8aa3b, v190
	v_mul_f32_e32 v191, 0xbfb8aa3b, v191
	v_mul_f32_e32 v194, 0xbfb8aa3b, v194
	v_mul_f32_e32 v195, 0xbfb8aa3b, v195
	v_exp_f32_e32 v135, v135
	v_exp_f32_e32 v190, v190
	v_exp_f32_e32 v191, v191
	v_exp_f32_e32 v194, v194
	v_exp_f32_e32 v195, v195
	v_add_f32_e32 v135, 1.0, v135
	v_add_f32_e32 v190, 1.0, v190
	v_add_f32_e32 v191, 1.0, v191
	v_add_f32_e32 v194, 1.0, v194
	v_add_f32_e32 v195, 1.0, v195
	v_rcp_f32_e32 v134, v134
	v_rcp_f32_e32 v135, v135
	v_rcp_f32_e32 v190, v190
	v_rcp_f32_e32 v194, v194
	v_rcp_f32_e32 v195, v195
	v_rcp_f32_e32 v191, v191
	v_mul_f32_e32 v134, v130, v134
	v_mul_f32_e32 v135, v131, v135
	v_mul_f32_e32 v198, v128, v188
	v_mul_f32_e32 v199, v129, v189
	v_mul_f32_e32 v128, v132, v194
	v_mul_f32_e32 v129, v133, v195
	v_mul_f32_e32 v130, v184, v190
	v_mul_f32_e32 v131, v185, v191
	v_cvt_pk_bf16_f32 v188, v198, v199
	v_cvt_pk_bf16_f32 v189, v134, v135
	v_cvt_pk_bf16_f32 v190, v130, v131
	v_cvt_pk_bf16_f32 v191, v128, v129
	v_mul_f32_e32 v132, v100, v176
	v_mul_f32_e32 v133, v101, v177
	v_lshl_add_u64 v[192:193], v[138:139], 0, s[24:25]
	v_lshl_add_u64 v[186:187], v[138:139], 0, s[26:27]
	v_lshl_add_u64 v[178:179], v[138:139], 0, s[28:29]
	s_waitcnt lgkmcnt(0)
	v_lshl_add_u64 v[172:173], v[138:139], 0, s[30:31]
	global_store_dwordx4 v[138:139], v[188:191], off offset:256
	v_mul_f32_e32 v138, 0x3d922279, v132
	v_fmaak_f32 v138, v132, v138, 0x3fcc422a
	v_mul_f32_e32 v138, v132, v138
	v_mul_f32_e32 v138, 0xbfb8aa3b, v138
	v_exp_f32_e32 v184, v138
	v_mul_f32_e32 v138, v102, v180
	v_mul_f32_e32 v139, v103, v181
	v_mul_f32_e32 v185, 0x3d922279, v133
	v_fmaak_f32 v185, v133, v185, 0x3fcc422a
	v_mul_f32_e32 v194, 0x3d922279, v138
	v_mul_f32_e32 v185, v133, v185
	v_fmaak_f32 v194, v138, v194, 0x3fcc422a
	v_mul_f32_e32 v185, 0xbfb8aa3b, v185
	v_mul_f32_e32 v194, v138, v194
	v_exp_f32_e32 v185, v185
	v_mul_f32_e32 v194, 0xbfb8aa3b, v194
	v_exp_f32_e32 v196, v194
	v_add_f32_e32 v184, 1.0, v184
	v_mul_f32_e32 v188, v98, v182
	v_mul_f32_e32 v189, v99, v183
	v_mul_f32_e32 v190, v96, v174
	v_mul_f32_e32 v191, v97, v175
	v_rcp_f32_e32 v194, v184
	v_add_f32_e32 v184, 1.0, v185
	v_rcp_f32_e32 v195, v184
	v_add_f32_e32 v184, 1.0, v196
	v_mul_f32_e32 v185, 0x3d922279, v139
	v_mul_f32_e32 v196, 0x3d922279, v190
	v_mul_f32_e32 v197, 0x3d922279, v191
	v_mul_f32_e32 v200, 0x3d922279, v188
	v_mul_f32_e32 v201, 0x3d922279, v189
	v_fmaak_f32 v185, v139, v185, 0x3fcc422a
	v_fmaak_f32 v196, v190, v196, 0x3fcc422a
	v_fmaak_f32 v197, v191, v197, 0x3fcc422a
	v_fmaak_f32 v200, v188, v200, 0x3fcc422a
	v_fmaak_f32 v201, v189, v201, 0x3fcc422a
	v_mul_f32_e32 v185, v139, v185
	v_mul_f32_e32 v196, v190, v196
	v_mul_f32_e32 v197, v191, v197
	v_mul_f32_e32 v200, v188, v200
	v_mul_f32_e32 v201, v189, v201
	v_mul_f32_e32 v185, 0xbfb8aa3b, v185
	v_mul_f32_e32 v196, 0xbfb8aa3b, v196
	v_mul_f32_e32 v197, 0xbfb8aa3b, v197
	v_mul_f32_e32 v200, 0xbfb8aa3b, v200
	v_mul_f32_e32 v201, 0xbfb8aa3b, v201
	v_exp_f32_e32 v185, v185
	v_exp_f32_e32 v196, v196
	v_exp_f32_e32 v197, v197
	v_exp_f32_e32 v200, v200
	v_exp_f32_e32 v201, v201
	v_add_f32_e32 v185, 1.0, v185
	v_add_f32_e32 v196, 1.0, v196
	v_add_f32_e32 v197, 1.0, v197
	v_add_f32_e32 v200, 1.0, v200
	v_add_f32_e32 v201, 1.0, v201
	v_rcp_f32_e32 v184, v184
	v_rcp_f32_e32 v185, v185
	v_rcp_f32_e32 v196, v196
	v_rcp_f32_e32 v200, v200
	v_rcp_f32_e32 v201, v201
	v_rcp_f32_e32 v197, v197
	v_mul_f32_e32 v184, v138, v184
	v_mul_f32_e32 v185, v139, v185
	v_mul_f32_e32 v204, v132, v194
	v_mul_f32_e32 v205, v133, v195
; DI float gelu_tanh(float x) { const float t = x * (1.5957691216f + 0.0713548163f * x * x); return x * __builtin_amdgcn_rcpf(1.f + __builtin_amdgcn_exp2f(-1.4426950409f * t)); }
; #define ROWS8 _Pragma("unroll") for (int ai = 0; ai < 2; ++ai) _Pragma("unroll") for (int m = 0; m < 4; ++m) if (ai == 0 || !hf)
; #define PK8(v0, v1) ({ const u32x2 h0_ = pk4(v0), h1_ = pk4(v1); (u32x4){h0_.x, h0_.y, h1_.x, h1_.y}; })
; #define LOAD_COLP_RS(rsc, ssqp, invn) f32x4 rsc[2][2]; COLS4 rsc[bj][n] = *(const f32x4*)((ssqp) + colp + bj * HALF + n * 4); \
;         COLS4 rsc[bj][n] = (f32x4){rstd_of(rsc[bj][n][0], invn), rstd_of(rsc[bj][n][1], invn), rstd_of(rsc[bj][n][2], invn), rstd_of(rsc[bj][n][3], invn)}
;     DI void operator()(const Acc& acc, const Unit& u, int wr, int wc, int fr, int fq) const {
;     ...
;                 float* ssqv = SSQ(1 + sqo);
;                 LOAD_COLP_RS(rsc, SSQ(0), 1.f / 2048.f);
; #pragma unroll
;                 for (int bj = 0; bj < 2; ++bj) { const int cc = colp + bj * HALF;
;                     f32x4 sq0 = {0.f, 0.f, 0.f, 0.f}, sq1 = {0.f, 0.f, 0.f, 0.f};
;                     ROWS8 { const int r = row0 + ai * HALF + m * 16; f32x4 v0 = acc[ai][bj][m][0] * rsc[bj][0], v1 = acc[ai][bj][m][1] * rsc[bj][1];
;                         v0[0] = gelu_tanh(v0[0]); v0[1] = gelu_tanh(v0[1]); v0[2] = gelu_tanh(v0[2]); v0[3] = gelu_tanh(v0[3]);
;                         v1[0] = gelu_tanh(v1[0]); v1[1] = gelu_tanh(v1[1]); v1[2] = gelu_tanh(v1[2]); v1[3] = gelu_tanh(v1[3]);
;                         sq0 += v0 * v0; sq1 += v1 * v1; *(u32x4*)(WSB(OFF_VT) + (size_t)r * 8192 + cc) = PK8(v0, v1); }
	v_mul_f32_e32 v132, v188, v200
	v_mul_f32_e32 v133, v189, v201
	v_mul_f32_e32 v138, v190, v196
	v_mul_f32_e32 v139, v191, v197
	v_cvt_pk_bf16_f32 v188, v204, v205
	v_cvt_pk_bf16_f32 v189, v184, v185
	v_cvt_pk_bf16_f32 v190, v138, v139
	v_cvt_pk_bf16_f32 v191, v132, v133
	global_store_dwordx4 v[166:167], v[188:191], off offset:256
	v_mul_f32_e32 v166, v84, v176
	v_mul_f32_e32 v167, v85, v177
	v_mul_f32_e32 v194, v82, v182
	v_mul_f32_e32 v195, v83, v183
	v_mul_f32_e32 v188, 0x3d922279, v166
	v_fmaak_f32 v188, v166, v188, 0x3fcc422a
	v_mul_f32_e32 v188, v166, v188
	v_mul_f32_e32 v188, 0xbfb8aa3b, v188
	v_exp_f32_e32 v190, v188
	v_mul_f32_e32 v188, v86, v180
	v_mul_f32_e32 v189, v87, v181
	v_mul_f32_e32 v191, 0x3d922279, v167
	v_fmaak_f32 v191, v167, v191, 0x3fcc422a
	v_mul_f32_e32 v200, 0x3d922279, v188
	v_mul_f32_e32 v191, v167, v191
	v_fmaak_f32 v200, v188, v200, 0x3fcc422a
	v_mul_f32_e32 v191, 0xbfb8aa3b, v191
	v_mul_f32_e32 v200, v188, v200
	v_exp_f32_e32 v191, v191
	v_mul_f32_e32 v200, 0xbfb8aa3b, v200
	v_exp_f32_e32 v202, v200
	v_add_f32_e32 v190, 1.0, v190
	v_mul_f32_e32 v196, v80, v174
	v_mul_f32_e32 v197, v81, v175
	v_rcp_f32_e32 v200, v190
	v_add_f32_e32 v190, 1.0, v191
	v_rcp_f32_e32 v201, v190
	v_add_f32_e32 v190, 1.0, v202
	v_mul_f32_e32 v191, 0x3d922279, v189
	v_mul_f32_e32 v202, 0x3d922279, v196
	v_mul_f32_e32 v203, 0x3d922279, v197
	v_mul_f32_e32 v206, 0x3d922279, v194
	v_mul_f32_e32 v207, 0x3d922279, v195
	v_fmaak_f32 v191, v189, v191, 0x3fcc422a
	v_fmaak_f32 v202, v196, v202, 0x3fcc422a
	v_fmaak_f32 v203, v197, v203, 0x3fcc422a
	v_fmaak_f32 v206, v194, v206, 0x3fcc422a
	v_fmaak_f32 v207, v195, v207, 0x3fcc422a
	v_mul_f32_e32 v191, v189, v191
	v_mul_f32_e32 v202, v196, v202
	v_mul_f32_e32 v203, v197, v203
	v_mul_f32_e32 v206, v194, v206
	v_mul_f32_e32 v207, v195, v207
	v_mul_f32_e32 v191, 0xbfb8aa3b, v191
	v_mul_f32_e32 v202, 0xbfb8aa3b, v202
	v_mul_f32_e32 v203, 0xbfb8aa3b, v203
	v_mul_f32_e32 v206, 0xbfb8aa3b, v206
	v_mul_f32_e32 v207, 0xbfb8aa3b, v207
	v_exp_f32_e32 v191, v191
	v_exp_f32_e32 v202, v202
	v_exp_f32_e32 v203, v203
	v_exp_f32_e32 v206, v206
	v_exp_f32_e32 v207, v207
	v_add_f32_e32 v191, 1.0, v191
	v_add_f32_e32 v202, 1.0, v202
	v_add_f32_e32 v203, 1.0, v203
	v_add_f32_e32 v206, 1.0, v206
	v_add_f32_e32 v207, 1.0, v207
	v_rcp_f32_e32 v190, v190
	v_rcp_f32_e32 v191, v191
	v_rcp_f32_e32 v202, v202
	v_rcp_f32_e32 v206, v206
	v_rcp_f32_e32 v207, v207
	v_rcp_f32_e32 v203, v203
	v_mul_f32_e32 v190, v188, v190
	v_mul_f32_e32 v191, v189, v191
	v_mul_f32_e32 v208, v166, v200
	v_mul_f32_e32 v209, v167, v201
	v_mul_f32_e32 v166, v194, v206
	v_mul_f32_e32 v167, v195, v207
	v_mul_f32_e32 v188, v196, v202
	v_mul_f32_e32 v189, v197, v203
	v_cvt_pk_bf16_f32 v194, v208, v209
	v_cvt_pk_bf16_f32 v195, v190, v191
	v_cvt_pk_bf16_f32 v196, v188, v189
	v_cvt_pk_bf16_f32 v197, v166, v167
	global_store_dwordx4 v[168:169], v[194:197], off offset:256
	v_mul_f32_e32 v168, v68, v176
	v_mul_f32_e32 v169, v69, v177
	v_mul_f32_e32 v200, v66, v182
	v_mul_f32_e32 v201, v67, v183
	v_mul_f32_e32 v194, 0x3d922279, v168
	v_fmaak_f32 v194, v168, v194, 0x3fcc422a
	v_mul_f32_e32 v194, v168, v194
	v_mul_f32_e32 v194, 0xbfb8aa3b, v194
	v_exp_f32_e32 v196, v194
	v_mul_f32_e32 v194, v70, v180
	v_mul_f32_e32 v195, v71, v181
	v_mul_f32_e32 v197, 0x3d922279, v169
	v_fmaak_f32 v197, v169, v197, 0x3fcc422a
	v_mul_f32_e32 v206, 0x3d922279, v194
	v_mul_f32_e32 v197, v169, v197
	v_fmaak_f32 v206, v194, v206, 0x3fcc422a
	v_mul_f32_e32 v197, 0xbfb8aa3b, v197
	v_mul_f32_e32 v206, v194, v206
	v_exp_f32_e32 v197, v197
	v_mul_f32_e32 v206, 0xbfb8aa3b, v206
	v_exp_f32_e32 v210, v206
	v_add_f32_e32 v196, 1.0, v196
	v_mul_f32_e32 v202, v64, v174
	v_mul_f32_e32 v203, v65, v175
	v_rcp_f32_e32 v206, v196
	v_add_f32_e32 v196, 1.0, v197
	v_rcp_f32_e32 v207, v196
	v_add_f32_e32 v196, 1.0, v210
	v_mul_f32_e32 v197, 0x3d922279, v195
	v_mul_f32_e32 v210, 0x3d922279, v202
	v_mul_f32_e32 v211, 0x3d922279, v203
	v_mul_f32_e32 v212, 0x3d922279, v200
	v_mul_f32_e32 v213, 0x3d922279, v201
	v_fmaak_f32 v197, v195, v197, 0x3fcc422a
	v_fmaak_f32 v210, v202, v210, 0x3fcc422a
	v_fmaak_f32 v211, v203, v211, 0x3fcc422a
	v_fmaak_f32 v212, v200, v212, 0x3fcc422a
	v_fmaak_f32 v213, v201, v213, 0x3fcc422a
	v_mul_f32_e32 v197, v195, v197
	v_mul_f32_e32 v210, v202, v210
	v_mul_f32_e32 v211, v203, v211
	v_mul_f32_e32 v212, v200, v212
	v_mul_f32_e32 v213, v201, v213
	v_mul_f32_e32 v197, 0xbfb8aa3b, v197
	v_mul_f32_e32 v210, 0xbfb8aa3b, v210
	v_mul_f32_e32 v211, 0xbfb8aa3b, v211
	v_mul_f32_e32 v212, 0xbfb8aa3b, v212
	v_mul_f32_e32 v213, 0xbfb8aa3b, v213
	v_exp_f32_e32 v197, v197
	v_exp_f32_e32 v210, v210
	v_exp_f32_e32 v211, v211
	v_exp_f32_e32 v212, v212
	v_exp_f32_e32 v213, v213
	v_add_f32_e32 v197, 1.0, v197
	v_add_f32_e32 v210, 1.0, v210
	v_add_f32_e32 v211, 1.0, v211
	v_add_f32_e32 v212, 1.0, v212
	v_add_f32_e32 v213, 1.0, v213
	v_rcp_f32_e32 v196, v196
	v_rcp_f32_e32 v197, v197
	v_rcp_f32_e32 v210, v210
	v_rcp_f32_e32 v212, v212
	v_rcp_f32_e32 v213, v213
	v_rcp_f32_e32 v211, v211
	v_mul_f32_e32 v196, v194, v196
	v_mul_f32_e32 v197, v195, v197
	v_mul_f32_e32 v206, v168, v206
	v_mul_f32_e32 v207, v169, v207
	v_mul_f32_e32 v168, v200, v212
	v_mul_f32_e32 v169, v201, v213
	v_mul_f32_e32 v194, v202, v210
	v_mul_f32_e32 v195, v203, v211
	v_cvt_pk_bf16_f32 v200, v206, v207
	v_cvt_pk_bf16_f32 v201, v196, v197
	v_cvt_pk_bf16_f32 v202, v194, v195
	v_cvt_pk_bf16_f32 v203, v168, v169
	global_store_dwordx4 v[170:171], v[200:203], off offset:256
	v_mul_f32_e32 v170, v204, v204
	v_mul_f32_e32 v171, v205, v205
	v_mul_f32_e32 v204, v50, v182
	v_mul_f32_e32 v205, v51, v183
	v_fma_f32 v170, v198, v198, v170
; DI float gelu_tanh(float x) { const float t = x * (1.5957691216f + 0.0713548163f * x * x); return x * __builtin_amdgcn_rcpf(1.f + __builtin_amdgcn_exp2f(-1.4426950409f * t)); }
; #define ROWS8 _Pragma("unroll") for (int ai = 0; ai < 2; ++ai) _Pragma("unroll") for (int m = 0; m < 4; ++m) if (ai == 0 || !hf)
; #define PK8(v0, v1) ({ const u32x2 h0_ = pk4(v0), h1_ = pk4(v1); (u32x4){h0_.x, h0_.y, h1_.x, h1_.y}; })
;     DI void operator()(const Acc& acc, const Unit& u, int wr, int wc, int fr, int fq) const {
;     ...
;                     ROWS8 { const int r = row0 + ai * HALF + m * 16; f32x4 v0 = acc[ai][bj][m][0] * rsc[bj][0], v1 = acc[ai][bj][m][1] * rsc[bj][1];
;                         v0[0] = gelu_tanh(v0[0]); v0[1] = gelu_tanh(v0[1]); v0[2] = gelu_tanh(v0[2]); v0[3] = gelu_tanh(v0[3]);
;                         v1[0] = gelu_tanh(v1[0]); v1[1] = gelu_tanh(v1[1]); v1[2] = gelu_tanh(v1[2]); v1[3] = gelu_tanh(v1[3]);
;                         sq0 += v0 * v0; sq1 += v1 * v1; *(u32x4*)(WSB(OFF_VT) + (size_t)r * 8192 + cc) = PK8(v0, v1); }
	v_fma_f32 v171, v199, v199, v171
	v_mul_f32_e32 v212, 0x3d922279, v204
	v_fma_f32 v170, v208, v208, v170
	v_fma_f32 v171, v209, v209, v171
	v_mul_f32_e32 v213, 0x3d922279, v205
	v_fma_f32 v202, v206, v206, v170
	v_fma_f32 v203, v207, v207, v171
	v_mul_f32_e32 v170, v52, v176
	v_mul_f32_e32 v171, v53, v177
	v_mul_f32_e32 v206, v48, v174
	v_mul_f32_e32 v207, v49, v175
	v_mul_f32_e32 v198, 0x3d922279, v170
	v_fmaak_f32 v198, v170, v198, 0x3fcc422a
	v_mul_f32_e32 v198, v170, v198
	v_mul_f32_e32 v198, 0xbfb8aa3b, v198
	v_exp_f32_e32 v200, v198
	v_mul_f32_e32 v198, v54, v180
	v_mul_f32_e32 v199, v55, v181
	v_mul_f32_e32 v201, 0x3d922279, v171
	v_fmaak_f32 v201, v171, v201, 0x3fcc422a
	v_mul_f32_e32 v208, 0x3d922279, v198
	v_mul_f32_e32 v201, v171, v201
	v_fmaak_f32 v208, v198, v208, 0x3fcc422a
	v_mul_f32_e32 v201, 0xbfb8aa3b, v201
	v_mul_f32_e32 v208, v198, v208
	v_exp_f32_e32 v201, v201
	v_mul_f32_e32 v208, 0xbfb8aa3b, v208
	v_exp_f32_e32 v210, v208
	v_add_f32_e32 v200, 1.0, v200
	v_rcp_f32_e32 v208, v200
	v_add_f32_e32 v200, 1.0, v201
	v_rcp_f32_e32 v209, v200
	v_add_f32_e32 v200, 1.0, v210
	v_mul_f32_e32 v201, 0x3d922279, v199
	v_mul_f32_e32 v210, 0x3d922279, v206
	v_mul_f32_e32 v211, 0x3d922279, v207
	v_fmaak_f32 v201, v199, v201, 0x3fcc422a
	v_fmaak_f32 v210, v206, v210, 0x3fcc422a
	v_fmaak_f32 v211, v207, v211, 0x3fcc422a
	v_fmaak_f32 v212, v204, v212, 0x3fcc422a
	v_fmaak_f32 v213, v205, v213, 0x3fcc422a
	v_mul_f32_e32 v201, v199, v201
	v_mul_f32_e32 v210, v206, v210
	v_mul_f32_e32 v211, v207, v211
	v_mul_f32_e32 v212, v204, v212
	v_mul_f32_e32 v213, v205, v213
	v_mul_f32_e32 v201, 0xbfb8aa3b, v201
	v_mul_f32_e32 v210, 0xbfb8aa3b, v210
	v_mul_f32_e32 v211, 0xbfb8aa3b, v211
	v_mul_f32_e32 v212, 0xbfb8aa3b, v212
	v_mul_f32_e32 v213, 0xbfb8aa3b, v213
	v_exp_f32_e32 v201, v201
	v_exp_f32_e32 v210, v210
	v_exp_f32_e32 v211, v211
	v_exp_f32_e32 v212, v212
	v_exp_f32_e32 v213, v213
	v_add_f32_e32 v201, 1.0, v201
	v_add_f32_e32 v210, 1.0, v210
	v_add_f32_e32 v211, 1.0, v211
	v_add_f32_e32 v212, 1.0, v212
	v_add_f32_e32 v213, 1.0, v213
	v_rcp_f32_e32 v200, v200
	v_rcp_f32_e32 v201, v201
	v_rcp_f32_e32 v210, v210
	v_rcp_f32_e32 v212, v212
	v_rcp_f32_e32 v213, v213
	v_rcp_f32_e32 v211, v211
	v_mul_f32_e32 v200, v198, v200
	v_mul_f32_e32 v201, v199, v201
	v_mul_f32_e32 v208, v170, v208
	v_mul_f32_e32 v209, v171, v209
	v_mul_f32_e32 v170, v204, v212
	v_mul_f32_e32 v171, v205, v213
	v_mul_f32_e32 v198, v206, v210
	v_mul_f32_e32 v199, v207, v211
	v_fma_f32 v206, v208, v208, v202
	v_fma_f32 v207, v209, v209, v203
	v_cvt_pk_bf16_f32 v202, v208, v209
	v_cvt_pk_bf16_f32 v203, v200, v201
	v_cvt_pk_bf16_f32 v204, v198, v199
	v_cvt_pk_bf16_f32 v205, v170, v171
	global_store_dwordx4 v[192:193], v[202:205], off offset:256
	v_mul_f32_e32 v192, v36, v176
	v_mul_f32_e32 v193, v37, v177
	v_mul_f32_e32 v208, v34, v182
	v_mul_f32_e32 v209, v35, v183
	v_mul_f32_e32 v202, 0x3d922279, v192
	v_fmaak_f32 v202, v192, v202, 0x3fcc422a
	v_mul_f32_e32 v202, v192, v202
	v_mul_f32_e32 v202, 0xbfb8aa3b, v202
	v_exp_f32_e32 v204, v202
	v_mul_f32_e32 v202, v38, v180
	v_mul_f32_e32 v203, v39, v181
	v_mul_f32_e32 v210, v32, v174
	v_mul_f32_e32 v211, v33, v175
	v_mul_f32_e32 v205, 0x3d922279, v193
	v_mul_f32_e32 v212, 0x3d922279, v202
	v_mul_f32_e32 v213, 0x3d922279, v203
	v_mul_f32_e32 v214, 0x3d922279, v210
	v_mul_f32_e32 v215, 0x3d922279, v211
	v_mul_f32_e32 v216, 0x3d922279, v208
	v_mul_f32_e32 v217, 0x3d922279, v209
	v_fmaak_f32 v205, v193, v205, 0x3fcc422a
	v_fmaak_f32 v212, v202, v212, 0x3fcc422a
	v_fmaak_f32 v213, v203, v213, 0x3fcc422a
	v_fmaak_f32 v214, v210, v214, 0x3fcc422a
	v_fmaak_f32 v215, v211, v215, 0x3fcc422a
	v_fmaak_f32 v216, v208, v216, 0x3fcc422a
	v_fmaak_f32 v217, v209, v217, 0x3fcc422a
	v_mul_f32_e32 v205, v193, v205
	v_mul_f32_e32 v212, v202, v212
	v_mul_f32_e32 v213, v203, v213
	v_mul_f32_e32 v214, v210, v214
	v_mul_f32_e32 v215, v211, v215
	v_mul_f32_e32 v216, v208, v216
	v_mul_f32_e32 v217, v209, v217
	v_mul_f32_e32 v205, 0xbfb8aa3b, v205
	v_mul_f32_e32 v212, 0xbfb8aa3b, v212
	v_mul_f32_e32 v213, 0xbfb8aa3b, v213
	v_mul_f32_e32 v214, 0xbfb8aa3b, v214
	v_mul_f32_e32 v215, 0xbfb8aa3b, v215
	v_mul_f32_e32 v216, 0xbfb8aa3b, v216
	v_mul_f32_e32 v217, 0xbfb8aa3b, v217
	v_exp_f32_e32 v205, v205
	v_exp_f32_e32 v212, v212
	v_exp_f32_e32 v213, v213
	v_exp_f32_e32 v214, v214
	v_exp_f32_e32 v215, v215
	v_exp_f32_e32 v216, v216
	v_exp_f32_e32 v217, v217
	v_add_f32_e32 v204, 1.0, v204
	v_add_f32_e32 v205, 1.0, v205
	v_add_f32_e32 v212, 1.0, v212
	v_add_f32_e32 v213, 1.0, v213
	v_add_f32_e32 v214, 1.0, v214
	v_add_f32_e32 v215, 1.0, v215
	v_add_f32_e32 v216, 1.0, v216
	v_add_f32_e32 v217, 1.0, v217
	v_rcp_f32_e32 v204, v204
	v_rcp_f32_e32 v205, v205
	v_rcp_f32_e32 v212, v212
	v_rcp_f32_e32 v213, v213
	v_rcp_f32_e32 v214, v214
	v_rcp_f32_e32 v216, v216
	v_rcp_f32_e32 v217, v217
	v_rcp_f32_e32 v215, v215
	v_mul_f32_e32 v218, v192, v204
	v_mul_f32_e32 v219, v193, v205
	v_mul_f32_e32 v204, v202, v212
	v_mul_f32_e32 v205, v203, v213
	v_mul_f32_e32 v192, v208, v216
	v_mul_f32_e32 v193, v209, v217
	v_mul_f32_e32 v202, v210, v214
	v_mul_f32_e32 v203, v211, v215
	v_fma_f32 v210, v218, v218, v206
	v_fma_f32 v211, v219, v219, v207
	v_cvt_pk_bf16_f32 v206, v218, v219
	v_cvt_pk_bf16_f32 v207, v204, v205
	v_cvt_pk_bf16_f32 v208, v202, v203
	v_cvt_pk_bf16_f32 v209, v192, v193
	global_store_dwordx4 v[186:187], v[206:209], off offset:256
	v_mul_f32_e32 v186, v20, v176
	v_mul_f32_e32 v187, v21, v177
	v_mul_f32_e32 v212, v18, v182
	v_mul_f32_e32 v213, v19, v183
	v_mul_f32_e32 v206, 0x3d922279, v186
	v_fmaak_f32 v206, v186, v206, 0x3fcc422a
	v_mul_f32_e32 v206, v186, v206
; DI float gelu_tanh(float x) { const float t = x * (1.5957691216f + 0.0713548163f * x * x); return x * __builtin_amdgcn_rcpf(1.f + __builtin_amdgcn_exp2f(-1.4426950409f * t)); }
; #define ROWS8 _Pragma("unroll") for (int ai = 0; ai < 2; ++ai) _Pragma("unroll") for (int m = 0; m < 4; ++m) if (ai == 0 || !hf)
; #define PK8(v0, v1) ({ const u32x2 h0_ = pk4(v0), h1_ = pk4(v1); (u32x4){h0_.x, h0_.y, h1_.x, h1_.y}; })
;     DI void operator()(const Acc& acc, const Unit& u, int wr, int wc, int fr, int fq) const {
;     ...
;                     ROWS8 { const int r = row0 + ai * HALF + m * 16; f32x4 v0 = acc[ai][bj][m][0] * rsc[bj][0], v1 = acc[ai][bj][m][1] * rsc[bj][1];
;                         v0[0] = gelu_tanh(v0[0]); v0[1] = gelu_tanh(v0[1]); v0[2] = gelu_tanh(v0[2]); v0[3] = gelu_tanh(v0[3]);
;                         v1[0] = gelu_tanh(v1[0]); v1[1] = gelu_tanh(v1[1]); v1[2] = gelu_tanh(v1[2]); v1[3] = gelu_tanh(v1[3]);
;                         sq0 += v0 * v0; sq1 += v1 * v1; *(u32x4*)(WSB(OFF_VT) + (size_t)r * 8192 + cc) = PK8(v0, v1); }
; #pragma unroll
;                     for (int j = 0; j < 8; ++j) { float t = j < 4 ? sq0[j & 3] : sq1[j & 3];
;                         t += __shfl_xor(t, 1); t += __shfl_xor(t, 2); t += __shfl_xor(t, 4); t += __shfl_xor(t, 8);
;                         if (fr == 0) unsafeAtomicAdd(ssqv + cc + j, t); }
	v_mul_f32_e32 v206, 0xbfb8aa3b, v206
	v_exp_f32_e32 v208, v206
	v_mul_f32_e32 v206, v22, v180
	v_mul_f32_e32 v207, v23, v181
	v_mul_f32_e32 v209, 0x3d922279, v187
	v_fmaak_f32 v209, v187, v209, 0x3fcc422a
	v_mul_f32_e32 v216, 0x3d922279, v206
	v_mul_f32_e32 v209, v187, v209
	v_fmaak_f32 v216, v206, v216, 0x3fcc422a
	v_mul_f32_e32 v209, 0xbfb8aa3b, v209
	v_mul_f32_e32 v216, v206, v216
	v_exp_f32_e32 v209, v209
	v_mul_f32_e32 v216, 0xbfb8aa3b, v216
	v_exp_f32_e32 v218, v216
	v_add_f32_e32 v208, 1.0, v208
	v_mul_f32_e32 v214, v16, v174
	v_mul_f32_e32 v215, v17, v175
	v_rcp_f32_e32 v216, v208
	v_add_f32_e32 v208, 1.0, v209
	v_rcp_f32_e32 v217, v208
	v_add_f32_e32 v208, 1.0, v218
	v_mul_f32_e32 v209, 0x3d922279, v207
	v_mul_f32_e32 v218, 0x3d922279, v214
	v_mul_f32_e32 v219, 0x3d922279, v215
	v_mul_f32_e32 v220, 0x3d922279, v212
	v_mul_f32_e32 v221, 0x3d922279, v213
	v_fmaak_f32 v209, v207, v209, 0x3fcc422a
	v_fmaak_f32 v218, v214, v218, 0x3fcc422a
	v_fmaak_f32 v219, v215, v219, 0x3fcc422a
	v_fmaak_f32 v220, v212, v220, 0x3fcc422a
	v_fmaak_f32 v221, v213, v221, 0x3fcc422a
	v_mul_f32_e32 v209, v207, v209
	v_mul_f32_e32 v218, v214, v218
	v_mul_f32_e32 v219, v215, v219
	v_mul_f32_e32 v220, v212, v220
	v_mul_f32_e32 v221, v213, v221
	v_mul_f32_e32 v209, 0xbfb8aa3b, v209
	v_mul_f32_e32 v218, 0xbfb8aa3b, v218
	v_mul_f32_e32 v219, 0xbfb8aa3b, v219
	v_mul_f32_e32 v220, 0xbfb8aa3b, v220
	v_mul_f32_e32 v221, 0xbfb8aa3b, v221
	v_exp_f32_e32 v209, v209
	v_exp_f32_e32 v218, v218
	v_exp_f32_e32 v219, v219
	v_exp_f32_e32 v220, v220
	v_exp_f32_e32 v221, v221
	v_add_f32_e32 v209, 1.0, v209
	v_add_f32_e32 v218, 1.0, v218
	v_add_f32_e32 v219, 1.0, v219
	v_add_f32_e32 v220, 1.0, v220
	v_add_f32_e32 v221, 1.0, v221
	v_rcp_f32_e32 v208, v208
	v_rcp_f32_e32 v209, v209
	v_rcp_f32_e32 v218, v218
	v_rcp_f32_e32 v220, v220
	v_rcp_f32_e32 v221, v221
	v_rcp_f32_e32 v219, v219
	v_mul_f32_e32 v208, v206, v208
	v_mul_f32_e32 v209, v207, v209
	v_mul_f32_e32 v216, v186, v216
	v_mul_f32_e32 v217, v187, v217
	v_mul_f32_e32 v186, v212, v220
	v_mul_f32_e32 v187, v213, v221
	v_mul_f32_e32 v206, v214, v218
	v_mul_f32_e32 v207, v215, v219
	v_fma_f32 v214, v216, v216, v210
	v_fma_f32 v215, v217, v217, v211
	v_cvt_pk_bf16_f32 v210, v216, v217
	v_cvt_pk_bf16_f32 v211, v208, v209
	v_cvt_pk_bf16_f32 v212, v206, v207
	v_cvt_pk_bf16_f32 v213, v186, v187
	v_mul_f32_e32 v176, v4, v176
	v_mul_f32_e32 v177, v5, v177
	global_store_dwordx4 v[178:179], v[210:213], off offset:256
	v_mul_f32_e32 v178, 0x3d922279, v176
	v_fmaak_f32 v178, v176, v178, 0x3fcc422a
	v_mul_f32_e32 v179, 0x3d922279, v177
	v_mul_f32_e32 v178, v176, v178
	v_fmaak_f32 v179, v177, v179, 0x3fcc422a
	v_mul_f32_e32 v178, 0xbfb8aa3b, v178
	v_mul_f32_e32 v179, v177, v179
	v_exp_f32_e32 v178, v178
	v_mul_f32_e32 v179, 0xbfb8aa3b, v179
	v_exp_f32_e32 v179, v179
	v_mul_f32_e32 v180, v6, v180
	v_mul_f32_e32 v181, v7, v181
	v_mul_f32_e32 v210, v0, v174
	v_mul_f32_e32 v211, v1, v175
	v_add_f32_e32 v174, 1.0, v178
	v_mul_f32_e32 v178, 0x3d922279, v180
	v_add_f32_e32 v175, 1.0, v179
	v_fmaak_f32 v178, v180, v178, 0x3fcc422a
	v_mul_f32_e32 v179, 0x3d922279, v181
	v_mul_f32_e32 v178, v180, v178
	v_fmaak_f32 v179, v181, v179, 0x3fcc422a
	v_mul_f32_e32 v178, 0xbfb8aa3b, v178
	v_mul_f32_e32 v179, v181, v179
	v_exp_f32_e32 v178, v178
	v_mul_f32_e32 v179, 0xbfb8aa3b, v179
	v_exp_f32_e32 v179, v179
	v_rcp_f32_e32 v174, v174
	v_add_f32_e32 v178, 1.0, v178
	v_rcp_f32_e32 v212, v178
	v_add_f32_e32 v178, 1.0, v179
	v_rcp_f32_e32 v213, v178
	v_mul_f32_e32 v178, 0x3d922279, v210
	v_fmaak_f32 v178, v210, v178, 0x3fcc422a
	v_mul_f32_e32 v179, 0x3d922279, v211
	v_mul_f32_e32 v178, v210, v178
	v_fmaak_f32 v179, v211, v179, 0x3fcc422a
	v_mul_f32_e32 v178, 0xbfb8aa3b, v178
	v_mul_f32_e32 v179, v211, v179
	v_rcp_f32_e32 v175, v175
	v_exp_f32_e32 v178, v178
	v_mul_f32_e32 v179, 0xbfb8aa3b, v179
	v_exp_f32_e32 v179, v179
	v_mul_f32_e32 v216, v176, v174
	v_mul_f32_e32 v217, v177, v175
	v_add_f32_e32 v174, 1.0, v178
	v_rcp_f32_e32 v176, v174
	v_add_f32_e32 v174, 1.0, v179
	v_fma_f32 v178, v216, v216, v214
	v_fma_f32 v179, v217, v217, v215
	ds_bpermute_b32 v214, v226, v178
	v_mul_f32_e32 v182, v2, v182
	v_mul_f32_e32 v183, v3, v183
	v_rcp_f32_e32 v177, v174
	v_mul_f32_e32 v174, 0x3d922279, v182
	v_mul_f32_e32 v175, 0x3d922279, v183
	s_waitcnt lgkmcnt(0)
	v_add_f32_e32 v178, v178, v214
	v_fmaak_f32 v174, v182, v174, 0x3fcc422a
	v_fmaak_f32 v175, v183, v175, 0x3fcc422a
	ds_bpermute_b32 v214, v227, v178
	v_mul_f32_e32 v174, v182, v174
	v_mul_f32_e32 v175, v183, v175
	v_mul_f32_e32 v174, 0xbfb8aa3b, v174
	v_mul_f32_e32 v175, 0xbfb8aa3b, v175
	v_exp_f32_e32 v174, v174
	v_exp_f32_e32 v175, v175
	s_waitcnt lgkmcnt(0)
	v_add_f32_e32 v178, v178, v214
	ds_bpermute_b32 v214, v228, v178
	v_add_f32_e32 v174, 1.0, v174
	v_add_f32_e32 v175, 1.0, v175
	v_rcp_f32_e32 v174, v174
	v_rcp_f32_e32 v175, v175
	s_waitcnt lgkmcnt(0)
	v_add_f32_e32 v178, v178, v214
	v_mul_f32_e32 v180, v180, v212
	v_mul_f32_e32 v181, v181, v213
	v_mul_f32_e32 v176, v210, v176
	v_mul_f32_e32 v177, v211, v177
	v_mul_f32_e32 v174, v182, v174
	v_mul_f32_e32 v175, v183, v175
	ds_bpermute_b32 v182, v229, v178
	v_cvt_pk_bf16_f32 v210, v216, v217
	v_cvt_pk_bf16_f32 v211, v180, v181
	v_cvt_pk_bf16_f32 v212, v176, v177
	v_cvt_pk_bf16_f32 v213, v174, v175
	global_store_dwordx4 v[172:173], v[210:213], off offset:256
	s_and_saveexec_b64 s[4:5], s[2:3]
	s_cbranch_execz .LBB0_347
	s_waitcnt lgkmcnt(0)
	v_add_f32_e32 v172, v178, v182
	global_atomic_add_f32 v[136:137], v172, off offset:512
.LBB0_347:
	s_or_b64 exec, exec, s[4:5]
	ds_bpermute_b32 v172, v226, v179
	s_waitcnt lgkmcnt(0)
	v_add_f32_e32 v172, v179, v172
	ds_bpermute_b32 v173, v227, v172
	s_waitcnt lgkmcnt(0)
	v_add_f32_e32 v178, v172, v173
	ds_bpermute_b32 v179, v228, v178
	v_mul_f32_e32 v172, v184, v184
	v_mul_f32_e32 v173, v185, v185
	s_nop 0
	v_fma_f32 v134, v134, v134, v172
	v_fma_f32 v135, v135, v135, v173
	s_waitcnt lgkmcnt(0)
	v_add_f32_e32 v172, v178, v179
	v_fma_f32 v134, v190, v190, v134
	v_fma_f32 v135, v191, v191, v135
	ds_bpermute_b32 v173, v229, v172
	v_fma_f32 v134, v196, v196, v134
	v_fma_f32 v135, v197, v197, v135
	s_nop 0
	v_fma_f32 v134, v200, v200, v134
	v_fma_f32 v135, v201, v201, v135
	s_nop 0
	v_fma_f32 v134, v204, v204, v134
	v_fma_f32 v135, v205, v205, v135
	s_nop 0
	v_fma_f32 v134, v208, v208, v134
	v_fma_f32 v135, v209, v209, v135
	s_nop 0
	v_fma_f32 v134, v180, v180, v134
	v_fma_f32 v135, v181, v181, v135
	s_and_saveexec_b64 s[4:5], s[2:3]
	s_cbranch_execz .LBB0_349
	s_waitcnt lgkmcnt(0)
	v_add_f32_e32 v172, v172, v173
	global_atomic_add_f32 v[136:137], v172, off offset:516

; #define PK8(v0, v1) ({ const u32x2 h0_ = pk4(v0), h1_ = pk4(v1); (u32x4){h0_.x, h0_.y, h1_.x, h1_.y}; })
;     DI void operator()(const Acc& acc, const Unit& u, int wr, int wc, int fr, int fq) const {
;     ...
;                         sq0 += v0 * v0; sq1 += v1 * v1; *(u32x4*)(WSB(OFF_VT) + (size_t)r * 8192 + cc) = PK8(v0, v1); }
; #pragma unroll
;                     for (int j = 0; j < 8; ++j) { float t = j < 4 ? sq0[j & 3] : sq1[j & 3];
;                         t += __shfl_xor(t, 1); t += __shfl_xor(t, 2); t += __shfl_xor(t, 4); t += __shfl_xor(t, 8);
;                         if (fr == 0) unsafeAtomicAdd(ssqv + cc + j, t); }
.LBB0_353:
	s_or_b64 exec, exec, s[4:5]
	s_waitcnt lgkmcnt(0)
	v_mul_f32_e32 v134, v138, v138
	v_mul_f32_e32 v135, v139, v139
	s_nop 0
	v_fma_f32 v130, v130, v130, v134
	v_fma_f32 v131, v131, v131, v135
	s_nop 0
	v_fma_f32 v130, v188, v188, v130
	v_fma_f32 v131, v189, v189, v131
	s_nop 0
	v_fma_f32 v130, v194, v194, v130
	v_fma_f32 v131, v195, v195, v131
	s_nop 0
	v_fma_f32 v130, v198, v198, v130
	v_fma_f32 v131, v199, v199, v131
	s_nop 0
	v_fma_f32 v130, v202, v202, v130
	v_fma_f32 v131, v203, v203, v131
	s_nop 0
	v_fma_f32 v130, v206, v206, v130
	v_fma_f32 v131, v207, v207, v131
	s_nop 0
	v_fma_f32 v130, v176, v176, v130
	v_fma_f32 v131, v177, v177, v131
	ds_bpermute_b32 v134, v226, v130
	s_waitcnt lgkmcnt(0)
	v_add_f32_e32 v130, v130, v134
	ds_bpermute_b32 v134, v227, v130
	s_waitcnt lgkmcnt(0)
	v_add_f32_e32 v130, v130, v134
	ds_bpermute_b32 v134, v228, v130
	s_waitcnt lgkmcnt(0)
	v_add_f32_e32 v130, v130, v134
	ds_bpermute_b32 v134, v229, v130
	s_and_saveexec_b64 s[4:5], s[2:3]
	s_cbranch_execz .LBB0_355
	s_waitcnt lgkmcnt(0)
	v_add_f32_e32 v130, v130, v134
	global_atomic_add_f32 v[136:137], v130, off offset:528
.LBB0_355:
	s_or_b64 exec, exec, s[4:5]
	ds_bpermute_b32 v130, v226, v131
	s_waitcnt lgkmcnt(0)
	v_add_f32_e32 v130, v131, v130
	ds_bpermute_b32 v131, v227, v130
	s_waitcnt lgkmcnt(0)
	v_add_f32_e32 v134, v130, v131
	ds_bpermute_b32 v135, v228, v134
	v_mul_f32_e32 v130, v132, v132
	v_mul_f32_e32 v131, v133, v133
	s_nop 0
	v_fma_f32 v128, v128, v128, v130
	v_fma_f32 v129, v129, v129, v131
	s_waitcnt lgkmcnt(0)
	v_add_f32_e32 v130, v134, v135
	v_fma_f32 v128, v166, v166, v128
	v_fma_f32 v129, v167, v167, v129
	ds_bpermute_b32 v131, v229, v130
	v_fma_f32 v128, v168, v168, v128
	v_fma_f32 v129, v169, v169, v129
	s_nop 0
	v_fma_f32 v128, v170, v170, v128
	v_fma_f32 v129, v171, v171, v129
	s_nop 0
	v_fma_f32 v128, v192, v192, v128
	v_fma_f32 v129, v193, v193, v129
	s_nop 0
	v_fma_f32 v128, v186, v186, v128
	v_fma_f32 v129, v187, v187, v129
	s_nop 0
	v_fma_f32 v128, v174, v174, v128
	v_fma_f32 v129, v175, v175, v129
	s_and_saveexec_b64 s[4:5], s[2:3]
	s_cbranch_execz .LBB0_357
	s_waitcnt lgkmcnt(0)
	v_add_f32_e32 v130, v130, v131
	global_atomic_add_f32 v[136:137], v130, off offset:532

; DI float gelu_tanh(float x) { const float t = x * (1.5957691216f + 0.0713548163f * x * x); return x * __builtin_amdgcn_rcpf(1.f + __builtin_amdgcn_exp2f(-1.4426950409f * t)); }
; #define ROWS8 _Pragma("unroll") for (int ai = 0; ai < 2; ++ai) _Pragma("unroll") for (int m = 0; m < 4; ++m) if (ai == 0 || !hf)
; #define COLS4 _Pragma("unroll") for (int bj = 0; bj < 2; ++bj) _Pragma("unroll") for (int n = 0; n < 2; ++n)
; #define LOAD_ROW_RS(rsv, ssqp, invn) float rsv[2][4]; ROWS8_ALL rsv[ai][m] = (ssqp)[row0 + ai * HALF + m * 16]; ROWS8_ALL rsv[ai][m] = rstd_of(rsv[ai][m], invn)
; #define PK8(v0, v1) ({ const u32x2 h0_ = pk4(v0), h1_ = pk4(v1); (u32x4){h0_.x, h0_.y, h1_.x, h1_.y}; })
;     DI void operator()(const Acc& acc, const Unit& u, int wr, int wc, int fr, int fq) const {
;     ...
;                 LOAD_ROW_RS(rsv, SSQ(0), 1.f / 2048.f);
;                 ROWS8 { const int r = row0 + ai * HALF + m * 16; const float rs = rsv[ai][m];
;                     if (u.pn < 4) { bf16_t* dst = WSB(OFF_U) + (size_t)r * 1024 + colp;
; #pragma unroll
;                         for (int bj = 0; bj < 2; ++bj) { f32x4 v0 = acc[ai][bj][m][0] * rs, v1 = acc[ai][bj][m][1] * rs;
;                             v0[0] = gelu_tanh(v0[0]); v0[1] = gelu_tanh(v0[1]); v0[2] = gelu_tanh(v0[2]); v0[3] = gelu_tanh(v0[3]);
;                             v1[0] = gelu_tanh(v1[0]); v1[1] = gelu_tanh(v1[1]); v1[2] = gelu_tanh(v1[2]); v1[3] = gelu_tanh(v1[3]);
;                             *(u32x4*)(dst + bj * HALF) = PK8(v0, v1); }
;                     } else { float* dst = WSF(OFF_Z) + (size_t)r * 1024 + (colp - 1024);
;                         COLS4 *(f32x4*)(dst + bj * HALF + n * 4) = acc[ai][bj][m][n] * rs;
;                     }
.LBB0_362:
	s_cbranch_execz .LBB0_314
	s_waitcnt lgkmcnt(0)
	v_lshl_add_u64 v[128:129], v[158:159], 2, s[16:17]
	global_load_dword v136, v[128:129], off
	v_lshl_add_u64 v[130:131], v[164:165], 2, s[16:17]
	v_lshl_add_u64 v[132:133], v[162:163], 2, s[16:17]
	v_lshl_add_u64 v[134:135], v[160:161], 2, s[16:17]
	global_load_dword v174, v[130:131], off
	global_load_dword v173, v[132:133], off
	global_load_dword v172, v[134:135], off
	global_load_dword v171, v[128:129], off offset:512
	global_load_dword v170, v[128:129], off offset:576
	global_load_dword v169, v[128:129], off offset:640
	global_load_dword v168, v[128:129], off offset:704
	s_cmp_gt_i32 s73, 3
	s_cselect_b64 s[46:47], -1, 0
	s_mov_b64 s[4:5], -1
	s_and_b64 vcc, exec, s[46:47]
	s_waitcnt vmcnt(0)
	v_fmamk_f32 v128, v136, 0x3a000000, v233
	v_rsq_f32_e32 v166, v128
	s_nop 0
	v_mov_b32_e32 v167, v166
	v_mul_f32_e32 v134, v126, v166
	v_mul_f32_e32 v135, v127, v166
	v_mul_f32_e32 v132, v124, v166
	v_mul_f32_e32 v133, v125, v166
	v_mul_f32_e32 v136, v120, v166
	v_mul_f32_e32 v137, v121, v167
	v_mul_f32_e32 v128, v116, v166
	v_mul_f32_e32 v129, v117, v167
	v_mul_f32_e32 v124, v112, v166
	v_mul_f32_e32 v125, v113, v167
	s_cbranch_vccz .LBB0_365
	v_lshlrev_b64 v[112:113], 12, v[158:159]
	v_lshl_add_u64 v[112:113], s[10:11], 0, v[112:113]
	v_lshl_add_u64 v[112:113], v[156:157], 2, v[112:113]
	v_add_co_u32_e32 v112, vcc, 0xefff000, v112
	v_mov_b32_e32 v167, v166
	s_nop 0
	v_addc_co_u32_e32 v113, vcc, 0, v113, vcc
	v_mul_f32_e32 v138, v122, v166
	v_mul_f32_e32 v139, v123, v167
	v_mul_f32_e32 v130, v118, v166
	v_mul_f32_e32 v131, v119, v167
	v_mul_f32_e32 v126, v114, v166
	v_mul_f32_e32 v127, v115, v167
	global_store_dwordx4 v[112:113], v[132:135], off
	global_store_dwordx4 v[112:113], v[136:139], off offset:16
	global_store_dwordx4 v[112:113], v[128:131], off offset:512
	global_store_dwordx4 v[112:113], v[124:127], off offset:528
	s_mov_b64 s[4:5], 0
.LBB0_365:
	s_andn2_b64 vcc, exec, s[4:5]
	s_cbranch_vccnz .LBB0_367
	v_lshlrev_b64 v[112:113], 11, v[158:159]
	v_lshl_add_u64 v[112:113], s[22:23], 0, v[112:113]
	v_lshl_add_u64 v[116:117], v[156:157], 1, v[112:113]
	v_mul_f32_e32 v112, 0x3d922279, v132
	v_fmaak_f32 v112, v132, v112, 0x3fcc422a
	v_mul_f32_e32 v112, v132, v112
	v_mul_f32_e32 v112, 0xbfb8aa3b, v112
	v_exp_f32_e32 v120, v112
	v_mul_f32_e32 v112, 0x3d922279, v133
	v_fmaak_f32 v112, v133, v112, 0x3fcc422a
	v_mul_f32_e32 v112, v133, v112
	v_mov_b32_e32 v167, v166
	v_mul_f32_e32 v112, 0xbfb8aa3b, v112
	v_exp_f32_e32 v121, v112
	v_mul_f32_e32 v112, v122, v166
	v_mul_f32_e32 v113, v123, v167
	v_mul_f32_e32 v122, 0x3d922279, v134
	v_mul_f32_e32 v123, 0x3d922279, v135
	v_mul_f32_e32 v126, 0x3d922279, v136
	v_mul_f32_e32 v127, 0x3d922279, v137
	v_mul_f32_e32 v130, 0x3d922279, v112
	v_mul_f32_e32 v131, 0x3d922279, v113
	v_fmaak_f32 v122, v134, v122, 0x3fcc422a
	v_fmaak_f32 v123, v135, v123, 0x3fcc422a
	v_fmaak_f32 v126, v136, v126, 0x3fcc422a
	v_fmaak_f32 v127, v137, v127, 0x3fcc422a
	v_fmaak_f32 v130, v112, v130, 0x3fcc422a
	v_fmaak_f32 v131, v113, v131, 0x3fcc422a
	v_mul_f32_e32 v122, v134, v122
	v_mul_f32_e32 v123, v135, v123
	v_mul_f32_e32 v126, v136, v126
	v_mul_f32_e32 v127, v137, v127
	v_mul_f32_e32 v130, v112, v130
	v_mul_f32_e32 v131, v113, v131
	v_mul_f32_e32 v122, 0xbfb8aa3b, v122
	v_mul_f32_e32 v123, 0xbfb8aa3b, v123
	v_mul_f32_e32 v126, 0xbfb8aa3b, v126
	v_mul_f32_e32 v127, 0xbfb8aa3b, v127
	v_mul_f32_e32 v130, 0xbfb8aa3b, v130
	v_mul_f32_e32 v131, 0xbfb8aa3b, v131
	v_exp_f32_e32 v122, v122
	v_exp_f32_e32 v123, v123
	v_exp_f32_e32 v126, v126
	v_exp_f32_e32 v127, v127
	v_exp_f32_e32 v130, v130
	v_exp_f32_e32 v131, v131
	v_add_f32_e32 v120, 1.0, v120
	v_add_f32_e32 v121, 1.0, v121
	v_add_f32_e32 v122, 1.0, v122
	v_add_f32_e32 v123, 1.0, v123
	v_add_f32_e32 v126, 1.0, v126
	v_add_f32_e32 v127, 1.0, v127
	v_add_f32_e32 v130, 1.0, v130
	v_add_f32_e32 v131, 1.0, v131
	v_rcp_f32_e32 v120, v120
	v_rcp_f32_e32 v121, v121
	v_rcp_f32_e32 v122, v122
	v_rcp_f32_e32 v123, v123
	v_rcp_f32_e32 v126, v126
	v_rcp_f32_e32 v127, v127
	v_rcp_f32_e32 v130, v130
	v_rcp_f32_e32 v131, v131
	v_mul_f32_e32 v120, v132, v120
	v_mul_f32_e32 v121, v133, v121
	v_mul_f32_e32 v122, v134, v122
	v_mul_f32_e32 v123, v135, v123
	v_mul_f32_e32 v126, v136, v126
	v_mul_f32_e32 v127, v137, v127
	v_mul_f32_e32 v112, v112, v130
	v_mul_f32_e32 v113, v113, v131
	v_cvt_pk_bf16_f32 v120, v120, v121
	v_cvt_pk_bf16_f32 v121, v122, v123
	v_cvt_pk_bf16_f32 v122, v126, v127
	v_cvt_pk_bf16_f32 v123, v112, v113
	v_mul_f32_e32 v112, v118, v166
	v_mul_f32_e32 v113, v119, v167
	v_mul_f32_e32 v114, v114, v166
	v_mul_f32_e32 v115, v115, v167
	global_store_dwordx4 v[116:117], v[120:123], off
	v_mul_f32_e32 v118, 0x3d922279, v128
	v_mul_f32_e32 v119, 0x3d922279, v129
	v_mul_f32_e32 v120, 0x3d922279, v112
	v_mul_f32_e32 v121, 0x3d922279, v113
	v_mul_f32_e32 v122, 0x3d922279, v124
	v_mul_f32_e32 v123, 0x3d922279, v125
	v_mul_f32_e32 v126, 0x3d922279, v114
	v_mul_f32_e32 v127, 0x3d922279, v115
	v_fmaak_f32 v118, v128, v118, 0x3fcc422a
	v_fmaak_f32 v119, v129, v119, 0x3fcc422a
	v_fmaak_f32 v120, v112, v120, 0x3fcc422a
	v_fmaak_f32 v121, v113, v121, 0x3fcc422a
	v_fmaak_f32 v122, v124, v122, 0x3fcc422a
	v_fmaak_f32 v123, v125, v123, 0x3fcc422a
	v_fmaak_f32 v126, v114, v126, 0x3fcc422a
	v_fmaak_f32 v127, v115, v127, 0x3fcc422a
	v_mul_f32_e32 v118, v128, v118
	v_mul_f32_e32 v119, v129, v119
	v_mul_f32_e32 v120, v112, v120
	v_mul_f32_e32 v121, v113, v121
	v_mul_f32_e32 v122, v124, v122
	v_mul_f32_e32 v123, v125, v123
	v_mul_f32_e32 v126, v114, v126
	v_mul_f32_e32 v127, v115, v127
	v_mul_f32_e32 v118, 0xbfb8aa3b, v118
	v_mul_f32_e32 v119, 0xbfb8aa3b, v119
	v_mul_f32_e32 v120, 0xbfb8aa3b, v120
	v_mul_f32_e32 v121, 0xbfb8aa3b, v121
	v_mul_f32_e32 v122, 0xbfb8aa3b, v122
	v_mul_f32_e32 v123, 0xbfb8aa3b, v123
	v_mul_f32_e32 v126, 0xbfb8aa3b, v126
	v_mul_f32_e32 v127, 0xbfb8aa3b, v127
	v_exp_f32_e32 v118, v118
	v_exp_f32_e32 v119, v119
	v_exp_f32_e32 v120, v120
	v_exp_f32_e32 v121, v121
	v_exp_f32_e32 v122, v122
	v_exp_f32_e32 v123, v123
	v_exp_f32_e32 v126, v126
	v_exp_f32_e32 v127, v127
	v_add_f32_e32 v118, 1.0, v118
	v_add_f32_e32 v119, 1.0, v119
	v_add_f32_e32 v120, 1.0, v120
	v_add_f32_e32 v121, 1.0, v121
	v_add_f32_e32 v122, 1.0, v122
	v_add_f32_e32 v123, 1.0, v123
	v_add_f32_e32 v126, 1.0, v126
	v_add_f32_e32 v127, 1.0, v127
	v_rcp_f32_e32 v118, v118
	v_rcp_f32_e32 v119, v119
	v_rcp_f32_e32 v120, v120
	v_rcp_f32_e32 v121, v121
	v_rcp_f32_e32 v122, v122
	v_rcp_f32_e32 v123, v123
	v_rcp_f32_e32 v126, v126
	v_rcp_f32_e32 v127, v127
	v_mul_f32_e32 v118, v128, v118
	v_mul_f32_e32 v119, v129, v119
	v_mul_f32_e32 v120, v112, v120
	v_mul_f32_e32 v121, v113, v121
	v_mul_f32_e32 v122, v124, v122
	v_mul_f32_e32 v123, v125, v123
	v_mul_f32_e32 v124, v114, v126
	v_mul_f32_e32 v125, v115, v127
	v_cvt_pk_bf16_f32 v112, v118, v119
	v_cvt_pk_bf16_f32 v113, v120, v121
	v_cvt_pk_bf16_f32 v114, v122, v123
	v_cvt_pk_bf16_f32 v115, v124, v125
	global_store_dwordx4 v[116:117], v[112:115], off offset:256
; DI float gelu_tanh(float x) { const float t = x * (1.5957691216f + 0.0713548163f * x * x); return x * __builtin_amdgcn_rcpf(1.f + __builtin_amdgcn_exp2f(-1.4426950409f * t)); }
; #define ROWS8 _Pragma("unroll") for (int ai = 0; ai < 2; ++ai) _Pragma("unroll") for (int m = 0; m < 4; ++m) if (ai == 0 || !hf)
; #define COLS4 _Pragma("unroll") for (int bj = 0; bj < 2; ++bj) _Pragma("unroll") for (int n = 0; n < 2; ++n)
; #define LOAD_ROW_RS(rsv, ssqp, invn) float rsv[2][4]; ROWS8_ALL rsv[ai][m] = (ssqp)[row0 + ai * HALF + m * 16]; ROWS8_ALL rsv[ai][m] = rstd_of(rsv[ai][m], invn)
; #define PK8(v0, v1) ({ const u32x2 h0_ = pk4(v0), h1_ = pk4(v1); (u32x4){h0_.x, h0_.y, h1_.x, h1_.y}; })
;     DI void operator()(const Acc& acc, const Unit& u, int wr, int wc, int fr, int fq) const {
;     ...
;                 LOAD_ROW_RS(rsv, SSQ(0), 1.f / 2048.f);
;                 ROWS8 { const int r = row0 + ai * HALF + m * 16; const float rs = rsv[ai][m];
;                     if (u.pn < 4) { bf16_t* dst = WSB(OFF_U) + (size_t)r * 1024 + colp;
; #pragma unroll
;                         for (int bj = 0; bj < 2; ++bj) { f32x4 v0 = acc[ai][bj][m][0] * rs, v1 = acc[ai][bj][m][1] * rs;
;                             v0[0] = gelu_tanh(v0[0]); v0[1] = gelu_tanh(v0[1]); v0[2] = gelu_tanh(v0[2]); v0[3] = gelu_tanh(v0[3]);
;                             v1[0] = gelu_tanh(v1[0]); v1[1] = gelu_tanh(v1[1]); v1[2] = gelu_tanh(v1[2]); v1[3] = gelu_tanh(v1[3]);
;                             *(u32x4*)(dst + bj * HALF) = PK8(v0, v1); }
;                     } else { float* dst = WSF(OFF_Z) + (size_t)r * 1024 + (colp - 1024);
;                         COLS4 *(f32x4*)(dst + bj * HALF + n * 4) = acc[ai][bj][m][n] * rs;
;                     }
.LBB0_367:
	s_nop 1
	v_fmamk_f32 v112, v174, 0x3a000000, v233
	v_rsq_f32_e32 v124, v112
	v_cndmask_b32_e64 v112, 0, 1, s[46:47]
	s_mov_b64 s[48:49], -1
	v_cmp_ne_u32_e64 s[4:5], 1, v112
	v_mov_b32_e32 v125, v124
	v_mul_f32_e32 v118, v110, v124
	v_mul_f32_e32 v119, v111, v124
	v_mul_f32_e32 v116, v108, v124
	v_mul_f32_e32 v117, v109, v124
	s_andn2_b64 vcc, exec, s[46:47]
	v_mul_f32_e32 v120, v104, v124
	v_mul_f32_e32 v121, v105, v125
	v_mul_f32_e32 v112, v100, v124
	v_mul_f32_e32 v113, v101, v125
	v_mul_f32_e32 v108, v96, v124
	v_mul_f32_e32 v109, v97, v125
	s_cbranch_vccnz .LBB0_369
	v_lshlrev_b64 v[96:97], 12, v[164:165]
	v_lshl_add_u64 v[96:97], s[10:11], 0, v[96:97]
	v_lshl_add_u64 v[96:97], v[156:157], 2, v[96:97]
	v_add_co_u32_e32 v96, vcc, 0xefff000, v96
	v_mov_b32_e32 v125, v124
	s_nop 0
	v_addc_co_u32_e32 v97, vcc, 0, v97, vcc
	v_mul_f32_e32 v122, v106, v124
	v_mul_f32_e32 v123, v107, v125
	v_mul_f32_e32 v114, v102, v124
	v_mul_f32_e32 v115, v103, v125
	v_mul_f32_e32 v110, v98, v124
	v_mul_f32_e32 v111, v99, v125
	s_mov_b64 s[48:49], 0
	global_store_dwordx4 v[96:97], v[116:119], off
	global_store_dwordx4 v[96:97], v[120:123], off offset:16
	global_store_dwordx4 v[96:97], v[112:115], off offset:512
	global_store_dwordx4 v[96:97], v[108:111], off offset:528
.LBB0_369:
	s_andn2_b64 vcc, exec, s[48:49]
	s_cbranch_vccnz .LBB0_371
	v_lshlrev_b64 v[96:97], 11, v[164:165]
	v_lshl_add_u64 v[96:97], s[22:23], 0, v[96:97]
	v_lshl_add_u64 v[100:101], v[156:157], 1, v[96:97]
	v_mul_f32_e32 v96, 0x3d922279, v116
	v_fmaak_f32 v96, v116, v96, 0x3fcc422a
	v_mul_f32_e32 v96, v116, v96
	v_mul_f32_e32 v96, 0xbfb8aa3b, v96
	v_exp_f32_e32 v104, v96
	v_mul_f32_e32 v96, 0x3d922279, v117
	v_fmaak_f32 v96, v117, v96, 0x3fcc422a
	v_mul_f32_e32 v96, v117, v96
	v_mov_b32_e32 v125, v124
	v_mul_f32_e32 v96, 0xbfb8aa3b, v96
	v_exp_f32_e32 v105, v96
	v_mul_f32_e32 v96, v106, v124
	v_mul_f32_e32 v97, v107, v125
	v_mul_f32_e32 v106, 0x3d922279, v118
	v_mul_f32_e32 v107, 0x3d922279, v119
	v_mul_f32_e32 v110, 0x3d922279, v120
	v_mul_f32_e32 v111, 0x3d922279, v121
	v_mul_f32_e32 v114, 0x3d922279, v96
	v_mul_f32_e32 v115, 0x3d922279, v97
	v_fmaak_f32 v106, v118, v106, 0x3fcc422a
	v_fmaak_f32 v107, v119, v107, 0x3fcc422a
	v_fmaak_f32 v110, v120, v110, 0x3fcc422a
	v_fmaak_f32 v111, v121, v111, 0x3fcc422a
	v_fmaak_f32 v114, v96, v114, 0x3fcc422a
	v_fmaak_f32 v115, v97, v115, 0x3fcc422a
	v_mul_f32_e32 v106, v118, v106
	v_mul_f32_e32 v107, v119, v107
	v_mul_f32_e32 v110, v120, v110
	v_mul_f32_e32 v111, v121, v111
	v_mul_f32_e32 v114, v96, v114
	v_mul_f32_e32 v115, v97, v115
	v_mul_f32_e32 v106, 0xbfb8aa3b, v106
	v_mul_f32_e32 v107, 0xbfb8aa3b, v107
	v_mul_f32_e32 v110, 0xbfb8aa3b, v110
	v_mul_f32_e32 v111, 0xbfb8aa3b, v111
	v_mul_f32_e32 v114, 0xbfb8aa3b, v114
	v_mul_f32_e32 v115, 0xbfb8aa3b, v115
	v_exp_f32_e32 v106, v106
	v_exp_f32_e32 v107, v107
	v_exp_f32_e32 v110, v110
	v_exp_f32_e32 v111, v111
	v_exp_f32_e32 v114, v114
	v_exp_f32_e32 v115, v115
	v_add_f32_e32 v104, 1.0, v104
	v_add_f32_e32 v105, 1.0, v105
	v_add_f32_e32 v106, 1.0, v106
	v_add_f32_e32 v107, 1.0, v107
	v_add_f32_e32 v110, 1.0, v110
	v_add_f32_e32 v111, 1.0, v111
	v_add_f32_e32 v114, 1.0, v114
	v_add_f32_e32 v115, 1.0, v115
	v_rcp_f32_e32 v104, v104
	v_rcp_f32_e32 v105, v105
	v_rcp_f32_e32 v106, v106
	v_rcp_f32_e32 v107, v107
	v_rcp_f32_e32 v110, v110
	v_rcp_f32_e32 v111, v111
	v_rcp_f32_e32 v114, v114
	v_rcp_f32_e32 v115, v115
	v_mul_f32_e32 v104, v116, v104
	v_mul_f32_e32 v105, v117, v105
	v_mul_f32_e32 v106, v118, v106
	v_mul_f32_e32 v107, v119, v107
	v_mul_f32_e32 v110, v120, v110
	v_mul_f32_e32 v111, v121, v111
	v_mul_f32_e32 v96, v96, v114
	v_mul_f32_e32 v97, v97, v115
	v_cvt_pk_bf16_f32 v104, v104, v105
	v_cvt_pk_bf16_f32 v105, v106, v107
	v_cvt_pk_bf16_f32 v106, v110, v111
	v_cvt_pk_bf16_f32 v107, v96, v97
	v_mul_f32_e32 v96, v102, v124
	v_mul_f32_e32 v97, v103, v125
	v_mul_f32_e32 v98, v98, v124
	v_mul_f32_e32 v99, v99, v125
	global_store_dwordx4 v[100:101], v[104:107], off
	v_mul_f32_e32 v102, 0x3d922279, v112
	v_mul_f32_e32 v103, 0x3d922279, v113
	v_mul_f32_e32 v104, 0x3d922279, v96
	v_mul_f32_e32 v105, 0x3d922279, v97
	v_mul_f32_e32 v106, 0x3d922279, v108
	v_mul_f32_e32 v107, 0x3d922279, v109
	v_mul_f32_e32 v110, 0x3d922279, v98
	v_mul_f32_e32 v111, 0x3d922279, v99
	v_fmaak_f32 v102, v112, v102, 0x3fcc422a
	v_fmaak_f32 v103, v113, v103, 0x3fcc422a
	v_fmaak_f32 v104, v96, v104, 0x3fcc422a
	v_fmaak_f32 v105, v97, v105, 0x3fcc422a
	v_fmaak_f32 v106, v108, v106, 0x3fcc422a
	v_fmaak_f32 v107, v109, v107, 0x3fcc422a
	v_fmaak_f32 v110, v98, v110, 0x3fcc422a
	v_fmaak_f32 v111, v99, v111, 0x3fcc422a
	v_mul_f32_e32 v102, v112, v102
	v_mul_f32_e32 v103, v113, v103
	v_mul_f32_e32 v104, v96, v104
	v_mul_f32_e32 v105, v97, v105
	v_mul_f32_e32 v106, v108, v106
	v_mul_f32_e32 v107, v109, v107
	v_mul_f32_e32 v110, v98, v110
	v_mul_f32_e32 v111, v99, v111
	v_mul_f32_e32 v102, 0xbfb8aa3b, v102
	v_mul_f32_e32 v103, 0xbfb8aa3b, v103
	v_mul_f32_e32 v104, 0xbfb8aa3b, v104
	v_mul_f32_e32 v105, 0xbfb8aa3b, v105
	v_mul_f32_e32 v106, 0xbfb8aa3b, v106
	v_mul_f32_e32 v107, 0xbfb8aa3b, v107
	v_mul_f32_e32 v110, 0xbfb8aa3b, v110
	v_mul_f32_e32 v111, 0xbfb8aa3b, v111
	v_exp_f32_e32 v102, v102
	v_exp_f32_e32 v103, v103
	v_exp_f32_e32 v104, v104
	v_exp_f32_e32 v105, v105
	v_exp_f32_e32 v106, v106
	v_exp_f32_e32 v107, v107
	v_exp_f32_e32 v110, v110
	v_exp_f32_e32 v111, v111
	v_add_f32_e32 v102, 1.0, v102
	v_add_f32_e32 v103, 1.0, v103
	v_add_f32_e32 v104, 1.0, v104
	v_add_f32_e32 v105, 1.0, v105
	v_add_f32_e32 v106, 1.0, v106
	v_add_f32_e32 v107, 1.0, v107
	v_add_f32_e32 v110, 1.0, v110
	v_add_f32_e32 v111, 1.0, v111
	v_rcp_f32_e32 v102, v102
	v_rcp_f32_e32 v103, v103
	v_rcp_f32_e32 v104, v104
	v_rcp_f32_e32 v105, v105
	v_rcp_f32_e32 v106, v106
	v_rcp_f32_e32 v107, v107
	v_rcp_f32_e32 v110, v110
	v_rcp_f32_e32 v111, v111
	v_mul_f32_e32 v102, v112, v102
	v_mul_f32_e32 v103, v113, v103
	v_mul_f32_e32 v104, v96, v104
	v_mul_f32_e32 v105, v97, v105
	v_mul_f32_e32 v106, v108, v106
	v_mul_f32_e32 v107, v109, v107
	v_mul_f32_e32 v108, v98, v110
	v_mul_f32_e32 v109, v99, v111
	v_cvt_pk_bf16_f32 v96, v102, v103
	v_cvt_pk_bf16_f32 v97, v104, v105
	v_cvt_pk_bf16_f32 v98, v106, v107
	v_cvt_pk_bf16_f32 v99, v108, v109
	global_store_dwordx4 v[100:101], v[96:99], off offset:256
; DI float gelu_tanh(float x) { const float t = x * (1.5957691216f + 0.0713548163f * x * x); return x * __builtin_amdgcn_rcpf(1.f + __builtin_amdgcn_exp2f(-1.4426950409f * t)); }
; #define ROWS8 _Pragma("unroll") for (int ai = 0; ai < 2; ++ai) _Pragma("unroll") for (int m = 0; m < 4; ++m) if (ai == 0 || !hf)
; #define COLS4 _Pragma("unroll") for (int bj = 0; bj < 2; ++bj) _Pragma("unroll") for (int n = 0; n < 2; ++n)
; #define LOAD_ROW_RS(rsv, ssqp, invn) float rsv[2][4]; ROWS8_ALL rsv[ai][m] = (ssqp)[row0 + ai * HALF + m * 16]; ROWS8_ALL rsv[ai][m] = rstd_of(rsv[ai][m], invn)
; #define PK8(v0, v1) ({ const u32x2 h0_ = pk4(v0), h1_ = pk4(v1); (u32x4){h0_.x, h0_.y, h1_.x, h1_.y}; })
;     DI void operator()(const Acc& acc, const Unit& u, int wr, int wc, int fr, int fq) const {
;     ...
;                 LOAD_ROW_RS(rsv, SSQ(0), 1.f / 2048.f);
;                 ROWS8 { const int r = row0 + ai * HALF + m * 16; const float rs = rsv[ai][m];
;                     if (u.pn < 4) { bf16_t* dst = WSB(OFF_U) + (size_t)r * 1024 + colp;
; #pragma unroll
;                         for (int bj = 0; bj < 2; ++bj) { f32x4 v0 = acc[ai][bj][m][0] * rs, v1 = acc[ai][bj][m][1] * rs;
;                             v0[0] = gelu_tanh(v0[0]); v0[1] = gelu_tanh(v0[1]); v0[2] = gelu_tanh(v0[2]); v0[3] = gelu_tanh(v0[3]);
;                             v1[0] = gelu_tanh(v1[0]); v1[1] = gelu_tanh(v1[1]); v1[2] = gelu_tanh(v1[2]); v1[3] = gelu_tanh(v1[3]);
;                             *(u32x4*)(dst + bj * HALF) = PK8(v0, v1); }
;                     } else { float* dst = WSF(OFF_Z) + (size_t)r * 1024 + (colp - 1024);
;                         COLS4 *(f32x4*)(dst + bj * HALF + n * 4) = acc[ai][bj][m][n] * rs;
;                     }
.LBB0_371:
	s_nop 1
	v_fmamk_f32 v96, v173, 0x3a000000, v233
	v_rsq_f32_e32 v108, v96
	s_mov_b64 s[46:47], -1
	s_and_b64 vcc, exec, s[4:5]
	v_mov_b32_e32 v109, v108
	v_mul_f32_e32 v102, v94, v108
	v_mul_f32_e32 v103, v95, v108
	v_mul_f32_e32 v100, v92, v108
	v_mul_f32_e32 v101, v93, v108
	v_mul_f32_e32 v104, v88, v108
	v_mul_f32_e32 v105, v89, v109
	v_mul_f32_e32 v96, v84, v108
	v_mul_f32_e32 v97, v85, v109
	v_mul_f32_e32 v92, v80, v108
	v_mul_f32_e32 v93, v81, v109
	s_cbranch_vccnz .LBB0_373
	v_lshlrev_b64 v[80:81], 12, v[162:163]
	v_lshl_add_u64 v[80:81], s[10:11], 0, v[80:81]
	v_lshl_add_u64 v[80:81], v[156:157], 2, v[80:81]
	v_add_co_u32_e32 v80, vcc, 0xefff000, v80
	v_mov_b32_e32 v109, v108
	s_nop 0
	v_addc_co_u32_e32 v81, vcc, 0, v81, vcc
	v_mul_f32_e32 v106, v90, v108
	v_mul_f32_e32 v107, v91, v109
	v_mul_f32_e32 v98, v86, v108
	v_mul_f32_e32 v99, v87, v109
	v_mul_f32_e32 v94, v82, v108
	v_mul_f32_e32 v95, v83, v109
	s_mov_b64 s[46:47], 0
	global_store_dwordx4 v[80:81], v[100:103], off
	global_store_dwordx4 v[80:81], v[104:107], off offset:16
	global_store_dwordx4 v[80:81], v[96:99], off offset:512
	global_store_dwordx4 v[80:81], v[92:95], off offset:528
.LBB0_373:
	s_andn2_b64 vcc, exec, s[46:47]
	s_cbranch_vccnz .LBB0_375
	v_lshlrev_b64 v[80:81], 11, v[162:163]
	v_lshl_add_u64 v[80:81], s[22:23], 0, v[80:81]
	v_lshl_add_u64 v[84:85], v[156:157], 1, v[80:81]
	v_mul_f32_e32 v80, 0x3d922279, v100
	v_fmaak_f32 v80, v100, v80, 0x3fcc422a
	v_mul_f32_e32 v80, v100, v80
	v_mul_f32_e32 v80, 0xbfb8aa3b, v80
	v_exp_f32_e32 v88, v80
	v_mul_f32_e32 v80, 0x3d922279, v101
	v_fmaak_f32 v80, v101, v80, 0x3fcc422a
	v_mul_f32_e32 v80, v101, v80
	v_mov_b32_e32 v109, v108
	v_mul_f32_e32 v80, 0xbfb8aa3b, v80
	v_exp_f32_e32 v89, v80
	v_mul_f32_e32 v80, v90, v108
	v_mul_f32_e32 v81, v91, v109
	v_mul_f32_e32 v90, 0x3d922279, v102
	v_mul_f32_e32 v91, 0x3d922279, v103
	v_mul_f32_e32 v94, 0x3d922279, v104
	v_mul_f32_e32 v95, 0x3d922279, v105
	v_mul_f32_e32 v98, 0x3d922279, v80
	v_mul_f32_e32 v99, 0x3d922279, v81
	v_fmaak_f32 v90, v102, v90, 0x3fcc422a
	v_fmaak_f32 v91, v103, v91, 0x3fcc422a
	v_fmaak_f32 v94, v104, v94, 0x3fcc422a
	v_fmaak_f32 v95, v105, v95, 0x3fcc422a
	v_fmaak_f32 v98, v80, v98, 0x3fcc422a
	v_fmaak_f32 v99, v81, v99, 0x3fcc422a
	v_mul_f32_e32 v90, v102, v90
	v_mul_f32_e32 v91, v103, v91
	v_mul_f32_e32 v94, v104, v94
	v_mul_f32_e32 v95, v105, v95
	v_mul_f32_e32 v98, v80, v98
	v_mul_f32_e32 v99, v81, v99
	v_mul_f32_e32 v90, 0xbfb8aa3b, v90
	v_mul_f32_e32 v91, 0xbfb8aa3b, v91
	v_mul_f32_e32 v94, 0xbfb8aa3b, v94
	v_mul_f32_e32 v95, 0xbfb8aa3b, v95
	v_mul_f32_e32 v98, 0xbfb8aa3b, v98
	v_mul_f32_e32 v99, 0xbfb8aa3b, v99
	v_exp_f32_e32 v90, v90
	v_exp_f32_e32 v91, v91
	v_exp_f32_e32 v94, v94
	v_exp_f32_e32 v95, v95
	v_exp_f32_e32 v98, v98
	v_exp_f32_e32 v99, v99
	v_add_f32_e32 v88, 1.0, v88
	v_add_f32_e32 v89, 1.0, v89
	v_add_f32_e32 v90, 1.0, v90
	v_add_f32_e32 v91, 1.0, v91
	v_add_f32_e32 v94, 1.0, v94
	v_add_f32_e32 v95, 1.0, v95
	v_add_f32_e32 v98, 1.0, v98
	v_add_f32_e32 v99, 1.0, v99
	v_rcp_f32_e32 v88, v88
	v_rcp_f32_e32 v89, v89
	v_rcp_f32_e32 v90, v90
	v_rcp_f32_e32 v91, v91
	v_rcp_f32_e32 v94, v94
	v_rcp_f32_e32 v95, v95
	v_rcp_f32_e32 v98, v98
	v_rcp_f32_e32 v99, v99
	v_mul_f32_e32 v88, v100, v88
	v_mul_f32_e32 v89, v101, v89
	v_mul_f32_e32 v90, v102, v90
	v_mul_f32_e32 v91, v103, v91
	v_mul_f32_e32 v94, v104, v94
	v_mul_f32_e32 v95, v105, v95
	v_mul_f32_e32 v80, v80, v98
	v_mul_f32_e32 v81, v81, v99
	v_cvt_pk_bf16_f32 v88, v88, v89
	v_cvt_pk_bf16_f32 v89, v90, v91
	v_cvt_pk_bf16_f32 v90, v94, v95
	v_cvt_pk_bf16_f32 v91, v80, v81
	v_mul_f32_e32 v80, v86, v108
	v_mul_f32_e32 v81, v87, v109
	v_mul_f32_e32 v82, v82, v108
	v_mul_f32_e32 v83, v83, v109
	global_store_dwordx4 v[84:85], v[88:91], off
	v_mul_f32_e32 v86, 0x3d922279, v96
	v_mul_f32_e32 v87, 0x3d922279, v97
	v_mul_f32_e32 v88, 0x3d922279, v80
	v_mul_f32_e32 v89, 0x3d922279, v81
	v_mul_f32_e32 v90, 0x3d922279, v92
	v_mul_f32_e32 v91, 0x3d922279, v93
	v_mul_f32_e32 v94, 0x3d922279, v82
	v_mul_f32_e32 v95, 0x3d922279, v83
	v_fmaak_f32 v86, v96, v86, 0x3fcc422a
	v_fmaak_f32 v87, v97, v87, 0x3fcc422a
	v_fmaak_f32 v88, v80, v88, 0x3fcc422a
	v_fmaak_f32 v89, v81, v89, 0x3fcc422a
	v_fmaak_f32 v90, v92, v90, 0x3fcc422a
	v_fmaak_f32 v91, v93, v91, 0x3fcc422a
	v_fmaak_f32 v94, v82, v94, 0x3fcc422a
	v_fmaak_f32 v95, v83, v95, 0x3fcc422a
	v_mul_f32_e32 v86, v96, v86
	v_mul_f32_e32 v87, v97, v87
	v_mul_f32_e32 v88, v80, v88
	v_mul_f32_e32 v89, v81, v89
	v_mul_f32_e32 v90, v92, v90
	v_mul_f32_e32 v91, v93, v91
	v_mul_f32_e32 v94, v82, v94
	v_mul_f32_e32 v95, v83, v95
	v_mul_f32_e32 v86, 0xbfb8aa3b, v86
	v_mul_f32_e32 v87, 0xbfb8aa3b, v87
	v_mul_f32_e32 v88, 0xbfb8aa3b, v88
	v_mul_f32_e32 v89, 0xbfb8aa3b, v89
	v_mul_f32_e32 v90, 0xbfb8aa3b, v90
	v_mul_f32_e32 v91, 0xbfb8aa3b, v91
	v_mul_f32_e32 v94, 0xbfb8aa3b, v94
	v_mul_f32_e32 v95, 0xbfb8aa3b, v95
	v_exp_f32_e32 v86, v86
	v_exp_f32_e32 v87, v87
	v_exp_f32_e32 v88, v88
	v_exp_f32_e32 v89, v89
	v_exp_f32_e32 v90, v90
	v_exp_f32_e32 v91, v91
	v_exp_f32_e32 v94, v94
	v_exp_f32_e32 v95, v95
	v_add_f32_e32 v86, 1.0, v86
	v_add_f32_e32 v87, 1.0, v87
	v_add_f32_e32 v88, 1.0, v88
	v_add_f32_e32 v89, 1.0, v89
	v_add_f32_e32 v90, 1.0, v90
	v_add_f32_e32 v91, 1.0, v91
	v_add_f32_e32 v94, 1.0, v94
	v_add_f32_e32 v95, 1.0, v95
	v_rcp_f32_e32 v86, v86
	v_rcp_f32_e32 v87, v87
	v_rcp_f32_e32 v88, v88
	v_rcp_f32_e32 v89, v89
	v_rcp_f32_e32 v90, v90
	v_rcp_f32_e32 v91, v91
	v_rcp_f32_e32 v94, v94
	v_rcp_f32_e32 v95, v95
	v_mul_f32_e32 v86, v96, v86
	v_mul_f32_e32 v87, v97, v87
	v_mul_f32_e32 v88, v80, v88
	v_mul_f32_e32 v89, v81, v89
	v_mul_f32_e32 v90, v92, v90
	v_mul_f32_e32 v91, v93, v91
	v_mul_f32_e32 v92, v82, v94
	v_mul_f32_e32 v93, v83, v95
	v_cvt_pk_bf16_f32 v80, v86, v87
	v_cvt_pk_bf16_f32 v81, v88, v89
	v_cvt_pk_bf16_f32 v82, v90, v91
	v_cvt_pk_bf16_f32 v83, v92, v93
	global_store_dwordx4 v[84:85], v[80:83], off offset:256
; DI float gelu_tanh(float x) { const float t = x * (1.5957691216f + 0.0713548163f * x * x); return x * __builtin_amdgcn_rcpf(1.f + __builtin_amdgcn_exp2f(-1.4426950409f * t)); }
; #define ROWS8 _Pragma("unroll") for (int ai = 0; ai < 2; ++ai) _Pragma("unroll") for (int m = 0; m < 4; ++m) if (ai == 0 || !hf)
; #define COLS4 _Pragma("unroll") for (int bj = 0; bj < 2; ++bj) _Pragma("unroll") for (int n = 0; n < 2; ++n)
; #define LOAD_ROW_RS(rsv, ssqp, invn) float rsv[2][4]; ROWS8_ALL rsv[ai][m] = (ssqp)[row0 + ai * HALF + m * 16]; ROWS8_ALL rsv[ai][m] = rstd_of(rsv[ai][m], invn)
; #define PK8(v0, v1) ({ const u32x2 h0_ = pk4(v0), h1_ = pk4(v1); (u32x4){h0_.x, h0_.y, h1_.x, h1_.y}; })
;     DI void operator()(const Acc& acc, const Unit& u, int wr, int wc, int fr, int fq) const {
;     ...
;                 LOAD_ROW_RS(rsv, SSQ(0), 1.f / 2048.f);
;                 ROWS8 { const int r = row0 + ai * HALF + m * 16; const float rs = rsv[ai][m];
;                     if (u.pn < 4) { bf16_t* dst = WSB(OFF_U) + (size_t)r * 1024 + colp;
; #pragma unroll
;                         for (int bj = 0; bj < 2; ++bj) { f32x4 v0 = acc[ai][bj][m][0] * rs, v1 = acc[ai][bj][m][1] * rs;
;                             v0[0] = gelu_tanh(v0[0]); v0[1] = gelu_tanh(v0[1]); v0[2] = gelu_tanh(v0[2]); v0[3] = gelu_tanh(v0[3]);
;                             v1[0] = gelu_tanh(v1[0]); v1[1] = gelu_tanh(v1[1]); v1[2] = gelu_tanh(v1[2]); v1[3] = gelu_tanh(v1[3]);
;                             *(u32x4*)(dst + bj * HALF) = PK8(v0, v1); }
;                     } else { float* dst = WSF(OFF_Z) + (size_t)r * 1024 + (colp - 1024);
;                         COLS4 *(f32x4*)(dst + bj * HALF + n * 4) = acc[ai][bj][m][n] * rs;
;                     }
.LBB0_375:
	s_nop 1
	v_fmamk_f32 v80, v172, 0x3a000000, v233
	v_rsq_f32_e32 v92, v80
	s_mov_b64 s[46:47], -1
	s_and_b64 vcc, exec, s[4:5]
	v_mov_b32_e32 v93, v92
	v_mul_f32_e32 v86, v78, v92
	v_mul_f32_e32 v87, v79, v92
	v_mul_f32_e32 v84, v76, v92
	v_mul_f32_e32 v85, v77, v92
	v_mul_f32_e32 v88, v72, v92
	v_mul_f32_e32 v89, v73, v93
	v_mul_f32_e32 v80, v68, v92
	v_mul_f32_e32 v81, v69, v93
	v_mul_f32_e32 v76, v64, v92
	v_mul_f32_e32 v77, v65, v93
	s_cbranch_vccnz .LBB0_377
	v_lshlrev_b64 v[64:65], 12, v[160:161]
	v_lshl_add_u64 v[64:65], s[10:11], 0, v[64:65]
	v_lshl_add_u64 v[64:65], v[156:157], 2, v[64:65]
	v_add_co_u32_e32 v64, vcc, 0xefff000, v64
	v_mov_b32_e32 v93, v92
	s_nop 0
	v_addc_co_u32_e32 v65, vcc, 0, v65, vcc
	v_mul_f32_e32 v90, v74, v92
	v_mul_f32_e32 v91, v75, v93
	v_mul_f32_e32 v82, v70, v92
	v_mul_f32_e32 v83, v71, v93
	v_mul_f32_e32 v78, v66, v92
	v_mul_f32_e32 v79, v67, v93
	s_mov_b64 s[46:47], 0
	global_store_dwordx4 v[64:65], v[84:87], off
	global_store_dwordx4 v[64:65], v[88:91], off offset:16
	global_store_dwordx4 v[64:65], v[80:83], off offset:512
	global_store_dwordx4 v[64:65], v[76:79], off offset:528
.LBB0_377:
	s_andn2_b64 vcc, exec, s[46:47]
	s_cbranch_vccnz .LBB0_379
	v_lshlrev_b64 v[64:65], 11, v[160:161]
	v_lshl_add_u64 v[64:65], s[22:23], 0, v[64:65]
	v_lshl_add_u64 v[68:69], v[156:157], 1, v[64:65]
	v_mul_f32_e32 v64, 0x3d922279, v84
	v_fmaak_f32 v64, v84, v64, 0x3fcc422a
	v_mul_f32_e32 v64, v84, v64
	v_mul_f32_e32 v64, 0xbfb8aa3b, v64
	v_exp_f32_e32 v72, v64
	v_mul_f32_e32 v64, 0x3d922279, v85
	v_fmaak_f32 v64, v85, v64, 0x3fcc422a
	v_mul_f32_e32 v64, v85, v64
	v_mov_b32_e32 v93, v92
	v_mul_f32_e32 v64, 0xbfb8aa3b, v64
	v_exp_f32_e32 v73, v64
	v_mul_f32_e32 v64, v74, v92
	v_mul_f32_e32 v65, v75, v93
	v_mul_f32_e32 v74, 0x3d922279, v86
	v_mul_f32_e32 v75, 0x3d922279, v87
	v_mul_f32_e32 v78, 0x3d922279, v88
	v_mul_f32_e32 v79, 0x3d922279, v89
	v_mul_f32_e32 v82, 0x3d922279, v64
	v_mul_f32_e32 v83, 0x3d922279, v65
	v_fmaak_f32 v74, v86, v74, 0x3fcc422a
	v_fmaak_f32 v75, v87, v75, 0x3fcc422a
	v_fmaak_f32 v78, v88, v78, 0x3fcc422a
	v_fmaak_f32 v79, v89, v79, 0x3fcc422a
	v_fmaak_f32 v82, v64, v82, 0x3fcc422a
	v_fmaak_f32 v83, v65, v83, 0x3fcc422a
	v_mul_f32_e32 v74, v86, v74
	v_mul_f32_e32 v75, v87, v75
	v_mul_f32_e32 v78, v88, v78
	v_mul_f32_e32 v79, v89, v79
	v_mul_f32_e32 v82, v64, v82
	v_mul_f32_e32 v83, v65, v83
	v_mul_f32_e32 v74, 0xbfb8aa3b, v74
	v_mul_f32_e32 v75, 0xbfb8aa3b, v75
	v_mul_f32_e32 v78, 0xbfb8aa3b, v78
	v_mul_f32_e32 v79, 0xbfb8aa3b, v79
	v_mul_f32_e32 v82, 0xbfb8aa3b, v82
	v_mul_f32_e32 v83, 0xbfb8aa3b, v83
	v_exp_f32_e32 v74, v74
	v_exp_f32_e32 v75, v75
	v_exp_f32_e32 v78, v78
	v_exp_f32_e32 v79, v79
	v_exp_f32_e32 v82, v82
	v_exp_f32_e32 v83, v83
	v_add_f32_e32 v72, 1.0, v72
	v_add_f32_e32 v73, 1.0, v73
	v_add_f32_e32 v74, 1.0, v74
	v_add_f32_e32 v75, 1.0, v75
	v_add_f32_e32 v78, 1.0, v78
	v_add_f32_e32 v79, 1.0, v79
	v_add_f32_e32 v82, 1.0, v82
	v_add_f32_e32 v83, 1.0, v83
	v_rcp_f32_e32 v72, v72
	v_rcp_f32_e32 v73, v73
	v_rcp_f32_e32 v74, v74
	v_rcp_f32_e32 v75, v75
	v_rcp_f32_e32 v78, v78
	v_rcp_f32_e32 v79, v79
	v_rcp_f32_e32 v82, v82
	v_rcp_f32_e32 v83, v83
	v_mul_f32_e32 v72, v84, v72
	v_mul_f32_e32 v73, v85, v73
	v_mul_f32_e32 v74, v86, v74
	v_mul_f32_e32 v75, v87, v75
	v_mul_f32_e32 v78, v88, v78
	v_mul_f32_e32 v79, v89, v79
	v_mul_f32_e32 v64, v64, v82
	v_mul_f32_e32 v65, v65, v83
	v_cvt_pk_bf16_f32 v72, v72, v73
	v_cvt_pk_bf16_f32 v73, v74, v75
	v_cvt_pk_bf16_f32 v74, v78, v79
	v_cvt_pk_bf16_f32 v75, v64, v65
	v_mul_f32_e32 v64, v70, v92
	v_mul_f32_e32 v65, v71, v93
	v_mul_f32_e32 v66, v66, v92
	v_mul_f32_e32 v67, v67, v93
	global_store_dwordx4 v[68:69], v[72:75], off
	v_mul_f32_e32 v70, 0x3d922279, v80
	v_mul_f32_e32 v71, 0x3d922279, v81
	v_mul_f32_e32 v72, 0x3d922279, v64
	v_mul_f32_e32 v73, 0x3d922279, v65
	v_mul_f32_e32 v74, 0x3d922279, v76
	v_mul_f32_e32 v75, 0x3d922279, v77
	v_mul_f32_e32 v78, 0x3d922279, v66
	v_mul_f32_e32 v79, 0x3d922279, v67
	v_fmaak_f32 v70, v80, v70, 0x3fcc422a
	v_fmaak_f32 v71, v81, v71, 0x3fcc422a
	v_fmaak_f32 v72, v64, v72, 0x3fcc422a
	v_fmaak_f32 v73, v65, v73, 0x3fcc422a
	v_fmaak_f32 v74, v76, v74, 0x3fcc422a
	v_fmaak_f32 v75, v77, v75, 0x3fcc422a
	v_fmaak_f32 v78, v66, v78, 0x3fcc422a
	v_fmaak_f32 v79, v67, v79, 0x3fcc422a
	v_mul_f32_e32 v70, v80, v70
	v_mul_f32_e32 v71, v81, v71
	v_mul_f32_e32 v72, v64, v72
	v_mul_f32_e32 v73, v65, v73
	v_mul_f32_e32 v74, v76, v74
	v_mul_f32_e32 v75, v77, v75
	v_mul_f32_e32 v78, v66, v78
	v_mul_f32_e32 v79, v67, v79
	v_mul_f32_e32 v70, 0xbfb8aa3b, v70
	v_mul_f32_e32 v71, 0xbfb8aa3b, v71
	v_mul_f32_e32 v72, 0xbfb8aa3b, v72
	v_mul_f32_e32 v73, 0xbfb8aa3b, v73
	v_mul_f32_e32 v74, 0xbfb8aa3b, v74
	v_mul_f32_e32 v75, 0xbfb8aa3b, v75
	v_mul_f32_e32 v78, 0xbfb8aa3b, v78
	v_mul_f32_e32 v79, 0xbfb8aa3b, v79
	v_exp_f32_e32 v70, v70
	v_exp_f32_e32 v71, v71
	v_exp_f32_e32 v72, v72
	v_exp_f32_e32 v73, v73
	v_exp_f32_e32 v74, v74
	v_exp_f32_e32 v75, v75
	v_exp_f32_e32 v78, v78
	v_exp_f32_e32 v79, v79
	v_add_f32_e32 v70, 1.0, v70
	v_add_f32_e32 v71, 1.0, v71
	v_add_f32_e32 v72, 1.0, v72
	v_add_f32_e32 v73, 1.0, v73
	v_add_f32_e32 v74, 1.0, v74
	v_add_f32_e32 v75, 1.0, v75
	v_add_f32_e32 v78, 1.0, v78
	v_add_f32_e32 v79, 1.0, v79
	v_rcp_f32_e32 v70, v70
	v_rcp_f32_e32 v71, v71
	v_rcp_f32_e32 v72, v72
	v_rcp_f32_e32 v73, v73
	v_rcp_f32_e32 v74, v74
	v_rcp_f32_e32 v75, v75
	v_rcp_f32_e32 v78, v78
	v_rcp_f32_e32 v79, v79
	v_mul_f32_e32 v70, v80, v70
	v_mul_f32_e32 v71, v81, v71
	v_mul_f32_e32 v72, v64, v72
	v_mul_f32_e32 v73, v65, v73
	v_mul_f32_e32 v74, v76, v74
	v_mul_f32_e32 v75, v77, v75
	v_mul_f32_e32 v76, v66, v78
	v_mul_f32_e32 v77, v67, v79
	v_cvt_pk_bf16_f32 v64, v70, v71
	v_cvt_pk_bf16_f32 v65, v72, v73
	v_cvt_pk_bf16_f32 v66, v74, v75
	v_cvt_pk_bf16_f32 v67, v76, v77
	global_store_dwordx4 v[68:69], v[64:67], off offset:256
; DI float gelu_tanh(float x) { const float t = x * (1.5957691216f + 0.0713548163f * x * x); return x * __builtin_amdgcn_rcpf(1.f + __builtin_amdgcn_exp2f(-1.4426950409f * t)); }
; #define ROWS8 _Pragma("unroll") for (int ai = 0; ai < 2; ++ai) _Pragma("unroll") for (int m = 0; m < 4; ++m) if (ai == 0 || !hf)
; #define COLS4 _Pragma("unroll") for (int bj = 0; bj < 2; ++bj) _Pragma("unroll") for (int n = 0; n < 2; ++n)
; #define LOAD_ROW_RS(rsv, ssqp, invn) float rsv[2][4]; ROWS8_ALL rsv[ai][m] = (ssqp)[row0 + ai * HALF + m * 16]; ROWS8_ALL rsv[ai][m] = rstd_of(rsv[ai][m], invn)
; #define PK8(v0, v1) ({ const u32x2 h0_ = pk4(v0), h1_ = pk4(v1); (u32x4){h0_.x, h0_.y, h1_.x, h1_.y}; })
;     DI void operator()(const Acc& acc, const Unit& u, int wr, int wc, int fr, int fq) const {
;     ...
;                 LOAD_ROW_RS(rsv, SSQ(0), 1.f / 2048.f);
;                 ROWS8 { const int r = row0 + ai * HALF + m * 16; const float rs = rsv[ai][m];
;                     if (u.pn < 4) { bf16_t* dst = WSB(OFF_U) + (size_t)r * 1024 + colp;
; #pragma unroll
;                         for (int bj = 0; bj < 2; ++bj) { f32x4 v0 = acc[ai][bj][m][0] * rs, v1 = acc[ai][bj][m][1] * rs;
;                             v0[0] = gelu_tanh(v0[0]); v0[1] = gelu_tanh(v0[1]); v0[2] = gelu_tanh(v0[2]); v0[3] = gelu_tanh(v0[3]);
;                             v1[0] = gelu_tanh(v1[0]); v1[1] = gelu_tanh(v1[1]); v1[2] = gelu_tanh(v1[2]); v1[3] = gelu_tanh(v1[3]);
;                             *(u32x4*)(dst + bj * HALF) = PK8(v0, v1); }
;                     } else { float* dst = WSF(OFF_Z) + (size_t)r * 1024 + (colp - 1024);
;                         COLS4 *(f32x4*)(dst + bj * HALF + n * 4) = acc[ai][bj][m][n] * rs;
;                     }
.LBB0_379:
	s_nop 1
	v_fmamk_f32 v64, v171, 0x3a000000, v233
	v_rsq_f32_e32 v76, v64
	v_add_u32_e32 v78, 0x80, v158
	v_ashrrev_i32_e32 v79, 31, v78
	s_mov_b64 s[46:47], -1
	v_mov_b32_e32 v77, v76
	v_mul_f32_e32 v70, v62, v76
	v_mul_f32_e32 v71, v63, v76
	v_mul_f32_e32 v68, v60, v76
	v_mul_f32_e32 v69, v61, v76
	s_and_b64 vcc, exec, s[4:5]
	v_mul_f32_e32 v72, v56, v76
	v_mul_f32_e32 v73, v57, v77
	v_mul_f32_e32 v64, v52, v76
	v_mul_f32_e32 v65, v53, v77
	v_mul_f32_e32 v60, v48, v76
	v_mul_f32_e32 v61, v49, v77
	s_cbranch_vccnz .LBB0_381
	v_lshlrev_b64 v[48:49], 12, v[78:79]
	v_lshl_add_u64 v[48:49], s[10:11], 0, v[48:49]
	v_lshl_add_u64 v[48:49], v[156:157], 2, v[48:49]
	v_add_co_u32_e32 v48, vcc, 0xefff000, v48
	v_mov_b32_e32 v77, v76
	s_nop 0
	v_addc_co_u32_e32 v49, vcc, 0, v49, vcc
	v_mul_f32_e32 v74, v58, v76
	v_mul_f32_e32 v75, v59, v77
	v_mul_f32_e32 v66, v54, v76
	v_mul_f32_e32 v67, v55, v77
	v_mul_f32_e32 v62, v50, v76
	v_mul_f32_e32 v63, v51, v77
	s_mov_b64 s[46:47], 0
	global_store_dwordx4 v[48:49], v[68:71], off
	global_store_dwordx4 v[48:49], v[72:75], off offset:16
	global_store_dwordx4 v[48:49], v[64:67], off offset:512
	global_store_dwordx4 v[48:49], v[60:63], off offset:528
.LBB0_381:
	s_andn2_b64 vcc, exec, s[46:47]
	s_cbranch_vccnz .LBB0_383
	v_lshlrev_b64 v[48:49], 11, v[78:79]
	v_lshl_add_u64 v[48:49], s[22:23], 0, v[48:49]
	v_lshl_add_u64 v[52:53], v[156:157], 1, v[48:49]
	v_mul_f32_e32 v48, 0x3d922279, v68
	v_fmaak_f32 v48, v68, v48, 0x3fcc422a
	v_mul_f32_e32 v48, v68, v48
	v_mul_f32_e32 v48, 0xbfb8aa3b, v48
	v_exp_f32_e32 v56, v48
	v_mul_f32_e32 v48, 0x3d922279, v69
	v_fmaak_f32 v48, v69, v48, 0x3fcc422a
	v_mul_f32_e32 v48, v69, v48
	v_mov_b32_e32 v77, v76
	v_mul_f32_e32 v48, 0xbfb8aa3b, v48
	v_exp_f32_e32 v57, v48
	v_mul_f32_e32 v48, v58, v76
	v_mul_f32_e32 v49, v59, v77
	v_mul_f32_e32 v58, 0x3d922279, v70
	v_mul_f32_e32 v59, 0x3d922279, v71
	v_mul_f32_e32 v62, 0x3d922279, v72
	v_mul_f32_e32 v63, 0x3d922279, v73
	v_mul_f32_e32 v66, 0x3d922279, v48
	v_mul_f32_e32 v67, 0x3d922279, v49
	v_fmaak_f32 v58, v70, v58, 0x3fcc422a
	v_fmaak_f32 v59, v71, v59, 0x3fcc422a
	v_fmaak_f32 v62, v72, v62, 0x3fcc422a
	v_fmaak_f32 v63, v73, v63, 0x3fcc422a
	v_fmaak_f32 v66, v48, v66, 0x3fcc422a
	v_fmaak_f32 v67, v49, v67, 0x3fcc422a
	v_mul_f32_e32 v58, v70, v58
	v_mul_f32_e32 v59, v71, v59
	v_mul_f32_e32 v62, v72, v62
	v_mul_f32_e32 v63, v73, v63
	v_mul_f32_e32 v66, v48, v66
	v_mul_f32_e32 v67, v49, v67
	v_mul_f32_e32 v58, 0xbfb8aa3b, v58
	v_mul_f32_e32 v59, 0xbfb8aa3b, v59
	v_mul_f32_e32 v62, 0xbfb8aa3b, v62
	v_mul_f32_e32 v63, 0xbfb8aa3b, v63
	v_mul_f32_e32 v66, 0xbfb8aa3b, v66
	v_mul_f32_e32 v67, 0xbfb8aa3b, v67
	v_exp_f32_e32 v58, v58
	v_exp_f32_e32 v59, v59
	v_exp_f32_e32 v62, v62
	v_exp_f32_e32 v63, v63
	v_exp_f32_e32 v66, v66
	v_exp_f32_e32 v67, v67
	v_add_f32_e32 v56, 1.0, v56
	v_add_f32_e32 v57, 1.0, v57
	v_add_f32_e32 v58, 1.0, v58
	v_add_f32_e32 v59, 1.0, v59
	v_add_f32_e32 v62, 1.0, v62
	v_add_f32_e32 v63, 1.0, v63
	v_add_f32_e32 v66, 1.0, v66
	v_add_f32_e32 v67, 1.0, v67
	v_rcp_f32_e32 v56, v56
	v_rcp_f32_e32 v57, v57
	v_rcp_f32_e32 v58, v58
	v_rcp_f32_e32 v59, v59
	v_rcp_f32_e32 v62, v62
	v_rcp_f32_e32 v63, v63
	v_rcp_f32_e32 v66, v66
	v_rcp_f32_e32 v67, v67
	v_mul_f32_e32 v56, v68, v56
	v_mul_f32_e32 v57, v69, v57
	v_mul_f32_e32 v58, v70, v58
	v_mul_f32_e32 v59, v71, v59
	v_mul_f32_e32 v62, v72, v62
	v_mul_f32_e32 v63, v73, v63
	v_mul_f32_e32 v48, v48, v66
	v_mul_f32_e32 v49, v49, v67
	v_cvt_pk_bf16_f32 v56, v56, v57
	v_cvt_pk_bf16_f32 v57, v58, v59
	v_cvt_pk_bf16_f32 v58, v62, v63
	v_cvt_pk_bf16_f32 v59, v48, v49
	v_mul_f32_e32 v48, v54, v76
	v_mul_f32_e32 v49, v55, v77
	v_mul_f32_e32 v50, v50, v76
	v_mul_f32_e32 v51, v51, v77
	global_store_dwordx4 v[52:53], v[56:59], off
	v_mul_f32_e32 v54, 0x3d922279, v64
	v_mul_f32_e32 v55, 0x3d922279, v65
	v_mul_f32_e32 v56, 0x3d922279, v48
	v_mul_f32_e32 v57, 0x3d922279, v49
	v_mul_f32_e32 v58, 0x3d922279, v60
	v_mul_f32_e32 v59, 0x3d922279, v61
	v_mul_f32_e32 v62, 0x3d922279, v50
	v_mul_f32_e32 v63, 0x3d922279, v51
	v_fmaak_f32 v54, v64, v54, 0x3fcc422a
	v_fmaak_f32 v55, v65, v55, 0x3fcc422a
	v_fmaak_f32 v56, v48, v56, 0x3fcc422a
	v_fmaak_f32 v57, v49, v57, 0x3fcc422a
	v_fmaak_f32 v58, v60, v58, 0x3fcc422a
	v_fmaak_f32 v59, v61, v59, 0x3fcc422a
	v_fmaak_f32 v62, v50, v62, 0x3fcc422a
	v_fmaak_f32 v63, v51, v63, 0x3fcc422a
	v_mul_f32_e32 v54, v64, v54
	v_mul_f32_e32 v55, v65, v55
	v_mul_f32_e32 v56, v48, v56
	v_mul_f32_e32 v57, v49, v57
	v_mul_f32_e32 v58, v60, v58
	v_mul_f32_e32 v59, v61, v59
	v_mul_f32_e32 v62, v50, v62
	v_mul_f32_e32 v63, v51, v63
	v_mul_f32_e32 v54, 0xbfb8aa3b, v54
	v_mul_f32_e32 v55, 0xbfb8aa3b, v55
	v_mul_f32_e32 v56, 0xbfb8aa3b, v56
	v_mul_f32_e32 v57, 0xbfb8aa3b, v57
	v_mul_f32_e32 v58, 0xbfb8aa3b, v58
	v_mul_f32_e32 v59, 0xbfb8aa3b, v59
	v_mul_f32_e32 v62, 0xbfb8aa3b, v62
	v_mul_f32_e32 v63, 0xbfb8aa3b, v63
	v_exp_f32_e32 v54, v54
	v_exp_f32_e32 v55, v55
	v_exp_f32_e32 v56, v56
	v_exp_f32_e32 v57, v57
	v_exp_f32_e32 v58, v58
	v_exp_f32_e32 v59, v59
	v_exp_f32_e32 v62, v62
	v_exp_f32_e32 v63, v63
	v_add_f32_e32 v54, 1.0, v54
	v_add_f32_e32 v55, 1.0, v55
	v_add_f32_e32 v56, 1.0, v56
	v_add_f32_e32 v57, 1.0, v57
	v_add_f32_e32 v58, 1.0, v58
	v_add_f32_e32 v59, 1.0, v59
	v_add_f32_e32 v62, 1.0, v62
	v_add_f32_e32 v63, 1.0, v63
	v_rcp_f32_e32 v54, v54
	v_rcp_f32_e32 v55, v55
	v_rcp_f32_e32 v56, v56
	v_rcp_f32_e32 v57, v57
	v_rcp_f32_e32 v58, v58
	v_rcp_f32_e32 v59, v59
	v_rcp_f32_e32 v62, v62
	v_rcp_f32_e32 v63, v63
	v_mul_f32_e32 v54, v64, v54
	v_mul_f32_e32 v55, v65, v55
	v_mul_f32_e32 v56, v48, v56
	v_mul_f32_e32 v57, v49, v57
	v_mul_f32_e32 v58, v60, v58
	v_mul_f32_e32 v59, v61, v59
	v_mul_f32_e32 v60, v50, v62
	v_mul_f32_e32 v61, v51, v63
	v_cvt_pk_bf16_f32 v48, v54, v55
	v_cvt_pk_bf16_f32 v49, v56, v57
	v_cvt_pk_bf16_f32 v50, v58, v59
	v_cvt_pk_bf16_f32 v51, v60, v61
	global_store_dwordx4 v[52:53], v[48:51], off offset:256
; DI float gelu_tanh(float x) { const float t = x * (1.5957691216f + 0.0713548163f * x * x); return x * __builtin_amdgcn_rcpf(1.f + __builtin_amdgcn_exp2f(-1.4426950409f * t)); }
; #define ROWS8 _Pragma("unroll") for (int ai = 0; ai < 2; ++ai) _Pragma("unroll") for (int m = 0; m < 4; ++m) if (ai == 0 || !hf)
; #define COLS4 _Pragma("unroll") for (int bj = 0; bj < 2; ++bj) _Pragma("unroll") for (int n = 0; n < 2; ++n)
; #define LOAD_ROW_RS(rsv, ssqp, invn) float rsv[2][4]; ROWS8_ALL rsv[ai][m] = (ssqp)[row0 + ai * HALF + m * 16]; ROWS8_ALL rsv[ai][m] = rstd_of(rsv[ai][m], invn)
; #define PK8(v0, v1) ({ const u32x2 h0_ = pk4(v0), h1_ = pk4(v1); (u32x4){h0_.x, h0_.y, h1_.x, h1_.y}; })
;     DI void operator()(const Acc& acc, const Unit& u, int wr, int wc, int fr, int fq) const {
;     ...
;                 LOAD_ROW_RS(rsv, SSQ(0), 1.f / 2048.f);
;                 ROWS8 { const int r = row0 + ai * HALF + m * 16; const float rs = rsv[ai][m];
;                     if (u.pn < 4) { bf16_t* dst = WSB(OFF_U) + (size_t)r * 1024 + colp;
; #pragma unroll
;                         for (int bj = 0; bj < 2; ++bj) { f32x4 v0 = acc[ai][bj][m][0] * rs, v1 = acc[ai][bj][m][1] * rs;
;                             v0[0] = gelu_tanh(v0[0]); v0[1] = gelu_tanh(v0[1]); v0[2] = gelu_tanh(v0[2]); v0[3] = gelu_tanh(v0[3]);
;                             v1[0] = gelu_tanh(v1[0]); v1[1] = gelu_tanh(v1[1]); v1[2] = gelu_tanh(v1[2]); v1[3] = gelu_tanh(v1[3]);
;                             *(u32x4*)(dst + bj * HALF) = PK8(v0, v1); }
;                     } else { float* dst = WSF(OFF_Z) + (size_t)r * 1024 + (colp - 1024);
;                         COLS4 *(f32x4*)(dst + bj * HALF + n * 4) = acc[ai][bj][m][n] * rs;
;                     }
.LBB0_383:
	s_nop 1
	v_fmamk_f32 v48, v170, 0x3a000000, v233
	v_rsq_f32_e32 v60, v48
	v_add_u32_e32 v62, 0x90, v158
	v_ashrrev_i32_e32 v63, 31, v62
	s_mov_b64 s[46:47], -1
	v_mov_b32_e32 v61, v60
	v_mul_f32_e32 v54, v46, v60
	v_mul_f32_e32 v55, v47, v60
	v_mul_f32_e32 v52, v44, v60
	v_mul_f32_e32 v53, v45, v60
	s_and_b64 vcc, exec, s[4:5]
	v_mul_f32_e32 v56, v40, v60
	v_mul_f32_e32 v57, v41, v61
	v_mul_f32_e32 v48, v36, v60
	v_mul_f32_e32 v49, v37, v61
	v_mul_f32_e32 v44, v32, v60
	v_mul_f32_e32 v45, v33, v61
	s_cbranch_vccnz .LBB0_385
	v_lshlrev_b64 v[32:33], 12, v[62:63]
	v_lshl_add_u64 v[32:33], s[10:11], 0, v[32:33]
	v_lshl_add_u64 v[32:33], v[156:157], 2, v[32:33]
	v_add_co_u32_e32 v32, vcc, 0xefff000, v32
	v_mov_b32_e32 v61, v60
	s_nop 0
	v_addc_co_u32_e32 v33, vcc, 0, v33, vcc
	v_mul_f32_e32 v58, v42, v60
	v_mul_f32_e32 v59, v43, v61
	v_mul_f32_e32 v50, v38, v60
	v_mul_f32_e32 v51, v39, v61
	v_mul_f32_e32 v46, v34, v60
	v_mul_f32_e32 v47, v35, v61
	s_mov_b64 s[46:47], 0
	global_store_dwordx4 v[32:33], v[52:55], off
	global_store_dwordx4 v[32:33], v[56:59], off offset:16
	global_store_dwordx4 v[32:33], v[48:51], off offset:512
	global_store_dwordx4 v[32:33], v[44:47], off offset:528
.LBB0_385:
	s_andn2_b64 vcc, exec, s[46:47]
	s_cbranch_vccnz .LBB0_387
	v_lshlrev_b64 v[32:33], 11, v[62:63]
	v_lshl_add_u64 v[32:33], s[22:23], 0, v[32:33]
	v_lshl_add_u64 v[36:37], v[156:157], 1, v[32:33]
	v_mul_f32_e32 v32, 0x3d922279, v52
	v_fmaak_f32 v32, v52, v32, 0x3fcc422a
	v_mul_f32_e32 v32, v52, v32
	v_mul_f32_e32 v32, 0xbfb8aa3b, v32
	v_exp_f32_e32 v40, v32
	v_mul_f32_e32 v32, 0x3d922279, v53
	v_fmaak_f32 v32, v53, v32, 0x3fcc422a
	v_mul_f32_e32 v32, v53, v32
	v_mov_b32_e32 v61, v60
	v_mul_f32_e32 v32, 0xbfb8aa3b, v32
	v_exp_f32_e32 v41, v32
	v_mul_f32_e32 v32, v42, v60
	v_mul_f32_e32 v33, v43, v61
	v_mul_f32_e32 v42, 0x3d922279, v54
	v_mul_f32_e32 v43, 0x3d922279, v55
	v_mul_f32_e32 v46, 0x3d922279, v56
	v_mul_f32_e32 v47, 0x3d922279, v57
	v_mul_f32_e32 v50, 0x3d922279, v32
	v_mul_f32_e32 v51, 0x3d922279, v33
	v_fmaak_f32 v42, v54, v42, 0x3fcc422a
	v_fmaak_f32 v43, v55, v43, 0x3fcc422a
	v_fmaak_f32 v46, v56, v46, 0x3fcc422a
	v_fmaak_f32 v47, v57, v47, 0x3fcc422a
	v_fmaak_f32 v50, v32, v50, 0x3fcc422a
	v_fmaak_f32 v51, v33, v51, 0x3fcc422a
	v_mul_f32_e32 v42, v54, v42
	v_mul_f32_e32 v43, v55, v43
	v_mul_f32_e32 v46, v56, v46
	v_mul_f32_e32 v47, v57, v47
	v_mul_f32_e32 v50, v32, v50
	v_mul_f32_e32 v51, v33, v51
	v_mul_f32_e32 v42, 0xbfb8aa3b, v42
	v_mul_f32_e32 v43, 0xbfb8aa3b, v43
	v_mul_f32_e32 v46, 0xbfb8aa3b, v46
	v_mul_f32_e32 v47, 0xbfb8aa3b, v47
	v_mul_f32_e32 v50, 0xbfb8aa3b, v50
	v_mul_f32_e32 v51, 0xbfb8aa3b, v51
	v_exp_f32_e32 v42, v42
	v_exp_f32_e32 v43, v43
	v_exp_f32_e32 v46, v46
	v_exp_f32_e32 v47, v47
	v_exp_f32_e32 v50, v50
	v_exp_f32_e32 v51, v51
	v_add_f32_e32 v40, 1.0, v40
	v_add_f32_e32 v41, 1.0, v41
	v_add_f32_e32 v42, 1.0, v42
	v_add_f32_e32 v43, 1.0, v43
	v_add_f32_e32 v46, 1.0, v46
	v_add_f32_e32 v47, 1.0, v47
	v_add_f32_e32 v50, 1.0, v50
	v_add_f32_e32 v51, 1.0, v51
	v_rcp_f32_e32 v40, v40
	v_rcp_f32_e32 v41, v41
	v_rcp_f32_e32 v42, v42
	v_rcp_f32_e32 v43, v43
	v_rcp_f32_e32 v46, v46
	v_rcp_f32_e32 v47, v47
	v_rcp_f32_e32 v50, v50
	v_rcp_f32_e32 v51, v51
	v_mul_f32_e32 v40, v52, v40
	v_mul_f32_e32 v41, v53, v41
	v_mul_f32_e32 v42, v54, v42
	v_mul_f32_e32 v43, v55, v43
	v_mul_f32_e32 v46, v56, v46
	v_mul_f32_e32 v47, v57, v47
	v_mul_f32_e32 v32, v32, v50
	v_mul_f32_e32 v33, v33, v51
	v_cvt_pk_bf16_f32 v40, v40, v41
	v_cvt_pk_bf16_f32 v41, v42, v43
	v_cvt_pk_bf16_f32 v42, v46, v47
	v_cvt_pk_bf16_f32 v43, v32, v33
	v_mul_f32_e32 v32, v38, v60
	v_mul_f32_e32 v33, v39, v61
	v_mul_f32_e32 v34, v34, v60
	v_mul_f32_e32 v35, v35, v61
	global_store_dwordx4 v[36:37], v[40:43], off
	v_mul_f32_e32 v38, 0x3d922279, v48
	v_mul_f32_e32 v39, 0x3d922279, v49
	v_mul_f32_e32 v40, 0x3d922279, v32
	v_mul_f32_e32 v41, 0x3d922279, v33
	v_mul_f32_e32 v42, 0x3d922279, v44
	v_mul_f32_e32 v43, 0x3d922279, v45
	v_mul_f32_e32 v46, 0x3d922279, v34
	v_mul_f32_e32 v47, 0x3d922279, v35
	v_fmaak_f32 v38, v48, v38, 0x3fcc422a
	v_fmaak_f32 v39, v49, v39, 0x3fcc422a
	v_fmaak_f32 v40, v32, v40, 0x3fcc422a
	v_fmaak_f32 v41, v33, v41, 0x3fcc422a
	v_fmaak_f32 v42, v44, v42, 0x3fcc422a
	v_fmaak_f32 v43, v45, v43, 0x3fcc422a
	v_fmaak_f32 v46, v34, v46, 0x3fcc422a
	v_fmaak_f32 v47, v35, v47, 0x3fcc422a
	v_mul_f32_e32 v38, v48, v38
	v_mul_f32_e32 v39, v49, v39
	v_mul_f32_e32 v40, v32, v40
	v_mul_f32_e32 v41, v33, v41
	v_mul_f32_e32 v42, v44, v42
	v_mul_f32_e32 v43, v45, v43
	v_mul_f32_e32 v46, v34, v46
	v_mul_f32_e32 v47, v35, v47
	v_mul_f32_e32 v38, 0xbfb8aa3b, v38
	v_mul_f32_e32 v39, 0xbfb8aa3b, v39
	v_mul_f32_e32 v40, 0xbfb8aa3b, v40
	v_mul_f32_e32 v41, 0xbfb8aa3b, v41
	v_mul_f32_e32 v42, 0xbfb8aa3b, v42
	v_mul_f32_e32 v43, 0xbfb8aa3b, v43
	v_mul_f32_e32 v46, 0xbfb8aa3b, v46
	v_mul_f32_e32 v47, 0xbfb8aa3b, v47
	v_exp_f32_e32 v38, v38
	v_exp_f32_e32 v39, v39
	v_exp_f32_e32 v40, v40
	v_exp_f32_e32 v41, v41
	v_exp_f32_e32 v42, v42
	v_exp_f32_e32 v43, v43
	v_exp_f32_e32 v46, v46
	v_exp_f32_e32 v47, v47
	v_add_f32_e32 v38, 1.0, v38
	v_add_f32_e32 v39, 1.0, v39
	v_add_f32_e32 v40, 1.0, v40
	v_add_f32_e32 v41, 1.0, v41
	v_add_f32_e32 v42, 1.0, v42
	v_add_f32_e32 v43, 1.0, v43
	v_add_f32_e32 v46, 1.0, v46
	v_add_f32_e32 v47, 1.0, v47
	v_rcp_f32_e32 v38, v38
	v_rcp_f32_e32 v39, v39
	v_rcp_f32_e32 v40, v40
	v_rcp_f32_e32 v41, v41
	v_rcp_f32_e32 v42, v42
	v_rcp_f32_e32 v43, v43
	v_rcp_f32_e32 v46, v46
	v_rcp_f32_e32 v47, v47
	v_mul_f32_e32 v38, v48, v38
	v_mul_f32_e32 v39, v49, v39
	v_mul_f32_e32 v40, v32, v40
	v_mul_f32_e32 v41, v33, v41
	v_mul_f32_e32 v42, v44, v42
	v_mul_f32_e32 v43, v45, v43
	v_mul_f32_e32 v44, v34, v46
	v_mul_f32_e32 v45, v35, v47
	v_cvt_pk_bf16_f32 v32, v38, v39
	v_cvt_pk_bf16_f32 v33, v40, v41
	v_cvt_pk_bf16_f32 v34, v42, v43
	v_cvt_pk_bf16_f32 v35, v44, v45
	global_store_dwordx4 v[36:37], v[32:35], off offset:256
; DI float gelu_tanh(float x) { const float t = x * (1.5957691216f + 0.0713548163f * x * x); return x * __builtin_amdgcn_rcpf(1.f + __builtin_amdgcn_exp2f(-1.4426950409f * t)); }
; #define ROWS8 _Pragma("unroll") for (int ai = 0; ai < 2; ++ai) _Pragma("unroll") for (int m = 0; m < 4; ++m) if (ai == 0 || !hf)
; #define COLS4 _Pragma("unroll") for (int bj = 0; bj < 2; ++bj) _Pragma("unroll") for (int n = 0; n < 2; ++n)
; #define LOAD_ROW_RS(rsv, ssqp, invn) float rsv[2][4]; ROWS8_ALL rsv[ai][m] = (ssqp)[row0 + ai * HALF + m * 16]; ROWS8_ALL rsv[ai][m] = rstd_of(rsv[ai][m], invn)
; #define PK8(v0, v1) ({ const u32x2 h0_ = pk4(v0), h1_ = pk4(v1); (u32x4){h0_.x, h0_.y, h1_.x, h1_.y}; })
;     DI void operator()(const Acc& acc, const Unit& u, int wr, int wc, int fr, int fq) const {
;     ...
;                 LOAD_ROW_RS(rsv, SSQ(0), 1.f / 2048.f);
;                 ROWS8 { const int r = row0 + ai * HALF + m * 16; const float rs = rsv[ai][m];
;                     if (u.pn < 4) { bf16_t* dst = WSB(OFF_U) + (size_t)r * 1024 + colp;
; #pragma unroll
;                         for (int bj = 0; bj < 2; ++bj) { f32x4 v0 = acc[ai][bj][m][0] * rs, v1 = acc[ai][bj][m][1] * rs;
;                             v0[0] = gelu_tanh(v0[0]); v0[1] = gelu_tanh(v0[1]); v0[2] = gelu_tanh(v0[2]); v0[3] = gelu_tanh(v0[3]);
;                             v1[0] = gelu_tanh(v1[0]); v1[1] = gelu_tanh(v1[1]); v1[2] = gelu_tanh(v1[2]); v1[3] = gelu_tanh(v1[3]);
;                             *(u32x4*)(dst + bj * HALF) = PK8(v0, v1); }
;                     } else { float* dst = WSF(OFF_Z) + (size_t)r * 1024 + (colp - 1024);
;                         COLS4 *(f32x4*)(dst + bj * HALF + n * 4) = acc[ai][bj][m][n] * rs;
;                     }
.LBB0_387:
	s_nop 1
	v_fmamk_f32 v32, v169, 0x3a000000, v233
	v_rsq_f32_e32 v44, v32
	v_add_u32_e32 v46, 0xa0, v158
	v_ashrrev_i32_e32 v47, 31, v46
	s_mov_b64 s[46:47], -1
	v_mov_b32_e32 v45, v44
	v_mul_f32_e32 v38, v30, v44
	v_mul_f32_e32 v39, v31, v44
	v_mul_f32_e32 v36, v28, v44
	v_mul_f32_e32 v37, v29, v44
	s_and_b64 vcc, exec, s[4:5]
	v_mul_f32_e32 v40, v24, v44
	v_mul_f32_e32 v41, v25, v45
	v_mul_f32_e32 v32, v20, v44
	v_mul_f32_e32 v33, v21, v45
	v_mul_f32_e32 v28, v16, v44
	v_mul_f32_e32 v29, v17, v45
	s_cbranch_vccnz .LBB0_389
	v_lshlrev_b64 v[16:17], 12, v[46:47]
	v_lshl_add_u64 v[16:17], s[10:11], 0, v[16:17]
	v_lshl_add_u64 v[16:17], v[156:157], 2, v[16:17]
	v_add_co_u32_e32 v16, vcc, 0xefff000, v16
	v_mov_b32_e32 v45, v44
	s_nop 0
	v_addc_co_u32_e32 v17, vcc, 0, v17, vcc
	v_mul_f32_e32 v42, v26, v44
	v_mul_f32_e32 v43, v27, v45
	v_mul_f32_e32 v34, v22, v44
	v_mul_f32_e32 v35, v23, v45
	v_mul_f32_e32 v30, v18, v44
	v_mul_f32_e32 v31, v19, v45
	s_mov_b64 s[46:47], 0
	global_store_dwordx4 v[16:17], v[36:39], off
	global_store_dwordx4 v[16:17], v[40:43], off offset:16
	global_store_dwordx4 v[16:17], v[32:35], off offset:512
	global_store_dwordx4 v[16:17], v[28:31], off offset:528
.LBB0_389:
	s_andn2_b64 vcc, exec, s[46:47]
	s_cbranch_vccnz .LBB0_391
	v_lshlrev_b64 v[16:17], 11, v[46:47]
	v_lshl_add_u64 v[16:17], s[22:23], 0, v[16:17]
	v_lshl_add_u64 v[20:21], v[156:157], 1, v[16:17]
	v_mul_f32_e32 v16, 0x3d922279, v36
	v_fmaak_f32 v16, v36, v16, 0x3fcc422a
	v_mul_f32_e32 v16, v36, v16
	v_mul_f32_e32 v16, 0xbfb8aa3b, v16
	v_exp_f32_e32 v24, v16
	v_mul_f32_e32 v16, 0x3d922279, v37
	v_fmaak_f32 v16, v37, v16, 0x3fcc422a
	v_mul_f32_e32 v16, v37, v16
	v_mov_b32_e32 v45, v44
	v_mul_f32_e32 v16, 0xbfb8aa3b, v16
	v_exp_f32_e32 v25, v16
	v_mul_f32_e32 v16, v26, v44
	v_mul_f32_e32 v17, v27, v45
	v_mul_f32_e32 v26, 0x3d922279, v38
	v_mul_f32_e32 v27, 0x3d922279, v39
	v_mul_f32_e32 v30, 0x3d922279, v40
	v_mul_f32_e32 v31, 0x3d922279, v41
	v_mul_f32_e32 v34, 0x3d922279, v16
	v_mul_f32_e32 v35, 0x3d922279, v17
	v_fmaak_f32 v26, v38, v26, 0x3fcc422a
	v_fmaak_f32 v27, v39, v27, 0x3fcc422a
	v_fmaak_f32 v30, v40, v30, 0x3fcc422a
	v_fmaak_f32 v31, v41, v31, 0x3fcc422a
	v_fmaak_f32 v34, v16, v34, 0x3fcc422a
	v_fmaak_f32 v35, v17, v35, 0x3fcc422a
	v_mul_f32_e32 v26, v38, v26
	v_mul_f32_e32 v27, v39, v27
	v_mul_f32_e32 v30, v40, v30
	v_mul_f32_e32 v31, v41, v31
	v_mul_f32_e32 v34, v16, v34
	v_mul_f32_e32 v35, v17, v35
	v_mul_f32_e32 v26, 0xbfb8aa3b, v26
	v_mul_f32_e32 v27, 0xbfb8aa3b, v27
	v_mul_f32_e32 v30, 0xbfb8aa3b, v30
	v_mul_f32_e32 v31, 0xbfb8aa3b, v31
	v_mul_f32_e32 v34, 0xbfb8aa3b, v34
	v_mul_f32_e32 v35, 0xbfb8aa3b, v35
	v_exp_f32_e32 v26, v26
	v_exp_f32_e32 v27, v27
	v_exp_f32_e32 v30, v30
	v_exp_f32_e32 v31, v31
	v_exp_f32_e32 v34, v34
	v_exp_f32_e32 v35, v35
	v_add_f32_e32 v24, 1.0, v24
	v_add_f32_e32 v25, 1.0, v25
	v_add_f32_e32 v26, 1.0, v26
	v_add_f32_e32 v27, 1.0, v27
	v_add_f32_e32 v30, 1.0, v30
	v_add_f32_e32 v31, 1.0, v31
	v_add_f32_e32 v34, 1.0, v34
	v_add_f32_e32 v35, 1.0, v35
	v_rcp_f32_e32 v24, v24
	v_rcp_f32_e32 v25, v25
	v_rcp_f32_e32 v26, v26
	v_rcp_f32_e32 v27, v27
	v_rcp_f32_e32 v30, v30
	v_rcp_f32_e32 v31, v31
	v_rcp_f32_e32 v34, v34
	v_rcp_f32_e32 v35, v35
	v_mul_f32_e32 v24, v36, v24
	v_mul_f32_e32 v25, v37, v25
	v_mul_f32_e32 v26, v38, v26
	v_mul_f32_e32 v27, v39, v27
	v_mul_f32_e32 v30, v40, v30
	v_mul_f32_e32 v31, v41, v31
	v_mul_f32_e32 v16, v16, v34
	v_mul_f32_e32 v17, v17, v35
	v_cvt_pk_bf16_f32 v24, v24, v25
	v_cvt_pk_bf16_f32 v25, v26, v27
	v_cvt_pk_bf16_f32 v26, v30, v31
	v_cvt_pk_bf16_f32 v27, v16, v17
	v_mul_f32_e32 v16, v22, v44
	v_mul_f32_e32 v17, v23, v45
	v_mul_f32_e32 v18, v18, v44
	v_mul_f32_e32 v19, v19, v45
	global_store_dwordx4 v[20:21], v[24:27], off
	v_mul_f32_e32 v22, 0x3d922279, v32
	v_mul_f32_e32 v23, 0x3d922279, v33
	v_mul_f32_e32 v24, 0x3d922279, v16
	v_mul_f32_e32 v25, 0x3d922279, v17
	v_mul_f32_e32 v26, 0x3d922279, v28
	v_mul_f32_e32 v27, 0x3d922279, v29
	v_mul_f32_e32 v30, 0x3d922279, v18
	v_mul_f32_e32 v31, 0x3d922279, v19
	v_fmaak_f32 v22, v32, v22, 0x3fcc422a
	v_fmaak_f32 v23, v33, v23, 0x3fcc422a
	v_fmaak_f32 v24, v16, v24, 0x3fcc422a
	v_fmaak_f32 v25, v17, v25, 0x3fcc422a
	v_fmaak_f32 v26, v28, v26, 0x3fcc422a
	v_fmaak_f32 v27, v29, v27, 0x3fcc422a
	v_fmaak_f32 v30, v18, v30, 0x3fcc422a
	v_fmaak_f32 v31, v19, v31, 0x3fcc422a
	v_mul_f32_e32 v22, v32, v22
	v_mul_f32_e32 v23, v33, v23
	v_mul_f32_e32 v24, v16, v24
	v_mul_f32_e32 v25, v17, v25
	v_mul_f32_e32 v26, v28, v26
	v_mul_f32_e32 v27, v29, v27
	v_mul_f32_e32 v30, v18, v30
	v_mul_f32_e32 v31, v19, v31
	v_mul_f32_e32 v22, 0xbfb8aa3b, v22
	v_mul_f32_e32 v23, 0xbfb8aa3b, v23
	v_mul_f32_e32 v24, 0xbfb8aa3b, v24
	v_mul_f32_e32 v25, 0xbfb8aa3b, v25
	v_mul_f32_e32 v26, 0xbfb8aa3b, v26
	v_mul_f32_e32 v27, 0xbfb8aa3b, v27
	v_mul_f32_e32 v30, 0xbfb8aa3b, v30
	v_mul_f32_e32 v31, 0xbfb8aa3b, v31
	v_exp_f32_e32 v22, v22
	v_exp_f32_e32 v23, v23
	v_exp_f32_e32 v24, v24
	v_exp_f32_e32 v25, v25
	v_exp_f32_e32 v26, v26
	v_exp_f32_e32 v27, v27
	v_exp_f32_e32 v30, v30
	v_exp_f32_e32 v31, v31
	v_add_f32_e32 v22, 1.0, v22
	v_add_f32_e32 v23, 1.0, v23
	v_add_f32_e32 v24, 1.0, v24
	v_add_f32_e32 v25, 1.0, v25
	v_add_f32_e32 v26, 1.0, v26
	v_add_f32_e32 v27, 1.0, v27
	v_add_f32_e32 v30, 1.0, v30
	v_add_f32_e32 v31, 1.0, v31
	v_rcp_f32_e32 v22, v22
	v_rcp_f32_e32 v23, v23
	v_rcp_f32_e32 v24, v24
	v_rcp_f32_e32 v25, v25
	v_rcp_f32_e32 v26, v26
	v_rcp_f32_e32 v27, v27
	v_rcp_f32_e32 v30, v30
	v_rcp_f32_e32 v31, v31
	v_mul_f32_e32 v22, v32, v22
	v_mul_f32_e32 v23, v33, v23
	v_mul_f32_e32 v24, v16, v24
	v_mul_f32_e32 v25, v17, v25
	v_mul_f32_e32 v26, v28, v26
	v_mul_f32_e32 v27, v29, v27
	v_mul_f32_e32 v28, v18, v30
	v_mul_f32_e32 v29, v19, v31
	v_cvt_pk_bf16_f32 v16, v22, v23
	v_cvt_pk_bf16_f32 v17, v24, v25
	v_cvt_pk_bf16_f32 v18, v26, v27
	v_cvt_pk_bf16_f32 v19, v28, v29
	global_store_dwordx4 v[20:21], v[16:19], off offset:256
; DI float gelu_tanh(float x) { const float t = x * (1.5957691216f + 0.0713548163f * x * x); return x * __builtin_amdgcn_rcpf(1.f + __builtin_amdgcn_exp2f(-1.4426950409f * t)); }
; #define ROWS8 _Pragma("unroll") for (int ai = 0; ai < 2; ++ai) _Pragma("unroll") for (int m = 0; m < 4; ++m) if (ai == 0 || !hf)
; #define COLS4 _Pragma("unroll") for (int bj = 0; bj < 2; ++bj) _Pragma("unroll") for (int n = 0; n < 2; ++n)
; #define LOAD_ROW_RS(rsv, ssqp, invn) float rsv[2][4]; ROWS8_ALL rsv[ai][m] = (ssqp)[row0 + ai * HALF + m * 16]; ROWS8_ALL rsv[ai][m] = rstd_of(rsv[ai][m], invn)
; #define PK8(v0, v1) ({ const u32x2 h0_ = pk4(v0), h1_ = pk4(v1); (u32x4){h0_.x, h0_.y, h1_.x, h1_.y}; })
;     DI void operator()(const Acc& acc, const Unit& u, int wr, int wc, int fr, int fq) const {
;     ...
;                 LOAD_ROW_RS(rsv, SSQ(0), 1.f / 2048.f);
;                 ROWS8 { const int r = row0 + ai * HALF + m * 16; const float rs = rsv[ai][m];
;                     if (u.pn < 4) { bf16_t* dst = WSB(OFF_U) + (size_t)r * 1024 + colp;
; #pragma unroll
;                         for (int bj = 0; bj < 2; ++bj) { f32x4 v0 = acc[ai][bj][m][0] * rs, v1 = acc[ai][bj][m][1] * rs;
;                             v0[0] = gelu_tanh(v0[0]); v0[1] = gelu_tanh(v0[1]); v0[2] = gelu_tanh(v0[2]); v0[3] = gelu_tanh(v0[3]);
;                             v1[0] = gelu_tanh(v1[0]); v1[1] = gelu_tanh(v1[1]); v1[2] = gelu_tanh(v1[2]); v1[3] = gelu_tanh(v1[3]);
;                             *(u32x4*)(dst + bj * HALF) = PK8(v0, v1); }
;                     } else { float* dst = WSF(OFF_Z) + (size_t)r * 1024 + (colp - 1024);
;                         COLS4 *(f32x4*)(dst + bj * HALF + n * 4) = acc[ai][bj][m][n] * rs;
;                     }
.LBB0_391:
	s_nop 1
	v_fmamk_f32 v16, v168, 0x3a000000, v233
	v_rsq_f32_e32 v28, v16
	v_add_u32_e32 v30, 0xb0, v158
	v_ashrrev_i32_e32 v31, 31, v30
	s_mov_b64 s[46:47], -1
	v_mov_b32_e32 v29, v28
	v_mul_f32_e32 v22, v14, v28
	v_mul_f32_e32 v23, v15, v28
	v_mul_f32_e32 v20, v12, v28
	v_mul_f32_e32 v21, v13, v28
	s_and_b64 vcc, exec, s[4:5]
	v_mul_f32_e32 v24, v8, v28
	v_mul_f32_e32 v25, v9, v29
	v_mul_f32_e32 v16, v4, v28
	v_mul_f32_e32 v17, v5, v29
	v_mul_f32_e32 v12, v0, v28
	v_mul_f32_e32 v13, v1, v29
	s_cbranch_vccnz .LBB0_393
	v_lshlrev_b64 v[0:1], 12, v[30:31]
	v_lshl_add_u64 v[0:1], s[10:11], 0, v[0:1]
	v_lshl_add_u64 v[0:1], v[156:157], 2, v[0:1]
	v_add_co_u32_e32 v0, vcc, 0xefff000, v0
	v_mov_b32_e32 v29, v28
	s_nop 0
	v_addc_co_u32_e32 v1, vcc, 0, v1, vcc
	v_mul_f32_e32 v26, v10, v28
	v_mul_f32_e32 v27, v11, v29
	v_mul_f32_e32 v18, v6, v28
	v_mul_f32_e32 v19, v7, v29
	v_mul_f32_e32 v14, v2, v28
	v_mul_f32_e32 v15, v3, v29
	s_mov_b64 s[46:47], 0
	global_store_dwordx4 v[0:1], v[20:23], off
	global_store_dwordx4 v[0:1], v[24:27], off offset:16
	global_store_dwordx4 v[0:1], v[16:19], off offset:512
	global_store_dwordx4 v[0:1], v[12:15], off offset:528
.LBB0_393:
	s_andn2_b64 vcc, exec, s[46:47]
	s_cbranch_vccnz .LBB0_314
	v_lshlrev_b64 v[0:1], 11, v[30:31]
	v_lshl_add_u64 v[0:1], s[22:23], 0, v[0:1]
	v_lshl_add_u64 v[4:5], v[156:157], 1, v[0:1]
	v_mul_f32_e32 v0, 0x3d922279, v20
	v_fmaak_f32 v0, v20, v0, 0x3fcc422a
	v_mul_f32_e32 v0, v20, v0
	v_mul_f32_e32 v0, 0xbfb8aa3b, v0
	v_exp_f32_e32 v8, v0
	v_mul_f32_e32 v0, 0x3d922279, v21
	v_fmaak_f32 v0, v21, v0, 0x3fcc422a
	v_mul_f32_e32 v0, v21, v0
	v_mov_b32_e32 v29, v28
	v_mul_f32_e32 v0, 0xbfb8aa3b, v0
	v_exp_f32_e32 v9, v0
	v_mul_f32_e32 v0, v10, v28
	v_mul_f32_e32 v1, v11, v29
	v_mul_f32_e32 v10, 0x3d922279, v22
	v_mul_f32_e32 v11, 0x3d922279, v23
	v_mul_f32_e32 v14, 0x3d922279, v24
	v_mul_f32_e32 v15, 0x3d922279, v25
	v_mul_f32_e32 v18, 0x3d922279, v0
	v_mul_f32_e32 v19, 0x3d922279, v1
	v_fmaak_f32 v10, v22, v10, 0x3fcc422a
	v_fmaak_f32 v11, v23, v11, 0x3fcc422a
	v_fmaak_f32 v14, v24, v14, 0x3fcc422a
	v_fmaak_f32 v15, v25, v15, 0x3fcc422a
	v_fmaak_f32 v18, v0, v18, 0x3fcc422a
	v_fmaak_f32 v19, v1, v19, 0x3fcc422a
	v_mul_f32_e32 v10, v22, v10
	v_mul_f32_e32 v11, v23, v11
	v_mul_f32_e32 v14, v24, v14
	v_mul_f32_e32 v15, v25, v15
	v_mul_f32_e32 v18, v0, v18
	v_mul_f32_e32 v19, v1, v19
	v_mul_f32_e32 v10, 0xbfb8aa3b, v10
	v_mul_f32_e32 v11, 0xbfb8aa3b, v11
	v_mul_f32_e32 v14, 0xbfb8aa3b, v14
	v_mul_f32_e32 v15, 0xbfb8aa3b, v15
	v_mul_f32_e32 v18, 0xbfb8aa3b, v18
	v_mul_f32_e32 v19, 0xbfb8aa3b, v19
	v_exp_f32_e32 v10, v10
	v_exp_f32_e32 v11, v11
	v_exp_f32_e32 v14, v14
	v_exp_f32_e32 v15, v15
	v_exp_f32_e32 v18, v18
	v_exp_f32_e32 v19, v19
	v_add_f32_e32 v8, 1.0, v8
	v_add_f32_e32 v9, 1.0, v9
	v_add_f32_e32 v10, 1.0, v10
	v_add_f32_e32 v11, 1.0, v11
	v_add_f32_e32 v14, 1.0, v14
	v_add_f32_e32 v15, 1.0, v15
	v_add_f32_e32 v18, 1.0, v18
	v_add_f32_e32 v19, 1.0, v19
	v_rcp_f32_e32 v8, v8
	v_rcp_f32_e32 v9, v9
	v_rcp_f32_e32 v10, v10
	v_rcp_f32_e32 v11, v11
	v_rcp_f32_e32 v14, v14
	v_rcp_f32_e32 v15, v15
	v_rcp_f32_e32 v18, v18
	v_rcp_f32_e32 v19, v19
	v_mul_f32_e32 v8, v20, v8
	v_mul_f32_e32 v9, v21, v9
	v_mul_f32_e32 v10, v22, v10
	v_mul_f32_e32 v11, v23, v11
	v_mul_f32_e32 v14, v24, v14
	v_mul_f32_e32 v15, v25, v15
	v_mul_f32_e32 v0, v0, v18
	v_mul_f32_e32 v1, v1, v19
	v_cvt_pk_bf16_f32 v8, v8, v9
	v_cvt_pk_bf16_f32 v9, v10, v11
	v_cvt_pk_bf16_f32 v10, v14, v15
	v_cvt_pk_bf16_f32 v11, v0, v1
	v_mul_f32_e32 v0, v6, v28
	v_mul_f32_e32 v1, v7, v29
	v_mul_f32_e32 v2, v2, v28
	v_mul_f32_e32 v3, v3, v29
	global_store_dwordx4 v[4:5], v[8:11], off
	v_mul_f32_e32 v6, 0x3d922279, v16
	v_mul_f32_e32 v7, 0x3d922279, v17
	v_mul_f32_e32 v8, 0x3d922279, v0
	v_mul_f32_e32 v9, 0x3d922279, v1
	v_mul_f32_e32 v10, 0x3d922279, v12
	v_mul_f32_e32 v11, 0x3d922279, v13
	v_mul_f32_e32 v14, 0x3d922279, v2
	v_mul_f32_e32 v15, 0x3d922279, v3
	v_fmaak_f32 v6, v16, v6, 0x3fcc422a
	v_fmaak_f32 v7, v17, v7, 0x3fcc422a
	v_fmaak_f32 v8, v0, v8, 0x3fcc422a
	v_fmaak_f32 v9, v1, v9, 0x3fcc422a
	v_fmaak_f32 v10, v12, v10, 0x3fcc422a
	v_fmaak_f32 v11, v13, v11, 0x3fcc422a
	v_fmaak_f32 v14, v2, v14, 0x3fcc422a
	v_fmaak_f32 v15, v3, v15, 0x3fcc422a
	v_mul_f32_e32 v6, v16, v6
	v_mul_f32_e32 v7, v17, v7
	v_mul_f32_e32 v8, v0, v8
	v_mul_f32_e32 v9, v1, v9
	v_mul_f32_e32 v10, v12, v10
	v_mul_f32_e32 v11, v13, v11
	v_mul_f32_e32 v14, v2, v14
	v_mul_f32_e32 v15, v3, v15
	v_mul_f32_e32 v6, 0xbfb8aa3b, v6
	v_mul_f32_e32 v7, 0xbfb8aa3b, v7
	v_mul_f32_e32 v8, 0xbfb8aa3b, v8
	v_mul_f32_e32 v9, 0xbfb8aa3b, v9
	v_mul_f32_e32 v10, 0xbfb8aa3b, v10
	v_mul_f32_e32 v11, 0xbfb8aa3b, v11
	v_mul_f32_e32 v14, 0xbfb8aa3b, v14
	v_mul_f32_e32 v15, 0xbfb8aa3b, v15
	v_exp_f32_e32 v6, v6
	v_exp_f32_e32 v7, v7
	v_exp_f32_e32 v8, v8
	v_exp_f32_e32 v9, v9
	v_exp_f32_e32 v10, v10
	v_exp_f32_e32 v11, v11
	v_exp_f32_e32 v14, v14
	v_exp_f32_e32 v15, v15
	v_add_f32_e32 v6, 1.0, v6
	v_add_f32_e32 v7, 1.0, v7
	v_add_f32_e32 v8, 1.0, v8
	v_add_f32_e32 v9, 1.0, v9
	v_add_f32_e32 v10, 1.0, v10
	v_add_f32_e32 v11, 1.0, v11
	v_add_f32_e32 v14, 1.0, v14
	v_add_f32_e32 v15, 1.0, v15
	v_rcp_f32_e32 v6, v6
	v_rcp_f32_e32 v7, v7
	v_rcp_f32_e32 v8, v8
	v_rcp_f32_e32 v9, v9
	v_rcp_f32_e32 v10, v10
	v_rcp_f32_e32 v11, v11
	v_rcp_f32_e32 v14, v14
	v_rcp_f32_e32 v15, v15
	v_mul_f32_e32 v6, v16, v6
	v_mul_f32_e32 v7, v17, v7
	v_mul_f32_e32 v8, v0, v8
	v_mul_f32_e32 v9, v1, v9
	v_mul_f32_e32 v10, v12, v10
	v_mul_f32_e32 v11, v13, v11
	v_mul_f32_e32 v12, v2, v14
	v_mul_f32_e32 v13, v3, v15
	v_cvt_pk_bf16_f32 v0, v6, v7
	v_cvt_pk_bf16_f32 v1, v8, v9
	v_cvt_pk_bf16_f32 v2, v10, v11
	v_cvt_pk_bf16_f32 v3, v12, v13
	global_store_dwordx4 v[4:5], v[0:3], off offset:256
	s_branch .LBB0_314

; DI void phase2(CP& p, LAS unsigned char* lds, int wid) {
;     ...
;             const int gt = it * NTHR + tid, c = (gt & 255) * 4, run = gt >> 8, g = c >> 8, win = 2 << g;
;             const int t0 = run * 16, tb = t0 & (SEQ - 1);
;             f32x4 sum = {0.f, 0.f, 0.f, 0.f};
;             for (int j = 1; j < win; ++j) if (tb - j >= 0) sum += *(const f32x4*)(Z + (size_t)(t0 - j) * 1024 + c);
;             for (int i = 0; i < 16; ++i) { const int t = t0 + i, pos = tb + i; const f32x4 zc = *(const f32x4*)(Z + (size_t)t * 1024 + c);
.Lp2_item:
	s_cmpk_gt_i32 s39, 0xff
	s_cbranch_scc1 .Lp2_gmlp
	s_lshr_b32 s2, s33, 2
	s_lshl_b32 s3, s39, 1
	s_add_i32 s2, s2, s3
	s_lshl_b32 s2, s2, 4
	s_and_b32 s3, s2, 0xfff
	s_and_b32 s4, s33, 3
	s_lshl_b32 s5, 2, s4
	s_lshl_b32 s10, s2, 12
	s_add_u32 s10, s24, s10
	s_addc_u32 s11, s25, 0
	s_add_u32 s10, s10, 0x1000
	s_addc_u32 s11, s11, 0
	s_add_i32 s18, s5, -1
	s_lshl_b32 s18, s18, 12
	s_sub_u32 s8, s10, s18
	s_subb_u32 s9, s11, 0
	global_load_dwordx4 v[164:167], v3, s[8:9] offset:-4096
	global_load_dwordx4 v[168:171], v3, s[8:9]
	s_add_u32 s8, s8, 0x2000
	s_addc_u32 s9, s9, 0
	global_load_dwordx4 v[172:175], v3, s[8:9] offset:-4096
	global_load_dwordx4 v[176:179], v3, s[8:9]
	s_add_u32 s8, s8, 0x2000
	s_addc_u32 s9, s9, 0
	global_load_dwordx4 v[180:183], v3, s[8:9] offset:-4096
	global_load_dwordx4 v[184:187], v3, s[8:9]
	s_add_u32 s8, s8, 0x2000
	s_addc_u32 s9, s9, 0
	global_load_dwordx4 v[188:191], v3, s[8:9] offset:-4096
	global_load_dwordx4 v[192:195], v3, s[8:9]
	s_add_u32 s8, s8, 0x2000
	s_addc_u32 s9, s9, 0
	global_load_dwordx4 v[196:199], v3, s[8:9] offset:-4096
	global_load_dwordx4 v[200:203], v3, s[8:9]
	s_add_u32 s8, s8, 0x2000
	s_addc_u32 s9, s9, 0
	global_load_dwordx4 v[204:207], v3, s[8:9] offset:-4096
	global_load_dwordx4 v[208:211], v3, s[8:9]
	s_add_u32 s8, s8, 0x2000
	s_addc_u32 s9, s9, 0
	global_load_dwordx4 v[212:215], v3, s[8:9] offset:-4096
	global_load_dwordx4 v[216:219], v3, s[8:9]
	s_add_u32 s8, s8, 0x2000
	s_addc_u32 s9, s9, 0
	global_load_dwordx4 v[220:223], v3, s[8:9] offset:-4096
	global_load_dwordx4 v[224:227], v3, s[8:9]
	global_load_dwordx4 v[100:103], v3, s[10:11] offset:-4096
	global_load_dwordx4 v[104:107], v3, s[10:11]
	s_add_u32 s10, s10, 0x2000
	s_addc_u32 s11, s11, 0
	global_load_dwordx4 v[108:111], v3, s[10:11] offset:-4096
	global_load_dwordx4 v[112:115], v3, s[10:11]
	s_add_u32 s10, s10, 0x2000
	s_addc_u32 s11, s11, 0
	global_load_dwordx4 v[116:119], v3, s[10:11] offset:-4096
	global_load_dwordx4 v[120:123], v3, s[10:11]
	s_add_u32 s10, s10, 0x2000
	s_addc_u32 s11, s11, 0
	global_load_dwordx4 v[124:127], v3, s[10:11] offset:-4096
	global_load_dwordx4 v[128:131], v3, s[10:11]
	s_add_u32 s10, s10, 0x2000
	s_addc_u32 s11, s11, 0
	global_load_dwordx4 v[132:135], v3, s[10:11] offset:-4096
	global_load_dwordx4 v[136:139], v3, s[10:11]
	s_add_u32 s10, s10, 0x2000
	s_addc_u32 s11, s11, 0
	global_load_dwordx4 v[140:143], v3, s[10:11] offset:-4096
	global_load_dwordx4 v[144:147], v3, s[10:11]
	s_add_u32 s10, s10, 0x2000
	s_addc_u32 s11, s11, 0
	global_load_dwordx4 v[148:151], v3, s[10:11] offset:-4096
	global_load_dwordx4 v[152:155], v3, s[10:11]
	s_add_u32 s10, s10, 0x2000
	s_addc_u32 s11, s11, 0
	global_load_dwordx4 v[156:159], v3, s[10:11] offset:-4096
	global_load_dwordx4 v[160:163], v3, s[10:11]
	s_lshl_b32 s10, s2, 11
	s_add_u32 s10, s26, s10
	s_addc_u32 s11, s27, 0
	s_add_u32 s10, s10, 0x1000
	s_addc_u32 s11, s11, 0
	v_mov_b32_e32 v24, 0
	v_mov_b32_e32 v25, 0
	v_mov_b32_e32 v26, 0
	v_mov_b32_e32 v27, 0
	s_cmp_eq_u32 s3, 0
	s_cbranch_scc1 .Lp2_pool_slow
	s_sub_i32 s18, 0x7e, s4
	s_lshl_b32 s18, s18, 23
	v_mov_b32_e32 v28, s18
	v_mov_b32_e32 v29, s18
	s_waitcnt vmcnt(31)
	v_add_f32_e32 v24, v24, v164
	v_add_f32_e32 v25, v25, v165
	v_add_f32_e32 v26, v26, v166
	v_add_f32_e32 v27, v27, v167
	s_cmp_lt_u32 s5, 4
	s_cbranch_scc1 .Lp2_pf_main
	s_waitcnt vmcnt(29)
	v_add_f32_e32 v24, v24, v168
	v_add_f32_e32 v25, v25, v169
	v_add_f32_e32 v26, v26, v170
	v_add_f32_e32 v27, v27, v171
	v_add_f32_e32 v24, v24, v172
	v_add_f32_e32 v25, v25, v173
	v_add_f32_e32 v26, v26, v174
	v_add_f32_e32 v27, v27, v175
	s_cmp_lt_u32 s5, 8
	s_cbranch_scc1 .Lp2_pf_main
	s_waitcnt vmcnt(25)
	v_add_f32_e32 v24, v24, v176
	v_add_f32_e32 v25, v25, v177
	v_add_f32_e32 v26, v26, v178
	v_add_f32_e32 v27, v27, v179
	v_add_f32_e32 v24, v24, v180
	v_add_f32_e32 v25, v25, v181
	v_add_f32_e32 v26, v26, v182
	v_add_f32_e32 v27, v27, v183
	v_add_f32_e32 v24, v24, v184
	v_add_f32_e32 v25, v25, v185
	v_add_f32_e32 v26, v26, v186
	v_add_f32_e32 v27, v27, v187
	v_add_f32_e32 v24, v24, v188
	v_add_f32_e32 v25, v25, v189
	v_add_f32_e32 v26, v26, v190
	v_add_f32_e32 v27, v27, v191
	s_cmp_lt_u32 s5, 16
	s_cbranch_scc1 .Lp2_pf_main
	s_waitcnt vmcnt(17)
	v_add_f32_e32 v24, v24, v192
	v_add_f32_e32 v25, v25, v193
	v_add_f32_e32 v26, v26, v194
	v_add_f32_e32 v27, v27, v195
	v_add_f32_e32 v24, v24, v196
	v_add_f32_e32 v25, v25, v197
	v_add_f32_e32 v26, v26, v198
	v_add_f32_e32 v27, v27, v199
	v_add_f32_e32 v24, v24, v200
	v_add_f32_e32 v25, v25, v201
	v_add_f32_e32 v26, v26, v202
	v_add_f32_e32 v27, v27, v203
	v_add_f32_e32 v24, v24, v204
	v_add_f32_e32 v25, v25, v205
	v_add_f32_e32 v26, v26, v206
	v_add_f32_e32 v27, v27, v207
	v_add_f32_e32 v24, v24, v208
	v_add_f32_e32 v25, v25, v209
	v_add_f32_e32 v26, v26, v210
	v_add_f32_e32 v27, v27, v211
	v_add_f32_e32 v24, v24, v212
	v_add_f32_e32 v25, v25, v213
	v_add_f32_e32 v26, v26, v214
	v_add_f32_e32 v27, v27, v215
	v_add_f32_e32 v24, v24, v216
	v_add_f32_e32 v25, v25, v217
	v_add_f32_e32 v26, v26, v218
	v_add_f32_e32 v27, v27, v219
	v_add_f32_e32 v24, v24, v220
	v_add_f32_e32 v25, v25, v221
	v_add_f32_e32 v26, v26, v222
	v_add_f32_e32 v27, v27, v223
; DI u32x2 pk4(f32x4 v) { u32x2 r; r.x = pk2(v[0], v[1]); r.y = pk2(v[2], v[3]); return r; }
; DI void phase2(CP& p, LAS unsigned char* lds, int wid) {
;     ...
;             for (int i = 0; i < 16; ++i) { const int t = t0 + i, pos = tb + i; const f32x4 zc = *(const f32x4*)(Z + (size_t)t * 1024 + c);
;                 sum += zc; const float cnt = (float)((pos + 1) < win ? (pos + 1) : win); const f32x4 d = sum / cnt - zc;
;                 *(u32x2*)(DP + (size_t)t * 1024 + c) = pk4(d);
;                 if (pos - win + 1 >= 0) sum -= *(const f32x4*)(Z + (size_t)(t - win + 1) * 1024 + c); }
.Lp2_pf_main:
	s_waitcnt vmcnt(15)
	v_add_f32_e32 v24, v24, v100
	v_add_f32_e32 v25, v25, v101
	v_add_f32_e32 v26, v26, v102
	v_add_f32_e32 v27, v27, v103
	v_mul_f32_e32 v30, v24, v28
	v_mul_f32_e32 v31, v25, v29
	v_mul_f32_e32 v32, v26, v28
	v_mul_f32_e32 v33, v27, v29
	v_sub_f32_e32 v30, v30, v100
	v_sub_f32_e32 v31, v31, v101
	v_sub_f32_e32 v32, v32, v102
	v_sub_f32_e32 v33, v33, v103
	v_cvt_pk_bf16_f32 v34, v30, v31
	v_cvt_pk_bf16_f32 v35, v32, v33
	global_store_dwordx2 v4, v[34:35], s[10:11] offset:-4096
	v_sub_f32_e32 v24, v24, v164
	v_sub_f32_e32 v25, v25, v165
	v_sub_f32_e32 v26, v26, v166
	v_sub_f32_e32 v27, v27, v167
	s_waitcnt vmcnt(15)
	v_add_f32_e32 v24, v24, v104
	v_add_f32_e32 v25, v25, v105
	v_add_f32_e32 v26, v26, v106
	v_add_f32_e32 v27, v27, v107
	v_mul_f32_e32 v30, v24, v28
	v_mul_f32_e32 v31, v25, v29
	v_mul_f32_e32 v32, v26, v28
	v_mul_f32_e32 v33, v27, v29
	v_sub_f32_e32 v30, v30, v104
	v_sub_f32_e32 v31, v31, v105
	v_sub_f32_e32 v32, v32, v106
	v_sub_f32_e32 v33, v33, v107
	v_cvt_pk_bf16_f32 v36, v30, v31
	v_cvt_pk_bf16_f32 v37, v32, v33
	global_store_dwordx2 v4, v[36:37], s[10:11] offset:-2048
	v_sub_f32_e32 v24, v24, v168
	v_sub_f32_e32 v25, v25, v169
	v_sub_f32_e32 v26, v26, v170
	v_sub_f32_e32 v27, v27, v171
	s_waitcnt vmcnt(15)
	v_add_f32_e32 v24, v24, v108
	v_add_f32_e32 v25, v25, v109
	v_add_f32_e32 v26, v26, v110
	v_add_f32_e32 v27, v27, v111
	v_mul_f32_e32 v30, v24, v28
	v_mul_f32_e32 v31, v25, v29
	v_mul_f32_e32 v32, v26, v28
	v_mul_f32_e32 v33, v27, v29
	v_sub_f32_e32 v30, v30, v108
	v_sub_f32_e32 v31, v31, v109
	v_sub_f32_e32 v32, v32, v110
	v_sub_f32_e32 v33, v33, v111
	v_cvt_pk_bf16_f32 v34, v30, v31
	v_cvt_pk_bf16_f32 v35, v32, v33
	global_store_dwordx2 v4, v[34:35], s[10:11]
	v_sub_f32_e32 v24, v24, v172
	v_sub_f32_e32 v25, v25, v173
	v_sub_f32_e32 v26, v26, v174
	v_sub_f32_e32 v27, v27, v175
	s_waitcnt vmcnt(15)
	v_add_f32_e32 v24, v24, v112
	v_add_f32_e32 v25, v25, v113
	v_add_f32_e32 v26, v26, v114
	v_add_f32_e32 v27, v27, v115
	v_mul_f32_e32 v30, v24, v28
	v_mul_f32_e32 v31, v25, v29
	v_mul_f32_e32 v32, v26, v28
	v_mul_f32_e32 v33, v27, v29
	v_sub_f32_e32 v30, v30, v112
	v_sub_f32_e32 v31, v31, v113
	v_sub_f32_e32 v32, v32, v114
	v_sub_f32_e32 v33, v33, v115
	v_cvt_pk_bf16_f32 v36, v30, v31
	v_cvt_pk_bf16_f32 v37, v32, v33
	global_store_dwordx2 v4, v[36:37], s[10:11] offset:2048
	v_sub_f32_e32 v24, v24, v176
	v_sub_f32_e32 v25, v25, v177
	v_sub_f32_e32 v26, v26, v178
	v_sub_f32_e32 v27, v27, v179
	s_waitcnt vmcnt(15)
	v_add_f32_e32 v24, v24, v116
	v_add_f32_e32 v25, v25, v117
	v_add_f32_e32 v26, v26, v118
	v_add_f32_e32 v27, v27, v119
	v_mul_f32_e32 v30, v24, v28
	v_mul_f32_e32 v31, v25, v29
	v_mul_f32_e32 v32, v26, v28
	v_mul_f32_e32 v33, v27, v29
	v_sub_f32_e32 v30, v30, v116
	v_sub_f32_e32 v31, v31, v117
	v_sub_f32_e32 v32, v32, v118
	v_sub_f32_e32 v33, v33, v119
	v_cvt_pk_bf16_f32 v34, v30, v31
	v_cvt_pk_bf16_f32 v35, v32, v33
	s_add_u32 s10, s10, 0x2000
	s_addc_u32 s11, s11, 0
	global_store_dwordx2 v4, v[34:35], s[10:11] offset:-4096
	v_sub_f32_e32 v24, v24, v180
	v_sub_f32_e32 v25, v25, v181
	v_sub_f32_e32 v26, v26, v182
	v_sub_f32_e32 v27, v27, v183
	s_waitcnt vmcnt(15)
	v_add_f32_e32 v24, v24, v120
	v_add_f32_e32 v25, v25, v121
	v_add_f32_e32 v26, v26, v122
	v_add_f32_e32 v27, v27, v123
	v_mul_f32_e32 v30, v24, v28
	v_mul_f32_e32 v31, v25, v29
	v_mul_f32_e32 v32, v26, v28
	v_mul_f32_e32 v33, v27, v29
	v_sub_f32_e32 v30, v30, v120
	v_sub_f32_e32 v31, v31, v121
	v_sub_f32_e32 v32, v32, v122
	v_sub_f32_e32 v33, v33, v123
	v_cvt_pk_bf16_f32 v36, v30, v31
	v_cvt_pk_bf16_f32 v37, v32, v33
	global_store_dwordx2 v4, v[36:37], s[10:11] offset:-2048
	v_sub_f32_e32 v24, v24, v184
	v_sub_f32_e32 v25, v25, v185
	v_sub_f32_e32 v26, v26, v186
	v_sub_f32_e32 v27, v27, v187
	s_waitcnt vmcnt(15)
	v_add_f32_e32 v24, v24, v124
	v_add_f32_e32 v25, v25, v125
	v_add_f32_e32 v26, v26, v126
	v_add_f32_e32 v27, v27, v127
	v_mul_f32_e32 v30, v24, v28
	v_mul_f32_e32 v31, v25, v29
	v_mul_f32_e32 v32, v26, v28
	v_mul_f32_e32 v33, v27, v29
	v_sub_f32_e32 v30, v30, v124
	v_sub_f32_e32 v31, v31, v125
	v_sub_f32_e32 v32, v32, v126
	v_sub_f32_e32 v33, v33, v127
	v_cvt_pk_bf16_f32 v34, v30, v31
	v_cvt_pk_bf16_f32 v35, v32, v33
	global_store_dwordx2 v4, v[34:35], s[10:11]
	v_sub_f32_e32 v24, v24, v188
	v_sub_f32_e32 v25, v25, v189
	v_sub_f32_e32 v26, v26, v190
	v_sub_f32_e32 v27, v27, v191
	s_waitcnt vmcnt(15)
	v_add_f32_e32 v24, v24, v128
	v_add_f32_e32 v25, v25, v129
	v_add_f32_e32 v26, v26, v130
	v_add_f32_e32 v27, v27, v131
	v_mul_f32_e32 v30, v24, v28
	v_mul_f32_e32 v31, v25, v29
	v_mul_f32_e32 v32, v26, v28
	v_mul_f32_e32 v33, v27, v29
	v_sub_f32_e32 v30, v30, v128
	v_sub_f32_e32 v31, v31, v129
	v_sub_f32_e32 v32, v32, v130
	v_sub_f32_e32 v33, v33, v131
	v_cvt_pk_bf16_f32 v36, v30, v31
	v_cvt_pk_bf16_f32 v37, v32, v33
	global_store_dwordx2 v4, v[36:37], s[10:11] offset:2048
	v_sub_f32_e32 v24, v24, v192
	v_sub_f32_e32 v25, v25, v193
	v_sub_f32_e32 v26, v26, v194
	v_sub_f32_e32 v27, v27, v195
	s_waitcnt vmcnt(15)
	v_add_f32_e32 v24, v24, v132
	v_add_f32_e32 v25, v25, v133
	v_add_f32_e32 v26, v26, v134
	v_add_f32_e32 v27, v27, v135
	v_mul_f32_e32 v30, v24, v28
	v_mul_f32_e32 v31, v25, v29
	v_mul_f32_e32 v32, v26, v28
	v_mul_f32_e32 v33, v27, v29
	v_sub_f32_e32 v30, v30, v132
	v_sub_f32_e32 v31, v31, v133
	v_sub_f32_e32 v32, v32, v134
	v_sub_f32_e32 v33, v33, v135
	v_cvt_pk_bf16_f32 v34, v30, v31
	v_cvt_pk_bf16_f32 v35, v32, v33
	s_add_u32 s10, s10, 0x2000
	s_addc_u32 s11, s11, 0
	global_store_dwordx2 v4, v[34:35], s[10:11] offset:-4096
	v_sub_f32_e32 v24, v24, v196
	v_sub_f32_e32 v25, v25, v197
	v_sub_f32_e32 v26, v26, v198
	v_sub_f32_e32 v27, v27, v199
	s_waitcnt vmcnt(15)
; DI u32x2 pk4(f32x4 v) { u32x2 r; r.x = pk2(v[0], v[1]); r.y = pk2(v[2], v[3]); return r; }
; DI void phase2(CP& p, LAS unsigned char* lds, int wid) {
;     ...
;             for (int i = 0; i < 16; ++i) { const int t = t0 + i, pos = tb + i; const f32x4 zc = *(const f32x4*)(Z + (size_t)t * 1024 + c);
;                 sum += zc; const float cnt = (float)((pos + 1) < win ? (pos + 1) : win); const f32x4 d = sum / cnt - zc;
;                 *(u32x2*)(DP + (size_t)t * 1024 + c) = pk4(d);
;                 if (pos - win + 1 >= 0) sum -= *(const f32x4*)(Z + (size_t)(t - win + 1) * 1024 + c); }
	v_add_f32_e32 v24, v24, v136
	v_add_f32_e32 v25, v25, v137
	v_add_f32_e32 v26, v26, v138
	v_add_f32_e32 v27, v27, v139
	v_mul_f32_e32 v30, v24, v28
	v_mul_f32_e32 v31, v25, v29
	v_mul_f32_e32 v32, v26, v28
	v_mul_f32_e32 v33, v27, v29
	v_sub_f32_e32 v30, v30, v136
	v_sub_f32_e32 v31, v31, v137
	v_sub_f32_e32 v32, v32, v138
	v_sub_f32_e32 v33, v33, v139
	v_cvt_pk_bf16_f32 v36, v30, v31
	v_cvt_pk_bf16_f32 v37, v32, v33
	global_store_dwordx2 v4, v[36:37], s[10:11] offset:-2048
	v_sub_f32_e32 v24, v24, v200
	v_sub_f32_e32 v25, v25, v201
	v_sub_f32_e32 v26, v26, v202
	v_sub_f32_e32 v27, v27, v203
	s_waitcnt vmcnt(15)
	v_add_f32_e32 v24, v24, v140
	v_add_f32_e32 v25, v25, v141
	v_add_f32_e32 v26, v26, v142
	v_add_f32_e32 v27, v27, v143
	v_mul_f32_e32 v30, v24, v28
	v_mul_f32_e32 v31, v25, v29
	v_mul_f32_e32 v32, v26, v28
	v_mul_f32_e32 v33, v27, v29
	v_sub_f32_e32 v30, v30, v140
	v_sub_f32_e32 v31, v31, v141
	v_sub_f32_e32 v32, v32, v142
	v_sub_f32_e32 v33, v33, v143
	v_cvt_pk_bf16_f32 v34, v30, v31
	v_cvt_pk_bf16_f32 v35, v32, v33
	global_store_dwordx2 v4, v[34:35], s[10:11]
	v_sub_f32_e32 v24, v24, v204
	v_sub_f32_e32 v25, v25, v205
	v_sub_f32_e32 v26, v26, v206
	v_sub_f32_e32 v27, v27, v207
	s_waitcnt vmcnt(15)
	v_add_f32_e32 v24, v24, v144
	v_add_f32_e32 v25, v25, v145
	v_add_f32_e32 v26, v26, v146
	v_add_f32_e32 v27, v27, v147
	v_mul_f32_e32 v30, v24, v28
	v_mul_f32_e32 v31, v25, v29
	v_mul_f32_e32 v32, v26, v28
	v_mul_f32_e32 v33, v27, v29
	v_sub_f32_e32 v30, v30, v144
	v_sub_f32_e32 v31, v31, v145
	v_sub_f32_e32 v32, v32, v146
	v_sub_f32_e32 v33, v33, v147
	v_cvt_pk_bf16_f32 v36, v30, v31
	v_cvt_pk_bf16_f32 v37, v32, v33
	global_store_dwordx2 v4, v[36:37], s[10:11] offset:2048
	v_sub_f32_e32 v24, v24, v208
	v_sub_f32_e32 v25, v25, v209
	v_sub_f32_e32 v26, v26, v210
	v_sub_f32_e32 v27, v27, v211
	s_waitcnt vmcnt(15)
	v_add_f32_e32 v24, v24, v148
	v_add_f32_e32 v25, v25, v149
	v_add_f32_e32 v26, v26, v150
	v_add_f32_e32 v27, v27, v151
	v_mul_f32_e32 v30, v24, v28
	v_mul_f32_e32 v31, v25, v29
	v_mul_f32_e32 v32, v26, v28
	v_mul_f32_e32 v33, v27, v29
	v_sub_f32_e32 v30, v30, v148
	v_sub_f32_e32 v31, v31, v149
	v_sub_f32_e32 v32, v32, v150
	v_sub_f32_e32 v33, v33, v151
	v_cvt_pk_bf16_f32 v34, v30, v31
	v_cvt_pk_bf16_f32 v35, v32, v33
	s_add_u32 s10, s10, 0x2000
	s_addc_u32 s11, s11, 0
	global_store_dwordx2 v4, v[34:35], s[10:11] offset:-4096
	v_sub_f32_e32 v24, v24, v212
	v_sub_f32_e32 v25, v25, v213
	v_sub_f32_e32 v26, v26, v214
	v_sub_f32_e32 v27, v27, v215
	s_waitcnt vmcnt(15)
	v_add_f32_e32 v24, v24, v152
	v_add_f32_e32 v25, v25, v153
	v_add_f32_e32 v26, v26, v154
	v_add_f32_e32 v27, v27, v155
	v_mul_f32_e32 v30, v24, v28
	v_mul_f32_e32 v31, v25, v29
	v_mul_f32_e32 v32, v26, v28
	v_mul_f32_e32 v33, v27, v29
	v_sub_f32_e32 v30, v30, v152
	v_sub_f32_e32 v31, v31, v153
	v_sub_f32_e32 v32, v32, v154
	v_sub_f32_e32 v33, v33, v155
	v_cvt_pk_bf16_f32 v36, v30, v31
	v_cvt_pk_bf16_f32 v37, v32, v33
	global_store_dwordx2 v4, v[36:37], s[10:11] offset:-2048
	v_sub_f32_e32 v24, v24, v216
	v_sub_f32_e32 v25, v25, v217
	v_sub_f32_e32 v26, v26, v218
	v_sub_f32_e32 v27, v27, v219
	s_waitcnt vmcnt(15)
	v_add_f32_e32 v24, v24, v156
	v_add_f32_e32 v25, v25, v157
	v_add_f32_e32 v26, v26, v158
	v_add_f32_e32 v27, v27, v159
	v_mul_f32_e32 v30, v24, v28
	v_mul_f32_e32 v31, v25, v29
	v_mul_f32_e32 v32, v26, v28
	v_mul_f32_e32 v33, v27, v29
	v_sub_f32_e32 v30, v30, v156
	v_sub_f32_e32 v31, v31, v157
	v_sub_f32_e32 v32, v32, v158
	v_sub_f32_e32 v33, v33, v159
	v_cvt_pk_bf16_f32 v34, v30, v31
	v_cvt_pk_bf16_f32 v35, v32, v33
	global_store_dwordx2 v4, v[34:35], s[10:11]
	v_sub_f32_e32 v24, v24, v220
	v_sub_f32_e32 v25, v25, v221
	v_sub_f32_e32 v26, v26, v222
	v_sub_f32_e32 v27, v27, v223
	s_waitcnt vmcnt(15)
	v_add_f32_e32 v24, v24, v160
	v_add_f32_e32 v25, v25, v161
	v_add_f32_e32 v26, v26, v162
	v_add_f32_e32 v27, v27, v163
	v_mul_f32_e32 v30, v24, v28
	v_mul_f32_e32 v31, v25, v29
	v_mul_f32_e32 v32, v26, v28
	v_mul_f32_e32 v33, v27, v29
	v_sub_f32_e32 v30, v30, v160
	v_sub_f32_e32 v31, v31, v161
	v_sub_f32_e32 v32, v32, v162
	v_sub_f32_e32 v33, v33, v163
	v_cvt_pk_bf16_f32 v36, v30, v31
	v_cvt_pk_bf16_f32 v37, v32, v33
	global_store_dwordx2 v4, v[36:37], s[10:11] offset:2048
	v_sub_f32_e32 v24, v24, v224
	v_sub_f32_e32 v25, v25, v225
	v_sub_f32_e32 v26, v26, v226
	v_sub_f32_e32 v27, v27, v227
	s_branch .Lp2_next
.Lp2_pool_slow:
	s_waitcnt vmcnt(0)
	s_min_u32 s18, s5, 1
	v_cvt_f32_u32_e32 v28, s18
	v_rcp_f32_e32 v29, v28
	v_add_f32_e32 v24, v24, v100
	v_add_f32_e32 v25, v25, v101
	v_add_f32_e32 v26, v26, v102
	v_add_f32_e32 v27, v27, v103
	v_fma_f32 v30, -v28, v29, 1.0
	v_fmac_f32_e32 v29, v30, v29
	v_mul_f32_e32 v30, v24, v29
	v_fma_f32 v31, -v28, v30, v24
	v_fmac_f32_e32 v30, v31, v29
	v_fma_f32 v31, -v28, v30, v24
	v_fmac_f32_e32 v30, v31, v29
	v_sub_f32_e32 v36, v30, v100
	v_mul_f32_e32 v30, v25, v29
	v_fma_f32 v31, -v28, v30, v25
	v_fmac_f32_e32 v30, v31, v29
	v_fma_f32 v31, -v28, v30, v25
	v_fmac_f32_e32 v30, v31, v29
	v_sub_f32_e32 v37, v30, v101
	v_mul_f32_e32 v30, v26, v29
	v_fma_f32 v31, -v28, v30, v26
	v_fmac_f32_e32 v30, v31, v29
	v_fma_f32 v31, -v28, v30, v26
	v_fmac_f32_e32 v30, v31, v29
	v_sub_f32_e32 v38, v30, v102
	v_mul_f32_e32 v30, v27, v29
	v_fma_f32 v31, -v28, v30, v27
	v_fmac_f32_e32 v30, v31, v29
	v_fma_f32 v31, -v28, v30, v27
	v_fmac_f32_e32 v30, v31, v29
	v_sub_f32_e32 v39, v30, v103
	v_cvt_pk_bf16_f32 v34, v36, v37
	v_cvt_pk_bf16_f32 v35, v38, v39
	s_nop 0
	global_store_dwordx2 v4, v[34:35], s[10:11] offset:-4096
	s_cmp_gt_u32 s5, 1
	s_cbranch_scc1 .Lp2_ps_0
	v_sub_f32_e32 v24, v24, v164
	v_sub_f32_e32 v25, v25, v165
	v_sub_f32_e32 v26, v26, v166
	v_sub_f32_e32 v27, v27, v167
; DI u32x2 pk4(f32x4 v) { u32x2 r; r.x = pk2(v[0], v[1]); r.y = pk2(v[2], v[3]); return r; }
; DI void phase2(CP& p, LAS unsigned char* lds, int wid) {
;     ...
;             for (int i = 0; i < 16; ++i) { const int t = t0 + i, pos = tb + i; const f32x4 zc = *(const f32x4*)(Z + (size_t)t * 1024 + c);
;                 sum += zc; const float cnt = (float)((pos + 1) < win ? (pos + 1) : win); const f32x4 d = sum / cnt - zc;
;                 *(u32x2*)(DP + (size_t)t * 1024 + c) = pk4(d);
;                 if (pos - win + 1 >= 0) sum -= *(const f32x4*)(Z + (size_t)(t - win + 1) * 1024 + c); }
.Lp2_ps_0:
	s_min_u32 s18, s5, 2
	v_cvt_f32_u32_e32 v28, s18
	v_rcp_f32_e32 v29, v28
	v_add_f32_e32 v24, v24, v104
	v_add_f32_e32 v25, v25, v105
	v_add_f32_e32 v26, v26, v106
	v_add_f32_e32 v27, v27, v107
	v_fma_f32 v30, -v28, v29, 1.0
	v_fmac_f32_e32 v29, v30, v29
	v_mul_f32_e32 v30, v24, v29
	v_fma_f32 v31, -v28, v30, v24
	v_fmac_f32_e32 v30, v31, v29
	v_fma_f32 v31, -v28, v30, v24
	v_fmac_f32_e32 v30, v31, v29
	v_sub_f32_e32 v36, v30, v104
	v_mul_f32_e32 v30, v25, v29
	v_fma_f32 v31, -v28, v30, v25
	v_fmac_f32_e32 v30, v31, v29
	v_fma_f32 v31, -v28, v30, v25
	v_fmac_f32_e32 v30, v31, v29
	v_sub_f32_e32 v37, v30, v105
	v_mul_f32_e32 v30, v26, v29
	v_fma_f32 v31, -v28, v30, v26
	v_fmac_f32_e32 v30, v31, v29
	v_fma_f32 v31, -v28, v30, v26
	v_fmac_f32_e32 v30, v31, v29
	v_sub_f32_e32 v38, v30, v106
	v_mul_f32_e32 v30, v27, v29
	v_fma_f32 v31, -v28, v30, v27
	v_fmac_f32_e32 v30, v31, v29
	v_fma_f32 v31, -v28, v30, v27
	v_fmac_f32_e32 v30, v31, v29
	v_sub_f32_e32 v39, v30, v107
	v_cvt_pk_bf16_f32 v34, v36, v37
	v_cvt_pk_bf16_f32 v35, v38, v39
	s_nop 0
	global_store_dwordx2 v4, v[34:35], s[10:11] offset:-2048
	s_cmp_gt_u32 s5, 2
	s_cbranch_scc1 .Lp2_ps_1
	v_sub_f32_e32 v24, v24, v168
	v_sub_f32_e32 v25, v25, v169
	v_sub_f32_e32 v26, v26, v170
	v_sub_f32_e32 v27, v27, v171
.Lp2_ps_1:
	s_min_u32 s18, s5, 3
	v_cvt_f32_u32_e32 v28, s18
	v_rcp_f32_e32 v29, v28
	v_add_f32_e32 v24, v24, v108
	v_add_f32_e32 v25, v25, v109
	v_add_f32_e32 v26, v26, v110
	v_add_f32_e32 v27, v27, v111
	v_fma_f32 v30, -v28, v29, 1.0
	v_fmac_f32_e32 v29, v30, v29
	v_mul_f32_e32 v30, v24, v29
	v_fma_f32 v31, -v28, v30, v24
	v_fmac_f32_e32 v30, v31, v29
	v_fma_f32 v31, -v28, v30, v24
	v_fmac_f32_e32 v30, v31, v29
	v_sub_f32_e32 v36, v30, v108
	v_mul_f32_e32 v30, v25, v29
	v_fma_f32 v31, -v28, v30, v25
	v_fmac_f32_e32 v30, v31, v29
	v_fma_f32 v31, -v28, v30, v25
	v_fmac_f32_e32 v30, v31, v29
	v_sub_f32_e32 v37, v30, v109
	v_mul_f32_e32 v30, v26, v29
	v_fma_f32 v31, -v28, v30, v26
	v_fmac_f32_e32 v30, v31, v29
	v_fma_f32 v31, -v28, v30, v26
	v_fmac_f32_e32 v30, v31, v29
	v_sub_f32_e32 v38, v30, v110
	v_mul_f32_e32 v30, v27, v29
	v_fma_f32 v31, -v28, v30, v27
	v_fmac_f32_e32 v30, v31, v29
	v_fma_f32 v31, -v28, v30, v27
	v_fmac_f32_e32 v30, v31, v29
	v_sub_f32_e32 v39, v30, v111
	v_cvt_pk_bf16_f32 v34, v36, v37
	v_cvt_pk_bf16_f32 v35, v38, v39
	s_nop 0
	global_store_dwordx2 v4, v[34:35], s[10:11]
	s_cmp_gt_u32 s5, 3
	s_cbranch_scc1 .Lp2_ps_2
	v_sub_f32_e32 v24, v24, v172
	v_sub_f32_e32 v25, v25, v173
	v_sub_f32_e32 v26, v26, v174
	v_sub_f32_e32 v27, v27, v175
.Lp2_ps_2:
	s_min_u32 s18, s5, 4
	v_cvt_f32_u32_e32 v28, s18
	v_rcp_f32_e32 v29, v28
	v_add_f32_e32 v24, v24, v112
	v_add_f32_e32 v25, v25, v113
	v_add_f32_e32 v26, v26, v114
	v_add_f32_e32 v27, v27, v115
	v_fma_f32 v30, -v28, v29, 1.0
	v_fmac_f32_e32 v29, v30, v29
	v_mul_f32_e32 v30, v24, v29
	v_fma_f32 v31, -v28, v30, v24
	v_fmac_f32_e32 v30, v31, v29
	v_fma_f32 v31, -v28, v30, v24
	v_fmac_f32_e32 v30, v31, v29
	v_sub_f32_e32 v36, v30, v112
	v_mul_f32_e32 v30, v25, v29
	v_fma_f32 v31, -v28, v30, v25
	v_fmac_f32_e32 v30, v31, v29
	v_fma_f32 v31, -v28, v30, v25
	v_fmac_f32_e32 v30, v31, v29
	v_sub_f32_e32 v37, v30, v113
	v_mul_f32_e32 v30, v26, v29
	v_fma_f32 v31, -v28, v30, v26
	v_fmac_f32_e32 v30, v31, v29
	v_fma_f32 v31, -v28, v30, v26
	v_fmac_f32_e32 v30, v31, v29
	v_sub_f32_e32 v38, v30, v114
	v_mul_f32_e32 v30, v27, v29
	v_fma_f32 v31, -v28, v30, v27
	v_fmac_f32_e32 v30, v31, v29
	v_fma_f32 v31, -v28, v30, v27
	v_fmac_f32_e32 v30, v31, v29
	v_sub_f32_e32 v39, v30, v115
	v_cvt_pk_bf16_f32 v34, v36, v37
	v_cvt_pk_bf16_f32 v35, v38, v39
	s_nop 0
	global_store_dwordx2 v4, v[34:35], s[10:11] offset:2048
	s_cmp_gt_u32 s5, 4
	s_cbranch_scc1 .Lp2_ps_3
	v_sub_f32_e32 v24, v24, v176
	v_sub_f32_e32 v25, v25, v177
	v_sub_f32_e32 v26, v26, v178
	v_sub_f32_e32 v27, v27, v179
.Lp2_ps_3:
	s_min_u32 s18, s5, 5
	v_cvt_f32_u32_e32 v28, s18
	v_rcp_f32_e32 v29, v28
	v_add_f32_e32 v24, v24, v116
	v_add_f32_e32 v25, v25, v117
	v_add_f32_e32 v26, v26, v118
	v_add_f32_e32 v27, v27, v119
	v_fma_f32 v30, -v28, v29, 1.0
	v_fmac_f32_e32 v29, v30, v29
	v_mul_f32_e32 v30, v24, v29
	v_fma_f32 v31, -v28, v30, v24
	v_fmac_f32_e32 v30, v31, v29
	v_fma_f32 v31, -v28, v30, v24
	v_fmac_f32_e32 v30, v31, v29
	v_sub_f32_e32 v36, v30, v116
	v_mul_f32_e32 v30, v25, v29
	v_fma_f32 v31, -v28, v30, v25
	v_fmac_f32_e32 v30, v31, v29
	v_fma_f32 v31, -v28, v30, v25
	v_fmac_f32_e32 v30, v31, v29
	v_sub_f32_e32 v37, v30, v117
	v_mul_f32_e32 v30, v26, v29
	v_fma_f32 v31, -v28, v30, v26
	v_fmac_f32_e32 v30, v31, v29
	v_fma_f32 v31, -v28, v30, v26
	v_fmac_f32_e32 v30, v31, v29
	v_sub_f32_e32 v38, v30, v118
	v_mul_f32_e32 v30, v27, v29
	v_fma_f32 v31, -v28, v30, v27
	v_fmac_f32_e32 v30, v31, v29
	v_fma_f32 v31, -v28, v30, v27
	v_fmac_f32_e32 v30, v31, v29
	v_sub_f32_e32 v39, v30, v119
	v_cvt_pk_bf16_f32 v34, v36, v37
	v_cvt_pk_bf16_f32 v35, v38, v39
	s_add_u32 s10, s10, 0x2000
	s_addc_u32 s11, s11, 0
	s_nop 0
	global_store_dwordx2 v4, v[34:35], s[10:11] offset:-4096
	s_cmp_gt_u32 s5, 5
	s_cbranch_scc1 .Lp2_ps_4
	v_sub_f32_e32 v24, v24, v180
	v_sub_f32_e32 v25, v25, v181
	v_sub_f32_e32 v26, v26, v182
	v_sub_f32_e32 v27, v27, v183
; DI u32x2 pk4(f32x4 v) { u32x2 r; r.x = pk2(v[0], v[1]); r.y = pk2(v[2], v[3]); return r; }
; DI void phase2(CP& p, LAS unsigned char* lds, int wid) {
;     ...
;             for (int i = 0; i < 16; ++i) { const int t = t0 + i, pos = tb + i; const f32x4 zc = *(const f32x4*)(Z + (size_t)t * 1024 + c);
;                 sum += zc; const float cnt = (float)((pos + 1) < win ? (pos + 1) : win); const f32x4 d = sum / cnt - zc;
;                 *(u32x2*)(DP + (size_t)t * 1024 + c) = pk4(d);
;                 if (pos - win + 1 >= 0) sum -= *(const f32x4*)(Z + (size_t)(t - win + 1) * 1024 + c); }
.Lp2_ps_4:
	s_min_u32 s18, s5, 6
	v_cvt_f32_u32_e32 v28, s18
	v_rcp_f32_e32 v29, v28
	v_add_f32_e32 v24, v24, v120
	v_add_f32_e32 v25, v25, v121
	v_add_f32_e32 v26, v26, v122
	v_add_f32_e32 v27, v27, v123
	v_fma_f32 v30, -v28, v29, 1.0
	v_fmac_f32_e32 v29, v30, v29
	v_mul_f32_e32 v30, v24, v29
	v_fma_f32 v31, -v28, v30, v24
	v_fmac_f32_e32 v30, v31, v29
	v_fma_f32 v31, -v28, v30, v24
	v_fmac_f32_e32 v30, v31, v29
	v_sub_f32_e32 v36, v30, v120
	v_mul_f32_e32 v30, v25, v29
	v_fma_f32 v31, -v28, v30, v25
	v_fmac_f32_e32 v30, v31, v29
	v_fma_f32 v31, -v28, v30, v25
	v_fmac_f32_e32 v30, v31, v29
	v_sub_f32_e32 v37, v30, v121
	v_mul_f32_e32 v30, v26, v29
	v_fma_f32 v31, -v28, v30, v26
	v_fmac_f32_e32 v30, v31, v29
	v_fma_f32 v31, -v28, v30, v26
	v_fmac_f32_e32 v30, v31, v29
	v_sub_f32_e32 v38, v30, v122
	v_mul_f32_e32 v30, v27, v29
	v_fma_f32 v31, -v28, v30, v27
	v_fmac_f32_e32 v30, v31, v29
	v_fma_f32 v31, -v28, v30, v27
	v_fmac_f32_e32 v30, v31, v29
	v_sub_f32_e32 v39, v30, v123
	v_cvt_pk_bf16_f32 v34, v36, v37
	v_cvt_pk_bf16_f32 v35, v38, v39
	s_nop 0
	global_store_dwordx2 v4, v[34:35], s[10:11] offset:-2048
	s_cmp_gt_u32 s5, 6
	s_cbranch_scc1 .Lp2_ps_5
	v_sub_f32_e32 v24, v24, v184
	v_sub_f32_e32 v25, v25, v185
	v_sub_f32_e32 v26, v26, v186
	v_sub_f32_e32 v27, v27, v187
.Lp2_ps_5:
	s_min_u32 s18, s5, 7
	v_cvt_f32_u32_e32 v28, s18
	v_rcp_f32_e32 v29, v28
	v_add_f32_e32 v24, v24, v124
	v_add_f32_e32 v25, v25, v125
	v_add_f32_e32 v26, v26, v126
	v_add_f32_e32 v27, v27, v127
	v_fma_f32 v30, -v28, v29, 1.0
	v_fmac_f32_e32 v29, v30, v29
	v_mul_f32_e32 v30, v24, v29
	v_fma_f32 v31, -v28, v30, v24
	v_fmac_f32_e32 v30, v31, v29
	v_fma_f32 v31, -v28, v30, v24
	v_fmac_f32_e32 v30, v31, v29
	v_sub_f32_e32 v36, v30, v124
	v_mul_f32_e32 v30, v25, v29
	v_fma_f32 v31, -v28, v30, v25
	v_fmac_f32_e32 v30, v31, v29
	v_fma_f32 v31, -v28, v30, v25
	v_fmac_f32_e32 v30, v31, v29
	v_sub_f32_e32 v37, v30, v125
	v_mul_f32_e32 v30, v26, v29
	v_fma_f32 v31, -v28, v30, v26
	v_fmac_f32_e32 v30, v31, v29
	v_fma_f32 v31, -v28, v30, v26
	v_fmac_f32_e32 v30, v31, v29
	v_sub_f32_e32 v38, v30, v126
	v_mul_f32_e32 v30, v27, v29
	v_fma_f32 v31, -v28, v30, v27
	v_fmac_f32_e32 v30, v31, v29
	v_fma_f32 v31, -v28, v30, v27
	v_fmac_f32_e32 v30, v31, v29
	v_sub_f32_e32 v39, v30, v127
	v_cvt_pk_bf16_f32 v34, v36, v37
	v_cvt_pk_bf16_f32 v35, v38, v39
	s_nop 0
	global_store_dwordx2 v4, v[34:35], s[10:11]
	s_cmp_gt_u32 s5, 7
	s_cbranch_scc1 .Lp2_ps_6
	v_sub_f32_e32 v24, v24, v188
	v_sub_f32_e32 v25, v25, v189
	v_sub_f32_e32 v26, v26, v190
	v_sub_f32_e32 v27, v27, v191
.Lp2_ps_6:
	s_min_u32 s18, s5, 8
	v_cvt_f32_u32_e32 v28, s18
	v_rcp_f32_e32 v29, v28
	v_add_f32_e32 v24, v24, v128
	v_add_f32_e32 v25, v25, v129
	v_add_f32_e32 v26, v26, v130
	v_add_f32_e32 v27, v27, v131
	v_fma_f32 v30, -v28, v29, 1.0
	v_fmac_f32_e32 v29, v30, v29
	v_mul_f32_e32 v30, v24, v29
	v_fma_f32 v31, -v28, v30, v24
	v_fmac_f32_e32 v30, v31, v29
	v_fma_f32 v31, -v28, v30, v24
	v_fmac_f32_e32 v30, v31, v29
	v_sub_f32_e32 v36, v30, v128
	v_mul_f32_e32 v30, v25, v29
	v_fma_f32 v31, -v28, v30, v25
	v_fmac_f32_e32 v30, v31, v29
	v_fma_f32 v31, -v28, v30, v25
	v_fmac_f32_e32 v30, v31, v29
	v_sub_f32_e32 v37, v30, v129
	v_mul_f32_e32 v30, v26, v29
	v_fma_f32 v31, -v28, v30, v26
	v_fmac_f32_e32 v30, v31, v29
	v_fma_f32 v31, -v28, v30, v26
	v_fmac_f32_e32 v30, v31, v29
	v_sub_f32_e32 v38, v30, v130
	v_mul_f32_e32 v30, v27, v29
	v_fma_f32 v31, -v28, v30, v27
	v_fmac_f32_e32 v30, v31, v29
	v_fma_f32 v31, -v28, v30, v27
	v_fmac_f32_e32 v30, v31, v29
	v_sub_f32_e32 v39, v30, v131
	v_cvt_pk_bf16_f32 v34, v36, v37
	v_cvt_pk_bf16_f32 v35, v38, v39
	s_nop 0
	global_store_dwordx2 v4, v[34:35], s[10:11] offset:2048
	s_cmp_gt_u32 s5, 8
	s_cbranch_scc1 .Lp2_ps_7
	v_sub_f32_e32 v24, v24, v192
	v_sub_f32_e32 v25, v25, v193
	v_sub_f32_e32 v26, v26, v194
	v_sub_f32_e32 v27, v27, v195
.Lp2_ps_7:
	s_min_u32 s18, s5, 9
	v_cvt_f32_u32_e32 v28, s18
	v_rcp_f32_e32 v29, v28
	v_add_f32_e32 v24, v24, v132
	v_add_f32_e32 v25, v25, v133
	v_add_f32_e32 v26, v26, v134
	v_add_f32_e32 v27, v27, v135
	v_fma_f32 v30, -v28, v29, 1.0
	v_fmac_f32_e32 v29, v30, v29
	v_mul_f32_e32 v30, v24, v29
	v_fma_f32 v31, -v28, v30, v24
	v_fmac_f32_e32 v30, v31, v29
	v_fma_f32 v31, -v28, v30, v24
	v_fmac_f32_e32 v30, v31, v29
	v_sub_f32_e32 v36, v30, v132
	v_mul_f32_e32 v30, v25, v29
	v_fma_f32 v31, -v28, v30, v25
	v_fmac_f32_e32 v30, v31, v29
	v_fma_f32 v31, -v28, v30, v25
	v_fmac_f32_e32 v30, v31, v29
	v_sub_f32_e32 v37, v30, v133
	v_mul_f32_e32 v30, v26, v29
	v_fma_f32 v31, -v28, v30, v26
	v_fmac_f32_e32 v30, v31, v29
	v_fma_f32 v31, -v28, v30, v26
	v_fmac_f32_e32 v30, v31, v29
	v_sub_f32_e32 v38, v30, v134
	v_mul_f32_e32 v30, v27, v29
	v_fma_f32 v31, -v28, v30, v27
	v_fmac_f32_e32 v30, v31, v29
	v_fma_f32 v31, -v28, v30, v27
	v_fmac_f32_e32 v30, v31, v29
	v_sub_f32_e32 v39, v30, v135
	v_cvt_pk_bf16_f32 v34, v36, v37
	v_cvt_pk_bf16_f32 v35, v38, v39
	s_add_u32 s10, s10, 0x2000
	s_addc_u32 s11, s11, 0
	s_nop 0
	global_store_dwordx2 v4, v[34:35], s[10:11] offset:-4096
	s_cmp_gt_u32 s5, 9
	s_cbranch_scc1 .Lp2_ps_8
	v_sub_f32_e32 v24, v24, v196
	v_sub_f32_e32 v25, v25, v197
	v_sub_f32_e32 v26, v26, v198
	v_sub_f32_e32 v27, v27, v199
; DI u32x2 pk4(f32x4 v) { u32x2 r; r.x = pk2(v[0], v[1]); r.y = pk2(v[2], v[3]); return r; }
; DI void phase2(CP& p, LAS unsigned char* lds, int wid) {
;     ...
;             for (int i = 0; i < 16; ++i) { const int t = t0 + i, pos = tb + i; const f32x4 zc = *(const f32x4*)(Z + (size_t)t * 1024 + c);
;                 sum += zc; const float cnt = (float)((pos + 1) < win ? (pos + 1) : win); const f32x4 d = sum / cnt - zc;
;                 *(u32x2*)(DP + (size_t)t * 1024 + c) = pk4(d);
;                 if (pos - win + 1 >= 0) sum -= *(const f32x4*)(Z + (size_t)(t - win + 1) * 1024 + c); }
.Lp2_ps_8:
	s_min_u32 s18, s5, 10
	v_cvt_f32_u32_e32 v28, s18
	v_rcp_f32_e32 v29, v28
	v_add_f32_e32 v24, v24, v136
	v_add_f32_e32 v25, v25, v137
	v_add_f32_e32 v26, v26, v138
	v_add_f32_e32 v27, v27, v139
	v_fma_f32 v30, -v28, v29, 1.0
	v_fmac_f32_e32 v29, v30, v29
	v_mul_f32_e32 v30, v24, v29
	v_fma_f32 v31, -v28, v30, v24
	v_fmac_f32_e32 v30, v31, v29
	v_fma_f32 v31, -v28, v30, v24
	v_fmac_f32_e32 v30, v31, v29
	v_sub_f32_e32 v36, v30, v136
	v_mul_f32_e32 v30, v25, v29
	v_fma_f32 v31, -v28, v30, v25
	v_fmac_f32_e32 v30, v31, v29
	v_fma_f32 v31, -v28, v30, v25
	v_fmac_f32_e32 v30, v31, v29
	v_sub_f32_e32 v37, v30, v137
	v_mul_f32_e32 v30, v26, v29
	v_fma_f32 v31, -v28, v30, v26
	v_fmac_f32_e32 v30, v31, v29
	v_fma_f32 v31, -v28, v30, v26
	v_fmac_f32_e32 v30, v31, v29
	v_sub_f32_e32 v38, v30, v138
	v_mul_f32_e32 v30, v27, v29
	v_fma_f32 v31, -v28, v30, v27
	v_fmac_f32_e32 v30, v31, v29
	v_fma_f32 v31, -v28, v30, v27
	v_fmac_f32_e32 v30, v31, v29
	v_sub_f32_e32 v39, v30, v139
	v_cvt_pk_bf16_f32 v34, v36, v37
	v_cvt_pk_bf16_f32 v35, v38, v39
	s_nop 0
	global_store_dwordx2 v4, v[34:35], s[10:11] offset:-2048
	s_cmp_gt_u32 s5, 10
	s_cbranch_scc1 .Lp2_ps_9
	v_sub_f32_e32 v24, v24, v200
	v_sub_f32_e32 v25, v25, v201
	v_sub_f32_e32 v26, v26, v202
	v_sub_f32_e32 v27, v27, v203
.Lp2_ps_9:
	s_min_u32 s18, s5, 11
	v_cvt_f32_u32_e32 v28, s18
	v_rcp_f32_e32 v29, v28
	v_add_f32_e32 v24, v24, v140
	v_add_f32_e32 v25, v25, v141
	v_add_f32_e32 v26, v26, v142
	v_add_f32_e32 v27, v27, v143
	v_fma_f32 v30, -v28, v29, 1.0
	v_fmac_f32_e32 v29, v30, v29
	v_mul_f32_e32 v30, v24, v29
	v_fma_f32 v31, -v28, v30, v24
	v_fmac_f32_e32 v30, v31, v29
	v_fma_f32 v31, -v28, v30, v24
	v_fmac_f32_e32 v30, v31, v29
	v_sub_f32_e32 v36, v30, v140
	v_mul_f32_e32 v30, v25, v29
	v_fma_f32 v31, -v28, v30, v25
	v_fmac_f32_e32 v30, v31, v29
	v_fma_f32 v31, -v28, v30, v25
	v_fmac_f32_e32 v30, v31, v29
	v_sub_f32_e32 v37, v30, v141
	v_mul_f32_e32 v30, v26, v29
	v_fma_f32 v31, -v28, v30, v26
	v_fmac_f32_e32 v30, v31, v29
	v_fma_f32 v31, -v28, v30, v26
	v_fmac_f32_e32 v30, v31, v29
	v_sub_f32_e32 v38, v30, v142
	v_mul_f32_e32 v30, v27, v29
	v_fma_f32 v31, -v28, v30, v27
	v_fmac_f32_e32 v30, v31, v29
	v_fma_f32 v31, -v28, v30, v27
	v_fmac_f32_e32 v30, v31, v29
	v_sub_f32_e32 v39, v30, v143
	v_cvt_pk_bf16_f32 v34, v36, v37
	v_cvt_pk_bf16_f32 v35, v38, v39
	s_nop 0
	global_store_dwordx2 v4, v[34:35], s[10:11]
	s_cmp_gt_u32 s5, 11
	s_cbranch_scc1 .Lp2_ps_10
	v_sub_f32_e32 v24, v24, v204
	v_sub_f32_e32 v25, v25, v205
	v_sub_f32_e32 v26, v26, v206
	v_sub_f32_e32 v27, v27, v207
.Lp2_ps_10:
	s_min_u32 s18, s5, 12
	v_cvt_f32_u32_e32 v28, s18
	v_rcp_f32_e32 v29, v28
	v_add_f32_e32 v24, v24, v144
	v_add_f32_e32 v25, v25, v145
	v_add_f32_e32 v26, v26, v146
	v_add_f32_e32 v27, v27, v147
	v_fma_f32 v30, -v28, v29, 1.0
	v_fmac_f32_e32 v29, v30, v29
	v_mul_f32_e32 v30, v24, v29
	v_fma_f32 v31, -v28, v30, v24
	v_fmac_f32_e32 v30, v31, v29
	v_fma_f32 v31, -v28, v30, v24
	v_fmac_f32_e32 v30, v31, v29
	v_sub_f32_e32 v36, v30, v144
	v_mul_f32_e32 v30, v25, v29
	v_fma_f32 v31, -v28, v30, v25
	v_fmac_f32_e32 v30, v31, v29
	v_fma_f32 v31, -v28, v30, v25
	v_fmac_f32_e32 v30, v31, v29
	v_sub_f32_e32 v37, v30, v145
	v_mul_f32_e32 v30, v26, v29
	v_fma_f32 v31, -v28, v30, v26
	v_fmac_f32_e32 v30, v31, v29
	v_fma_f32 v31, -v28, v30, v26
	v_fmac_f32_e32 v30, v31, v29
	v_sub_f32_e32 v38, v30, v146
	v_mul_f32_e32 v30, v27, v29
	v_fma_f32 v31, -v28, v30, v27
	v_fmac_f32_e32 v30, v31, v29
	v_fma_f32 v31, -v28, v30, v27
	v_fmac_f32_e32 v30, v31, v29
	v_sub_f32_e32 v39, v30, v147
	v_cvt_pk_bf16_f32 v34, v36, v37
	v_cvt_pk_bf16_f32 v35, v38, v39
	s_nop 0
	global_store_dwordx2 v4, v[34:35], s[10:11] offset:2048
	s_cmp_gt_u32 s5, 12
	s_cbranch_scc1 .Lp2_ps_11
	v_sub_f32_e32 v24, v24, v208
	v_sub_f32_e32 v25, v25, v209
	v_sub_f32_e32 v26, v26, v210
	v_sub_f32_e32 v27, v27, v211
.Lp2_ps_11:
	s_min_u32 s18, s5, 13
	v_cvt_f32_u32_e32 v28, s18
	v_rcp_f32_e32 v29, v28
	v_add_f32_e32 v24, v24, v148
	v_add_f32_e32 v25, v25, v149
	v_add_f32_e32 v26, v26, v150
	v_add_f32_e32 v27, v27, v151
	v_fma_f32 v30, -v28, v29, 1.0
	v_fmac_f32_e32 v29, v30, v29
	v_mul_f32_e32 v30, v24, v29
	v_fma_f32 v31, -v28, v30, v24
	v_fmac_f32_e32 v30, v31, v29
	v_fma_f32 v31, -v28, v30, v24
	v_fmac_f32_e32 v30, v31, v29
	v_sub_f32_e32 v36, v30, v148
	v_mul_f32_e32 v30, v25, v29
	v_fma_f32 v31, -v28, v30, v25
	v_fmac_f32_e32 v30, v31, v29
	v_fma_f32 v31, -v28, v30, v25
	v_fmac_f32_e32 v30, v31, v29
	v_sub_f32_e32 v37, v30, v149
	v_mul_f32_e32 v30, v26, v29
	v_fma_f32 v31, -v28, v30, v26
	v_fmac_f32_e32 v30, v31, v29
	v_fma_f32 v31, -v28, v30, v26
	v_fmac_f32_e32 v30, v31, v29
	v_sub_f32_e32 v38, v30, v150
	v_mul_f32_e32 v30, v27, v29
	v_fma_f32 v31, -v28, v30, v27
	v_fmac_f32_e32 v30, v31, v29
	v_fma_f32 v31, -v28, v30, v27
	v_fmac_f32_e32 v30, v31, v29
	v_sub_f32_e32 v39, v30, v151
	v_cvt_pk_bf16_f32 v34, v36, v37
	v_cvt_pk_bf16_f32 v35, v38, v39
	s_add_u32 s10, s10, 0x2000
	s_addc_u32 s11, s11, 0
	s_nop 0
	global_store_dwordx2 v4, v[34:35], s[10:11] offset:-4096
	s_cmp_gt_u32 s5, 13
	s_cbranch_scc1 .Lp2_ps_12
	v_sub_f32_e32 v24, v24, v212
	v_sub_f32_e32 v25, v25, v213
	v_sub_f32_e32 v26, v26, v214
	v_sub_f32_e32 v27, v27, v215
; DI u32x2 pk4(f32x4 v) { u32x2 r; r.x = pk2(v[0], v[1]); r.y = pk2(v[2], v[3]); return r; }
; DI void phase2(CP& p, LAS unsigned char* lds, int wid) {
;     ...
;             for (int i = 0; i < 16; ++i) { const int t = t0 + i, pos = tb + i; const f32x4 zc = *(const f32x4*)(Z + (size_t)t * 1024 + c);
;                 sum += zc; const float cnt = (float)((pos + 1) < win ? (pos + 1) : win); const f32x4 d = sum / cnt - zc;
;                 *(u32x2*)(DP + (size_t)t * 1024 + c) = pk4(d);
;                 if (pos - win + 1 >= 0) sum -= *(const f32x4*)(Z + (size_t)(t - win + 1) * 1024 + c); }
.Lp2_ps_12:
	s_min_u32 s18, s5, 14
	v_cvt_f32_u32_e32 v28, s18
	v_rcp_f32_e32 v29, v28
	v_add_f32_e32 v24, v24, v152
	v_add_f32_e32 v25, v25, v153
	v_add_f32_e32 v26, v26, v154
	v_add_f32_e32 v27, v27, v155
	v_fma_f32 v30, -v28, v29, 1.0
	v_fmac_f32_e32 v29, v30, v29
	v_mul_f32_e32 v30, v24, v29
	v_fma_f32 v31, -v28, v30, v24
	v_fmac_f32_e32 v30, v31, v29
	v_fma_f32 v31, -v28, v30, v24
	v_fmac_f32_e32 v30, v31, v29
	v_sub_f32_e32 v36, v30, v152
	v_mul_f32_e32 v30, v25, v29
	v_fma_f32 v31, -v28, v30, v25
	v_fmac_f32_e32 v30, v31, v29
	v_fma_f32 v31, -v28, v30, v25
	v_fmac_f32_e32 v30, v31, v29
	v_sub_f32_e32 v37, v30, v153
	v_mul_f32_e32 v30, v26, v29
	v_fma_f32 v31, -v28, v30, v26
	v_fmac_f32_e32 v30, v31, v29
	v_fma_f32 v31, -v28, v30, v26
	v_fmac_f32_e32 v30, v31, v29
	v_sub_f32_e32 v38, v30, v154
	v_mul_f32_e32 v30, v27, v29
	v_fma_f32 v31, -v28, v30, v27
	v_fmac_f32_e32 v30, v31, v29
	v_fma_f32 v31, -v28, v30, v27
	v_fmac_f32_e32 v30, v31, v29
	v_sub_f32_e32 v39, v30, v155
	v_cvt_pk_bf16_f32 v34, v36, v37
	v_cvt_pk_bf16_f32 v35, v38, v39
	s_nop 0
	global_store_dwordx2 v4, v[34:35], s[10:11] offset:-2048
	s_cmp_gt_u32 s5, 14
	s_cbranch_scc1 .Lp2_ps_13
	v_sub_f32_e32 v24, v24, v216
	v_sub_f32_e32 v25, v25, v217
	v_sub_f32_e32 v26, v26, v218
	v_sub_f32_e32 v27, v27, v219
.Lp2_ps_13:
	s_min_u32 s18, s5, 15
	v_cvt_f32_u32_e32 v28, s18
	v_rcp_f32_e32 v29, v28
	v_add_f32_e32 v24, v24, v156
	v_add_f32_e32 v25, v25, v157
	v_add_f32_e32 v26, v26, v158
	v_add_f32_e32 v27, v27, v159
	v_fma_f32 v30, -v28, v29, 1.0
	v_fmac_f32_e32 v29, v30, v29
	v_mul_f32_e32 v30, v24, v29
	v_fma_f32 v31, -v28, v30, v24
	v_fmac_f32_e32 v30, v31, v29
	v_fma_f32 v31, -v28, v30, v24
	v_fmac_f32_e32 v30, v31, v29
	v_sub_f32_e32 v36, v30, v156
	v_mul_f32_e32 v30, v25, v29
	v_fma_f32 v31, -v28, v30, v25
	v_fmac_f32_e32 v30, v31, v29
	v_fma_f32 v31, -v28, v30, v25
	v_fmac_f32_e32 v30, v31, v29
	v_sub_f32_e32 v37, v30, v157
	v_mul_f32_e32 v30, v26, v29
	v_fma_f32 v31, -v28, v30, v26
	v_fmac_f32_e32 v30, v31, v29
	v_fma_f32 v31, -v28, v30, v26
	v_fmac_f32_e32 v30, v31, v29
	v_sub_f32_e32 v38, v30, v158
	v_mul_f32_e32 v30, v27, v29
	v_fma_f32 v31, -v28, v30, v27
	v_fmac_f32_e32 v30, v31, v29
	v_fma_f32 v31, -v28, v30, v27
	v_fmac_f32_e32 v30, v31, v29
	v_sub_f32_e32 v39, v30, v159
	v_cvt_pk_bf16_f32 v34, v36, v37
	v_cvt_pk_bf16_f32 v35, v38, v39
	s_nop 0
	global_store_dwordx2 v4, v[34:35], s[10:11]
	s_cmp_gt_u32 s5, 15
	s_cbranch_scc1 .Lp2_ps_14
	v_sub_f32_e32 v24, v24, v220
	v_sub_f32_e32 v25, v25, v221
	v_sub_f32_e32 v26, v26, v222
	v_sub_f32_e32 v27, v27, v223
.Lp2_ps_14:
	s_min_u32 s18, s5, 16
	v_cvt_f32_u32_e32 v28, s18
	v_rcp_f32_e32 v29, v28
	v_add_f32_e32 v24, v24, v160
	v_add_f32_e32 v25, v25, v161
	v_add_f32_e32 v26, v26, v162
	v_add_f32_e32 v27, v27, v163
	v_fma_f32 v30, -v28, v29, 1.0
	v_fmac_f32_e32 v29, v30, v29
	v_mul_f32_e32 v30, v24, v29
	v_fma_f32 v31, -v28, v30, v24
	v_fmac_f32_e32 v30, v31, v29
	v_fma_f32 v31, -v28, v30, v24
	v_fmac_f32_e32 v30, v31, v29
	v_sub_f32_e32 v36, v30, v160
	v_mul_f32_e32 v30, v25, v29
	v_fma_f32 v31, -v28, v30, v25
	v_fmac_f32_e32 v30, v31, v29
	v_fma_f32 v31, -v28, v30, v25
	v_fmac_f32_e32 v30, v31, v29
	v_sub_f32_e32 v37, v30, v161
	v_mul_f32_e32 v30, v26, v29
	v_fma_f32 v31, -v28, v30, v26
	v_fmac_f32_e32 v30, v31, v29
	v_fma_f32 v31, -v28, v30, v26
	v_fmac_f32_e32 v30, v31, v29
	v_sub_f32_e32 v38, v30, v162
	v_mul_f32_e32 v30, v27, v29
	v_fma_f32 v31, -v28, v30, v27
	v_fmac_f32_e32 v30, v31, v29
	v_fma_f32 v31, -v28, v30, v27
	v_fmac_f32_e32 v30, v31, v29
	v_sub_f32_e32 v39, v30, v163
	v_cvt_pk_bf16_f32 v34, v36, v37
	v_cvt_pk_bf16_f32 v35, v38, v39
	s_nop 0
	global_store_dwordx2 v4, v[34:35], s[10:11] offset:2048
	s_cmp_gt_u32 s5, 16
	s_cbranch_scc1 .Lp2_ps_15
	v_sub_f32_e32 v24, v24, v224
	v_sub_f32_e32 v25, v25, v225
	v_sub_f32_e32 v26, v26, v226
	v_sub_f32_e32 v27, v27, v227

; #define LAS __attribute__((address_space(3)))
; DI unsigned pk2(float a, float b) { f32x2 f = {a, b}; bf16v2 r = __builtin_convertvector(f, bf16v2); return __builtin_bit_cast(unsigned, r); }
; DI float rstd_of(float ssq, float inv_n) { return __builtin_amdgcn_rsqf(ssq * inv_n + 1e-6f); }
; DI void phase2(CP& p, LAS unsigned char* lds, int wid) {
;     ...
;             if (tid < 128) rsl[tid] = rstd_of(SSQ(1)[t0 + tid], 1.f / 1024.f);
;             __syncthreads();
;             { const int t = tid >> 2, sq = (tid & 3) * 32; const float* wrow = p.w_s + ((size_t)h * 128 + t) * 128 + sq;
; #pragma unroll
;               for (int e = 0; e < 4; ++e) { const f32x4 a = *(const f32x4*)(wrow + e * 8), b = *(const f32x4*)(wrow + e * 8 + 4); const int s0 = sq + e * 8;
;                   const float mk = ((s0 >> 6) <= (t >> 6)) ? 1.f : 0.f;
;                   u32x4 w; w.x = pk2(a[0] * mk * rsl[s0], a[1] * mk * rsl[s0 + 1]); w.y = pk2(a[2] * mk * rsl[s0 + 2], a[3] * mk * rsl[s0 + 3]);
;                   w.z = pk2(b[0] * mk * rsl[s0 + 4], b[1] * mk * rsl[s0 + 5]); w.w = pk2(b[2] * mk * rsl[s0 + 6], b[3] * mk * rsl[s0 + 7]);
;                   *(LAS u32x4*)(wm + t * 272 + s0 * 2) = w; } }
.Lp2_g_item:
	s_mov_b64 s[18:19], s[8:9]
	s_waitcnt vmcnt(0)
	v_fmamk_f32 v22, v22, 0x3a800000, v23
	v_rsq_f32_e32 v22, v22
	s_nop 0
	ds_write_b32 v21, v22
	s_waitcnt lgkmcnt(0)
	s_barrier
	ds_read_b128 v[24:27], v12
	ds_read_b128 v[28:31], v12 offset:16
	ds_read_b128 v[32:35], v12 offset:32
	ds_read_b128 v[36:39], v12 offset:48
	ds_read_b128 v[40:43], v12 offset:64
	ds_read_b128 v[44:47], v12 offset:80
	ds_read_b128 v[48:51], v12 offset:96
	ds_read_b128 v[52:55], v12 offset:112
	v_mov_b32_e32 v192, v132
	v_mov_b32_e32 v193, v133
	v_mov_b32_e32 v194, v134
	v_mov_b32_e32 v195, v135
	v_mov_b32_e32 v196, v136
	v_mov_b32_e32 v197, v137
	v_mov_b32_e32 v198, v138
	v_mov_b32_e32 v199, v139
	v_mov_b32_e32 v200, v140
	v_mov_b32_e32 v201, v141
	v_mov_b32_e32 v202, v142
	v_mov_b32_e32 v203, v143
	v_mov_b32_e32 v204, v144
	v_mov_b32_e32 v205, v145
	v_mov_b32_e32 v206, v146
	v_mov_b32_e32 v207, v147
	v_mov_b32_e32 v208, v148
	v_mov_b32_e32 v209, v149
	v_mov_b32_e32 v210, v150
	v_mov_b32_e32 v211, v151
	v_mov_b32_e32 v212, v160
	v_mov_b32_e32 v213, v161
	v_mov_b32_e32 v214, v162
	v_mov_b32_e32 v215, v163
	v_mov_b32_e32 v216, v164
	v_mov_b32_e32 v217, v165
	v_mov_b32_e32 v218, v166
	v_mov_b32_e32 v219, v167
	v_mov_b32_e32 v220, v168
	v_mov_b32_e32 v221, v169
	v_mov_b32_e32 v222, v170
	v_mov_b32_e32 v223, v171
	v_mov_b32_e32 v224, v172
	v_mov_b32_e32 v225, v173
	v_mov_b32_e32 v226, v174
	v_mov_b32_e32 v227, v175
	v_mov_b32_e32 v228, v176
	v_mov_b32_e32 v230, v178
	v_mov_b32_e32 v232, v180
	v_mov_b32_e32 v234, v182
	v_mov_b32_e32 v236, v184
	v_mov_b32_e32 v238, v186
	v_mov_b32_e32 v240, v188
	v_mov_b32_e32 v242, v190
	s_waitcnt lgkmcnt(7)
	v_mul_f32_e32 v100, v10, v100
	v_mul_f32_e32 v101, v11, v101
	v_mul_f32_e32 v102, v10, v102
	v_mul_f32_e32 v103, v11, v103
	v_mul_f32_e32 v100, v100, v24
	v_mul_f32_e32 v101, v101, v25
	v_mul_f32_e32 v102, v102, v26
	v_mul_f32_e32 v103, v103, v27
	s_waitcnt lgkmcnt(6)
	v_mul_f32_e32 v104, v10, v104
	v_mul_f32_e32 v105, v11, v105
	v_mul_f32_e32 v106, v10, v106
	v_mul_f32_e32 v107, v11, v107
	v_mul_f32_e32 v104, v104, v28
	v_mul_f32_e32 v105, v105, v29
	v_mul_f32_e32 v106, v106, v30
	v_mul_f32_e32 v107, v107, v31
	s_waitcnt lgkmcnt(5)
	v_mul_f32_e32 v108, v10, v108
	v_mul_f32_e32 v109, v11, v109
	v_mul_f32_e32 v110, v10, v110
	v_mul_f32_e32 v111, v11, v111
	v_mul_f32_e32 v108, v108, v32
	v_mul_f32_e32 v109, v109, v33
	v_mul_f32_e32 v110, v110, v34
	v_mul_f32_e32 v111, v111, v35
	s_waitcnt lgkmcnt(4)
	v_mul_f32_e32 v112, v10, v112
	v_mul_f32_e32 v113, v11, v113
	v_mul_f32_e32 v114, v10, v114
	v_mul_f32_e32 v115, v11, v115
	v_mul_f32_e32 v112, v112, v36
	v_mul_f32_e32 v113, v113, v37
	v_mul_f32_e32 v114, v114, v38
	v_mul_f32_e32 v115, v115, v39
	s_waitcnt lgkmcnt(3)
	v_mul_f32_e32 v116, v10, v116
	v_mul_f32_e32 v117, v11, v117
	v_mul_f32_e32 v118, v10, v118
	v_mul_f32_e32 v119, v11, v119
	v_mul_f32_e32 v116, v116, v40
	v_mul_f32_e32 v117, v117, v41
	v_mul_f32_e32 v118, v118, v42
	v_mul_f32_e32 v119, v119, v43
	s_waitcnt lgkmcnt(2)
	v_mul_f32_e32 v120, v10, v120
	v_mul_f32_e32 v121, v11, v121
	v_mul_f32_e32 v122, v10, v122
	v_mul_f32_e32 v123, v11, v123
	v_mul_f32_e32 v120, v120, v44
	v_mul_f32_e32 v121, v121, v45
	v_mul_f32_e32 v122, v122, v46
	v_mul_f32_e32 v123, v123, v47
	s_waitcnt lgkmcnt(1)
	v_mul_f32_e32 v124, v10, v124
	v_mul_f32_e32 v125, v11, v125
	v_mul_f32_e32 v126, v10, v126
	v_mul_f32_e32 v127, v11, v127
	v_mul_f32_e32 v124, v124, v48
	v_mul_f32_e32 v125, v125, v49
	v_mul_f32_e32 v126, v126, v50
	v_mul_f32_e32 v127, v127, v51
	s_waitcnt lgkmcnt(0)
	v_mul_f32_e32 v128, v10, v128
	v_mul_f32_e32 v129, v11, v129
	v_mul_f32_e32 v130, v10, v130
	v_mul_f32_e32 v131, v11, v131
	v_mul_f32_e32 v128, v128, v52
	v_mul_f32_e32 v129, v129, v53
	v_mul_f32_e32 v130, v130, v54
	v_mul_f32_e32 v131, v131, v55
	v_cvt_pk_bf16_f32 v24, v100, v101
	v_cvt_pk_bf16_f32 v25, v102, v103
	v_cvt_pk_bf16_f32 v26, v104, v105
	v_cvt_pk_bf16_f32 v27, v106, v107
	v_cvt_pk_bf16_f32 v28, v108, v109
	v_cvt_pk_bf16_f32 v29, v110, v111
	v_cvt_pk_bf16_f32 v30, v112, v113
	v_cvt_pk_bf16_f32 v31, v114, v115
	v_cvt_pk_bf16_f32 v32, v116, v117
	v_cvt_pk_bf16_f32 v33, v118, v119
	v_cvt_pk_bf16_f32 v34, v120, v121
	v_cvt_pk_bf16_f32 v35, v122, v123
	v_cvt_pk_bf16_f32 v36, v124, v125
	v_cvt_pk_bf16_f32 v37, v126, v127
	v_cvt_pk_bf16_f32 v38, v128, v129
	v_cvt_pk_bf16_f32 v39, v130, v131
	s_nop 0
	ds_write_b128 v13, v[24:27]
	ds_write_b128 v13, v[28:31] offset:16
	ds_write_b128 v13, v[32:35] offset:32
	ds_write_b128 v13, v[36:39] offset:48
	s_add_i32 s39, s39, s100
	s_cmp_ge_i32 s39, s101
	s_cbranch_scc1 .Lp2_g_nonext
; #define LAS __attribute__((address_space(3)))
; DI void phase2(CP& p, LAS unsigned char* lds, int wid) {
;     ...
;             const int ch = h * 128 + 16 * wid + fr; const bf16_t* vt = WSB(OFF_VT) + (size_t)ch * 8192 + t0 + 8 * fq;
;             bf16x8 bfr[4];
; #pragma unroll
;             for (int ks = 0; ks < 4; ++ks) bfr[ks] = *(const bf16x8*)(vt + 32 * ks);
;             f32x4 acc[8];
; #pragma unroll
;             for (int tt = 0; tt < 8; ++tt) { acc[tt] = (f32x4){0.f, 0.f, 0.f, 0.f};
; #pragma unroll
;                 for (int ks = 0; ks < 4; ++ks) { const bf16x8 af = *(const LAS bf16x8*)(wm + (16 * tt + fr) * 272 + (32 * ks + 8 * fq) * 2);
;                     acc[tt] = __builtin_amdgcn_mfma_f32_16x16x32_bf16(bfr[ks], af, acc[tt], 0, 0, 0); } }
;             const int d0 = h * 128 + 16 * wid + 4 * fq; const f32x4 gv = *(const f32x4*)(p.g_v + d0);
; #pragma unroll
;             for (int tt = 0; tt < 8; ++tt) { const int t = 16 * tt + fr, tok = t0 + t; const float bs = p.b_s[h * 128 + t];
;                 const u32x2 uw = *(const u32x2*)(WSB(OFF_U) + (size_t)tok * 1024 + d0);
	s_add_i32 s2, s39, 0xffffff00
	s_and_b32 s3, s2, 7
	s_lshr_b32 s2, s2, 3
	s_lshl_b32 s2, s2, 7
	s_lshl_b32 s4, s2, 2
	s_add_u32 s10, s20, s4
	s_addc_u32 s11, s21, 0
	global_load_dword v22, v20, s[10:11]
	s_lshl_b32 s4, s3, 16
	s_add_u32 s10, s14, s4
	s_addc_u32 s11, s15, 0
	global_load_dwordx4 v[100:103], v8, s[10:11]
	global_load_dwordx4 v[104:107], v8, s[10:11] offset:16
	global_load_dwordx4 v[108:111], v8, s[10:11] offset:32
	global_load_dwordx4 v[112:115], v8, s[10:11] offset:48
	global_load_dwordx4 v[116:119], v8, s[10:11] offset:64
	global_load_dwordx4 v[120:123], v8, s[10:11] offset:80
	global_load_dwordx4 v[124:127], v8, s[10:11] offset:96
	global_load_dwordx4 v[128:131], v8, s[10:11] offset:112
	s_lshl_b32 s4, s3, 21
	s_lshl_b32 s5, s2, 1
	s_add_i32 s4, s4, s5
	s_add_u32 s10, s28, s4
	s_addc_u32 s11, s29, 0
	global_load_dwordx4 v[132:135], v14, s[10:11]
	global_load_dwordx4 v[136:139], v14, s[10:11] offset:64
	global_load_dwordx4 v[140:143], v14, s[10:11] offset:128
	global_load_dwordx4 v[144:147], v14, s[10:11] offset:192
	s_lshl_b32 s4, s3, 9
	s_add_u32 s10, s12, s4
	s_addc_u32 s11, s13, 0
	global_load_dwordx4 v[148:151], v15, s[10:11]
	s_add_u32 s10, s22, s4
	s_addc_u32 s11, s23, 0
	global_load_dword v176, v16, s[10:11]
	global_load_dword v178, v16, s[10:11] offset:64
	global_load_dword v180, v16, s[10:11] offset:128
	global_load_dword v182, v16, s[10:11] offset:192
	global_load_dword v184, v16, s[10:11] offset:256
	global_load_dword v186, v16, s[10:11] offset:320
	global_load_dword v188, v16, s[10:11] offset:384
	global_load_dword v190, v16, s[10:11] offset:448
	s_lshl_b32 s4, s2, 11
	s_lshl_b32 s5, s3, 8
	s_add_i32 s4, s4, s5
	s_add_u32 s10, s30, s4
	s_addc_u32 s11, s31, 0
	global_load_dwordx2 v[160:161], v17, s[10:11]
	s_add_u32 s10, s10, 0x8000
	s_addc_u32 s11, s11, 0
	global_load_dwordx2 v[162:163], v17, s[10:11]
	s_add_u32 s10, s10, 0x8000
	s_addc_u32 s11, s11, 0
	global_load_dwordx2 v[164:165], v17, s[10:11]
	s_add_u32 s10, s10, 0x8000
	s_addc_u32 s11, s11, 0
	global_load_dwordx2 v[166:167], v17, s[10:11]
	s_add_u32 s10, s10, 0x8000
	s_addc_u32 s11, s11, 0
	global_load_dwordx2 v[168:169], v17, s[10:11]
	s_add_u32 s10, s10, 0x8000
	s_addc_u32 s11, s11, 0
	global_load_dwordx2 v[170:171], v17, s[10:11]
	s_add_u32 s10, s10, 0x8000
	s_addc_u32 s11, s11, 0
	global_load_dwordx2 v[172:173], v17, s[10:11]
	s_add_u32 s10, s10, 0x8000
	s_addc_u32 s11, s11, 0
	global_load_dwordx2 v[174:175], v17, s[10:11]
	s_lshl_b32 s4, s2, 12
	s_add_i32 s4, s4, s5
	s_add_u32 s8, s36, s4
	s_addc_u32 s9, s37, 0
.Lp2_g_nonext:
	s_waitcnt lgkmcnt(0)
	s_barrier
	ds_read_b128 v[24:27], v19 offset:0
	ds_read_b128 v[28:31], v19 offset:64
	ds_read_b128 v[32:35], v19 offset:128
	ds_read_b128 v[36:39], v19 offset:192
	ds_read_b128 v[40:43], v19 offset:4352
	ds_read_b128 v[44:47], v19 offset:4416
	ds_read_b128 v[48:51], v19 offset:4480
	ds_read_b128 v[52:55], v19 offset:4544
	s_waitcnt lgkmcnt(7)
	v_mfma_f32_16x16x32_bf16 v[56:59], v[192:195], v[24:27], 0
	s_waitcnt lgkmcnt(6)
	v_mfma_f32_16x16x32_bf16 v[56:59], v[196:199], v[28:31], v[56:59]
	s_waitcnt lgkmcnt(5)
	v_mfma_f32_16x16x32_bf16 v[56:59], v[200:203], v[32:35], v[56:59]
	s_waitcnt lgkmcnt(4)
	v_mfma_f32_16x16x32_bf16 v[56:59], v[204:207], v[36:39], v[56:59]
	ds_read_b128 v[24:27], v19 offset:8704
	ds_read_b128 v[28:31], v19 offset:8768
	ds_read_b128 v[32:35], v19 offset:8832
	ds_read_b128 v[36:39], v19 offset:8896
	s_waitcnt lgkmcnt(7)
	v_mfma_f32_16x16x32_bf16 v[60:63], v[192:195], v[40:43], 0
	s_waitcnt lgkmcnt(6)
	v_mfma_f32_16x16x32_bf16 v[60:63], v[196:199], v[44:47], v[60:63]
	s_waitcnt lgkmcnt(5)
	v_mfma_f32_16x16x32_bf16 v[60:63], v[200:203], v[48:51], v[60:63]
	s_waitcnt lgkmcnt(4)
	v_mfma_f32_16x16x32_bf16 v[60:63], v[204:207], v[52:55], v[60:63]
	ds_read_b128 v[40:43], v19 offset:13056
	ds_read_b128 v[44:47], v19 offset:13120
	ds_read_b128 v[48:51], v19 offset:13184
	ds_read_b128 v[52:55], v19 offset:13248
	s_waitcnt lgkmcnt(7)
	v_mfma_f32_16x16x32_bf16 v[64:67], v[192:195], v[24:27], 0
	s_waitcnt lgkmcnt(6)
	v_mfma_f32_16x16x32_bf16 v[64:67], v[196:199], v[28:31], v[64:67]
	s_waitcnt lgkmcnt(5)
	v_mfma_f32_16x16x32_bf16 v[64:67], v[200:203], v[32:35], v[64:67]
	s_waitcnt lgkmcnt(4)
	v_mfma_f32_16x16x32_bf16 v[64:67], v[204:207], v[36:39], v[64:67]
	ds_read_b128 v[24:27], v19 offset:17408
	ds_read_b128 v[28:31], v19 offset:17472
	ds_read_b128 v[32:35], v19 offset:17536
	ds_read_b128 v[36:39], v19 offset:17600
	s_waitcnt lgkmcnt(7)
	v_mfma_f32_16x16x32_bf16 v[68:71], v[192:195], v[40:43], 0
	s_waitcnt lgkmcnt(6)
	v_mfma_f32_16x16x32_bf16 v[68:71], v[196:199], v[44:47], v[68:71]
	s_waitcnt lgkmcnt(5)
	v_mfma_f32_16x16x32_bf16 v[68:71], v[200:203], v[48:51], v[68:71]
	s_waitcnt lgkmcnt(4)
	v_mfma_f32_16x16x32_bf16 v[68:71], v[204:207], v[52:55], v[68:71]
	ds_read_b128 v[40:43], v19 offset:21760
	ds_read_b128 v[44:47], v19 offset:21824
	ds_read_b128 v[48:51], v19 offset:21888
	ds_read_b128 v[52:55], v19 offset:21952
	s_waitcnt lgkmcnt(7)
	v_mfma_f32_16x16x32_bf16 v[72:75], v[192:195], v[24:27], 0
	s_waitcnt lgkmcnt(6)
	v_mfma_f32_16x16x32_bf16 v[72:75], v[196:199], v[28:31], v[72:75]
	s_waitcnt lgkmcnt(5)
	v_mfma_f32_16x16x32_bf16 v[72:75], v[200:203], v[32:35], v[72:75]
	s_waitcnt lgkmcnt(4)
	v_mfma_f32_16x16x32_bf16 v[72:75], v[204:207], v[36:39], v[72:75]
	ds_read_b128 v[24:27], v19 offset:26112
	ds_read_b128 v[28:31], v19 offset:26176
	ds_read_b128 v[32:35], v19 offset:26240
	ds_read_b128 v[36:39], v19 offset:26304
	s_waitcnt lgkmcnt(7)
	v_mfma_f32_16x16x32_bf16 v[76:79], v[192:195], v[40:43], 0
	s_waitcnt lgkmcnt(6)
; DI u32x2 pk4(f32x4 v) { u32x2 r; r.x = pk2(v[0], v[1]); r.y = pk2(v[2], v[3]); return r; }
; DI float bf_lo(unsigned w) { return __uint_as_float(w << 16); }
; DI float bf_hi(unsigned w) { return __uint_as_float(w & 0xffff0000u); }
; DI void phase2(CP& p, LAS unsigned char* lds, int wid) {
;     ...
;             const int d0 = h * 128 + 16 * wid + 4 * fq; const f32x4 gv = *(const f32x4*)(p.g_v + d0);
; #pragma unroll
;             for (int tt = 0; tt < 8; ++tt) { const int t = 16 * tt + fr, tok = t0 + t; const float bs = p.b_s[h * 128 + t];
;                 const u32x2 uw = *(const u32x2*)(WSB(OFF_U) + (size_t)tok * 1024 + d0);
;                 f32x4 a; a[0] = bf_lo(uw.x) * (acc[tt][0] * gv[0] + bs); a[1] = bf_hi(uw.x) * (acc[tt][1] * gv[1] + bs);
;                 a[2] = bf_lo(uw.y) * (acc[tt][2] * gv[2] + bs); a[3] = bf_hi(uw.y) * (acc[tt][3] * gv[3] + bs);
;                 *(u32x2*)(WSB(OFF_CAT) + (size_t)tok * 2048 + d0) = pk4(a); }
	v_mfma_f32_16x16x32_bf16 v[76:79], v[196:199], v[44:47], v[76:79]
	s_waitcnt lgkmcnt(5)
	v_mfma_f32_16x16x32_bf16 v[76:79], v[200:203], v[48:51], v[76:79]
	s_waitcnt lgkmcnt(4)
	v_mfma_f32_16x16x32_bf16 v[76:79], v[204:207], v[52:55], v[76:79]
	ds_read_b128 v[40:43], v19 offset:30464
	ds_read_b128 v[44:47], v19 offset:30528
	ds_read_b128 v[48:51], v19 offset:30592
	ds_read_b128 v[52:55], v19 offset:30656
	s_waitcnt lgkmcnt(7)
	v_mfma_f32_16x16x32_bf16 v[80:83], v[192:195], v[24:27], 0
	s_waitcnt lgkmcnt(6)
	v_mfma_f32_16x16x32_bf16 v[80:83], v[196:199], v[28:31], v[80:83]
	s_waitcnt lgkmcnt(5)
	v_mfma_f32_16x16x32_bf16 v[80:83], v[200:203], v[32:35], v[80:83]
	s_waitcnt lgkmcnt(4)
	v_mfma_f32_16x16x32_bf16 v[80:83], v[204:207], v[36:39], v[80:83]
	s_waitcnt lgkmcnt(3)
	v_mfma_f32_16x16x32_bf16 v[84:87], v[192:195], v[40:43], 0
	s_waitcnt lgkmcnt(2)
	v_mfma_f32_16x16x32_bf16 v[84:87], v[196:199], v[44:47], v[84:87]
	s_waitcnt lgkmcnt(1)
	v_mfma_f32_16x16x32_bf16 v[84:87], v[200:203], v[48:51], v[84:87]
	s_waitcnt lgkmcnt(0)
	v_mfma_f32_16x16x32_bf16 v[84:87], v[204:207], v[52:55], v[84:87]
	s_nop 7
	v_fma_f32 v56, v56, v208, v228
	v_fma_f32 v57, v57, v209, v228
	v_fma_f32 v58, v58, v210, v228
	v_fma_f32 v59, v59, v211, v228
	v_lshlrev_b32_e32 v24, 16, v212
	v_and_b32_e32 v25, 0xffff0000, v212
	v_lshlrev_b32_e32 v26, 16, v213
	v_and_b32_e32 v27, 0xffff0000, v213
	v_mul_f32_e32 v56, v56, v24
	v_mul_f32_e32 v57, v57, v25
	v_mul_f32_e32 v58, v58, v26
	v_mul_f32_e32 v59, v59, v27
	v_cvt_pk_bf16_f32 v56, v56, v57
	v_cvt_pk_bf16_f32 v57, v58, v59
	global_store_dwordx2 v18, v[56:57], s[18:19]
	v_fma_f32 v60, v60, v208, v230
	v_fma_f32 v61, v61, v209, v230
	v_fma_f32 v62, v62, v210, v230
	v_fma_f32 v63, v63, v211, v230
	v_lshlrev_b32_e32 v24, 16, v214
	v_and_b32_e32 v25, 0xffff0000, v214
	v_lshlrev_b32_e32 v26, 16, v215
	v_and_b32_e32 v27, 0xffff0000, v215
	v_mul_f32_e32 v60, v60, v24
	v_mul_f32_e32 v61, v61, v25
	v_mul_f32_e32 v62, v62, v26
	v_mul_f32_e32 v63, v63, v27
	v_cvt_pk_bf16_f32 v60, v60, v61
	v_cvt_pk_bf16_f32 v61, v62, v63
	s_add_u32 s18, s18, 0x10000
	s_addc_u32 s19, s19, 0
	global_store_dwordx2 v18, v[60:61], s[18:19]
	v_fma_f32 v64, v64, v208, v232
	v_fma_f32 v65, v65, v209, v232
	v_fma_f32 v66, v66, v210, v232
	v_fma_f32 v67, v67, v211, v232
	v_lshlrev_b32_e32 v24, 16, v216
	v_and_b32_e32 v25, 0xffff0000, v216
	v_lshlrev_b32_e32 v26, 16, v217
	v_and_b32_e32 v27, 0xffff0000, v217
	v_mul_f32_e32 v64, v64, v24
	v_mul_f32_e32 v65, v65, v25
	v_mul_f32_e32 v66, v66, v26
	v_mul_f32_e32 v67, v67, v27
	v_cvt_pk_bf16_f32 v64, v64, v65
	v_cvt_pk_bf16_f32 v65, v66, v67
	s_add_u32 s18, s18, 0x10000
	s_addc_u32 s19, s19, 0
	global_store_dwordx2 v18, v[64:65], s[18:19]
	v_fma_f32 v68, v68, v208, v234
	v_fma_f32 v69, v69, v209, v234
	v_fma_f32 v70, v70, v210, v234
	v_fma_f32 v71, v71, v211, v234
	v_lshlrev_b32_e32 v24, 16, v218
	v_and_b32_e32 v25, 0xffff0000, v218
	v_lshlrev_b32_e32 v26, 16, v219
	v_and_b32_e32 v27, 0xffff0000, v219
	v_mul_f32_e32 v68, v68, v24
	v_mul_f32_e32 v69, v69, v25
	v_mul_f32_e32 v70, v70, v26
	v_mul_f32_e32 v71, v71, v27
	v_cvt_pk_bf16_f32 v68, v68, v69
	v_cvt_pk_bf16_f32 v69, v70, v71
	s_add_u32 s18, s18, 0x10000
	s_addc_u32 s19, s19, 0
	global_store_dwordx2 v18, v[68:69], s[18:19]
	v_fma_f32 v72, v72, v208, v236
	v_fma_f32 v73, v73, v209, v236
	v_fma_f32 v74, v74, v210, v236
	v_fma_f32 v75, v75, v211, v236
	v_lshlrev_b32_e32 v24, 16, v220
	v_and_b32_e32 v25, 0xffff0000, v220
	v_lshlrev_b32_e32 v26, 16, v221
	v_and_b32_e32 v27, 0xffff0000, v221
	v_mul_f32_e32 v72, v72, v24
	v_mul_f32_e32 v73, v73, v25
	v_mul_f32_e32 v74, v74, v26
	v_mul_f32_e32 v75, v75, v27
	v_cvt_pk_bf16_f32 v72, v72, v73
	v_cvt_pk_bf16_f32 v73, v74, v75
	s_add_u32 s18, s18, 0x10000
	s_addc_u32 s19, s19, 0
	global_store_dwordx2 v18, v[72:73], s[18:19]
	v_fma_f32 v76, v76, v208, v238
	v_fma_f32 v77, v77, v209, v238
	v_fma_f32 v78, v78, v210, v238
	v_fma_f32 v79, v79, v211, v238
	v_lshlrev_b32_e32 v24, 16, v222
	v_and_b32_e32 v25, 0xffff0000, v222
	v_lshlrev_b32_e32 v26, 16, v223
	v_and_b32_e32 v27, 0xffff0000, v223
	v_mul_f32_e32 v76, v76, v24
	v_mul_f32_e32 v77, v77, v25
	v_mul_f32_e32 v78, v78, v26
	v_mul_f32_e32 v79, v79, v27
	v_cvt_pk_bf16_f32 v76, v76, v77
	v_cvt_pk_bf16_f32 v77, v78, v79
	s_add_u32 s18, s18, 0x10000
	s_addc_u32 s19, s19, 0
	global_store_dwordx2 v18, v[76:77], s[18:19]
	v_fma_f32 v80, v80, v208, v240
	v_fma_f32 v81, v81, v209, v240
	v_fma_f32 v82, v82, v210, v240
	v_fma_f32 v83, v83, v211, v240
	v_lshlrev_b32_e32 v24, 16, v224
	v_and_b32_e32 v25, 0xffff0000, v224
	v_lshlrev_b32_e32 v26, 16, v225
	v_and_b32_e32 v27, 0xffff0000, v225
	v_mul_f32_e32 v80, v80, v24
	v_mul_f32_e32 v81, v81, v25
	v_mul_f32_e32 v82, v82, v26
	v_mul_f32_e32 v83, v83, v27
	v_cvt_pk_bf16_f32 v80, v80, v81
	v_cvt_pk_bf16_f32 v81, v82, v83
	s_add_u32 s18, s18, 0x10000
	s_addc_u32 s19, s19, 0
	global_store_dwordx2 v18, v[80:81], s[18:19]
	v_fma_f32 v84, v84, v208, v242
	v_fma_f32 v85, v85, v209, v242
	v_fma_f32 v86, v86, v210, v242
	v_fma_f32 v87, v87, v211, v242
	v_lshlrev_b32_e32 v24, 16, v226
	v_and_b32_e32 v25, 0xffff0000, v226
	v_lshlrev_b32_e32 v26, 16, v227
	v_and_b32_e32 v27, 0xffff0000, v227
	v_mul_f32_e32 v84, v84, v24
	v_mul_f32_e32 v85, v85, v25
	v_mul_f32_e32 v86, v86, v26
	v_mul_f32_e32 v87, v87, v27
	v_cvt_pk_bf16_f32 v84, v84, v85
	v_cvt_pk_bf16_f32 v85, v86, v87
	s_add_u32 s18, s18, 0x10000
	s_addc_u32 s19, s19, 0
	global_store_dwordx2 v18, v[84:85], s[18:19]
	s_cmp_lt_i32 s39, s101
	s_cbranch_scc1 .Lp2_g_item
	s_branch .Lp2_done

; #define PG8_STAGE(bufoff, gbase, voff) do { _Pragma("unroll") for (int _i = 0; _i < 2; ++_i) \
;         __builtin_amdgcn_global_load_lds((const unsigned*)((const char*)(gbase) + (voff)[_i]), (LAS unsigned*)(lds + (bufoff) + ldsw + _i * 8192), 16, 0, 0); } while (0)
; #define PG8_LDA(dst, b, h) do { _Pragma("unroll") for (int m = 0; m < 4; ++m) _Pragma("unroll") for (int k = 0; k < 2; ++k) dst[m][k] = *(const LAS bf16x8*)(lds + PG8_SA(b, h) + aoff + m * 2048 + k * 1024); } while (0)
; #define PG8_LDB(dst, b, h) do { _Pragma("unroll") for (int n = 0; n < 2; ++n) _Pragma("unroll") for (int k = 0; k < 2; ++k) dst[n][k] = *(const LAS bf16x8*)(lds + PG8_SB(b, h) + boff + n * 2048 + k * 1024); } while (0)
; #define PG8_MMA(ai, bj, At, Bt) do { __builtin_amdgcn_s_setprio(1); _Pragma("unroll") for (int m = 0; m < 4; ++m) _Pragma("unroll") for (int n = 0; n < 2; ++n) _Pragma("unroll") for (int k = 0; k < 2; ++k) \
;         acc[ai][bj][m][n] = __builtin_amdgcn_mfma_f32_16x16x32_bf16(Bt[n][k], At[m][k], acc[ai][bj][m][n], 0, 0, 0); __builtin_amdgcn_s_setprio(0); } while (0)
; #define PG8_WAIT_V(n) asm volatile("s_waitcnt vmcnt(" #n ")" ::: "memory")
; #define PG8_WAIT_L(n) asm volatile("s_waitcnt lgkmcnt(" #n ")" ::: "memory")
; #define PG8_BAR __builtin_amdgcn_s_barrier()
; #define PG8_SCHED __builtin_amdgcn_sched_barrier(0)
; template <class Epi>
; DI void gemm_phase(LAS unsigned char* lds, int wid, int K, int lda, int ldb, bool bperm, const Sched3& S, const Epi& E) {
;     ...
;             PG8_LDB(B0, 0, 0); PG8_SCHED; PG8_LDA(At, 0, 0); PG8_STAGE(PG8_SA(1, 1), a1 + hA, voffA);
;             PG8_WAIT_L(8); PG8_BAR; PG8_WAIT_L(0); PG8_MMA(0, 0, At, B0); PG8_BAR; PG8_SCHED;
;             PG8_LDB(B1, 0, 1); PG8_STAGE(PG8_SB(0, 0), b2, voffB);
;             PG8_BAR; PG8_WAIT_L(0); PG8_MMA(0, 1, At, B1); PG8_BAR;
;             PG8_LDA(At, 0, 1); PG8_STAGE(PG8_SA(0, 0), a2, voffA);
;             PG8_BAR; PG8_WAIT_L(0); if (full) PG8_MMA(1, 0, At, B0); PG8_BAR; PG8_SCHED;
;             PG8_STAGE(PG8_SB(0, 1), b2 + hstepB, voffB);
;             PG8_WAIT_V(6); PG8_BAR; if (full) PG8_MMA(1, 1, At, B1); PG8_BAR;
.LBB0_537:
	ds_read_b128 v[0:3], v146
	ds_read_b128 v[4:7], v146 offset:1024
	ds_read_b128 v[8:11], v146 offset:2048
	ds_read_b128 v[12:15], v146 offset:3072
	s_add_u32 s70, s42, 0x40080
	s_addc_u32 s71, s43, 0
	s_add_i32 s74, s55, 0xc000
	v_lshl_add_u64 v[48:49], s[70:71], 0, v[128:129]
	s_mov_b32 m0, s74
	s_add_i32 s29, s55, 0xe000
	ds_read_b128 v[16:19], v147
	ds_read_b128 v[20:23], v147 offset:1024
	ds_read_b128 v[24:27], v147 offset:2048
	ds_read_b128 v[28:31], v147 offset:3072
	ds_read_b128 v[32:35], v147 offset:4096
	ds_read_b128 v[36:39], v147 offset:5120
	ds_read_b128 v[40:43], v147 offset:6144
	ds_read_b128 v[44:47], v147 offset:7168
	global_load_lds_dwordx4 v[48:49], off
	v_lshl_add_u64 v[48:49], s[70:71], 0, v[132:133]
	s_mov_b32 m0, s29
	s_nop 0
	global_load_lds_dwordx4 v[48:49], off
	s_waitcnt lgkmcnt(8)
	s_barrier
	s_waitcnt lgkmcnt(0)
	s_setprio 1
	s_waitcnt lgkmcnt(0)
	v_mfma_f32_16x16x32_bf16 v[48:51], v[0:3], v[16:19], 0
	v_mfma_f32_16x16x32_bf16 v[52:55], v[8:11], v[16:19], 0
	v_mfma_f32_16x16x32_bf16 v[56:59], v[0:3], v[24:27], 0
	v_mfma_f32_16x16x32_bf16 v[60:63], v[8:11], v[24:27], 0
	v_mfma_f32_16x16x32_bf16 v[64:67], v[0:3], v[32:35], 0
	v_mfma_f32_16x16x32_bf16 v[68:71], v[8:11], v[32:35], 0
	v_mfma_f32_16x16x32_bf16 v[72:75], v[0:3], v[40:43], 0
	v_mfma_f32_16x16x32_bf16 v[76:79], v[8:11], v[40:43], 0
	v_mfma_f32_16x16x32_bf16 v[48:51], v[4:7], v[20:23], v[48:51]
	v_mfma_f32_16x16x32_bf16 v[52:55], v[12:15], v[20:23], v[52:55]
	v_mfma_f32_16x16x32_bf16 v[56:59], v[4:7], v[28:31], v[56:59]
	v_mfma_f32_16x16x32_bf16 v[60:63], v[12:15], v[28:31], v[60:63]
	v_mfma_f32_16x16x32_bf16 v[64:67], v[4:7], v[36:39], v[64:67]
	v_mfma_f32_16x16x32_bf16 v[68:71], v[12:15], v[36:39], v[68:71]
	v_mfma_f32_16x16x32_bf16 v[72:75], v[4:7], v[44:47], v[72:75]
	v_mfma_f32_16x16x32_bf16 v[76:79], v[12:15], v[44:47], v[76:79]
	s_setprio 0
	s_barrier
	v_lshl_add_u64 v[142:143], s[44:45], 0, v[130:131]
	s_add_i32 s71, s63, s54
	v_lshl_add_u64 v[96:97], v[142:143], 0, s[14:15]
	s_mov_b32 m0, s71
	v_lshl_add_u64 v[214:215], s[44:45], 0, v[134:135]
	s_add_i32 s31, s71, 0x2000
	ds_read_b128 v[80:83], v148
	ds_read_b128 v[84:87], v148 offset:1024
	ds_read_b128 v[88:91], v148 offset:2048
	ds_read_b128 v[92:95], v148 offset:3072
	global_load_lds_dwordx4 v[96:97], off
	v_lshl_add_u64 v[96:97], v[214:215], 0, s[14:15]
	s_mov_b32 m0, s31
	s_nop 0
	global_load_lds_dwordx4 v[96:97], off
	s_barrier
	s_waitcnt lgkmcnt(0)
	s_setprio 1
	s_waitcnt lgkmcnt(0)
	v_mfma_f32_16x16x32_bf16 v[96:99], v[80:83], v[16:19], 0
	v_mfma_f32_16x16x32_bf16 v[16:19], v[88:91], v[16:19], 0
	v_mfma_f32_16x16x32_bf16 v[96:99], v[84:87], v[20:23], v[96:99]
	v_mfma_f32_16x16x32_bf16 v[16:19], v[92:95], v[20:23], v[16:19]
	v_mfma_f32_16x16x32_bf16 v[20:23], v[80:83], v[24:27], 0
	v_mfma_f32_16x16x32_bf16 v[24:27], v[88:91], v[24:27], 0
	v_mfma_f32_16x16x32_bf16 v[20:23], v[84:87], v[28:31], v[20:23]
	v_mfma_f32_16x16x32_bf16 v[24:27], v[92:95], v[28:31], v[24:27]
	v_mfma_f32_16x16x32_bf16 v[28:31], v[80:83], v[32:35], 0
	v_mfma_f32_16x16x32_bf16 v[32:35], v[88:91], v[32:35], 0
	v_mfma_f32_16x16x32_bf16 v[28:31], v[84:87], v[36:39], v[28:31]
	v_mfma_f32_16x16x32_bf16 v[32:35], v[92:95], v[36:39], v[32:35]
	v_mfma_f32_16x16x32_bf16 v[36:39], v[80:83], v[40:43], 0
	v_mfma_f32_16x16x32_bf16 v[40:43], v[88:91], v[40:43], 0
	v_mfma_f32_16x16x32_bf16 v[36:39], v[84:87], v[44:47], v[36:39]
	v_mfma_f32_16x16x32_bf16 v[40:43], v[92:95], v[44:47], v[40:43]
	s_setprio 0
	v_lshl_add_u64 v[216:217], s[42:43], 0, v[128:129]
	s_mov_b32 m0, s55
	v_lshl_add_u64 v[150:151], v[216:217], 0, s[14:15]
	v_lshl_add_u64 v[218:219], s[42:43], 0, v[132:133]
	s_barrier
	ds_read_b128 v[44:47], v147 offset:16384
	ds_read_b128 v[100:103], v147 offset:17408
	ds_read_b128 v[104:107], v147 offset:18432
	ds_read_b128 v[108:111], v147 offset:19456
	ds_read_b128 v[112:115], v147 offset:20480
	ds_read_b128 v[116:119], v147 offset:21504
	ds_read_b128 v[120:123], v147 offset:22528
	ds_read_b128 v[124:127], v147 offset:23552
	global_load_lds_dwordx4 v[150:151], off
	v_lshl_add_u64 v[150:151], v[218:219], 0, s[14:15]
	s_mov_b32 m0, s56
	s_nop 0
	global_load_lds_dwordx4 v[150:151], off
	s_barrier
	s_waitcnt lgkmcnt(0)
	s_setprio 1
	s_waitcnt lgkmcnt(0)
	v_mfma_f32_16x16x32_bf16 v[150:153], v[0:3], v[44:47], 0
	v_mfma_f32_16x16x32_bf16 v[158:161], v[0:3], v[104:107], 0
	v_mfma_f32_16x16x32_bf16 v[166:169], v[0:3], v[112:115], 0
	v_mfma_f32_16x16x32_bf16 v[0:3], v[0:3], v[120:123], 0
	v_mfma_f32_16x16x32_bf16 v[150:153], v[4:7], v[100:103], v[150:153]
	v_mfma_f32_16x16x32_bf16 v[154:157], v[8:11], v[44:47], 0
	v_mfma_f32_16x16x32_bf16 v[158:161], v[4:7], v[108:111], v[158:161]
	v_mfma_f32_16x16x32_bf16 v[162:165], v[8:11], v[104:107], 0
	v_mfma_f32_16x16x32_bf16 v[166:169], v[4:7], v[116:119], v[166:169]
	v_mfma_f32_16x16x32_bf16 v[170:173], v[8:11], v[112:115], 0
	v_mfma_f32_16x16x32_bf16 v[0:3], v[4:7], v[124:127], v[0:3]
	v_mfma_f32_16x16x32_bf16 v[4:7], v[8:11], v[120:123], 0
	v_mfma_f32_16x16x32_bf16 v[154:157], v[12:15], v[100:103], v[154:157]
	v_mfma_f32_16x16x32_bf16 v[162:165], v[12:15], v[108:111], v[162:165]
	v_mfma_f32_16x16x32_bf16 v[170:173], v[12:15], v[116:119], v[170:173]
	v_mfma_f32_16x16x32_bf16 v[4:7], v[12:15], v[124:127], v[4:7]
	s_setprio 0
	s_barrier
	s_add_u32 s76, s44, 0x10100
	s_addc_u32 s77, s45, 0
	s_add_i32 s72, s64, s54
	v_lshl_add_u64 v[8:9], s[76:77], 0, v[130:131]
	s_mov_b32 m0, s72
	s_add_i32 s70, s72, 0x2000
	global_load_lds_dwordx4 v[8:9], off
	v_lshl_add_u64 v[8:9], s[76:77], 0, v[134:135]
	s_mov_b32 m0, s70
	s_nop 0
	global_load_lds_dwordx4 v[8:9], off
	s_waitcnt vmcnt(6)
	s_barrier
; #define PG8_STAGE(bufoff, gbase, voff) do { _Pragma("unroll") for (int _i = 0; _i < 2; ++_i) \
;         __builtin_amdgcn_global_load_lds((const unsigned*)((const char*)(gbase) + (voff)[_i]), (LAS unsigned*)(lds + (bufoff) + ldsw + _i * 8192), 16, 0, 0); } while (0)
; #define PG8_LDA(dst, b, h) do { _Pragma("unroll") for (int m = 0; m < 4; ++m) _Pragma("unroll") for (int k = 0; k < 2; ++k) dst[m][k] = *(const LAS bf16x8*)(lds + PG8_SA(b, h) + aoff + m * 2048 + k * 1024); } while (0)
; #define PG8_LDB(dst, b, h) do { _Pragma("unroll") for (int n = 0; n < 2; ++n) _Pragma("unroll") for (int k = 0; k < 2; ++k) dst[n][k] = *(const LAS bf16x8*)(lds + PG8_SB(b, h) + boff + n * 2048 + k * 1024); } while (0)
; #define PG8_MMA(ai, bj, At, Bt) do { __builtin_amdgcn_s_setprio(1); _Pragma("unroll") for (int m = 0; m < 4; ++m) _Pragma("unroll") for (int n = 0; n < 2; ++n) _Pragma("unroll") for (int k = 0; k < 2; ++k) \
;         acc[ai][bj][m][n] = __builtin_amdgcn_mfma_f32_16x16x32_bf16(Bt[n][k], At[m][k], acc[ai][bj][m][n], 0, 0, 0); __builtin_amdgcn_s_setprio(0); } while (0)
; #define PG8_WAIT_V(n) asm volatile("s_waitcnt vmcnt(" #n ")" ::: "memory")
; #define PG8_WAIT_L(n) asm volatile("s_waitcnt lgkmcnt(" #n ")" ::: "memory")
; #define PG8_BAR __builtin_amdgcn_s_barrier()
; #define PG8_SCHED __builtin_amdgcn_sched_barrier(0)
; template <class Epi>
; DI void gemm_phase(LAS unsigned char* lds, int wid, int K, int lda, int ldb, bool bperm, const Sched3& S, const Epi& E) {
;     ...
;             PG8_WAIT_V(6); PG8_BAR; if (full) PG8_MMA(1, 1, At, B1); PG8_BAR;
;             PG8_LDB(B0, 1, 0); PG8_SCHED; PG8_LDA(At, 1, 0); PG8_STAGE(PG8_SA(0, 1), a2 + h2, voffA);
;             PG8_WAIT_L(8); PG8_BAR; PG8_WAIT_L(0); PG8_MMA(0, 0, At, B0); PG8_BAR; PG8_SCHED;
;             PG8_LDB(B1, 1, 1); PG8_STAGE(PG8_SB(1, 0), b3, voffB);
;             PG8_BAR; PG8_WAIT_L(0); PG8_MMA(0, 1, At, B1); PG8_BAR;
	s_setprio 1
	v_mfma_f32_16x16x32_bf16 v[8:11], v[80:83], v[44:47], 0
	v_mfma_f32_16x16x32_bf16 v[12:15], v[88:91], v[44:47], 0
	v_mfma_f32_16x16x32_bf16 v[8:11], v[84:87], v[100:103], v[8:11]
	v_mfma_f32_16x16x32_bf16 v[12:15], v[92:95], v[100:103], v[12:15]
	v_mfma_f32_16x16x32_bf16 v[44:47], v[80:83], v[104:107], 0
	v_mfma_f32_16x16x32_bf16 v[100:103], v[88:91], v[104:107], 0
	v_mfma_f32_16x16x32_bf16 v[104:107], v[80:83], v[112:115], 0
	v_mfma_f32_16x16x32_bf16 v[80:83], v[80:83], v[120:123], 0
	v_mfma_f32_16x16x32_bf16 v[44:47], v[84:87], v[108:111], v[44:47]
	v_mfma_f32_16x16x32_bf16 v[100:103], v[92:95], v[108:111], v[100:103]
	v_mfma_f32_16x16x32_bf16 v[104:107], v[84:87], v[116:119], v[104:107]
	v_mfma_f32_16x16x32_bf16 v[108:111], v[88:91], v[112:115], 0
	v_mfma_f32_16x16x32_bf16 v[80:83], v[84:87], v[124:127], v[80:83]
	v_mfma_f32_16x16x32_bf16 v[84:87], v[88:91], v[120:123], 0
	v_mfma_f32_16x16x32_bf16 v[108:111], v[92:95], v[116:119], v[108:111]
	v_mfma_f32_16x16x32_bf16 v[84:87], v[92:95], v[124:127], v[84:87]
	s_setprio 0
	s_add_i32 s75, 0, 0x18000
	v_add_u32_e32 v149, s75, v145
	s_barrier
	ds_read_b128 v[88:91], v149
	ds_read_b128 v[92:95], v149 offset:1024
	ds_read_b128 v[112:115], v149 offset:2048
	ds_read_b128 v[116:119], v149 offset:3072
	s_add_u32 s76, s42, 0x40100
	s_addc_u32 s77, s43, 0
	s_mov_b32 m0, s57
	v_lshl_add_u64 v[198:199], s[76:77], 0, v[128:129]
	ds_read_b128 v[120:123], v147 offset:32768
	ds_read_b128 v[124:127], v147 offset:33792
	ds_read_b128 v[174:177], v147 offset:34816
	ds_read_b128 v[178:181], v147 offset:35840
	ds_read_b128 v[182:185], v147 offset:36864
	ds_read_b128 v[186:189], v147 offset:37888
	ds_read_b128 v[190:193], v147 offset:38912
	ds_read_b128 v[194:197], v147 offset:39936
	global_load_lds_dwordx4 v[198:199], off
	v_lshl_add_u64 v[198:199], s[76:77], 0, v[132:133]
	s_mov_b32 m0, s58
	s_nop 0
	global_load_lds_dwordx4 v[198:199], off
	s_waitcnt lgkmcnt(8)
	s_barrier
	s_waitcnt lgkmcnt(0)
	s_setprio 1
	s_waitcnt lgkmcnt(0)
	v_mfma_f32_16x16x32_bf16 v[48:51], v[88:91], v[120:123], v[48:51]
	v_mfma_f32_16x16x32_bf16 v[52:55], v[112:115], v[120:123], v[52:55]
	v_mfma_f32_16x16x32_bf16 v[56:59], v[88:91], v[174:177], v[56:59]
	v_mfma_f32_16x16x32_bf16 v[60:63], v[112:115], v[174:177], v[60:63]
	v_mfma_f32_16x16x32_bf16 v[64:67], v[88:91], v[182:185], v[64:67]
	v_mfma_f32_16x16x32_bf16 v[68:71], v[112:115], v[182:185], v[68:71]
	v_mfma_f32_16x16x32_bf16 v[72:75], v[88:91], v[190:193], v[72:75]
	v_mfma_f32_16x16x32_bf16 v[76:79], v[112:115], v[190:193], v[76:79]
	v_mfma_f32_16x16x32_bf16 v[48:51], v[92:95], v[124:127], v[48:51]
	v_mfma_f32_16x16x32_bf16 v[52:55], v[116:119], v[124:127], v[52:55]
	v_mfma_f32_16x16x32_bf16 v[56:59], v[92:95], v[178:181], v[56:59]
	v_mfma_f32_16x16x32_bf16 v[60:63], v[116:119], v[178:181], v[60:63]
	v_mfma_f32_16x16x32_bf16 v[64:67], v[92:95], v[186:189], v[64:67]
	v_mfma_f32_16x16x32_bf16 v[68:71], v[116:119], v[186:189], v[68:71]
	v_mfma_f32_16x16x32_bf16 v[72:75], v[92:95], v[194:197], v[72:75]
	v_mfma_f32_16x16x32_bf16 v[76:79], v[116:119], v[194:197], v[76:79]
	s_setprio 0
	s_barrier
	s_add_i32 s78, 0, 0x1c000
	s_add_i32 s75, s75, s54
	v_add_u32_e32 v236, s78, v145
	v_lshl_add_u64 v[142:143], v[142:143], 0, s[16:17]
	s_mov_b32 m0, s75
	s_add_i32 s73, s75, 0x2000
	ds_read_b128 v[198:201], v236
	ds_read_b128 v[202:205], v236 offset:1024
	ds_read_b128 v[206:209], v236 offset:2048
	ds_read_b128 v[210:213], v236 offset:3072
	global_load_lds_dwordx4 v[142:143], off
	v_lshl_add_u64 v[142:143], v[214:215], 0, s[16:17]
	s_mov_b32 m0, s73
	s_nop 0
	global_load_lds_dwordx4 v[142:143], off
	s_barrier
	s_waitcnt lgkmcnt(0)
	s_setprio 1
	s_waitcnt lgkmcnt(0)
	v_mfma_f32_16x16x32_bf16 v[96:99], v[198:201], v[120:123], v[96:99]
	v_mfma_f32_16x16x32_bf16 v[16:19], v[206:209], v[120:123], v[16:19]
	v_mfma_f32_16x16x32_bf16 v[20:23], v[198:201], v[174:177], v[20:23]
	v_mfma_f32_16x16x32_bf16 v[24:27], v[206:209], v[174:177], v[24:27]
	v_mfma_f32_16x16x32_bf16 v[28:31], v[198:201], v[182:185], v[28:31]
	v_mfma_f32_16x16x32_bf16 v[32:35], v[206:209], v[182:185], v[32:35]
	v_mfma_f32_16x16x32_bf16 v[36:39], v[198:201], v[190:193], v[36:39]
	v_mfma_f32_16x16x32_bf16 v[40:43], v[206:209], v[190:193], v[40:43]
	v_mfma_f32_16x16x32_bf16 v[96:99], v[202:205], v[124:127], v[96:99]
	v_mfma_f32_16x16x32_bf16 v[16:19], v[210:213], v[124:127], v[16:19]
	v_mfma_f32_16x16x32_bf16 v[20:23], v[202:205], v[178:181], v[20:23]
	v_mfma_f32_16x16x32_bf16 v[24:27], v[210:213], v[178:181], v[24:27]
	v_mfma_f32_16x16x32_bf16 v[28:31], v[202:205], v[186:189], v[28:31]
	v_mfma_f32_16x16x32_bf16 v[32:35], v[210:213], v[186:189], v[32:35]
	v_mfma_f32_16x16x32_bf16 v[36:39], v[202:205], v[194:197], v[36:39]
	v_mfma_f32_16x16x32_bf16 v[40:43], v[210:213], v[194:197], v[40:43]
	s_setprio 0
	s_mov_b32 m0, s59
	v_lshl_add_u64 v[142:143], v[216:217], 0, s[16:17]
	s_barrier
	ds_read_b128 v[120:123], v147 offset:49152
	ds_read_b128 v[124:127], v147 offset:50176
	ds_read_b128 v[174:177], v147 offset:51200
	ds_read_b128 v[178:181], v147 offset:52224
	ds_read_b128 v[182:185], v147 offset:53248
	ds_read_b128 v[186:189], v147 offset:54272
	ds_read_b128 v[190:193], v147 offset:55296
	ds_read_b128 v[194:197], v147 offset:56320
	global_load_lds_dwordx4 v[142:143], off
	v_lshl_add_u64 v[142:143], v[218:219], 0, s[16:17]
	s_mov_b32 m0, s60
	s_nop 0
	global_load_lds_dwordx4 v[142:143], off
	s_barrier
; #define PG8_STAGE(bufoff, gbase, voff) do { _Pragma("unroll") for (int _i = 0; _i < 2; ++_i) \
;         __builtin_amdgcn_global_load_lds((const unsigned*)((const char*)(gbase) + (voff)[_i]), (LAS unsigned*)(lds + (bufoff) + ldsw + _i * 8192), 16, 0, 0); } while (0)
; #define PG8_LDA(dst, b, h) do { _Pragma("unroll") for (int m = 0; m < 4; ++m) _Pragma("unroll") for (int k = 0; k < 2; ++k) dst[m][k] = *(const LAS bf16x8*)(lds + PG8_SA(b, h) + aoff + m * 2048 + k * 1024); } while (0)
; #define PG8_LDB(dst, b, h) do { _Pragma("unroll") for (int n = 0; n < 2; ++n) _Pragma("unroll") for (int k = 0; k < 2; ++k) dst[n][k] = *(const LAS bf16x8*)(lds + PG8_SB(b, h) + boff + n * 2048 + k * 1024); } while (0)
; #define PG8_MMA(ai, bj, At, Bt) do { __builtin_amdgcn_s_setprio(1); _Pragma("unroll") for (int m = 0; m < 4; ++m) _Pragma("unroll") for (int n = 0; n < 2; ++n) _Pragma("unroll") for (int k = 0; k < 2; ++k) \
;         acc[ai][bj][m][n] = __builtin_amdgcn_mfma_f32_16x16x32_bf16(Bt[n][k], At[m][k], acc[ai][bj][m][n], 0, 0, 0); __builtin_amdgcn_s_setprio(0); } while (0)
; #define PG8_WAIT_V(n) asm volatile("s_waitcnt vmcnt(" #n ")" ::: "memory")
; #define PG8_WAIT_L(n) asm volatile("s_waitcnt lgkmcnt(" #n ")" ::: "memory")
; #define PG8_BAR __builtin_amdgcn_s_barrier()
; #define PG8_SCHED __builtin_amdgcn_sched_barrier(0)
; template <class Epi>
; DI void gemm_phase(LAS unsigned char* lds, int wid, int K, int lda, int ldb, bool bperm, const Sched3& S, const Epi& E) {
;     ...
;             PG8_LDB(B0, 0, 0); PG8_SCHED; PG8_LDA(At, 0, 0); PG8_STAGE(PG8_SA(1, 1), a1 + hA, voffA);
;             PG8_WAIT_L(8); PG8_BAR; PG8_WAIT_L(0); PG8_MMA(0, 0, At, B0); PG8_BAR; PG8_SCHED;
;             PG8_LDB(B1, 0, 1); PG8_STAGE(PG8_SB(0, 0), b2, voffB);
;             PG8_BAR; PG8_WAIT_L(0); PG8_MMA(0, 1, At, B1); PG8_BAR;
;     ...
;             PG8_BAR; PG8_WAIT_L(0); PG8_MMA(0, 1, At, B1); PG8_BAR;
;             PG8_LDA(At, 1, 1); PG8_STAGE(PG8_SA(1, 0), a3, voffA);
;             PG8_BAR; PG8_WAIT_L(0); if (full) PG8_MMA(1, 0, At, B0); PG8_BAR; PG8_SCHED;
;             PG8_STAGE(PG8_SB(1, 1), b3 + hstepB, voffB);
;             PG8_WAIT_V(6); PG8_BAR; if (full) PG8_MMA(1, 1, At, B1); PG8_BAR;
	s_waitcnt lgkmcnt(0)
	s_setprio 1
	s_waitcnt lgkmcnt(0)
	v_mfma_f32_16x16x32_bf16 v[150:153], v[88:91], v[120:123], v[150:153]
	v_mfma_f32_16x16x32_bf16 v[154:157], v[112:115], v[120:123], v[154:157]
	v_mfma_f32_16x16x32_bf16 v[158:161], v[88:91], v[174:177], v[158:161]
	v_mfma_f32_16x16x32_bf16 v[162:165], v[112:115], v[174:177], v[162:165]
	v_mfma_f32_16x16x32_bf16 v[166:169], v[88:91], v[182:185], v[166:169]
	v_mfma_f32_16x16x32_bf16 v[170:173], v[112:115], v[182:185], v[170:173]
	v_mfma_f32_16x16x32_bf16 v[0:3], v[88:91], v[190:193], v[0:3]
	v_mfma_f32_16x16x32_bf16 v[4:7], v[112:115], v[190:193], v[4:7]
	v_mfma_f32_16x16x32_bf16 v[150:153], v[92:95], v[124:127], v[150:153]
	v_mfma_f32_16x16x32_bf16 v[154:157], v[116:119], v[124:127], v[154:157]
	v_mfma_f32_16x16x32_bf16 v[158:161], v[92:95], v[178:181], v[158:161]
	v_mfma_f32_16x16x32_bf16 v[162:165], v[116:119], v[178:181], v[162:165]
	v_mfma_f32_16x16x32_bf16 v[166:169], v[92:95], v[186:189], v[166:169]
	v_mfma_f32_16x16x32_bf16 v[170:173], v[116:119], v[186:189], v[170:173]
	v_mfma_f32_16x16x32_bf16 v[0:3], v[92:95], v[194:197], v[0:3]
	v_mfma_f32_16x16x32_bf16 v[4:7], v[116:119], v[194:197], v[4:7]
	s_setprio 0
	s_barrier
	s_add_u32 s76, s44, 0x10180
	s_addc_u32 s77, s45, 0
	s_add_i32 s45, s78, s54
	v_lshl_add_u64 v[88:89], s[76:77], 0, v[130:131]
	s_mov_b32 m0, s45
	s_add_i32 s44, s45, 0x2000
	global_load_lds_dwordx4 v[88:89], off
	v_lshl_add_u64 v[88:89], s[76:77], 0, v[134:135]
	s_mov_b32 m0, s44
	s_nop 0
	global_load_lds_dwordx4 v[88:89], off
	s_waitcnt vmcnt(6)
	s_barrier
	s_setprio 1
	v_mfma_f32_16x16x32_bf16 v[8:11], v[198:201], v[120:123], v[8:11]
	v_mfma_f32_16x16x32_bf16 v[12:15], v[206:209], v[120:123], v[12:15]
	v_mfma_f32_16x16x32_bf16 v[44:47], v[198:201], v[174:177], v[44:47]
	v_mfma_f32_16x16x32_bf16 v[88:91], v[206:209], v[174:177], v[100:103]
	v_mfma_f32_16x16x32_bf16 v[92:95], v[198:201], v[182:185], v[104:107]
	v_mfma_f32_16x16x32_bf16 v[100:103], v[206:209], v[182:185], v[108:111]
	v_mfma_f32_16x16x32_bf16 v[80:83], v[198:201], v[190:193], v[80:83]
	v_mfma_f32_16x16x32_bf16 v[84:87], v[206:209], v[190:193], v[84:87]
	v_mfma_f32_16x16x32_bf16 v[8:11], v[202:205], v[124:127], v[8:11]
	v_mfma_f32_16x16x32_bf16 v[12:15], v[210:213], v[124:127], v[12:15]
	v_mfma_f32_16x16x32_bf16 v[44:47], v[202:205], v[178:181], v[44:47]
	v_mfma_f32_16x16x32_bf16 v[88:91], v[210:213], v[178:181], v[88:91]
	v_mfma_f32_16x16x32_bf16 v[92:95], v[202:205], v[186:189], v[92:95]
	v_mfma_f32_16x16x32_bf16 v[100:103], v[210:213], v[186:189], v[100:103]
	v_mfma_f32_16x16x32_bf16 v[80:83], v[202:205], v[194:197], v[80:83]
	v_mfma_f32_16x16x32_bf16 v[84:87], v[210:213], v[194:197], v[84:87]
	s_setprio 0
	s_barrier
	ds_read_b128 v[104:107], v146
	ds_read_b128 v[108:111], v146 offset:1024
	ds_read_b128 v[112:115], v146 offset:2048
	ds_read_b128 v[116:119], v146 offset:3072
	s_add_u32 s42, s42, 0x40180
	s_addc_u32 s43, s43, 0
	s_mov_b32 m0, s74
	v_lshl_add_u64 v[142:143], s[42:43], 0, v[128:129]
	ds_read_b128 v[120:123], v147
	ds_read_b128 v[124:127], v147 offset:1024
	ds_read_b128 v[174:177], v147 offset:2048
	ds_read_b128 v[178:181], v147 offset:3072
	ds_read_b128 v[182:185], v147 offset:4096
	ds_read_b128 v[186:189], v147 offset:5120
	ds_read_b128 v[190:193], v147 offset:6144
	ds_read_b128 v[194:197], v147 offset:7168
	global_load_lds_dwordx4 v[142:143], off
	v_lshl_add_u64 v[142:143], s[42:43], 0, v[132:133]
	s_mov_b32 m0, s29
	s_nop 0
	global_load_lds_dwordx4 v[142:143], off
	s_waitcnt lgkmcnt(8)
	s_barrier
	s_waitcnt lgkmcnt(0)
	s_setprio 1
	s_waitcnt lgkmcnt(0)
	v_mfma_f32_16x16x32_bf16 v[48:51], v[104:107], v[120:123], v[48:51]
	v_mfma_f32_16x16x32_bf16 v[52:55], v[112:115], v[120:123], v[52:55]
	v_mfma_f32_16x16x32_bf16 v[56:59], v[104:107], v[174:177], v[56:59]
	v_mfma_f32_16x16x32_bf16 v[60:63], v[112:115], v[174:177], v[60:63]
	v_mfma_f32_16x16x32_bf16 v[64:67], v[104:107], v[182:185], v[64:67]
	v_mfma_f32_16x16x32_bf16 v[68:71], v[112:115], v[182:185], v[68:71]
	v_mfma_f32_16x16x32_bf16 v[72:75], v[104:107], v[190:193], v[72:75]
	v_mfma_f32_16x16x32_bf16 v[76:79], v[112:115], v[190:193], v[76:79]
	v_mfma_f32_16x16x32_bf16 v[48:51], v[108:111], v[124:127], v[48:51]
	v_mfma_f32_16x16x32_bf16 v[52:55], v[116:119], v[124:127], v[52:55]
	v_mfma_f32_16x16x32_bf16 v[56:59], v[108:111], v[178:181], v[56:59]
	v_mfma_f32_16x16x32_bf16 v[60:63], v[116:119], v[178:181], v[60:63]
	v_mfma_f32_16x16x32_bf16 v[64:67], v[108:111], v[186:189], v[64:67]
	v_mfma_f32_16x16x32_bf16 v[68:71], v[116:119], v[186:189], v[68:71]
	v_mfma_f32_16x16x32_bf16 v[72:75], v[108:111], v[194:197], v[72:75]
	v_mfma_f32_16x16x32_bf16 v[76:79], v[116:119], v[194:197], v[76:79]
	s_setprio 0
	s_barrier
	s_mov_b32 m0, s71
	v_lshl_add_u64 v[142:143], s[46:47], 0, v[130:131]
	ds_read_b128 v[198:201], v148
	ds_read_b128 v[202:205], v148 offset:1024
	ds_read_b128 v[206:209], v148 offset:2048
	ds_read_b128 v[210:213], v148 offset:3072
	global_load_lds_dwordx4 v[142:143], off
	v_lshl_add_u64 v[240:241], s[46:47], 0, v[134:135]
	s_mov_b32 m0, s31
	s_nop 0
	global_load_lds_dwordx4 v[240:241], off
	s_barrier
; #define PG8_STAGE(bufoff, gbase, voff) do { _Pragma("unroll") for (int _i = 0; _i < 2; ++_i) \
;         __builtin_amdgcn_global_load_lds((const unsigned*)((const char*)(gbase) + (voff)[_i]), (LAS unsigned*)(lds + (bufoff) + ldsw + _i * 8192), 16, 0, 0); } while (0)
; #define PG8_LDA(dst, b, h) do { _Pragma("unroll") for (int m = 0; m < 4; ++m) _Pragma("unroll") for (int k = 0; k < 2; ++k) dst[m][k] = *(const LAS bf16x8*)(lds + PG8_SA(b, h) + aoff + m * 2048 + k * 1024); } while (0)
; #define PG8_LDB(dst, b, h) do { _Pragma("unroll") for (int n = 0; n < 2; ++n) _Pragma("unroll") for (int k = 0; k < 2; ++k) dst[n][k] = *(const LAS bf16x8*)(lds + PG8_SB(b, h) + boff + n * 2048 + k * 1024); } while (0)
; #define PG8_MMA(ai, bj, At, Bt) do { __builtin_amdgcn_s_setprio(1); _Pragma("unroll") for (int m = 0; m < 4; ++m) _Pragma("unroll") for (int n = 0; n < 2; ++n) _Pragma("unroll") for (int k = 0; k < 2; ++k) \
;         acc[ai][bj][m][n] = __builtin_amdgcn_mfma_f32_16x16x32_bf16(Bt[n][k], At[m][k], acc[ai][bj][m][n], 0, 0, 0); __builtin_amdgcn_s_setprio(0); } while (0)
; #define PG8_WAIT_V(n) asm volatile("s_waitcnt vmcnt(" #n ")" ::: "memory")
; #define PG8_WAIT_L(n) asm volatile("s_waitcnt lgkmcnt(" #n ")" ::: "memory")
; #define PG8_BAR __builtin_amdgcn_s_barrier()
; #define PG8_SCHED __builtin_amdgcn_sched_barrier(0)
; template <class Epi>
; DI void gemm_phase(LAS unsigned char* lds, int wid, int K, int lda, int ldb, bool bperm, const Sched3& S, const Epi& E) {
;     ...
;             PG8_BAR; PG8_WAIT_L(0); PG8_MMA(0, 1, At, B1); PG8_BAR;
;             PG8_LDA(At, 0, 1); PG8_STAGE(PG8_SA(0, 0), a2, voffA);
;             PG8_BAR; PG8_WAIT_L(0); if (full) PG8_MMA(1, 0, At, B0); PG8_BAR; PG8_SCHED;
;             PG8_STAGE(PG8_SB(0, 1), b2 + hstepB, voffB);
;             PG8_WAIT_V(6); PG8_BAR; if (full) PG8_MMA(1, 1, At, B1); PG8_BAR;
;             PG8_LDB(B0, 1, 0); PG8_SCHED; PG8_LDA(At, 1, 0); PG8_STAGE(PG8_SA(0, 1), a2 + h2, voffA);
;             PG8_WAIT_L(8); PG8_BAR; PG8_WAIT_L(0); PG8_MMA(0, 0, At, B0); PG8_BAR; PG8_SCHED;
;             PG8_LDB(B1, 1, 1); PG8_STAGE(PG8_SB(1, 0), b3, voffB);
;             PG8_BAR; PG8_WAIT_L(0); PG8_MMA(0, 1, At, B1); PG8_BAR;
	s_waitcnt lgkmcnt(0)
	s_setprio 1
	s_waitcnt lgkmcnt(0)
	v_mfma_f32_16x16x32_bf16 v[96:99], v[198:201], v[120:123], v[96:99]
	v_mfma_f32_16x16x32_bf16 v[16:19], v[206:209], v[120:123], v[16:19]
	v_mfma_f32_16x16x32_bf16 v[20:23], v[198:201], v[174:177], v[20:23]
	v_mfma_f32_16x16x32_bf16 v[24:27], v[206:209], v[174:177], v[24:27]
	v_mfma_f32_16x16x32_bf16 v[28:31], v[198:201], v[182:185], v[28:31]
	v_mfma_f32_16x16x32_bf16 v[32:35], v[206:209], v[182:185], v[32:35]
	v_mfma_f32_16x16x32_bf16 v[36:39], v[198:201], v[190:193], v[36:39]
	v_mfma_f32_16x16x32_bf16 v[40:43], v[206:209], v[190:193], v[40:43]
	v_mfma_f32_16x16x32_bf16 v[96:99], v[202:205], v[124:127], v[96:99]
	v_mfma_f32_16x16x32_bf16 v[16:19], v[210:213], v[124:127], v[16:19]
	v_mfma_f32_16x16x32_bf16 v[20:23], v[202:205], v[178:181], v[20:23]
	v_mfma_f32_16x16x32_bf16 v[24:27], v[210:213], v[178:181], v[24:27]
	v_mfma_f32_16x16x32_bf16 v[28:31], v[202:205], v[186:189], v[28:31]
	v_mfma_f32_16x16x32_bf16 v[32:35], v[210:213], v[186:189], v[32:35]
	v_mfma_f32_16x16x32_bf16 v[36:39], v[202:205], v[194:197], v[36:39]
	v_mfma_f32_16x16x32_bf16 v[40:43], v[210:213], v[194:197], v[40:43]
	s_setprio 0
	s_mov_b32 m0, s55
	v_lshl_add_u64 v[252:253], s[48:49], 0, v[128:129]
	s_barrier
	ds_read_b128 v[120:123], v147 offset:16384
	ds_read_b128 v[124:127], v147 offset:17408
	ds_read_b128 v[174:177], v147 offset:18432
	ds_read_b128 v[178:181], v147 offset:19456
	ds_read_b128 v[182:185], v147 offset:20480
	ds_read_b128 v[186:189], v147 offset:21504
	ds_read_b128 v[190:193], v147 offset:22528
	ds_read_b128 v[194:197], v147 offset:23552
	global_load_lds_dwordx4 v[252:253], off
	v_lshl_add_u64 v[222:223], s[48:49], 0, v[132:133]
	s_mov_b32 m0, s56
	s_nop 0
	global_load_lds_dwordx4 v[222:223], off
	s_barrier
	s_waitcnt lgkmcnt(0)
	s_setprio 1
	s_waitcnt lgkmcnt(0)
	v_mfma_f32_16x16x32_bf16 v[150:153], v[104:107], v[120:123], v[150:153]
	v_mfma_f32_16x16x32_bf16 v[154:157], v[112:115], v[120:123], v[154:157]
	v_mfma_f32_16x16x32_bf16 v[158:161], v[104:107], v[174:177], v[158:161]
	v_mfma_f32_16x16x32_bf16 v[162:165], v[112:115], v[174:177], v[162:165]
	v_mfma_f32_16x16x32_bf16 v[166:169], v[104:107], v[182:185], v[166:169]
	v_mfma_f32_16x16x32_bf16 v[170:173], v[112:115], v[182:185], v[170:173]
	v_mfma_f32_16x16x32_bf16 v[0:3], v[104:107], v[190:193], v[0:3]
	v_mfma_f32_16x16x32_bf16 v[4:7], v[112:115], v[190:193], v[4:7]
	v_mfma_f32_16x16x32_bf16 v[150:153], v[108:111], v[124:127], v[150:153]
	v_mfma_f32_16x16x32_bf16 v[154:157], v[116:119], v[124:127], v[154:157]
	v_mfma_f32_16x16x32_bf16 v[158:161], v[108:111], v[178:181], v[158:161]
	v_mfma_f32_16x16x32_bf16 v[162:165], v[116:119], v[178:181], v[162:165]
	v_mfma_f32_16x16x32_bf16 v[166:169], v[108:111], v[186:189], v[166:169]
	v_mfma_f32_16x16x32_bf16 v[170:173], v[116:119], v[186:189], v[170:173]
	v_mfma_f32_16x16x32_bf16 v[0:3], v[108:111], v[194:197], v[0:3]
	v_mfma_f32_16x16x32_bf16 v[214:217], v[116:119], v[194:197], v[4:7]
	s_setprio 0
	s_barrier
	s_add_u32 s42, s46, 0x10000
	s_addc_u32 s43, s47, 0
	s_mov_b32 m0, s72
	v_lshl_add_u64 v[4:5], s[42:43], 0, v[130:131]
	global_load_lds_dwordx4 v[4:5], off
	v_lshl_add_u64 v[4:5], s[42:43], 0, v[134:135]
	s_mov_b32 m0, s70
	s_nop 0
	global_load_lds_dwordx4 v[4:5], off
	s_waitcnt vmcnt(6)
	s_barrier
	s_setprio 1
	v_mfma_f32_16x16x32_bf16 v[4:7], v[198:201], v[120:123], v[8:11]
	v_mfma_f32_16x16x32_bf16 v[8:11], v[202:205], v[124:127], v[4:7]
	v_mfma_f32_16x16x32_bf16 v[4:7], v[206:209], v[120:123], v[12:15]
	v_mfma_f32_16x16x32_bf16 v[12:15], v[210:213], v[124:127], v[4:7]
	v_mfma_f32_16x16x32_bf16 v[4:7], v[198:201], v[174:177], v[44:47]
	v_mfma_f32_16x16x32_bf16 v[44:47], v[202:205], v[178:181], v[4:7]
	v_mfma_f32_16x16x32_bf16 v[4:7], v[206:209], v[174:177], v[88:91]
	v_mfma_f32_16x16x32_bf16 v[174:177], v[210:213], v[178:181], v[4:7]
	v_mfma_f32_16x16x32_bf16 v[4:7], v[198:201], v[182:185], v[92:95]
	v_mfma_f32_16x16x32_bf16 v[178:181], v[202:205], v[186:189], v[4:7]
	v_mfma_f32_16x16x32_bf16 v[4:7], v[206:209], v[182:185], v[100:103]
	v_mfma_f32_16x16x32_bf16 v[182:185], v[210:213], v[186:189], v[4:7]
	v_mfma_f32_16x16x32_bf16 v[4:7], v[198:201], v[190:193], v[80:83]
	v_mfma_f32_16x16x32_bf16 v[186:189], v[202:205], v[194:197], v[4:7]
	v_mfma_f32_16x16x32_bf16 v[4:7], v[206:209], v[190:193], v[84:87]
	v_mfma_f32_16x16x32_bf16 v[190:193], v[210:213], v[194:197], v[4:7]
	s_setprio 0
	s_barrier
	s_nop 4
	ds_read_b128 v[4:7], v149
	ds_read_b128 v[88:91], v149 offset:1024
	ds_read_b128 v[92:95], v149 offset:2048
	ds_read_b128 v[194:197], v149 offset:3072
	s_add_u32 s42, s48, 0x40000
	s_addc_u32 s43, s49, 0
	s_mov_b32 m0, s57
	v_lshl_add_u64 v[100:101], s[42:43], 0, v[128:129]
	ds_read_b128 v[80:83], v147 offset:32768
	ds_read_b128 v[84:87], v147 offset:33792
	ds_read_b128 v[108:111], v147 offset:34816
	ds_read_b128 v[198:201], v147 offset:35840
	ds_read_b128 v[202:205], v147 offset:36864
	ds_read_b128 v[206:209], v147 offset:37888
	ds_read_b128 v[210:213], v147 offset:38912
	ds_read_b128 v[218:221], v147 offset:39936
	global_load_lds_dwordx4 v[100:101], off
	v_lshl_add_u64 v[100:101], s[42:43], 0, v[132:133]
	s_mov_b32 m0, s58
	s_nop 0
	global_load_lds_dwordx4 v[100:101], off
	s_waitcnt lgkmcnt(8)
	s_barrier
; #define PG8_STAGE(bufoff, gbase, voff) do { _Pragma("unroll") for (int _i = 0; _i < 2; ++_i) \
;         __builtin_amdgcn_global_load_lds((const unsigned*)((const char*)(gbase) + (voff)[_i]), (LAS unsigned*)(lds + (bufoff) + ldsw + _i * 8192), 16, 0, 0); } while (0)
; #define PG8_LDA(dst, b, h) do { _Pragma("unroll") for (int m = 0; m < 4; ++m) _Pragma("unroll") for (int k = 0; k < 2; ++k) dst[m][k] = *(const LAS bf16x8*)(lds + PG8_SA(b, h) + aoff + m * 2048 + k * 1024); } while (0)
; #define PG8_LDB(dst, b, h) do { _Pragma("unroll") for (int n = 0; n < 2; ++n) _Pragma("unroll") for (int k = 0; k < 2; ++k) dst[n][k] = *(const LAS bf16x8*)(lds + PG8_SB(b, h) + boff + n * 2048 + k * 1024); } while (0)
; #define PG8_MMA(ai, bj, At, Bt) do { __builtin_amdgcn_s_setprio(1); _Pragma("unroll") for (int m = 0; m < 4; ++m) _Pragma("unroll") for (int n = 0; n < 2; ++n) _Pragma("unroll") for (int k = 0; k < 2; ++k) \
;         acc[ai][bj][m][n] = __builtin_amdgcn_mfma_f32_16x16x32_bf16(Bt[n][k], At[m][k], acc[ai][bj][m][n], 0, 0, 0); __builtin_amdgcn_s_setprio(0); } while (0)
; #define PG8_WAIT_V(n) asm volatile("s_waitcnt vmcnt(" #n ")" ::: "memory")
; #define PG8_WAIT_L(n) asm volatile("s_waitcnt lgkmcnt(" #n ")" ::: "memory")
; #define PG8_BAR __builtin_amdgcn_s_barrier()
; #define PG8_SCHED __builtin_amdgcn_sched_barrier(0)
; template <class Epi>
; DI void gemm_phase(LAS unsigned char* lds, int wid, int K, int lda, int ldb, bool bperm, const Sched3& S, const Epi& E) {
;     ...
;             PG8_WAIT_L(8); PG8_BAR; PG8_WAIT_L(0); PG8_MMA(0, 0, At, B0); PG8_BAR; PG8_SCHED;
;             PG8_LDB(B1, 1, 1); PG8_STAGE(PG8_SB(1, 0), b3, voffB);
;             PG8_BAR; PG8_WAIT_L(0); PG8_MMA(0, 1, At, B1); PG8_BAR;
;             PG8_LDA(At, 1, 1); PG8_STAGE(PG8_SA(1, 0), a3, voffA);
;             PG8_BAR; PG8_WAIT_L(0); if (full) PG8_MMA(1, 0, At, B0); PG8_BAR; PG8_SCHED;
;             PG8_STAGE(PG8_SB(1, 1), b3 + hstepB, voffB);
;             PG8_WAIT_V(6); PG8_BAR; if (full) PG8_MMA(1, 1, At, B1); PG8_BAR;
	s_waitcnt lgkmcnt(0)
	s_setprio 1
	s_waitcnt lgkmcnt(0)
	v_mfma_f32_16x16x32_bf16 v[48:51], v[4:7], v[80:83], v[48:51]
	v_mfma_f32_16x16x32_bf16 v[120:123], v[88:91], v[84:87], v[48:51]
	v_mfma_f32_16x16x32_bf16 v[48:51], v[92:95], v[80:83], v[52:55]
	v_mfma_f32_16x16x32_bf16 v[124:127], v[194:197], v[84:87], v[48:51]
	v_mfma_f32_16x16x32_bf16 v[48:51], v[4:7], v[108:111], v[56:59]
	v_mfma_f32_16x16x32_bf16 v[112:115], v[88:91], v[198:201], v[48:51]
	v_mfma_f32_16x16x32_bf16 v[48:51], v[92:95], v[108:111], v[60:63]
	v_mfma_f32_16x16x32_bf16 v[116:119], v[194:197], v[198:201], v[48:51]
	v_mfma_f32_16x16x32_bf16 v[48:51], v[4:7], v[202:205], v[64:67]
	v_mfma_f32_16x16x32_bf16 v[100:103], v[88:91], v[206:209], v[48:51]
	v_mfma_f32_16x16x32_bf16 v[48:51], v[92:95], v[202:205], v[68:71]
	v_mfma_f32_16x16x32_bf16 v[104:107], v[194:197], v[206:209], v[48:51]
	v_mfma_f32_16x16x32_bf16 v[48:51], v[4:7], v[210:213], v[72:75]
	v_mfma_f32_16x16x32_bf16 v[68:71], v[88:91], v[218:221], v[48:51]
	v_mfma_f32_16x16x32_bf16 v[48:51], v[92:95], v[210:213], v[76:79]
	v_mfma_f32_16x16x32_bf16 v[64:67], v[194:197], v[218:221], v[48:51]
	s_setprio 0
	s_barrier
	s_mov_b32 m0, s75
	s_nop 3
	v_lshl_add_u64 v[48:49], v[142:143], 0, s[12:13]
	ds_read_b128 v[224:227], v236
	ds_read_b128 v[228:231], v236 offset:1024
	ds_read_b128 v[232:235], v236 offset:2048
	ds_read_b128 v[236:239], v236 offset:3072
	global_load_lds_dwordx4 v[48:49], off
	v_lshl_add_u64 v[48:49], v[240:241], 0, s[12:13]
	s_mov_b32 m0, s73
	s_nop 0
	global_load_lds_dwordx4 v[48:49], off
	s_barrier
	s_waitcnt lgkmcnt(0)
	s_setprio 1
	s_waitcnt lgkmcnt(0)
	v_mfma_f32_16x16x32_bf16 v[16:19], v[232:235], v[80:83], v[16:19]
	v_mfma_f32_16x16x32_bf16 v[244:247], v[236:239], v[84:87], v[16:19]
	v_mfma_f32_16x16x32_bf16 v[16:19], v[224:227], v[108:111], v[20:23]
	v_mfma_f32_16x16x32_bf16 v[248:251], v[228:231], v[198:201], v[16:19]
	v_mfma_f32_16x16x32_bf16 v[16:19], v[232:235], v[108:111], v[24:27]
	v_mfma_f32_16x16x32_bf16 v[198:201], v[236:239], v[198:201], v[16:19]
	v_mfma_f32_16x16x32_bf16 v[16:19], v[224:227], v[202:205], v[28:31]
	v_mfma_f32_16x16x32_bf16 v[108:111], v[228:231], v[206:209], v[16:19]
	v_mfma_f32_16x16x32_bf16 v[16:19], v[232:235], v[202:205], v[32:35]
	v_mfma_f32_16x16x32_bf16 v[48:51], v[224:227], v[80:83], v[96:99]
	v_mfma_f32_16x16x32_bf16 v[96:99], v[236:239], v[206:209], v[16:19]
	v_mfma_f32_16x16x32_bf16 v[16:19], v[224:227], v[210:213], v[36:39]
	v_mfma_f32_16x16x32_bf16 v[76:79], v[228:231], v[218:221], v[16:19]
	v_mfma_f32_16x16x32_bf16 v[16:19], v[232:235], v[210:213], v[40:43]
	v_mfma_f32_16x16x32_bf16 v[240:243], v[228:231], v[84:87], v[48:51]
	v_mfma_f32_16x16x32_bf16 v[72:75], v[236:239], v[218:221], v[16:19]
	s_setprio 0
	s_mov_b32 m0, s59
	v_lshl_add_u64 v[24:25], v[252:253], 0, s[12:13]
	s_barrier
	s_nop 1
	ds_read_b128 v[16:19], v147 offset:49152
	ds_read_b128 v[20:23], v147 offset:50176
	ds_read_b128 v[32:35], v147 offset:51200
	ds_read_b128 v[36:39], v147 offset:52224
	ds_read_b128 v[40:43], v147 offset:53248
	ds_read_b128 v[202:205], v147 offset:54272
	ds_read_b128 v[206:209], v147 offset:55296
	ds_read_b128 v[210:213], v147 offset:56320
	global_load_lds_dwordx4 v[24:25], off
	v_lshl_add_u64 v[24:25], v[222:223], 0, s[12:13]
	s_mov_b32 m0, s60
	s_nop 0
	global_load_lds_dwordx4 v[24:25], off
	s_barrier
	s_waitcnt lgkmcnt(0)
	s_setprio 1
	s_waitcnt lgkmcnt(0)
	v_mfma_f32_16x16x32_bf16 v[24:27], v[4:7], v[16:19], v[150:153]
	v_mfma_f32_16x16x32_bf16 v[84:87], v[88:91], v[20:23], v[24:27]
	v_mfma_f32_16x16x32_bf16 v[24:27], v[92:95], v[16:19], v[154:157]
	v_mfma_f32_16x16x32_bf16 v[80:83], v[194:197], v[20:23], v[24:27]
	v_mfma_f32_16x16x32_bf16 v[24:27], v[4:7], v[32:35], v[158:161]
	v_mfma_f32_16x16x32_bf16 v[52:55], v[88:91], v[36:39], v[24:27]
	v_mfma_f32_16x16x32_bf16 v[24:27], v[92:95], v[32:35], v[162:165]
	v_mfma_f32_16x16x32_bf16 v[48:51], v[194:197], v[36:39], v[24:27]
	v_mfma_f32_16x16x32_bf16 v[24:27], v[4:7], v[40:43], v[166:169]
	v_mfma_f32_16x16x32_bf16 v[0:3], v[4:7], v[206:209], v[0:3]
	v_mfma_f32_16x16x32_bf16 v[28:31], v[88:91], v[202:205], v[24:27]
	v_mfma_f32_16x16x32_bf16 v[24:27], v[92:95], v[40:43], v[170:173]
	v_mfma_f32_16x16x32_bf16 v[4:7], v[88:91], v[210:213], v[0:3]
	v_mfma_f32_16x16x32_bf16 v[0:3], v[92:95], v[206:209], v[214:217]
	v_mfma_f32_16x16x32_bf16 v[24:27], v[194:197], v[202:205], v[24:27]
	v_mfma_f32_16x16x32_bf16 v[0:3], v[194:197], v[210:213], v[0:3]
	s_setprio 0
	s_barrier
	s_add_u32 s42, s46, 0x10080
	s_addc_u32 s43, s47, 0
	s_mov_b32 m0, s45
	v_lshl_add_u64 v[56:57], s[42:43], 0, v[130:131]
	global_load_lds_dwordx4 v[56:57], off
	v_lshl_add_u64 v[56:57], s[42:43], 0, v[134:135]
	s_mov_b32 m0, s44
	s_nop 0
	global_load_lds_dwordx4 v[56:57], off
	s_waitcnt vmcnt(6)
	s_barrier
	s_setprio 1
	v_mfma_f32_16x16x32_bf16 v[8:11], v[224:227], v[16:19], v[8:11]
	v_mfma_f32_16x16x32_bf16 v[92:95], v[228:231], v[20:23], v[8:11]
	v_mfma_f32_16x16x32_bf16 v[8:11], v[232:235], v[16:19], v[12:15]
	v_mfma_f32_16x16x32_bf16 v[88:91], v[236:239], v[20:23], v[8:11]
	v_mfma_f32_16x16x32_bf16 v[8:11], v[224:227], v[32:35], v[44:47]
	v_mfma_f32_16x16x32_bf16 v[60:63], v[228:231], v[36:39], v[8:11]
	v_mfma_f32_16x16x32_bf16 v[8:11], v[232:235], v[32:35], v[174:177]
	v_mfma_f32_16x16x32_bf16 v[56:59], v[236:239], v[36:39], v[8:11]
	v_mfma_f32_16x16x32_bf16 v[8:11], v[224:227], v[40:43], v[178:181]
	v_mfma_f32_16x16x32_bf16 v[44:47], v[228:231], v[202:205], v[8:11]
	v_mfma_f32_16x16x32_bf16 v[8:11], v[232:235], v[40:43], v[182:185]
	v_mfma_f32_16x16x32_bf16 v[36:39], v[236:239], v[202:205], v[8:11]
	v_mfma_f32_16x16x32_bf16 v[8:11], v[224:227], v[206:209], v[186:189]
	v_mfma_f32_16x16x32_bf16 v[12:15], v[228:231], v[210:213], v[8:11]
	v_mfma_f32_16x16x32_bf16 v[8:11], v[232:235], v[206:209], v[190:193]
	v_mfma_f32_16x16x32_bf16 v[8:11], v[236:239], v[210:213], v[8:11]
	s_setprio 0
	s_lshl_b32 s42, s41, 8
	s_ashr_i32 s43, s42, 31
	v_lshl_add_u64 v[16:17], s[42:43], 2, v[136:137]
	s_barrier
; #define ROWS8 _Pragma("unroll") for (int ai = 0; ai < 2; ++ai) _Pragma("unroll") for (int m = 0; m < 4; ++m) if (ai == 0 || !hf)
; #define COLS4 _Pragma("unroll") for (int bj = 0; bj < 2; ++bj) _Pragma("unroll") for (int n = 0; n < 2; ++n)
; #define PK8(v0, v1) ({ const u32x2 h0_ = pk4(v0), h1_ = pk4(v1); (u32x4){h0_.x, h0_.y, h1_.x, h1_.y}; })
;     DI void operator()(const Acc& acc, const Unit& u, int wr, int wc, int fr, int fq) const {
;     ...
;         } else if constexpr (PH == 3) {
;             const int lc = wc * 32 + 8 * fq;
;             f32x4 sc[2][2];
;             COLS4 sc[bj][n] = *(const f32x4*)(p.pool_scale + u.pn * 256 + lc + bj * HALF + n * 4);
;             ROWS8 { const int r = row0 + ai * HALF + m * 16; bf16_t* dst = WSB(OFF_CAT) + (size_t)r * 2048 + 1024 + u.pn * 256 + lc;
; #pragma unroll
;                 for (int bj = 0; bj < 2; ++bj) *(u32x4*)(dst + bj * HALF) = PK8(acc[ai][bj][m][0] * sc[bj][0], acc[ai][bj][m][1] * sc[bj][1]); }
	global_load_dwordx4 v[40:43], v[16:17], off
	global_load_dwordx4 v[32:35], v[16:17], off offset:16
	global_load_dwordx4 v[20:23], v[16:17], off offset:512
	s_nop 0
	global_load_dwordx4 v[16:19], v[16:17], off offset:528
	v_lshl_add_u32 v150, s40, 8, v144
	v_ashrrev_i32_e32 v151, 31, v150
	v_or_b32_e32 v142, 16, v150
	v_lshlrev_b64 v[154:155], 12, v[150:151]
	s_lshl_b64 s[40:41], s[42:43], 1
	v_ashrrev_i32_e32 v143, 31, v142
	v_lshl_add_u64 v[154:155], s[10:11], 0, v[154:155]
	v_or_b32_e32 v152, 32, v150
	v_lshlrev_b64 v[142:143], 12, v[142:143]
	v_lshl_add_u64 v[154:155], v[154:155], 0, s[40:41]
	v_ashrrev_i32_e32 v153, 31, v152
	v_lshl_add_u64 v[156:157], s[10:11], 0, v[142:143]
	v_lshl_add_u64 v[142:143], v[154:155], 0, v[140:141]
	v_lshlrev_b64 v[152:153], 12, v[152:153]
	v_lshl_add_u64 v[154:155], v[156:157], 0, s[40:41]
	v_add_co_u32_e32 v158, vcc, s65, v142
	v_lshl_add_u64 v[152:153], s[10:11], 0, v[152:153]
	s_nop 0
	v_addc_co_u32_e32 v159, vcc, 0, v143, vcc
	v_lshl_add_u64 v[154:155], v[154:155], 0, v[140:141]
	v_lshl_add_u64 v[152:153], v[152:153], 0, s[40:41]
	v_lshl_add_u64 v[160:161], v[154:155], 0, s[18:19]
	v_add_co_u32_e32 v154, vcc, s65, v154
	v_lshl_add_u64 v[152:153], v[152:153], 0, v[140:141]
	s_nop 0
	v_addc_co_u32_e32 v155, vcc, 0, v155, vcc
	v_lshl_add_u64 v[162:163], v[152:153], 0, s[18:19]
	v_add_co_u32_e32 v152, vcc, s65, v152
	v_lshl_add_u64 v[156:157], v[142:143], 0, s[18:19]
	s_nop 0
	v_addc_co_u32_e32 v153, vcc, 0, v153, vcc
	s_add_i32 s62, s62, s7
	s_mov_b64 s[44:45], s[38:39]
	s_mov_b64 s[42:43], s[36:37]
	s_waitcnt vmcnt(0)
	v_mul_f32_e32 v122, v122, v42
	v_mul_f32_e32 v123, v123, v43
	v_mul_f32_e32 v120, v120, v40
	v_mul_f32_e32 v121, v121, v41
	v_mul_f32_e32 v126, v126, v34
	v_mul_f32_e32 v127, v127, v35
	v_mul_f32_e32 v124, v124, v32
	v_mul_f32_e32 v125, v125, v33
	v_mul_f32_e32 v164, v242, v22
	v_mul_f32_e32 v165, v243, v23
	v_mul_f32_e32 v166, v240, v20
	v_mul_f32_e32 v167, v241, v21
	v_mul_f32_e32 v168, v246, v18
	v_mul_f32_e32 v169, v247, v19
	v_mul_f32_e32 v170, v244, v16
	v_mul_f32_e32 v171, v245, v17
	v_mul_f32_e32 v114, v114, v42
	v_mul_f32_e32 v115, v115, v43
	v_mul_f32_e32 v112, v112, v40
	v_mul_f32_e32 v113, v113, v41
	v_mul_f32_e32 v118, v118, v34
	v_mul_f32_e32 v119, v119, v35
	v_mul_f32_e32 v116, v116, v32
	v_mul_f32_e32 v117, v117, v33
	v_mul_f32_e32 v172, v250, v22
	v_mul_f32_e32 v173, v251, v23
	v_mul_f32_e32 v174, v248, v20
	v_mul_f32_e32 v175, v249, v21
	v_mul_f32_e32 v176, v200, v18
	v_mul_f32_e32 v177, v201, v19
	v_mul_f32_e32 v178, v198, v16
	v_mul_f32_e32 v179, v199, v17
	v_mul_f32_e32 v180, v102, v42
	v_mul_f32_e32 v181, v103, v43
	v_mul_f32_e32 v182, v100, v40
	v_mul_f32_e32 v183, v101, v41
	v_mul_f32_e32 v184, v106, v34
	v_mul_f32_e32 v185, v107, v35
	v_mul_f32_e32 v186, v104, v32
	v_mul_f32_e32 v187, v105, v33
	v_cvt_pk_bf16_f32 v100, v120, v121
	v_cvt_pk_bf16_f32 v101, v122, v123
	v_cvt_pk_bf16_f32 v102, v124, v125
	v_cvt_pk_bf16_f32 v103, v126, v127
	v_cvt_pk_bf16_f32 v104, v166, v167
	v_cvt_pk_bf16_f32 v105, v164, v165
	v_cvt_pk_bf16_f32 v106, v170, v171
	v_cvt_pk_bf16_f32 v107, v168, v169
	v_cvt_pk_bf16_f32 v112, v112, v113
	v_cvt_pk_bf16_f32 v113, v114, v115
	v_cvt_pk_bf16_f32 v114, v116, v117
	v_cvt_pk_bf16_f32 v115, v118, v119
	v_cvt_pk_bf16_f32 v116, v174, v175
	v_cvt_pk_bf16_f32 v117, v172, v173
	v_cvt_pk_bf16_f32 v118, v178, v179
	v_cvt_pk_bf16_f32 v119, v176, v177
	v_cvt_pk_bf16_f32 v120, v182, v183
	v_cvt_pk_bf16_f32 v121, v180, v181
	v_cvt_pk_bf16_f32 v122, v186, v187
	v_cvt_pk_bf16_f32 v123, v184, v185
	global_store_dwordx4 v[158:159], v[100:103], off offset:2048
	global_store_dwordx4 v[156:157], v[104:107], off offset:256
	global_store_dwordx4 v[154:155], v[112:115], off offset:2048
	global_store_dwordx4 v[160:161], v[116:119], off offset:256
	global_store_dwordx4 v[152:153], v[120:123], off offset:2048
	v_mul_f32_e32 v102, v110, v22
	v_mul_f32_e32 v103, v111, v23
	v_mul_f32_e32 v100, v108, v20
	v_mul_f32_e32 v101, v109, v21
	v_mul_f32_e32 v96, v96, v16
	v_mul_f32_e32 v97, v97, v17
	v_cvt_pk_bf16_f32 v100, v100, v101
	v_cvt_pk_bf16_f32 v101, v102, v103
	v_cvt_pk_bf16_f32 v102, v96, v97
	v_or_b32_e32 v96, 48, v150
	v_ashrrev_i32_e32 v97, 31, v96
	v_lshlrev_b64 v[96:97], 12, v[96:97]
	v_lshl_add_u64 v[96:97], s[10:11], 0, v[96:97]
	v_lshl_add_u64 v[96:97], v[96:97], 0, s[40:41]
	v_lshl_add_u64 v[96:97], v[96:97], 0, v[140:141]
	v_mul_f32_e32 v70, v70, v42
	v_mul_f32_e32 v71, v71, v43
	v_mul_f32_e32 v68, v68, v40
	v_mul_f32_e32 v69, v69, v41
	v_mul_f32_e32 v64, v64, v32
	v_mul_f32_e32 v65, v65, v33
	v_cvt_pk_bf16_f32 v68, v68, v69
	v_cvt_pk_bf16_f32 v69, v70, v71
	v_mul_f32_e32 v66, v66, v34
	v_mul_f32_e32 v67, v67, v35
	v_cvt_pk_bf16_f32 v70, v64, v65
; #define ROWS8 _Pragma("unroll") for (int ai = 0; ai < 2; ++ai) _Pragma("unroll") for (int m = 0; m < 4; ++m) if (ai == 0 || !hf)
; #define COLS4 _Pragma("unroll") for (int bj = 0; bj < 2; ++bj) _Pragma("unroll") for (int n = 0; n < 2; ++n)
; #define PK8(v0, v1) ({ const u32x2 h0_ = pk4(v0), h1_ = pk4(v1); (u32x4){h0_.x, h0_.y, h1_.x, h1_.y}; })
;     DI void operator()(const Acc& acc, const Unit& u, int wr, int wc, int fr, int fq) const {
;     ...
;         } else if constexpr (PH == 3) {
;             const int lc = wc * 32 + 8 * fq;
;             f32x4 sc[2][2];
;             COLS4 sc[bj][n] = *(const f32x4*)(p.pool_scale + u.pn * 256 + lc + bj * HALF + n * 4);
;             ROWS8 { const int r = row0 + ai * HALF + m * 16; bf16_t* dst = WSB(OFF_CAT) + (size_t)r * 2048 + 1024 + u.pn * 256 + lc;
; #pragma unroll
;                 for (int bj = 0; bj < 2; ++bj) *(u32x4*)(dst + bj * HALF) = PK8(acc[ai][bj][m][0] * sc[bj][0], acc[ai][bj][m][1] * sc[bj][1]); }
	v_add_co_u32_e32 v64, vcc, s65, v96
	v_cvt_pk_bf16_f32 v71, v66, v67
	s_nop 0
	v_addc_co_u32_e32 v65, vcc, 0, v97, vcc
	global_store_dwordx4 v[64:65], v[68:71], off offset:2048
	v_mul_f32_e32 v66, v78, v22
	v_mul_f32_e32 v67, v79, v23
	v_mul_f32_e32 v64, v76, v20
	v_mul_f32_e32 v65, v77, v21
	v_mul_f32_e32 v98, v98, v18
	v_mul_f32_e32 v99, v99, v19
	v_cvt_pk_bf16_f32 v64, v64, v65
	v_cvt_pk_bf16_f32 v65, v66, v67
	v_mul_f32_e32 v68, v74, v18
	v_mul_f32_e32 v69, v75, v19
	v_mul_f32_e32 v66, v72, v16
	v_mul_f32_e32 v67, v73, v17
	v_cvt_pk_bf16_f32 v103, v98, v99
	v_lshl_add_u64 v[98:99], v[96:97], 0, s[18:19]
	v_cvt_pk_bf16_f32 v66, v66, v67
	v_cvt_pk_bf16_f32 v67, v68, v69
	global_store_dwordx4 v[98:99], v[64:67], off offset:256
	v_mul_f32_e32 v70, v82, v34
	v_mul_f32_e32 v71, v83, v35
	v_mul_f32_e32 v54, v54, v42
	v_mul_f32_e32 v55, v55, v43
	v_mul_f32_e32 v66, v86, v42
	v_mul_f32_e32 v67, v87, v43
	v_mul_f32_e32 v64, v84, v40
	v_mul_f32_e32 v65, v85, v41
	v_mul_f32_e32 v52, v52, v40
	v_mul_f32_e32 v53, v53, v41
	v_cvt_pk_bf16_f32 v64, v64, v65
	v_cvt_pk_bf16_f32 v65, v66, v67
	v_mul_f32_e32 v66, v80, v32
	v_mul_f32_e32 v67, v81, v33
	v_mul_f32_e32 v48, v48, v32
	v_mul_f32_e32 v49, v49, v33
	v_cvt_pk_bf16_f32 v66, v66, v67
	v_cvt_pk_bf16_f32 v67, v70, v71
	v_add_co_u32_e32 v70, vcc, s66, v142
	v_cvt_pk_bf16_f32 v52, v52, v53
	s_nop 0
	v_addc_co_u32_e32 v71, vcc, 0, v143, vcc
	v_cvt_pk_bf16_f32 v53, v54, v55
	v_cvt_pk_bf16_f32 v54, v48, v49
	v_add_co_u32_e32 v48, vcc, s67, v142
	v_mul_f32_e32 v30, v30, v42
	v_mul_f32_e32 v31, v31, v43
	s_nop 0
	v_addc_co_u32_e32 v49, vcc, 0, v143, vcc
	v_mul_f32_e32 v28, v28, v40
	v_mul_f32_e32 v29, v29, v41
	v_mul_f32_e32 v24, v24, v32
	v_mul_f32_e32 v25, v25, v33
	v_mul_f32_e32 v50, v50, v34
	v_mul_f32_e32 v51, v51, v35
	v_cvt_pk_bf16_f32 v28, v28, v29
	v_cvt_pk_bf16_f32 v29, v30, v31
	v_cvt_pk_bf16_f32 v30, v24, v25
	v_add_co_u32_e32 v24, vcc, s68, v142
	global_store_dwordx4 v[70:71], v[64:67], off offset:2048
	v_cvt_pk_bf16_f32 v55, v50, v51
	v_mul_f32_e32 v26, v26, v34
	v_mul_f32_e32 v27, v27, v35
	v_mul_f32_e32 v66, v94, v22
	v_mul_f32_e32 v67, v95, v23
	v_mul_f32_e32 v64, v92, v20
	v_mul_f32_e32 v65, v93, v21
	v_addc_co_u32_e32 v25, vcc, 0, v143, vcc
	v_mul_f32_e32 v6, v6, v42
	v_mul_f32_e32 v7, v7, v43
	v_mul_f32_e32 v4, v4, v40
	v_mul_f32_e32 v5, v5, v41
	v_mul_f32_e32 v0, v0, v32
	v_mul_f32_e32 v1, v1, v33
	v_cvt_pk_bf16_f32 v64, v64, v65
	v_cvt_pk_bf16_f32 v65, v66, v67
	v_mul_f32_e32 v70, v90, v18
	v_mul_f32_e32 v71, v91, v19
	v_mul_f32_e32 v66, v88, v16
	v_mul_f32_e32 v67, v89, v17
	global_store_dwordx4 v[48:49], v[52:55], off offset:2048
	v_mul_f32_e32 v50, v62, v22
	v_mul_f32_e32 v51, v63, v23
	v_mul_f32_e32 v48, v60, v20
	v_mul_f32_e32 v49, v61, v21
	v_cvt_pk_bf16_f32 v31, v26, v27
	v_cvt_pk_bf16_f32 v4, v4, v5
	v_cvt_pk_bf16_f32 v5, v6, v7
	v_mul_f32_e32 v2, v2, v34
	v_mul_f32_e32 v3, v3, v35
	v_cvt_pk_bf16_f32 v6, v0, v1
	v_add_co_u32_e32 v0, vcc, s69, v142
	v_lshl_add_u64 v[68:69], v[142:143], 0, s[20:21]
	v_cvt_pk_bf16_f32 v66, v66, v67
	v_cvt_pk_bf16_f32 v67, v70, v71
	v_cvt_pk_bf16_f32 v48, v48, v49
	v_cvt_pk_bf16_f32 v49, v50, v51
	v_mul_f32_e32 v52, v58, v18
	v_mul_f32_e32 v53, v59, v19
	v_mul_f32_e32 v50, v56, v16
	v_mul_f32_e32 v51, v57, v17
	global_store_dwordx4 v[24:25], v[28:31], off offset:2048
	v_mul_f32_e32 v26, v46, v22
	v_mul_f32_e32 v27, v47, v23
	v_mul_f32_e32 v24, v44, v20
	v_mul_f32_e32 v25, v45, v21
	v_cvt_pk_bf16_f32 v7, v2, v3
	v_addc_co_u32_e32 v1, vcc, 0, v143, vcc
	global_store_dwordx4 v[68:69], v[64:67], off offset:256
	v_cvt_pk_bf16_f32 v50, v50, v51
	v_cvt_pk_bf16_f32 v51, v52, v53
	v_lshl_add_u64 v[64:65], v[142:143], 0, s[22:23]
	v_cvt_pk_bf16_f32 v24, v24, v25
	v_cvt_pk_bf16_f32 v25, v26, v27
	v_mul_f32_e32 v28, v38, v18
	v_mul_f32_e32 v29, v39, v19
	v_mul_f32_e32 v26, v36, v16
	v_mul_f32_e32 v27, v37, v17
	global_store_dwordx4 v[0:1], v[4:7], off offset:2048
	v_mul_f32_e32 v2, v14, v22
	v_mul_f32_e32 v3, v15, v23
	v_mul_f32_e32 v0, v12, v20
	v_mul_f32_e32 v1, v13, v21
	global_store_dwordx4 v[64:65], v[48:51], off offset:256
	v_cvt_pk_bf16_f32 v26, v26, v27
	v_cvt_pk_bf16_f32 v27, v28, v29
	v_lshl_add_u64 v[48:49], v[142:143], 0, s[24:25]
	v_cvt_pk_bf16_f32 v0, v0, v1
	v_cvt_pk_bf16_f32 v1, v2, v3
	v_mul_f32_e32 v4, v10, v18
	v_mul_f32_e32 v5, v11, v19
	v_mul_f32_e32 v2, v8, v16
	v_mul_f32_e32 v3, v9, v17
	global_store_dwordx4 v[48:49], v[24:27], off offset:256
	v_cvt_pk_bf16_f32 v2, v2, v3
	v_cvt_pk_bf16_f32 v3, v4, v5
	v_lshl_add_u64 v[24:25], v[142:143], 0, s[26:27]
	s_andn2_b64 vcc, exec, s[2:3]
	s_mov_b32 s41, s28
	s_mov_b32 s40, s30
	global_store_dwordx4 v[162:163], v[100:103], off offset:256
	global_store_dwordx4 v[24:25], v[0:3], off offset:256
	s_cbranch_vccz .LBB0_543

; #define PG8_STAGE(bufoff, gbase, voff) do { _Pragma("unroll") for (int _i = 0; _i < 2; ++_i) \
;         __builtin_amdgcn_global_load_lds((const unsigned*)((const char*)(gbase) + (voff)[_i]), (LAS unsigned*)(lds + (bufoff) + ldsw + _i * 8192), 16, 0, 0); } while (0)
; #define PG8_LDA(dst, b, h) do { _Pragma("unroll") for (int m = 0; m < 4; ++m) _Pragma("unroll") for (int k = 0; k < 2; ++k) dst[m][k] = *(const LAS bf16x8*)(lds + PG8_SA(b, h) + aoff + m * 2048 + k * 1024); } while (0)
; #define PG8_LDB(dst, b, h) do { _Pragma("unroll") for (int n = 0; n < 2; ++n) _Pragma("unroll") for (int k = 0; k < 2; ++k) dst[n][k] = *(const LAS bf16x8*)(lds + PG8_SB(b, h) + boff + n * 2048 + k * 1024); } while (0)
; #define PG8_MMA(ai, bj, At, Bt) do { __builtin_amdgcn_s_setprio(1); _Pragma("unroll") for (int m = 0; m < 4; ++m) _Pragma("unroll") for (int n = 0; n < 2; ++n) _Pragma("unroll") for (int k = 0; k < 2; ++k) \
;         acc[ai][bj][m][n] = __builtin_amdgcn_mfma_f32_16x16x32_bf16(Bt[n][k], At[m][k], acc[ai][bj][m][n], 0, 0, 0); __builtin_amdgcn_s_setprio(0); } while (0)
; #define PG8_WAIT_V(n) asm volatile("s_waitcnt vmcnt(" #n ")" ::: "memory")
; #define PG8_WAIT_L(n) asm volatile("s_waitcnt lgkmcnt(" #n ")" ::: "memory")
; #define PG8_BAR __builtin_amdgcn_s_barrier()
; #define PG8_SCHED __builtin_amdgcn_sched_barrier(0)
; template <class Epi>
; DI void gemm_phase(LAS unsigned char* lds, int wid, int K, int lda, int ldb, bool bperm, const Sched3& S, const Epi& E) {
;     ...
;             PG8_LDB(B0, 0, 0); PG8_SCHED; PG8_LDA(At, 0, 0); PG8_STAGE(PG8_SA(1, 1), a1 + hA, voffA);
;             PG8_WAIT_L(8); PG8_BAR; PG8_WAIT_L(0); PG8_MMA(0, 0, At, B0); PG8_BAR; PG8_SCHED;
;             PG8_LDB(B1, 0, 1); PG8_STAGE(PG8_SB(0, 0), b2, voffB);
;             PG8_BAR; PG8_WAIT_L(0); PG8_MMA(0, 1, At, B1); PG8_BAR;
;             PG8_LDA(At, 0, 1); PG8_STAGE(PG8_SA(0, 0), a2, voffA);
;             PG8_BAR; PG8_WAIT_L(0); if (full) PG8_MMA(1, 0, At, B0); PG8_BAR; PG8_SCHED;
;             PG8_STAGE(PG8_SB(0, 1), b2 + hstepB, voffB);
;             PG8_WAIT_V(6); PG8_BAR; if (full) PG8_MMA(1, 1, At, B1); PG8_BAR;
.LBB0_621:
	ds_read_b128 v[128:131], v203
	ds_read_b128 v[132:135], v203 offset:1024
	ds_read_b128 v[136:139], v203 offset:2048
	ds_read_b128 v[140:143], v203 offset:3072
	s_add_u32 s40, s38, 0xfff80080
	s_addc_u32 s41, s39, -1
	s_cmp_eq_u32 s29, 28
	s_cselect_b32 s43, s31, s41
	s_cselect_b32 s42, s30, s40
	s_cselect_b32 s41, s37, s23
	s_cselect_b32 s40, s36, s21
	v_lshl_add_u64 v[186:187], s[38:39], 0, v[180:181]
	s_add_i32 m0, s50, 0xc000
	ds_read_b128 v[144:147], v204
	ds_read_b128 v[148:151], v204 offset:1024
	ds_read_b128 v[152:155], v204 offset:2048
	ds_read_b128 v[156:159], v204 offset:3072
	ds_read_b128 v[160:163], v204 offset:4096
	ds_read_b128 v[164:167], v204 offset:5120
	ds_read_b128 v[168:171], v204 offset:6144
	ds_read_b128 v[172:175], v204 offset:7168
	global_load_lds_dwordx4 v[186:187], off
	v_lshl_add_u64 v[186:187], s[38:39], 0, v[182:183]
	s_add_i32 m0, s50, 0xe000
	s_nop 0
	global_load_lds_dwordx4 v[186:187], off
	s_waitcnt lgkmcnt(8)
	s_barrier
	s_waitcnt lgkmcnt(0)
	s_setprio 1
	s_waitcnt lgkmcnt(0)
	v_mfma_f32_16x16x32_bf16 v[124:127], v[128:131], v[144:147], v[124:127]
	v_mfma_f32_16x16x32_bf16 v[120:123], v[136:139], v[144:147], v[120:123]
	v_mfma_f32_16x16x32_bf16 v[108:111], v[128:131], v[152:155], v[108:111]
	v_mfma_f32_16x16x32_bf16 v[104:107], v[136:139], v[152:155], v[104:107]
	v_mfma_f32_16x16x32_bf16 v[92:95], v[128:131], v[160:163], v[92:95]
	v_mfma_f32_16x16x32_bf16 v[88:91], v[136:139], v[160:163], v[88:91]
	v_mfma_f32_16x16x32_bf16 v[76:79], v[128:131], v[168:171], v[76:79]
	v_mfma_f32_16x16x32_bf16 v[72:75], v[136:139], v[168:171], v[72:75]
	v_mfma_f32_16x16x32_bf16 v[124:127], v[132:135], v[148:151], v[124:127]
	v_mfma_f32_16x16x32_bf16 v[120:123], v[140:143], v[148:151], v[120:123]
	v_mfma_f32_16x16x32_bf16 v[108:111], v[132:135], v[156:159], v[108:111]
	v_mfma_f32_16x16x32_bf16 v[104:107], v[140:143], v[156:159], v[104:107]
	v_mfma_f32_16x16x32_bf16 v[92:95], v[132:135], v[164:167], v[92:95]
	v_mfma_f32_16x16x32_bf16 v[88:91], v[140:143], v[164:167], v[88:91]
	v_mfma_f32_16x16x32_bf16 v[76:79], v[132:135], v[172:175], v[76:79]
	v_mfma_f32_16x16x32_bf16 v[72:75], v[140:143], v[172:175], v[72:75]
	s_setprio 0
	s_barrier
	s_add_i32 s63, s59, s49
	v_lshl_add_u64 v[210:211], s[40:41], 0, v[176:177]
	s_mov_b32 m0, s63
	ds_read_b128 v[186:189], v205
	ds_read_b128 v[190:193], v205 offset:1024
	ds_read_b128 v[194:197], v205 offset:2048
	ds_read_b128 v[206:209], v205 offset:3072
	global_load_lds_dwordx4 v[210:211], off
	v_lshl_add_u64 v[212:213], s[40:41], 0, v[178:179]
	s_add_i32 m0, s63, 0x2000
	s_nop 0
	global_load_lds_dwordx4 v[212:213], off
	s_barrier
	s_waitcnt lgkmcnt(0)
	s_setprio 1
	s_waitcnt lgkmcnt(0)
	v_mfma_f32_16x16x32_bf16 v[116:119], v[186:189], v[144:147], v[116:119]
	v_mfma_f32_16x16x32_bf16 v[112:115], v[194:197], v[144:147], v[112:115]
	v_mfma_f32_16x16x32_bf16 v[100:103], v[186:189], v[152:155], v[100:103]
	v_mfma_f32_16x16x32_bf16 v[96:99], v[194:197], v[152:155], v[96:99]
	v_mfma_f32_16x16x32_bf16 v[84:87], v[186:189], v[160:163], v[84:87]
	v_mfma_f32_16x16x32_bf16 v[80:83], v[194:197], v[160:163], v[80:83]
	v_mfma_f32_16x16x32_bf16 v[68:71], v[186:189], v[168:171], v[68:71]
	v_mfma_f32_16x16x32_bf16 v[64:67], v[194:197], v[168:171], v[64:67]
	v_mfma_f32_16x16x32_bf16 v[116:119], v[190:193], v[148:151], v[116:119]
	v_mfma_f32_16x16x32_bf16 v[112:115], v[206:209], v[148:151], v[112:115]
	v_mfma_f32_16x16x32_bf16 v[100:103], v[190:193], v[156:159], v[100:103]
	v_mfma_f32_16x16x32_bf16 v[96:99], v[206:209], v[156:159], v[96:99]
	v_mfma_f32_16x16x32_bf16 v[84:87], v[190:193], v[164:167], v[84:87]
	v_mfma_f32_16x16x32_bf16 v[80:83], v[206:209], v[164:167], v[80:83]
	v_mfma_f32_16x16x32_bf16 v[68:71], v[190:193], v[172:175], v[68:71]
	v_mfma_f32_16x16x32_bf16 v[64:67], v[206:209], v[172:175], v[64:67]
	s_setprio 0
	s_mov_b32 m0, s50
	v_lshl_add_u64 v[214:215], s[42:43], 0, v[176:177]
	s_barrier
	ds_read_b128 v[144:147], v204 offset:16384
	ds_read_b128 v[148:151], v204 offset:17408
	ds_read_b128 v[152:155], v204 offset:18432
	ds_read_b128 v[156:159], v204 offset:19456
	ds_read_b128 v[160:163], v204 offset:20480
	ds_read_b128 v[164:167], v204 offset:21504
	ds_read_b128 v[168:171], v204 offset:22528
	ds_read_b128 v[172:175], v204 offset:23552
	global_load_lds_dwordx4 v[214:215], off
	v_lshl_add_u64 v[216:217], s[42:43], 0, v[178:179]
	s_mov_b32 m0, s51
	s_nop 0
	global_load_lds_dwordx4 v[216:217], off
	s_barrier
	s_waitcnt lgkmcnt(0)
	s_setprio 1
	s_waitcnt lgkmcnt(0)
	v_mfma_f32_16x16x32_bf16 v[60:63], v[128:131], v[144:147], v[60:63]
	v_mfma_f32_16x16x32_bf16 v[56:59], v[136:139], v[144:147], v[56:59]
	v_mfma_f32_16x16x32_bf16 v[44:47], v[128:131], v[152:155], v[44:47]
	v_mfma_f32_16x16x32_bf16 v[40:43], v[136:139], v[152:155], v[40:43]
	v_mfma_f32_16x16x32_bf16 v[28:31], v[128:131], v[160:163], v[28:31]
	v_mfma_f32_16x16x32_bf16 v[24:27], v[136:139], v[160:163], v[24:27]
	v_mfma_f32_16x16x32_bf16 v[12:15], v[128:131], v[168:171], v[12:15]
	v_mfma_f32_16x16x32_bf16 v[8:11], v[136:139], v[168:171], v[8:11]
	v_mfma_f32_16x16x32_bf16 v[60:63], v[132:135], v[148:151], v[60:63]
	v_mfma_f32_16x16x32_bf16 v[56:59], v[140:143], v[148:151], v[56:59]
	v_mfma_f32_16x16x32_bf16 v[44:47], v[132:135], v[156:159], v[44:47]
	v_mfma_f32_16x16x32_bf16 v[40:43], v[140:143], v[156:159], v[40:43]
	v_mfma_f32_16x16x32_bf16 v[28:31], v[132:135], v[164:167], v[28:31]
	v_mfma_f32_16x16x32_bf16 v[24:27], v[140:143], v[164:167], v[24:27]
	v_mfma_f32_16x16x32_bf16 v[12:15], v[132:135], v[172:175], v[12:15]
	v_mfma_f32_16x16x32_bf16 v[8:11], v[140:143], v[172:175], v[8:11]
	s_setprio 0
	s_barrier
; #define PG8_STAGE(bufoff, gbase, voff) do { _Pragma("unroll") for (int _i = 0; _i < 2; ++_i) \
;         __builtin_amdgcn_global_load_lds((const unsigned*)((const char*)(gbase) + (voff)[_i]), (LAS unsigned*)(lds + (bufoff) + ldsw + _i * 8192), 16, 0, 0); } while (0)
; #define PG8_LDA(dst, b, h) do { _Pragma("unroll") for (int m = 0; m < 4; ++m) _Pragma("unroll") for (int k = 0; k < 2; ++k) dst[m][k] = *(const LAS bf16x8*)(lds + PG8_SA(b, h) + aoff + m * 2048 + k * 1024); } while (0)
; #define PG8_LDB(dst, b, h) do { _Pragma("unroll") for (int n = 0; n < 2; ++n) _Pragma("unroll") for (int k = 0; k < 2; ++k) dst[n][k] = *(const LAS bf16x8*)(lds + PG8_SB(b, h) + boff + n * 2048 + k * 1024); } while (0)
; #define PG8_MMA(ai, bj, At, Bt) do { __builtin_amdgcn_s_setprio(1); _Pragma("unroll") for (int m = 0; m < 4; ++m) _Pragma("unroll") for (int n = 0; n < 2; ++n) _Pragma("unroll") for (int k = 0; k < 2; ++k) \
;         acc[ai][bj][m][n] = __builtin_amdgcn_mfma_f32_16x16x32_bf16(Bt[n][k], At[m][k], acc[ai][bj][m][n], 0, 0, 0); __builtin_amdgcn_s_setprio(0); } while (0)
; #define PG8_WAIT_V(n) asm volatile("s_waitcnt vmcnt(" #n ")" ::: "memory")
; #define PG8_WAIT_L(n) asm volatile("s_waitcnt lgkmcnt(" #n ")" ::: "memory")
; #define PG8_BAR __builtin_amdgcn_s_barrier()
; #define PG8_SCHED __builtin_amdgcn_sched_barrier(0)
; template <class Epi>
; DI void gemm_phase(LAS unsigned char* lds, int wid, int K, int lda, int ldb, bool bperm, const Sched3& S, const Epi& E) {
;     ...
;             PG8_WAIT_V(6); PG8_BAR; if (full) PG8_MMA(1, 1, At, B1); PG8_BAR;
;             PG8_LDB(B0, 1, 0); PG8_SCHED; PG8_LDA(At, 1, 0); PG8_STAGE(PG8_SA(0, 1), a2 + h2, voffA);
;             PG8_WAIT_L(8); PG8_BAR; PG8_WAIT_L(0); PG8_MMA(0, 0, At, B0); PG8_BAR; PG8_SCHED;
;             PG8_LDB(B1, 1, 1); PG8_STAGE(PG8_SB(1, 0), b3, voffB);
;             PG8_BAR; PG8_WAIT_L(0); PG8_MMA(0, 1, At, B1); PG8_BAR;
;             PG8_LDA(At, 1, 1); PG8_STAGE(PG8_SA(1, 0), a3, voffA);
;             PG8_BAR; PG8_WAIT_L(0); if (full) PG8_MMA(1, 0, At, B0); PG8_BAR; PG8_SCHED;
	s_add_u32 s64, s40, 0x80000
	s_addc_u32 s65, s41, 0
	s_add_i32 s63, s60, s49
	v_lshl_add_u64 v[128:129], s[64:65], 0, v[176:177]
	s_mov_b32 m0, s63
	s_nop 0
	global_load_lds_dwordx4 v[128:129], off
	v_lshl_add_u64 v[128:129], s[64:65], 0, v[178:179]
	s_add_i32 m0, s63, 0x2000
	s_nop 0
	global_load_lds_dwordx4 v[128:129], off
	s_waitcnt vmcnt(6)
	s_barrier
	s_setprio 1
	v_mfma_f32_16x16x32_bf16 v[52:55], v[186:189], v[144:147], v[52:55]
	v_mfma_f32_16x16x32_bf16 v[48:51], v[194:197], v[144:147], v[48:51]
	v_mfma_f32_16x16x32_bf16 v[36:39], v[186:189], v[152:155], v[36:39]
	v_mfma_f32_16x16x32_bf16 v[32:35], v[194:197], v[152:155], v[32:35]
	v_mfma_f32_16x16x32_bf16 v[20:23], v[186:189], v[160:163], v[20:23]
	v_mfma_f32_16x16x32_bf16 v[16:19], v[194:197], v[160:163], v[16:19]
	v_mfma_f32_16x16x32_bf16 v[4:7], v[186:189], v[168:171], v[4:7]
	v_mfma_f32_16x16x32_bf16 v[0:3], v[194:197], v[168:171], v[0:3]
	v_mfma_f32_16x16x32_bf16 v[52:55], v[190:193], v[148:151], v[52:55]
	v_mfma_f32_16x16x32_bf16 v[48:51], v[206:209], v[148:151], v[48:51]
	v_mfma_f32_16x16x32_bf16 v[36:39], v[190:193], v[156:159], v[36:39]
	v_mfma_f32_16x16x32_bf16 v[32:35], v[206:209], v[156:159], v[32:35]
	v_mfma_f32_16x16x32_bf16 v[20:23], v[190:193], v[164:167], v[20:23]
	v_mfma_f32_16x16x32_bf16 v[16:19], v[206:209], v[164:167], v[16:19]
	v_mfma_f32_16x16x32_bf16 v[4:7], v[190:193], v[172:175], v[4:7]
	v_mfma_f32_16x16x32_bf16 v[0:3], v[206:209], v[172:175], v[0:3]
	s_setprio 0
	s_add_i32 s63, 0, 0x18000
	v_add_u32_e32 v140, s63, v199
	s_barrier
	ds_read_b128 v[128:131], v140
	ds_read_b128 v[132:135], v140 offset:1024
	ds_read_b128 v[136:139], v140 offset:2048
	ds_read_b128 v[140:143], v140 offset:3072
	s_add_u32 s42, s42, 0x80000
	s_addc_u32 s43, s43, 0
	s_mov_b32 m0, s52
	v_lshl_add_u64 v[186:187], s[42:43], 0, v[176:177]
	ds_read_b128 v[144:147], v204 offset:32768
	ds_read_b128 v[148:151], v204 offset:33792
	ds_read_b128 v[152:155], v204 offset:34816
	ds_read_b128 v[156:159], v204 offset:35840
	ds_read_b128 v[160:163], v204 offset:36864
	ds_read_b128 v[164:167], v204 offset:37888
	ds_read_b128 v[168:171], v204 offset:38912
	ds_read_b128 v[172:175], v204 offset:39936
	global_load_lds_dwordx4 v[186:187], off
	v_lshl_add_u64 v[186:187], s[42:43], 0, v[178:179]
	s_mov_b32 m0, s53
	s_nop 0
	global_load_lds_dwordx4 v[186:187], off
	s_waitcnt lgkmcnt(8)
	s_barrier
	s_waitcnt lgkmcnt(0)
	s_setprio 1
	s_waitcnt lgkmcnt(0)
	v_mfma_f32_16x16x32_bf16 v[124:127], v[128:131], v[144:147], v[124:127]
	v_mfma_f32_16x16x32_bf16 v[120:123], v[136:139], v[144:147], v[120:123]
	v_mfma_f32_16x16x32_bf16 v[108:111], v[128:131], v[152:155], v[108:111]
	v_mfma_f32_16x16x32_bf16 v[104:107], v[136:139], v[152:155], v[104:107]
	v_mfma_f32_16x16x32_bf16 v[92:95], v[128:131], v[160:163], v[92:95]
	v_mfma_f32_16x16x32_bf16 v[88:91], v[136:139], v[160:163], v[88:91]
	v_mfma_f32_16x16x32_bf16 v[76:79], v[128:131], v[168:171], v[76:79]
	v_mfma_f32_16x16x32_bf16 v[72:75], v[136:139], v[168:171], v[72:75]
	v_mfma_f32_16x16x32_bf16 v[124:127], v[132:135], v[148:151], v[124:127]
	v_mfma_f32_16x16x32_bf16 v[120:123], v[140:143], v[148:151], v[120:123]
	v_mfma_f32_16x16x32_bf16 v[108:111], v[132:135], v[156:159], v[108:111]
	v_mfma_f32_16x16x32_bf16 v[104:107], v[140:143], v[156:159], v[104:107]
	v_mfma_f32_16x16x32_bf16 v[92:95], v[132:135], v[164:167], v[92:95]
	v_mfma_f32_16x16x32_bf16 v[88:91], v[140:143], v[164:167], v[88:91]
	v_mfma_f32_16x16x32_bf16 v[76:79], v[132:135], v[172:175], v[76:79]
	v_mfma_f32_16x16x32_bf16 v[72:75], v[140:143], v[172:175], v[72:75]
	s_setprio 0
	s_barrier
	s_add_i32 s42, 0, 0x1c000
	s_add_i32 s43, s63, s49
	v_add_u32_e32 v206, s42, v199
	v_lshl_add_u64 v[210:211], v[210:211], 0, s[12:13]
	s_mov_b32 m0, s43
	ds_read_b128 v[186:189], v206
	ds_read_b128 v[190:193], v206 offset:1024
	ds_read_b128 v[194:197], v206 offset:2048
	ds_read_b128 v[206:209], v206 offset:3072
	global_load_lds_dwordx4 v[210:211], off
	v_lshl_add_u64 v[210:211], v[212:213], 0, s[12:13]
	s_add_i32 m0, s43, 0x2000
	s_nop 0
	global_load_lds_dwordx4 v[210:211], off
	s_barrier
	s_waitcnt lgkmcnt(0)
	s_setprio 1
	s_waitcnt lgkmcnt(0)
	v_mfma_f32_16x16x32_bf16 v[116:119], v[186:189], v[144:147], v[116:119]
	v_mfma_f32_16x16x32_bf16 v[112:115], v[194:197], v[144:147], v[112:115]
	v_mfma_f32_16x16x32_bf16 v[100:103], v[186:189], v[152:155], v[100:103]
	v_mfma_f32_16x16x32_bf16 v[96:99], v[194:197], v[152:155], v[96:99]
	v_mfma_f32_16x16x32_bf16 v[84:87], v[186:189], v[160:163], v[84:87]
	v_mfma_f32_16x16x32_bf16 v[80:83], v[194:197], v[160:163], v[80:83]
	v_mfma_f32_16x16x32_bf16 v[68:71], v[186:189], v[168:171], v[68:71]
	v_mfma_f32_16x16x32_bf16 v[64:67], v[194:197], v[168:171], v[64:67]
	v_mfma_f32_16x16x32_bf16 v[116:119], v[190:193], v[148:151], v[116:119]
	v_mfma_f32_16x16x32_bf16 v[112:115], v[206:209], v[148:151], v[112:115]
	v_mfma_f32_16x16x32_bf16 v[100:103], v[190:193], v[156:159], v[100:103]
	v_mfma_f32_16x16x32_bf16 v[96:99], v[206:209], v[156:159], v[96:99]
	v_mfma_f32_16x16x32_bf16 v[84:87], v[190:193], v[164:167], v[84:87]
	v_mfma_f32_16x16x32_bf16 v[80:83], v[206:209], v[164:167], v[80:83]
	v_mfma_f32_16x16x32_bf16 v[68:71], v[190:193], v[172:175], v[68:71]
	v_mfma_f32_16x16x32_bf16 v[64:67], v[206:209], v[172:175], v[64:67]
	s_setprio 0
	s_mov_b32 m0, s55
	v_lshl_add_u64 v[210:211], v[214:215], 0, s[12:13]
	s_barrier
	ds_read_b128 v[144:147], v204 offset:49152
	ds_read_b128 v[148:151], v204 offset:50176
	ds_read_b128 v[152:155], v204 offset:51200
	ds_read_b128 v[156:159], v204 offset:52224
	ds_read_b128 v[160:163], v204 offset:53248
	ds_read_b128 v[164:167], v204 offset:54272
	ds_read_b128 v[168:171], v204 offset:55296
	ds_read_b128 v[172:175], v204 offset:56320
	global_load_lds_dwordx4 v[210:211], off
	v_lshl_add_u64 v[210:211], v[216:217], 0, s[12:13]
	s_mov_b32 m0, s56
	s_nop 0
	global_load_lds_dwordx4 v[210:211], off
	s_barrier
; DI u32x2 pk4(f32x4 v) { u32x2 r; r.x = pk2(v[0], v[1]); r.y = pk2(v[2], v[3]); return r; }
; DI float bf_lo(unsigned w) { return __uint_as_float(w << 16); }
; DI float bf_hi(unsigned w) { return __uint_as_float(w & 0xffff0000u); }
; #define PG8_STAGE(bufoff, gbase, voff) do { _Pragma("unroll") for (int _i = 0; _i < 2; ++_i) \
;         __builtin_amdgcn_global_load_lds((const unsigned*)((const char*)(gbase) + (voff)[_i]), (LAS unsigned*)(lds + (bufoff) + ldsw + _i * 8192), 16, 0, 0); } while (0)
; #define PG8_BAR __builtin_amdgcn_s_barrier()
; template <class Epi>
; DI void gemm_phase(LAS unsigned char* lds, int wid, int K, int lda, int ldb, bool bperm, const Sched3& S, const Epi& E) {
;     ...
;             PG8_BAR; PG8_WAIT_L(0); if (full) PG8_MMA(1, 0, At, B0); PG8_BAR; PG8_SCHED;
;             PG8_STAGE(PG8_SB(1, 1), b3 + hstepB, voffB);
;             PG8_WAIT_V(6); PG8_BAR; if (full) PG8_MMA(1, 1, At, B1); PG8_BAR;
;     DI void operator()(const Acc& acc, const Unit& u, int wr, int wc, int fr, int fq) const {
;     ...
;                 for (int m = 0; m < 4; ++m) { const size_t o = (size_t)(row0 + ai * HALF + m * 16) * 2048 + colp;
;                     if (PH == 4) { COLS4 xo[m][bj][n] = *(const f32x4*)(p.x + o + bj * HALF + n * 4); }
;                     else {
; #pragma unroll
;                         for (int bj = 0; bj < 2; ++bj) { const u32x4 w = *(const u32x4*)(WSB(OFF_XB) + o + bj * HALF);
;                             xo[m][bj][0] = (f32x4){bf_lo(w.x), bf_hi(w.x), bf_lo(w.y), bf_hi(w.y)}; xo[m][bj][1] = (f32x4){bf_lo(w.z), bf_hi(w.z), bf_lo(w.w), bf_hi(w.w)}; } } }
; #pragma unroll
;                 for (int m = 0; m < 4; ++m) { const int r = row0 + ai * HALF + m * 16; const size_t o = (size_t)r * 2048 + colp; float part = 0.f;
; #pragma unroll
;                     for (int bj = 0; bj < 2; ++bj) { const f32x4 x0 = xo[m][bj][0] + acc[ai][bj][m][0], x1 = xo[m][bj][1] + acc[ai][bj][m][1];
;                         const u32x2 h0 = pk4(x0), h1 = pk4(x1);
;                         *(u32x4*)(WSB(OFF_XB) + o + bj * HALF) = (u32x4){h0.x, h0.y, h1.x, h1.y};
;                         part += x0[0] * x0[0] + x0[1] * x0[1] + x0[2] * x0[2] + x0[3] * x0[3] + x1[0] * x1[0] + x1[1] * x1[1] + x1[2] * x1[2] + x1[3] * x1[3]; }
;                     part += __shfl_xor(part, 16); part += __shfl_xor(part, 32);
;                     if (fq == 0) unsafeAtomicAdd(ssq + r, part);
	s_waitcnt lgkmcnt(0)
	s_setprio 1
	s_waitcnt lgkmcnt(0)
	v_mfma_f32_16x16x32_bf16 v[60:63], v[128:131], v[144:147], v[60:63]
	v_mfma_f32_16x16x32_bf16 v[56:59], v[136:139], v[144:147], v[56:59]
	v_mfma_f32_16x16x32_bf16 v[44:47], v[128:131], v[152:155], v[44:47]
	v_mfma_f32_16x16x32_bf16 v[40:43], v[136:139], v[152:155], v[40:43]
	v_mfma_f32_16x16x32_bf16 v[28:31], v[128:131], v[160:163], v[28:31]
	v_mfma_f32_16x16x32_bf16 v[24:27], v[136:139], v[160:163], v[24:27]
	v_mfma_f32_16x16x32_bf16 v[12:15], v[128:131], v[168:171], v[12:15]
	v_mfma_f32_16x16x32_bf16 v[8:11], v[136:139], v[168:171], v[8:11]
	v_mfma_f32_16x16x32_bf16 v[60:63], v[132:135], v[148:151], v[60:63]
	v_mfma_f32_16x16x32_bf16 v[56:59], v[140:143], v[148:151], v[56:59]
	v_mfma_f32_16x16x32_bf16 v[44:47], v[132:135], v[156:159], v[44:47]
	v_mfma_f32_16x16x32_bf16 v[40:43], v[140:143], v[156:159], v[40:43]
	v_mfma_f32_16x16x32_bf16 v[28:31], v[132:135], v[164:167], v[28:31]
	v_mfma_f32_16x16x32_bf16 v[24:27], v[140:143], v[164:167], v[24:27]
	v_mfma_f32_16x16x32_bf16 v[12:15], v[132:135], v[172:175], v[12:15]
	v_mfma_f32_16x16x32_bf16 v[8:11], v[140:143], v[172:175], v[8:11]
	s_setprio 0
	s_barrier
	s_add_u32 s40, s40, 0x80080
	s_addc_u32 s41, s41, 0
	s_add_i32 s42, s42, s49
	v_lshl_add_u64 v[128:129], s[40:41], 0, v[176:177]
	s_mov_b32 m0, s42
	s_nop 0
	global_load_lds_dwordx4 v[128:129], off
	v_lshl_add_u64 v[128:129], s[40:41], 0, v[178:179]
	s_add_i32 m0, s42, 0x2000
	s_nop 0
	global_load_lds_dwordx4 v[128:129], off
	s_waitcnt vmcnt(6)
	s_barrier
	s_setprio 1
	v_mfma_f32_16x16x32_bf16 v[52:55], v[186:189], v[144:147], v[52:55]
	v_mfma_f32_16x16x32_bf16 v[48:51], v[194:197], v[144:147], v[48:51]
	v_mfma_f32_16x16x32_bf16 v[36:39], v[186:189], v[152:155], v[36:39]
	v_mfma_f32_16x16x32_bf16 v[32:35], v[194:197], v[152:155], v[32:35]
	v_mfma_f32_16x16x32_bf16 v[20:23], v[186:189], v[160:163], v[20:23]
	v_mfma_f32_16x16x32_bf16 v[16:19], v[194:197], v[160:163], v[16:19]
	v_mfma_f32_16x16x32_bf16 v[4:7], v[186:189], v[168:171], v[4:7]
	v_mfma_f32_16x16x32_bf16 v[0:3], v[194:197], v[168:171], v[0:3]
	v_mfma_f32_16x16x32_bf16 v[52:55], v[190:193], v[148:151], v[52:55]
	v_mfma_f32_16x16x32_bf16 v[48:51], v[206:209], v[148:151], v[48:51]
	v_mfma_f32_16x16x32_bf16 v[36:39], v[190:193], v[156:159], v[36:39]
	v_mfma_f32_16x16x32_bf16 v[32:35], v[206:209], v[156:159], v[32:35]
	v_mfma_f32_16x16x32_bf16 v[20:23], v[190:193], v[164:167], v[20:23]
	v_mfma_f32_16x16x32_bf16 v[16:19], v[206:209], v[164:167], v[16:19]
	v_mfma_f32_16x16x32_bf16 v[4:7], v[190:193], v[172:175], v[4:7]
	v_mfma_f32_16x16x32_bf16 v[0:3], v[206:209], v[172:175], v[0:3]
	s_setprio 0
	s_add_i32 s29, s29, 2
	s_add_u32 s38, s38, 0x100
	s_addc_u32 s39, s39, 0
	s_add_u32 s21, s21, 0x100
	s_addc_u32 s23, s23, 0
	s_cmp_gt_u32 s29, 29
	s_barrier
	s_cbranch_scc0 .LBB0_621
	v_lshl_add_u32 v190, s28, 8, v198
	v_lshl_add_u32 v186, s62, 8, v200
	v_ashrrev_i32_e32 v187, 31, v186
	v_ashrrev_i32_e32 v191, 31, v190
	v_lshl_add_u64 v[188:189], v[186:187], 2, s[16:17]
	v_lshlrev_b64 v[128:129], 13, v[190:191]
	v_lshl_add_u64 v[128:129], v[188:189], 0, v[128:129]
	global_load_dwordx4 v[206:209], v[128:129], off
	global_load_dwordx4 v[210:213], v[128:129], off offset:16
	global_load_dwordx4 v[214:217], v[128:129], off offset:512
	global_load_dwordx4 v[218:221], v[128:129], off offset:528
	v_or_b32_e32 v196, 16, v190
	v_or_b32_e32 v194, 32, v190
	v_or_b32_e32 v192, 48, v190
	v_ashrrev_i32_e32 v197, 31, v196
	v_ashrrev_i32_e32 v195, 31, v194
	v_ashrrev_i32_e32 v193, 31, v192
	v_lshlrev_b64 v[128:129], 13, v[196:197]
	v_lshlrev_b64 v[130:131], 13, v[194:195]
	v_lshlrev_b64 v[132:133], 13, v[192:193]
	v_lshl_add_u64 v[128:129], v[188:189], 0, v[128:129]
	v_lshl_add_u64 v[130:131], v[188:189], 0, v[130:131]
	v_lshl_add_u64 v[132:133], v[188:189], 0, v[132:133]
	global_load_dwordx4 v[168:171], v[128:129], off offset:16
	global_load_dwordx4 v[172:175], v[128:129], off
	global_load_dwordx4 v[160:163], v[128:129], off offset:528
	global_load_dwordx4 v[164:167], v[128:129], off offset:512
	global_load_dwordx4 v[152:155], v[130:131], off offset:16
	global_load_dwordx4 v[156:159], v[130:131], off
	global_load_dwordx4 v[144:147], v[130:131], off offset:528
	global_load_dwordx4 v[148:151], v[130:131], off offset:512
	global_load_dwordx4 v[136:139], v[132:133], off offset:16
	global_load_dwordx4 v[140:143], v[132:133], off
	s_nop 0
	global_load_dwordx4 v[128:131], v[132:133], off offset:528
	s_nop 0
	global_load_dwordx4 v[132:135], v[132:133], off offset:512
	v_lshlrev_b64 v[222:223], 12, v[190:191]
	v_lshlrev_b64 v[186:187], 1, v[186:187]
	v_lshl_add_u64 v[224:225], s[18:19], 0, v[222:223]
	v_lshl_add_u64 v[224:225], v[224:225], 0, v[186:187]
	v_lshl_add_u64 v[222:223], s[10:11], 0, v[222:223]
	v_lshl_add_u64 v[222:223], v[222:223], 0, v[186:187]
	s_waitcnt vmcnt(0)
	v_add_f32_e32 v124, v124, v206
	v_add_f32_e32 v125, v125, v207
	v_add_f32_e32 v120, v120, v210
	v_add_f32_e32 v121, v121, v211
	v_add_f32_e32 v206, v116, v214
	v_add_f32_e32 v207, v117, v215
	v_add_f32_e32 v210, v112, v218
	v_add_f32_e32 v211, v113, v219
	v_cvt_pk_bf16_f32 v112, v124, v125
	v_mul_f32_e32 v117, v125, v125
	v_mul_f32_e32 v125, v207, v207
	v_add_f32_e32 v126, v126, v208
	v_add_f32_e32 v127, v127, v209
	v_add_f32_e32 v118, v118, v216
	v_add_f32_e32 v119, v119, v217
	v_fmac_f32_e32 v117, v124, v124
	v_fmac_f32_e32 v125, v206, v206
	v_fmac_f32_e32 v117, v126, v126
	v_fmac_f32_e32 v125, v118, v118
	v_fmac_f32_e32 v117, v127, v127
	v_fmac_f32_e32 v125, v119, v119
	v_fmac_f32_e32 v117, v120, v120
	v_fmac_f32_e32 v125, v210, v210
	v_add_f32_e32 v122, v122, v212
	v_add_f32_e32 v123, v123, v213
	v_add_f32_e32 v208, v114, v220
	v_add_f32_e32 v209, v115, v221
	v_fmac_f32_e32 v117, v121, v121
	v_fmac_f32_e32 v125, v211, v211
	v_fmac_f32_e32 v117, v122, v122
	v_fmac_f32_e32 v125, v208, v208
	v_fmac_f32_e32 v117, v123, v123
	v_fmac_f32_e32 v125, v209, v209
	v_cvt_pk_bf16_f32 v114, v120, v121
	v_add_f32_e32 v120, v117, v125
	ds_bpermute_b32 v121, v201, v120
	v_cvt_pk_bf16_f32 v113, v126, v127
	v_cvt_pk_bf16_f32 v115, v122, v123
	global_store_dwordx4 v[224:225], v[112:115], off sc1
	v_cvt_pk_bf16_f32 v116, v206, v207
	v_cvt_pk_bf16_f32 v117, v118, v119
	s_waitcnt lgkmcnt(0)
	v_add_f32_e32 v112, v120, v121
	ds_bpermute_b32 v113, v202, v112
	v_add_co_u32_e32 v114, vcc, s61, v222
	v_cvt_pk_bf16_f32 v118, v210, v211
	v_cvt_pk_bf16_f32 v119, v208, v209
	v_addc_co_u32_e32 v115, vcc, 0, v223, vcc
	global_store_dwordx4 v[114:115], v[116:119], off offset:256 sc1
	s_and_saveexec_b64 s[28:29], s[2:3]
	s_cbranch_execz .LBB0_624
	s_waitcnt lgkmcnt(0)
	v_add_f32_e32 v114, v112, v113
	v_lshl_add_u64 v[112:113], v[190:191], 2, s[14:15]
	global_atomic_add_f32 v[112:113], v114, off
; DI u32x2 pk4(f32x4 v) { u32x2 r; r.x = pk2(v[0], v[1]); r.y = pk2(v[2], v[3]); return r; }
;     DI void operator()(const Acc& acc, const Unit& u, int wr, int wc, int fr, int fq) const {
;     ...
;                 for (int m = 0; m < 4; ++m) { const int r = row0 + ai * HALF + m * 16; const size_t o = (size_t)r * 2048 + colp; float part = 0.f;
; #pragma unroll
;                     for (int bj = 0; bj < 2; ++bj) { const f32x4 x0 = xo[m][bj][0] + acc[ai][bj][m][0], x1 = xo[m][bj][1] + acc[ai][bj][m][1];
;                         const u32x2 h0 = pk4(x0), h1 = pk4(x1);
;                         *(u32x4*)(WSB(OFF_XB) + o + bj * HALF) = (u32x4){h0.x, h0.y, h1.x, h1.y};
;                         part += x0[0] * x0[0] + x0[1] * x0[1] + x0[2] * x0[2] + x0[3] * x0[3] + x1[0] * x1[0] + x1[1] * x1[1] + x1[2] * x1[2] + x1[3] * x1[3]; }
;                     part += __shfl_xor(part, 16); part += __shfl_xor(part, 32);
;                     if (fq == 0) unsafeAtomicAdd(ssq + r, part);
.LBB0_624:
	s_or_b64 exec, exec, s[28:29]
	s_waitcnt lgkmcnt(0)
	v_lshlrev_b64 v[112:113], 12, v[196:197]
	v_add_f32_e32 v110, v110, v174
	v_add_f32_e32 v111, v111, v175
	v_add_f32_e32 v108, v108, v172
	v_add_f32_e32 v109, v109, v173
	v_add_f32_e32 v114, v106, v170
	v_add_f32_e32 v115, v107, v171
	v_add_f32_e32 v116, v104, v168
	v_add_f32_e32 v117, v105, v169
	v_lshl_add_u64 v[118:119], s[18:19], 0, v[112:113]
	v_cvt_pk_bf16_f32 v104, v108, v109
	v_cvt_pk_bf16_f32 v105, v110, v111
	v_cvt_pk_bf16_f32 v106, v116, v117
	v_cvt_pk_bf16_f32 v107, v114, v115
	v_lshl_add_u64 v[118:119], v[118:119], 0, v[186:187]
	v_add_f32_e32 v100, v100, v164
	v_add_f32_e32 v101, v101, v165
	global_store_dwordx4 v[118:119], v[104:107], off sc1
	v_add_f32_e32 v102, v102, v166
	v_add_f32_e32 v103, v103, v167
	v_add_f32_e32 v96, v96, v160
	v_add_f32_e32 v97, v97, v161
	v_mul_f32_e32 v106, v109, v109
	v_add_f32_e32 v104, v98, v162
	v_add_f32_e32 v105, v99, v163
	v_cvt_pk_bf16_f32 v98, v100, v101
	v_mul_f32_e32 v101, v101, v101
	v_fmac_f32_e32 v106, v108, v108
	v_fmac_f32_e32 v101, v100, v100
	v_fmac_f32_e32 v106, v110, v110
	v_fmac_f32_e32 v101, v102, v102
	v_fmac_f32_e32 v106, v111, v111
	v_fmac_f32_e32 v101, v103, v103
	v_fmac_f32_e32 v106, v116, v116
	v_fmac_f32_e32 v101, v96, v96
	v_fmac_f32_e32 v106, v117, v117
	v_fmac_f32_e32 v101, v97, v97
	v_fmac_f32_e32 v106, v114, v114
	v_fmac_f32_e32 v101, v104, v104
	v_fmac_f32_e32 v106, v115, v115
	v_fmac_f32_e32 v101, v105, v105
	v_add_f32_e32 v106, v106, v101
	ds_bpermute_b32 v107, v201, v106
	v_cvt_pk_bf16_f32 v100, v96, v97
	v_lshl_add_u64 v[96:97], s[10:11], 0, v[112:113]
	v_cvt_pk_bf16_f32 v99, v102, v103
	v_lshl_add_u64 v[102:103], v[96:97], 0, v[186:187]
	s_waitcnt lgkmcnt(0)
	v_add_f32_e32 v96, v106, v107
	ds_bpermute_b32 v97, v202, v96
	v_add_co_u32_e32 v102, vcc, s61, v102
	v_cvt_pk_bf16_f32 v101, v104, v105
	s_nop 0
	v_addc_co_u32_e32 v103, vcc, 0, v103, vcc
	global_store_dwordx4 v[102:103], v[98:101], off offset:256 sc1
	s_and_saveexec_b64 s[28:29], s[2:3]
	s_cbranch_execz .LBB0_626
	s_waitcnt lgkmcnt(0)
	v_add_f32_e32 v98, v96, v97
	v_lshl_add_u64 v[96:97], v[196:197], 2, s[14:15]
	global_atomic_add_f32 v[96:97], v98, off
.LBB0_626:
	s_or_b64 exec, exec, s[28:29]
	s_waitcnt lgkmcnt(0)
	v_lshlrev_b64 v[96:97], 12, v[194:195]
	v_add_f32_e32 v94, v94, v158
	v_add_f32_e32 v95, v95, v159
	v_add_f32_e32 v92, v92, v156
	v_add_f32_e32 v93, v93, v157
	v_add_f32_e32 v98, v90, v154
	v_add_f32_e32 v99, v91, v155
	v_add_f32_e32 v100, v88, v152
	v_add_f32_e32 v101, v89, v153
	v_lshl_add_u64 v[102:103], s[18:19], 0, v[96:97]
	v_cvt_pk_bf16_f32 v88, v92, v93
	v_cvt_pk_bf16_f32 v89, v94, v95
	v_cvt_pk_bf16_f32 v90, v100, v101
	v_cvt_pk_bf16_f32 v91, v98, v99
	v_lshl_add_u64 v[102:103], v[102:103], 0, v[186:187]
	v_add_f32_e32 v84, v84, v148
	v_add_f32_e32 v85, v85, v149
	global_store_dwordx4 v[102:103], v[88:91], off sc1
	v_add_f32_e32 v86, v86, v150
	v_add_f32_e32 v87, v87, v151
	v_add_f32_e32 v80, v80, v144
	v_add_f32_e32 v81, v81, v145
	v_mul_f32_e32 v90, v93, v93
	v_add_f32_e32 v88, v82, v146
	v_add_f32_e32 v89, v83, v147
	v_cvt_pk_bf16_f32 v82, v84, v85
	v_mul_f32_e32 v85, v85, v85
	v_fmac_f32_e32 v90, v92, v92
	v_fmac_f32_e32 v85, v84, v84
	v_fmac_f32_e32 v90, v94, v94
	v_fmac_f32_e32 v85, v86, v86
	v_fmac_f32_e32 v90, v95, v95
	v_fmac_f32_e32 v85, v87, v87
	v_fmac_f32_e32 v90, v100, v100
	v_fmac_f32_e32 v85, v80, v80
	v_fmac_f32_e32 v90, v101, v101
	v_fmac_f32_e32 v85, v81, v81
	v_fmac_f32_e32 v90, v98, v98
	v_fmac_f32_e32 v85, v88, v88
	v_fmac_f32_e32 v90, v99, v99
	v_fmac_f32_e32 v85, v89, v89
	v_add_f32_e32 v90, v90, v85
	ds_bpermute_b32 v91, v201, v90
	v_cvt_pk_bf16_f32 v84, v80, v81
	v_lshl_add_u64 v[80:81], s[10:11], 0, v[96:97]
	v_cvt_pk_bf16_f32 v83, v86, v87
	v_lshl_add_u64 v[86:87], v[80:81], 0, v[186:187]
	s_waitcnt lgkmcnt(0)
	v_add_f32_e32 v80, v90, v91
	ds_bpermute_b32 v81, v202, v80
	v_add_co_u32_e32 v86, vcc, s61, v86
	v_cvt_pk_bf16_f32 v85, v88, v89
	s_nop 0
	v_addc_co_u32_e32 v87, vcc, 0, v87, vcc
	global_store_dwordx4 v[86:87], v[82:85], off offset:256 sc1
	s_and_saveexec_b64 s[28:29], s[2:3]
	s_cbranch_execz .LBB0_628
	s_waitcnt lgkmcnt(0)
	v_add_f32_e32 v82, v80, v81
	v_lshl_add_u64 v[80:81], v[194:195], 2, s[14:15]
	global_atomic_add_f32 v[80:81], v82, off
.LBB0_628:
	s_or_b64 exec, exec, s[28:29]
	s_waitcnt lgkmcnt(0)
	v_lshlrev_b64 v[80:81], 12, v[192:193]
	v_add_f32_e32 v78, v78, v142
	v_add_f32_e32 v79, v79, v143
	v_add_f32_e32 v76, v76, v140
	v_add_f32_e32 v77, v77, v141
	v_add_f32_e32 v82, v74, v138
	v_add_f32_e32 v83, v75, v139
	v_add_f32_e32 v84, v72, v136
	v_add_f32_e32 v85, v73, v137
	v_lshl_add_u64 v[86:87], s[18:19], 0, v[80:81]
	v_cvt_pk_bf16_f32 v72, v76, v77
	v_cvt_pk_bf16_f32 v73, v78, v79
	v_cvt_pk_bf16_f32 v74, v84, v85
	v_cvt_pk_bf16_f32 v75, v82, v83
	v_lshl_add_u64 v[86:87], v[86:87], 0, v[186:187]
	v_add_f32_e32 v68, v68, v132
	v_add_f32_e32 v69, v69, v133
	global_store_dwordx4 v[86:87], v[72:75], off sc1
	v_add_f32_e32 v70, v70, v134
	v_add_f32_e32 v71, v71, v135
	v_add_f32_e32 v64, v64, v128
	v_add_f32_e32 v65, v65, v129
	v_mul_f32_e32 v74, v77, v77
	v_add_f32_e32 v72, v66, v130
	v_add_f32_e32 v73, v67, v131
	v_cvt_pk_bf16_f32 v66, v68, v69
	v_mul_f32_e32 v69, v69, v69
	v_fmac_f32_e32 v74, v76, v76
	v_fmac_f32_e32 v69, v68, v68
	v_fmac_f32_e32 v74, v78, v78
	v_fmac_f32_e32 v69, v70, v70
	v_fmac_f32_e32 v74, v79, v79
	v_fmac_f32_e32 v69, v71, v71
	v_fmac_f32_e32 v74, v84, v84
	v_fmac_f32_e32 v69, v64, v64
	v_fmac_f32_e32 v74, v85, v85
	v_fmac_f32_e32 v69, v65, v65
	v_fmac_f32_e32 v74, v82, v82
	v_fmac_f32_e32 v69, v72, v72
	v_fmac_f32_e32 v74, v83, v83
	v_fmac_f32_e32 v69, v73, v73
	v_add_f32_e32 v74, v74, v69
	ds_bpermute_b32 v75, v201, v74
	v_cvt_pk_bf16_f32 v68, v64, v65
	v_lshl_add_u64 v[64:65], s[10:11], 0, v[80:81]
	v_cvt_pk_bf16_f32 v67, v70, v71
	v_lshl_add_u64 v[70:71], v[64:65], 0, v[186:187]
	s_waitcnt lgkmcnt(0)
	v_add_f32_e32 v64, v74, v75
	ds_bpermute_b32 v65, v202, v64
	v_add_co_u32_e32 v70, vcc, s61, v70
	v_cvt_pk_bf16_f32 v69, v72, v73
	s_nop 0
	v_addc_co_u32_e32 v71, vcc, 0, v71, vcc
	global_store_dwordx4 v[70:71], v[66:69], off offset:256 sc1
	s_and_saveexec_b64 s[28:29], s[2:3]
	s_cbranch_execz .LBB0_630
	s_waitcnt lgkmcnt(0)
	v_add_f32_e32 v66, v64, v65
	v_lshl_add_u64 v[64:65], v[192:193], 2, s[14:15]
	global_atomic_add_f32 v[64:65], v66, off
; DI u32x2 pk4(f32x4 v) { u32x2 r; r.x = pk2(v[0], v[1]); r.y = pk2(v[2], v[3]); return r; }
; DI float bf_lo(unsigned w) { return __uint_as_float(w << 16); }
; DI float bf_hi(unsigned w) { return __uint_as_float(w & 0xffff0000u); }
; #define COLS4 _Pragma("unroll") for (int bj = 0; bj < 2; ++bj) _Pragma("unroll") for (int n = 0; n < 2; ++n)
;     DI void operator()(const Acc& acc, const Unit& u, int wr, int wc, int fr, int fq) const {
;     ...
;                 for (int m = 0; m < 4; ++m) { const size_t o = (size_t)(row0 + ai * HALF + m * 16) * 2048 + colp;
;                     if (PH == 4) { COLS4 xo[m][bj][n] = *(const f32x4*)(p.x + o + bj * HALF + n * 4); }
;                     else {
; #pragma unroll
;                         for (int bj = 0; bj < 2; ++bj) { const u32x4 w = *(const u32x4*)(WSB(OFF_XB) + o + bj * HALF);
;                             xo[m][bj][0] = (f32x4){bf_lo(w.x), bf_hi(w.x), bf_lo(w.y), bf_hi(w.y)}; xo[m][bj][1] = (f32x4){bf_lo(w.z), bf_hi(w.z), bf_lo(w.w), bf_hi(w.w)}; } } }
; #pragma unroll
;                 for (int m = 0; m < 4; ++m) { const int r = row0 + ai * HALF + m * 16; const size_t o = (size_t)r * 2048 + colp; float part = 0.f;
; #pragma unroll
;                     for (int bj = 0; bj < 2; ++bj) { const f32x4 x0 = xo[m][bj][0] + acc[ai][bj][m][0], x1 = xo[m][bj][1] + acc[ai][bj][m][1];
;                         const u32x2 h0 = pk4(x0), h1 = pk4(x1);
;                         *(u32x4*)(WSB(OFF_XB) + o + bj * HALF) = (u32x4){h0.x, h0.y, h1.x, h1.y};
;                         part += x0[0] * x0[0] + x0[1] * x0[1] + x0[2] * x0[2] + x0[3] * x0[3] + x1[0] * x1[0] + x1[1] * x1[1] + x1[2] * x1[2] + x1[3] * x1[3]; }
;                     part += __shfl_xor(part, 16); part += __shfl_xor(part, 32);
;                     if (fq == 0) unsafeAtomicAdd(ssq + r, part);
.LBB0_630:
	s_or_b64 exec, exec, s[28:29]
	v_add_u32_e32 v118, 0x80, v190
	v_ashrrev_i32_e32 v119, 31, v118
	s_waitcnt lgkmcnt(0)
	v_lshlrev_b64 v[64:65], 13, v[118:119]
	v_lshl_add_u64 v[64:65], v[188:189], 0, v[64:65]
	global_load_dwordx4 v[120:123], v[64:65], off
	global_load_dwordx4 v[124:127], v[64:65], off offset:16
	global_load_dwordx4 v[128:131], v[64:65], off offset:512
	global_load_dwordx4 v[132:135], v[64:65], off offset:528
	v_add_u32_e32 v116, 0x90, v190
	v_add_u32_e32 v114, 0xa0, v190
	v_add_u32_e32 v112, 0xb0, v190
	v_ashrrev_i32_e32 v117, 31, v116
	v_ashrrev_i32_e32 v115, 31, v114
	v_ashrrev_i32_e32 v113, 31, v112
	v_lshlrev_b64 v[64:65], 13, v[116:117]
	v_lshlrev_b64 v[66:67], 13, v[114:115]
	v_lshlrev_b64 v[68:69], 13, v[112:113]
	v_lshl_add_u64 v[64:65], v[188:189], 0, v[64:65]
	v_lshl_add_u64 v[66:67], v[188:189], 0, v[66:67]
	v_lshl_add_u64 v[68:69], v[188:189], 0, v[68:69]
	global_load_dwordx4 v[104:107], v[64:65], off offset:16
	global_load_dwordx4 v[108:111], v[64:65], off
	global_load_dwordx4 v[96:99], v[64:65], off offset:528
	global_load_dwordx4 v[100:103], v[64:65], off offset:512
	global_load_dwordx4 v[88:91], v[66:67], off offset:16
	global_load_dwordx4 v[92:95], v[66:67], off
	global_load_dwordx4 v[80:83], v[66:67], off offset:528
	global_load_dwordx4 v[84:87], v[66:67], off offset:512
	global_load_dwordx4 v[72:75], v[68:69], off offset:16
	global_load_dwordx4 v[76:79], v[68:69], off
	s_nop 0
	global_load_dwordx4 v[64:67], v[68:69], off offset:528
	s_nop 0
	global_load_dwordx4 v[68:71], v[68:69], off offset:512
	v_lshlrev_b64 v[136:137], 12, v[118:119]
	v_lshl_add_u64 v[138:139], s[18:19], 0, v[136:137]
	v_lshl_add_u64 v[138:139], v[138:139], 0, v[186:187]
	v_lshl_add_u64 v[136:137], s[10:11], 0, v[136:137]
	v_lshl_add_u64 v[136:137], v[136:137], 0, v[186:187]
	s_waitcnt vmcnt(15)
	v_add_f32_e32 v60, v60, v120
	v_add_f32_e32 v61, v61, v121
	s_waitcnt vmcnt(14)
	v_add_f32_e32 v56, v56, v124
	v_add_f32_e32 v57, v57, v125
	s_waitcnt vmcnt(13)
	v_add_f32_e32 v120, v52, v128
	v_add_f32_e32 v121, v53, v129
	s_waitcnt vmcnt(12)
	v_add_f32_e32 v124, v48, v132
	v_add_f32_e32 v125, v49, v133
	v_cvt_pk_bf16_f32 v48, v60, v61
	v_mul_f32_e32 v53, v61, v61
	v_mul_f32_e32 v61, v121, v121
	v_add_f32_e32 v62, v62, v122
	v_add_f32_e32 v63, v63, v123
	v_add_f32_e32 v54, v54, v130
	v_add_f32_e32 v55, v55, v131
	v_fmac_f32_e32 v53, v60, v60
	v_fmac_f32_e32 v61, v120, v120
	v_fmac_f32_e32 v53, v62, v62
	v_fmac_f32_e32 v61, v54, v54
	v_fmac_f32_e32 v53, v63, v63
	v_fmac_f32_e32 v61, v55, v55
	v_fmac_f32_e32 v53, v56, v56
	v_fmac_f32_e32 v61, v124, v124
	v_add_f32_e32 v58, v58, v126
	v_add_f32_e32 v59, v59, v127
	v_add_f32_e32 v122, v50, v134
	v_add_f32_e32 v123, v51, v135
	v_fmac_f32_e32 v53, v57, v57
	v_fmac_f32_e32 v61, v125, v125
	v_fmac_f32_e32 v53, v58, v58
	v_fmac_f32_e32 v61, v122, v122
	v_fmac_f32_e32 v53, v59, v59
	v_fmac_f32_e32 v61, v123, v123
	v_cvt_pk_bf16_f32 v50, v56, v57
	v_add_f32_e32 v56, v53, v61
	ds_bpermute_b32 v57, v201, v56
	v_cvt_pk_bf16_f32 v49, v62, v63
	v_cvt_pk_bf16_f32 v51, v58, v59
	global_store_dwordx4 v[138:139], v[48:51], off sc1
	v_cvt_pk_bf16_f32 v52, v120, v121
	v_cvt_pk_bf16_f32 v53, v54, v55
	s_waitcnt lgkmcnt(0)
	v_add_f32_e32 v48, v56, v57
	ds_bpermute_b32 v49, v202, v48
	v_add_co_u32_e32 v50, vcc, s61, v136
	v_cvt_pk_bf16_f32 v54, v124, v125
	v_cvt_pk_bf16_f32 v55, v122, v123
	v_addc_co_u32_e32 v51, vcc, 0, v137, vcc
	global_store_dwordx4 v[50:51], v[52:55], off offset:256 sc1
	s_and_saveexec_b64 s[28:29], s[2:3]
	s_cbranch_execz .LBB0_632
	s_waitcnt lgkmcnt(0)
	v_add_f32_e32 v50, v48, v49
	v_lshl_add_u64 v[48:49], v[118:119], 2, s[14:15]
	global_atomic_add_f32 v[48:49], v50, off
.LBB0_632:
	s_or_b64 exec, exec, s[28:29]
	s_waitcnt lgkmcnt(0)
	v_lshlrev_b64 v[48:49], 12, v[116:117]
	s_waitcnt vmcnt(12)
	v_add_f32_e32 v46, v46, v110
	v_add_f32_e32 v47, v47, v111
	v_add_f32_e32 v44, v44, v108
	v_add_f32_e32 v45, v45, v109
	v_add_f32_e32 v50, v42, v106
	v_add_f32_e32 v51, v43, v107
	v_add_f32_e32 v52, v40, v104
	v_add_f32_e32 v53, v41, v105
	v_lshl_add_u64 v[54:55], s[18:19], 0, v[48:49]
	v_cvt_pk_bf16_f32 v40, v44, v45
	v_cvt_pk_bf16_f32 v41, v46, v47
	v_cvt_pk_bf16_f32 v42, v52, v53
	v_cvt_pk_bf16_f32 v43, v50, v51
	v_lshl_add_u64 v[54:55], v[54:55], 0, v[186:187]
	s_waitcnt vmcnt(10)
	v_add_f32_e32 v36, v36, v100
	v_add_f32_e32 v37, v37, v101
	global_store_dwordx4 v[54:55], v[40:43], off sc1
	v_add_f32_e32 v38, v38, v102
	v_add_f32_e32 v39, v39, v103
	v_add_f32_e32 v32, v32, v96
	v_add_f32_e32 v33, v33, v97
	v_mul_f32_e32 v42, v45, v45
	v_add_f32_e32 v40, v34, v98
	v_add_f32_e32 v41, v35, v99
	v_cvt_pk_bf16_f32 v34, v36, v37
	v_mul_f32_e32 v37, v37, v37
	v_fmac_f32_e32 v42, v44, v44
	v_fmac_f32_e32 v37, v36, v36
	v_fmac_f32_e32 v42, v46, v46
	v_fmac_f32_e32 v37, v38, v38
	v_fmac_f32_e32 v42, v47, v47
	v_fmac_f32_e32 v37, v39, v39
	v_fmac_f32_e32 v42, v52, v52
	v_fmac_f32_e32 v37, v32, v32
	v_fmac_f32_e32 v42, v53, v53
	v_fmac_f32_e32 v37, v33, v33
	v_fmac_f32_e32 v42, v50, v50
	v_fmac_f32_e32 v37, v40, v40
	v_fmac_f32_e32 v42, v51, v51
	v_fmac_f32_e32 v37, v41, v41
	v_add_f32_e32 v42, v42, v37
	ds_bpermute_b32 v43, v201, v42
	v_cvt_pk_bf16_f32 v36, v32, v33
	v_lshl_add_u64 v[32:33], s[10:11], 0, v[48:49]
	v_cvt_pk_bf16_f32 v35, v38, v39
	v_lshl_add_u64 v[38:39], v[32:33], 0, v[186:187]
	s_waitcnt lgkmcnt(0)
	v_add_f32_e32 v32, v42, v43
	ds_bpermute_b32 v33, v202, v32
	v_add_co_u32_e32 v38, vcc, s61, v38
	v_cvt_pk_bf16_f32 v37, v40, v41
	s_nop 0
	v_addc_co_u32_e32 v39, vcc, 0, v39, vcc
	global_store_dwordx4 v[38:39], v[34:37], off offset:256 sc1
	s_and_saveexec_b64 s[28:29], s[2:3]
	s_cbranch_execz .LBB0_634
	s_waitcnt lgkmcnt(0)
	v_add_f32_e32 v34, v32, v33
	v_lshl_add_u64 v[32:33], v[116:117], 2, s[14:15]
	global_atomic_add_f32 v[32:33], v34, off
; DI u32x2 pk4(f32x4 v) { u32x2 r; r.x = pk2(v[0], v[1]); r.y = pk2(v[2], v[3]); return r; }
;     DI void operator()(const Acc& acc, const Unit& u, int wr, int wc, int fr, int fq) const {
;     ...
;                 for (int m = 0; m < 4; ++m) { const int r = row0 + ai * HALF + m * 16; const size_t o = (size_t)r * 2048 + colp; float part = 0.f;
; #pragma unroll
;                     for (int bj = 0; bj < 2; ++bj) { const f32x4 x0 = xo[m][bj][0] + acc[ai][bj][m][0], x1 = xo[m][bj][1] + acc[ai][bj][m][1];
;                         const u32x2 h0 = pk4(x0), h1 = pk4(x1);
;                         *(u32x4*)(WSB(OFF_XB) + o + bj * HALF) = (u32x4){h0.x, h0.y, h1.x, h1.y};
;                         part += x0[0] * x0[0] + x0[1] * x0[1] + x0[2] * x0[2] + x0[3] * x0[3] + x1[0] * x1[0] + x1[1] * x1[1] + x1[2] * x1[2] + x1[3] * x1[3]; }
;                     part += __shfl_xor(part, 16); part += __shfl_xor(part, 32);
;                     if (fq == 0) unsafeAtomicAdd(ssq + r, part);
.LBB0_634:
	s_or_b64 exec, exec, s[28:29]
	s_waitcnt lgkmcnt(0)
	v_lshlrev_b64 v[32:33], 12, v[114:115]
	s_waitcnt vmcnt(10)
	v_add_f32_e32 v30, v30, v94
	v_add_f32_e32 v31, v31, v95
	v_add_f32_e32 v28, v28, v92
	v_add_f32_e32 v29, v29, v93
	v_add_f32_e32 v34, v26, v90
	v_add_f32_e32 v35, v27, v91
	v_add_f32_e32 v36, v24, v88
	v_add_f32_e32 v37, v25, v89
	v_lshl_add_u64 v[38:39], s[18:19], 0, v[32:33]
	v_cvt_pk_bf16_f32 v24, v28, v29
	v_cvt_pk_bf16_f32 v25, v30, v31
	v_cvt_pk_bf16_f32 v26, v36, v37
	v_cvt_pk_bf16_f32 v27, v34, v35
	v_lshl_add_u64 v[38:39], v[38:39], 0, v[186:187]
	s_waitcnt vmcnt(8)
	v_add_f32_e32 v20, v20, v84
	v_add_f32_e32 v21, v21, v85
	global_store_dwordx4 v[38:39], v[24:27], off sc1
	v_add_f32_e32 v22, v22, v86
	v_add_f32_e32 v23, v23, v87
	v_add_f32_e32 v16, v16, v80
	v_add_f32_e32 v17, v17, v81
	v_mul_f32_e32 v26, v29, v29
	v_add_f32_e32 v24, v18, v82
	v_add_f32_e32 v25, v19, v83
	v_cvt_pk_bf16_f32 v18, v20, v21
	v_mul_f32_e32 v21, v21, v21
	v_fmac_f32_e32 v26, v28, v28
	v_fmac_f32_e32 v21, v20, v20
	v_fmac_f32_e32 v26, v30, v30
	v_fmac_f32_e32 v21, v22, v22
	v_fmac_f32_e32 v26, v31, v31
	v_fmac_f32_e32 v21, v23, v23
	v_fmac_f32_e32 v26, v36, v36
	v_fmac_f32_e32 v21, v16, v16
	v_fmac_f32_e32 v26, v37, v37
	v_fmac_f32_e32 v21, v17, v17
	v_fmac_f32_e32 v26, v34, v34
	v_fmac_f32_e32 v21, v24, v24
	v_fmac_f32_e32 v26, v35, v35
	v_fmac_f32_e32 v21, v25, v25
	v_add_f32_e32 v26, v26, v21
	ds_bpermute_b32 v27, v201, v26
	v_cvt_pk_bf16_f32 v20, v16, v17
	v_lshl_add_u64 v[16:17], s[10:11], 0, v[32:33]
	v_cvt_pk_bf16_f32 v19, v22, v23
	v_lshl_add_u64 v[22:23], v[16:17], 0, v[186:187]
	s_waitcnt lgkmcnt(0)
	v_add_f32_e32 v16, v26, v27
	ds_bpermute_b32 v17, v202, v16
	v_add_co_u32_e32 v22, vcc, s61, v22
	v_cvt_pk_bf16_f32 v21, v24, v25
	s_nop 0
	v_addc_co_u32_e32 v23, vcc, 0, v23, vcc
	global_store_dwordx4 v[22:23], v[18:21], off offset:256 sc1
	s_and_saveexec_b64 s[28:29], s[2:3]
	s_cbranch_execz .LBB0_636
	s_waitcnt lgkmcnt(0)
	v_add_f32_e32 v18, v16, v17
	v_lshl_add_u64 v[16:17], v[114:115], 2, s[14:15]
	global_atomic_add_f32 v[16:17], v18, off
.LBB0_636:
	s_or_b64 exec, exec, s[28:29]
	s_waitcnt lgkmcnt(0)
	v_lshlrev_b64 v[16:17], 12, v[112:113]
	s_waitcnt vmcnt(8)
	v_add_f32_e32 v14, v14, v78
	v_add_f32_e32 v15, v15, v79
	v_add_f32_e32 v12, v12, v76
	v_add_f32_e32 v13, v13, v77
	v_add_f32_e32 v18, v10, v74
	v_add_f32_e32 v19, v11, v75
	v_add_f32_e32 v20, v8, v72
	v_add_f32_e32 v21, v9, v73
	v_lshl_add_u64 v[22:23], s[18:19], 0, v[16:17]
	v_cvt_pk_bf16_f32 v8, v12, v13
	v_cvt_pk_bf16_f32 v9, v14, v15
	v_cvt_pk_bf16_f32 v10, v20, v21
	v_cvt_pk_bf16_f32 v11, v18, v19
	v_lshl_add_u64 v[22:23], v[22:23], 0, v[186:187]
	s_waitcnt vmcnt(6)
	v_add_f32_e32 v4, v4, v68
	v_add_f32_e32 v5, v5, v69
	global_store_dwordx4 v[22:23], v[8:11], off sc1
	v_add_f32_e32 v6, v6, v70
	v_add_f32_e32 v7, v7, v71
	v_add_f32_e32 v0, v0, v64
	v_add_f32_e32 v1, v1, v65
	v_mul_f32_e32 v10, v13, v13
	v_add_f32_e32 v8, v2, v66
	v_add_f32_e32 v9, v3, v67
	v_cvt_pk_bf16_f32 v2, v4, v5
	v_mul_f32_e32 v5, v5, v5
	v_fmac_f32_e32 v10, v12, v12
	v_fmac_f32_e32 v5, v4, v4
	v_fmac_f32_e32 v10, v14, v14
	v_fmac_f32_e32 v5, v6, v6
	v_fmac_f32_e32 v10, v15, v15
	v_fmac_f32_e32 v5, v7, v7
	v_fmac_f32_e32 v10, v20, v20
	v_fmac_f32_e32 v5, v0, v0
	v_fmac_f32_e32 v10, v21, v21
	v_fmac_f32_e32 v5, v1, v1
	v_fmac_f32_e32 v10, v18, v18
	v_fmac_f32_e32 v5, v8, v8
	v_fmac_f32_e32 v10, v19, v19
	v_fmac_f32_e32 v5, v9, v9
	v_add_f32_e32 v10, v10, v5
	ds_bpermute_b32 v11, v201, v10
	v_cvt_pk_bf16_f32 v4, v0, v1
	v_lshl_add_u64 v[0:1], s[10:11], 0, v[16:17]
	v_cvt_pk_bf16_f32 v3, v6, v7
	v_lshl_add_u64 v[6:7], v[0:1], 0, v[186:187]
	s_waitcnt lgkmcnt(0)
	v_add_f32_e32 v0, v10, v11
	ds_bpermute_b32 v1, v202, v0
	v_add_co_u32_e32 v6, vcc, s61, v6
	v_cvt_pk_bf16_f32 v5, v8, v9
	s_nop 0
	v_addc_co_u32_e32 v7, vcc, 0, v7, vcc
	global_store_dwordx4 v[6:7], v[2:5], off offset:256 sc1
	s_and_saveexec_b64 s[28:29], s[2:3]
	s_cbranch_execz .LBB0_613
	s_waitcnt lgkmcnt(0)
	v_add_f32_e32 v2, v0, v1
	v_lshl_add_u64 v[0:1], v[112:113], 2, s[14:15]
	global_atomic_add_f32 v[0:1], v2, off
	s_branch .LBB0_613

; #define PG8_STAGE(bufoff, gbase, voff) do { _Pragma("unroll") for (int _i = 0; _i < 2; ++_i) \
;         __builtin_amdgcn_global_load_lds((const unsigned*)((const char*)(gbase) + (voff)[_i]), (LAS unsigned*)(lds + (bufoff) + ldsw + _i * 8192), 16, 0, 0); } while (0)
; #define PG8_LDA(dst, b, h) do { _Pragma("unroll") for (int m = 0; m < 4; ++m) _Pragma("unroll") for (int k = 0; k < 2; ++k) dst[m][k] = *(const LAS bf16x8*)(lds + PG8_SA(b, h) + aoff + m * 2048 + k * 1024); } while (0)
; #define PG8_LDB(dst, b, h) do { _Pragma("unroll") for (int n = 0; n < 2; ++n) _Pragma("unroll") for (int k = 0; k < 2; ++k) dst[n][k] = *(const LAS bf16x8*)(lds + PG8_SB(b, h) + boff + n * 2048 + k * 1024); } while (0)
; #define PG8_MMA(ai, bj, At, Bt) do { __builtin_amdgcn_s_setprio(1); _Pragma("unroll") for (int m = 0; m < 4; ++m) _Pragma("unroll") for (int n = 0; n < 2; ++n) _Pragma("unroll") for (int k = 0; k < 2; ++k) \
;         acc[ai][bj][m][n] = __builtin_amdgcn_mfma_f32_16x16x32_bf16(Bt[n][k], At[m][k], acc[ai][bj][m][n], 0, 0, 0); __builtin_amdgcn_s_setprio(0); } while (0)
; #define PG8_WAIT_V(n) asm volatile("s_waitcnt vmcnt(" #n ")" ::: "memory")
; #define PG8_WAIT_L(n) asm volatile("s_waitcnt lgkmcnt(" #n ")" ::: "memory")
; #define PG8_BAR __builtin_amdgcn_s_barrier()
; #define PG8_SCHED __builtin_amdgcn_sched_barrier(0)
; template <class Epi>
; DI void gemm_phase(LAS unsigned char* lds, int wid, int K, int lda, int ldb, bool bperm, const Sched3& S, const Epi& E) {
;     ...
;             PG8_LDB(B0, 0, 0); PG8_SCHED; PG8_LDA(At, 0, 0); PG8_STAGE(PG8_SA(1, 1), a1 + hA, voffA);
;             PG8_WAIT_L(8); PG8_BAR; PG8_WAIT_L(0); PG8_MMA(0, 0, At, B0); PG8_BAR; PG8_SCHED;
;             PG8_LDB(B1, 0, 1); PG8_STAGE(PG8_SB(0, 0), b2, voffB);
;             PG8_BAR; PG8_WAIT_L(0); PG8_MMA(0, 1, At, B1); PG8_BAR;
;             PG8_LDA(At, 0, 1); PG8_STAGE(PG8_SA(0, 0), a2, voffA);
;             PG8_BAR; PG8_WAIT_L(0); if (full) PG8_MMA(1, 0, At, B0); PG8_BAR; PG8_SCHED;
;             PG8_STAGE(PG8_SB(0, 1), b2 + hstepB, voffB);
;             PG8_WAIT_V(6); PG8_BAR; if (full) PG8_MMA(1, 1, At, B1); PG8_BAR;
.LBB0_705:
	ds_read_b128 v[138:141], v160
	ds_read_b128 v[142:145], v160 offset:1024
	ds_read_b128 v[146:149], v160 offset:2048
	ds_read_b128 v[150:153], v160 offset:3072
	s_add_u32 s30, s28, 0xfff80080
	s_addc_u32 s31, s29, -1
	s_cmp_eq_u32 s57, 28
	s_cselect_b32 s37, s25, s31
	s_cselect_b32 s36, s24, s30
	s_cselect_b32 s31, s27, s17
	s_cselect_b32 s30, s26, s15
	v_lshl_add_u64 v[156:157], s[28:29], 0, v[132:133]
	s_add_i32 m0, s23, 0xc000
	ds_read_b128 v[164:167], v161
	ds_read_b128 v[168:171], v161 offset:1024
	ds_read_b128 v[172:175], v161 offset:2048
	ds_read_b128 v[176:179], v161 offset:3072
	ds_read_b128 v[180:183], v161 offset:4096
	ds_read_b128 v[184:187], v161 offset:5120
	ds_read_b128 v[188:191], v161 offset:6144
	ds_read_b128 v[192:195], v161 offset:7168
	global_load_lds_dwordx4 v[156:157], off
	v_lshl_add_u64 v[156:157], s[28:29], 0, v[134:135]
	s_add_i32 m0, s23, 0xe000
	s_nop 0
	global_load_lds_dwordx4 v[156:157], off
	s_waitcnt lgkmcnt(8)
	s_barrier
	s_waitcnt lgkmcnt(0)
	s_setprio 1
	s_waitcnt lgkmcnt(0)
	v_mfma_f32_16x16x32_bf16 v[124:127], v[138:141], v[164:167], v[124:127]
	v_mfma_f32_16x16x32_bf16 v[120:123], v[146:149], v[164:167], v[120:123]
	v_mfma_f32_16x16x32_bf16 v[116:119], v[138:141], v[172:175], v[116:119]
	v_mfma_f32_16x16x32_bf16 v[104:107], v[146:149], v[172:175], v[104:107]
	v_mfma_f32_16x16x32_bf16 v[96:99], v[138:141], v[180:183], v[96:99]
	v_mfma_f32_16x16x32_bf16 v[88:91], v[146:149], v[180:183], v[88:91]
	v_mfma_f32_16x16x32_bf16 v[80:83], v[138:141], v[188:191], v[80:83]
	v_mfma_f32_16x16x32_bf16 v[72:75], v[146:149], v[188:191], v[72:75]
	v_mfma_f32_16x16x32_bf16 v[124:127], v[142:145], v[168:171], v[124:127]
	v_mfma_f32_16x16x32_bf16 v[120:123], v[150:153], v[168:171], v[120:123]
	v_mfma_f32_16x16x32_bf16 v[116:119], v[142:145], v[176:179], v[116:119]
	v_mfma_f32_16x16x32_bf16 v[104:107], v[150:153], v[176:179], v[104:107]
	v_mfma_f32_16x16x32_bf16 v[96:99], v[142:145], v[184:187], v[96:99]
	v_mfma_f32_16x16x32_bf16 v[88:91], v[150:153], v[184:187], v[88:91]
	v_mfma_f32_16x16x32_bf16 v[80:83], v[142:145], v[192:195], v[80:83]
	v_mfma_f32_16x16x32_bf16 v[72:75], v[150:153], v[192:195], v[72:75]
	s_setprio 0
	s_barrier
	s_add_i32 s58, s53, s43
	v_lshl_add_u64 v[156:157], s[30:31], 0, v[130:131]
	s_mov_b32 m0, s58
	ds_read_b128 v[196:199], v162
	ds_read_b128 v[200:203], v162 offset:1024
	ds_read_b128 v[204:207], v162 offset:2048
	ds_read_b128 v[208:211], v162 offset:3072
	global_load_lds_dwordx4 v[156:157], off
	v_lshl_add_u64 v[212:213], s[30:31], 0, v[128:129]
	s_add_i32 m0, s58, 0x2000
	s_nop 0
	global_load_lds_dwordx4 v[212:213], off
	s_barrier
	s_waitcnt lgkmcnt(0)
	s_setprio 1
	s_waitcnt lgkmcnt(0)
	v_mfma_f32_16x16x32_bf16 v[112:115], v[196:199], v[164:167], v[112:115]
	v_mfma_f32_16x16x32_bf16 v[108:111], v[204:207], v[164:167], v[108:111]
	v_mfma_f32_16x16x32_bf16 v[100:103], v[196:199], v[172:175], v[100:103]
	v_mfma_f32_16x16x32_bf16 v[92:95], v[204:207], v[172:175], v[92:95]
	v_mfma_f32_16x16x32_bf16 v[84:87], v[196:199], v[180:183], v[84:87]
	v_mfma_f32_16x16x32_bf16 v[76:79], v[204:207], v[180:183], v[76:79]
	v_mfma_f32_16x16x32_bf16 v[68:71], v[196:199], v[188:191], v[68:71]
	v_mfma_f32_16x16x32_bf16 v[64:67], v[204:207], v[188:191], v[64:67]
	v_mfma_f32_16x16x32_bf16 v[112:115], v[200:203], v[168:171], v[112:115]
	v_mfma_f32_16x16x32_bf16 v[108:111], v[208:211], v[168:171], v[108:111]
	v_mfma_f32_16x16x32_bf16 v[100:103], v[200:203], v[176:179], v[100:103]
	v_mfma_f32_16x16x32_bf16 v[92:95], v[208:211], v[176:179], v[92:95]
	v_mfma_f32_16x16x32_bf16 v[84:87], v[200:203], v[184:187], v[84:87]
	v_mfma_f32_16x16x32_bf16 v[76:79], v[208:211], v[184:187], v[76:79]
	v_mfma_f32_16x16x32_bf16 v[68:71], v[200:203], v[192:195], v[68:71]
	v_mfma_f32_16x16x32_bf16 v[64:67], v[208:211], v[192:195], v[64:67]
	s_setprio 0
	s_mov_b32 m0, s23
	v_lshl_add_u64 v[214:215], s[36:37], 0, v[130:131]
	s_barrier
	ds_read_b128 v[164:167], v161 offset:16384
	ds_read_b128 v[168:171], v161 offset:17408
	ds_read_b128 v[172:175], v161 offset:18432
	ds_read_b128 v[176:179], v161 offset:19456
	ds_read_b128 v[180:183], v161 offset:20480
	ds_read_b128 v[184:187], v161 offset:21504
	ds_read_b128 v[188:191], v161 offset:22528
	ds_read_b128 v[192:195], v161 offset:23552
	global_load_lds_dwordx4 v[214:215], off
	v_lshl_add_u64 v[216:217], s[36:37], 0, v[128:129]
	s_mov_b32 m0, s46
	s_nop 0
	global_load_lds_dwordx4 v[216:217], off
	s_barrier
	s_waitcnt lgkmcnt(0)
	s_setprio 1
	s_waitcnt lgkmcnt(0)
	v_mfma_f32_16x16x32_bf16 v[60:63], v[138:141], v[164:167], v[60:63]
	v_mfma_f32_16x16x32_bf16 v[56:59], v[146:149], v[164:167], v[56:59]
	v_mfma_f32_16x16x32_bf16 v[48:51], v[138:141], v[172:175], v[48:51]
	v_mfma_f32_16x16x32_bf16 v[40:43], v[146:149], v[172:175], v[40:43]
	v_mfma_f32_16x16x32_bf16 v[32:35], v[138:141], v[180:183], v[32:35]
	v_mfma_f32_16x16x32_bf16 v[24:27], v[146:149], v[180:183], v[24:27]
	v_mfma_f32_16x16x32_bf16 v[16:19], v[138:141], v[188:191], v[16:19]
	v_mfma_f32_16x16x32_bf16 v[8:11], v[146:149], v[188:191], v[8:11]
	v_mfma_f32_16x16x32_bf16 v[60:63], v[142:145], v[168:171], v[60:63]
	v_mfma_f32_16x16x32_bf16 v[56:59], v[150:153], v[168:171], v[56:59]
	v_mfma_f32_16x16x32_bf16 v[48:51], v[142:145], v[176:179], v[48:51]
	v_mfma_f32_16x16x32_bf16 v[40:43], v[150:153], v[176:179], v[40:43]
	v_mfma_f32_16x16x32_bf16 v[32:35], v[142:145], v[184:187], v[32:35]
	v_mfma_f32_16x16x32_bf16 v[24:27], v[150:153], v[184:187], v[24:27]
	v_mfma_f32_16x16x32_bf16 v[16:19], v[142:145], v[192:195], v[16:19]
	v_mfma_f32_16x16x32_bf16 v[8:11], v[150:153], v[192:195], v[8:11]
	s_setprio 0
	s_barrier
; #define PG8_STAGE(bufoff, gbase, voff) do { _Pragma("unroll") for (int _i = 0; _i < 2; ++_i) \
;         __builtin_amdgcn_global_load_lds((const unsigned*)((const char*)(gbase) + (voff)[_i]), (LAS unsigned*)(lds + (bufoff) + ldsw + _i * 8192), 16, 0, 0); } while (0)
; #define PG8_LDA(dst, b, h) do { _Pragma("unroll") for (int m = 0; m < 4; ++m) _Pragma("unroll") for (int k = 0; k < 2; ++k) dst[m][k] = *(const LAS bf16x8*)(lds + PG8_SA(b, h) + aoff + m * 2048 + k * 1024); } while (0)
; #define PG8_LDB(dst, b, h) do { _Pragma("unroll") for (int n = 0; n < 2; ++n) _Pragma("unroll") for (int k = 0; k < 2; ++k) dst[n][k] = *(const LAS bf16x8*)(lds + PG8_SB(b, h) + boff + n * 2048 + k * 1024); } while (0)
; #define PG8_MMA(ai, bj, At, Bt) do { __builtin_amdgcn_s_setprio(1); _Pragma("unroll") for (int m = 0; m < 4; ++m) _Pragma("unroll") for (int n = 0; n < 2; ++n) _Pragma("unroll") for (int k = 0; k < 2; ++k) \
;         acc[ai][bj][m][n] = __builtin_amdgcn_mfma_f32_16x16x32_bf16(Bt[n][k], At[m][k], acc[ai][bj][m][n], 0, 0, 0); __builtin_amdgcn_s_setprio(0); } while (0)
; #define PG8_WAIT_V(n) asm volatile("s_waitcnt vmcnt(" #n ")" ::: "memory")
; #define PG8_WAIT_L(n) asm volatile("s_waitcnt lgkmcnt(" #n ")" ::: "memory")
; #define PG8_BAR __builtin_amdgcn_s_barrier()
; #define PG8_SCHED __builtin_amdgcn_sched_barrier(0)
; template <class Epi>
; DI void gemm_phase(LAS unsigned char* lds, int wid, int K, int lda, int ldb, bool bperm, const Sched3& S, const Epi& E) {
;     ...
;             PG8_STAGE(PG8_SB(0, 1), b2 + hstepB, voffB);
;             PG8_WAIT_V(6); PG8_BAR; if (full) PG8_MMA(1, 1, At, B1); PG8_BAR;
;             PG8_LDB(B0, 1, 0); PG8_SCHED; PG8_LDA(At, 1, 0); PG8_STAGE(PG8_SA(0, 1), a2 + h2, voffA);
;             PG8_WAIT_L(8); PG8_BAR; PG8_WAIT_L(0); PG8_MMA(0, 0, At, B0); PG8_BAR; PG8_SCHED;
;             PG8_LDB(B1, 1, 1); PG8_STAGE(PG8_SB(1, 0), b3, voffB);
;             PG8_BAR; PG8_WAIT_L(0); PG8_MMA(0, 1, At, B1); PG8_BAR;
;             PG8_LDA(At, 1, 1); PG8_STAGE(PG8_SA(1, 0), a3, voffA);
	s_add_u32 s58, s30, 0x80000
	s_addc_u32 s59, s31, 0
	s_add_i32 s60, s54, s43
	v_lshl_add_u64 v[138:139], s[58:59], 0, v[130:131]
	s_mov_b32 m0, s60
	s_nop 0
	global_load_lds_dwordx4 v[138:139], off
	v_lshl_add_u64 v[138:139], s[58:59], 0, v[128:129]
	s_add_i32 m0, s60, 0x2000
	s_nop 0
	global_load_lds_dwordx4 v[138:139], off
	s_waitcnt vmcnt(6)
	s_barrier
	s_setprio 1
	v_mfma_f32_16x16x32_bf16 v[52:55], v[196:199], v[164:167], v[52:55]
	v_mfma_f32_16x16x32_bf16 v[44:47], v[204:207], v[164:167], v[44:47]
	v_mfma_f32_16x16x32_bf16 v[36:39], v[196:199], v[172:175], v[36:39]
	v_mfma_f32_16x16x32_bf16 v[28:31], v[204:207], v[172:175], v[28:31]
	v_mfma_f32_16x16x32_bf16 v[20:23], v[196:199], v[180:183], v[20:23]
	v_mfma_f32_16x16x32_bf16 v[12:15], v[204:207], v[180:183], v[12:15]
	v_mfma_f32_16x16x32_bf16 v[4:7], v[196:199], v[188:191], v[4:7]
	v_mfma_f32_16x16x32_bf16 v[0:3], v[204:207], v[188:191], v[0:3]
	v_mfma_f32_16x16x32_bf16 v[52:55], v[200:203], v[168:171], v[52:55]
	v_mfma_f32_16x16x32_bf16 v[44:47], v[208:211], v[168:171], v[44:47]
	v_mfma_f32_16x16x32_bf16 v[36:39], v[200:203], v[176:179], v[36:39]
	v_mfma_f32_16x16x32_bf16 v[28:31], v[208:211], v[176:179], v[28:31]
	v_mfma_f32_16x16x32_bf16 v[20:23], v[200:203], v[184:187], v[20:23]
	v_mfma_f32_16x16x32_bf16 v[12:15], v[208:211], v[184:187], v[12:15]
	v_mfma_f32_16x16x32_bf16 v[4:7], v[200:203], v[192:195], v[4:7]
	v_mfma_f32_16x16x32_bf16 v[0:3], v[208:211], v[192:195], v[0:3]
	s_setprio 0
	s_add_i32 s58, 0, 0x18000
	v_add_u32_e32 v150, s58, v158
	s_barrier
	ds_read_b128 v[138:141], v150
	ds_read_b128 v[142:145], v150 offset:1024
	ds_read_b128 v[146:149], v150 offset:2048
	ds_read_b128 v[150:153], v150 offset:3072
	s_add_u32 s36, s36, 0x80000
	s_addc_u32 s37, s37, 0
	s_mov_b32 m0, s47
	v_lshl_add_u64 v[196:197], s[36:37], 0, v[130:131]
	ds_read_b128 v[164:167], v161 offset:32768
	ds_read_b128 v[168:171], v161 offset:33792
	ds_read_b128 v[172:175], v161 offset:34816
	ds_read_b128 v[176:179], v161 offset:35840
	ds_read_b128 v[180:183], v161 offset:36864
	ds_read_b128 v[184:187], v161 offset:37888
	ds_read_b128 v[188:191], v161 offset:38912
	ds_read_b128 v[192:195], v161 offset:39936
	global_load_lds_dwordx4 v[196:197], off
	v_lshl_add_u64 v[196:197], s[36:37], 0, v[128:129]
	s_mov_b32 m0, s48
	s_nop 0
	global_load_lds_dwordx4 v[196:197], off
	s_waitcnt lgkmcnt(8)
	s_barrier
	s_waitcnt lgkmcnt(0)
	s_setprio 1
	s_waitcnt lgkmcnt(0)
	v_mfma_f32_16x16x32_bf16 v[124:127], v[138:141], v[164:167], v[124:127]
	v_mfma_f32_16x16x32_bf16 v[120:123], v[146:149], v[164:167], v[120:123]
	v_mfma_f32_16x16x32_bf16 v[116:119], v[138:141], v[172:175], v[116:119]
	v_mfma_f32_16x16x32_bf16 v[104:107], v[146:149], v[172:175], v[104:107]
	v_mfma_f32_16x16x32_bf16 v[96:99], v[138:141], v[180:183], v[96:99]
	v_mfma_f32_16x16x32_bf16 v[88:91], v[146:149], v[180:183], v[88:91]
	v_mfma_f32_16x16x32_bf16 v[80:83], v[138:141], v[188:191], v[80:83]
	v_mfma_f32_16x16x32_bf16 v[72:75], v[146:149], v[188:191], v[72:75]
	v_mfma_f32_16x16x32_bf16 v[124:127], v[142:145], v[168:171], v[124:127]
	v_mfma_f32_16x16x32_bf16 v[120:123], v[150:153], v[168:171], v[120:123]
	v_mfma_f32_16x16x32_bf16 v[116:119], v[142:145], v[176:179], v[116:119]
	v_mfma_f32_16x16x32_bf16 v[104:107], v[150:153], v[176:179], v[104:107]
	v_mfma_f32_16x16x32_bf16 v[96:99], v[142:145], v[184:187], v[96:99]
	v_mfma_f32_16x16x32_bf16 v[88:91], v[150:153], v[184:187], v[88:91]
	v_mfma_f32_16x16x32_bf16 v[80:83], v[142:145], v[192:195], v[80:83]
	v_mfma_f32_16x16x32_bf16 v[72:75], v[150:153], v[192:195], v[72:75]
	s_setprio 0
	s_barrier
	s_add_i32 s36, 0, 0x1c000
	s_add_i32 s37, s58, s43
	v_add_u32_e32 v154, s36, v158
	v_lshl_add_u64 v[156:157], v[156:157], 0, s[8:9]
	s_mov_b32 m0, s37
	ds_read_b128 v[196:199], v154
	ds_read_b128 v[200:203], v154 offset:1024
	ds_read_b128 v[204:207], v154 offset:2048
	ds_read_b128 v[208:211], v154 offset:3072
	global_load_lds_dwordx4 v[156:157], off
	v_lshl_add_u64 v[156:157], v[212:213], 0, s[8:9]
	s_add_i32 m0, s37, 0x2000
	s_nop 0
	global_load_lds_dwordx4 v[156:157], off
	s_barrier
	s_waitcnt lgkmcnt(0)
	s_setprio 1
	s_waitcnt lgkmcnt(0)
	v_mfma_f32_16x16x32_bf16 v[112:115], v[196:199], v[164:167], v[112:115]
	v_mfma_f32_16x16x32_bf16 v[108:111], v[204:207], v[164:167], v[108:111]
	v_mfma_f32_16x16x32_bf16 v[100:103], v[196:199], v[172:175], v[100:103]
	v_mfma_f32_16x16x32_bf16 v[92:95], v[204:207], v[172:175], v[92:95]
	v_mfma_f32_16x16x32_bf16 v[84:87], v[196:199], v[180:183], v[84:87]
	v_mfma_f32_16x16x32_bf16 v[76:79], v[204:207], v[180:183], v[76:79]
	v_mfma_f32_16x16x32_bf16 v[68:71], v[196:199], v[188:191], v[68:71]
	v_mfma_f32_16x16x32_bf16 v[64:67], v[204:207], v[188:191], v[64:67]
	v_mfma_f32_16x16x32_bf16 v[112:115], v[200:203], v[168:171], v[112:115]
	v_mfma_f32_16x16x32_bf16 v[108:111], v[208:211], v[168:171], v[108:111]
	v_mfma_f32_16x16x32_bf16 v[100:103], v[200:203], v[176:179], v[100:103]
	v_mfma_f32_16x16x32_bf16 v[92:95], v[208:211], v[176:179], v[92:95]
	v_mfma_f32_16x16x32_bf16 v[84:87], v[200:203], v[184:187], v[84:87]
	v_mfma_f32_16x16x32_bf16 v[76:79], v[208:211], v[184:187], v[76:79]
	v_mfma_f32_16x16x32_bf16 v[68:71], v[200:203], v[192:195], v[68:71]
	v_mfma_f32_16x16x32_bf16 v[64:67], v[208:211], v[192:195], v[64:67]
	s_setprio 0
	s_mov_b32 m0, s49
	v_lshl_add_u64 v[156:157], v[214:215], 0, s[8:9]
	s_barrier
	ds_read_b128 v[164:167], v161 offset:49152
	ds_read_b128 v[168:171], v161 offset:50176
	ds_read_b128 v[172:175], v161 offset:51200
	ds_read_b128 v[176:179], v161 offset:52224
	ds_read_b128 v[180:183], v161 offset:53248
	ds_read_b128 v[184:187], v161 offset:54272
	ds_read_b128 v[188:191], v161 offset:55296
	ds_read_b128 v[192:195], v161 offset:56320
	global_load_lds_dwordx4 v[156:157], off
	v_lshl_add_u64 v[156:157], v[216:217], 0, s[8:9]
	s_mov_b32 m0, s50
	s_nop 0
	global_load_lds_dwordx4 v[156:157], off
	s_barrier
; DI u32x2 pk4(f32x4 v) { u32x2 r; r.x = pk2(v[0], v[1]); r.y = pk2(v[2], v[3]); return r; }
; DI float silu_f(float x) { return x * __builtin_amdgcn_rcpf(1.f + __builtin_amdgcn_exp2f(-1.4426950409f * x)); }
; #define PG8_STAGE(bufoff, gbase, voff) do { _Pragma("unroll") for (int _i = 0; _i < 2; ++_i) \
;         __builtin_amdgcn_global_load_lds((const unsigned*)((const char*)(gbase) + (voff)[_i]), (LAS unsigned*)(lds + (bufoff) + ldsw + _i * 8192), 16, 0, 0); } while (0)
; #define PG8_MMA(ai, bj, At, Bt) do { __builtin_amdgcn_s_setprio(1); _Pragma("unroll") for (int m = 0; m < 4; ++m) _Pragma("unroll") for (int n = 0; n < 2; ++n) _Pragma("unroll") for (int k = 0; k < 2; ++k) \
;         acc[ai][bj][m][n] = __builtin_amdgcn_mfma_f32_16x16x32_bf16(Bt[n][k], At[m][k], acc[ai][bj][m][n], 0, 0, 0); __builtin_amdgcn_s_setprio(0); } while (0)
; #define PG8_WAIT_V(n) asm volatile("s_waitcnt vmcnt(" #n ")" ::: "memory")
; #define PG8_WAIT_L(n) asm volatile("s_waitcnt lgkmcnt(" #n ")" ::: "memory")
; #define PG8_BAR __builtin_amdgcn_s_barrier()
; #define PG8_SCHED __builtin_amdgcn_sched_barrier(0)
; #define ROWS8 _Pragma("unroll") for (int ai = 0; ai < 2; ++ai) _Pragma("unroll") for (int m = 0; m < 4; ++m) if (ai == 0 || !hf)
; template <class Epi>
; DI void gemm_phase(LAS unsigned char* lds, int wid, int K, int lda, int ldb, bool bperm, const Sched3& S, const Epi& E) {
;     ...
;             PG8_BAR; PG8_WAIT_L(0); if (full) PG8_MMA(1, 0, At, B0); PG8_BAR; PG8_SCHED;
;             PG8_STAGE(PG8_SB(1, 1), b3 + hstepB, voffB);
;             PG8_WAIT_V(6); PG8_BAR; if (full) PG8_MMA(1, 1, At, B1); PG8_BAR;
;     DI void operator()(const Acc& acc, const Unit& u, int wr, int wc, int fr, int fq) const {
;     ...
;             LOAD_ROW_RS(rsv, SSQ(PH == 5 ? 2 : 6), 1.f / 2048.f);
;             const int ac0 = u.pn * 128 + wc * 32 + 8 * fq;
;             ROWS8 { const int r = row0 + ai * HALF + m * 16; const float rs = rsv[ai][m];
;                 u32x4 w;
; #pragma unroll
;                 for (int bj = 0; bj < 2; ++bj) { const f32x4 g = acc[ai][bj][m][0] * rs, uu = acc[ai][bj][m][1] * rs;
;                     f32x4 a; a[0] = silu_f(g[0]) * uu[0]; a[1] = silu_f(g[1]) * uu[1]; a[2] = silu_f(g[2]) * uu[2]; a[3] = silu_f(g[3]) * uu[3];
;                     const u32x2 h = pk4(a); if (bj == 0) { w.x = h.x; w.y = h.y; } else { w.z = h.x; w.w = h.y; } }
	s_waitcnt lgkmcnt(0)
	s_setprio 1
	s_waitcnt lgkmcnt(0)
	v_mfma_f32_16x16x32_bf16 v[60:63], v[138:141], v[164:167], v[60:63]
	v_mfma_f32_16x16x32_bf16 v[56:59], v[146:149], v[164:167], v[56:59]
	v_mfma_f32_16x16x32_bf16 v[48:51], v[138:141], v[172:175], v[48:51]
	v_mfma_f32_16x16x32_bf16 v[40:43], v[146:149], v[172:175], v[40:43]
	v_mfma_f32_16x16x32_bf16 v[32:35], v[138:141], v[180:183], v[32:35]
	v_mfma_f32_16x16x32_bf16 v[24:27], v[146:149], v[180:183], v[24:27]
	v_mfma_f32_16x16x32_bf16 v[16:19], v[138:141], v[188:191], v[16:19]
	v_mfma_f32_16x16x32_bf16 v[8:11], v[146:149], v[188:191], v[8:11]
	v_mfma_f32_16x16x32_bf16 v[60:63], v[142:145], v[168:171], v[60:63]
	v_mfma_f32_16x16x32_bf16 v[56:59], v[150:153], v[168:171], v[56:59]
	v_mfma_f32_16x16x32_bf16 v[48:51], v[142:145], v[176:179], v[48:51]
	v_mfma_f32_16x16x32_bf16 v[40:43], v[150:153], v[176:179], v[40:43]
	v_mfma_f32_16x16x32_bf16 v[32:35], v[142:145], v[184:187], v[32:35]
	v_mfma_f32_16x16x32_bf16 v[24:27], v[150:153], v[184:187], v[24:27]
	v_mfma_f32_16x16x32_bf16 v[16:19], v[142:145], v[192:195], v[16:19]
	v_mfma_f32_16x16x32_bf16 v[8:11], v[150:153], v[192:195], v[8:11]
	s_setprio 0
	s_barrier
	s_add_u32 s30, s30, 0x80080
	s_addc_u32 s31, s31, 0
	s_add_i32 s36, s36, s43
	v_lshl_add_u64 v[138:139], s[30:31], 0, v[130:131]
	s_mov_b32 m0, s36
	s_nop 0
	global_load_lds_dwordx4 v[138:139], off
	v_lshl_add_u64 v[138:139], s[30:31], 0, v[128:129]
	s_add_i32 m0, s36, 0x2000
	s_nop 0
	global_load_lds_dwordx4 v[138:139], off
	s_waitcnt vmcnt(6)
	s_barrier
	s_setprio 1
	v_mfma_f32_16x16x32_bf16 v[52:55], v[196:199], v[164:167], v[52:55]
	v_mfma_f32_16x16x32_bf16 v[44:47], v[204:207], v[164:167], v[44:47]
	v_mfma_f32_16x16x32_bf16 v[36:39], v[196:199], v[172:175], v[36:39]
	v_mfma_f32_16x16x32_bf16 v[28:31], v[204:207], v[172:175], v[28:31]
	v_mfma_f32_16x16x32_bf16 v[20:23], v[196:199], v[180:183], v[20:23]
	v_mfma_f32_16x16x32_bf16 v[12:15], v[204:207], v[180:183], v[12:15]
	v_mfma_f32_16x16x32_bf16 v[4:7], v[196:199], v[188:191], v[4:7]
	v_mfma_f32_16x16x32_bf16 v[0:3], v[204:207], v[188:191], v[0:3]
	v_mfma_f32_16x16x32_bf16 v[52:55], v[200:203], v[168:171], v[52:55]
	v_mfma_f32_16x16x32_bf16 v[44:47], v[208:211], v[168:171], v[44:47]
	v_mfma_f32_16x16x32_bf16 v[36:39], v[200:203], v[176:179], v[36:39]
	v_mfma_f32_16x16x32_bf16 v[28:31], v[208:211], v[176:179], v[28:31]
	v_mfma_f32_16x16x32_bf16 v[20:23], v[200:203], v[184:187], v[20:23]
	v_mfma_f32_16x16x32_bf16 v[12:15], v[208:211], v[184:187], v[12:15]
	v_mfma_f32_16x16x32_bf16 v[4:7], v[200:203], v[192:195], v[4:7]
	v_mfma_f32_16x16x32_bf16 v[0:3], v[208:211], v[192:195], v[0:3]
	s_setprio 0
	s_add_i32 s57, s57, 2
	s_add_u32 s28, s28, 0x100
	s_addc_u32 s29, s29, 0
	s_add_u32 s15, s15, 0x100
	s_addc_u32 s17, s17, 0
	s_cmp_gt_u32 s57, 29
	s_barrier
	s_cbranch_scc0 .LBB0_705
	v_lshl_add_u32 v142, s22, 8, v155
	v_or_b32_e32 v156, 16, v142
	v_ashrrev_i32_e32 v157, 31, v156
	v_or_b32_e32 v152, 32, v142
	v_or_b32_e32 v150, 48, v142
	v_lshl_add_u64 v[138:139], v[156:157], 2, s[10:11]
	v_ashrrev_i32_e32 v153, 31, v152
	v_ashrrev_i32_e32 v151, 31, v150
	v_ashrrev_i32_e32 v143, 31, v142
	v_lshl_add_u64 v[140:141], v[152:153], 2, s[10:11]
	v_lshl_add_u64 v[144:145], v[150:151], 2, s[10:11]
	v_lshl_add_u64 v[146:147], v[142:143], 2, s[10:11]
	v_add_u32_e32 v148, 0x80, v142
	v_add_u32_e32 v146, 0x90, v142
	v_add_u32_e32 v144, 0xa0, v142
	v_add_u32_e32 v138, 0xb0, v142
	v_ashrrev_i32_e32 v149, 31, v148
	v_ashrrev_i32_e32 v147, 31, v146
	v_ashrrev_i32_e32 v145, 31, v144
	v_ashrrev_i32_e32 v139, 31, v138
	v_lshl_add_u64 v[140:141], v[148:149], 2, s[10:11]
	v_lshl_add_u64 v[164:165], v[146:147], 2, s[10:11]
	v_lshl_add_u64 v[166:167], v[144:145], 2, s[10:11]
	v_lshl_add_u64 v[168:169], v[138:139], 2, s[10:11]
	v_lshl_add_u32 v164, s56, 7, v159
	v_mov_b64_e32 v[140:141], s[12:13]
	v_ashrrev_i32_e32 v165, 31, v164
	v_mad_i64_i32 v[166:167], s[24:25], v142, s55, v[140:141]
	v_lshlrev_b64 v[142:143], 1, v[164:165]
	v_lshl_add_u64 v[164:165], v[166:167], 0, v[142:143]
	s_and_b64 vcc, exec, s[2:3]
	s_mov_b32 s56, s14
	s_mov_b32 s22, s16
	s_mov_b64 s[30:31], s[18:19]
	s_mov_b64 s[28:29], s[20:21]
	v_mov_b32_e32 v151, v221
	v_mov_b32_e32 v153, v222
	v_mov_b32_e32 v154, v223
	v_mov_b32_e32 v157, v220
	v_mov_b32_e32 v139, v224
	v_mov_b32_e32 v145, v225
	v_mov_b32_e32 v147, v226
	v_mov_b32_e32 v149, v227
	v_fmamk_f32 v151, v151, 0x3a000000, v163
	v_rsq_f32_e32 v168, v151
	v_fmamk_f32 v153, v153, 0x3a000000, v163
	v_fmamk_f32 v157, v157, 0x3a000000, v163
	v_rsq_f32_e32 v166, v157
	v_rsq_f32_e32 v170, v153
	v_mul_f32_e32 v118, v118, v168
	v_mul_f32_e32 v119, v119, v168
	v_mul_f32_e32 v116, v116, v168
	v_mul_f32_e32 v117, v117, v168
	v_mul_f32_e32 v126, v126, v166
	v_mul_f32_e32 v127, v127, v166
	v_mul_f32_e32 v124, v124, v166
	v_mul_f32_e32 v125, v125, v166
	v_mul_f32_e32 v114, v114, v166
	v_mul_f32_e32 v115, v115, v166
	v_mul_f32_e32 v112, v112, v166
	v_mul_f32_e32 v113, v113, v166
	v_mul_f32_e32 v122, v122, v166
	v_mul_f32_e32 v123, v123, v166
	v_mul_f32_e32 v120, v120, v166
	v_mul_f32_e32 v121, v121, v166
	v_mul_f32_e32 v110, v110, v166
	v_mul_f32_e32 v111, v111, v166
	v_mul_f32_e32 v108, v108, v166
	v_mul_f32_e32 v109, v109, v166
	v_mul_f32_e32 v151, 0xbfb8aa3b, v124
	v_mul_f32_e32 v153, 0xbfb8aa3b, v125
	v_mul_f32_e32 v157, 0xbfb8aa3b, v126
	v_mul_f32_e32 v166, 0xbfb8aa3b, v127
	v_mul_f32_e32 v167, 0xbfb8aa3b, v112
	v_mul_f32_e32 v169, 0xbfb8aa3b, v113
	v_mul_f32_e32 v171, 0xbfb8aa3b, v114
	v_mul_f32_e32 v172, 0xbfb8aa3b, v115
	v_exp_f32_e32 v151, v151
	v_exp_f32_e32 v153, v153
	v_exp_f32_e32 v157, v157
	v_exp_f32_e32 v166, v166
	v_exp_f32_e32 v167, v167
; DI u32x2 pk4(f32x4 v) { u32x2 r; r.x = pk2(v[0], v[1]); r.y = pk2(v[2], v[3]); return r; }
; DI float silu_f(float x) { return x * __builtin_amdgcn_rcpf(1.f + __builtin_amdgcn_exp2f(-1.4426950409f * x)); }
;     DI void operator()(const Acc& acc, const Unit& u, int wr, int wc, int fr, int fq) const {
;     ...
;                 for (int bj = 0; bj < 2; ++bj) { const f32x4 g = acc[ai][bj][m][0] * rs, uu = acc[ai][bj][m][1] * rs;
;                     f32x4 a; a[0] = silu_f(g[0]) * uu[0]; a[1] = silu_f(g[1]) * uu[1]; a[2] = silu_f(g[2]) * uu[2]; a[3] = silu_f(g[3]) * uu[3];
;                     const u32x2 h = pk4(a); if (bj == 0) { w.x = h.x; w.y = h.y; } else { w.z = h.x; w.w = h.y; } }
;                 *(u32x4*)(WSB(OFF_ACT) + (size_t)r * DFF + ac0) = w;
	v_exp_f32_e32 v169, v169
	v_exp_f32_e32 v171, v171
	v_exp_f32_e32 v172, v172
	v_mul_f32_e32 v173, 0xbfb8aa3b, v116
	v_exp_f32_e32 v178, v173
	v_add_f32_e32 v151, 1.0, v151
	v_add_f32_e32 v153, 1.0, v153
	v_add_f32_e32 v157, 1.0, v157
	v_add_f32_e32 v173, 1.0, v166
	v_add_f32_e32 v174, 1.0, v167
	v_add_f32_e32 v169, 1.0, v169
	v_add_f32_e32 v171, 1.0, v171
	v_add_f32_e32 v177, 1.0, v172
	v_rcp_f32_e32 v166, v151
	v_rcp_f32_e32 v167, v153
	v_rcp_f32_e32 v172, v157
	v_rcp_f32_e32 v173, v173
	v_rcp_f32_e32 v174, v174
	v_rcp_f32_e32 v175, v169
	v_rcp_f32_e32 v176, v171
	v_rcp_f32_e32 v177, v177
	v_mul_f32_e32 v124, v124, v166
	v_mul_f32_e32 v125, v125, v167
	v_mul_f32_e32 v126, v126, v172
	v_mul_f32_e32 v127, v127, v173
	v_mul_f32_e32 v112, v112, v174
	v_mul_f32_e32 v113, v113, v175
	v_mul_f32_e32 v114, v114, v176
	v_mul_f32_e32 v115, v115, v177
	v_mul_f32_e32 v120, v120, v124
	v_mul_f32_e32 v121, v121, v125
	v_mul_f32_e32 v122, v122, v126
	v_mul_f32_e32 v123, v123, v127
	v_mul_f32_e32 v112, v108, v112
	v_mul_f32_e32 v113, v109, v113
	v_mul_f32_e32 v114, v110, v114
	v_mul_f32_e32 v115, v111, v115
	v_cvt_pk_bf16_f32 v108, v120, v121
	v_cvt_pk_bf16_f32 v109, v122, v123
	v_cvt_pk_bf16_f32 v110, v112, v113
	v_cvt_pk_bf16_f32 v111, v114, v115
	global_store_dwordx4 v[164:165], v[108:111], off
	v_mul_f32_e32 v104, v104, v168
	v_mul_f32_e32 v105, v105, v168
	v_mul_f32_e32 v106, v106, v168
	v_mul_f32_e32 v107, v107, v168
	v_mul_f32_e32 v108, 0xbfb8aa3b, v117
	v_exp_f32_e32 v109, v108
	v_mul_f32_e32 v110, 0xbfb8aa3b, v118
	v_mul_f32_e32 v111, 0xbfb8aa3b, v119
	v_exp_f32_e32 v110, v110
	v_exp_f32_e32 v111, v111
	v_add_f32_e32 v108, 1.0, v178
	v_add_f32_e32 v109, 1.0, v109
	v_rcp_f32_e32 v108, v108
	v_rcp_f32_e32 v109, v109
	v_add_f32_e32 v110, 1.0, v110
	v_add_f32_e32 v111, 1.0, v111
	v_rcp_f32_e32 v110, v110
	v_rcp_f32_e32 v111, v111
	v_mul_f32_e32 v108, v116, v108
	v_mul_f32_e32 v109, v117, v109
	v_mul_f32_e32 v100, v100, v168
	v_mul_f32_e32 v101, v101, v168
	v_mul_f32_e32 v104, v104, v108
	v_mul_f32_e32 v105, v105, v109
	v_mul_f32_e32 v108, v118, v110
	v_mul_f32_e32 v109, v119, v111
	v_cvt_pk_bf16_f32 v104, v104, v105
	v_mul_f32_e32 v106, v106, v108
	v_mul_f32_e32 v107, v107, v109
	v_mul_f32_e32 v102, v102, v168
	v_mul_f32_e32 v103, v103, v168
	v_cvt_pk_bf16_f32 v105, v106, v107
	v_mul_f32_e32 v106, 0xbfb8aa3b, v100
	v_mul_f32_e32 v107, 0xbfb8aa3b, v101
	v_exp_f32_e32 v106, v106
	v_exp_f32_e32 v107, v107
	v_mul_f32_e32 v108, 0xbfb8aa3b, v102
	v_mul_f32_e32 v109, 0xbfb8aa3b, v103
	v_exp_f32_e32 v108, v108
	v_exp_f32_e32 v109, v109
	v_add_f32_e32 v106, 1.0, v106
	v_add_f32_e32 v107, 1.0, v107
	v_rcp_f32_e32 v106, v106
	v_rcp_f32_e32 v107, v107
	v_add_f32_e32 v108, 1.0, v108
	v_add_f32_e32 v109, 1.0, v109
	v_rcp_f32_e32 v108, v108
	v_rcp_f32_e32 v109, v109
	v_mul_f32_e32 v92, v92, v168
	v_mul_f32_e32 v93, v93, v168
	v_mul_f32_e32 v100, v100, v106
	v_mul_f32_e32 v101, v101, v107
	v_mul_f32_e32 v94, v94, v168
	v_mul_f32_e32 v95, v95, v168
	v_mul_f32_e32 v92, v92, v100
	v_mul_f32_e32 v93, v93, v101
	v_mul_f32_e32 v100, v102, v108
	v_mul_f32_e32 v101, v103, v109
	v_cvt_pk_bf16_f32 v106, v92, v93
	v_mul_f32_e32 v94, v94, v100
	v_mul_f32_e32 v95, v95, v101
	v_mad_i64_i32 v[92:93], s[24:25], v156, s55, v[140:141]
	v_cvt_pk_bf16_f32 v107, v94, v95
	v_lshl_add_u64 v[92:93], v[92:93], 0, v[142:143]
	global_store_dwordx4 v[92:93], v[104:107], off
	v_mul_f32_e32 v92, v98, v170
	v_mul_f32_e32 v93, v99, v170
	v_mul_f32_e32 v94, v96, v170
	v_mul_f32_e32 v95, v97, v170
	v_mul_f32_e32 v98, 0xbfb8aa3b, v92
	v_mul_f32_e32 v96, 0xbfb8aa3b, v94
	v_mul_f32_e32 v97, 0xbfb8aa3b, v95
	v_mul_f32_e32 v99, 0xbfb8aa3b, v93
	v_exp_f32_e32 v96, v96
	v_exp_f32_e32 v97, v97
	v_exp_f32_e32 v98, v98
	v_exp_f32_e32 v99, v99
	v_add_f32_e32 v96, 1.0, v96
	v_add_f32_e32 v97, 1.0, v97
	v_add_f32_e32 v98, 1.0, v98
	v_add_f32_e32 v99, 1.0, v99
	v_rcp_f32_e32 v96, v96
	v_rcp_f32_e32 v97, v97
	v_rcp_f32_e32 v98, v98
	v_rcp_f32_e32 v99, v99
	v_mul_f32_e32 v90, v90, v170
	v_mul_f32_e32 v91, v91, v170
	v_mul_f32_e32 v88, v88, v170
	v_mul_f32_e32 v89, v89, v170
	v_mul_f32_e32 v94, v94, v96
	v_mul_f32_e32 v95, v95, v97
	v_mul_f32_e32 v92, v92, v98
	v_mul_f32_e32 v93, v93, v99
	v_mul_f32_e32 v88, v88, v94
	v_mul_f32_e32 v89, v89, v95
	v_mul_f32_e32 v90, v90, v92
	v_mul_f32_e32 v91, v91, v93
	v_mul_f32_e32 v84, v84, v170
	v_mul_f32_e32 v85, v85, v170
	v_cvt_pk_bf16_f32 v88, v88, v89
	v_cvt_pk_bf16_f32 v89, v90, v91
	v_mul_f32_e32 v86, v86, v170
	v_mul_f32_e32 v87, v87, v170
	v_mul_f32_e32 v90, 0xbfb8aa3b, v84
	v_mul_f32_e32 v91, 0xbfb8aa3b, v85
	v_exp_f32_e32 v90, v90
	v_exp_f32_e32 v91, v91
	v_mul_f32_e32 v92, 0xbfb8aa3b, v86
	v_mul_f32_e32 v93, 0xbfb8aa3b, v87
	v_exp_f32_e32 v92, v92
	v_exp_f32_e32 v93, v93
	v_add_f32_e32 v90, 1.0, v90
	v_add_f32_e32 v91, 1.0, v91
	v_rcp_f32_e32 v90, v90
	v_rcp_f32_e32 v91, v91
	v_add_f32_e32 v92, 1.0, v92
	v_add_f32_e32 v93, 1.0, v93
	v_rcp_f32_e32 v92, v92
	v_rcp_f32_e32 v93, v93
	v_fmamk_f32 v154, v154, 0x3a000000, v163
	v_rsq_f32_e32 v154, v154
	v_mul_f32_e32 v76, v76, v170
	v_mul_f32_e32 v77, v77, v170
	v_mul_f32_e32 v84, v84, v90
	v_mul_f32_e32 v85, v85, v91
	v_mul_f32_e32 v78, v78, v170
	v_mul_f32_e32 v79, v79, v170
	v_mul_f32_e32 v76, v76, v84
	v_mul_f32_e32 v77, v77, v85
	v_mul_f32_e32 v84, v86, v92
	v_mul_f32_e32 v85, v87, v93
	v_cvt_pk_bf16_f32 v90, v76, v77
	v_mul_f32_e32 v78, v78, v84
	v_mul_f32_e32 v79, v79, v85
	v_mad_i64_i32 v[76:77], s[24:25], v152, s55, v[140:141]
	v_cvt_pk_bf16_f32 v91, v78, v79
	v_lshl_add_u64 v[76:77], v[76:77], 0, v[142:143]
	global_store_dwordx4 v[76:77], v[88:91], off
	v_mul_f32_e32 v76, v82, v154
	v_mul_f32_e32 v77, v83, v154
; DI u32x2 pk4(f32x4 v) { u32x2 r; r.x = pk2(v[0], v[1]); r.y = pk2(v[2], v[3]); return r; }
; DI float silu_f(float x) { return x * __builtin_amdgcn_rcpf(1.f + __builtin_amdgcn_exp2f(-1.4426950409f * x)); }
; #define ROWS8 _Pragma("unroll") for (int ai = 0; ai < 2; ++ai) _Pragma("unroll") for (int m = 0; m < 4; ++m) if (ai == 0 || !hf)
;     DI void operator()(const Acc& acc, const Unit& u, int wr, int wc, int fr, int fq) const {
;     ...
;             ROWS8 { const int r = row0 + ai * HALF + m * 16; const float rs = rsv[ai][m];
;                 u32x4 w;
; #pragma unroll
;                 for (int bj = 0; bj < 2; ++bj) { const f32x4 g = acc[ai][bj][m][0] * rs, uu = acc[ai][bj][m][1] * rs;
;                     f32x4 a; a[0] = silu_f(g[0]) * uu[0]; a[1] = silu_f(g[1]) * uu[1]; a[2] = silu_f(g[2]) * uu[2]; a[3] = silu_f(g[3]) * uu[3];
;                     const u32x2 h = pk4(a); if (bj == 0) { w.x = h.x; w.y = h.y; } else { w.z = h.x; w.w = h.y; } }
;                 *(u32x4*)(WSB(OFF_ACT) + (size_t)r * DFF + ac0) = w;
	v_mul_f32_e32 v78, v80, v154
	v_mul_f32_e32 v79, v81, v154
	v_mul_f32_e32 v82, 0xbfb8aa3b, v76
	v_mul_f32_e32 v80, 0xbfb8aa3b, v78
	v_mul_f32_e32 v81, 0xbfb8aa3b, v79
	v_mul_f32_e32 v83, 0xbfb8aa3b, v77
	v_exp_f32_e32 v80, v80
	v_exp_f32_e32 v81, v81
	v_exp_f32_e32 v82, v82
	v_exp_f32_e32 v83, v83
	v_add_f32_e32 v80, 1.0, v80
	v_add_f32_e32 v81, 1.0, v81
	v_add_f32_e32 v82, 1.0, v82
	v_add_f32_e32 v83, 1.0, v83
	v_rcp_f32_e32 v80, v80
	v_rcp_f32_e32 v81, v81
	v_rcp_f32_e32 v82, v82
	v_rcp_f32_e32 v83, v83
	v_mul_f32_e32 v74, v74, v154
	v_mul_f32_e32 v75, v75, v154
	v_mul_f32_e32 v72, v72, v154
	v_mul_f32_e32 v73, v73, v154
	v_mul_f32_e32 v78, v78, v80
	v_mul_f32_e32 v79, v79, v81
	v_mul_f32_e32 v76, v76, v82
	v_mul_f32_e32 v77, v77, v83
	v_mul_f32_e32 v72, v72, v78
	v_mul_f32_e32 v73, v73, v79
	v_mul_f32_e32 v74, v74, v76
	v_mul_f32_e32 v75, v75, v77
	v_mul_f32_e32 v68, v68, v154
	v_mul_f32_e32 v69, v69, v154
	v_cvt_pk_bf16_f32 v72, v72, v73
	v_cvt_pk_bf16_f32 v73, v74, v75
	v_mul_f32_e32 v70, v70, v154
	v_mul_f32_e32 v71, v71, v154
	v_mul_f32_e32 v74, 0xbfb8aa3b, v68
	v_mul_f32_e32 v75, 0xbfb8aa3b, v69
	v_exp_f32_e32 v74, v74
	v_exp_f32_e32 v75, v75
	v_mul_f32_e32 v76, 0xbfb8aa3b, v70
	v_mul_f32_e32 v77, 0xbfb8aa3b, v71
	v_exp_f32_e32 v76, v76
	v_exp_f32_e32 v77, v77
	v_add_f32_e32 v74, 1.0, v74
	v_add_f32_e32 v75, 1.0, v75
	v_rcp_f32_e32 v74, v74
	v_rcp_f32_e32 v75, v75
	v_add_f32_e32 v76, 1.0, v76
	v_add_f32_e32 v77, 1.0, v77
	v_rcp_f32_e32 v76, v76
	v_rcp_f32_e32 v77, v77
	v_mul_f32_e32 v64, v64, v154
	v_mul_f32_e32 v65, v65, v154
	v_mul_f32_e32 v68, v68, v74
	v_mul_f32_e32 v69, v69, v75
	v_mul_f32_e32 v66, v66, v154
	v_mul_f32_e32 v67, v67, v154
	v_mul_f32_e32 v64, v64, v68
	v_mul_f32_e32 v65, v65, v69
	v_mul_f32_e32 v68, v70, v76
	v_mul_f32_e32 v69, v71, v77
	v_cvt_pk_bf16_f32 v74, v64, v65
	v_mul_f32_e32 v66, v66, v68
	v_mul_f32_e32 v67, v67, v69
	v_mad_i64_i32 v[64:65], s[24:25], v150, s55, v[140:141]
	v_cvt_pk_bf16_f32 v75, v66, v67
	v_fmamk_f32 v66, v139, 0x3a000000, v163
	v_rsq_f32_e32 v68, v66
	v_lshl_add_u64 v[64:65], v[64:65], 0, v[142:143]
	global_store_dwordx4 v[64:65], v[72:75], off
	v_fmamk_f32 v65, v147, 0x3a000000, v163
	v_rsq_f32_e32 v66, v65
	v_fmamk_f32 v65, v145, 0x3a000000, v163
	v_mul_f32_e32 v60, v60, v68
	v_mul_f32_e32 v61, v61, v68
	v_rsq_f32_e32 v70, v65
	v_mul_f32_e32 v65, 0xbfb8aa3b, v60
	v_exp_f32_e32 v65, v65
	v_mul_f32_e32 v67, 0xbfb8aa3b, v61
	v_exp_f32_e32 v67, v67
	v_mul_f32_e32 v62, v62, v68
	v_mul_f32_e32 v63, v63, v68
	v_add_f32_e32 v65, 1.0, v65
	v_rcp_f32_e32 v72, v65
	v_add_f32_e32 v65, 1.0, v67
	v_mul_f32_e32 v67, 0xbfb8aa3b, v62
	v_mul_f32_e32 v58, v58, v68
	v_mul_f32_e32 v59, v59, v68
	v_exp_f32_e32 v67, v67
	v_mul_f32_e32 v69, 0xbfb8aa3b, v63
	v_exp_f32_e32 v69, v69
	v_rcp_f32_e32 v73, v65
	v_add_f32_e32 v65, 1.0, v67
	v_rcp_f32_e32 v74, v65
	v_add_f32_e32 v65, 1.0, v69
	v_rcp_f32_e32 v75, v65
	v_mul_f32_e32 v56, v56, v68
	v_mul_f32_e32 v57, v57, v68
	v_mul_f32_e32 v60, v60, v72
	v_mul_f32_e32 v61, v61, v73
	v_mul_f32_e32 v52, v52, v68
	v_mul_f32_e32 v53, v53, v68
	v_mul_f32_e32 v56, v56, v60
	v_mul_f32_e32 v57, v57, v61
	v_mul_f32_e32 v60, v62, v74
	v_mul_f32_e32 v61, v63, v75
	v_cvt_pk_bf16_f32 v56, v56, v57
	v_mul_f32_e32 v58, v58, v60
	v_mul_f32_e32 v59, v59, v61
	v_mul_f32_e32 v54, v54, v68
	v_mul_f32_e32 v55, v55, v68
	v_cvt_pk_bf16_f32 v57, v58, v59
	v_mul_f32_e32 v58, 0xbfb8aa3b, v52
	v_mul_f32_e32 v59, 0xbfb8aa3b, v53
	v_exp_f32_e32 v58, v58
	v_exp_f32_e32 v59, v59
	v_mul_f32_e32 v60, 0xbfb8aa3b, v54
	v_mul_f32_e32 v61, 0xbfb8aa3b, v55
	v_exp_f32_e32 v60, v60
	v_exp_f32_e32 v61, v61
	v_add_f32_e32 v58, 1.0, v58
	v_add_f32_e32 v59, 1.0, v59
	v_rcp_f32_e32 v58, v58
	v_rcp_f32_e32 v59, v59
	v_add_f32_e32 v60, 1.0, v60
	v_add_f32_e32 v61, 1.0, v61
	v_rcp_f32_e32 v60, v60
	v_rcp_f32_e32 v61, v61
	v_mul_f32_e32 v44, v44, v68
	v_mul_f32_e32 v45, v45, v68
	v_mul_f32_e32 v52, v52, v58
	v_mul_f32_e32 v53, v53, v59
	v_mul_f32_e32 v46, v46, v68
	v_mul_f32_e32 v47, v47, v68
	v_mul_f32_e32 v44, v44, v52
	v_mul_f32_e32 v45, v45, v53
	v_mul_f32_e32 v52, v54, v60
	v_mul_f32_e32 v53, v55, v61
	v_cvt_pk_bf16_f32 v58, v44, v45
	v_mul_f32_e32 v46, v46, v52
	v_mul_f32_e32 v47, v47, v53
	v_mad_i64_i32 v[44:45], s[24:25], v148, s55, v[140:141]
	v_cvt_pk_bf16_f32 v59, v46, v47
	v_lshl_add_u64 v[44:45], v[44:45], 0, v[142:143]
	global_store_dwordx4 v[44:45], v[56:59], off
	v_mul_f32_e32 v44, v50, v70
	v_mul_f32_e32 v45, v51, v70
	v_mul_f32_e32 v46, v48, v70
	v_mul_f32_e32 v47, v49, v70
	v_mul_f32_e32 v50, 0xbfb8aa3b, v44
	v_mul_f32_e32 v48, 0xbfb8aa3b, v46
	v_mul_f32_e32 v49, 0xbfb8aa3b, v47
	v_mul_f32_e32 v51, 0xbfb8aa3b, v45
	v_exp_f32_e32 v48, v48
	v_exp_f32_e32 v49, v49
	v_exp_f32_e32 v50, v50
	v_exp_f32_e32 v51, v51
	v_add_f32_e32 v48, 1.0, v48
	v_add_f32_e32 v49, 1.0, v49
	v_add_f32_e32 v50, 1.0, v50
	v_add_f32_e32 v51, 1.0, v51
	v_rcp_f32_e32 v48, v48
	v_rcp_f32_e32 v49, v49
	v_rcp_f32_e32 v50, v50
	v_rcp_f32_e32 v51, v51
	v_mul_f32_e32 v42, v42, v70
	v_mul_f32_e32 v43, v43, v70
	v_mul_f32_e32 v40, v40, v70
	v_mul_f32_e32 v41, v41, v70
	v_mul_f32_e32 v46, v46, v48
	v_mul_f32_e32 v47, v47, v49
	v_mul_f32_e32 v44, v44, v50
	v_mul_f32_e32 v45, v45, v51
	v_mul_f32_e32 v40, v40, v46
	v_mul_f32_e32 v41, v41, v47
	v_mul_f32_e32 v42, v42, v44
	v_mul_f32_e32 v43, v43, v45
	v_mul_f32_e32 v36, v36, v70
	v_mul_f32_e32 v37, v37, v70
	v_cvt_pk_bf16_f32 v40, v40, v41
	v_cvt_pk_bf16_f32 v41, v42, v43
; DI u32x2 pk4(f32x4 v) { u32x2 r; r.x = pk2(v[0], v[1]); r.y = pk2(v[2], v[3]); return r; }
; DI float silu_f(float x) { return x * __builtin_amdgcn_rcpf(1.f + __builtin_amdgcn_exp2f(-1.4426950409f * x)); }
; #define ROWS8 _Pragma("unroll") for (int ai = 0; ai < 2; ++ai) _Pragma("unroll") for (int m = 0; m < 4; ++m) if (ai == 0 || !hf)
;     DI void operator()(const Acc& acc, const Unit& u, int wr, int wc, int fr, int fq) const {
;     ...
;             ROWS8 { const int r = row0 + ai * HALF + m * 16; const float rs = rsv[ai][m];
;                 u32x4 w;
; #pragma unroll
;                 for (int bj = 0; bj < 2; ++bj) { const f32x4 g = acc[ai][bj][m][0] * rs, uu = acc[ai][bj][m][1] * rs;
;                     f32x4 a; a[0] = silu_f(g[0]) * uu[0]; a[1] = silu_f(g[1]) * uu[1]; a[2] = silu_f(g[2]) * uu[2]; a[3] = silu_f(g[3]) * uu[3];
;                     const u32x2 h = pk4(a); if (bj == 0) { w.x = h.x; w.y = h.y; } else { w.z = h.x; w.w = h.y; } }
;                 *(u32x4*)(WSB(OFF_ACT) + (size_t)r * DFF + ac0) = w;
;             }
	v_mul_f32_e32 v38, v38, v70
	v_mul_f32_e32 v39, v39, v70
	v_mul_f32_e32 v42, 0xbfb8aa3b, v36
	v_mul_f32_e32 v43, 0xbfb8aa3b, v37
	v_exp_f32_e32 v42, v42
	v_exp_f32_e32 v43, v43
	v_mul_f32_e32 v44, 0xbfb8aa3b, v38
	v_mul_f32_e32 v45, 0xbfb8aa3b, v39
	v_exp_f32_e32 v44, v44
	v_exp_f32_e32 v45, v45
	v_add_f32_e32 v42, 1.0, v42
	v_add_f32_e32 v43, 1.0, v43
	v_rcp_f32_e32 v42, v42
	v_rcp_f32_e32 v43, v43
	v_add_f32_e32 v44, 1.0, v44
	v_add_f32_e32 v45, 1.0, v45
	v_rcp_f32_e32 v44, v44
	v_rcp_f32_e32 v45, v45
	v_mul_f32_e32 v28, v28, v70
	v_mul_f32_e32 v29, v29, v70
	v_mul_f32_e32 v36, v36, v42
	v_mul_f32_e32 v37, v37, v43
	v_mul_f32_e32 v30, v30, v70
	v_mul_f32_e32 v31, v31, v70
	v_mul_f32_e32 v28, v28, v36
	v_mul_f32_e32 v29, v29, v37
	v_mul_f32_e32 v36, v38, v44
	v_mul_f32_e32 v37, v39, v45
	v_cvt_pk_bf16_f32 v42, v28, v29
	v_mul_f32_e32 v30, v30, v36
	v_mul_f32_e32 v31, v31, v37
	v_mad_i64_i32 v[28:29], s[24:25], v146, s55, v[140:141]
	v_cvt_pk_bf16_f32 v43, v30, v31
	v_lshl_add_u64 v[28:29], v[28:29], 0, v[142:143]
	global_store_dwordx4 v[28:29], v[40:43], off
	v_mul_f32_e32 v28, v34, v66
	v_mul_f32_e32 v29, v35, v66
	v_mul_f32_e32 v30, v32, v66
	v_mul_f32_e32 v31, v33, v66
	v_mul_f32_e32 v34, 0xbfb8aa3b, v28
	v_mul_f32_e32 v32, 0xbfb8aa3b, v30
	v_mul_f32_e32 v33, 0xbfb8aa3b, v31
	v_mul_f32_e32 v35, 0xbfb8aa3b, v29
	v_exp_f32_e32 v32, v32
	v_exp_f32_e32 v33, v33
	v_exp_f32_e32 v34, v34
	v_exp_f32_e32 v35, v35
	v_add_f32_e32 v32, 1.0, v32
	v_add_f32_e32 v33, 1.0, v33
	v_add_f32_e32 v34, 1.0, v34
	v_add_f32_e32 v35, 1.0, v35
	v_rcp_f32_e32 v32, v32
	v_rcp_f32_e32 v33, v33
	v_rcp_f32_e32 v34, v34
	v_rcp_f32_e32 v35, v35
	v_mul_f32_e32 v26, v26, v66
	v_mul_f32_e32 v27, v27, v66
	v_mul_f32_e32 v24, v24, v66
	v_mul_f32_e32 v25, v25, v66
	v_mul_f32_e32 v30, v30, v32
	v_mul_f32_e32 v31, v31, v33
	v_mul_f32_e32 v28, v28, v34
	v_mul_f32_e32 v29, v29, v35
	v_mul_f32_e32 v24, v24, v30
	v_mul_f32_e32 v25, v25, v31
	v_mul_f32_e32 v26, v26, v28
	v_mul_f32_e32 v27, v27, v29
	v_mul_f32_e32 v20, v20, v66
	v_mul_f32_e32 v21, v21, v66
	v_cvt_pk_bf16_f32 v24, v24, v25
	v_cvt_pk_bf16_f32 v25, v26, v27
	v_mul_f32_e32 v22, v22, v66
	v_mul_f32_e32 v23, v23, v66
	v_mul_f32_e32 v26, 0xbfb8aa3b, v20
	v_mul_f32_e32 v27, 0xbfb8aa3b, v21
	v_exp_f32_e32 v26, v26
	v_exp_f32_e32 v27, v27
	v_mul_f32_e32 v28, 0xbfb8aa3b, v22
	v_mul_f32_e32 v29, 0xbfb8aa3b, v23
	v_exp_f32_e32 v28, v28
	v_exp_f32_e32 v29, v29
	v_add_f32_e32 v26, 1.0, v26
	v_add_f32_e32 v27, 1.0, v27
	v_rcp_f32_e32 v26, v26
	v_rcp_f32_e32 v27, v27
	v_add_f32_e32 v28, 1.0, v28
	v_add_f32_e32 v29, 1.0, v29
	v_rcp_f32_e32 v28, v28
	v_rcp_f32_e32 v29, v29
	v_fmamk_f32 v64, v149, 0x3a000000, v163
	v_rsq_f32_e32 v64, v64
	v_mul_f32_e32 v12, v12, v66
	v_mul_f32_e32 v13, v13, v66
	v_mul_f32_e32 v20, v20, v26
	v_mul_f32_e32 v21, v21, v27
	v_mul_f32_e32 v14, v14, v66
	v_mul_f32_e32 v15, v15, v66
	v_mul_f32_e32 v12, v12, v20
	v_mul_f32_e32 v13, v13, v21
	v_mul_f32_e32 v20, v22, v28
	v_mul_f32_e32 v21, v23, v29
	v_cvt_pk_bf16_f32 v26, v12, v13
	v_mul_f32_e32 v14, v14, v20
	v_mul_f32_e32 v15, v15, v21
	v_mad_i64_i32 v[12:13], s[24:25], v144, s55, v[140:141]
	v_cvt_pk_bf16_f32 v27, v14, v15
	v_lshl_add_u64 v[12:13], v[12:13], 0, v[142:143]
	global_store_dwordx4 v[12:13], v[24:27], off
	v_mul_f32_e32 v12, v18, v64
	v_mul_f32_e32 v13, v19, v64
	v_mul_f32_e32 v14, v16, v64
	v_mul_f32_e32 v15, v17, v64
	v_mul_f32_e32 v18, 0xbfb8aa3b, v12
	v_mul_f32_e32 v16, 0xbfb8aa3b, v14
	v_mul_f32_e32 v17, 0xbfb8aa3b, v15
	v_mul_f32_e32 v19, 0xbfb8aa3b, v13
	v_exp_f32_e32 v16, v16
	v_exp_f32_e32 v17, v17
	v_exp_f32_e32 v18, v18
	v_exp_f32_e32 v19, v19
	v_add_f32_e32 v16, 1.0, v16
	v_add_f32_e32 v17, 1.0, v17
	v_add_f32_e32 v18, 1.0, v18
	v_add_f32_e32 v19, 1.0, v19
	v_rcp_f32_e32 v16, v16
	v_rcp_f32_e32 v17, v17
	v_rcp_f32_e32 v18, v18
	v_rcp_f32_e32 v19, v19
	v_mul_f32_e32 v10, v10, v64
	v_mul_f32_e32 v11, v11, v64
	v_mul_f32_e32 v8, v8, v64
	v_mul_f32_e32 v9, v9, v64
	v_mul_f32_e32 v14, v14, v16
	v_mul_f32_e32 v15, v15, v17
	v_mul_f32_e32 v12, v12, v18
	v_mul_f32_e32 v13, v13, v19
	v_mul_f32_e32 v8, v8, v14
	v_mul_f32_e32 v9, v9, v15
	v_mul_f32_e32 v10, v10, v12
	v_mul_f32_e32 v11, v11, v13
	v_mul_f32_e32 v4, v4, v64
	v_mul_f32_e32 v5, v5, v64
	v_cvt_pk_bf16_f32 v8, v8, v9
	v_cvt_pk_bf16_f32 v9, v10, v11
	v_mul_f32_e32 v6, v6, v64
	v_mul_f32_e32 v7, v7, v64
	v_mul_f32_e32 v10, 0xbfb8aa3b, v4
	v_mul_f32_e32 v11, 0xbfb8aa3b, v5
	v_exp_f32_e32 v10, v10
	v_exp_f32_e32 v11, v11
	v_mul_f32_e32 v12, 0xbfb8aa3b, v6
	v_mul_f32_e32 v13, 0xbfb8aa3b, v7
	v_exp_f32_e32 v12, v12
	v_exp_f32_e32 v13, v13
	v_add_f32_e32 v10, 1.0, v10
	v_add_f32_e32 v11, 1.0, v11
	v_rcp_f32_e32 v10, v10
	v_rcp_f32_e32 v11, v11
	v_add_f32_e32 v12, 1.0, v12
	v_add_f32_e32 v13, 1.0, v13
	v_rcp_f32_e32 v12, v12
	v_rcp_f32_e32 v13, v13
	v_mul_f32_e32 v0, v0, v64
	v_mul_f32_e32 v1, v1, v64
	v_mul_f32_e32 v4, v4, v10
	v_mul_f32_e32 v5, v5, v11
	v_mul_f32_e32 v2, v2, v64
	v_mul_f32_e32 v3, v3, v64
	v_mul_f32_e32 v0, v0, v4
	v_mul_f32_e32 v1, v1, v5
	v_mul_f32_e32 v4, v6, v12
	v_mul_f32_e32 v5, v7, v13
	v_cvt_pk_bf16_f32 v10, v0, v1
	v_mul_f32_e32 v2, v2, v4
	v_mul_f32_e32 v3, v3, v5
	v_mad_i64_i32 v[0:1], s[24:25], v138, s55, v[140:141]
	v_cvt_pk_bf16_f32 v11, v2, v3
	v_lshl_add_u64 v[0:1], v[0:1], 0, v[142:143]
	global_store_dwordx4 v[0:1], v[8:11], off
	s_cbranch_vccz .LBB0_702
	s_waitcnt vmcnt(0)
	s_cmpk_gt_u32 s88, 0xff
	s_cbranch_scc1 .LBB0_709
	s_barrier

; #define PG8_STAGE(bufoff, gbase, voff) do { _Pragma("unroll") for (int _i = 0; _i < 2; ++_i) \
;         __builtin_amdgcn_global_load_lds((const unsigned*)((const char*)(gbase) + (voff)[_i]), (LAS unsigned*)(lds + (bufoff) + ldsw + _i * 8192), 16, 0, 0); } while (0)
; #define PG8_LDA(dst, b, h) do { _Pragma("unroll") for (int m = 0; m < 4; ++m) _Pragma("unroll") for (int k = 0; k < 2; ++k) dst[m][k] = *(const LAS bf16x8*)(lds + PG8_SA(b, h) + aoff + m * 2048 + k * 1024); } while (0)
; #define PG8_LDB(dst, b, h) do { _Pragma("unroll") for (int n = 0; n < 2; ++n) _Pragma("unroll") for (int k = 0; k < 2; ++k) dst[n][k] = *(const LAS bf16x8*)(lds + PG8_SB(b, h) + boff + n * 2048 + k * 1024); } while (0)
; #define PG8_MMA(ai, bj, At, Bt) do { __builtin_amdgcn_s_setprio(1); _Pragma("unroll") for (int m = 0; m < 4; ++m) _Pragma("unroll") for (int n = 0; n < 2; ++n) _Pragma("unroll") for (int k = 0; k < 2; ++k) \
;         acc[ai][bj][m][n] = __builtin_amdgcn_mfma_f32_16x16x32_bf16(Bt[n][k], At[m][k], acc[ai][bj][m][n], 0, 0, 0); __builtin_amdgcn_s_setprio(0); } while (0)
; #define PG8_WAIT_V(n) asm volatile("s_waitcnt vmcnt(" #n ")" ::: "memory")
; #define PG8_WAIT_L(n) asm volatile("s_waitcnt lgkmcnt(" #n ")" ::: "memory")
; #define PG8_BAR __builtin_amdgcn_s_barrier()
; #define PG8_SCHED __builtin_amdgcn_sched_barrier(0)
; template <class Epi>
; DI void gemm_phase(LAS unsigned char* lds, int wid, int K, int lda, int ldb, bool bperm, const Sched3& S, const Epi& E) {
;     ...
;             PG8_LDB(B0, 0, 0); PG8_SCHED; PG8_LDA(At, 0, 0); PG8_STAGE(PG8_SA(1, 1), a1 + hA, voffA);
;             PG8_WAIT_L(8); PG8_BAR; PG8_WAIT_L(0); PG8_MMA(0, 0, At, B0); PG8_BAR; PG8_SCHED;
;             PG8_LDB(B1, 0, 1); PG8_STAGE(PG8_SB(0, 0), b2, voffB);
;             PG8_BAR; PG8_WAIT_L(0); PG8_MMA(0, 1, At, B1); PG8_BAR;
;             PG8_LDA(At, 0, 1); PG8_STAGE(PG8_SA(0, 0), a2, voffA);
;             PG8_BAR; PG8_WAIT_L(0); if (full) PG8_MMA(1, 0, At, B0); PG8_BAR; PG8_SCHED;
;             PG8_STAGE(PG8_SB(0, 1), b2 + hstepB, voffB);
;             PG8_WAIT_V(6); PG8_BAR; if (full) PG8_MMA(1, 1, At, B1); PG8_BAR;
.LBB0_785:
	ds_read_b128 v[128:131], v185
	ds_read_b128 v[132:135], v185 offset:1024
	ds_read_b128 v[136:139], v185 offset:2048
	ds_read_b128 v[140:143], v185 offset:3072
	s_add_u32 s28, s26, 0x100
	s_addc_u32 s29, s27, 0
	s_cmpk_eq_i32 s62, 0x54
	s_cselect_b32 s37, s23, s29
	s_cselect_b32 s36, s22, s28
	s_cselect_b32 s31, s25, s61
	s_cselect_b32 s30, s24, s60
	v_lshl_add_u64 v[178:179], s[26:27], 0, v[156:157]
	s_add_i32 m0, s44, 0xc000
	ds_read_b128 v[144:147], v186
	ds_read_b128 v[148:151], v186 offset:1024
	ds_read_b128 v[162:165], v186 offset:2048
	ds_read_b128 v[166:169], v186 offset:3072
	ds_read_b128 v[170:173], v186 offset:4096
	ds_read_b128 v[174:177], v186 offset:5120
	ds_read_b128 v[188:191], v186 offset:6144
	ds_read_b128 v[192:195], v186 offset:7168
	global_load_lds_dwordx4 v[178:179], off
	v_lshl_add_u64 v[178:179], s[26:27], 0, v[158:159]
	s_add_i32 m0, s44, 0xe000
	s_nop 0
	global_load_lds_dwordx4 v[178:179], off
	s_waitcnt lgkmcnt(8)
	s_barrier
	s_waitcnt lgkmcnt(0)
	s_setprio 1
	s_waitcnt lgkmcnt(0)
	v_mfma_f32_16x16x32_bf16 v[124:127], v[128:131], v[144:147], v[124:127]
	v_mfma_f32_16x16x32_bf16 v[120:123], v[136:139], v[144:147], v[120:123]
	v_mfma_f32_16x16x32_bf16 v[108:111], v[128:131], v[162:165], v[108:111]
	v_mfma_f32_16x16x32_bf16 v[104:107], v[136:139], v[162:165], v[104:107]
	v_mfma_f32_16x16x32_bf16 v[92:95], v[128:131], v[170:173], v[92:95]
	v_mfma_f32_16x16x32_bf16 v[88:91], v[136:139], v[170:173], v[88:91]
	v_mfma_f32_16x16x32_bf16 v[76:79], v[128:131], v[188:191], v[76:79]
	v_mfma_f32_16x16x32_bf16 v[72:75], v[136:139], v[188:191], v[72:75]
	v_mfma_f32_16x16x32_bf16 v[124:127], v[132:135], v[148:151], v[124:127]
	v_mfma_f32_16x16x32_bf16 v[120:123], v[140:143], v[148:151], v[120:123]
	v_mfma_f32_16x16x32_bf16 v[108:111], v[132:135], v[166:169], v[108:111]
	v_mfma_f32_16x16x32_bf16 v[104:107], v[140:143], v[166:169], v[104:107]
	v_mfma_f32_16x16x32_bf16 v[92:95], v[132:135], v[174:177], v[92:95]
	v_mfma_f32_16x16x32_bf16 v[88:91], v[140:143], v[174:177], v[88:91]
	v_mfma_f32_16x16x32_bf16 v[76:79], v[132:135], v[192:195], v[76:79]
	v_mfma_f32_16x16x32_bf16 v[72:75], v[140:143], v[192:195], v[72:75]
	s_setprio 0
	s_barrier
	s_add_i32 s26, s53, s43
	v_lshl_add_u64 v[178:179], s[30:31], 0, v[152:153]
	s_mov_b32 m0, s26
	ds_read_b128 v[196:199], v187
	ds_read_b128 v[200:203], v187 offset:1024
	ds_read_b128 v[204:207], v187 offset:2048
	ds_read_b128 v[208:211], v187 offset:3072
	global_load_lds_dwordx4 v[178:179], off
	v_lshl_add_u64 v[212:213], s[30:31], 0, v[154:155]
	s_add_i32 m0, s26, 0x2000
	s_nop 0
	global_load_lds_dwordx4 v[212:213], off
	s_barrier
	s_waitcnt lgkmcnt(0)
	s_setprio 1
	s_waitcnt lgkmcnt(0)
	v_mfma_f32_16x16x32_bf16 v[116:119], v[196:199], v[144:147], v[116:119]
	v_mfma_f32_16x16x32_bf16 v[112:115], v[204:207], v[144:147], v[112:115]
	v_mfma_f32_16x16x32_bf16 v[100:103], v[196:199], v[162:165], v[100:103]
	v_mfma_f32_16x16x32_bf16 v[96:99], v[204:207], v[162:165], v[96:99]
	v_mfma_f32_16x16x32_bf16 v[84:87], v[196:199], v[170:173], v[84:87]
	v_mfma_f32_16x16x32_bf16 v[80:83], v[204:207], v[170:173], v[80:83]
	v_mfma_f32_16x16x32_bf16 v[68:71], v[196:199], v[188:191], v[68:71]
	v_mfma_f32_16x16x32_bf16 v[64:67], v[204:207], v[188:191], v[64:67]
	v_mfma_f32_16x16x32_bf16 v[116:119], v[200:203], v[148:151], v[116:119]
	v_mfma_f32_16x16x32_bf16 v[112:115], v[208:211], v[148:151], v[112:115]
	v_mfma_f32_16x16x32_bf16 v[100:103], v[200:203], v[166:169], v[100:103]
	v_mfma_f32_16x16x32_bf16 v[96:99], v[208:211], v[166:169], v[96:99]
	v_mfma_f32_16x16x32_bf16 v[84:87], v[200:203], v[174:177], v[84:87]
	v_mfma_f32_16x16x32_bf16 v[80:83], v[208:211], v[174:177], v[80:83]
	v_mfma_f32_16x16x32_bf16 v[68:71], v[200:203], v[192:195], v[68:71]
	v_mfma_f32_16x16x32_bf16 v[64:67], v[208:211], v[192:195], v[64:67]
	s_setprio 0
	s_mov_b32 m0, s44
	v_lshl_add_u64 v[214:215], s[36:37], 0, v[152:153]
	s_barrier
	ds_read_b128 v[144:147], v186 offset:16384
	ds_read_b128 v[148:151], v186 offset:17408
	ds_read_b128 v[162:165], v186 offset:18432
	ds_read_b128 v[166:169], v186 offset:19456
	ds_read_b128 v[170:173], v186 offset:20480
	ds_read_b128 v[174:177], v186 offset:21504
	ds_read_b128 v[188:191], v186 offset:22528
	ds_read_b128 v[192:195], v186 offset:23552
	global_load_lds_dwordx4 v[214:215], off
	v_lshl_add_u64 v[216:217], s[36:37], 0, v[154:155]
	s_mov_b32 m0, s45
	s_nop 0
	global_load_lds_dwordx4 v[216:217], off
	s_barrier
	s_waitcnt lgkmcnt(0)
	s_setprio 1
	s_waitcnt lgkmcnt(0)
	v_mfma_f32_16x16x32_bf16 v[60:63], v[128:131], v[144:147], v[60:63]
	v_mfma_f32_16x16x32_bf16 v[56:59], v[136:139], v[144:147], v[56:59]
	v_mfma_f32_16x16x32_bf16 v[44:47], v[128:131], v[162:165], v[44:47]
	v_mfma_f32_16x16x32_bf16 v[40:43], v[136:139], v[162:165], v[40:43]
	v_mfma_f32_16x16x32_bf16 v[28:31], v[128:131], v[170:173], v[28:31]
	v_mfma_f32_16x16x32_bf16 v[24:27], v[136:139], v[170:173], v[24:27]
	v_mfma_f32_16x16x32_bf16 v[12:15], v[128:131], v[188:191], v[12:15]
	v_mfma_f32_16x16x32_bf16 v[8:11], v[136:139], v[188:191], v[8:11]
	v_mfma_f32_16x16x32_bf16 v[60:63], v[132:135], v[148:151], v[60:63]
	v_mfma_f32_16x16x32_bf16 v[56:59], v[140:143], v[148:151], v[56:59]
	v_mfma_f32_16x16x32_bf16 v[44:47], v[132:135], v[166:169], v[44:47]
	v_mfma_f32_16x16x32_bf16 v[40:43], v[140:143], v[166:169], v[40:43]
	v_mfma_f32_16x16x32_bf16 v[28:31], v[132:135], v[174:177], v[28:31]
	v_mfma_f32_16x16x32_bf16 v[24:27], v[140:143], v[174:177], v[24:27]
	v_mfma_f32_16x16x32_bf16 v[12:15], v[132:135], v[192:195], v[12:15]
	v_mfma_f32_16x16x32_bf16 v[8:11], v[140:143], v[192:195], v[8:11]
	s_setprio 0
	s_barrier
; #define PG8_STAGE(bufoff, gbase, voff) do { _Pragma("unroll") for (int _i = 0; _i < 2; ++_i) \
;         __builtin_amdgcn_global_load_lds((const unsigned*)((const char*)(gbase) + (voff)[_i]), (LAS unsigned*)(lds + (bufoff) + ldsw + _i * 8192), 16, 0, 0); } while (0)
; #define PG8_LDA(dst, b, h) do { _Pragma("unroll") for (int m = 0; m < 4; ++m) _Pragma("unroll") for (int k = 0; k < 2; ++k) dst[m][k] = *(const LAS bf16x8*)(lds + PG8_SA(b, h) + aoff + m * 2048 + k * 1024); } while (0)
; #define PG8_LDB(dst, b, h) do { _Pragma("unroll") for (int n = 0; n < 2; ++n) _Pragma("unroll") for (int k = 0; k < 2; ++k) dst[n][k] = *(const LAS bf16x8*)(lds + PG8_SB(b, h) + boff + n * 2048 + k * 1024); } while (0)
; #define PG8_MMA(ai, bj, At, Bt) do { __builtin_amdgcn_s_setprio(1); _Pragma("unroll") for (int m = 0; m < 4; ++m) _Pragma("unroll") for (int n = 0; n < 2; ++n) _Pragma("unroll") for (int k = 0; k < 2; ++k) \
;         acc[ai][bj][m][n] = __builtin_amdgcn_mfma_f32_16x16x32_bf16(Bt[n][k], At[m][k], acc[ai][bj][m][n], 0, 0, 0); __builtin_amdgcn_s_setprio(0); } while (0)
; #define PG8_WAIT_V(n) asm volatile("s_waitcnt vmcnt(" #n ")" ::: "memory")
; #define PG8_WAIT_L(n) asm volatile("s_waitcnt lgkmcnt(" #n ")" ::: "memory")
; #define PG8_BAR __builtin_amdgcn_s_barrier()
; #define PG8_SCHED __builtin_amdgcn_sched_barrier(0)
; template <class Epi>
; DI void gemm_phase(LAS unsigned char* lds, int wid, int K, int lda, int ldb, bool bperm, const Sched3& S, const Epi& E) {
;     ...
;             PG8_STAGE(PG8_SB(0, 1), b2 + hstepB, voffB);
;             PG8_WAIT_V(6); PG8_BAR; if (full) PG8_MMA(1, 1, At, B1); PG8_BAR;
;             PG8_LDB(B0, 1, 0); PG8_SCHED; PG8_LDA(At, 1, 0); PG8_STAGE(PG8_SA(0, 1), a2 + h2, voffA);
;             PG8_WAIT_L(8); PG8_BAR; PG8_WAIT_L(0); PG8_MMA(0, 0, At, B0); PG8_BAR; PG8_SCHED;
;             PG8_LDB(B1, 1, 1); PG8_STAGE(PG8_SB(1, 0), b3, voffB);
;             PG8_BAR; PG8_WAIT_L(0); PG8_MMA(0, 1, At, B1); PG8_BAR;
;             PG8_LDA(At, 1, 1); PG8_STAGE(PG8_SA(1, 0), a3, voffA);
	s_add_u32 s26, s30, 0x160000
	s_addc_u32 s27, s31, 0
	s_add_i32 s63, s54, s43
	v_lshl_add_u64 v[128:129], s[26:27], 0, v[152:153]
	s_mov_b32 m0, s63
	s_nop 0
	global_load_lds_dwordx4 v[128:129], off
	v_lshl_add_u64 v[128:129], s[26:27], 0, v[154:155]
	s_add_i32 m0, s63, 0x2000
	s_nop 0
	global_load_lds_dwordx4 v[128:129], off
	s_waitcnt vmcnt(6)
	s_barrier
	s_setprio 1
	v_mfma_f32_16x16x32_bf16 v[52:55], v[196:199], v[144:147], v[52:55]
	v_mfma_f32_16x16x32_bf16 v[48:51], v[204:207], v[144:147], v[48:51]
	v_mfma_f32_16x16x32_bf16 v[36:39], v[196:199], v[162:165], v[36:39]
	v_mfma_f32_16x16x32_bf16 v[32:35], v[204:207], v[162:165], v[32:35]
	v_mfma_f32_16x16x32_bf16 v[20:23], v[196:199], v[170:173], v[20:23]
	v_mfma_f32_16x16x32_bf16 v[16:19], v[204:207], v[170:173], v[16:19]
	v_mfma_f32_16x16x32_bf16 v[4:7], v[196:199], v[188:191], v[4:7]
	v_mfma_f32_16x16x32_bf16 v[0:3], v[204:207], v[188:191], v[0:3]
	v_mfma_f32_16x16x32_bf16 v[52:55], v[200:203], v[148:151], v[52:55]
	v_mfma_f32_16x16x32_bf16 v[48:51], v[208:211], v[148:151], v[48:51]
	v_mfma_f32_16x16x32_bf16 v[36:39], v[200:203], v[166:169], v[36:39]
	v_mfma_f32_16x16x32_bf16 v[32:35], v[208:211], v[166:169], v[32:35]
	v_mfma_f32_16x16x32_bf16 v[20:23], v[200:203], v[174:177], v[20:23]
	v_mfma_f32_16x16x32_bf16 v[16:19], v[208:211], v[174:177], v[16:19]
	v_mfma_f32_16x16x32_bf16 v[4:7], v[200:203], v[192:195], v[4:7]
	v_mfma_f32_16x16x32_bf16 v[0:3], v[208:211], v[192:195], v[0:3]
	s_setprio 0
	s_add_i32 s63, 0, 0x18000
	v_add_u32_e32 v140, s63, v181
	s_barrier
	ds_read_b128 v[128:131], v140
	ds_read_b128 v[132:135], v140 offset:1024
	ds_read_b128 v[136:139], v140 offset:2048
	ds_read_b128 v[140:143], v140 offset:3072
	s_add_u32 s26, s36, 0x160000
	s_addc_u32 s27, s37, 0
	s_mov_b32 m0, s46
	v_lshl_add_u64 v[196:197], s[26:27], 0, v[152:153]
	ds_read_b128 v[144:147], v186 offset:32768
	ds_read_b128 v[148:151], v186 offset:33792
	ds_read_b128 v[162:165], v186 offset:34816
	ds_read_b128 v[166:169], v186 offset:35840
	ds_read_b128 v[170:173], v186 offset:36864
	ds_read_b128 v[174:177], v186 offset:37888
	ds_read_b128 v[188:191], v186 offset:38912
	ds_read_b128 v[192:195], v186 offset:39936
	global_load_lds_dwordx4 v[196:197], off
	v_lshl_add_u64 v[196:197], s[26:27], 0, v[154:155]
	s_mov_b32 m0, s47
	s_nop 0
	global_load_lds_dwordx4 v[196:197], off
	s_waitcnt lgkmcnt(8)
	s_barrier
	s_waitcnt lgkmcnt(0)
	s_setprio 1
	s_waitcnt lgkmcnt(0)
	v_mfma_f32_16x16x32_bf16 v[124:127], v[128:131], v[144:147], v[124:127]
	v_mfma_f32_16x16x32_bf16 v[120:123], v[136:139], v[144:147], v[120:123]
	v_mfma_f32_16x16x32_bf16 v[108:111], v[128:131], v[162:165], v[108:111]
	v_mfma_f32_16x16x32_bf16 v[104:107], v[136:139], v[162:165], v[104:107]
	v_mfma_f32_16x16x32_bf16 v[92:95], v[128:131], v[170:173], v[92:95]
	v_mfma_f32_16x16x32_bf16 v[88:91], v[136:139], v[170:173], v[88:91]
	v_mfma_f32_16x16x32_bf16 v[76:79], v[128:131], v[188:191], v[76:79]
	v_mfma_f32_16x16x32_bf16 v[72:75], v[136:139], v[188:191], v[72:75]
	v_mfma_f32_16x16x32_bf16 v[124:127], v[132:135], v[148:151], v[124:127]
	v_mfma_f32_16x16x32_bf16 v[120:123], v[140:143], v[148:151], v[120:123]
	v_mfma_f32_16x16x32_bf16 v[108:111], v[132:135], v[166:169], v[108:111]
	v_mfma_f32_16x16x32_bf16 v[104:107], v[140:143], v[166:169], v[104:107]
	v_mfma_f32_16x16x32_bf16 v[92:95], v[132:135], v[174:177], v[92:95]
	v_mfma_f32_16x16x32_bf16 v[88:91], v[140:143], v[174:177], v[88:91]
	v_mfma_f32_16x16x32_bf16 v[76:79], v[132:135], v[192:195], v[76:79]
	v_mfma_f32_16x16x32_bf16 v[72:75], v[140:143], v[192:195], v[72:75]
	s_setprio 0
	s_barrier
	s_add_i32 s36, 0, 0x1c000
	s_add_i32 s26, s63, s43
	v_add_u32_e32 v208, s36, v181
	v_lshl_add_u64 v[178:179], v[178:179], 0, s[12:13]
	s_mov_b32 m0, s26
	ds_read_b128 v[196:199], v208
	ds_read_b128 v[200:203], v208 offset:1024
	ds_read_b128 v[204:207], v208 offset:2048
	ds_read_b128 v[208:211], v208 offset:3072
	global_load_lds_dwordx4 v[178:179], off
	v_lshl_add_u64 v[178:179], v[212:213], 0, s[12:13]
	s_add_i32 m0, s26, 0x2000
	s_nop 0
	global_load_lds_dwordx4 v[178:179], off
	s_barrier
	s_waitcnt lgkmcnt(0)
	s_setprio 1
	s_waitcnt lgkmcnt(0)
	v_mfma_f32_16x16x32_bf16 v[116:119], v[196:199], v[144:147], v[116:119]
	v_mfma_f32_16x16x32_bf16 v[112:115], v[204:207], v[144:147], v[112:115]
	v_mfma_f32_16x16x32_bf16 v[100:103], v[196:199], v[162:165], v[100:103]
	v_mfma_f32_16x16x32_bf16 v[96:99], v[204:207], v[162:165], v[96:99]
	v_mfma_f32_16x16x32_bf16 v[84:87], v[196:199], v[170:173], v[84:87]
	v_mfma_f32_16x16x32_bf16 v[80:83], v[204:207], v[170:173], v[80:83]
	v_mfma_f32_16x16x32_bf16 v[68:71], v[196:199], v[188:191], v[68:71]
	v_mfma_f32_16x16x32_bf16 v[64:67], v[204:207], v[188:191], v[64:67]
	v_mfma_f32_16x16x32_bf16 v[116:119], v[200:203], v[148:151], v[116:119]
	v_mfma_f32_16x16x32_bf16 v[112:115], v[208:211], v[148:151], v[112:115]
	v_mfma_f32_16x16x32_bf16 v[100:103], v[200:203], v[166:169], v[100:103]
	v_mfma_f32_16x16x32_bf16 v[96:99], v[208:211], v[166:169], v[96:99]
	v_mfma_f32_16x16x32_bf16 v[84:87], v[200:203], v[174:177], v[84:87]
	v_mfma_f32_16x16x32_bf16 v[80:83], v[208:211], v[174:177], v[80:83]
	v_mfma_f32_16x16x32_bf16 v[68:71], v[200:203], v[192:195], v[68:71]
	v_mfma_f32_16x16x32_bf16 v[64:67], v[208:211], v[192:195], v[64:67]
	s_setprio 0
	s_mov_b32 m0, s49
	v_lshl_add_u64 v[178:179], v[214:215], 0, s[12:13]
	s_barrier
	ds_read_b128 v[144:147], v186 offset:49152
	ds_read_b128 v[148:151], v186 offset:50176
	ds_read_b128 v[162:165], v186 offset:51200
	ds_read_b128 v[166:169], v186 offset:52224
	ds_read_b128 v[170:173], v186 offset:53248
	ds_read_b128 v[174:177], v186 offset:54272
	ds_read_b128 v[188:191], v186 offset:55296
	ds_read_b128 v[192:195], v186 offset:56320
	global_load_lds_dwordx4 v[178:179], off
	v_lshl_add_u64 v[178:179], v[216:217], 0, s[12:13]
	s_mov_b32 m0, s50
	s_nop 0
	global_load_lds_dwordx4 v[178:179], off
	s_barrier
; DI u32x2 pk4(f32x4 v) { u32x2 r; r.x = pk2(v[0], v[1]); r.y = pk2(v[2], v[3]); return r; }
; DI float bf_lo(unsigned w) { return __uint_as_float(w << 16); }
; DI float bf_hi(unsigned w) { return __uint_as_float(w & 0xffff0000u); }
; #define PG8_STAGE(bufoff, gbase, voff) do { _Pragma("unroll") for (int _i = 0; _i < 2; ++_i) \
;         __builtin_amdgcn_global_load_lds((const unsigned*)((const char*)(gbase) + (voff)[_i]), (LAS unsigned*)(lds + (bufoff) + ldsw + _i * 8192), 16, 0, 0); } while (0)
; #define PG8_BAR __builtin_amdgcn_s_barrier()
; template <class Epi>
; DI void gemm_phase(LAS unsigned char* lds, int wid, int K, int lda, int ldb, bool bperm, const Sched3& S, const Epi& E) {
;     ...
;             PG8_BAR; PG8_WAIT_L(0); if (full) PG8_MMA(1, 0, At, B0); PG8_BAR; PG8_SCHED;
;             PG8_STAGE(PG8_SB(1, 1), b3 + hstepB, voffB);
;             PG8_WAIT_V(6); PG8_BAR; if (full) PG8_MMA(1, 1, At, B1); PG8_BAR;
;     DI void operator()(const Acc& acc, const Unit& u, int wr, int wc, int fr, int fq) const {
;     ...
;                 for (int m = 0; m < 4; ++m) { const size_t o = (size_t)(row0 + ai * HALF + m * 16) * 2048 + colp;
;                     if (PH == 4) { COLS4 xo[m][bj][n] = *(const f32x4*)(p.x + o + bj * HALF + n * 4); }
;                     else {
; #pragma unroll
;                         for (int bj = 0; bj < 2; ++bj) { const u32x4 w = *(const u32x4*)(WSB(OFF_XB) + o + bj * HALF);
;                             xo[m][bj][0] = (f32x4){bf_lo(w.x), bf_hi(w.x), bf_lo(w.y), bf_hi(w.y)}; xo[m][bj][1] = (f32x4){bf_lo(w.z), bf_hi(w.z), bf_lo(w.w), bf_hi(w.w)}; } } }
; #pragma unroll
;                 for (int m = 0; m < 4; ++m) { const int r = row0 + ai * HALF + m * 16; const size_t o = (size_t)r * 2048 + colp; float part = 0.f;
; #pragma unroll
;                     for (int bj = 0; bj < 2; ++bj) { const f32x4 x0 = xo[m][bj][0] + acc[ai][bj][m][0], x1 = xo[m][bj][1] + acc[ai][bj][m][1];
;                         const u32x2 h0 = pk4(x0), h1 = pk4(x1);
;                         *(u32x4*)(WSB(OFF_XB) + o + bj * HALF) = (u32x4){h0.x, h0.y, h1.x, h1.y};
;                         part += x0[0] * x0[0] + x0[1] * x0[1] + x0[2] * x0[2] + x0[3] * x0[3] + x1[0] * x1[0] + x1[1] * x1[1] + x1[2] * x1[2] + x1[3] * x1[3]; }
;                     part += __shfl_xor(part, 16); part += __shfl_xor(part, 32);
;                     if (fq == 0) unsafeAtomicAdd(ssq + r, part);
	s_waitcnt lgkmcnt(0)
	s_setprio 1
	s_waitcnt lgkmcnt(0)
	v_mfma_f32_16x16x32_bf16 v[60:63], v[128:131], v[144:147], v[60:63]
	v_mfma_f32_16x16x32_bf16 v[56:59], v[136:139], v[144:147], v[56:59]
	v_mfma_f32_16x16x32_bf16 v[44:47], v[128:131], v[162:165], v[44:47]
	v_mfma_f32_16x16x32_bf16 v[40:43], v[136:139], v[162:165], v[40:43]
	v_mfma_f32_16x16x32_bf16 v[28:31], v[128:131], v[170:173], v[28:31]
	v_mfma_f32_16x16x32_bf16 v[24:27], v[136:139], v[170:173], v[24:27]
	v_mfma_f32_16x16x32_bf16 v[12:15], v[128:131], v[188:191], v[12:15]
	v_mfma_f32_16x16x32_bf16 v[8:11], v[136:139], v[188:191], v[8:11]
	v_mfma_f32_16x16x32_bf16 v[60:63], v[132:135], v[148:151], v[60:63]
	v_mfma_f32_16x16x32_bf16 v[56:59], v[140:143], v[148:151], v[56:59]
	v_mfma_f32_16x16x32_bf16 v[44:47], v[132:135], v[166:169], v[44:47]
	v_mfma_f32_16x16x32_bf16 v[40:43], v[140:143], v[166:169], v[40:43]
	v_mfma_f32_16x16x32_bf16 v[28:31], v[132:135], v[174:177], v[28:31]
	v_mfma_f32_16x16x32_bf16 v[24:27], v[140:143], v[174:177], v[24:27]
	v_mfma_f32_16x16x32_bf16 v[12:15], v[132:135], v[192:195], v[12:15]
	v_mfma_f32_16x16x32_bf16 v[8:11], v[140:143], v[192:195], v[8:11]
	s_setprio 0
	s_barrier
	s_add_u32 s26, s30, 0x160080
	s_addc_u32 s27, s31, 0
	s_add_i32 s30, s36, s43
	v_lshl_add_u64 v[128:129], s[26:27], 0, v[152:153]
	s_mov_b32 m0, s30
	s_nop 0
	global_load_lds_dwordx4 v[128:129], off
	v_lshl_add_u64 v[128:129], s[26:27], 0, v[154:155]
	s_add_i32 m0, s30, 0x2000
	s_nop 0
	global_load_lds_dwordx4 v[128:129], off
	s_waitcnt vmcnt(6)
	s_barrier
	s_setprio 1
	v_mfma_f32_16x16x32_bf16 v[52:55], v[196:199], v[144:147], v[52:55]
	v_mfma_f32_16x16x32_bf16 v[48:51], v[204:207], v[144:147], v[48:51]
	v_mfma_f32_16x16x32_bf16 v[36:39], v[196:199], v[162:165], v[36:39]
	v_mfma_f32_16x16x32_bf16 v[32:35], v[204:207], v[162:165], v[32:35]
	v_mfma_f32_16x16x32_bf16 v[20:23], v[196:199], v[170:173], v[20:23]
	v_mfma_f32_16x16x32_bf16 v[16:19], v[204:207], v[170:173], v[16:19]
	v_mfma_f32_16x16x32_bf16 v[4:7], v[196:199], v[188:191], v[4:7]
	v_mfma_f32_16x16x32_bf16 v[0:3], v[204:207], v[188:191], v[0:3]
	v_mfma_f32_16x16x32_bf16 v[52:55], v[200:203], v[148:151], v[52:55]
	v_mfma_f32_16x16x32_bf16 v[48:51], v[208:211], v[148:151], v[48:51]
	v_mfma_f32_16x16x32_bf16 v[36:39], v[200:203], v[166:169], v[36:39]
	v_mfma_f32_16x16x32_bf16 v[32:35], v[208:211], v[166:169], v[32:35]
	v_mfma_f32_16x16x32_bf16 v[20:23], v[200:203], v[174:177], v[20:23]
	v_mfma_f32_16x16x32_bf16 v[16:19], v[208:211], v[174:177], v[16:19]
	v_mfma_f32_16x16x32_bf16 v[4:7], v[200:203], v[192:195], v[4:7]
	v_mfma_f32_16x16x32_bf16 v[0:3], v[208:211], v[192:195], v[0:3]
	s_setprio 0
	s_add_i32 s62, s62, 2
	s_add_u32 s60, s60, 0x100
	s_addc_u32 s61, s61, 0
	s_cmpk_gt_u32 s62, 0x55
	s_mov_b64 s[26:27], s[28:29]
	s_barrier
	s_cbranch_scc0 .LBB0_785
	v_lshl_add_u32 v128, s58, 8, v182
	v_lshl_add_u32 v166, s59, 8, v180
	v_ashrrev_i32_e32 v129, 31, v128
	v_lshlrev_b64 v[162:163], 1, v[128:129]
	v_ashrrev_i32_e32 v167, 31, v166
	v_lshl_add_u64 v[164:165], s[16:17], 0, v[162:163]
	v_lshlrev_b64 v[196:197], 12, v[166:167]
	v_lshl_add_u64 v[128:129], v[164:165], 0, v[196:197]
	global_load_dwordx4 v[188:191], v[128:129], off
	global_load_dwordx4 v[192:195], v[128:129], off offset:256
	v_or_b32_e32 v176, 16, v166
	v_or_b32_e32 v172, 32, v166
	v_or_b32_e32 v168, 48, v166
	v_ashrrev_i32_e32 v177, 31, v176
	v_ashrrev_i32_e32 v173, 31, v172
	v_ashrrev_i32_e32 v169, 31, v168
	v_lshlrev_b64 v[178:179], 12, v[176:177]
	v_lshlrev_b64 v[174:175], 12, v[172:173]
	v_lshlrev_b64 v[170:171], 12, v[168:169]
	v_lshl_add_u64 v[128:129], v[164:165], 0, v[178:179]
	v_lshl_add_u64 v[130:131], v[164:165], 0, v[174:175]
	v_lshl_add_u64 v[198:199], v[164:165], 0, v[170:171]
	global_load_dwordx4 v[148:151], v[128:129], off
	global_load_dwordx4 v[144:147], v[128:129], off offset:256
	global_load_dwordx4 v[140:143], v[130:131], off
	global_load_dwordx4 v[136:139], v[130:131], off offset:256
	global_load_dwordx4 v[132:135], v[198:199], off
	s_nop 0
	global_load_dwordx4 v[128:131], v[198:199], off offset:256
	v_lshl_add_u64 v[198:199], s[16:17], 0, v[196:197]
	v_lshl_add_u64 v[198:199], v[198:199], 0, v[162:163]
	v_lshl_add_u64 v[196:197], s[10:11], 0, v[196:197]
	v_lshl_add_u64 v[196:197], v[196:197], 0, v[162:163]
	s_waitcnt vmcnt(0)
	v_lshlrev_b32_e32 v200, 16, v188
	v_and_b32_e32 v201, 0xffff0000, v188
	v_lshlrev_b32_e32 v188, 16, v189
	v_and_b32_e32 v189, 0xffff0000, v189
	v_lshlrev_b32_e32 v204, 16, v192
	v_and_b32_e32 v205, 0xffff0000, v192
	v_lshlrev_b32_e32 v192, 16, v193
	v_and_b32_e32 v193, 0xffff0000, v193
	v_lshlrev_b32_e32 v206, 16, v194
	v_and_b32_e32 v207, 0xffff0000, v194
	v_add_f32_e32 v126, v126, v188
	v_add_f32_e32 v127, v127, v189
	v_add_f32_e32 v124, v124, v200
	v_add_f32_e32 v125, v125, v201
	v_add_f32_e32 v188, v116, v204
	v_add_f32_e32 v189, v117, v205
	v_add_f32_e32 v118, v118, v192
	v_add_f32_e32 v119, v119, v193
	v_add_f32_e32 v192, v112, v206
	v_add_f32_e32 v193, v113, v207
	v_cvt_pk_bf16_f32 v112, v124, v125
	v_mul_f32_e32 v117, v125, v125
	v_mul_f32_e32 v125, v189, v189
	v_fmac_f32_e32 v117, v124, v124
	v_fmac_f32_e32 v125, v188, v188
	v_lshlrev_b32_e32 v202, 16, v190
	v_and_b32_e32 v203, 0xffff0000, v190
	v_fmac_f32_e32 v117, v126, v126
	v_fmac_f32_e32 v125, v118, v118
	v_add_f32_e32 v120, v120, v202
	v_add_f32_e32 v121, v121, v203
	v_fmac_f32_e32 v117, v127, v127
	v_fmac_f32_e32 v125, v119, v119
	v_lshlrev_b32_e32 v190, 16, v191
	v_and_b32_e32 v191, 0xffff0000, v191
	v_lshlrev_b32_e32 v194, 16, v195
	v_and_b32_e32 v195, 0xffff0000, v195
	v_fmac_f32_e32 v117, v120, v120
	v_fmac_f32_e32 v125, v192, v192
	v_add_f32_e32 v122, v122, v190
	v_add_f32_e32 v123, v123, v191
	v_add_f32_e32 v190, v114, v194
	v_add_f32_e32 v191, v115, v195
	v_fmac_f32_e32 v117, v121, v121
	v_fmac_f32_e32 v125, v193, v193
	v_fmac_f32_e32 v117, v122, v122
	v_fmac_f32_e32 v125, v190, v190
	v_fmac_f32_e32 v117, v123, v123
	v_fmac_f32_e32 v125, v191, v191
	v_cvt_pk_bf16_f32 v114, v120, v121
	v_add_f32_e32 v120, v117, v125
	ds_bpermute_b32 v121, v183, v120
	v_cvt_pk_bf16_f32 v113, v126, v127
	v_cvt_pk_bf16_f32 v115, v122, v123
	global_store_dwordx4 v[198:199], v[112:115], off sc1
	v_cvt_pk_bf16_f32 v116, v188, v189
	v_cvt_pk_bf16_f32 v117, v118, v119
	s_waitcnt lgkmcnt(0)
	v_add_f32_e32 v112, v120, v121
	ds_bpermute_b32 v113, v184, v112
	v_add_co_u32_e32 v114, vcc, s55, v196
	v_cvt_pk_bf16_f32 v118, v192, v193
	v_cvt_pk_bf16_f32 v119, v190, v191
	v_addc_co_u32_e32 v115, vcc, 0, v197, vcc
	global_store_dwordx4 v[114:115], v[116:119], off offset:256 sc1
	s_and_saveexec_b64 s[22:23], s[2:3]
	s_cbranch_execz .LBB0_788
	s_waitcnt lgkmcnt(0)
	v_add_f32_e32 v114, v112, v113
	v_lshl_add_u64 v[112:113], v[166:167], 2, s[14:15]
	global_atomic_add_f32 v[112:113], v114, off
; DI u32x2 pk4(f32x4 v) { u32x2 r; r.x = pk2(v[0], v[1]); r.y = pk2(v[2], v[3]); return r; }
; DI float bf_lo(unsigned w) { return __uint_as_float(w << 16); }
; DI float bf_hi(unsigned w) { return __uint_as_float(w & 0xffff0000u); }
; #define COLS4 _Pragma("unroll") for (int bj = 0; bj < 2; ++bj) _Pragma("unroll") for (int n = 0; n < 2; ++n)
;     DI void operator()(const Acc& acc, const Unit& u, int wr, int wc, int fr, int fq) const {
;     ...
;                 for (int m = 0; m < 4; ++m) { const size_t o = (size_t)(row0 + ai * HALF + m * 16) * 2048 + colp;
;                     if (PH == 4) { COLS4 xo[m][bj][n] = *(const f32x4*)(p.x + o + bj * HALF + n * 4); }
;                     else {
; #pragma unroll
;                         for (int bj = 0; bj < 2; ++bj) { const u32x4 w = *(const u32x4*)(WSB(OFF_XB) + o + bj * HALF);
;                             xo[m][bj][0] = (f32x4){bf_lo(w.x), bf_hi(w.x), bf_lo(w.y), bf_hi(w.y)}; xo[m][bj][1] = (f32x4){bf_lo(w.z), bf_hi(w.z), bf_lo(w.w), bf_hi(w.w)}; } } }
; #pragma unroll
;                 for (int m = 0; m < 4; ++m) { const int r = row0 + ai * HALF + m * 16; const size_t o = (size_t)r * 2048 + colp; float part = 0.f;
; #pragma unroll
;                     for (int bj = 0; bj < 2; ++bj) { const f32x4 x0 = xo[m][bj][0] + acc[ai][bj][m][0], x1 = xo[m][bj][1] + acc[ai][bj][m][1];
;                         const u32x2 h0 = pk4(x0), h1 = pk4(x1);
;                         *(u32x4*)(WSB(OFF_XB) + o + bj * HALF) = (u32x4){h0.x, h0.y, h1.x, h1.y};
;                         part += x0[0] * x0[0] + x0[1] * x0[1] + x0[2] * x0[2] + x0[3] * x0[3] + x1[0] * x1[0] + x1[1] * x1[1] + x1[2] * x1[2] + x1[3] * x1[3]; }
;                     part += __shfl_xor(part, 16); part += __shfl_xor(part, 32);
;                     if (fq == 0) unsafeAtomicAdd(ssq + r, part);
.LBB0_788:
	s_or_b64 exec, exec, s[22:23]
	v_lshlrev_b32_e32 v112, 16, v148
	s_waitcnt lgkmcnt(0)
	v_and_b32_e32 v113, 0xffff0000, v148
	v_lshlrev_b32_e32 v114, 16, v149
	v_and_b32_e32 v115, 0xffff0000, v149
	v_lshlrev_b32_e32 v116, 16, v150
	v_and_b32_e32 v117, 0xffff0000, v150
	v_lshlrev_b32_e32 v118, 16, v151
	v_and_b32_e32 v119, 0xffff0000, v151
	v_lshlrev_b32_e32 v120, 16, v144
	v_and_b32_e32 v121, 0xffff0000, v144
	v_add_f32_e32 v110, v110, v114
	v_add_f32_e32 v111, v111, v115
	v_add_f32_e32 v108, v108, v112
	v_add_f32_e32 v109, v109, v113
	v_add_f32_e32 v112, v106, v118
	v_add_f32_e32 v113, v107, v119
	v_add_f32_e32 v114, v104, v116
	v_add_f32_e32 v115, v105, v117
	v_lshl_add_u64 v[116:117], s[16:17], 0, v[178:179]
	v_lshlrev_b32_e32 v126, 16, v147
	v_and_b32_e32 v127, 0xffff0000, v147
	v_cvt_pk_bf16_f32 v104, v108, v109
	v_cvt_pk_bf16_f32 v105, v110, v111
	v_cvt_pk_bf16_f32 v106, v114, v115
	v_cvt_pk_bf16_f32 v107, v112, v113
	v_lshl_add_u64 v[116:117], v[116:117], 0, v[162:163]
	v_add_f32_e32 v100, v100, v120
	v_add_f32_e32 v101, v101, v121
	v_lshlrev_b32_e32 v122, 16, v145
	v_and_b32_e32 v123, 0xffff0000, v145
	global_store_dwordx4 v[116:117], v[104:107], off sc1
	v_add_f32_e32 v102, v102, v122
	v_add_f32_e32 v103, v103, v123
	v_lshlrev_b32_e32 v124, 16, v146
	v_mul_f32_e32 v106, v109, v109
	v_add_f32_e32 v104, v98, v126
	v_add_f32_e32 v105, v99, v127
	v_cvt_pk_bf16_f32 v98, v100, v101
	v_mul_f32_e32 v101, v101, v101
	v_fmac_f32_e32 v106, v108, v108
	v_fmac_f32_e32 v101, v100, v100
	v_and_b32_e32 v125, 0xffff0000, v146
	v_fmac_f32_e32 v106, v110, v110
	v_fmac_f32_e32 v101, v102, v102
	v_fmac_f32_e32 v106, v111, v111
	v_add_f32_e32 v96, v96, v124
	v_add_f32_e32 v97, v97, v125
	v_fmac_f32_e32 v101, v103, v103
	v_fmac_f32_e32 v106, v114, v114
	v_fmac_f32_e32 v101, v96, v96
	v_fmac_f32_e32 v106, v115, v115
	v_fmac_f32_e32 v101, v97, v97
	v_fmac_f32_e32 v106, v112, v112
	v_fmac_f32_e32 v101, v104, v104
	v_fmac_f32_e32 v106, v113, v113
	v_fmac_f32_e32 v101, v105, v105
	v_add_f32_e32 v106, v106, v101
	ds_bpermute_b32 v107, v183, v106
	v_cvt_pk_bf16_f32 v100, v96, v97
	v_lshl_add_u64 v[96:97], s[10:11], 0, v[178:179]
	v_cvt_pk_bf16_f32 v99, v102, v103
	v_lshl_add_u64 v[102:103], v[96:97], 0, v[162:163]
	s_waitcnt lgkmcnt(0)
	v_add_f32_e32 v96, v106, v107
	ds_bpermute_b32 v97, v184, v96
	v_add_co_u32_e32 v102, vcc, s55, v102
	v_cvt_pk_bf16_f32 v101, v104, v105
	s_nop 0
	v_addc_co_u32_e32 v103, vcc, 0, v103, vcc
	global_store_dwordx4 v[102:103], v[98:101], off offset:256 sc1
	s_and_saveexec_b64 s[22:23], s[2:3]
	s_cbranch_execz .LBB0_790
	s_waitcnt lgkmcnt(0)
	v_add_f32_e32 v98, v96, v97
	v_lshl_add_u64 v[96:97], v[176:177], 2, s[14:15]
	global_atomic_add_f32 v[96:97], v98, off
.LBB0_790:
	s_or_b64 exec, exec, s[22:23]
	v_lshlrev_b32_e32 v96, 16, v140
	s_waitcnt lgkmcnt(0)
	v_and_b32_e32 v97, 0xffff0000, v140
	v_lshlrev_b32_e32 v98, 16, v141
	v_and_b32_e32 v99, 0xffff0000, v141
	v_lshlrev_b32_e32 v100, 16, v142
	v_and_b32_e32 v101, 0xffff0000, v142
	v_lshlrev_b32_e32 v102, 16, v143
	v_and_b32_e32 v103, 0xffff0000, v143
	v_lshlrev_b32_e32 v104, 16, v136
	v_and_b32_e32 v105, 0xffff0000, v136
	v_add_f32_e32 v94, v94, v98
	v_add_f32_e32 v95, v95, v99
	v_add_f32_e32 v92, v92, v96
	v_add_f32_e32 v93, v93, v97
	v_add_f32_e32 v96, v90, v102
	v_add_f32_e32 v97, v91, v103
	v_add_f32_e32 v98, v88, v100
	v_add_f32_e32 v99, v89, v101
	v_lshl_add_u64 v[100:101], s[16:17], 0, v[174:175]
	v_lshlrev_b32_e32 v110, 16, v139
	v_and_b32_e32 v111, 0xffff0000, v139
	v_cvt_pk_bf16_f32 v88, v92, v93
	v_cvt_pk_bf16_f32 v89, v94, v95
	v_cvt_pk_bf16_f32 v90, v98, v99
	v_cvt_pk_bf16_f32 v91, v96, v97
	v_lshl_add_u64 v[100:101], v[100:101], 0, v[162:163]
	v_add_f32_e32 v84, v84, v104
	v_add_f32_e32 v85, v85, v105
	v_lshlrev_b32_e32 v106, 16, v137
	v_and_b32_e32 v107, 0xffff0000, v137
	global_store_dwordx4 v[100:101], v[88:91], off sc1
	v_add_f32_e32 v86, v86, v106
	v_add_f32_e32 v87, v87, v107
	v_lshlrev_b32_e32 v108, 16, v138
	v_mul_f32_e32 v90, v93, v93
	v_add_f32_e32 v88, v82, v110
	v_add_f32_e32 v89, v83, v111
	v_cvt_pk_bf16_f32 v82, v84, v85
	v_mul_f32_e32 v85, v85, v85
	v_fmac_f32_e32 v90, v92, v92
	v_fmac_f32_e32 v85, v84, v84
	v_and_b32_e32 v109, 0xffff0000, v138
	v_fmac_f32_e32 v90, v94, v94
	v_fmac_f32_e32 v85, v86, v86
	v_fmac_f32_e32 v90, v95, v95
	v_add_f32_e32 v80, v80, v108
	v_add_f32_e32 v81, v81, v109
	v_fmac_f32_e32 v85, v87, v87
	v_fmac_f32_e32 v90, v98, v98
	v_fmac_f32_e32 v85, v80, v80
	v_fmac_f32_e32 v90, v99, v99
	v_fmac_f32_e32 v85, v81, v81
	v_fmac_f32_e32 v90, v96, v96
	v_fmac_f32_e32 v85, v88, v88
	v_fmac_f32_e32 v90, v97, v97
	v_fmac_f32_e32 v85, v89, v89
	v_add_f32_e32 v90, v90, v85
	ds_bpermute_b32 v91, v183, v90
	v_cvt_pk_bf16_f32 v84, v80, v81
	v_lshl_add_u64 v[80:81], s[10:11], 0, v[174:175]
	v_cvt_pk_bf16_f32 v83, v86, v87
	v_lshl_add_u64 v[86:87], v[80:81], 0, v[162:163]
	s_waitcnt lgkmcnt(0)
	v_add_f32_e32 v80, v90, v91
	ds_bpermute_b32 v81, v184, v80
	v_add_co_u32_e32 v86, vcc, s55, v86
	v_cvt_pk_bf16_f32 v85, v88, v89
	s_nop 0
	v_addc_co_u32_e32 v87, vcc, 0, v87, vcc
	global_store_dwordx4 v[86:87], v[82:85], off offset:256 sc1
	s_and_saveexec_b64 s[22:23], s[2:3]
	s_cbranch_execz .LBB0_792
	s_waitcnt lgkmcnt(0)
	v_add_f32_e32 v82, v80, v81
	v_lshl_add_u64 v[80:81], v[172:173], 2, s[14:15]
	global_atomic_add_f32 v[80:81], v82, off
; DI u32x2 pk4(f32x4 v) { u32x2 r; r.x = pk2(v[0], v[1]); r.y = pk2(v[2], v[3]); return r; }
; DI float bf_lo(unsigned w) { return __uint_as_float(w << 16); }
; DI float bf_hi(unsigned w) { return __uint_as_float(w & 0xffff0000u); }
; #define COLS4 _Pragma("unroll") for (int bj = 0; bj < 2; ++bj) _Pragma("unroll") for (int n = 0; n < 2; ++n)
;     DI void operator()(const Acc& acc, const Unit& u, int wr, int wc, int fr, int fq) const {
;     ...
;                 for (int m = 0; m < 4; ++m) { const size_t o = (size_t)(row0 + ai * HALF + m * 16) * 2048 + colp;
;                     if (PH == 4) { COLS4 xo[m][bj][n] = *(const f32x4*)(p.x + o + bj * HALF + n * 4); }
;                     else {
; #pragma unroll
;                         for (int bj = 0; bj < 2; ++bj) { const u32x4 w = *(const u32x4*)(WSB(OFF_XB) + o + bj * HALF);
;                             xo[m][bj][0] = (f32x4){bf_lo(w.x), bf_hi(w.x), bf_lo(w.y), bf_hi(w.y)}; xo[m][bj][1] = (f32x4){bf_lo(w.z), bf_hi(w.z), bf_lo(w.w), bf_hi(w.w)}; } } }
; #pragma unroll
;                 for (int m = 0; m < 4; ++m) { const int r = row0 + ai * HALF + m * 16; const size_t o = (size_t)r * 2048 + colp; float part = 0.f;
; #pragma unroll
;                     for (int bj = 0; bj < 2; ++bj) { const f32x4 x0 = xo[m][bj][0] + acc[ai][bj][m][0], x1 = xo[m][bj][1] + acc[ai][bj][m][1];
;                         const u32x2 h0 = pk4(x0), h1 = pk4(x1);
;                         *(u32x4*)(WSB(OFF_XB) + o + bj * HALF) = (u32x4){h0.x, h0.y, h1.x, h1.y};
;                         part += x0[0] * x0[0] + x0[1] * x0[1] + x0[2] * x0[2] + x0[3] * x0[3] + x1[0] * x1[0] + x1[1] * x1[1] + x1[2] * x1[2] + x1[3] * x1[3]; }
;                     part += __shfl_xor(part, 16); part += __shfl_xor(part, 32);
;                     if (fq == 0) unsafeAtomicAdd(ssq + r, part);
.LBB0_792:
	s_or_b64 exec, exec, s[22:23]
	v_lshlrev_b32_e32 v80, 16, v132
	s_waitcnt lgkmcnt(0)
	v_and_b32_e32 v81, 0xffff0000, v132
	v_lshlrev_b32_e32 v82, 16, v133
	v_and_b32_e32 v83, 0xffff0000, v133
	v_lshlrev_b32_e32 v84, 16, v134
	v_and_b32_e32 v85, 0xffff0000, v134
	v_lshlrev_b32_e32 v86, 16, v135
	v_and_b32_e32 v87, 0xffff0000, v135
	v_lshlrev_b32_e32 v88, 16, v128
	v_and_b32_e32 v89, 0xffff0000, v128
	v_add_f32_e32 v78, v78, v82
	v_add_f32_e32 v79, v79, v83
	v_add_f32_e32 v76, v76, v80
	v_add_f32_e32 v77, v77, v81
	v_add_f32_e32 v80, v74, v86
	v_add_f32_e32 v81, v75, v87
	v_add_f32_e32 v82, v72, v84
	v_add_f32_e32 v83, v73, v85
	v_lshl_add_u64 v[84:85], s[16:17], 0, v[170:171]
	v_lshlrev_b32_e32 v94, 16, v131
	v_and_b32_e32 v95, 0xffff0000, v131
	v_cvt_pk_bf16_f32 v72, v76, v77
	v_cvt_pk_bf16_f32 v73, v78, v79
	v_cvt_pk_bf16_f32 v74, v82, v83
	v_cvt_pk_bf16_f32 v75, v80, v81
	v_lshl_add_u64 v[84:85], v[84:85], 0, v[162:163]
	v_add_f32_e32 v68, v68, v88
	v_add_f32_e32 v69, v69, v89
	v_lshlrev_b32_e32 v90, 16, v129
	v_and_b32_e32 v91, 0xffff0000, v129
	global_store_dwordx4 v[84:85], v[72:75], off sc1
	v_add_f32_e32 v70, v70, v90
	v_add_f32_e32 v71, v71, v91
	v_lshlrev_b32_e32 v92, 16, v130
	v_mul_f32_e32 v74, v77, v77
	v_add_f32_e32 v72, v66, v94
	v_add_f32_e32 v73, v67, v95
	v_cvt_pk_bf16_f32 v66, v68, v69
	v_mul_f32_e32 v69, v69, v69
	v_fmac_f32_e32 v74, v76, v76
	v_fmac_f32_e32 v69, v68, v68
	v_and_b32_e32 v93, 0xffff0000, v130
	v_fmac_f32_e32 v74, v78, v78
	v_fmac_f32_e32 v69, v70, v70
	v_fmac_f32_e32 v74, v79, v79
	v_add_f32_e32 v64, v64, v92
	v_add_f32_e32 v65, v65, v93
	v_fmac_f32_e32 v69, v71, v71
	v_fmac_f32_e32 v74, v82, v82
	v_fmac_f32_e32 v69, v64, v64
	v_fmac_f32_e32 v74, v83, v83
	v_fmac_f32_e32 v69, v65, v65
	v_fmac_f32_e32 v74, v80, v80
	v_fmac_f32_e32 v69, v72, v72
	v_fmac_f32_e32 v74, v81, v81
	v_fmac_f32_e32 v69, v73, v73
	v_add_f32_e32 v74, v74, v69
	ds_bpermute_b32 v75, v183, v74
	v_cvt_pk_bf16_f32 v68, v64, v65
	v_lshl_add_u64 v[64:65], s[10:11], 0, v[170:171]
	v_cvt_pk_bf16_f32 v67, v70, v71
	v_lshl_add_u64 v[70:71], v[64:65], 0, v[162:163]
	s_waitcnt lgkmcnt(0)
	v_add_f32_e32 v64, v74, v75
	ds_bpermute_b32 v65, v184, v64
	v_add_co_u32_e32 v70, vcc, s55, v70
	v_cvt_pk_bf16_f32 v69, v72, v73
	s_nop 0
	v_addc_co_u32_e32 v71, vcc, 0, v71, vcc
	global_store_dwordx4 v[70:71], v[66:69], off offset:256 sc1
	s_and_saveexec_b64 s[22:23], s[2:3]
	s_cbranch_execz .LBB0_794
	s_waitcnt lgkmcnt(0)
	v_add_f32_e32 v66, v64, v65
	v_lshl_add_u64 v[64:65], v[168:169], 2, s[14:15]
	global_atomic_add_f32 v[64:65], v66, off
.LBB0_794:
	s_or_b64 exec, exec, s[22:23]
	v_add_u32_e32 v100, 0x80, v166
	v_ashrrev_i32_e32 v101, 31, v100
	v_lshlrev_b64 v[110:111], 12, v[100:101]
	s_waitcnt lgkmcnt(0)
	v_lshl_add_u64 v[64:65], v[164:165], 0, v[110:111]
	global_load_dwordx4 v[102:105], v[64:65], off
	global_load_dwordx4 v[106:109], v[64:65], off offset:256
	v_add_u32_e32 v96, 0x90, v166
	v_add_u32_e32 v92, 0xa0, v166
	v_add_u32_e32 v88, 0xb0, v166
	v_ashrrev_i32_e32 v97, 31, v96
	v_ashrrev_i32_e32 v93, 31, v92
	v_ashrrev_i32_e32 v89, 31, v88
	v_lshlrev_b64 v[98:99], 12, v[96:97]
	v_lshlrev_b64 v[94:95], 12, v[92:93]
	v_lshlrev_b64 v[90:91], 12, v[88:89]
	v_lshl_add_u64 v[64:65], v[164:165], 0, v[98:99]
	v_lshl_add_u64 v[66:67], v[164:165], 0, v[94:95]
	v_lshl_add_u64 v[112:113], v[164:165], 0, v[90:91]
	global_load_dwordx4 v[84:87], v[64:65], off
	global_load_dwordx4 v[80:83], v[64:65], off offset:256
	global_load_dwordx4 v[76:79], v[66:67], off
	global_load_dwordx4 v[72:75], v[66:67], off offset:256
	global_load_dwordx4 v[68:71], v[112:113], off
	s_nop 0
	global_load_dwordx4 v[64:67], v[112:113], off offset:256
	v_lshl_add_u64 v[112:113], s[16:17], 0, v[110:111]
	v_lshl_add_u64 v[112:113], v[112:113], 0, v[162:163]
	v_lshl_add_u64 v[110:111], s[10:11], 0, v[110:111]
	v_lshl_add_u64 v[110:111], v[110:111], 0, v[162:163]
	s_waitcnt vmcnt(7)
	v_lshlrev_b32_e32 v114, 16, v102
	v_and_b32_e32 v115, 0xffff0000, v102
	v_lshlrev_b32_e32 v102, 16, v103
	v_and_b32_e32 v103, 0xffff0000, v103
	s_waitcnt vmcnt(6)
	v_lshlrev_b32_e32 v118, 16, v106
	v_and_b32_e32 v119, 0xffff0000, v106
	v_lshlrev_b32_e32 v106, 16, v107
	v_and_b32_e32 v107, 0xffff0000, v107
	v_lshlrev_b32_e32 v120, 16, v108
	v_and_b32_e32 v121, 0xffff0000, v108
	v_add_f32_e32 v62, v62, v102
	v_add_f32_e32 v63, v63, v103
	v_add_f32_e32 v60, v60, v114
	v_add_f32_e32 v61, v61, v115
	v_add_f32_e32 v102, v52, v118
	v_add_f32_e32 v103, v53, v119
	v_add_f32_e32 v54, v54, v106
	v_add_f32_e32 v55, v55, v107
	v_add_f32_e32 v106, v48, v120
	v_add_f32_e32 v107, v49, v121
	v_cvt_pk_bf16_f32 v48, v60, v61
	v_mul_f32_e32 v53, v61, v61
	v_mul_f32_e32 v61, v103, v103
	v_fmac_f32_e32 v53, v60, v60
	v_fmac_f32_e32 v61, v102, v102
	v_lshlrev_b32_e32 v116, 16, v104
	v_and_b32_e32 v117, 0xffff0000, v104
	v_fmac_f32_e32 v53, v62, v62
	v_fmac_f32_e32 v61, v54, v54
	v_add_f32_e32 v56, v56, v116
	v_add_f32_e32 v57, v57, v117
	v_fmac_f32_e32 v53, v63, v63
	v_fmac_f32_e32 v61, v55, v55
	v_lshlrev_b32_e32 v104, 16, v105
	v_and_b32_e32 v105, 0xffff0000, v105
	v_lshlrev_b32_e32 v108, 16, v109
	v_and_b32_e32 v109, 0xffff0000, v109
	v_fmac_f32_e32 v53, v56, v56
	v_fmac_f32_e32 v61, v106, v106
	v_add_f32_e32 v58, v58, v104
	v_add_f32_e32 v59, v59, v105
	v_add_f32_e32 v104, v50, v108
	v_add_f32_e32 v105, v51, v109
	v_fmac_f32_e32 v53, v57, v57
	v_fmac_f32_e32 v61, v107, v107
	v_fmac_f32_e32 v53, v58, v58
	v_fmac_f32_e32 v61, v104, v104
	v_fmac_f32_e32 v53, v59, v59
	v_fmac_f32_e32 v61, v105, v105
	v_cvt_pk_bf16_f32 v50, v56, v57
	v_add_f32_e32 v56, v53, v61
	ds_bpermute_b32 v57, v183, v56
	v_cvt_pk_bf16_f32 v49, v62, v63
	v_cvt_pk_bf16_f32 v51, v58, v59
	global_store_dwordx4 v[112:113], v[48:51], off sc1
	v_cvt_pk_bf16_f32 v52, v102, v103
	v_cvt_pk_bf16_f32 v53, v54, v55
	s_waitcnt lgkmcnt(0)
	v_add_f32_e32 v48, v56, v57
	ds_bpermute_b32 v49, v184, v48
	v_add_co_u32_e32 v50, vcc, s55, v110
	v_cvt_pk_bf16_f32 v54, v106, v107
	v_cvt_pk_bf16_f32 v55, v104, v105
	v_addc_co_u32_e32 v51, vcc, 0, v111, vcc
	global_store_dwordx4 v[50:51], v[52:55], off offset:256 sc1
	s_and_saveexec_b64 s[22:23], s[2:3]
	s_cbranch_execz .LBB0_796
	s_waitcnt lgkmcnt(0)
	v_add_f32_e32 v50, v48, v49
	v_lshl_add_u64 v[48:49], v[100:101], 2, s[14:15]
	global_atomic_add_f32 v[48:49], v50, off
; DI u32x2 pk4(f32x4 v) { u32x2 r; r.x = pk2(v[0], v[1]); r.y = pk2(v[2], v[3]); return r; }
; DI float bf_lo(unsigned w) { return __uint_as_float(w << 16); }
; DI float bf_hi(unsigned w) { return __uint_as_float(w & 0xffff0000u); }
; #define COLS4 _Pragma("unroll") for (int bj = 0; bj < 2; ++bj) _Pragma("unroll") for (int n = 0; n < 2; ++n)
;     DI void operator()(const Acc& acc, const Unit& u, int wr, int wc, int fr, int fq) const {
;     ...
;                 for (int m = 0; m < 4; ++m) { const size_t o = (size_t)(row0 + ai * HALF + m * 16) * 2048 + colp;
;                     if (PH == 4) { COLS4 xo[m][bj][n] = *(const f32x4*)(p.x + o + bj * HALF + n * 4); }
;                     else {
; #pragma unroll
;                         for (int bj = 0; bj < 2; ++bj) { const u32x4 w = *(const u32x4*)(WSB(OFF_XB) + o + bj * HALF);
;                             xo[m][bj][0] = (f32x4){bf_lo(w.x), bf_hi(w.x), bf_lo(w.y), bf_hi(w.y)}; xo[m][bj][1] = (f32x4){bf_lo(w.z), bf_hi(w.z), bf_lo(w.w), bf_hi(w.w)}; } } }
; #pragma unroll
;                 for (int m = 0; m < 4; ++m) { const int r = row0 + ai * HALF + m * 16; const size_t o = (size_t)r * 2048 + colp; float part = 0.f;
; #pragma unroll
;                     for (int bj = 0; bj < 2; ++bj) { const f32x4 x0 = xo[m][bj][0] + acc[ai][bj][m][0], x1 = xo[m][bj][1] + acc[ai][bj][m][1];
;                         const u32x2 h0 = pk4(x0), h1 = pk4(x1);
;                         *(u32x4*)(WSB(OFF_XB) + o + bj * HALF) = (u32x4){h0.x, h0.y, h1.x, h1.y};
;                         part += x0[0] * x0[0] + x0[1] * x0[1] + x0[2] * x0[2] + x0[3] * x0[3] + x1[0] * x1[0] + x1[1] * x1[1] + x1[2] * x1[2] + x1[3] * x1[3]; }
;                     part += __shfl_xor(part, 16); part += __shfl_xor(part, 32);
;                     if (fq == 0) unsafeAtomicAdd(ssq + r, part);
.LBB0_796:
	s_or_b64 exec, exec, s[22:23]
	s_waitcnt vmcnt(7)
	v_lshlrev_b32_e32 v48, 16, v84
	s_waitcnt lgkmcnt(0)
	v_and_b32_e32 v49, 0xffff0000, v84
	v_lshlrev_b32_e32 v50, 16, v85
	v_and_b32_e32 v51, 0xffff0000, v85
	v_lshlrev_b32_e32 v52, 16, v86
	v_and_b32_e32 v53, 0xffff0000, v86
	v_lshlrev_b32_e32 v54, 16, v87
	v_and_b32_e32 v55, 0xffff0000, v87
	s_waitcnt vmcnt(6)
	v_lshlrev_b32_e32 v56, 16, v80
	v_and_b32_e32 v57, 0xffff0000, v80
	v_add_f32_e32 v46, v46, v50
	v_add_f32_e32 v47, v47, v51
	v_add_f32_e32 v44, v44, v48
	v_add_f32_e32 v45, v45, v49
	v_add_f32_e32 v48, v42, v54
	v_add_f32_e32 v49, v43, v55
	v_add_f32_e32 v50, v40, v52
	v_add_f32_e32 v51, v41, v53
	v_lshl_add_u64 v[52:53], s[16:17], 0, v[98:99]
	v_lshlrev_b32_e32 v62, 16, v83
	v_and_b32_e32 v63, 0xffff0000, v83
	v_cvt_pk_bf16_f32 v40, v44, v45
	v_cvt_pk_bf16_f32 v41, v46, v47
	v_cvt_pk_bf16_f32 v42, v50, v51
	v_cvt_pk_bf16_f32 v43, v48, v49
	v_lshl_add_u64 v[52:53], v[52:53], 0, v[162:163]
	v_add_f32_e32 v36, v36, v56
	v_add_f32_e32 v37, v37, v57
	v_lshlrev_b32_e32 v58, 16, v81
	v_and_b32_e32 v59, 0xffff0000, v81
	global_store_dwordx4 v[52:53], v[40:43], off sc1
	v_add_f32_e32 v38, v38, v58
	v_add_f32_e32 v39, v39, v59
	v_lshlrev_b32_e32 v60, 16, v82
	v_mul_f32_e32 v42, v45, v45
	v_add_f32_e32 v40, v34, v62
	v_add_f32_e32 v41, v35, v63
	v_cvt_pk_bf16_f32 v34, v36, v37
	v_mul_f32_e32 v37, v37, v37
	v_fmac_f32_e32 v42, v44, v44
	v_fmac_f32_e32 v37, v36, v36
	v_and_b32_e32 v61, 0xffff0000, v82
	v_fmac_f32_e32 v42, v46, v46
	v_fmac_f32_e32 v37, v38, v38
	v_fmac_f32_e32 v42, v47, v47
	v_add_f32_e32 v32, v32, v60
	v_add_f32_e32 v33, v33, v61
	v_fmac_f32_e32 v37, v39, v39
	v_fmac_f32_e32 v42, v50, v50
	v_fmac_f32_e32 v37, v32, v32
	v_fmac_f32_e32 v42, v51, v51
	v_fmac_f32_e32 v37, v33, v33
	v_fmac_f32_e32 v42, v48, v48
	v_fmac_f32_e32 v37, v40, v40
	v_fmac_f32_e32 v42, v49, v49
	v_fmac_f32_e32 v37, v41, v41
	v_add_f32_e32 v42, v42, v37
	ds_bpermute_b32 v43, v183, v42
	v_cvt_pk_bf16_f32 v36, v32, v33
	v_lshl_add_u64 v[32:33], s[10:11], 0, v[98:99]
	v_cvt_pk_bf16_f32 v35, v38, v39
	v_lshl_add_u64 v[38:39], v[32:33], 0, v[162:163]
	s_waitcnt lgkmcnt(0)
	v_add_f32_e32 v32, v42, v43
	ds_bpermute_b32 v33, v184, v32
	v_add_co_u32_e32 v38, vcc, s55, v38
	v_cvt_pk_bf16_f32 v37, v40, v41
	s_nop 0
	v_addc_co_u32_e32 v39, vcc, 0, v39, vcc
	global_store_dwordx4 v[38:39], v[34:37], off offset:256 sc1
	s_and_saveexec_b64 s[22:23], s[2:3]
	s_cbranch_execz .LBB0_798
	s_waitcnt lgkmcnt(0)
	v_add_f32_e32 v34, v32, v33
	v_lshl_add_u64 v[32:33], v[96:97], 2, s[14:15]
	global_atomic_add_f32 v[32:33], v34, off
; DI u32x2 pk4(f32x4 v) { u32x2 r; r.x = pk2(v[0], v[1]); r.y = pk2(v[2], v[3]); return r; }
; DI float bf_lo(unsigned w) { return __uint_as_float(w << 16); }
; DI float bf_hi(unsigned w) { return __uint_as_float(w & 0xffff0000u); }
; #define COLS4 _Pragma("unroll") for (int bj = 0; bj < 2; ++bj) _Pragma("unroll") for (int n = 0; n < 2; ++n)
;     DI void operator()(const Acc& acc, const Unit& u, int wr, int wc, int fr, int fq) const {
;     ...
;                 for (int m = 0; m < 4; ++m) { const size_t o = (size_t)(row0 + ai * HALF + m * 16) * 2048 + colp;
;                     if (PH == 4) { COLS4 xo[m][bj][n] = *(const f32x4*)(p.x + o + bj * HALF + n * 4); }
;                     else {
; #pragma unroll
;                         for (int bj = 0; bj < 2; ++bj) { const u32x4 w = *(const u32x4*)(WSB(OFF_XB) + o + bj * HALF);
;                             xo[m][bj][0] = (f32x4){bf_lo(w.x), bf_hi(w.x), bf_lo(w.y), bf_hi(w.y)}; xo[m][bj][1] = (f32x4){bf_lo(w.z), bf_hi(w.z), bf_lo(w.w), bf_hi(w.w)}; } } }
; #pragma unroll
;                 for (int m = 0; m < 4; ++m) { const int r = row0 + ai * HALF + m * 16; const size_t o = (size_t)r * 2048 + colp; float part = 0.f;
; #pragma unroll
;                     for (int bj = 0; bj < 2; ++bj) { const f32x4 x0 = xo[m][bj][0] + acc[ai][bj][m][0], x1 = xo[m][bj][1] + acc[ai][bj][m][1];
;                         const u32x2 h0 = pk4(x0), h1 = pk4(x1);
;                         *(u32x4*)(WSB(OFF_XB) + o + bj * HALF) = (u32x4){h0.x, h0.y, h1.x, h1.y};
;                         part += x0[0] * x0[0] + x0[1] * x0[1] + x0[2] * x0[2] + x0[3] * x0[3] + x1[0] * x1[0] + x1[1] * x1[1] + x1[2] * x1[2] + x1[3] * x1[3]; }
;                     part += __shfl_xor(part, 16); part += __shfl_xor(part, 32);
;                     if (fq == 0) unsafeAtomicAdd(ssq + r, part);
.LBB0_798:
	s_or_b64 exec, exec, s[22:23]
	s_waitcnt vmcnt(7)
	v_lshlrev_b32_e32 v32, 16, v76
	s_waitcnt lgkmcnt(0)
	v_and_b32_e32 v33, 0xffff0000, v76
	v_lshlrev_b32_e32 v34, 16, v77
	v_and_b32_e32 v35, 0xffff0000, v77
	v_lshlrev_b32_e32 v36, 16, v78
	v_and_b32_e32 v37, 0xffff0000, v78
	v_lshlrev_b32_e32 v38, 16, v79
	v_and_b32_e32 v39, 0xffff0000, v79
	s_waitcnt vmcnt(6)
	v_lshlrev_b32_e32 v40, 16, v72
	v_and_b32_e32 v41, 0xffff0000, v72
	v_add_f32_e32 v30, v30, v34
	v_add_f32_e32 v31, v31, v35
	v_add_f32_e32 v28, v28, v32
	v_add_f32_e32 v29, v29, v33
	v_add_f32_e32 v32, v26, v38
	v_add_f32_e32 v33, v27, v39
	v_add_f32_e32 v34, v24, v36
	v_add_f32_e32 v35, v25, v37
	v_lshl_add_u64 v[36:37], s[16:17], 0, v[94:95]
	v_lshlrev_b32_e32 v46, 16, v75
	v_and_b32_e32 v47, 0xffff0000, v75
	v_cvt_pk_bf16_f32 v24, v28, v29
	v_cvt_pk_bf16_f32 v25, v30, v31
	v_cvt_pk_bf16_f32 v26, v34, v35
	v_cvt_pk_bf16_f32 v27, v32, v33
	v_lshl_add_u64 v[36:37], v[36:37], 0, v[162:163]
	v_add_f32_e32 v20, v20, v40
	v_add_f32_e32 v21, v21, v41
	v_lshlrev_b32_e32 v42, 16, v73
	v_and_b32_e32 v43, 0xffff0000, v73
	global_store_dwordx4 v[36:37], v[24:27], off sc1
	v_add_f32_e32 v22, v22, v42
	v_add_f32_e32 v23, v23, v43
	v_lshlrev_b32_e32 v44, 16, v74
	v_mul_f32_e32 v26, v29, v29
	v_add_f32_e32 v24, v18, v46
	v_add_f32_e32 v25, v19, v47
	v_cvt_pk_bf16_f32 v18, v20, v21
	v_mul_f32_e32 v21, v21, v21
	v_fmac_f32_e32 v26, v28, v28
	v_fmac_f32_e32 v21, v20, v20
	v_and_b32_e32 v45, 0xffff0000, v74
	v_fmac_f32_e32 v26, v30, v30
	v_fmac_f32_e32 v21, v22, v22
	v_fmac_f32_e32 v26, v31, v31
	v_add_f32_e32 v16, v16, v44
	v_add_f32_e32 v17, v17, v45
	v_fmac_f32_e32 v21, v23, v23
	v_fmac_f32_e32 v26, v34, v34
	v_fmac_f32_e32 v21, v16, v16
	v_fmac_f32_e32 v26, v35, v35
	v_fmac_f32_e32 v21, v17, v17
	v_fmac_f32_e32 v26, v32, v32
	v_fmac_f32_e32 v21, v24, v24
	v_fmac_f32_e32 v26, v33, v33
	v_fmac_f32_e32 v21, v25, v25
	v_add_f32_e32 v26, v26, v21
	ds_bpermute_b32 v27, v183, v26
	v_cvt_pk_bf16_f32 v20, v16, v17
	v_lshl_add_u64 v[16:17], s[10:11], 0, v[94:95]
	v_cvt_pk_bf16_f32 v19, v22, v23
	v_lshl_add_u64 v[22:23], v[16:17], 0, v[162:163]
	s_waitcnt lgkmcnt(0)
	v_add_f32_e32 v16, v26, v27
	ds_bpermute_b32 v17, v184, v16
	v_add_co_u32_e32 v22, vcc, s55, v22
	v_cvt_pk_bf16_f32 v21, v24, v25
	s_nop 0
	v_addc_co_u32_e32 v23, vcc, 0, v23, vcc
	global_store_dwordx4 v[22:23], v[18:21], off offset:256 sc1
	s_and_saveexec_b64 s[22:23], s[2:3]
	s_cbranch_execz .LBB0_800
	s_waitcnt lgkmcnt(0)
	v_add_f32_e32 v18, v16, v17
	v_lshl_add_u64 v[16:17], v[92:93], 2, s[14:15]
	global_atomic_add_f32 v[16:17], v18, off
.LBB0_800:
	s_or_b64 exec, exec, s[22:23]
	s_waitcnt vmcnt(7)
	v_lshlrev_b32_e32 v16, 16, v68
	s_waitcnt lgkmcnt(0)
	v_and_b32_e32 v17, 0xffff0000, v68
	v_lshlrev_b32_e32 v18, 16, v69
	v_and_b32_e32 v19, 0xffff0000, v69
	v_lshlrev_b32_e32 v20, 16, v70
	v_and_b32_e32 v21, 0xffff0000, v70
	v_lshlrev_b32_e32 v22, 16, v71
	v_and_b32_e32 v23, 0xffff0000, v71
	s_waitcnt vmcnt(6)
	v_lshlrev_b32_e32 v24, 16, v64
	v_and_b32_e32 v25, 0xffff0000, v64
	v_add_f32_e32 v14, v14, v18
	v_add_f32_e32 v15, v15, v19
	v_add_f32_e32 v12, v12, v16
	v_add_f32_e32 v13, v13, v17
	v_add_f32_e32 v16, v10, v22
	v_add_f32_e32 v17, v11, v23
	v_add_f32_e32 v18, v8, v20
	v_add_f32_e32 v19, v9, v21
	v_lshl_add_u64 v[20:21], s[16:17], 0, v[90:91]
	v_lshlrev_b32_e32 v30, 16, v67
	v_and_b32_e32 v31, 0xffff0000, v67
	v_cvt_pk_bf16_f32 v8, v12, v13
	v_cvt_pk_bf16_f32 v9, v14, v15
	v_cvt_pk_bf16_f32 v10, v18, v19
	v_cvt_pk_bf16_f32 v11, v16, v17
	v_lshl_add_u64 v[20:21], v[20:21], 0, v[162:163]
	v_add_f32_e32 v4, v4, v24
	v_add_f32_e32 v5, v5, v25
	v_lshlrev_b32_e32 v26, 16, v65
	v_and_b32_e32 v27, 0xffff0000, v65
	global_store_dwordx4 v[20:21], v[8:11], off sc1
	v_add_f32_e32 v6, v6, v26
	v_add_f32_e32 v7, v7, v27
	v_lshlrev_b32_e32 v28, 16, v66
	v_mul_f32_e32 v10, v13, v13
	v_add_f32_e32 v8, v2, v30
	v_add_f32_e32 v9, v3, v31
	v_cvt_pk_bf16_f32 v2, v4, v5
	v_mul_f32_e32 v5, v5, v5
	v_fmac_f32_e32 v10, v12, v12
	v_fmac_f32_e32 v5, v4, v4
	v_and_b32_e32 v29, 0xffff0000, v66
	v_fmac_f32_e32 v10, v14, v14
	v_fmac_f32_e32 v5, v6, v6
	v_fmac_f32_e32 v10, v15, v15
	v_add_f32_e32 v0, v0, v28
	v_add_f32_e32 v1, v1, v29
	v_fmac_f32_e32 v5, v7, v7
	v_fmac_f32_e32 v10, v18, v18
	v_fmac_f32_e32 v5, v0, v0
	v_fmac_f32_e32 v10, v19, v19
	v_fmac_f32_e32 v5, v1, v1
	v_fmac_f32_e32 v10, v16, v16
	v_fmac_f32_e32 v5, v8, v8
	v_fmac_f32_e32 v10, v17, v17
	v_fmac_f32_e32 v5, v9, v9
	v_add_f32_e32 v10, v10, v5
	ds_bpermute_b32 v11, v183, v10
	v_cvt_pk_bf16_f32 v4, v0, v1
	v_lshl_add_u64 v[0:1], s[10:11], 0, v[90:91]
	v_cvt_pk_bf16_f32 v3, v6, v7
	v_lshl_add_u64 v[6:7], v[0:1], 0, v[162:163]
	s_waitcnt lgkmcnt(0)
	v_add_f32_e32 v0, v10, v11
	ds_bpermute_b32 v1, v184, v0
	v_add_co_u32_e32 v6, vcc, s55, v6
	v_cvt_pk_bf16_f32 v5, v8, v9
	s_nop 0
	v_addc_co_u32_e32 v7, vcc, 0, v7, vcc
	global_store_dwordx4 v[6:7], v[2:5], off offset:256 sc1
	s_and_saveexec_b64 s[22:23], s[2:3]
	s_cbranch_execz .LBB0_777
	s_waitcnt lgkmcnt(0)
	v_add_f32_e32 v2, v0, v1
	v_lshl_add_u64 v[0:1], v[88:89], 2, s[14:15]
	global_atomic_add_f32 v[0:1], v2, off
	s_branch .LBB0_777

; #define PG8_STAGE(bufoff, gbase, voff) do { _Pragma("unroll") for (int _i = 0; _i < 2; ++_i) \
;         __builtin_amdgcn_global_load_lds((const unsigned*)((const char*)(gbase) + (voff)[_i]), (LAS unsigned*)(lds + (bufoff) + ldsw + _i * 8192), 16, 0, 0); } while (0)
; #define PG8_LDA(dst, b, h) do { _Pragma("unroll") for (int m = 0; m < 4; ++m) _Pragma("unroll") for (int k = 0; k < 2; ++k) dst[m][k] = *(const LAS bf16x8*)(lds + PG8_SA(b, h) + aoff + m * 2048 + k * 1024); } while (0)
; #define PG8_LDB(dst, b, h) do { _Pragma("unroll") for (int n = 0; n < 2; ++n) _Pragma("unroll") for (int k = 0; k < 2; ++k) dst[n][k] = *(const LAS bf16x8*)(lds + PG8_SB(b, h) + boff + n * 2048 + k * 1024); } while (0)
; #define PG8_MMA(ai, bj, At, Bt) do { __builtin_amdgcn_s_setprio(1); _Pragma("unroll") for (int m = 0; m < 4; ++m) _Pragma("unroll") for (int n = 0; n < 2; ++n) _Pragma("unroll") for (int k = 0; k < 2; ++k) \
;         acc[ai][bj][m][n] = __builtin_amdgcn_mfma_f32_16x16x32_bf16(Bt[n][k], At[m][k], acc[ai][bj][m][n], 0, 0, 0); __builtin_amdgcn_s_setprio(0); } while (0)
; #define PG8_WAIT_V(n) asm volatile("s_waitcnt vmcnt(" #n ")" ::: "memory")
; #define PG8_WAIT_L(n) asm volatile("s_waitcnt lgkmcnt(" #n ")" ::: "memory")
; #define PG8_BAR __builtin_amdgcn_s_barrier()
; #define PG8_SCHED __builtin_amdgcn_sched_barrier(0)
; template <class Epi>
; DI void gemm_phase(LAS unsigned char* lds, int wid, int K, int lda, int ldb, bool bperm, const Sched3& S, const Epi& E) {
;     ...
;             PG8_LDB(B0, 0, 0); PG8_SCHED; PG8_LDA(At, 0, 0); PG8_STAGE(PG8_SA(1, 1), a1 + hA, voffA);
;             PG8_WAIT_L(8); PG8_BAR; PG8_WAIT_L(0); PG8_MMA(0, 0, At, B0); PG8_BAR; PG8_SCHED;
;             PG8_LDB(B1, 0, 1); PG8_STAGE(PG8_SB(0, 0), b2, voffB);
;             PG8_BAR; PG8_WAIT_L(0); PG8_MMA(0, 1, At, B1); PG8_BAR;
;             PG8_LDA(At, 0, 1); PG8_STAGE(PG8_SA(0, 0), a2, voffA);
;             PG8_BAR; PG8_WAIT_L(0); if (full) PG8_MMA(1, 0, At, B0); PG8_BAR; PG8_SCHED;
;             PG8_STAGE(PG8_SB(0, 1), b2 + hstepB, voffB);
;             PG8_WAIT_V(6); PG8_BAR; if (full) PG8_MMA(1, 1, At, B1); PG8_BAR;
.LBB0_873:
	ds_read_b128 v[128:131], v189
	ds_read_b128 v[132:135], v189 offset:1024
	ds_read_b128 v[136:139], v189 offset:2048
	ds_read_b128 v[140:143], v189 offset:3072
	s_add_u32 s38, s36, 0xfff80080
	s_addc_u32 s39, s37, -1
	s_cmp_eq_u32 s27, 28
	s_cselect_b32 s41, s29, s39
	s_cselect_b32 s40, s28, s38
	s_cselect_b32 s39, s31, s21
	s_cselect_b32 s38, s30, s19
	v_lshl_add_u64 v[168:169], s[36:37], 0, v[160:161]
	s_add_i32 m0, s48, 0xc000
	ds_read_b128 v[180:183], v195
	ds_read_b128 v[190:193], v195 offset:1024
	ds_read_b128 v[200:203], v195 offset:2048
	ds_read_b128 v[204:207], v195 offset:3072
	ds_read_b128 v[208:211], v195 offset:4096
	ds_read_b128 v[212:215], v195 offset:5120
	ds_read_b128 v[216:219], v195 offset:6144
	ds_read_b128 v[224:227], v195 offset:7168
	global_load_lds_dwordx4 v[168:169], off
	v_lshl_add_u64 v[168:169], s[36:37], 0, v[162:163]
	s_add_i32 m0, s48, 0xe000
	s_nop 0
	global_load_lds_dwordx4 v[168:169], off
	s_waitcnt lgkmcnt(8)
	s_barrier
	s_waitcnt lgkmcnt(0)
	s_setprio 1
	s_waitcnt lgkmcnt(0)
	v_mfma_f32_16x16x32_bf16 v[124:127], v[128:131], v[180:183], v[124:127]
	v_mfma_f32_16x16x32_bf16 v[120:123], v[136:139], v[180:183], v[120:123]
	v_mfma_f32_16x16x32_bf16 v[108:111], v[128:131], v[200:203], v[108:111]
	v_mfma_f32_16x16x32_bf16 v[104:107], v[136:139], v[200:203], v[104:107]
	v_mfma_f32_16x16x32_bf16 v[92:95], v[128:131], v[208:211], v[92:95]
	v_mfma_f32_16x16x32_bf16 v[88:91], v[136:139], v[208:211], v[88:91]
	v_mfma_f32_16x16x32_bf16 v[76:79], v[128:131], v[216:219], v[76:79]
	v_mfma_f32_16x16x32_bf16 v[72:75], v[136:139], v[216:219], v[72:75]
	v_mfma_f32_16x16x32_bf16 v[124:127], v[132:135], v[190:193], v[124:127]
	v_mfma_f32_16x16x32_bf16 v[120:123], v[140:143], v[190:193], v[120:123]
	v_mfma_f32_16x16x32_bf16 v[108:111], v[132:135], v[204:207], v[108:111]
	v_mfma_f32_16x16x32_bf16 v[104:107], v[140:143], v[204:207], v[104:107]
	v_mfma_f32_16x16x32_bf16 v[92:95], v[132:135], v[212:215], v[92:95]
	v_mfma_f32_16x16x32_bf16 v[88:91], v[140:143], v[212:215], v[88:91]
	v_mfma_f32_16x16x32_bf16 v[76:79], v[132:135], v[224:227], v[76:79]
	v_mfma_f32_16x16x32_bf16 v[72:75], v[140:143], v[224:227], v[72:75]
	s_setprio 0
	s_barrier
	s_add_i32 s64, s59, s47
	v_lshl_add_u64 v[168:169], s[38:39], 0, v[146:147]
	s_mov_b32 m0, s64
	ds_read_b128 v[228:231], v197
	ds_read_b128 v[232:235], v197 offset:1024
	ds_read_b128 v[236:239], v197 offset:2048
	ds_read_b128 v[240:243], v197 offset:3072
	global_load_lds_dwordx4 v[168:169], off
	v_lshl_add_u64 v[172:173], s[38:39], 0, v[150:151]
	s_add_i32 m0, s64, 0x2000
	s_nop 0
	global_load_lds_dwordx4 v[172:173], off
	s_barrier
	s_waitcnt lgkmcnt(0)
	s_setprio 1
	s_waitcnt lgkmcnt(0)
	v_mfma_f32_16x16x32_bf16 v[116:119], v[228:231], v[180:183], v[116:119]
	v_mfma_f32_16x16x32_bf16 v[112:115], v[236:239], v[180:183], v[112:115]
	v_mfma_f32_16x16x32_bf16 v[100:103], v[228:231], v[200:203], v[100:103]
	v_mfma_f32_16x16x32_bf16 v[96:99], v[236:239], v[200:203], v[96:99]
	v_mfma_f32_16x16x32_bf16 v[84:87], v[228:231], v[208:211], v[84:87]
	v_mfma_f32_16x16x32_bf16 v[80:83], v[236:239], v[208:211], v[80:83]
	v_mfma_f32_16x16x32_bf16 v[68:71], v[228:231], v[216:219], v[68:71]
	v_mfma_f32_16x16x32_bf16 v[64:67], v[236:239], v[216:219], v[64:67]
	v_mfma_f32_16x16x32_bf16 v[116:119], v[232:235], v[190:193], v[116:119]
	v_mfma_f32_16x16x32_bf16 v[112:115], v[240:243], v[190:193], v[112:115]
	v_mfma_f32_16x16x32_bf16 v[100:103], v[232:235], v[204:207], v[100:103]
	v_mfma_f32_16x16x32_bf16 v[96:99], v[240:243], v[204:207], v[96:99]
	v_mfma_f32_16x16x32_bf16 v[84:87], v[232:235], v[212:215], v[84:87]
	v_mfma_f32_16x16x32_bf16 v[80:83], v[240:243], v[212:215], v[80:83]
	v_mfma_f32_16x16x32_bf16 v[68:71], v[232:235], v[224:227], v[68:71]
	v_mfma_f32_16x16x32_bf16 v[64:67], v[240:243], v[224:227], v[64:67]
	s_setprio 0
	s_mov_b32 m0, s48
	v_lshl_add_u64 v[176:177], s[40:41], 0, v[144:145]
	s_barrier
	ds_read_b128 v[180:183], v195 offset:16384
	ds_read_b128 v[190:193], v195 offset:17408
	ds_read_b128 v[200:203], v195 offset:18432
	ds_read_b128 v[204:207], v195 offset:19456
	ds_read_b128 v[208:211], v195 offset:20480
	ds_read_b128 v[212:215], v195 offset:21504
	ds_read_b128 v[216:219], v195 offset:22528
	ds_read_b128 v[224:227], v195 offset:23552
	global_load_lds_dwordx4 v[176:177], off
	v_lshl_add_u64 v[186:187], s[40:41], 0, v[148:149]
	s_mov_b32 m0, s49
	s_nop 0
	global_load_lds_dwordx4 v[186:187], off
	s_barrier
	s_waitcnt lgkmcnt(0)
	s_setprio 1
	s_waitcnt lgkmcnt(0)
	v_mfma_f32_16x16x32_bf16 v[60:63], v[128:131], v[180:183], v[60:63]
	v_mfma_f32_16x16x32_bf16 v[56:59], v[136:139], v[180:183], v[56:59]
	v_mfma_f32_16x16x32_bf16 v[44:47], v[128:131], v[200:203], v[44:47]
	v_mfma_f32_16x16x32_bf16 v[40:43], v[136:139], v[200:203], v[40:43]
	v_mfma_f32_16x16x32_bf16 v[28:31], v[128:131], v[208:211], v[28:31]
	v_mfma_f32_16x16x32_bf16 v[24:27], v[136:139], v[208:211], v[24:27]
	v_mfma_f32_16x16x32_bf16 v[12:15], v[128:131], v[216:219], v[12:15]
	v_mfma_f32_16x16x32_bf16 v[8:11], v[136:139], v[216:219], v[8:11]
	v_mfma_f32_16x16x32_bf16 v[60:63], v[132:135], v[190:193], v[60:63]
	v_mfma_f32_16x16x32_bf16 v[56:59], v[140:143], v[190:193], v[56:59]
	v_mfma_f32_16x16x32_bf16 v[44:47], v[132:135], v[204:207], v[44:47]
	v_mfma_f32_16x16x32_bf16 v[40:43], v[140:143], v[204:207], v[40:43]
	v_mfma_f32_16x16x32_bf16 v[28:31], v[132:135], v[212:215], v[28:31]
	v_mfma_f32_16x16x32_bf16 v[24:27], v[140:143], v[212:215], v[24:27]
	v_mfma_f32_16x16x32_bf16 v[12:15], v[132:135], v[224:227], v[12:15]
	v_mfma_f32_16x16x32_bf16 v[8:11], v[140:143], v[224:227], v[8:11]
	s_setprio 0
	s_barrier
; #define PG8_STAGE(bufoff, gbase, voff) do { _Pragma("unroll") for (int _i = 0; _i < 2; ++_i) \
;         __builtin_amdgcn_global_load_lds((const unsigned*)((const char*)(gbase) + (voff)[_i]), (LAS unsigned*)(lds + (bufoff) + ldsw + _i * 8192), 16, 0, 0); } while (0)
; #define PG8_LDA(dst, b, h) do { _Pragma("unroll") for (int m = 0; m < 4; ++m) _Pragma("unroll") for (int k = 0; k < 2; ++k) dst[m][k] = *(const LAS bf16x8*)(lds + PG8_SA(b, h) + aoff + m * 2048 + k * 1024); } while (0)
; #define PG8_LDB(dst, b, h) do { _Pragma("unroll") for (int n = 0; n < 2; ++n) _Pragma("unroll") for (int k = 0; k < 2; ++k) dst[n][k] = *(const LAS bf16x8*)(lds + PG8_SB(b, h) + boff + n * 2048 + k * 1024); } while (0)
; #define PG8_MMA(ai, bj, At, Bt) do { __builtin_amdgcn_s_setprio(1); _Pragma("unroll") for (int m = 0; m < 4; ++m) _Pragma("unroll") for (int n = 0; n < 2; ++n) _Pragma("unroll") for (int k = 0; k < 2; ++k) \
;         acc[ai][bj][m][n] = __builtin_amdgcn_mfma_f32_16x16x32_bf16(Bt[n][k], At[m][k], acc[ai][bj][m][n], 0, 0, 0); __builtin_amdgcn_s_setprio(0); } while (0)
; #define PG8_WAIT_V(n) asm volatile("s_waitcnt vmcnt(" #n ")" ::: "memory")
; #define PG8_WAIT_L(n) asm volatile("s_waitcnt lgkmcnt(" #n ")" ::: "memory")
; #define PG8_BAR __builtin_amdgcn_s_barrier()
; #define PG8_SCHED __builtin_amdgcn_sched_barrier(0)
; template <class Epi>
; DI void gemm_phase(LAS unsigned char* lds, int wid, int K, int lda, int ldb, bool bperm, const Sched3& S, const Epi& E) {
;     ...
;             PG8_STAGE(PG8_SB(0, 1), b2 + hstepB, voffB);
;             PG8_WAIT_V(6); PG8_BAR; if (full) PG8_MMA(1, 1, At, B1); PG8_BAR;
;             PG8_LDB(B0, 1, 0); PG8_SCHED; PG8_LDA(At, 1, 0); PG8_STAGE(PG8_SA(0, 1), a2 + h2, voffA);
;             PG8_WAIT_L(8); PG8_BAR; PG8_WAIT_L(0); PG8_MMA(0, 0, At, B0); PG8_BAR; PG8_SCHED;
;             PG8_LDB(B1, 1, 1); PG8_STAGE(PG8_SB(1, 0), b3, voffB);
;             PG8_BAR; PG8_WAIT_L(0); PG8_MMA(0, 1, At, B1); PG8_BAR;
;             PG8_LDA(At, 1, 1); PG8_STAGE(PG8_SA(1, 0), a3, voffA);
	s_add_u32 s64, s38, 0x80000
	s_addc_u32 s65, s39, 0
	s_add_i32 s66, s60, s47
	v_lshl_add_u64 v[128:129], s[64:65], 0, v[146:147]
	s_mov_b32 m0, s66
	s_nop 0
	global_load_lds_dwordx4 v[128:129], off
	v_lshl_add_u64 v[128:129], s[64:65], 0, v[150:151]
	s_add_i32 m0, s66, 0x2000
	s_nop 0
	global_load_lds_dwordx4 v[128:129], off
	s_waitcnt vmcnt(6)
	s_barrier
	s_setprio 1
	v_mfma_f32_16x16x32_bf16 v[52:55], v[228:231], v[180:183], v[52:55]
	v_mfma_f32_16x16x32_bf16 v[48:51], v[236:239], v[180:183], v[48:51]
	v_mfma_f32_16x16x32_bf16 v[36:39], v[228:231], v[200:203], v[36:39]
	v_mfma_f32_16x16x32_bf16 v[32:35], v[236:239], v[200:203], v[32:35]
	v_mfma_f32_16x16x32_bf16 v[20:23], v[228:231], v[208:211], v[20:23]
	v_mfma_f32_16x16x32_bf16 v[16:19], v[236:239], v[208:211], v[16:19]
	v_mfma_f32_16x16x32_bf16 v[4:7], v[228:231], v[216:219], v[4:7]
	v_mfma_f32_16x16x32_bf16 v[0:3], v[236:239], v[216:219], v[0:3]
	v_mfma_f32_16x16x32_bf16 v[52:55], v[232:235], v[190:193], v[52:55]
	v_mfma_f32_16x16x32_bf16 v[48:51], v[240:243], v[190:193], v[48:51]
	v_mfma_f32_16x16x32_bf16 v[36:39], v[232:235], v[204:207], v[36:39]
	v_mfma_f32_16x16x32_bf16 v[32:35], v[240:243], v[204:207], v[32:35]
	v_mfma_f32_16x16x32_bf16 v[20:23], v[232:235], v[212:215], v[20:23]
	v_mfma_f32_16x16x32_bf16 v[16:19], v[240:243], v[212:215], v[16:19]
	v_mfma_f32_16x16x32_bf16 v[4:7], v[232:235], v[224:227], v[4:7]
	v_mfma_f32_16x16x32_bf16 v[0:3], v[240:243], v[224:227], v[0:3]
	s_setprio 0
	s_add_i32 s64, 0, 0x18000
	v_add_u32_e32 v140, s64, v171
	s_barrier
	ds_read_b128 v[128:131], v140
	ds_read_b128 v[132:135], v140 offset:1024
	ds_read_b128 v[136:139], v140 offset:2048
	ds_read_b128 v[140:143], v140 offset:3072
	s_add_u32 s40, s40, 0x80000
	s_addc_u32 s41, s41, 0
	s_mov_b32 m0, s50
	v_lshl_add_u64 v[220:221], s[40:41], 0, v[144:145]
	ds_read_b128 v[180:183], v195 offset:32768
	ds_read_b128 v[190:193], v195 offset:33792
	ds_read_b128 v[200:203], v195 offset:34816
	ds_read_b128 v[204:207], v195 offset:35840
	ds_read_b128 v[208:211], v195 offset:36864
	ds_read_b128 v[212:215], v195 offset:37888
	ds_read_b128 v[216:219], v195 offset:38912
	ds_read_b128 v[224:227], v195 offset:39936
	global_load_lds_dwordx4 v[220:221], off
	v_lshl_add_u64 v[220:221], s[40:41], 0, v[148:149]
	s_mov_b32 m0, s51
	s_nop 0
	global_load_lds_dwordx4 v[220:221], off
	s_waitcnt lgkmcnt(8)
	s_barrier
	s_waitcnt lgkmcnt(0)
	s_setprio 1
	s_waitcnt lgkmcnt(0)
	v_mfma_f32_16x16x32_bf16 v[124:127], v[128:131], v[180:183], v[124:127]
	v_mfma_f32_16x16x32_bf16 v[120:123], v[136:139], v[180:183], v[120:123]
	v_mfma_f32_16x16x32_bf16 v[108:111], v[128:131], v[200:203], v[108:111]
	v_mfma_f32_16x16x32_bf16 v[104:107], v[136:139], v[200:203], v[104:107]
	v_mfma_f32_16x16x32_bf16 v[92:95], v[128:131], v[208:211], v[92:95]
	v_mfma_f32_16x16x32_bf16 v[88:91], v[136:139], v[208:211], v[88:91]
	v_mfma_f32_16x16x32_bf16 v[76:79], v[128:131], v[216:219], v[76:79]
	v_mfma_f32_16x16x32_bf16 v[72:75], v[136:139], v[216:219], v[72:75]
	v_mfma_f32_16x16x32_bf16 v[124:127], v[132:135], v[190:193], v[124:127]
	v_mfma_f32_16x16x32_bf16 v[120:123], v[140:143], v[190:193], v[120:123]
	v_mfma_f32_16x16x32_bf16 v[108:111], v[132:135], v[204:207], v[108:111]
	v_mfma_f32_16x16x32_bf16 v[104:107], v[140:143], v[204:207], v[104:107]
	v_mfma_f32_16x16x32_bf16 v[92:95], v[132:135], v[212:215], v[92:95]
	v_mfma_f32_16x16x32_bf16 v[88:91], v[140:143], v[212:215], v[88:91]
	v_mfma_f32_16x16x32_bf16 v[76:79], v[132:135], v[224:227], v[76:79]
	v_mfma_f32_16x16x32_bf16 v[72:75], v[140:143], v[224:227], v[72:75]
	s_setprio 0
	s_barrier
	s_add_i32 s40, 0, 0x1c000
	s_add_i32 s41, s64, s47
	v_add_u32_e32 v152, s40, v171
	v_lshl_add_u64 v[168:169], v[168:169], 0, s[12:13]
	s_mov_b32 m0, s41
	ds_read_b128 v[228:231], v152
	ds_read_b128 v[232:235], v152 offset:1024
	ds_read_b128 v[236:239], v152 offset:2048
	ds_read_b128 v[240:243], v152 offset:3072
	global_load_lds_dwordx4 v[168:169], off
	v_lshl_add_u64 v[168:169], v[172:173], 0, s[12:13]
	s_add_i32 m0, s41, 0x2000
	s_nop 0
	global_load_lds_dwordx4 v[168:169], off
	s_barrier
	s_waitcnt lgkmcnt(0)
	s_setprio 1
	s_waitcnt lgkmcnt(0)
	v_mfma_f32_16x16x32_bf16 v[116:119], v[228:231], v[180:183], v[116:119]
	v_mfma_f32_16x16x32_bf16 v[112:115], v[236:239], v[180:183], v[112:115]
	v_mfma_f32_16x16x32_bf16 v[100:103], v[228:231], v[200:203], v[100:103]
	v_mfma_f32_16x16x32_bf16 v[96:99], v[236:239], v[200:203], v[96:99]
	v_mfma_f32_16x16x32_bf16 v[84:87], v[228:231], v[208:211], v[84:87]
	v_mfma_f32_16x16x32_bf16 v[80:83], v[236:239], v[208:211], v[80:83]
	v_mfma_f32_16x16x32_bf16 v[68:71], v[228:231], v[216:219], v[68:71]
	v_mfma_f32_16x16x32_bf16 v[64:67], v[236:239], v[216:219], v[64:67]
	v_mfma_f32_16x16x32_bf16 v[116:119], v[232:235], v[190:193], v[116:119]
	v_mfma_f32_16x16x32_bf16 v[112:115], v[240:243], v[190:193], v[112:115]
	v_mfma_f32_16x16x32_bf16 v[100:103], v[232:235], v[204:207], v[100:103]
	v_mfma_f32_16x16x32_bf16 v[96:99], v[240:243], v[204:207], v[96:99]
	v_mfma_f32_16x16x32_bf16 v[84:87], v[232:235], v[212:215], v[84:87]
	v_mfma_f32_16x16x32_bf16 v[80:83], v[240:243], v[212:215], v[80:83]
	v_mfma_f32_16x16x32_bf16 v[68:71], v[232:235], v[224:227], v[68:71]
	v_mfma_f32_16x16x32_bf16 v[64:67], v[240:243], v[224:227], v[64:67]
	s_setprio 0
	s_mov_b32 m0, s53
	v_lshl_add_u64 v[168:169], v[176:177], 0, s[12:13]
	s_barrier
	ds_read_b128 v[180:183], v195 offset:49152
	ds_read_b128 v[190:193], v195 offset:50176
	ds_read_b128 v[200:203], v195 offset:51200
	ds_read_b128 v[204:207], v195 offset:52224
	ds_read_b128 v[208:211], v195 offset:53248
	ds_read_b128 v[212:215], v195 offset:54272
	ds_read_b128 v[216:219], v195 offset:55296
	ds_read_b128 v[224:227], v195 offset:56320
	global_load_lds_dwordx4 v[168:169], off
	v_lshl_add_u64 v[168:169], v[186:187], 0, s[12:13]
	s_mov_b32 m0, s54
	s_nop 0
	global_load_lds_dwordx4 v[168:169], off
	s_barrier
; #define PG8_STAGE(bufoff, gbase, voff) do { _Pragma("unroll") for (int _i = 0; _i < 2; ++_i) \
;         __builtin_amdgcn_global_load_lds((const unsigned*)((const char*)(gbase) + (voff)[_i]), (LAS unsigned*)(lds + (bufoff) + ldsw + _i * 8192), 16, 0, 0); } while (0)
; #define PG8_MMA(ai, bj, At, Bt) do { __builtin_amdgcn_s_setprio(1); _Pragma("unroll") for (int m = 0; m < 4; ++m) _Pragma("unroll") for (int n = 0; n < 2; ++n) _Pragma("unroll") for (int k = 0; k < 2; ++k) \
;         acc[ai][bj][m][n] = __builtin_amdgcn_mfma_f32_16x16x32_bf16(Bt[n][k], At[m][k], acc[ai][bj][m][n], 0, 0, 0); __builtin_amdgcn_s_setprio(0); } while (0)
; #define PG8_WAIT_V(n) asm volatile("s_waitcnt vmcnt(" #n ")" ::: "memory")
; #define PG8_WAIT_L(n) asm volatile("s_waitcnt lgkmcnt(" #n ")" ::: "memory")
; #define PG8_BAR __builtin_amdgcn_s_barrier()
; #define PG8_SCHED __builtin_amdgcn_sched_barrier(0)
; #define LOAD_ROW_RS(rsv, ssqp, invn) float rsv[2][4]; ROWS8_ALL rsv[ai][m] = (ssqp)[row0 + ai * HALF + m * 16]; ROWS8_ALL rsv[ai][m] = rstd_of(rsv[ai][m], invn)
; template <class Epi>
; DI void gemm_phase(LAS unsigned char* lds, int wid, int K, int lda, int ldb, bool bperm, const Sched3& S, const Epi& E) {
;     ...
;             PG8_BAR; PG8_WAIT_L(0); if (full) PG8_MMA(1, 0, At, B0); PG8_BAR; PG8_SCHED;
;             PG8_STAGE(PG8_SB(1, 1), b3 + hstepB, voffB);
;             PG8_WAIT_V(6); PG8_BAR; if (full) PG8_MMA(1, 1, At, B1); PG8_BAR;
;     DI void operator()(const Acc& acc, const Unit& u, int wr, int wc, int fr, int fq) const {
;     ...
;             LOAD_ROW_RS(rsv, SSQ(3), 1.f / 2048.f);
	s_waitcnt lgkmcnt(0)
	s_setprio 1
	s_waitcnt lgkmcnt(0)
	v_mfma_f32_16x16x32_bf16 v[60:63], v[128:131], v[180:183], v[60:63]
	v_mfma_f32_16x16x32_bf16 v[56:59], v[136:139], v[180:183], v[56:59]
	v_mfma_f32_16x16x32_bf16 v[44:47], v[128:131], v[200:203], v[44:47]
	v_mfma_f32_16x16x32_bf16 v[40:43], v[136:139], v[200:203], v[40:43]
	v_mfma_f32_16x16x32_bf16 v[28:31], v[128:131], v[208:211], v[28:31]
	v_mfma_f32_16x16x32_bf16 v[24:27], v[136:139], v[208:211], v[24:27]
	v_mfma_f32_16x16x32_bf16 v[12:15], v[128:131], v[216:219], v[12:15]
	v_mfma_f32_16x16x32_bf16 v[8:11], v[136:139], v[216:219], v[8:11]
	v_mfma_f32_16x16x32_bf16 v[60:63], v[132:135], v[190:193], v[60:63]
	v_mfma_f32_16x16x32_bf16 v[56:59], v[140:143], v[190:193], v[56:59]
	v_mfma_f32_16x16x32_bf16 v[44:47], v[132:135], v[204:207], v[44:47]
	v_mfma_f32_16x16x32_bf16 v[40:43], v[140:143], v[204:207], v[40:43]
	v_mfma_f32_16x16x32_bf16 v[28:31], v[132:135], v[212:215], v[28:31]
	v_mfma_f32_16x16x32_bf16 v[24:27], v[140:143], v[212:215], v[24:27]
	v_mfma_f32_16x16x32_bf16 v[12:15], v[132:135], v[224:227], v[12:15]
	v_mfma_f32_16x16x32_bf16 v[8:11], v[140:143], v[224:227], v[8:11]
	s_setprio 0
	s_barrier
	s_add_u32 s38, s38, 0x80080
	s_addc_u32 s39, s39, 0
	s_add_i32 s40, s40, s47
	v_lshl_add_u64 v[128:129], s[38:39], 0, v[146:147]
	s_mov_b32 m0, s40
	s_nop 0
	global_load_lds_dwordx4 v[128:129], off
	v_lshl_add_u64 v[128:129], s[38:39], 0, v[150:151]
	s_add_i32 m0, s40, 0x2000
	s_nop 0
	global_load_lds_dwordx4 v[128:129], off
	s_waitcnt vmcnt(6)
	s_barrier
	s_setprio 1
	v_mfma_f32_16x16x32_bf16 v[52:55], v[228:231], v[180:183], v[52:55]
	v_mfma_f32_16x16x32_bf16 v[48:51], v[236:239], v[180:183], v[48:51]
	v_mfma_f32_16x16x32_bf16 v[36:39], v[228:231], v[200:203], v[36:39]
	v_mfma_f32_16x16x32_bf16 v[32:35], v[236:239], v[200:203], v[32:35]
	v_mfma_f32_16x16x32_bf16 v[20:23], v[228:231], v[208:211], v[20:23]
	v_mfma_f32_16x16x32_bf16 v[16:19], v[236:239], v[208:211], v[16:19]
	v_mfma_f32_16x16x32_bf16 v[4:7], v[228:231], v[216:219], v[4:7]
	v_mfma_f32_16x16x32_bf16 v[0:3], v[236:239], v[216:219], v[0:3]
	v_mfma_f32_16x16x32_bf16 v[52:55], v[232:235], v[190:193], v[52:55]
	v_mfma_f32_16x16x32_bf16 v[48:51], v[240:243], v[190:193], v[48:51]
	v_mfma_f32_16x16x32_bf16 v[36:39], v[232:235], v[204:207], v[36:39]
	v_mfma_f32_16x16x32_bf16 v[32:35], v[240:243], v[204:207], v[32:35]
	v_mfma_f32_16x16x32_bf16 v[20:23], v[232:235], v[212:215], v[20:23]
	v_mfma_f32_16x16x32_bf16 v[16:19], v[240:243], v[212:215], v[16:19]
	v_mfma_f32_16x16x32_bf16 v[4:7], v[232:235], v[224:227], v[4:7]
	v_mfma_f32_16x16x32_bf16 v[0:3], v[240:243], v[224:227], v[0:3]
	s_setprio 0
	s_add_i32 s27, s27, 2
	s_add_u32 s36, s36, 0x100
	s_addc_u32 s37, s37, 0
	s_add_u32 s19, s19, 0x100
	s_addc_u32 s21, s21, 0
	s_cmp_gt_u32 s27, 29
	s_barrier
	s_cbranch_scc0 .LBB0_873
	v_lshl_add_u32 v192, s26, 8, v167
	v_or_b32_e32 v190, 16, v192
	v_or_b32_e32 v186, 32, v192
	v_ashrrev_i32_e32 v193, 31, v192
	v_ashrrev_i32_e32 v191, 31, v190
	v_ashrrev_i32_e32 v187, 31, v186
	v_or_b32_e32 v182, 48, v192
	v_lshl_add_u64 v[128:129], v[192:193], 2, s[16:17]
	v_lshl_add_u64 v[130:131], v[190:191], 2, s[16:17]
	v_lshl_add_u64 v[132:133], v[186:187], 2, s[16:17]
	v_ashrrev_i32_e32 v183, 31, v182
	global_load_dword v136, v[128:129], off
	global_load_dword v137, v[128:129], off offset:512
	global_load_dword v138, v[128:129], off offset:576
	global_load_dword v139, v[128:129], off offset:640
	v_lshl_add_u64 v[134:135], v[182:183], 2, s[16:17]
	global_load_dword v130, v[130:131], off
	s_nop 0
	global_load_dword v131, v[132:133], off
	s_nop 0
	global_load_dword v132, v[134:135], off
	s_nop 0
	global_load_dword v128, v[128:129], off offset:704
	v_add_u32_e32 v180, 0x80, v192
	v_add_u32_e32 v176, 0x90, v192
	v_add_u32_e32 v172, 0xa0, v192
	v_add_u32_e32 v168, 0xb0, v192
	v_ashrrev_i32_e32 v181, 31, v180
	v_ashrrev_i32_e32 v177, 31, v176
	v_ashrrev_i32_e32 v173, 31, v172
	v_ashrrev_i32_e32 v169, 31, v168
	s_cmp_gt_i32 s63, 3
	s_mov_b64 s[26:27], -1
	s_waitcnt vmcnt(0)
	v_fmamk_f32 v129, v136, 0x3a000000, v198
	v_fmamk_f32 v133, v137, 0x3a000000, v198
	v_fmamk_f32 v134, v138, 0x3a000000, v198
	v_fmamk_f32 v135, v139, 0x3a000000, v198
	v_rsq_f32_e32 v196, v129
	v_fmamk_f32 v129, v130, 0x3a000000, v198
	v_fmamk_f32 v130, v131, 0x3a000000, v198
	v_fmamk_f32 v131, v132, 0x3a000000, v198
	v_fmamk_f32 v128, v128, 0x3a000000, v198
	v_rsq_f32_e32 v178, v133
	v_rsq_f32_e32 v174, v134
	v_rsq_f32_e32 v170, v135
	v_rsq_f32_e32 v194, v129
	v_rsq_f32_e32 v188, v130
	v_rsq_f32_e32 v184, v131
	v_rsq_f32_e32 v166, v128
	s_cbranch_scc0 .LBB0_878
	s_andn2_b64 vcc, exec, s[14:15]
	s_cbranch_vccnz .LBB0_877
; DI u32x2 pk4(f32x4 v) { u32x2 r; r.x = pk2(v[0], v[1]); r.y = pk2(v[2], v[3]); return r; }
;     DI void operator()(const Acc& acc, const Unit& u, int wr, int wc, int fr, int fq) const {
;     ...
;                 for (int ai = 0; ai < 2; ++ai) if (ai == 0 || !hf) {
;                     f32x4 c4[4], s4[4];
; #pragma unroll
;                     for (int m = 0; m < 4; ++m) { const int pos = (row0 + ai * HALF + m * 16) & (SEQ - 1); c4[m] = *(const f32x4*)(cs + pos * 32 + j0); s4[m] = *(const f32x4*)(cs + 4096 * 32 + pos * 32 + j0); }
; #pragma unroll
;                     for (int m = 0; m < 4; ++m) { const int r = row0 + ai * HALF + m * 16; const float rs = rsv[ai][m];
;                         const f32x4 x1 = acc[ai][0][m][0] * rs, x2 = acc[ai][0][m][1] * rs;
;                         bf16_t* dst = WSB(OFF_KR) + (size_t)r * 64 + j0;
;                         *(u32x2*)(dst) = pk4(x1 * c4[m] - x2 * s4[m]); *(u32x2*)(dst + 32) = pk4(x2 * c4[m] + x1 * s4[m]); }
	v_lshlrev_b32_e32 v128, 7, v192
	v_and_b32_e32 v152, 0x7e780, v128
	v_lshl_add_u64 v[128:129], v[154:155], 0, v[152:153]
	global_load_dwordx4 v[136:139], v[128:129], off
	v_lshl_add_u64 v[130:131], v[156:157], 0, v[152:153]
	global_load_dwordx4 v[140:143], v[130:131], off
	global_load_dwordx4 v[200:203], v[128:129], off offset:2048
	global_load_dwordx4 v[204:207], v[130:131], off offset:2048
	v_or_b32_e32 v128, 0x1000, v152
	v_mov_b32_e32 v129, v153
	v_lshl_add_u64 v[130:131], v[154:155], 0, v[128:129]
	v_lshl_add_u64 v[128:129], v[156:157], 0, v[128:129]
	global_load_dwordx4 v[208:211], v[130:131], off
	global_load_dwordx4 v[212:215], v[128:129], off
	v_or_b32_e32 v152, 0x1800, v152
	v_lshl_add_u64 v[128:129], v[154:155], 0, v[152:153]
	v_lshl_add_u64 v[132:133], v[156:157], 0, v[152:153]
	global_load_dwordx4 v[128:131], v[128:129], off
	v_mul_f32_e32 v216, v126, v196
	v_mul_f32_e32 v217, v127, v196
	global_load_dwordx4 v[132:135], v[132:133], off
	v_mul_f32_e32 v218, v124, v196
	v_mul_f32_e32 v219, v125, v196
	v_mul_f32_e32 v220, v122, v196
	v_mul_f32_e32 v221, v123, v196
	v_mul_f32_e32 v222, v120, v196
	v_mul_f32_e32 v223, v121, v196
	v_lshlrev_b64 v[224:225], 7, v[192:193]
	v_lshl_add_u64 v[224:225], v[158:159], 0, v[224:225]
	s_waitcnt vmcnt(0)
	v_mul_f32_e32 v226, v220, v142
	v_mul_f32_e32 v227, v221, v143
	v_mul_f32_e32 v228, v222, v140
	v_mul_f32_e32 v229, v223, v141
	v_mul_f32_e32 v142, v216, v142
	v_mul_f32_e32 v143, v217, v143
	v_mul_f32_e32 v140, v218, v140
	v_mul_f32_e32 v141, v219, v141
	v_fma_f32 v226, v216, v138, -v226
	v_fma_f32 v227, v217, v139, -v227
	v_fma_f32 v228, v218, v136, -v228
	v_fma_f32 v229, v219, v137, -v229
	v_fma_f32 v138, v220, v138, v142
	v_fma_f32 v139, v221, v139, v143
	v_fma_f32 v136, v222, v136, v140
	v_fma_f32 v137, v223, v137, v141
	v_mul_f32_e32 v140, v106, v194
	v_mul_f32_e32 v141, v107, v194
	v_cvt_pk_bf16_f32 v136, v136, v137
	v_cvt_pk_bf16_f32 v137, v138, v139
	v_mul_f32_e32 v142, v104, v194
	v_mul_f32_e32 v143, v105, v194
	global_store_dwordx2 v[224:225], v[136:137], off offset:64
	v_mul_f32_e32 v136, v110, v194
	v_mul_f32_e32 v137, v111, v194
	v_mul_f32_e32 v138, v108, v194
	v_mul_f32_e32 v139, v109, v194
	v_mul_f32_e32 v218, v140, v206
	v_mul_f32_e32 v219, v141, v207
	v_mul_f32_e32 v220, v142, v204
	v_mul_f32_e32 v221, v143, v205
	v_fma_f32 v218, v136, v202, -v218
	v_fma_f32 v219, v137, v203, -v219
	v_fma_f32 v220, v138, v200, -v220
	v_fma_f32 v221, v139, v201, -v221
	v_mul_f32_e32 v136, v136, v206
	v_mul_f32_e32 v137, v137, v207
	v_mul_f32_e32 v138, v138, v204
	v_mul_f32_e32 v139, v139, v205
	v_lshlrev_b64 v[216:217], 7, v[190:191]
	v_fma_f32 v136, v140, v202, v136
	v_fma_f32 v137, v141, v203, v137
	v_fma_f32 v138, v142, v200, v138
	v_fma_f32 v139, v143, v201, v139
	v_lshl_add_u64 v[216:217], v[158:159], 0, v[216:217]
	v_cvt_pk_bf16_f32 v138, v138, v139
	v_cvt_pk_bf16_f32 v139, v136, v137
	v_mul_f32_e32 v140, v90, v188
	v_mul_f32_e32 v141, v91, v188
	v_mul_f32_e32 v142, v88, v188
	v_mul_f32_e32 v143, v89, v188
	global_store_dwordx2 v[216:217], v[138:139], off offset:64
	v_mul_f32_e32 v136, v94, v188
	v_mul_f32_e32 v137, v95, v188
	v_mul_f32_e32 v138, v92, v188
	v_mul_f32_e32 v139, v93, v188
	v_mul_f32_e32 v202, v140, v214
	v_mul_f32_e32 v203, v141, v215
	v_mul_f32_e32 v204, v142, v212
	v_mul_f32_e32 v205, v143, v213
	v_fma_f32 v202, v136, v210, -v202
	v_fma_f32 v203, v137, v211, -v203
	v_fma_f32 v204, v138, v208, -v204
	v_fma_f32 v205, v139, v209, -v205
	v_mul_f32_e32 v136, v136, v214
	v_mul_f32_e32 v137, v137, v215
	v_mul_f32_e32 v138, v138, v212
	v_mul_f32_e32 v139, v139, v213
	v_lshlrev_b64 v[200:201], 7, v[186:187]
	v_fma_f32 v136, v140, v210, v136
	v_fma_f32 v137, v141, v211, v137
	v_fma_f32 v138, v142, v208, v138
	v_fma_f32 v139, v143, v209, v139
	v_lshl_add_u64 v[200:201], v[158:159], 0, v[200:201]
	v_cvt_pk_bf16_f32 v138, v138, v139
	v_cvt_pk_bf16_f32 v139, v136, v137
	v_cvt_pk_bf16_f32 v204, v204, v205
	v_cvt_pk_bf16_f32 v205, v202, v203
	global_store_dwordx2 v[200:201], v[138:139], off offset:64
	v_mul_f32_e32 v136, v78, v184
	v_mul_f32_e32 v137, v79, v184
	v_mul_f32_e32 v138, v76, v184
	v_mul_f32_e32 v139, v77, v184
	v_mul_f32_e32 v140, v74, v184
	v_mul_f32_e32 v141, v75, v184
	v_mul_f32_e32 v142, v72, v184
	v_mul_f32_e32 v143, v73, v184
	global_store_dwordx2 v[200:201], v[204:205], off
	v_mul_f32_e32 v202, v140, v134
	v_mul_f32_e32 v203, v141, v135
	v_mul_f32_e32 v204, v142, v132
	v_mul_f32_e32 v205, v143, v133
	v_mul_f32_e32 v134, v136, v134
	v_mul_f32_e32 v135, v137, v135
	v_mul_f32_e32 v132, v138, v132
	v_mul_f32_e32 v133, v139, v133
	v_lshlrev_b64 v[200:201], 7, v[182:183]
	v_fma_f32 v202, v136, v130, -v202
	v_fma_f32 v203, v137, v131, -v203
	v_fma_f32 v204, v138, v128, -v204
	v_fma_f32 v205, v139, v129, -v205
	v_fma_f32 v130, v140, v130, v134
	v_fma_f32 v131, v141, v131, v135
	v_fma_f32 v128, v142, v128, v132
	v_fma_f32 v129, v143, v129, v133
	v_lshl_add_u64 v[200:201], v[158:159], 0, v[200:201]
	v_cvt_pk_bf16_f32 v128, v128, v129
	v_cvt_pk_bf16_f32 v129, v130, v131
	global_store_dwordx2 v[200:201], v[128:129], off offset:64
	v_lshl_add_u32 v128, v192, 5, v199
	v_and_b32_e32 v128, 0x1f9e0, v128
	v_cvt_pk_bf16_f32 v228, v228, v229
	v_cvt_pk_bf16_f32 v229, v226, v227
	v_cvt_pk_bf16_f32 v220, v220, v221
	v_cvt_pk_bf16_f32 v221, v218, v219
	v_cvt_pk_bf16_f32 v204, v204, v205
	v_cvt_pk_bf16_f32 v205, v202, v203
	v_lshlrev_b32_e32 v152, 2, v128
	global_store_dwordx2 v[224:225], v[228:229], off
	global_store_dwordx2 v[216:217], v[220:221], off
	global_store_dwordx2 v[200:201], v[204:205], off
	v_lshl_add_u64 v[128:129], v[154:155], 0, v[152:153]
	global_load_dwordx4 v[200:203], v[128:129], off
	v_lshl_add_u64 v[130:131], v[156:157], 0, v[152:153]
	global_load_dwordx4 v[204:207], v[130:131], off
	global_load_dwordx4 v[208:211], v[128:129], off offset:2048
	global_load_dwordx4 v[212:215], v[130:131], off offset:2048
	v_or_b32_e32 v128, 0x1000, v152
	v_mov_b32_e32 v129, v153
	v_lshl_add_u64 v[130:131], v[154:155], 0, v[128:129]
	v_lshl_add_u64 v[128:129], v[156:157], 0, v[128:129]
	global_load_dwordx4 v[132:135], v[130:131], off
	global_load_dwordx4 v[140:143], v[128:129], off
	v_or_b32_e32 v152, 0x1800, v152
	v_lshl_add_u64 v[128:129], v[154:155], 0, v[152:153]
	v_lshl_add_u64 v[136:137], v[156:157], 0, v[152:153]
	global_load_dwordx4 v[128:131], v[128:129], off
	v_mul_f32_e32 v216, v62, v178
	v_mul_f32_e32 v217, v63, v178
	global_load_dwordx4 v[136:139], v[136:137], off
	v_mul_f32_e32 v218, v60, v178
	v_mul_f32_e32 v219, v61, v178
	v_mul_f32_e32 v220, v58, v178
	v_mul_f32_e32 v221, v59, v178
	v_mul_f32_e32 v222, v56, v178
	v_mul_f32_e32 v223, v57, v178
	v_lshlrev_b64 v[224:225], 7, v[180:181]
	v_lshl_add_u64 v[224:225], v[158:159], 0, v[224:225]
	s_waitcnt vmcnt(0)
; DI u32x2 pk4(f32x4 v) { u32x2 r; r.x = pk2(v[0], v[1]); r.y = pk2(v[2], v[3]); return r; }
;     DI void operator()(const Acc& acc, const Unit& u, int wr, int wc, int fr, int fq) const {
;     ...
;                 for (int ai = 0; ai < 2; ++ai) if (ai == 0 || !hf) {
;                     f32x4 c4[4], s4[4];
; #pragma unroll
;                     for (int m = 0; m < 4; ++m) { const int pos = (row0 + ai * HALF + m * 16) & (SEQ - 1); c4[m] = *(const f32x4*)(cs + pos * 32 + j0); s4[m] = *(const f32x4*)(cs + 4096 * 32 + pos * 32 + j0); }
; #pragma unroll
;                     for (int m = 0; m < 4; ++m) { const int r = row0 + ai * HALF + m * 16; const float rs = rsv[ai][m];
;                         const f32x4 x1 = acc[ai][0][m][0] * rs, x2 = acc[ai][0][m][1] * rs;
;                         bf16_t* dst = WSB(OFF_KR) + (size_t)r * 64 + j0;
;                         *(u32x2*)(dst) = pk4(x1 * c4[m] - x2 * s4[m]); *(u32x2*)(dst + 32) = pk4(x2 * c4[m] + x1 * s4[m]); }
	v_mul_f32_e32 v226, v220, v206
	v_mul_f32_e32 v227, v221, v207
	v_mul_f32_e32 v228, v222, v204
	v_mul_f32_e32 v229, v223, v205
	v_mul_f32_e32 v206, v216, v206
	v_mul_f32_e32 v207, v217, v207
	v_mul_f32_e32 v204, v218, v204
	v_mul_f32_e32 v205, v219, v205
	v_fma_f32 v226, v216, v202, -v226
	v_fma_f32 v227, v217, v203, -v227
	v_fma_f32 v228, v218, v200, -v228
	v_fma_f32 v229, v219, v201, -v229
	v_fma_f32 v202, v220, v202, v206
	v_fma_f32 v203, v221, v203, v207
	v_fma_f32 v200, v222, v200, v204
	v_fma_f32 v201, v223, v201, v205
	v_mul_f32_e32 v204, v42, v174
	v_mul_f32_e32 v205, v43, v174
	v_cvt_pk_bf16_f32 v200, v200, v201
	v_cvt_pk_bf16_f32 v201, v202, v203
	v_mul_f32_e32 v206, v40, v174
	v_mul_f32_e32 v207, v41, v174
	global_store_dwordx2 v[224:225], v[200:201], off offset:64
	v_mul_f32_e32 v200, v46, v174
	v_mul_f32_e32 v201, v47, v174
	v_mul_f32_e32 v202, v44, v174
	v_mul_f32_e32 v203, v45, v174
	v_mul_f32_e32 v218, v204, v214
	v_mul_f32_e32 v219, v205, v215
	v_mul_f32_e32 v220, v206, v212
	v_mul_f32_e32 v221, v207, v213
	v_fma_f32 v218, v200, v210, -v218
	v_fma_f32 v219, v201, v211, -v219
	v_fma_f32 v220, v202, v208, -v220
	v_fma_f32 v221, v203, v209, -v221
	v_mul_f32_e32 v200, v200, v214
	v_mul_f32_e32 v201, v201, v215
	v_mul_f32_e32 v202, v202, v212
	v_mul_f32_e32 v203, v203, v213
	v_lshlrev_b64 v[216:217], 7, v[176:177]
	v_fma_f32 v200, v204, v210, v200
	v_fma_f32 v201, v205, v211, v201
	v_fma_f32 v202, v206, v208, v202
	v_fma_f32 v203, v207, v209, v203
	v_lshl_add_u64 v[216:217], v[158:159], 0, v[216:217]
	v_cvt_pk_bf16_f32 v202, v202, v203
	v_cvt_pk_bf16_f32 v203, v200, v201
	global_store_dwordx2 v[216:217], v[202:203], off offset:64
	v_mul_f32_e32 v200, v30, v170
	v_mul_f32_e32 v201, v31, v170
	v_mul_f32_e32 v202, v28, v170
	v_mul_f32_e32 v203, v29, v170
	v_mul_f32_e32 v204, v26, v170
	v_mul_f32_e32 v205, v27, v170
	v_mul_f32_e32 v206, v24, v170
	v_mul_f32_e32 v207, v25, v170
	v_mul_f32_e32 v210, v204, v142
	v_mul_f32_e32 v211, v205, v143
	v_mul_f32_e32 v212, v206, v140
	v_mul_f32_e32 v213, v207, v141
	v_mul_f32_e32 v142, v200, v142
	v_mul_f32_e32 v143, v201, v143
	v_mul_f32_e32 v140, v202, v140
	v_mul_f32_e32 v141, v203, v141
	v_lshlrev_b64 v[208:209], 7, v[172:173]
	v_fma_f32 v210, v200, v134, -v210
	v_fma_f32 v211, v201, v135, -v211
	v_fma_f32 v212, v202, v132, -v212
	v_fma_f32 v213, v203, v133, -v213
	v_fma_f32 v134, v204, v134, v142
	v_fma_f32 v135, v205, v135, v143
	v_fma_f32 v132, v206, v132, v140
	v_fma_f32 v133, v207, v133, v141
	v_lshl_add_u64 v[208:209], v[158:159], 0, v[208:209]
	v_cvt_pk_bf16_f32 v132, v132, v133
	v_cvt_pk_bf16_f32 v133, v134, v135
	v_mul_f32_e32 v140, v10, v166
	v_mul_f32_e32 v141, v11, v166
	v_mul_f32_e32 v142, v8, v166
	v_mul_f32_e32 v143, v9, v166
	global_store_dwordx2 v[208:209], v[132:133], off offset:64
	v_mul_f32_e32 v132, v14, v166
	v_mul_f32_e32 v133, v15, v166
	v_mul_f32_e32 v134, v12, v166
	v_mul_f32_e32 v135, v13, v166
	v_mul_f32_e32 v202, v140, v138
	v_mul_f32_e32 v203, v141, v139
	v_mul_f32_e32 v204, v142, v136
	v_mul_f32_e32 v205, v143, v137
	v_fma_f32 v202, v132, v130, -v202
	v_fma_f32 v203, v133, v131, -v203
	v_fma_f32 v204, v134, v128, -v204
	v_fma_f32 v205, v135, v129, -v205
	v_mul_f32_e32 v132, v132, v138
	v_mul_f32_e32 v133, v133, v139
	v_mul_f32_e32 v134, v134, v136
	v_mul_f32_e32 v135, v135, v137
	v_lshlrev_b64 v[200:201], 7, v[168:169]
	v_fma_f32 v130, v140, v130, v132
	v_fma_f32 v131, v141, v131, v133
	v_fma_f32 v128, v142, v128, v134
	v_fma_f32 v129, v143, v129, v135
	v_cvt_pk_bf16_f32 v228, v228, v229
	v_cvt_pk_bf16_f32 v229, v226, v227
	v_cvt_pk_bf16_f32 v220, v220, v221
	v_cvt_pk_bf16_f32 v221, v218, v219
	v_cvt_pk_bf16_f32 v212, v212, v213
	v_cvt_pk_bf16_f32 v213, v210, v211
	v_lshl_add_u64 v[200:201], v[158:159], 0, v[200:201]
	v_cvt_pk_bf16_f32 v204, v204, v205
	v_cvt_pk_bf16_f32 v205, v202, v203
	v_cvt_pk_bf16_f32 v128, v128, v129
	v_cvt_pk_bf16_f32 v129, v130, v131
	global_store_dwordx2 v[224:225], v[228:229], off
	global_store_dwordx2 v[216:217], v[220:221], off
	global_store_dwordx2 v[208:209], v[212:213], off
	global_store_dwordx2 v[200:201], v[204:205], off
	global_store_dwordx2 v[200:201], v[128:129], off offset:64

; #define ROWS8 _Pragma("unroll") for (int ai = 0; ai < 2; ++ai) _Pragma("unroll") for (int m = 0; m < 4; ++m) if (ai == 0 || !hf)
; #define PK8(v0, v1) ({ const u32x2 h0_ = pk4(v0), h1_ = pk4(v1); (u32x4){h0_.x, h0_.y, h1_.x, h1_.y}; })
;     DI void operator()(const Acc& acc, const Unit& u, int wr, int wc, int fr, int fq) const {
;     ...
;             if (u.pn < 4) {
;                 bf16_t* dbase = (u.pn < 2) ? WSB(OFF_CQ) : WSB(OFF_CKV); float* sdst = (u.pn < 2) ? SSQ(4 + sqo) : SSQ(5 + sqo);
;                 const int cb = (u.pn & 1) * 256 + wc * 32 + 8 * fq;
;                 ROWS8 { const int r = row0 + ai * HALF + m * 16; const float rs = rsv[ai][m]; float part = 0.f;
;                     bf16_t* dst = dbase + (size_t)r * 512 + cb;
; #pragma unroll
;                     for (int bj = 0; bj < 2; ++bj) { const f32x4 v0 = acc[ai][bj][m][0] * rs, v1 = acc[ai][bj][m][1] * rs; *(u32x4*)(dst + bj * HALF) = PK8(v0, v1);
;                         part += v0[0] * v0[0] + v0[1] * v0[1] + v0[2] * v0[2] + v0[3] * v0[3] + v1[0] * v1[0] + v1[1] * v1[1] + v1[2] * v1[2] + v1[3] * v1[3]; }
;                     part += __shfl_xor(part, 16); part += __shfl_xor(part, 32);
;                     if (fq == 0) unsafeAtomicAdd(sdst + r, part);
;                 }
.LBB0_878:
	s_andn2_b64 vcc, exec, s[26:27]
	s_cbranch_vccnz .LBB0_869
	v_mul_f32_e32 v124, v124, v196
	v_mul_f32_e32 v125, v125, v196
	v_mul_f32_e32 v132, v122, v196
	v_mul_f32_e32 v133, v123, v196
	v_mul_f32_e32 v123, v125, v125
	v_mul_f32_e32 v116, v116, v196
	v_mul_f32_e32 v117, v117, v196
	v_mul_f32_e32 v134, v120, v196
	v_mul_f32_e32 v135, v121, v196
	v_cvt_pk_bf16_f32 v120, v124, v125
	v_fmac_f32_e32 v123, v124, v124
	v_mul_f32_e32 v124, v114, v196
	v_mul_f32_e32 v125, v115, v196
	v_mul_f32_e32 v114, v117, v117
	v_mul_f32_e32 v126, v126, v196
	v_mul_f32_e32 v127, v127, v196
	v_mul_f32_e32 v118, v118, v196
	v_mul_f32_e32 v119, v119, v196
	v_fmac_f32_e32 v114, v116, v116
	v_fmac_f32_e32 v123, v126, v126
	v_fmac_f32_e32 v114, v118, v118
	v_fmac_f32_e32 v123, v127, v127
	v_mul_f32_e32 v112, v112, v196
	v_mul_f32_e32 v113, v113, v196
	v_fmac_f32_e32 v114, v119, v119
	v_fmac_f32_e32 v123, v134, v134
	v_fmac_f32_e32 v114, v112, v112
	v_fmac_f32_e32 v123, v135, v135
	v_fmac_f32_e32 v114, v113, v113
	v_fmac_f32_e32 v123, v132, v132
	v_fmac_f32_e32 v114, v124, v124
	v_fmac_f32_e32 v123, v133, v133
	v_fmac_f32_e32 v114, v125, v125
	v_add_f32_e32 v114, v123, v114
	s_cmp_lt_i32 s63, 2
	ds_bpermute_b32 v115, v179, v114
	s_cselect_b32 s21, s62, 0x28000
	s_cselect_b32 s19, s61, 0xd800000
	s_add_u32 s26, s57, s21
	s_addc_u32 s27, s58, 0
	s_add_u32 s28, s10, s19
	s_addc_u32 s29, s11, 0
	s_lshl_b32 s19, s63, 8
	s_waitcnt lgkmcnt(0)
	v_add_f32_e32 v114, v114, v115
	s_and_b32 s19, s19, 0x100
	ds_bpermute_b32 v115, v185, v114
	v_add_u32_e32 v128, s19, v175
	v_ashrrev_i32_e32 v129, 31, v128
	v_lshl_add_u64 v[128:129], v[128:129], 1, s[28:29]
	v_lshlrev_b64 v[130:131], 10, v[192:193]
	v_lshl_add_u64 v[130:131], v[128:129], 0, v[130:131]
	v_cvt_pk_bf16_f32 v121, v126, v127
	v_cvt_pk_bf16_f32 v122, v134, v135
	v_cvt_pk_bf16_f32 v123, v132, v133
	v_cvt_pk_bf16_f32 v116, v116, v117
	v_cvt_pk_bf16_f32 v117, v118, v119
	v_cvt_pk_bf16_f32 v118, v112, v113
	v_cvt_pk_bf16_f32 v119, v124, v125
	v_lshl_add_u64 v[112:113], v[192:193], 2, s[26:27]
	global_store_dwordx4 v[130:131], v[120:123], off
	global_store_dwordx4 v[130:131], v[116:119], off offset:256
	s_and_saveexec_b64 s[26:27], s[2:3]
	s_cbranch_execz .LBB0_881
	s_waitcnt lgkmcnt(0)
	v_add_f32_e32 v114, v114, v115
	global_atomic_add_f32 v[112:113], v114, off
.LBB0_881:
	s_or_b64 exec, exec, s[26:27]
	v_mul_f32_e32 v108, v108, v194
	v_mul_f32_e32 v109, v109, v194
	v_mul_f32_e32 v110, v110, v194
	v_mul_f32_e32 v111, v111, v194
	v_mul_f32_e32 v118, v109, v109
	v_fmac_f32_e32 v118, v108, v108
	v_fmac_f32_e32 v118, v110, v110
	v_mul_f32_e32 v100, v100, v194
	v_mul_f32_e32 v101, v101, v194
	v_mul_f32_e32 v116, v106, v194
	v_mul_f32_e32 v117, v107, v194
	v_mul_f32_e32 v106, v104, v194
	v_mul_f32_e32 v107, v105, v194
	v_cvt_pk_bf16_f32 v105, v110, v111
	v_fmac_f32_e32 v118, v111, v111
	v_mul_f32_e32 v110, v96, v194
	v_mul_f32_e32 v111, v97, v194
	v_mul_f32_e32 v96, v101, v101
	v_mul_f32_e32 v102, v102, v194
	v_mul_f32_e32 v103, v103, v194
	v_fmac_f32_e32 v96, v100, v100
	v_fmac_f32_e32 v96, v102, v102
	v_fmac_f32_e32 v96, v103, v103
	v_fmac_f32_e32 v118, v106, v106
	v_fmac_f32_e32 v96, v110, v110
	v_cvt_pk_bf16_f32 v104, v108, v109
	v_fmac_f32_e32 v118, v107, v107
	v_mul_f32_e32 v108, v98, v194
	v_mul_f32_e32 v109, v99, v194
	v_fmac_f32_e32 v96, v111, v111
	v_fmac_f32_e32 v118, v116, v116
	v_fmac_f32_e32 v96, v108, v108
	v_fmac_f32_e32 v118, v117, v117
	v_fmac_f32_e32 v96, v109, v109
	v_add_f32_e32 v96, v118, v96
	ds_bpermute_b32 v97, v179, v96
	s_waitcnt lgkmcnt(1)
	v_lshlrev_b64 v[114:115], 10, v[190:191]
	v_lshl_add_u64 v[114:115], v[128:129], 0, v[114:115]
	v_cvt_pk_bf16_f32 v106, v106, v107
	v_cvt_pk_bf16_f32 v107, v116, v117
	s_waitcnt lgkmcnt(0)
	v_add_f32_e32 v96, v96, v97
	ds_bpermute_b32 v97, v185, v96
	v_cvt_pk_bf16_f32 v98, v100, v101
	v_cvt_pk_bf16_f32 v99, v102, v103
	v_cvt_pk_bf16_f32 v100, v110, v111
	v_cvt_pk_bf16_f32 v101, v108, v109
	global_store_dwordx4 v[114:115], v[104:107], off
	global_store_dwordx4 v[114:115], v[98:101], off offset:256
	s_and_saveexec_b64 s[26:27], s[2:3]
	s_cbranch_execz .LBB0_883
	s_waitcnt lgkmcnt(0)
	v_add_f32_e32 v96, v96, v97
	global_atomic_add_f32 v[112:113], v96, off offset:64
.LBB0_883:
	s_or_b64 exec, exec, s[26:27]
	v_mul_f32_e32 v92, v92, v188
	v_mul_f32_e32 v93, v93, v188
	v_mul_f32_e32 v94, v94, v188
	v_mul_f32_e32 v95, v95, v188
	v_mul_f32_e32 v100, v93, v93
	v_fmac_f32_e32 v100, v92, v92
	v_fmac_f32_e32 v100, v94, v94
	v_mul_f32_e32 v84, v84, v188
	v_mul_f32_e32 v85, v85, v188
	v_mul_f32_e32 v98, v90, v188
	v_mul_f32_e32 v99, v91, v188
	v_mul_f32_e32 v90, v88, v188
	v_mul_f32_e32 v91, v89, v188
	v_cvt_pk_bf16_f32 v89, v94, v95
	v_fmac_f32_e32 v100, v95, v95
	v_mul_f32_e32 v94, v80, v188
	v_mul_f32_e32 v95, v81, v188
	v_mul_f32_e32 v80, v85, v85
	v_mul_f32_e32 v86, v86, v188
	v_mul_f32_e32 v87, v87, v188
	v_fmac_f32_e32 v80, v84, v84
	v_fmac_f32_e32 v80, v86, v86
	v_fmac_f32_e32 v80, v87, v87
	v_fmac_f32_e32 v100, v90, v90
	v_fmac_f32_e32 v80, v94, v94
	v_cvt_pk_bf16_f32 v88, v92, v93
	v_fmac_f32_e32 v100, v91, v91
	v_mul_f32_e32 v92, v82, v188
	v_mul_f32_e32 v93, v83, v188
	v_fmac_f32_e32 v80, v95, v95
	v_fmac_f32_e32 v100, v98, v98
	v_fmac_f32_e32 v80, v92, v92
	v_fmac_f32_e32 v100, v99, v99
	v_fmac_f32_e32 v80, v93, v93
	v_add_f32_e32 v80, v100, v80
	ds_bpermute_b32 v81, v179, v80
	s_waitcnt lgkmcnt(1)
	v_lshlrev_b64 v[96:97], 10, v[186:187]
	v_lshl_add_u64 v[96:97], v[128:129], 0, v[96:97]
	v_cvt_pk_bf16_f32 v90, v90, v91
	v_cvt_pk_bf16_f32 v91, v98, v99
	s_waitcnt lgkmcnt(0)
	v_add_f32_e32 v80, v80, v81
	ds_bpermute_b32 v81, v185, v80
	v_cvt_pk_bf16_f32 v82, v84, v85
	v_cvt_pk_bf16_f32 v83, v86, v87
	v_cvt_pk_bf16_f32 v84, v94, v95
	v_cvt_pk_bf16_f32 v85, v92, v93
	global_store_dwordx4 v[96:97], v[88:91], off
	global_store_dwordx4 v[96:97], v[82:85], off offset:256
	s_and_saveexec_b64 s[26:27], s[2:3]
	s_cbranch_execz .LBB0_885
	s_waitcnt lgkmcnt(0)
	v_add_f32_e32 v80, v80, v81
	global_atomic_add_f32 v[112:113], v80, off offset:128
; #define ROWS8 _Pragma("unroll") for (int ai = 0; ai < 2; ++ai) _Pragma("unroll") for (int m = 0; m < 4; ++m) if (ai == 0 || !hf)
; #define PK8(v0, v1) ({ const u32x2 h0_ = pk4(v0), h1_ = pk4(v1); (u32x4){h0_.x, h0_.y, h1_.x, h1_.y}; })
;     DI void operator()(const Acc& acc, const Unit& u, int wr, int wc, int fr, int fq) const {
;     ...
;                 ROWS8 { const int r = row0 + ai * HALF + m * 16; const float rs = rsv[ai][m]; float part = 0.f;
;                     bf16_t* dst = dbase + (size_t)r * 512 + cb;
; #pragma unroll
;                     for (int bj = 0; bj < 2; ++bj) { const f32x4 v0 = acc[ai][bj][m][0] * rs, v1 = acc[ai][bj][m][1] * rs; *(u32x4*)(dst + bj * HALF) = PK8(v0, v1);
;                         part += v0[0] * v0[0] + v0[1] * v0[1] + v0[2] * v0[2] + v0[3] * v0[3] + v1[0] * v1[0] + v1[1] * v1[1] + v1[2] * v1[2] + v1[3] * v1[3]; }
;                     part += __shfl_xor(part, 16); part += __shfl_xor(part, 32);
;                     if (fq == 0) unsafeAtomicAdd(sdst + r, part);
;                 }
.LBB0_885:
	s_or_b64 exec, exec, s[26:27]
	v_mul_f32_e32 v76, v76, v184
	v_mul_f32_e32 v77, v77, v184
	v_mul_f32_e32 v78, v78, v184
	v_mul_f32_e32 v79, v79, v184
	v_mul_f32_e32 v84, v77, v77
	v_fmac_f32_e32 v84, v76, v76
	v_fmac_f32_e32 v84, v78, v78
	v_mul_f32_e32 v68, v68, v184
	v_mul_f32_e32 v69, v69, v184
	v_mul_f32_e32 v82, v74, v184
	v_mul_f32_e32 v83, v75, v184
	v_mul_f32_e32 v74, v72, v184
	v_mul_f32_e32 v75, v73, v184
	v_cvt_pk_bf16_f32 v73, v78, v79
	v_fmac_f32_e32 v84, v79, v79
	v_mul_f32_e32 v78, v64, v184
	v_mul_f32_e32 v79, v65, v184
	v_mul_f32_e32 v64, v69, v69
	v_mul_f32_e32 v70, v70, v184
	v_mul_f32_e32 v71, v71, v184
	v_fmac_f32_e32 v64, v68, v68
	v_fmac_f32_e32 v64, v70, v70
	v_fmac_f32_e32 v64, v71, v71
	v_fmac_f32_e32 v84, v74, v74
	v_fmac_f32_e32 v64, v78, v78
	v_cvt_pk_bf16_f32 v72, v76, v77
	v_fmac_f32_e32 v84, v75, v75
	v_mul_f32_e32 v76, v66, v184
	v_mul_f32_e32 v77, v67, v184
	v_fmac_f32_e32 v64, v79, v79
	v_fmac_f32_e32 v84, v82, v82
	v_fmac_f32_e32 v64, v76, v76
	v_fmac_f32_e32 v84, v83, v83
	v_fmac_f32_e32 v64, v77, v77
	v_add_f32_e32 v64, v84, v64
	ds_bpermute_b32 v65, v179, v64
	s_waitcnt lgkmcnt(1)
	v_lshlrev_b64 v[80:81], 10, v[182:183]
	v_lshl_add_u64 v[80:81], v[128:129], 0, v[80:81]
	v_cvt_pk_bf16_f32 v74, v74, v75
	v_cvt_pk_bf16_f32 v75, v82, v83
	s_waitcnt lgkmcnt(0)
	v_add_f32_e32 v64, v64, v65
	ds_bpermute_b32 v65, v185, v64
	v_cvt_pk_bf16_f32 v66, v68, v69
	v_cvt_pk_bf16_f32 v67, v70, v71
	v_cvt_pk_bf16_f32 v68, v78, v79
	v_cvt_pk_bf16_f32 v69, v76, v77
	global_store_dwordx4 v[80:81], v[72:75], off
	global_store_dwordx4 v[80:81], v[66:69], off offset:256
	s_and_saveexec_b64 s[26:27], s[2:3]
	s_cbranch_execz .LBB0_887
	s_waitcnt lgkmcnt(0)
	v_add_f32_e32 v64, v64, v65
	global_atomic_add_f32 v[112:113], v64, off offset:192
.LBB0_887:
	s_or_b64 exec, exec, s[26:27]
	v_mul_f32_e32 v60, v60, v178
	v_mul_f32_e32 v61, v61, v178
	v_mul_f32_e32 v62, v62, v178
	v_mul_f32_e32 v63, v63, v178
	v_mul_f32_e32 v68, v61, v61
	v_fmac_f32_e32 v68, v60, v60
	v_fmac_f32_e32 v68, v62, v62
	v_mul_f32_e32 v52, v52, v178
	v_mul_f32_e32 v53, v53, v178
	v_mul_f32_e32 v66, v58, v178
	v_mul_f32_e32 v67, v59, v178
	v_mul_f32_e32 v58, v56, v178
	v_mul_f32_e32 v59, v57, v178
	v_cvt_pk_bf16_f32 v57, v62, v63
	v_fmac_f32_e32 v68, v63, v63
	v_mul_f32_e32 v62, v48, v178
	v_mul_f32_e32 v63, v49, v178
	v_mul_f32_e32 v48, v53, v53
	v_mul_f32_e32 v54, v54, v178
	v_mul_f32_e32 v55, v55, v178
	v_fmac_f32_e32 v48, v52, v52
	v_fmac_f32_e32 v48, v54, v54
	v_fmac_f32_e32 v48, v55, v55
	v_fmac_f32_e32 v68, v58, v58
	v_fmac_f32_e32 v48, v62, v62
	v_cvt_pk_bf16_f32 v56, v60, v61
	v_fmac_f32_e32 v68, v59, v59
	v_mul_f32_e32 v60, v50, v178
	v_mul_f32_e32 v61, v51, v178
	v_fmac_f32_e32 v48, v63, v63
	v_fmac_f32_e32 v68, v66, v66
	v_fmac_f32_e32 v48, v60, v60
	v_fmac_f32_e32 v68, v67, v67
	v_fmac_f32_e32 v48, v61, v61
	v_add_f32_e32 v48, v68, v48
	ds_bpermute_b32 v49, v179, v48
	s_waitcnt lgkmcnt(1)
	v_lshlrev_b64 v[64:65], 10, v[180:181]
	v_lshl_add_u64 v[64:65], v[128:129], 0, v[64:65]
	v_cvt_pk_bf16_f32 v58, v58, v59
	v_cvt_pk_bf16_f32 v59, v66, v67
	s_waitcnt lgkmcnt(0)
	v_add_f32_e32 v48, v48, v49
	ds_bpermute_b32 v49, v185, v48
	v_cvt_pk_bf16_f32 v50, v52, v53
	v_cvt_pk_bf16_f32 v51, v54, v55
	v_cvt_pk_bf16_f32 v52, v62, v63
	v_cvt_pk_bf16_f32 v53, v60, v61
	global_store_dwordx4 v[64:65], v[56:59], off
	global_store_dwordx4 v[64:65], v[50:53], off offset:256
	s_and_saveexec_b64 s[26:27], s[2:3]
	s_cbranch_execz .LBB0_889
	s_waitcnt lgkmcnt(0)
	v_add_f32_e32 v48, v48, v49
	global_atomic_add_f32 v[112:113], v48, off offset:512
; #define ROWS8 _Pragma("unroll") for (int ai = 0; ai < 2; ++ai) _Pragma("unroll") for (int m = 0; m < 4; ++m) if (ai == 0 || !hf)
; #define PK8(v0, v1) ({ const u32x2 h0_ = pk4(v0), h1_ = pk4(v1); (u32x4){h0_.x, h0_.y, h1_.x, h1_.y}; })
;     DI void operator()(const Acc& acc, const Unit& u, int wr, int wc, int fr, int fq) const {
;     ...
;                 ROWS8 { const int r = row0 + ai * HALF + m * 16; const float rs = rsv[ai][m]; float part = 0.f;
;                     bf16_t* dst = dbase + (size_t)r * 512 + cb;
; #pragma unroll
;                     for (int bj = 0; bj < 2; ++bj) { const f32x4 v0 = acc[ai][bj][m][0] * rs, v1 = acc[ai][bj][m][1] * rs; *(u32x4*)(dst + bj * HALF) = PK8(v0, v1);
;                         part += v0[0] * v0[0] + v0[1] * v0[1] + v0[2] * v0[2] + v0[3] * v0[3] + v1[0] * v1[0] + v1[1] * v1[1] + v1[2] * v1[2] + v1[3] * v1[3]; }
;                     part += __shfl_xor(part, 16); part += __shfl_xor(part, 32);
;                     if (fq == 0) unsafeAtomicAdd(sdst + r, part);
;                 }
.LBB0_889:
	s_or_b64 exec, exec, s[26:27]
	v_mul_f32_e32 v44, v44, v174
	v_mul_f32_e32 v45, v45, v174
	v_mul_f32_e32 v46, v46, v174
	v_mul_f32_e32 v47, v47, v174
	v_mul_f32_e32 v52, v45, v45
	v_fmac_f32_e32 v52, v44, v44
	v_fmac_f32_e32 v52, v46, v46
	v_mul_f32_e32 v36, v36, v174
	v_mul_f32_e32 v37, v37, v174
	v_mul_f32_e32 v50, v42, v174
	v_mul_f32_e32 v51, v43, v174
	v_mul_f32_e32 v42, v40, v174
	v_mul_f32_e32 v43, v41, v174
	v_cvt_pk_bf16_f32 v41, v46, v47
	v_fmac_f32_e32 v52, v47, v47
	v_mul_f32_e32 v46, v32, v174
	v_mul_f32_e32 v47, v33, v174
	v_mul_f32_e32 v32, v37, v37
	v_mul_f32_e32 v38, v38, v174
	v_mul_f32_e32 v39, v39, v174
	v_fmac_f32_e32 v32, v36, v36
	v_fmac_f32_e32 v32, v38, v38
	v_fmac_f32_e32 v32, v39, v39
	v_fmac_f32_e32 v52, v42, v42
	v_fmac_f32_e32 v32, v46, v46
	v_cvt_pk_bf16_f32 v40, v44, v45
	v_fmac_f32_e32 v52, v43, v43
	v_mul_f32_e32 v44, v34, v174
	v_mul_f32_e32 v45, v35, v174
	v_fmac_f32_e32 v32, v47, v47
	v_fmac_f32_e32 v52, v50, v50
	v_fmac_f32_e32 v32, v44, v44
	v_fmac_f32_e32 v52, v51, v51
	v_fmac_f32_e32 v32, v45, v45
	v_add_f32_e32 v32, v52, v32
	ds_bpermute_b32 v33, v179, v32
	s_waitcnt lgkmcnt(1)
	v_lshlrev_b64 v[48:49], 10, v[176:177]
	v_lshl_add_u64 v[48:49], v[128:129], 0, v[48:49]
	v_cvt_pk_bf16_f32 v42, v42, v43
	v_cvt_pk_bf16_f32 v43, v50, v51
	s_waitcnt lgkmcnt(0)
	v_add_f32_e32 v32, v32, v33
	ds_bpermute_b32 v33, v185, v32
	v_cvt_pk_bf16_f32 v34, v36, v37
	v_cvt_pk_bf16_f32 v35, v38, v39
	v_cvt_pk_bf16_f32 v36, v46, v47
	v_cvt_pk_bf16_f32 v37, v44, v45
	global_store_dwordx4 v[48:49], v[40:43], off
	global_store_dwordx4 v[48:49], v[34:37], off offset:256
	s_and_saveexec_b64 s[26:27], s[2:3]
	s_cbranch_execz .LBB0_891
	s_waitcnt lgkmcnt(0)
	v_add_f32_e32 v32, v32, v33
	global_atomic_add_f32 v[112:113], v32, off offset:576
.LBB0_891:
	s_or_b64 exec, exec, s[26:27]
	v_mul_f32_e32 v28, v28, v170
	v_mul_f32_e32 v29, v29, v170
	v_mul_f32_e32 v30, v30, v170
	v_mul_f32_e32 v31, v31, v170
	v_mul_f32_e32 v36, v29, v29
	v_fmac_f32_e32 v36, v28, v28
	v_fmac_f32_e32 v36, v30, v30
	v_mul_f32_e32 v20, v20, v170
	v_mul_f32_e32 v21, v21, v170
	v_mul_f32_e32 v34, v26, v170
	v_mul_f32_e32 v35, v27, v170
	v_mul_f32_e32 v26, v24, v170
	v_mul_f32_e32 v27, v25, v170
	v_cvt_pk_bf16_f32 v25, v30, v31
	v_fmac_f32_e32 v36, v31, v31
	v_mul_f32_e32 v30, v16, v170
	v_mul_f32_e32 v31, v17, v170
	v_mul_f32_e32 v16, v21, v21
	v_mul_f32_e32 v22, v22, v170
	v_mul_f32_e32 v23, v23, v170
	v_fmac_f32_e32 v16, v20, v20
	v_fmac_f32_e32 v16, v22, v22
	v_fmac_f32_e32 v16, v23, v23
	v_fmac_f32_e32 v36, v26, v26
	v_fmac_f32_e32 v16, v30, v30
	v_cvt_pk_bf16_f32 v24, v28, v29
	v_fmac_f32_e32 v36, v27, v27
	v_mul_f32_e32 v28, v18, v170
	v_mul_f32_e32 v29, v19, v170
	v_fmac_f32_e32 v16, v31, v31
	v_fmac_f32_e32 v36, v34, v34
	v_fmac_f32_e32 v16, v28, v28
	v_fmac_f32_e32 v36, v35, v35
	v_fmac_f32_e32 v16, v29, v29
	v_add_f32_e32 v16, v36, v16
	ds_bpermute_b32 v17, v179, v16
	s_waitcnt lgkmcnt(1)
	v_lshlrev_b64 v[32:33], 10, v[172:173]
	v_lshl_add_u64 v[32:33], v[128:129], 0, v[32:33]
	v_cvt_pk_bf16_f32 v26, v26, v27
	v_cvt_pk_bf16_f32 v27, v34, v35
	s_waitcnt lgkmcnt(0)
	v_add_f32_e32 v16, v16, v17
	ds_bpermute_b32 v17, v185, v16
	v_cvt_pk_bf16_f32 v18, v20, v21
	v_cvt_pk_bf16_f32 v19, v22, v23
	v_cvt_pk_bf16_f32 v20, v30, v31
	v_cvt_pk_bf16_f32 v21, v28, v29
	global_store_dwordx4 v[32:33], v[24:27], off
	global_store_dwordx4 v[32:33], v[18:21], off offset:256
	s_and_saveexec_b64 s[26:27], s[2:3]
	s_cbranch_execz .LBB0_893
	s_waitcnt lgkmcnt(0)
	v_add_f32_e32 v16, v16, v17
	global_atomic_add_f32 v[112:113], v16, off offset:640
.LBB0_893:
	s_or_b64 exec, exec, s[26:27]
	v_mul_f32_e32 v12, v12, v166
	v_mul_f32_e32 v13, v13, v166
	v_mul_f32_e32 v14, v14, v166
	v_mul_f32_e32 v15, v15, v166
	v_mul_f32_e32 v20, v13, v13
	v_fmac_f32_e32 v20, v12, v12
	v_fmac_f32_e32 v20, v14, v14
	v_mul_f32_e32 v4, v4, v166
	v_mul_f32_e32 v5, v5, v166
	v_mul_f32_e32 v18, v10, v166
	v_mul_f32_e32 v19, v11, v166
	v_mul_f32_e32 v10, v8, v166
	v_mul_f32_e32 v11, v9, v166
	v_cvt_pk_bf16_f32 v9, v14, v15
	v_fmac_f32_e32 v20, v15, v15
	v_mul_f32_e32 v14, v0, v166
	v_mul_f32_e32 v15, v1, v166
	v_mul_f32_e32 v0, v5, v5
	v_mul_f32_e32 v6, v6, v166
	v_mul_f32_e32 v7, v7, v166
	v_fmac_f32_e32 v0, v4, v4
	v_fmac_f32_e32 v0, v6, v6
	v_fmac_f32_e32 v0, v7, v7
	v_fmac_f32_e32 v20, v10, v10
	v_fmac_f32_e32 v0, v14, v14
	v_cvt_pk_bf16_f32 v8, v12, v13
	v_fmac_f32_e32 v20, v11, v11
	v_mul_f32_e32 v12, v2, v166
	v_mul_f32_e32 v13, v3, v166
	v_fmac_f32_e32 v0, v15, v15
	v_fmac_f32_e32 v20, v18, v18
	v_fmac_f32_e32 v0, v12, v12
	v_fmac_f32_e32 v20, v19, v19
	v_fmac_f32_e32 v0, v13, v13
	v_add_f32_e32 v0, v20, v0
	ds_bpermute_b32 v1, v179, v0
	s_waitcnt lgkmcnt(1)
	v_lshlrev_b64 v[16:17], 10, v[168:169]
	v_lshl_add_u64 v[16:17], v[128:129], 0, v[16:17]
	v_cvt_pk_bf16_f32 v10, v10, v11
	v_cvt_pk_bf16_f32 v11, v18, v19
	s_waitcnt lgkmcnt(0)
	v_add_f32_e32 v0, v0, v1
	ds_bpermute_b32 v1, v185, v0
	v_cvt_pk_bf16_f32 v2, v4, v5
	v_cvt_pk_bf16_f32 v3, v6, v7
	v_cvt_pk_bf16_f32 v4, v14, v15
	v_cvt_pk_bf16_f32 v5, v12, v13
	global_store_dwordx4 v[16:17], v[8:11], off
	global_store_dwordx4 v[16:17], v[2:5], off offset:256
	s_and_saveexec_b64 s[26:27], s[2:3]
	s_cbranch_execz .LBB0_868
	s_waitcnt lgkmcnt(0)
	v_add_f32_e32 v0, v0, v1
	global_atomic_add_f32 v[112:113], v0, off offset:704
	s_branch .LBB0_868

; #define PG8_STAGE(bufoff, gbase, voff) do { _Pragma("unroll") for (int _i = 0; _i < 2; ++_i) \
;         __builtin_amdgcn_global_load_lds((const unsigned*)((const char*)(gbase) + (voff)[_i]), (LAS unsigned*)(lds + (bufoff) + ldsw + _i * 8192), 16, 0, 0); } while (0)
; #define PG8_LDA(dst, b, h) do { _Pragma("unroll") for (int m = 0; m < 4; ++m) _Pragma("unroll") for (int k = 0; k < 2; ++k) dst[m][k] = *(const LAS bf16x8*)(lds + PG8_SA(b, h) + aoff + m * 2048 + k * 1024); } while (0)
; #define PG8_LDB(dst, b, h) do { _Pragma("unroll") for (int n = 0; n < 2; ++n) _Pragma("unroll") for (int k = 0; k < 2; ++k) dst[n][k] = *(const LAS bf16x8*)(lds + PG8_SB(b, h) + boff + n * 2048 + k * 1024); } while (0)
; #define PG8_MMA(ai, bj, At, Bt) do { __builtin_amdgcn_s_setprio(1); _Pragma("unroll") for (int m = 0; m < 4; ++m) _Pragma("unroll") for (int n = 0; n < 2; ++n) _Pragma("unroll") for (int k = 0; k < 2; ++k) \
;         acc[ai][bj][m][n] = __builtin_amdgcn_mfma_f32_16x16x32_bf16(Bt[n][k], At[m][k], acc[ai][bj][m][n], 0, 0, 0); __builtin_amdgcn_s_setprio(0); } while (0)
; #define PG8_WAIT_L(n) asm volatile("s_waitcnt lgkmcnt(" #n ")" ::: "memory")
; #define PG8_BAR __builtin_amdgcn_s_barrier()
; #define PG8_SCHED __builtin_amdgcn_sched_barrier(0)
; template <class Epi>
; DI void gemm_phase(LAS unsigned char* lds, int wid, int K, int lda, int ldb, bool bperm, const Sched3& S, const Epi& E) {
;     ...
;             PG8_LDB(B0, 0, 0); PG8_SCHED; PG8_LDA(At, 0, 0); PG8_STAGE(PG8_SA(1, 1), a1 + hA, voffA);
;             PG8_WAIT_L(8); PG8_BAR; PG8_WAIT_L(0); PG8_MMA(0, 0, At, B0); PG8_BAR; PG8_SCHED;
;             PG8_LDB(B1, 0, 1); PG8_STAGE(PG8_SB(0, 0), b2, voffB);
;             PG8_BAR; PG8_WAIT_L(0); PG8_MMA(0, 1, At, B1); PG8_BAR;
;             PG8_LDA(At, 0, 1); PG8_STAGE(PG8_SA(0, 0), a2, voffA);
;             PG8_BAR; PG8_WAIT_L(0); if (full) PG8_MMA(1, 0, At, B0); PG8_BAR; PG8_SCHED;
.LBB0_996:
	ds_read_b128 v[156:159], v182
	ds_read_b128 v[160:163], v182 offset:1024
	ds_read_b128 v[164:167], v182 offset:2048
	ds_read_b128 v[168:171], v182 offset:3072
	s_add_u32 s54, s52, 0xfffe0080
	s_addc_u32 s55, s53, -1
	s_cmp_eq_u32 s61, 4
	s_cselect_b32 s57, s41, s55
	s_cselect_b32 s56, s43, s54
	s_cselect_b32 s55, s51, s60
	s_cselect_b32 s54, s58, s59
	v_lshl_add_u64 v[214:215], s[52:53], 0, v[144:145]
	s_add_i32 m0, s66, 0xc000
	ds_read_b128 v[172:175], v183
	ds_read_b128 v[186:189], v183 offset:1024
	ds_read_b128 v[190:193], v183 offset:2048
	ds_read_b128 v[194:197], v183 offset:3072
	ds_read_b128 v[198:201], v183 offset:4096
	ds_read_b128 v[202:205], v183 offset:5120
	ds_read_b128 v[206:209], v183 offset:6144
	ds_read_b128 v[210:213], v183 offset:7168
	global_load_lds_dwordx4 v[214:215], off
	v_lshl_add_u64 v[214:215], s[52:53], 0, v[146:147]
	s_add_i32 m0, s66, 0xe000
	s_nop 0
	global_load_lds_dwordx4 v[214:215], off
	s_waitcnt lgkmcnt(8)
	s_barrier
	s_waitcnt lgkmcnt(0)
	s_setprio 1
	s_waitcnt lgkmcnt(0)
	v_mfma_f32_16x16x32_bf16 v[124:127], v[156:159], v[172:175], v[124:127]
	v_mfma_f32_16x16x32_bf16 v[120:123], v[164:167], v[172:175], v[120:123]
	v_mfma_f32_16x16x32_bf16 v[116:119], v[156:159], v[190:193], v[116:119]
	v_mfma_f32_16x16x32_bf16 v[112:115], v[164:167], v[190:193], v[112:115]
	v_mfma_f32_16x16x32_bf16 v[108:111], v[156:159], v[198:201], v[108:111]
	v_mfma_f32_16x16x32_bf16 v[104:107], v[164:167], v[198:201], v[104:107]
	v_mfma_f32_16x16x32_bf16 v[100:103], v[156:159], v[206:209], v[100:103]
	v_mfma_f32_16x16x32_bf16 v[96:99], v[164:167], v[206:209], v[96:99]
	v_mfma_f32_16x16x32_bf16 v[124:127], v[160:163], v[186:189], v[124:127]
	v_mfma_f32_16x16x32_bf16 v[120:123], v[168:171], v[186:189], v[120:123]
	v_mfma_f32_16x16x32_bf16 v[116:119], v[160:163], v[194:197], v[116:119]
	v_mfma_f32_16x16x32_bf16 v[112:115], v[168:171], v[194:197], v[112:115]
	v_mfma_f32_16x16x32_bf16 v[108:111], v[160:163], v[202:205], v[108:111]
	v_mfma_f32_16x16x32_bf16 v[104:107], v[168:171], v[202:205], v[104:107]
	v_mfma_f32_16x16x32_bf16 v[100:103], v[160:163], v[210:213], v[100:103]
	v_mfma_f32_16x16x32_bf16 v[96:99], v[168:171], v[210:213], v[96:99]
	s_setprio 0
	s_barrier
	s_add_i32 s62, s76, s65
	v_lshl_add_u64 v[222:223], s[54:55], 0, v[130:131]
	s_mov_b32 m0, s62
	ds_read_b128 v[214:217], v184
	ds_read_b128 v[218:221], v184 offset:1024
	ds_read_b128 v[224:227], v184 offset:2048
	ds_read_b128 v[228:231], v184 offset:3072
	global_load_lds_dwordx4 v[222:223], off
	v_lshl_add_u64 v[232:233], s[54:55], 0, v[134:135]
	s_add_i32 m0, s62, 0x2000
	s_nop 0
	global_load_lds_dwordx4 v[232:233], off
	s_barrier
	s_waitcnt lgkmcnt(0)
	s_setprio 1
	s_waitcnt lgkmcnt(0)
	v_mfma_f32_16x16x32_bf16 v[60:63], v[214:217], v[172:175], v[60:63]
	v_mfma_f32_16x16x32_bf16 v[56:59], v[224:227], v[172:175], v[56:59]
	v_mfma_f32_16x16x32_bf16 v[52:55], v[214:217], v[190:193], v[52:55]
	v_mfma_f32_16x16x32_bf16 v[48:51], v[224:227], v[190:193], v[48:51]
	v_mfma_f32_16x16x32_bf16 v[44:47], v[214:217], v[198:201], v[44:47]
	v_mfma_f32_16x16x32_bf16 v[40:43], v[224:227], v[198:201], v[40:43]
	v_mfma_f32_16x16x32_bf16 v[36:39], v[214:217], v[206:209], v[36:39]
	v_mfma_f32_16x16x32_bf16 v[32:35], v[224:227], v[206:209], v[32:35]
	v_mfma_f32_16x16x32_bf16 v[60:63], v[218:221], v[186:189], v[60:63]
	v_mfma_f32_16x16x32_bf16 v[56:59], v[228:231], v[186:189], v[56:59]
	v_mfma_f32_16x16x32_bf16 v[52:55], v[218:221], v[194:197], v[52:55]
	v_mfma_f32_16x16x32_bf16 v[48:51], v[228:231], v[194:197], v[48:51]
	v_mfma_f32_16x16x32_bf16 v[44:47], v[218:221], v[202:205], v[44:47]
	v_mfma_f32_16x16x32_bf16 v[40:43], v[228:231], v[202:205], v[40:43]
	v_mfma_f32_16x16x32_bf16 v[36:39], v[218:221], v[210:213], v[36:39]
	v_mfma_f32_16x16x32_bf16 v[32:35], v[228:231], v[210:213], v[32:35]
	s_setprio 0
	s_mov_b32 m0, s66
	v_lshl_add_u64 v[234:235], s[56:57], 0, v[128:129]
	s_barrier
	ds_read_b128 v[172:175], v183 offset:16384
	ds_read_b128 v[186:189], v183 offset:17408
	ds_read_b128 v[190:193], v183 offset:18432
	ds_read_b128 v[194:197], v183 offset:19456
	ds_read_b128 v[198:201], v183 offset:20480
	ds_read_b128 v[202:205], v183 offset:21504
	ds_read_b128 v[206:209], v183 offset:22528
	ds_read_b128 v[210:213], v183 offset:23552
	global_load_lds_dwordx4 v[234:235], off
	v_lshl_add_u64 v[236:237], s[56:57], 0, v[132:133]
	s_mov_b32 m0, s67
	s_nop 0
	global_load_lds_dwordx4 v[236:237], off
	s_barrier
	s_waitcnt lgkmcnt(0)
	s_setprio 1
	s_waitcnt lgkmcnt(0)
	v_mfma_f32_16x16x32_bf16 v[92:95], v[156:159], v[172:175], v[92:95]
	v_mfma_f32_16x16x32_bf16 v[88:91], v[164:167], v[172:175], v[88:91]
	v_mfma_f32_16x16x32_bf16 v[84:87], v[156:159], v[190:193], v[84:87]
	v_mfma_f32_16x16x32_bf16 v[80:83], v[164:167], v[190:193], v[80:83]
	v_mfma_f32_16x16x32_bf16 v[76:79], v[156:159], v[198:201], v[76:79]
	v_mfma_f32_16x16x32_bf16 v[72:75], v[164:167], v[198:201], v[72:75]
	v_mfma_f32_16x16x32_bf16 v[68:71], v[156:159], v[206:209], v[68:71]
	v_mfma_f32_16x16x32_bf16 v[64:67], v[164:167], v[206:209], v[64:67]
	v_mfma_f32_16x16x32_bf16 v[92:95], v[160:163], v[186:189], v[92:95]
	v_mfma_f32_16x16x32_bf16 v[88:91], v[168:171], v[186:189], v[88:91]
	v_mfma_f32_16x16x32_bf16 v[84:87], v[160:163], v[194:197], v[84:87]
	v_mfma_f32_16x16x32_bf16 v[80:83], v[168:171], v[194:197], v[80:83]
	v_mfma_f32_16x16x32_bf16 v[76:79], v[160:163], v[202:205], v[76:79]
	v_mfma_f32_16x16x32_bf16 v[72:75], v[168:171], v[202:205], v[72:75]
	v_mfma_f32_16x16x32_bf16 v[68:71], v[160:163], v[210:213], v[68:71]
	v_mfma_f32_16x16x32_bf16 v[64:67], v[168:171], v[210:213], v[64:67]
	s_setprio 0
	s_barrier
; #define PG8_STAGE(bufoff, gbase, voff) do { _Pragma("unroll") for (int _i = 0; _i < 2; ++_i) \
;         __builtin_amdgcn_global_load_lds((const unsigned*)((const char*)(gbase) + (voff)[_i]), (LAS unsigned*)(lds + (bufoff) + ldsw + _i * 8192), 16, 0, 0); } while (0)
; #define PG8_LDA(dst, b, h) do { _Pragma("unroll") for (int m = 0; m < 4; ++m) _Pragma("unroll") for (int k = 0; k < 2; ++k) dst[m][k] = *(const LAS bf16x8*)(lds + PG8_SA(b, h) + aoff + m * 2048 + k * 1024); } while (0)
; #define PG8_LDB(dst, b, h) do { _Pragma("unroll") for (int n = 0; n < 2; ++n) _Pragma("unroll") for (int k = 0; k < 2; ++k) dst[n][k] = *(const LAS bf16x8*)(lds + PG8_SB(b, h) + boff + n * 2048 + k * 1024); } while (0)
; #define PG8_MMA(ai, bj, At, Bt) do { __builtin_amdgcn_s_setprio(1); _Pragma("unroll") for (int m = 0; m < 4; ++m) _Pragma("unroll") for (int n = 0; n < 2; ++n) _Pragma("unroll") for (int k = 0; k < 2; ++k) \
;         acc[ai][bj][m][n] = __builtin_amdgcn_mfma_f32_16x16x32_bf16(Bt[n][k], At[m][k], acc[ai][bj][m][n], 0, 0, 0); __builtin_amdgcn_s_setprio(0); } while (0)
; #define PG8_WAIT_V(n) asm volatile("s_waitcnt vmcnt(" #n ")" ::: "memory")
; #define PG8_WAIT_L(n) asm volatile("s_waitcnt lgkmcnt(" #n ")" ::: "memory")
; #define PG8_BAR __builtin_amdgcn_s_barrier()
; #define PG8_SCHED __builtin_amdgcn_sched_barrier(0)
; template <class Epi>
; DI void gemm_phase(LAS unsigned char* lds, int wid, int K, int lda, int ldb, bool bperm, const Sched3& S, const Epi& E) {
;     ...
;             PG8_STAGE(PG8_SB(0, 1), b2 + hstepB, voffB);
;             PG8_WAIT_V(6); PG8_BAR; if (full) PG8_MMA(1, 1, At, B1); PG8_BAR;
;             PG8_LDB(B0, 1, 0); PG8_SCHED; PG8_LDA(At, 1, 0); PG8_STAGE(PG8_SA(0, 1), a2 + h2, voffA);
;             PG8_WAIT_L(8); PG8_BAR; PG8_WAIT_L(0); PG8_MMA(0, 0, At, B0); PG8_BAR; PG8_SCHED;
;             PG8_LDB(B1, 1, 1); PG8_STAGE(PG8_SB(1, 0), b3, voffB);
;             PG8_BAR; PG8_WAIT_L(0); PG8_MMA(0, 1, At, B1); PG8_BAR;
;             PG8_LDA(At, 1, 1); PG8_STAGE(PG8_SA(1, 0), a3, voffA);
;             PG8_BAR; PG8_WAIT_L(0); if (full) PG8_MMA(1, 0, At, B0); PG8_BAR; PG8_SCHED;
	s_add_u32 s62, s54, 0x20000
	s_addc_u32 s63, s55, 0
	s_add_i32 s86, s77, s65
	v_lshl_add_u64 v[156:157], s[62:63], 0, v[130:131]
	s_mov_b32 m0, s86
	s_nop 0
	global_load_lds_dwordx4 v[156:157], off
	v_lshl_add_u64 v[156:157], s[62:63], 0, v[134:135]
	s_add_i32 m0, s86, 0x2000
	s_nop 0
	global_load_lds_dwordx4 v[156:157], off
	s_waitcnt vmcnt(6)
	s_barrier
	s_setprio 1
	v_mfma_f32_16x16x32_bf16 v[28:31], v[214:217], v[172:175], v[28:31]
	v_mfma_f32_16x16x32_bf16 v[24:27], v[224:227], v[172:175], v[24:27]
	v_mfma_f32_16x16x32_bf16 v[20:23], v[214:217], v[190:193], v[20:23]
	v_mfma_f32_16x16x32_bf16 v[16:19], v[224:227], v[190:193], v[16:19]
	v_mfma_f32_16x16x32_bf16 v[12:15], v[214:217], v[198:201], v[12:15]
	v_mfma_f32_16x16x32_bf16 v[8:11], v[224:227], v[198:201], v[8:11]
	v_mfma_f32_16x16x32_bf16 v[4:7], v[214:217], v[206:209], v[4:7]
	v_mfma_f32_16x16x32_bf16 v[0:3], v[224:227], v[206:209], v[0:3]
	v_mfma_f32_16x16x32_bf16 v[28:31], v[218:221], v[186:189], v[28:31]
	v_mfma_f32_16x16x32_bf16 v[24:27], v[228:231], v[186:189], v[24:27]
	v_mfma_f32_16x16x32_bf16 v[20:23], v[218:221], v[194:197], v[20:23]
	v_mfma_f32_16x16x32_bf16 v[16:19], v[228:231], v[194:197], v[16:19]
	v_mfma_f32_16x16x32_bf16 v[12:15], v[218:221], v[202:205], v[12:15]
	v_mfma_f32_16x16x32_bf16 v[8:11], v[228:231], v[202:205], v[8:11]
	v_mfma_f32_16x16x32_bf16 v[4:7], v[218:221], v[210:213], v[4:7]
	v_mfma_f32_16x16x32_bf16 v[0:3], v[228:231], v[210:213], v[0:3]
	s_setprio 0
	s_add_i32 s62, 0, 0x18000
	v_add_u32_e32 v136, s62, v179
	s_barrier
	ds_read_b128 v[156:159], v136
	ds_read_b128 v[160:163], v136 offset:1024
	ds_read_b128 v[164:167], v136 offset:2048
	ds_read_b128 v[168:171], v136 offset:3072
	s_add_u32 s56, s56, 0x20000
	s_addc_u32 s57, s57, 0
	s_mov_b32 m0, s68
	v_lshl_add_u64 v[214:215], s[56:57], 0, v[128:129]
	ds_read_b128 v[172:175], v183 offset:32768
	ds_read_b128 v[186:189], v183 offset:33792
	ds_read_b128 v[190:193], v183 offset:34816
	ds_read_b128 v[194:197], v183 offset:35840
	ds_read_b128 v[198:201], v183 offset:36864
	ds_read_b128 v[202:205], v183 offset:37888
	ds_read_b128 v[206:209], v183 offset:38912
	ds_read_b128 v[210:213], v183 offset:39936
	global_load_lds_dwordx4 v[214:215], off
	v_lshl_add_u64 v[214:215], s[56:57], 0, v[132:133]
	s_mov_b32 m0, s69
	s_nop 0
	global_load_lds_dwordx4 v[214:215], off
	s_waitcnt lgkmcnt(8)
	s_barrier
	s_waitcnt lgkmcnt(0)
	s_setprio 1
	s_waitcnt lgkmcnt(0)
	v_mfma_f32_16x16x32_bf16 v[124:127], v[156:159], v[172:175], v[124:127]
	v_mfma_f32_16x16x32_bf16 v[120:123], v[164:167], v[172:175], v[120:123]
	v_mfma_f32_16x16x32_bf16 v[116:119], v[156:159], v[190:193], v[116:119]
	v_mfma_f32_16x16x32_bf16 v[112:115], v[164:167], v[190:193], v[112:115]
	v_mfma_f32_16x16x32_bf16 v[108:111], v[156:159], v[198:201], v[108:111]
	v_mfma_f32_16x16x32_bf16 v[104:107], v[164:167], v[198:201], v[104:107]
	v_mfma_f32_16x16x32_bf16 v[100:103], v[156:159], v[206:209], v[100:103]
	v_mfma_f32_16x16x32_bf16 v[96:99], v[164:167], v[206:209], v[96:99]
	v_mfma_f32_16x16x32_bf16 v[124:127], v[160:163], v[186:189], v[124:127]
	v_mfma_f32_16x16x32_bf16 v[120:123], v[168:171], v[186:189], v[120:123]
	v_mfma_f32_16x16x32_bf16 v[116:119], v[160:163], v[194:197], v[116:119]
	v_mfma_f32_16x16x32_bf16 v[112:115], v[168:171], v[194:197], v[112:115]
	v_mfma_f32_16x16x32_bf16 v[108:111], v[160:163], v[202:205], v[108:111]
	v_mfma_f32_16x16x32_bf16 v[104:107], v[168:171], v[202:205], v[104:107]
	v_mfma_f32_16x16x32_bf16 v[100:103], v[160:163], v[210:213], v[100:103]
	v_mfma_f32_16x16x32_bf16 v[96:99], v[168:171], v[210:213], v[96:99]
	s_setprio 0
	s_barrier
	s_add_i32 s56, 0, 0x1c000
	s_add_i32 s57, s62, s65
	v_add_u32_e32 v136, s56, v179
	v_lshl_add_u64 v[222:223], v[222:223], 0, s[16:17]
	s_mov_b32 m0, s57
	ds_read_b128 v[214:217], v136
	ds_read_b128 v[218:221], v136 offset:1024
	ds_read_b128 v[224:227], v136 offset:2048
	ds_read_b128 v[228:231], v136 offset:3072
	global_load_lds_dwordx4 v[222:223], off
	v_lshl_add_u64 v[222:223], v[232:233], 0, s[16:17]
	s_add_i32 m0, s57, 0x2000
	s_nop 0
	global_load_lds_dwordx4 v[222:223], off
	s_barrier
	s_waitcnt lgkmcnt(0)
	s_setprio 1
	s_waitcnt lgkmcnt(0)
	v_mfma_f32_16x16x32_bf16 v[60:63], v[214:217], v[172:175], v[60:63]
	v_mfma_f32_16x16x32_bf16 v[56:59], v[224:227], v[172:175], v[56:59]
	v_mfma_f32_16x16x32_bf16 v[52:55], v[214:217], v[190:193], v[52:55]
	v_mfma_f32_16x16x32_bf16 v[48:51], v[224:227], v[190:193], v[48:51]
	v_mfma_f32_16x16x32_bf16 v[44:47], v[214:217], v[198:201], v[44:47]
	v_mfma_f32_16x16x32_bf16 v[40:43], v[224:227], v[198:201], v[40:43]
	v_mfma_f32_16x16x32_bf16 v[36:39], v[214:217], v[206:209], v[36:39]
	v_mfma_f32_16x16x32_bf16 v[32:35], v[224:227], v[206:209], v[32:35]
	v_mfma_f32_16x16x32_bf16 v[60:63], v[218:221], v[186:189], v[60:63]
	v_mfma_f32_16x16x32_bf16 v[56:59], v[228:231], v[186:189], v[56:59]
	v_mfma_f32_16x16x32_bf16 v[52:55], v[218:221], v[194:197], v[52:55]
	v_mfma_f32_16x16x32_bf16 v[48:51], v[228:231], v[194:197], v[48:51]
	v_mfma_f32_16x16x32_bf16 v[44:47], v[218:221], v[202:205], v[44:47]
	v_mfma_f32_16x16x32_bf16 v[40:43], v[228:231], v[202:205], v[40:43]
	v_mfma_f32_16x16x32_bf16 v[36:39], v[218:221], v[210:213], v[36:39]
	v_mfma_f32_16x16x32_bf16 v[32:35], v[228:231], v[210:213], v[32:35]
	s_setprio 0
	s_mov_b32 m0, s72
	v_lshl_add_u64 v[222:223], v[234:235], 0, s[16:17]
	s_barrier
	ds_read_b128 v[172:175], v183 offset:49152
	ds_read_b128 v[186:189], v183 offset:50176
	ds_read_b128 v[190:193], v183 offset:51200
	ds_read_b128 v[194:197], v183 offset:52224
	ds_read_b128 v[198:201], v183 offset:53248
	ds_read_b128 v[202:205], v183 offset:54272
	ds_read_b128 v[206:209], v183 offset:55296
	ds_read_b128 v[210:213], v183 offset:56320
	global_load_lds_dwordx4 v[222:223], off
	v_lshl_add_u64 v[222:223], v[236:237], 0, s[16:17]
	s_mov_b32 m0, s73
	s_nop 0
	global_load_lds_dwordx4 v[222:223], off
	s_barrier
; #define PG8_STAGE(bufoff, gbase, voff) do { _Pragma("unroll") for (int _i = 0; _i < 2; ++_i) \
;         __builtin_amdgcn_global_load_lds((const unsigned*)((const char*)(gbase) + (voff)[_i]), (LAS unsigned*)(lds + (bufoff) + ldsw + _i * 8192), 16, 0, 0); } while (0)
; #define PG8_MMA(ai, bj, At, Bt) do { __builtin_amdgcn_s_setprio(1); _Pragma("unroll") for (int m = 0; m < 4; ++m) _Pragma("unroll") for (int n = 0; n < 2; ++n) _Pragma("unroll") for (int k = 0; k < 2; ++k) \
;         acc[ai][bj][m][n] = __builtin_amdgcn_mfma_f32_16x16x32_bf16(Bt[n][k], At[m][k], acc[ai][bj][m][n], 0, 0, 0); __builtin_amdgcn_s_setprio(0); } while (0)
; #define PG8_WAIT_V(n) asm volatile("s_waitcnt vmcnt(" #n ")" ::: "memory")
; #define PG8_WAIT_L(n) asm volatile("s_waitcnt lgkmcnt(" #n ")" ::: "memory")
; #define PG8_BAR __builtin_amdgcn_s_barrier()
; #define PG8_SCHED __builtin_amdgcn_sched_barrier(0)
; #define LOAD_ROW_RS(rsv, ssqp, invn) float rsv[2][4]; ROWS8_ALL rsv[ai][m] = (ssqp)[row0 + ai * HALF + m * 16]; ROWS8_ALL rsv[ai][m] = rstd_of(rsv[ai][m], invn)
; template <class Epi>
; DI void gemm_phase(LAS unsigned char* lds, int wid, int K, int lda, int ldb, bool bperm, const Sched3& S, const Epi& E) {
;     ...
;             PG8_BAR; PG8_WAIT_L(0); if (full) PG8_MMA(1, 0, At, B0); PG8_BAR; PG8_SCHED;
;             PG8_STAGE(PG8_SB(1, 1), b3 + hstepB, voffB);
;             PG8_WAIT_V(6); PG8_BAR; if (full) PG8_MMA(1, 1, At, B1); PG8_BAR;
;         }
;     DI void operator()(const Acc& acc, const Unit& u, int wr, int wc, int fr, int fq) const {
;     ...
;             } else if (u.kind == K_KN) {
;                 LOAD_ROW_RS(rsv, SSQ(5), 1.f / 512.f);
	s_waitcnt lgkmcnt(0)
	s_setprio 1
	s_waitcnt lgkmcnt(0)
	v_mfma_f32_16x16x32_bf16 v[92:95], v[156:159], v[172:175], v[92:95]
	v_mfma_f32_16x16x32_bf16 v[88:91], v[164:167], v[172:175], v[88:91]
	v_mfma_f32_16x16x32_bf16 v[84:87], v[156:159], v[190:193], v[84:87]
	v_mfma_f32_16x16x32_bf16 v[80:83], v[164:167], v[190:193], v[80:83]
	v_mfma_f32_16x16x32_bf16 v[76:79], v[156:159], v[198:201], v[76:79]
	v_mfma_f32_16x16x32_bf16 v[72:75], v[164:167], v[198:201], v[72:75]
	v_mfma_f32_16x16x32_bf16 v[68:71], v[156:159], v[206:209], v[68:71]
	v_mfma_f32_16x16x32_bf16 v[64:67], v[164:167], v[206:209], v[64:67]
	v_mfma_f32_16x16x32_bf16 v[92:95], v[160:163], v[186:189], v[92:95]
	v_mfma_f32_16x16x32_bf16 v[88:91], v[168:171], v[186:189], v[88:91]
	v_mfma_f32_16x16x32_bf16 v[84:87], v[160:163], v[194:197], v[84:87]
	v_mfma_f32_16x16x32_bf16 v[80:83], v[168:171], v[194:197], v[80:83]
	v_mfma_f32_16x16x32_bf16 v[76:79], v[160:163], v[202:205], v[76:79]
	v_mfma_f32_16x16x32_bf16 v[72:75], v[168:171], v[202:205], v[72:75]
	v_mfma_f32_16x16x32_bf16 v[68:71], v[160:163], v[210:213], v[68:71]
	v_mfma_f32_16x16x32_bf16 v[64:67], v[168:171], v[210:213], v[64:67]
	s_setprio 0
	s_barrier
	s_add_u32 s54, s54, 0x20080
	s_addc_u32 s55, s55, 0
	s_add_i32 s56, s56, s65
	v_lshl_add_u64 v[156:157], s[54:55], 0, v[130:131]
	s_mov_b32 m0, s56
	s_nop 0
	global_load_lds_dwordx4 v[156:157], off
	v_lshl_add_u64 v[156:157], s[54:55], 0, v[134:135]
	s_add_i32 m0, s56, 0x2000
	s_nop 0
	global_load_lds_dwordx4 v[156:157], off
	s_waitcnt vmcnt(6)
	s_barrier
	s_setprio 1
	v_mfma_f32_16x16x32_bf16 v[28:31], v[214:217], v[172:175], v[28:31]
	v_mfma_f32_16x16x32_bf16 v[24:27], v[224:227], v[172:175], v[24:27]
	v_mfma_f32_16x16x32_bf16 v[20:23], v[214:217], v[190:193], v[20:23]
	v_mfma_f32_16x16x32_bf16 v[16:19], v[224:227], v[190:193], v[16:19]
	v_mfma_f32_16x16x32_bf16 v[12:15], v[214:217], v[198:201], v[12:15]
	v_mfma_f32_16x16x32_bf16 v[8:11], v[224:227], v[198:201], v[8:11]
	v_mfma_f32_16x16x32_bf16 v[4:7], v[214:217], v[206:209], v[4:7]
	v_mfma_f32_16x16x32_bf16 v[0:3], v[224:227], v[206:209], v[0:3]
	v_mfma_f32_16x16x32_bf16 v[28:31], v[218:221], v[186:189], v[28:31]
	v_mfma_f32_16x16x32_bf16 v[24:27], v[228:231], v[186:189], v[24:27]
	v_mfma_f32_16x16x32_bf16 v[20:23], v[218:221], v[194:197], v[20:23]
	v_mfma_f32_16x16x32_bf16 v[16:19], v[228:231], v[194:197], v[16:19]
	v_mfma_f32_16x16x32_bf16 v[12:15], v[218:221], v[202:205], v[12:15]
	v_mfma_f32_16x16x32_bf16 v[8:11], v[228:231], v[202:205], v[8:11]
	v_mfma_f32_16x16x32_bf16 v[4:7], v[218:221], v[210:213], v[4:7]
	v_mfma_f32_16x16x32_bf16 v[0:3], v[228:231], v[210:213], v[0:3]
	s_setprio 0
	s_add_i32 s61, s61, 2
	s_add_u32 s52, s52, 0x100
	s_addc_u32 s53, s53, 0
	s_add_u32 s59, s59, 0x100
	s_addc_u32 s60, s60, 0
	s_cmp_gt_u32 s61, 5
	s_barrier
	s_cbranch_scc0 .LBB0_996
	v_lshl_add_u32 v156, s50, 8, v177
	v_lshl_add_u32 v164, s84, 8, v181
	s_mov_b64 s[54:55], -1
	s_mov_b64 s[50:51], 0
	s_cmp_lt_i32 s85, 7
	s_mov_b64 s[52:53], 0
	s_cbranch_scc1 .LBB0_1001
	s_cmp_eq_u32 s85, 7
	s_mov_b64 s[52:53], -1
	s_cbranch_scc0 .LBB0_1000
	v_or_b32_e32 v168, 16, v156
	v_ashrrev_i32_e32 v169, 31, v168
	v_or_b32_e32 v170, 32, v156
	v_or_b32_e32 v198, 48, v156
	v_lshl_add_u64 v[158:159], v[168:169], 2, s[18:19]
	v_ashrrev_i32_e32 v171, 31, v170
	v_ashrrev_i32_e32 v199, 31, v198
	v_ashrrev_i32_e32 v157, 31, v156
	v_lshl_add_u64 v[160:161], v[170:171], 2, s[18:19]
	v_lshl_add_u64 v[162:163], v[198:199], 2, s[18:19]
	v_lshl_add_u64 v[166:167], v[156:157], 2, s[18:19]
	global_load_dword v136, v[158:159], off
	global_load_dword v176, v[160:161], off
	global_load_dword v178, v[162:163], off
	global_load_dword v180, v[166:167], off
	v_add_u32_e32 v200, 0x80, v156
	v_add_u32_e32 v166, 0x90, v156
	v_add_u32_e32 v162, 0xa0, v156
	v_add_u32_e32 v158, 0xb0, v156
	v_ashrrev_i32_e32 v201, 31, v200
	v_ashrrev_i32_e32 v167, 31, v166
	v_ashrrev_i32_e32 v163, 31, v162
	v_ashrrev_i32_e32 v159, 31, v158
	v_lshl_add_u64 v[160:161], v[200:201], 2, s[18:19]
	v_lshl_add_u64 v[172:173], v[166:167], 2, s[18:19]
	v_lshl_add_u64 v[174:175], v[162:163], 2, s[18:19]
	v_lshl_add_u64 v[186:187], v[158:159], 2, s[18:19]
	global_load_dword v228, v[160:161], off
	global_load_dword v229, v[172:173], off
	global_load_dword v230, v[174:175], off
	global_load_dword v231, v[186:187], off
	v_ashrrev_i32_e32 v165, 31, v164
	v_lshlrev_b64 v[172:173], 12, v[156:157]
	v_lshlrev_b64 v[168:169], 12, v[168:169]
	v_lshlrev_b64 v[160:161], 1, v[164:165]
	v_lshl_add_u64 v[168:169], s[20:21], 0, v[168:169]
	v_lshl_add_u64 v[202:203], v[168:169], 0, v[160:161]
	v_lshlrev_b64 v[170:171], 12, v[170:171]
	v_lshl_add_u64 v[172:173], s[20:21], 0, v[172:173]
	v_lshl_add_u64 v[170:171], s[20:21], 0, v[170:171]
	v_lshl_add_u64 v[196:197], v[172:173], 0, v[160:161]
	v_lshl_add_u64 v[204:205], v[170:171], 0, v[160:161]
	v_lshlrev_b64 v[166:167], 12, v[166:167]
	v_lshl_add_u64 v[166:167], s[20:21], 0, v[166:167]
	v_lshlrev_b64 v[162:163], 12, v[162:163]
	v_lshl_add_u64 v[162:163], s[20:21], 0, v[162:163]
	v_lshl_add_u64 v[162:163], v[162:163], 0, v[160:161]
	v_lshlrev_b64 v[158:159], 12, v[158:159]
	v_lshl_add_u64 v[158:159], s[20:21], 0, v[158:159]
	s_mov_b64 s[52:53], 0
	s_waitcnt vmcnt(0)
; #define ROWS8 _Pragma("unroll") for (int ai = 0; ai < 2; ++ai) _Pragma("unroll") for (int m = 0; m < 4; ++m) if (ai == 0 || !hf)
; #define LOAD_ROW_RS(rsv, ssqp, invn) float rsv[2][4]; ROWS8_ALL rsv[ai][m] = (ssqp)[row0 + ai * HALF + m * 16]; ROWS8_ALL rsv[ai][m] = rstd_of(rsv[ai][m], invn)
; #define PK8(v0, v1) ({ const u32x2 h0_ = pk4(v0), h1_ = pk4(v1); (u32x4){h0_.x, h0_.y, h1_.x, h1_.y}; })
;     DI void operator()(const Acc& acc, const Unit& u, int wr, int wc, int fr, int fq) const {
;     ...
;                 LOAD_ROW_RS(rsv, SSQ(5), 1.f / 512.f);
;                 ROWS8 { const int r = row0 + ai * HALF + m * 16; const float rs = rsv[ai][m];
;                     bf16_t* dst = WSB(OFF_KN) + (size_t)r * 2048 + colp;
; #pragma unroll
;                     for (int bj = 0; bj < 2; ++bj) *(u32x4*)(dst + bj * HALF) = PK8(acc[ai][bj][m][0] * rs, acc[ai][bj][m][1] * rs); }
	v_fmamk_f32 v157, v136, 0x3b000000, v185
	v_fmamk_f32 v165, v176, 0x3b000000, v185
	v_rsq_f32_e32 v168, v157
	v_fmamk_f32 v136, v180, 0x3b000000, v185
	v_rsq_f32_e32 v136, v136
	v_rsq_f32_e32 v176, v165
	v_fmamk_f32 v169, v178, 0x3b000000, v185
	v_rsq_f32_e32 v178, v169
	v_mul_f32_e32 v170, v126, v136
	v_mul_f32_e32 v171, v127, v136
	v_mul_f32_e32 v172, v124, v136
	v_mul_f32_e32 v173, v125, v136
	v_mul_f32_e32 v174, v122, v136
	v_mul_f32_e32 v175, v123, v136
	v_mul_f32_e32 v186, v120, v136
	v_mul_f32_e32 v187, v121, v136
	v_mul_f32_e32 v188, v62, v136
	v_mul_f32_e32 v189, v63, v136
	v_mul_f32_e32 v190, v60, v136
	v_mul_f32_e32 v191, v61, v136
	v_mul_f32_e32 v192, v58, v136
	v_mul_f32_e32 v193, v59, v136
	v_mul_f32_e32 v194, v56, v136
	v_mul_f32_e32 v195, v57, v136
	v_mul_f32_e32 v206, v118, v168
	v_mul_f32_e32 v207, v119, v168
	v_mul_f32_e32 v208, v116, v168
	v_mul_f32_e32 v209, v117, v168
	v_mul_f32_e32 v210, v114, v168
	v_mul_f32_e32 v211, v115, v168
	v_mul_f32_e32 v212, v112, v168
	v_mul_f32_e32 v213, v113, v168
	v_mul_f32_e32 v214, v54, v168
	v_mul_f32_e32 v215, v55, v168
	v_mul_f32_e32 v216, v52, v168
	v_mul_f32_e32 v217, v53, v168
	v_mul_f32_e32 v218, v50, v168
	v_mul_f32_e32 v219, v51, v168
	v_mul_f32_e32 v220, v48, v168
	v_mul_f32_e32 v221, v49, v168
	v_cvt_pk_bf16_f32 v168, v172, v173
	v_cvt_pk_bf16_f32 v169, v170, v171
	v_cvt_pk_bf16_f32 v170, v186, v187
	v_cvt_pk_bf16_f32 v171, v174, v175
	v_cvt_pk_bf16_f32 v172, v190, v191
	v_cvt_pk_bf16_f32 v173, v188, v189
	v_cvt_pk_bf16_f32 v174, v194, v195
	v_cvt_pk_bf16_f32 v175, v192, v193
	v_cvt_pk_bf16_f32 v186, v208, v209
	v_cvt_pk_bf16_f32 v187, v206, v207
	v_cvt_pk_bf16_f32 v188, v212, v213
	v_cvt_pk_bf16_f32 v189, v210, v211
	v_cvt_pk_bf16_f32 v190, v216, v217
	v_cvt_pk_bf16_f32 v191, v214, v215
	v_cvt_pk_bf16_f32 v192, v220, v221
	v_cvt_pk_bf16_f32 v193, v218, v219
	global_store_dwordx4 v[196:197], v[168:171], off
	global_store_dwordx4 v[196:197], v[172:175], off offset:256
	global_store_dwordx4 v[202:203], v[186:189], off
	global_store_dwordx4 v[202:203], v[190:193], off offset:256
	v_mul_f32_e32 v168, v104, v176
	v_mul_f32_e32 v169, v105, v176
	v_mul_f32_e32 v170, v46, v176
	v_mul_f32_e32 v171, v47, v176
	v_cvt_pk_bf16_f32 v196, v168, v169
	v_mul_f32_e32 v168, v44, v176
	v_mul_f32_e32 v169, v45, v176
	v_mul_f32_e32 v172, v42, v176
	v_mul_f32_e32 v173, v43, v176
	v_cvt_pk_bf16_f32 v168, v168, v169
	v_cvt_pk_bf16_f32 v169, v170, v171
	v_mul_f32_e32 v170, v40, v176
	v_mul_f32_e32 v171, v41, v176
	v_mul_f32_e32 v174, v98, v178
	v_mul_f32_e32 v175, v99, v178
	v_cvt_pk_bf16_f32 v170, v170, v171
	v_cvt_pk_bf16_f32 v171, v172, v173
	global_store_dwordx4 v[204:205], v[168:171], off offset:256
	v_fmamk_f32 v157, v230, 0x3b000000, v185
	v_mul_f32_e32 v222, v110, v176
	v_mul_f32_e32 v223, v111, v176
	v_lshlrev_b64 v[168:169], 12, v[198:199]
	v_lshl_add_u64 v[168:169], s[20:21], 0, v[168:169]
	v_lshl_add_u64 v[172:173], v[168:169], 0, v[160:161]
	v_mul_f32_e32 v170, v102, v178
	v_mul_f32_e32 v171, v103, v178
	v_mul_f32_e32 v168, v100, v178
	v_mul_f32_e32 v169, v101, v178
	v_mul_f32_e32 v224, v108, v176
	v_mul_f32_e32 v225, v109, v176
	v_cvt_pk_bf16_f32 v168, v168, v169
	v_cvt_pk_bf16_f32 v169, v170, v171
	v_mul_f32_e32 v170, v96, v178
	v_mul_f32_e32 v171, v97, v178
	v_mul_f32_e32 v226, v106, v176
	v_mul_f32_e32 v227, v107, v176
	v_cvt_pk_bf16_f32 v170, v170, v171
	v_cvt_pk_bf16_f32 v171, v174, v175
	global_store_dwordx4 v[172:173], v[168:171], off
	v_mul_f32_e32 v174, v34, v178
	v_mul_f32_e32 v175, v35, v178
	v_fmamk_f32 v136, v231, 0x3b000000, v185
	v_mul_f32_e32 v170, v38, v178
	v_mul_f32_e32 v171, v39, v178
	v_mul_f32_e32 v168, v36, v178
	v_mul_f32_e32 v169, v37, v178
	v_rsq_f32_e32 v136, v136
	v_cvt_pk_bf16_f32 v168, v168, v169
	v_cvt_pk_bf16_f32 v169, v170, v171
	v_mul_f32_e32 v170, v32, v178
	v_mul_f32_e32 v171, v33, v178
	v_cvt_pk_bf16_f32 v194, v224, v225
	v_cvt_pk_bf16_f32 v170, v170, v171
	v_cvt_pk_bf16_f32 v171, v174, v175
	global_store_dwordx4 v[172:173], v[168:171], off offset:256
	v_rsq_f32_e32 v172, v157
	v_fmamk_f32 v157, v229, 0x3b000000, v185
	v_rsq_f32_e32 v174, v157
	v_fmamk_f32 v157, v228, 0x3b000000, v185
; #define ROWS8 _Pragma("unroll") for (int ai = 0; ai < 2; ++ai) _Pragma("unroll") for (int m = 0; m < 4; ++m) if (ai == 0 || !hf)
; #define LOAD_ROW_RS(rsv, ssqp, invn) float rsv[2][4]; ROWS8_ALL rsv[ai][m] = (ssqp)[row0 + ai * HALF + m * 16]; ROWS8_ALL rsv[ai][m] = rstd_of(rsv[ai][m], invn)
; #define PK8(v0, v1) ({ const u32x2 h0_ = pk4(v0), h1_ = pk4(v1); (u32x4){h0_.x, h0_.y, h1_.x, h1_.y}; })
;     DI void operator()(const Acc& acc, const Unit& u, int wr, int wc, int fr, int fq) const {
;     ...
;                 LOAD_ROW_RS(rsv, SSQ(5), 1.f / 512.f);
;                 ROWS8 { const int r = row0 + ai * HALF + m * 16; const float rs = rsv[ai][m];
;                     bf16_t* dst = WSB(OFF_KN) + (size_t)r * 2048 + colp;
; #pragma unroll
;                     for (int bj = 0; bj < 2; ++bj) *(u32x4*)(dst + bj * HALF) = PK8(acc[ai][bj][m][0] * rs, acc[ai][bj][m][1] * rs); }
	v_rsq_f32_e32 v176, v157
	v_lshlrev_b64 v[168:169], 12, v[200:201]
	v_lshl_add_u64 v[168:169], s[20:21], 0, v[168:169]
	v_lshl_add_u64 v[186:187], v[168:169], 0, v[160:161]
	v_mul_f32_e32 v170, v94, v176
	v_mul_f32_e32 v171, v95, v176
	v_mul_f32_e32 v168, v92, v176
	v_mul_f32_e32 v169, v93, v176
	v_mul_f32_e32 v188, v90, v176
	v_mul_f32_e32 v189, v91, v176
	v_cvt_pk_bf16_f32 v168, v168, v169
	v_cvt_pk_bf16_f32 v169, v170, v171
	v_mul_f32_e32 v170, v88, v176
	v_mul_f32_e32 v171, v89, v176
	v_cvt_pk_bf16_f32 v195, v222, v223
	v_cvt_pk_bf16_f32 v170, v170, v171
	v_cvt_pk_bf16_f32 v171, v188, v189
	global_store_dwordx4 v[186:187], v[168:171], off
	v_mul_f32_e32 v188, v26, v176
	v_mul_f32_e32 v189, v27, v176
	v_cvt_pk_bf16_f32 v197, v226, v227
	v_mul_f32_e32 v170, v30, v176
	v_mul_f32_e32 v171, v31, v176
	v_mul_f32_e32 v168, v28, v176
	v_mul_f32_e32 v169, v29, v176
	global_store_dwordx4 v[204:205], v[194:197], off
	v_cvt_pk_bf16_f32 v168, v168, v169
	v_cvt_pk_bf16_f32 v169, v170, v171
	v_mul_f32_e32 v170, v24, v176
	v_mul_f32_e32 v171, v25, v176
	s_nop 0
	v_cvt_pk_bf16_f32 v170, v170, v171
	v_cvt_pk_bf16_f32 v171, v188, v189
	global_store_dwordx4 v[186:187], v[168:171], off offset:256
	v_mul_f32_e32 v186, v82, v174
	v_mul_f32_e32 v187, v83, v174
	s_nop 0
	v_lshl_add_u64 v[170:171], v[166:167], 0, v[160:161]
	v_mul_f32_e32 v168, v86, v174
	v_mul_f32_e32 v169, v87, v174
	v_mul_f32_e32 v166, v84, v174
	v_mul_f32_e32 v167, v85, v174
	s_nop 0
	v_cvt_pk_bf16_f32 v166, v166, v167
	v_cvt_pk_bf16_f32 v167, v168, v169
	v_mul_f32_e32 v168, v80, v174
	v_mul_f32_e32 v169, v81, v174
	s_nop 0
	v_cvt_pk_bf16_f32 v168, v168, v169
	v_cvt_pk_bf16_f32 v169, v186, v187
	global_store_dwordx4 v[170:171], v[166:169], off
	v_mul_f32_e32 v186, v18, v174
	v_mul_f32_e32 v187, v19, v174
	s_nop 0
	v_mul_f32_e32 v168, v22, v174
	v_mul_f32_e32 v169, v23, v174
	v_mul_f32_e32 v166, v20, v174
	v_mul_f32_e32 v167, v21, v174
	s_nop 0
	v_cvt_pk_bf16_f32 v166, v166, v167
	v_cvt_pk_bf16_f32 v167, v168, v169
	v_mul_f32_e32 v168, v16, v174
	v_mul_f32_e32 v169, v17, v174
	s_nop 0
	v_cvt_pk_bf16_f32 v168, v168, v169
	v_cvt_pk_bf16_f32 v169, v186, v187
	global_store_dwordx4 v[170:171], v[166:169], off offset:256
	v_mul_f32_e32 v170, v74, v172
	v_mul_f32_e32 v171, v75, v172
	s_nop 0
	v_mul_f32_e32 v168, v78, v172
	v_mul_f32_e32 v169, v79, v172
	v_mul_f32_e32 v166, v76, v172
	v_mul_f32_e32 v167, v77, v172
	s_nop 0
	v_cvt_pk_bf16_f32 v166, v166, v167
	v_cvt_pk_bf16_f32 v167, v168, v169
	v_mul_f32_e32 v168, v72, v172
	v_mul_f32_e32 v169, v73, v172
	s_nop 0
	v_cvt_pk_bf16_f32 v168, v168, v169
	v_cvt_pk_bf16_f32 v169, v170, v171
	global_store_dwordx4 v[162:163], v[166:169], off
	v_mul_f32_e32 v170, v10, v172
	v_mul_f32_e32 v171, v11, v172
	s_nop 0
	v_mul_f32_e32 v168, v14, v172
	v_mul_f32_e32 v169, v15, v172
	v_mul_f32_e32 v166, v12, v172
	v_mul_f32_e32 v167, v13, v172
	s_nop 0
	v_cvt_pk_bf16_f32 v166, v166, v167
	v_cvt_pk_bf16_f32 v167, v168, v169
	v_mul_f32_e32 v168, v8, v172
	v_mul_f32_e32 v169, v9, v172
	s_nop 0
	v_cvt_pk_bf16_f32 v168, v168, v169
	v_cvt_pk_bf16_f32 v169, v170, v171
	global_store_dwordx4 v[162:163], v[166:169], off offset:256
	v_lshl_add_u64 v[162:163], v[158:159], 0, v[160:161]
	v_mul_f32_e32 v160, v70, v136
	v_mul_f32_e32 v161, v71, v136
	v_mul_f32_e32 v158, v68, v136
	v_mul_f32_e32 v159, v69, v136
	v_mul_f32_e32 v166, v66, v136
	v_mul_f32_e32 v167, v67, v136
	v_cvt_pk_bf16_f32 v158, v158, v159
	v_cvt_pk_bf16_f32 v159, v160, v161
	v_mul_f32_e32 v160, v64, v136
	v_mul_f32_e32 v161, v65, v136
	s_nop 0
	v_cvt_pk_bf16_f32 v160, v160, v161
	v_cvt_pk_bf16_f32 v161, v166, v167
	global_store_dwordx4 v[162:163], v[158:161], off
	v_mul_f32_e32 v166, v2, v136
	v_mul_f32_e32 v167, v3, v136
	s_nop 0
	v_mul_f32_e32 v160, v6, v136
	v_mul_f32_e32 v161, v7, v136
	v_mul_f32_e32 v158, v4, v136
	v_mul_f32_e32 v159, v5, v136
	s_nop 0
	v_cvt_pk_bf16_f32 v158, v158, v159
	v_cvt_pk_bf16_f32 v159, v160, v161
	v_mul_f32_e32 v160, v0, v136
	v_mul_f32_e32 v161, v1, v136
	s_nop 0
	v_cvt_pk_bf16_f32 v160, v160, v161
	v_cvt_pk_bf16_f32 v161, v166, v167
	global_store_dwordx4 v[162:163], v[158:161], off offset:256

; #define ROWS8 _Pragma("unroll") for (int ai = 0; ai < 2; ++ai) _Pragma("unroll") for (int m = 0; m < 4; ++m) if (ai == 0 || !hf)
; #define PK8(v0, v1) ({ const u32x2 h0_ = pk4(v0), h1_ = pk4(v1); (u32x4){h0_.x, h0_.y, h1_.x, h1_.y}; })
; #define LOAD_COLP_RS(rsc, ssqp, invn) f32x4 rsc[2][2]; COLS4 rsc[bj][n] = *(const f32x4*)((ssqp) + colp + bj * HALF + n * 4); \
;         COLS4 rsc[bj][n] = (f32x4){rstd_of(rsc[bj][n][0], invn), rstd_of(rsc[bj][n][1], invn), rstd_of(rsc[bj][n][2], invn), rstd_of(rsc[bj][n][3], invn)}
;     DI void operator()(const Acc& acc, const Unit& u, int wr, int wc, int fr, int fq) const {
;     ...
;                 LOAD_COLP_RS(rsc, SSQ(5), 1.f / 512.f);
;                 ROWS8 { const int r = row0 + ai * HALF + m * 16; bf16_t* dst = WSB(OFF_VT2) + (size_t)r * 8192 + colp;
; #pragma unroll
;                     for (int bj = 0; bj < 2; ++bj) *(u32x4*)(dst + bj * HALF) = PK8(acc[ai][bj][m][0] * rsc[bj][0], acc[ai][bj][m][1] * rsc[bj][1]); }
.LBB0_1003:
	v_or_b32_e32 v160, 16, v156
	v_or_b32_e32 v162, 32, v156
	v_or_b32_e32 v158, 48, v156
	s_andn2_b64 vcc, exec, s[52:53]
	v_ashrrev_i32_e32 v157, 31, v156
	v_ashrrev_i32_e32 v161, 31, v160
	v_ashrrev_i32_e32 v163, 31, v162
	v_ashrrev_i32_e32 v159, 31, v158
	s_cbranch_vccnz .LBB0_1005
	v_ashrrev_i32_e32 v165, 31, v164
	v_lshl_add_u64 v[174:175], v[164:165], 2, s[18:19]
	global_load_dwordx4 v[166:169], v[174:175], off
	global_load_dwordx4 v[170:173], v[174:175], off offset:16
	global_load_dwordx4 v[186:189], v[174:175], off offset:512
	global_load_dwordx4 v[190:193], v[174:175], off offset:528
	v_lshlrev_b64 v[174:175], 14, v[156:157]
	v_lshlrev_b64 v[194:195], 14, v[160:161]
	v_lshlrev_b64 v[196:197], 14, v[162:163]
	v_lshl_add_u64 v[174:175], s[26:27], 0, v[174:175]
	v_lshlrev_b64 v[206:207], 1, v[164:165]
	v_lshl_add_u64 v[194:195], s[26:27], 0, v[194:195]
	v_lshl_add_u64 v[196:197], s[26:27], 0, v[196:197]
	v_lshl_add_u64 v[164:165], v[174:175], 0, v[206:207]
	v_lshl_add_u64 v[174:175], v[194:195], 0, v[206:207]
	v_lshl_add_u64 v[208:209], v[196:197], 0, v[206:207]
	s_mov_b64 s[50:51], 0
	s_waitcnt vmcnt(0)
	v_fmamk_f32 v136, v166, 0x3b000000, v185
	v_fmamk_f32 v166, v167, 0x3b000000, v185
	v_fmamk_f32 v167, v168, 0x3b000000, v185
	v_fmamk_f32 v168, v169, 0x3b000000, v185
	v_fmamk_f32 v169, v170, 0x3b000000, v185
	v_fmamk_f32 v170, v171, 0x3b000000, v185
	v_fmamk_f32 v171, v172, 0x3b000000, v185
	v_fmamk_f32 v172, v173, 0x3b000000, v185
	v_fmamk_f32 v173, v186, 0x3b000000, v185
	v_fmamk_f32 v176, v187, 0x3b000000, v185
	v_fmamk_f32 v178, v188, 0x3b000000, v185
	v_fmamk_f32 v180, v189, 0x3b000000, v185
	v_fmamk_f32 v186, v190, 0x3b000000, v185
	v_fmamk_f32 v187, v191, 0x3b000000, v185
	v_fmamk_f32 v188, v192, 0x3b000000, v185
	v_fmamk_f32 v189, v193, 0x3b000000, v185
	v_rsq_f32_e32 v210, v136
	v_rsq_f32_e32 v211, v166
	v_rsq_f32_e32 v212, v167
	v_rsq_f32_e32 v213, v168
	v_rsq_f32_e32 v214, v169
	v_rsq_f32_e32 v215, v170
	v_rsq_f32_e32 v216, v171
	v_rsq_f32_e32 v217, v172
	v_rsq_f32_e32 v168, v173
	v_rsq_f32_e32 v169, v176
	v_rsq_f32_e32 v172, v178
	v_rsq_f32_e32 v173, v180
	v_rsq_f32_e32 v166, v186
	v_rsq_f32_e32 v167, v187
	v_rsq_f32_e32 v170, v188
	v_rsq_f32_e32 v171, v189
	v_mul_f32_e32 v188, v126, v212
	v_mul_f32_e32 v189, v127, v213
	v_mul_f32_e32 v186, v124, v210
	v_mul_f32_e32 v187, v125, v211
	v_mul_f32_e32 v190, v122, v216
	v_mul_f32_e32 v191, v123, v217
	v_mul_f32_e32 v192, v120, v214
	v_mul_f32_e32 v193, v121, v215
	v_mul_f32_e32 v194, v62, v172
	v_mul_f32_e32 v195, v63, v173
	v_mul_f32_e32 v196, v60, v168
	v_mul_f32_e32 v197, v61, v169
	v_mul_f32_e32 v198, v58, v170
	v_mul_f32_e32 v199, v59, v171
	v_mul_f32_e32 v200, v56, v166
	v_mul_f32_e32 v201, v57, v167
	v_mul_f32_e32 v202, v118, v212
	v_mul_f32_e32 v203, v119, v213
	v_mul_f32_e32 v204, v116, v210
	v_mul_f32_e32 v205, v117, v211
	v_mul_f32_e32 v218, v114, v216
	v_mul_f32_e32 v219, v115, v217
	v_mul_f32_e32 v220, v112, v214
	v_mul_f32_e32 v221, v113, v215
	v_mul_f32_e32 v222, v54, v172
	v_mul_f32_e32 v223, v55, v173
	v_mul_f32_e32 v224, v52, v168
	v_mul_f32_e32 v225, v53, v169
	v_mul_f32_e32 v226, v50, v170
	v_mul_f32_e32 v227, v51, v171
	v_mul_f32_e32 v228, v48, v166
	v_mul_f32_e32 v229, v49, v167
	v_cvt_pk_bf16_f32 v186, v186, v187
	v_cvt_pk_bf16_f32 v187, v188, v189
	v_cvt_pk_bf16_f32 v188, v192, v193
	v_cvt_pk_bf16_f32 v189, v190, v191
	v_cvt_pk_bf16_f32 v190, v196, v197
	v_cvt_pk_bf16_f32 v191, v194, v195
	v_cvt_pk_bf16_f32 v192, v200, v201
	v_cvt_pk_bf16_f32 v193, v198, v199
	v_cvt_pk_bf16_f32 v194, v204, v205
	v_cvt_pk_bf16_f32 v195, v202, v203
	v_cvt_pk_bf16_f32 v196, v220, v221
	v_cvt_pk_bf16_f32 v197, v218, v219
	v_cvt_pk_bf16_f32 v198, v224, v225
	v_cvt_pk_bf16_f32 v199, v222, v223
	v_cvt_pk_bf16_f32 v200, v228, v229
	v_cvt_pk_bf16_f32 v201, v226, v227
	global_store_dwordx4 v[164:165], v[186:189], off
	global_store_dwordx4 v[164:165], v[190:193], off offset:256
	global_store_dwordx4 v[174:175], v[194:197], off
	global_store_dwordx4 v[174:175], v[198:201], off offset:256
	v_mul_f32_e32 v174, v46, v172
	v_mul_f32_e32 v175, v47, v173
	v_mul_f32_e32 v186, v44, v168
	v_mul_f32_e32 v187, v45, v169
	v_mul_f32_e32 v188, v40, v166
	v_mul_f32_e32 v189, v41, v167
	v_cvt_pk_bf16_f32 v186, v186, v187
	v_cvt_pk_bf16_f32 v187, v174, v175
	v_mul_f32_e32 v174, v42, v170
	v_mul_f32_e32 v175, v43, v171
	v_cvt_pk_bf16_f32 v188, v188, v189
	v_cvt_pk_bf16_f32 v189, v174, v175
	global_store_dwordx4 v[208:209], v[186:189], off offset:256
	v_lshlrev_b64 v[174:175], 14, v[158:159]
	v_lshl_add_u64 v[174:175], s[26:27], 0, v[174:175]
	v_mul_f32_e32 v188, v102, v212
	v_mul_f32_e32 v189, v103, v213
	v_mul_f32_e32 v186, v100, v210
	v_mul_f32_e32 v187, v101, v211
	v_mul_f32_e32 v190, v98, v216
	v_mul_f32_e32 v191, v99, v217
	v_cvt_pk_bf16_f32 v186, v186, v187
	v_cvt_pk_bf16_f32 v187, v188, v189
	v_mul_f32_e32 v188, v96, v214
	v_mul_f32_e32 v189, v97, v215
	v_lshl_add_u64 v[174:175], v[174:175], 0, v[206:207]
	v_cvt_pk_bf16_f32 v188, v188, v189
	v_cvt_pk_bf16_f32 v189, v190, v191
	global_store_dwordx4 v[174:175], v[186:189], off
	v_mul_f32_e32 v190, v34, v170
	v_mul_f32_e32 v191, v35, v171
	v_mul_f32_e32 v230, v110, v212
	v_mul_f32_e32 v231, v111, v213
	v_mul_f32_e32 v188, v38, v172
	v_mul_f32_e32 v189, v39, v173
	v_mul_f32_e32 v186, v36, v168
	v_mul_f32_e32 v187, v37, v169
	v_mul_f32_e32 v232, v108, v210
	v_mul_f32_e32 v233, v109, v211
	v_cvt_pk_bf16_f32 v186, v186, v187
	v_cvt_pk_bf16_f32 v187, v188, v189
	v_mul_f32_e32 v188, v32, v166
	v_mul_f32_e32 v189, v33, v167
	v_mul_f32_e32 v234, v106, v216
	v_mul_f32_e32 v235, v107, v217
	v_cvt_pk_bf16_f32 v188, v188, v189
; #define ROWS8 _Pragma("unroll") for (int ai = 0; ai < 2; ++ai) _Pragma("unroll") for (int m = 0; m < 4; ++m) if (ai == 0 || !hf)
; #define PK8(v0, v1) ({ const u32x2 h0_ = pk4(v0), h1_ = pk4(v1); (u32x4){h0_.x, h0_.y, h1_.x, h1_.y}; })
; #define LOAD_COLP_RS(rsc, ssqp, invn) f32x4 rsc[2][2]; COLS4 rsc[bj][n] = *(const f32x4*)((ssqp) + colp + bj * HALF + n * 4); \
;         COLS4 rsc[bj][n] = (f32x4){rstd_of(rsc[bj][n][0], invn), rstd_of(rsc[bj][n][1], invn), rstd_of(rsc[bj][n][2], invn), rstd_of(rsc[bj][n][3], invn)}
;     DI void operator()(const Acc& acc, const Unit& u, int wr, int wc, int fr, int fq) const {
;     ...
;                 LOAD_COLP_RS(rsc, SSQ(5), 1.f / 512.f);
;                 ROWS8 { const int r = row0 + ai * HALF + m * 16; bf16_t* dst = WSB(OFF_VT2) + (size_t)r * 8192 + colp;
; #pragma unroll
;                     for (int bj = 0; bj < 2; ++bj) *(u32x4*)(dst + bj * HALF) = PK8(acc[ai][bj][m][0] * rsc[bj][0], acc[ai][bj][m][1] * rsc[bj][1]); }
	v_cvt_pk_bf16_f32 v189, v190, v191
	global_store_dwordx4 v[174:175], v[186:189], off offset:256
	v_mul_f32_e32 v190, v90, v216
	v_mul_f32_e32 v191, v91, v217
	v_lshl_add_u64 v[174:175], v[164:165], 0, s[28:29]
	v_mul_f32_e32 v188, v94, v212
	v_mul_f32_e32 v189, v95, v213
	v_mul_f32_e32 v186, v92, v210
	v_mul_f32_e32 v187, v93, v211
	v_mul_f32_e32 v236, v104, v214
	v_mul_f32_e32 v237, v105, v215
	v_cvt_pk_bf16_f32 v186, v186, v187
	v_cvt_pk_bf16_f32 v187, v188, v189
	v_mul_f32_e32 v188, v88, v214
	v_mul_f32_e32 v189, v89, v215
	v_cvt_pk_bf16_f32 v202, v232, v233
	v_cvt_pk_bf16_f32 v188, v188, v189
	v_cvt_pk_bf16_f32 v189, v190, v191
	v_add_co_u32_e32 v190, vcc, s78, v164
	v_cvt_pk_bf16_f32 v203, v230, v231
	s_nop 0
	v_addc_co_u32_e32 v191, vcc, 0, v165, vcc
	global_store_dwordx4 v[190:191], v[186:189], off
	v_mul_f32_e32 v190, v26, v170
	v_mul_f32_e32 v191, v27, v171
	v_cvt_pk_bf16_f32 v204, v236, v237
	v_mul_f32_e32 v188, v30, v172
	v_mul_f32_e32 v189, v31, v173
	v_mul_f32_e32 v186, v28, v168
	v_mul_f32_e32 v187, v29, v169
	v_cvt_pk_bf16_f32 v205, v234, v235
	v_cvt_pk_bf16_f32 v186, v186, v187
	v_cvt_pk_bf16_f32 v187, v188, v189
	v_mul_f32_e32 v188, v24, v166
	v_mul_f32_e32 v189, v25, v167
	global_store_dwordx4 v[208:209], v[202:205], off
	v_cvt_pk_bf16_f32 v188, v188, v189
	v_cvt_pk_bf16_f32 v189, v190, v191
	global_store_dwordx4 v[174:175], v[186:189], off offset:256
	v_mul_f32_e32 v190, v82, v216
	v_mul_f32_e32 v191, v83, v217
	v_lshl_add_u64 v[174:175], v[164:165], 0, s[30:31]
	v_mul_f32_e32 v188, v86, v212
	v_mul_f32_e32 v189, v87, v213
	v_mul_f32_e32 v186, v84, v210
	v_mul_f32_e32 v187, v85, v211
	s_nop 0
	v_cvt_pk_bf16_f32 v186, v186, v187
	v_cvt_pk_bf16_f32 v187, v188, v189
	v_mul_f32_e32 v188, v80, v214
	v_mul_f32_e32 v189, v81, v215
	s_nop 0
	v_cvt_pk_bf16_f32 v188, v188, v189
	v_cvt_pk_bf16_f32 v189, v190, v191
	v_add_co_u32_e32 v190, vcc, s79, v164
	s_nop 1
	v_addc_co_u32_e32 v191, vcc, 0, v165, vcc
	global_store_dwordx4 v[190:191], v[186:189], off
	v_mul_f32_e32 v190, v18, v170
	v_mul_f32_e32 v191, v19, v171
	s_nop 0
	v_mul_f32_e32 v188, v22, v172
	v_mul_f32_e32 v189, v23, v173
	v_mul_f32_e32 v186, v20, v168
	v_mul_f32_e32 v187, v21, v169
	s_nop 0
	v_cvt_pk_bf16_f32 v186, v186, v187
	v_cvt_pk_bf16_f32 v187, v188, v189
	v_mul_f32_e32 v188, v16, v166
	v_mul_f32_e32 v189, v17, v167
	s_nop 0
	v_cvt_pk_bf16_f32 v188, v188, v189
	v_cvt_pk_bf16_f32 v189, v190, v191
	global_store_dwordx4 v[174:175], v[186:189], off offset:256
	v_mul_f32_e32 v190, v74, v216
	v_mul_f32_e32 v191, v75, v217
	v_lshl_add_u64 v[174:175], v[164:165], 0, s[36:37]
	v_mul_f32_e32 v188, v78, v212
	v_mul_f32_e32 v189, v79, v213
	v_mul_f32_e32 v186, v76, v210
	v_mul_f32_e32 v187, v77, v211
	s_nop 0
	v_cvt_pk_bf16_f32 v186, v186, v187
	v_cvt_pk_bf16_f32 v187, v188, v189
	v_mul_f32_e32 v188, v72, v214
	v_mul_f32_e32 v189, v73, v215
	s_nop 0
	v_cvt_pk_bf16_f32 v188, v188, v189
	v_cvt_pk_bf16_f32 v189, v190, v191
	v_add_co_u32_e32 v190, vcc, s80, v164
	s_nop 1
	v_addc_co_u32_e32 v191, vcc, 0, v165, vcc
	global_store_dwordx4 v[190:191], v[186:189], off
	v_mul_f32_e32 v190, v10, v170
	v_mul_f32_e32 v191, v11, v171
	s_nop 0
	v_mul_f32_e32 v188, v14, v172
	v_mul_f32_e32 v189, v15, v173
	v_mul_f32_e32 v186, v12, v168
	v_mul_f32_e32 v187, v13, v169
	v_mul_f32_e32 v172, v6, v172
	v_mul_f32_e32 v173, v7, v173
	v_cvt_pk_bf16_f32 v186, v186, v187
	v_cvt_pk_bf16_f32 v187, v188, v189
	v_mul_f32_e32 v188, v8, v166
	v_mul_f32_e32 v189, v9, v167
	v_mul_f32_e32 v166, v0, v166
	v_mul_f32_e32 v167, v1, v167
	v_cvt_pk_bf16_f32 v188, v188, v189
	v_cvt_pk_bf16_f32 v189, v190, v191
	global_store_dwordx4 v[174:175], v[186:189], off offset:256
	v_lshl_add_u64 v[174:175], v[164:165], 0, s[38:39]
	v_mul_f32_e32 v190, v66, v216
	v_mul_f32_e32 v191, v67, v217
	v_mul_f32_e32 v188, v70, v212
	v_mul_f32_e32 v189, v71, v213
	v_mul_f32_e32 v186, v68, v210
	v_mul_f32_e32 v187, v69, v211
	v_add_co_u32_e32 v164, vcc, s81, v164
	v_cvt_pk_bf16_f32 v186, v186, v187
	v_cvt_pk_bf16_f32 v187, v188, v189
	v_mul_f32_e32 v188, v64, v214
	v_mul_f32_e32 v189, v65, v215
	v_addc_co_u32_e32 v165, vcc, 0, v165, vcc
	v_cvt_pk_bf16_f32 v188, v188, v189
	v_cvt_pk_bf16_f32 v189, v190, v191
	global_store_dwordx4 v[164:165], v[186:189], off
	v_mul_f32_e32 v164, v4, v168
	v_mul_f32_e32 v165, v5, v169
	v_mul_f32_e32 v168, v2, v170
	v_mul_f32_e32 v169, v3, v171
	v_cvt_pk_bf16_f32 v164, v164, v165
	v_cvt_pk_bf16_f32 v165, v172, v173
	v_cvt_pk_bf16_f32 v166, v166, v167
	v_cvt_pk_bf16_f32 v167, v168, v169
	global_store_dwordx4 v[174:175], v[164:167], off offset:256
; #define ROWS8 _Pragma("unroll") for (int ai = 0; ai < 2; ++ai) _Pragma("unroll") for (int m = 0; m < 4; ++m) if (ai == 0 || !hf)
; #define LOAD_ROW_RS(rsv, ssqp, invn) float rsv[2][4]; ROWS8_ALL rsv[ai][m] = (ssqp)[row0 + ai * HALF + m * 16]; ROWS8_ALL rsv[ai][m] = rstd_of(rsv[ai][m], invn)
; #define PK8(v0, v1) ({ const u32x2 h0_ = pk4(v0), h1_ = pk4(v1); (u32x4){h0_.x, h0_.y, h1_.x, h1_.y}; })
;     DI void operator()(const Acc& acc, const Unit& u, int wr, int wc, int fr, int fq) const {
;     ...
;             if (u.kind == K_Q) {
;                 LOAD_ROW_RS(rsv, SSQ(4), 1.f / 512.f);
;                 const float* cs = WSF(OFF_CS);
; #pragma unroll
;                 for (int bj = 0; bj < 2; ++bj) {
;                     const int g32 = u.pn * 8 + bj * 4 + wc, g64 = g32 >> 1; const bool rope = (g64 % 3) == 2;
;                     if (!rope) {
;                         ROWS8 { const int r = row0 + ai * HALF + m * 16; const float rs = rsv[ai][m] * QSCALE;
;                             bf16_t* dst = WSB(OFF_Q) + (size_t)r * 3072 + g32 * 32 + 8 * fq; *(u32x4*)(dst) = PK8(acc[ai][bj][m][0] * rs, acc[ai][bj][m][1] * rs); }
.LBB0_1005:
	s_andn2_b64 vcc, exec, s[50:51]
	s_cbranch_vccnz .LBB0_978
	v_lshl_add_u64 v[164:165], v[156:157], 2, s[22:23]
	v_lshl_add_u64 v[166:167], v[160:161], 2, s[22:23]
	v_lshl_add_u64 v[168:169], v[162:163], 2, s[22:23]
	v_lshl_add_u64 v[170:171], v[158:159], 2, s[22:23]
	global_load_dword v136, v[164:165], off
	s_nop 0
	global_load_dword v166, v[166:167], off
	s_nop 0
	global_load_dword v167, v[168:169], off
	s_nop 0
	global_load_dword v168, v[170:171], off
	global_load_dword v169, v[164:165], off offset:512
	s_nop 0
	global_load_dword v170, v[164:165], off offset:576
	global_load_dword v171, v[164:165], off offset:640
	s_nop 0
	global_load_dword v164, v[164:165], off offset:704
	s_lshl_b32 s41, s84, 3
	s_or_b32 s41, s41, s71
	s_ashr_i32 s43, s41, 1
	s_mul_hi_i32 s52, s43, 0x55555556
	s_lshr_b32 s53, s52, 31
	s_add_i32 s52, s52, s53
	s_mul_i32 s52, s52, 3
	s_sub_i32 s52, s43, s52
	v_add_u32_e32 v161, 0x80, v156
	v_add_u32_e32 v163, 0x90, v156
	v_add_u32_e32 v159, 0xa0, v156
	v_add_u32_e32 v157, 0xb0, v156
	s_mov_b64 s[50:51], -1
	s_cmp_eq_u32 s52, 2
	s_waitcnt vmcnt(0)
	v_fmamk_f32 v136, v136, 0x3b000000, v185
	v_fmamk_f32 v165, v166, 0x3b000000, v185
	v_fmamk_f32 v166, v167, 0x3b000000, v185
	v_fmamk_f32 v167, v168, 0x3b000000, v185
	v_fmamk_f32 v168, v169, 0x3b000000, v185
	v_fmamk_f32 v169, v170, 0x3b000000, v185
	v_fmamk_f32 v170, v171, 0x3b000000, v185
	v_fmamk_f32 v164, v164, 0x3b000000, v185
	v_rsq_f32_e32 v136, v136
	v_rsq_f32_e32 v165, v165
	v_rsq_f32_e32 v166, v166
	v_rsq_f32_e32 v167, v167
	v_rsq_f32_e32 v168, v168
	v_rsq_f32_e32 v169, v169
	v_rsq_f32_e32 v171, v170
	v_rsq_f32_e32 v164, v164
	v_mul_f32_e32 v180, 0x3dd53b94, v136
	v_mul_f32_e32 v178, 0x3dd53b94, v165
	v_mul_f32_e32 v176, 0x3dd53b94, v166
	v_mul_f32_e32 v172, 0x3dd53b94, v167
	v_mul_f32_e32 v170, 0x3dd53b94, v168
	v_mul_f32_e32 v168, 0x3dd53b94, v169
	v_mul_f32_e32 v166, 0x3dd53b94, v171
	v_mul_f32_e32 v164, 0x3dd53b94, v164
	s_cbranch_scc1 .LBB0_1008
	s_lshl_b32 s50, s41, 5
	s_ashr_i32 s51, s50, 31
	v_mov_b64_e32 v[174:175], s[24:25]
	v_mad_i64_i32 v[186:187], s[52:53], v156, s82, v[174:175]
	s_lshl_b64 s[50:51], s[50:51], 1
	v_lshl_add_u64 v[186:187], v[186:187], 0, s[50:51]
	v_lshl_add_u64 v[190:191], v[186:187], 0, v[154:155]
	v_mul_f32_e32 v188, v126, v180
	v_mul_f32_e32 v189, v127, v180
	v_mul_f32_e32 v186, v124, v180
	v_mul_f32_e32 v187, v125, v180
	v_mul_f32_e32 v192, v122, v180
	v_mul_f32_e32 v193, v123, v180
	v_cvt_pk_bf16_f32 v186, v186, v187
	v_cvt_pk_bf16_f32 v187, v188, v189
	v_mul_f32_e32 v188, v120, v180
	v_mul_f32_e32 v189, v121, v180
	s_nop 0
	v_cvt_pk_bf16_f32 v188, v188, v189
	v_cvt_pk_bf16_f32 v189, v192, v193
	global_store_dwordx4 v[190:191], v[186:189], off
	v_mul_f32_e32 v192, v114, v178
	v_mul_f32_e32 v193, v115, v178
	s_nop 0
	v_mad_i64_i32 v[186:187], s[52:53], v160, s82, v[174:175]
	v_lshl_add_u64 v[186:187], v[186:187], 0, s[50:51]
	v_lshl_add_u64 v[190:191], v[186:187], 0, v[154:155]
	v_mul_f32_e32 v188, v118, v178
	v_mul_f32_e32 v189, v119, v178
	v_mul_f32_e32 v186, v116, v178
	v_mul_f32_e32 v187, v117, v178
	s_nop 0
	v_cvt_pk_bf16_f32 v186, v186, v187
	v_cvt_pk_bf16_f32 v187, v188, v189
	v_mul_f32_e32 v188, v112, v178
	v_mul_f32_e32 v189, v113, v178
	s_nop 0
	v_cvt_pk_bf16_f32 v188, v188, v189
	v_cvt_pk_bf16_f32 v189, v192, v193
	global_store_dwordx4 v[190:191], v[186:189], off
	v_mul_f32_e32 v192, v106, v176
	v_mul_f32_e32 v193, v107, v176
	s_nop 0
	v_mad_i64_i32 v[186:187], s[52:53], v162, s82, v[174:175]
	v_lshl_add_u64 v[186:187], v[186:187], 0, s[50:51]
	v_lshl_add_u64 v[190:191], v[186:187], 0, v[154:155]
	v_mul_f32_e32 v188, v110, v176
	v_mul_f32_e32 v189, v111, v176
	v_mul_f32_e32 v186, v108, v176
	v_mul_f32_e32 v187, v109, v176
	s_nop 0
	v_cvt_pk_bf16_f32 v186, v186, v187
	v_cvt_pk_bf16_f32 v187, v188, v189
	v_mul_f32_e32 v188, v104, v176
	v_mul_f32_e32 v189, v105, v176
	s_nop 0
	v_cvt_pk_bf16_f32 v188, v188, v189
	v_cvt_pk_bf16_f32 v189, v192, v193
	global_store_dwordx4 v[190:191], v[186:189], off
	v_mul_f32_e32 v192, v98, v172
	v_mul_f32_e32 v193, v99, v172
	s_nop 0
	v_mad_i64_i32 v[186:187], s[52:53], v158, s82, v[174:175]
	v_lshl_add_u64 v[186:187], v[186:187], 0, s[50:51]
	v_lshl_add_u64 v[190:191], v[186:187], 0, v[154:155]
	v_mul_f32_e32 v188, v102, v172
	v_mul_f32_e32 v189, v103, v172
	v_mul_f32_e32 v186, v100, v172
	v_mul_f32_e32 v187, v101, v172
	s_nop 0
	v_cvt_pk_bf16_f32 v186, v186, v187
	v_cvt_pk_bf16_f32 v187, v188, v189
	v_mul_f32_e32 v188, v96, v172
	v_mul_f32_e32 v189, v97, v172
	s_nop 0
	v_cvt_pk_bf16_f32 v188, v188, v189
	v_cvt_pk_bf16_f32 v189, v192, v193
	global_store_dwordx4 v[190:191], v[186:189], off
	v_mul_f32_e32 v192, v90, v170
	v_mul_f32_e32 v193, v91, v170
	s_nop 0
	v_mad_i64_i32 v[186:187], s[52:53], v161, s82, v[174:175]
	v_lshl_add_u64 v[186:187], v[186:187], 0, s[50:51]
	v_lshl_add_u64 v[190:191], v[186:187], 0, v[154:155]
	v_mul_f32_e32 v188, v94, v170
	v_mul_f32_e32 v189, v95, v170
	v_mul_f32_e32 v186, v92, v170
	v_mul_f32_e32 v187, v93, v170
	s_nop 0
	v_cvt_pk_bf16_f32 v186, v186, v187
	v_cvt_pk_bf16_f32 v187, v188, v189
	v_mul_f32_e32 v188, v88, v170
	v_mul_f32_e32 v189, v89, v170
	s_nop 0
	v_cvt_pk_bf16_f32 v188, v188, v189
	v_cvt_pk_bf16_f32 v189, v192, v193
	global_store_dwordx4 v[190:191], v[186:189], off
	v_mul_f32_e32 v192, v82, v168
	v_mul_f32_e32 v193, v83, v168
	s_nop 0
	v_mad_i64_i32 v[186:187], s[52:53], v163, s82, v[174:175]
	v_lshl_add_u64 v[186:187], v[186:187], 0, s[50:51]
	v_lshl_add_u64 v[190:191], v[186:187], 0, v[154:155]
	v_mul_f32_e32 v188, v86, v168
	v_mul_f32_e32 v189, v87, v168
	v_mul_f32_e32 v186, v84, v168
	v_mul_f32_e32 v187, v85, v168
	s_nop 0
; #define ROWS8 _Pragma("unroll") for (int ai = 0; ai < 2; ++ai) _Pragma("unroll") for (int m = 0; m < 4; ++m) if (ai == 0 || !hf)
; #define PK8(v0, v1) ({ const u32x2 h0_ = pk4(v0), h1_ = pk4(v1); (u32x4){h0_.x, h0_.y, h1_.x, h1_.y}; })
;     DI void operator()(const Acc& acc, const Unit& u, int wr, int wc, int fr, int fq) const {
;     ...
;                     const int g32 = u.pn * 8 + bj * 4 + wc, g64 = g32 >> 1; const bool rope = (g64 % 3) == 2;
;                     if (!rope) {
;                         ROWS8 { const int r = row0 + ai * HALF + m * 16; const float rs = rsv[ai][m] * QSCALE;
;                             bf16_t* dst = WSB(OFF_Q) + (size_t)r * 3072 + g32 * 32 + 8 * fq; *(u32x4*)(dst) = PK8(acc[ai][bj][m][0] * rs, acc[ai][bj][m][1] * rs); }
;                     } else {
;                         const int j0 = 16 * (g32 & 1) + 4 * fq;
; #pragma unroll
;                         for (int ai = 0; ai < 2; ++ai) if (ai == 0 || !hf) {
;                             f32x4 c4[4], s4[4];
; #pragma unroll
;                             for (int m = 0; m < 4; ++m) { const int pos = (row0 + ai * HALF + m * 16) & (SEQ - 1); c4[m] = *(const f32x4*)(cs + pos * 32 + j0); s4[m] = *(const f32x4*)(cs + 4096 * 32 + pos * 32 + j0); }
	v_cvt_pk_bf16_f32 v186, v186, v187
	v_cvt_pk_bf16_f32 v187, v188, v189
	v_mul_f32_e32 v188, v80, v168
	v_mul_f32_e32 v189, v81, v168
	s_nop 0
	v_cvt_pk_bf16_f32 v188, v188, v189
	v_cvt_pk_bf16_f32 v189, v192, v193
	global_store_dwordx4 v[190:191], v[186:189], off
	v_mul_f32_e32 v192, v74, v166
	v_mul_f32_e32 v193, v75, v166
	s_nop 0
	v_mad_i64_i32 v[186:187], s[52:53], v159, s82, v[174:175]
	v_lshl_add_u64 v[186:187], v[186:187], 0, s[50:51]
	v_lshl_add_u64 v[190:191], v[186:187], 0, v[154:155]
	v_mul_f32_e32 v188, v78, v166
	v_mul_f32_e32 v189, v79, v166
	v_mul_f32_e32 v186, v76, v166
	v_mul_f32_e32 v187, v77, v166
	v_mad_i64_i32 v[174:175], s[52:53], v157, s82, v[174:175]
	v_cvt_pk_bf16_f32 v186, v186, v187
	v_cvt_pk_bf16_f32 v187, v188, v189
	v_mul_f32_e32 v188, v72, v166
	v_mul_f32_e32 v189, v73, v166
	v_lshl_add_u64 v[174:175], v[174:175], 0, s[50:51]
	v_cvt_pk_bf16_f32 v188, v188, v189
	v_cvt_pk_bf16_f32 v189, v192, v193
	global_store_dwordx4 v[190:191], v[186:189], off
	v_mul_f32_e32 v190, v66, v164
	v_mul_f32_e32 v191, v67, v164
	v_lshl_add_u64 v[174:175], v[174:175], 0, v[154:155]
	v_mul_f32_e32 v188, v70, v164
	v_mul_f32_e32 v189, v71, v164
	v_mul_f32_e32 v186, v68, v164
	v_mul_f32_e32 v187, v69, v164
	s_mov_b64 s[50:51], 0
	v_cvt_pk_bf16_f32 v186, v186, v187
	v_cvt_pk_bf16_f32 v187, v188, v189
	v_mul_f32_e32 v188, v64, v164
	v_mul_f32_e32 v189, v65, v164
	s_nop 0
	v_cvt_pk_bf16_f32 v188, v188, v189
	v_cvt_pk_bf16_f32 v189, v190, v191
	global_store_dwordx4 v[174:175], v[186:189], off
.LBB0_1008:
	v_lshlrev_b32_e32 v136, 5, v156
	v_lshlrev_b32_e32 v165, 2, v136
	v_add_u32_e32 v167, 0x1000, v136
	s_andn2_b64 vcc, exec, s[50:51]
	v_lshlrev_b64 v[174:175], 1, v[138:139]
	v_and_b32_e32 v136, 0x7e780, v165
	v_and_b32_e32 v165, 0x1f9e0, v167
	s_cbranch_vccnz .LBB0_1010
	v_lshl_add_u64 v[190:191], v[142:143], 0, v[136:137]
	v_or_b32_e32 v206, 0x1000, v136
	v_mov_b32_e32 v207, v137
	global_load_dwordx4 v[186:189], v[190:191], off
	s_nop 0
	global_load_dwordx4 v[190:193], v[190:191], off offset:2048
	v_lshl_add_u64 v[198:199], v[140:141], 0, v[136:137]
	v_lshl_add_u64 v[202:203], v[142:143], 0, v[206:207]
	global_load_dwordx4 v[194:197], v[198:199], off
	s_nop 0
	global_load_dwordx4 v[198:201], v[198:199], off offset:2048
	v_lshl_add_u64 v[206:207], v[140:141], 0, v[206:207]
	global_load_dwordx4 v[202:205], v[202:203], off
	v_or_b32_e32 v210, 0x1800, v136
	global_load_dwordx4 v[206:209], v[206:207], off
	v_mov_b32_e32 v211, v137
	v_lshl_add_u64 v[214:215], v[140:141], 0, v[210:211]
	v_lshl_add_u64 v[210:211], v[142:143], 0, v[210:211]
	global_load_dwordx4 v[210:213], v[210:211], off
	s_nop 0
	global_load_dwordx4 v[214:217], v[214:215], off
	s_lshl_b32 s50, s43, 6
	v_mul_f32_e32 v126, v126, v180
	v_mul_f32_e32 v127, v127, v180
	v_mul_f32_e32 v122, v122, v180
	v_mul_f32_e32 v123, v123, v180
	v_mul_f32_e32 v116, v116, v178
	v_mul_f32_e32 v117, v117, v178
	v_mul_f32_e32 v112, v112, v178
	v_mul_f32_e32 v113, v113, v178
	v_mul_f32_e32 v124, v124, v180
	v_mul_f32_e32 v125, v125, v180
	v_mul_f32_e32 v218, v120, v180
	v_mul_f32_e32 v219, v121, v180
	v_mov_b64_e32 v[120:121], s[24:25]
	v_mul_f32_e32 v118, v118, v178
	v_mul_f32_e32 v119, v119, v178
	v_mul_f32_e32 v114, v114, v178
	v_mul_f32_e32 v115, v115, v178
	v_mul_f32_e32 v106, v106, v176
	v_mul_f32_e32 v107, v107, v176
	v_mul_f32_e32 v104, v104, v176
	v_mul_f32_e32 v105, v105, v176
	s_ashr_i32 s51, s50, 31
	v_mul_f32_e32 v110, v110, v176
	v_mul_f32_e32 v111, v111, v176
	v_mul_f32_e32 v108, v108, v176
	v_mul_f32_e32 v109, v109, v176
	v_mad_i64_i32 v[220:221], s[52:53], v156, s82, v[120:121]
	v_mad_i64_i32 v[224:225], s[52:53], v162, s82, v[120:121]
	s_lshl_b64 s[50:51], s[50:51], 1
	v_mad_i64_i32 v[222:223], s[52:53], v160, s82, v[120:121]
	v_lshl_add_u64 v[220:221], v[220:221], 0, s[50:51]
	v_lshl_add_u64 v[224:225], v[224:225], 0, s[50:51]
	v_lshl_add_u64 v[222:223], v[222:223], 0, s[50:51]
	v_lshl_add_u64 v[220:221], v[220:221], 0, v[174:175]
	v_lshl_add_u64 v[224:225], v[224:225], 0, v[174:175]
	v_mul_f32_e32 v98, v98, v172
	v_mul_f32_e32 v99, v99, v172
	v_mul_f32_e32 v96, v96, v172
	v_mul_f32_e32 v97, v97, v172
	v_lshl_add_u64 v[222:223], v[222:223], 0, v[174:175]
	v_mul_f32_e32 v102, v102, v172
	v_mul_f32_e32 v103, v103, v172
	v_mul_f32_e32 v100, v100, v172
	v_mul_f32_e32 v101, v101, v172
	v_mul_f32_e32 v90, v90, v170
	v_mul_f32_e32 v91, v91, v170
	v_mul_f32_e32 v88, v88, v170
	v_mul_f32_e32 v89, v89, v170
	v_mul_f32_e32 v82, v82, v168
	v_mul_f32_e32 v83, v83, v168
	v_mul_f32_e32 v80, v80, v168
	v_mul_f32_e32 v81, v81, v168
	v_mul_f32_e32 v94, v94, v170
	v_mul_f32_e32 v95, v95, v170
	v_mul_f32_e32 v92, v92, v170
	v_mul_f32_e32 v93, v93, v170
	v_mul_f32_e32 v86, v86, v168
	v_mul_f32_e32 v87, v87, v168
	v_mul_f32_e32 v84, v84, v168
	v_mul_f32_e32 v85, v85, v168
	v_mul_f32_e32 v74, v74, v166
	v_mul_f32_e32 v75, v75, v166
	v_mul_f32_e32 v72, v72, v166
	v_mul_f32_e32 v73, v73, v166
	v_mul_f32_e32 v78, v78, v166
	v_mul_f32_e32 v79, v79, v166
	v_mul_f32_e32 v76, v76, v166
	v_mul_f32_e32 v77, v77, v166
	v_mul_f32_e32 v66, v66, v164
	v_mul_f32_e32 v67, v67, v164
	v_mul_f32_e32 v64, v64, v164
	v_mul_f32_e32 v65, v65, v164
	v_mul_f32_e32 v70, v70, v164
	v_mul_f32_e32 v71, v71, v164
	v_mul_f32_e32 v68, v68, v164
	v_mul_f32_e32 v69, v69, v164
	s_waitcnt vmcnt(0)
; DI u32x2 pk4(f32x4 v) { u32x2 r; r.x = pk2(v[0], v[1]); r.y = pk2(v[2], v[3]); return r; }
;     DI void operator()(const Acc& acc, const Unit& u, int wr, int wc, int fr, int fq) const {
;     ...
;                         for (int ai = 0; ai < 2; ++ai) if (ai == 0 || !hf) {
;                             f32x4 c4[4], s4[4];
; #pragma unroll
;                             for (int m = 0; m < 4; ++m) { const int pos = (row0 + ai * HALF + m * 16) & (SEQ - 1); c4[m] = *(const f32x4*)(cs + pos * 32 + j0); s4[m] = *(const f32x4*)(cs + 4096 * 32 + pos * 32 + j0); }
; #pragma unroll
;                             for (int m = 0; m < 4; ++m) { const int r = row0 + ai * HALF + m * 16; const float rs = rsv[ai][m] * QSCALE;
;                                 const f32x4 v0 = acc[ai][bj][m][0] * rs, v1 = acc[ai][bj][m][1] * rs;
;                                 bf16_t* dst = WSB(OFF_Q) + (size_t)r * 3072 + g64 * 64 + j0;
;                                 *(u32x2*)(dst) = pk4(v0 * c4[m] - v1 * s4[m]); *(u32x2*)(dst + 32) = pk4(v1 * c4[m] + v0 * s4[m]); }
	v_mul_f32_e32 v226, v122, v188
	v_mul_f32_e32 v227, v123, v189
	v_mul_f32_e32 v188, v126, v188
	v_mul_f32_e32 v189, v127, v189
	v_mul_f32_e32 v232, v112, v190
	v_mul_f32_e32 v233, v113, v191
	v_mul_f32_e32 v190, v116, v190
	v_mul_f32_e32 v191, v117, v191
	v_mul_f32_e32 v228, v218, v186
	v_mul_f32_e32 v229, v219, v187
	v_mul_f32_e32 v186, v124, v186
	v_mul_f32_e32 v187, v125, v187
	v_mul_f32_e32 v230, v114, v192
	v_mul_f32_e32 v231, v115, v193
	v_mul_f32_e32 v192, v118, v192
	v_mul_f32_e32 v193, v119, v193
	v_fma_f32 v122, v122, v196, v188
	v_fma_f32 v123, v123, v197, v189
	v_fma_f32 v112, v112, v198, v190
	v_fma_f32 v113, v113, v199, v191
	v_mul_f32_e32 v188, v106, v204
	v_mul_f32_e32 v189, v107, v205
	v_mul_f32_e32 v190, v104, v202
	v_mul_f32_e32 v191, v105, v203
	v_fma_f32 v126, v126, v196, -v226
	v_fma_f32 v127, v127, v197, -v227
	v_fma_f32 v124, v124, v194, -v228
	v_fma_f32 v125, v125, v195, -v229
	v_fma_f32 v186, v218, v194, v186
	v_fma_f32 v187, v219, v195, v187
	v_fma_f32 v114, v114, v200, v192
	v_fma_f32 v115, v115, v201, v193
	v_mul_f32_e32 v192, v110, v204
	v_mul_f32_e32 v193, v111, v205
	v_mul_f32_e32 v194, v108, v202
	v_mul_f32_e32 v195, v109, v203
	v_fma_f32 v110, v110, v208, -v188
	v_fma_f32 v111, v111, v209, -v189
	v_fma_f32 v108, v108, v206, -v190
	v_fma_f32 v109, v109, v207, -v191
	v_fma_f32 v118, v118, v200, -v230
	v_fma_f32 v119, v119, v201, -v231
	v_fma_f32 v116, v116, v198, -v232
	v_fma_f32 v117, v117, v199, -v233
	v_cvt_pk_bf16_f32 v124, v124, v125
	v_cvt_pk_bf16_f32 v125, v126, v127
	v_fma_f32 v106, v106, v208, v192
	v_fma_f32 v107, v107, v209, v193
	v_fma_f32 v104, v104, v206, v194
	v_fma_f32 v105, v105, v207, v195
	v_cvt_pk_bf16_f32 v108, v108, v109
	v_cvt_pk_bf16_f32 v109, v110, v111
	v_cvt_pk_bf16_f32 v126, v186, v187
	v_cvt_pk_bf16_f32 v127, v122, v123
	v_cvt_pk_bf16_f32 v116, v116, v117
	v_cvt_pk_bf16_f32 v117, v118, v119
	v_cvt_pk_bf16_f32 v112, v112, v113
	v_cvt_pk_bf16_f32 v113, v114, v115
	global_store_dwordx2 v[220:221], v[124:125], off
	global_store_dwordx2 v[220:221], v[126:127], off offset:64
	global_store_dwordx2 v[222:223], v[116:117], off
	global_store_dwordx2 v[222:223], v[112:113], off offset:64
	v_cvt_pk_bf16_f32 v104, v104, v105
	global_store_dwordx2 v[224:225], v[108:109], off
	v_cvt_pk_bf16_f32 v105, v106, v107
	v_mul_f32_e32 v106, v98, v212
	v_mul_f32_e32 v107, v99, v213
	v_mul_f32_e32 v108, v96, v210
	v_mul_f32_e32 v109, v97, v211
	global_store_dwordx2 v[224:225], v[104:105], off offset:64
	v_mad_i64_i32 v[104:105], s[52:53], v158, s82, v[120:121]
	v_fma_f32 v106, v102, v216, -v106
	v_fma_f32 v107, v103, v217, -v107
	v_fma_f32 v108, v100, v214, -v108
	v_fma_f32 v109, v101, v215, -v109
	v_mul_f32_e32 v102, v102, v212
	v_mul_f32_e32 v103, v103, v213
	v_mul_f32_e32 v100, v100, v210
	v_mul_f32_e32 v101, v101, v211
	v_lshl_add_u64 v[104:105], v[104:105], 0, s[50:51]
	v_fma_f32 v98, v98, v216, v102
	v_fma_f32 v99, v99, v217, v103
	v_fma_f32 v96, v96, v214, v100
	v_fma_f32 v97, v97, v215, v101
	v_lshl_add_u64 v[104:105], v[104:105], 0, v[174:175]
	v_cvt_pk_bf16_f32 v108, v108, v109
	v_cvt_pk_bf16_f32 v109, v106, v107
	v_cvt_pk_bf16_f32 v96, v96, v97
	v_cvt_pk_bf16_f32 v97, v98, v99
	v_lshlrev_b32_e32 v122, 2, v165
	v_mov_b32_e32 v123, v137
	global_store_dwordx2 v[104:105], v[108:109], off
	global_store_dwordx2 v[104:105], v[96:97], off offset:64
	v_lshl_add_u64 v[100:101], v[142:143], 0, v[122:123]
	global_load_dwordx4 v[96:99], v[100:101], off
	s_nop 0
	global_load_dwordx4 v[100:103], v[100:101], off offset:2048
	v_lshl_add_u64 v[108:109], v[140:141], 0, v[122:123]
	global_load_dwordx4 v[104:107], v[108:109], off
	s_nop 0
	global_load_dwordx4 v[108:111], v[108:109], off offset:2048
	v_mov_b32_e32 v117, v137
	v_or_b32_e32 v116, 0x1000, v122
	v_lshl_add_u64 v[112:113], v[142:143], 0, v[116:117]
	global_load_dwordx4 v[112:115], v[112:113], off
	v_lshl_add_u64 v[116:117], v[140:141], 0, v[116:117]
	global_load_dwordx4 v[116:119], v[116:117], off
	v_mov_b32_e32 v127, v137
	v_or_b32_e32 v126, 0x1800, v122
	v_lshl_add_u64 v[122:123], v[142:143], 0, v[126:127]
	global_load_dwordx4 v[122:125], v[122:123], off
	v_lshl_add_u64 v[126:127], v[140:141], 0, v[126:127]
	global_load_dwordx4 v[186:189], v[126:127], off
	v_mad_i64_i32 v[126:127], s[52:53], v161, s82, v[120:121]
	v_mad_i64_i32 v[190:191], s[52:53], v163, s82, v[120:121]
	v_lshl_add_u64 v[126:127], v[126:127], 0, s[50:51]
	v_lshl_add_u64 v[190:191], v[190:191], 0, s[50:51]
	v_lshl_add_u64 v[126:127], v[126:127], 0, v[174:175]
	v_lshl_add_u64 v[190:191], v[190:191], 0, v[174:175]
	s_waitcnt vmcnt(0)
; DI u32x2 pk4(f32x4 v) { u32x2 r; r.x = pk2(v[0], v[1]); r.y = pk2(v[2], v[3]); return r; }
; #define ROWS8 _Pragma("unroll") for (int ai = 0; ai < 2; ++ai) _Pragma("unroll") for (int m = 0; m < 4; ++m) if (ai == 0 || !hf)
; #define PK8(v0, v1) ({ const u32x2 h0_ = pk4(v0), h1_ = pk4(v1); (u32x4){h0_.x, h0_.y, h1_.x, h1_.y}; })
;     DI void operator()(const Acc& acc, const Unit& u, int wr, int wc, int fr, int fq) const {
;     ...
;                 for (int bj = 0; bj < 2; ++bj) {
;                     const int g32 = u.pn * 8 + bj * 4 + wc, g64 = g32 >> 1; const bool rope = (g64 % 3) == 2;
;                     if (!rope) {
;                         ROWS8 { const int r = row0 + ai * HALF + m * 16; const float rs = rsv[ai][m] * QSCALE;
;                             bf16_t* dst = WSB(OFF_Q) + (size_t)r * 3072 + g32 * 32 + 8 * fq; *(u32x4*)(dst) = PK8(acc[ai][bj][m][0] * rs, acc[ai][bj][m][1] * rs); }
;     ...
; #pragma unroll
;                             for (int m = 0; m < 4; ++m) { const int r = row0 + ai * HALF + m * 16; const float rs = rsv[ai][m] * QSCALE;
;                                 const f32x4 v0 = acc[ai][bj][m][0] * rs, v1 = acc[ai][bj][m][1] * rs;
;                                 bf16_t* dst = WSB(OFF_Q) + (size_t)r * 3072 + g64 * 64 + j0;
;                                 *(u32x2*)(dst) = pk4(v0 * c4[m] - v1 * s4[m]); *(u32x2*)(dst + 32) = pk4(v1 * c4[m] + v0 * s4[m]); }
	v_mul_f32_e32 v192, v90, v98
	v_mul_f32_e32 v193, v91, v99
	v_mul_f32_e32 v194, v88, v96
	v_mul_f32_e32 v195, v89, v97
	v_mul_f32_e32 v196, v82, v102
	v_mul_f32_e32 v197, v83, v103
	v_mul_f32_e32 v198, v80, v100
	v_mul_f32_e32 v199, v81, v101
	v_mul_f32_e32 v98, v94, v98
	v_mul_f32_e32 v99, v95, v99
	v_mul_f32_e32 v96, v92, v96
	v_mul_f32_e32 v97, v93, v97
	v_mul_f32_e32 v102, v86, v102
	v_mul_f32_e32 v103, v87, v103
	v_mul_f32_e32 v100, v84, v100
	v_mul_f32_e32 v101, v85, v101
	v_fma_f32 v94, v94, v106, -v192
	v_fma_f32 v95, v95, v107, -v193
	v_fma_f32 v92, v92, v104, -v194
	v_fma_f32 v93, v93, v105, -v195
	v_fma_f32 v86, v86, v110, -v196
	v_fma_f32 v87, v87, v111, -v197
	v_fma_f32 v84, v84, v108, -v198
	v_fma_f32 v85, v85, v109, -v199
	v_fma_f32 v90, v90, v106, v98
	v_fma_f32 v91, v91, v107, v99
	v_fma_f32 v88, v88, v104, v96
	v_fma_f32 v89, v89, v105, v97
	v_fma_f32 v82, v82, v110, v102
	v_fma_f32 v83, v83, v111, v103
	v_cvt_pk_bf16_f32 v92, v92, v93
	v_cvt_pk_bf16_f32 v93, v94, v95
	v_cvt_pk_bf16_f32 v84, v84, v85
	v_cvt_pk_bf16_f32 v85, v86, v87
	v_fma_f32 v80, v80, v108, v100
	v_fma_f32 v81, v81, v109, v101
	v_cvt_pk_bf16_f32 v88, v88, v89
	v_cvt_pk_bf16_f32 v89, v90, v91
	global_store_dwordx2 v[126:127], v[92:93], off
	global_store_dwordx2 v[126:127], v[88:89], off offset:64
	global_store_dwordx2 v[190:191], v[84:85], off
	v_cvt_pk_bf16_f32 v80, v80, v81
	v_cvt_pk_bf16_f32 v81, v82, v83
	v_mul_f32_e32 v82, v74, v114
	v_mul_f32_e32 v83, v75, v115
	v_mul_f32_e32 v84, v72, v112
	v_mul_f32_e32 v85, v73, v113
	global_store_dwordx2 v[190:191], v[80:81], off offset:64
	v_mad_i64_i32 v[80:81], s[52:53], v159, s82, v[120:121]
	v_fma_f32 v82, v78, v118, -v82
	v_fma_f32 v83, v79, v119, -v83
	v_fma_f32 v84, v76, v116, -v84
	v_fma_f32 v85, v77, v117, -v85
	v_mul_f32_e32 v78, v78, v114
	v_mul_f32_e32 v79, v79, v115
	v_mul_f32_e32 v76, v76, v112
	v_mul_f32_e32 v77, v77, v113
	v_lshl_add_u64 v[80:81], v[80:81], 0, s[50:51]
	v_fma_f32 v74, v74, v118, v78
	v_fma_f32 v75, v75, v119, v79
	v_fma_f32 v72, v72, v116, v76
	v_fma_f32 v73, v73, v117, v77
	v_lshl_add_u64 v[80:81], v[80:81], 0, v[174:175]
	v_cvt_pk_bf16_f32 v72, v72, v73
	v_cvt_pk_bf16_f32 v73, v74, v75
	v_mul_f32_e32 v74, v66, v124
	v_mul_f32_e32 v75, v67, v125
	v_mul_f32_e32 v76, v64, v122
	v_mul_f32_e32 v77, v65, v123
	global_store_dwordx2 v[80:81], v[72:73], off offset:64
	v_mad_i64_i32 v[72:73], s[52:53], v157, s82, v[120:121]
	v_fma_f32 v74, v70, v188, -v74
	v_fma_f32 v75, v71, v189, -v75
	v_fma_f32 v76, v68, v186, -v76
	v_fma_f32 v77, v69, v187, -v77
	v_mul_f32_e32 v70, v70, v124
	v_mul_f32_e32 v71, v71, v125
	v_mul_f32_e32 v68, v68, v122
	v_mul_f32_e32 v69, v69, v123
	v_lshl_add_u64 v[72:73], v[72:73], 0, s[50:51]
	v_fma_f32 v66, v66, v188, v70
	v_fma_f32 v67, v67, v189, v71
	v_fma_f32 v64, v64, v186, v68
	v_fma_f32 v65, v65, v187, v69
	v_cvt_pk_bf16_f32 v84, v84, v85
	v_cvt_pk_bf16_f32 v85, v82, v83
	v_lshl_add_u64 v[72:73], v[72:73], 0, v[174:175]
	v_cvt_pk_bf16_f32 v76, v76, v77
	v_cvt_pk_bf16_f32 v77, v74, v75
	v_cvt_pk_bf16_f32 v64, v64, v65
	v_cvt_pk_bf16_f32 v65, v66, v67
	global_store_dwordx2 v[80:81], v[84:85], off
	global_store_dwordx2 v[72:73], v[76:77], off
	global_store_dwordx2 v[72:73], v[64:65], off offset:64
.LBB0_1010:
	s_or_b32 s43, s41, 4
	s_ashr_i32 s41, s43, 1
	s_mul_hi_i32 s50, s41, 0x55555556
	s_lshr_b32 s51, s50, 31
	s_add_i32 s50, s50, s51
	s_mul_i32 s50, s50, 3
	s_sub_i32 s50, s41, s50
	s_cmp_eq_u32 s50, 2
	s_mov_b64 s[50:51], -1
	s_cbranch_scc1 .LBB0_1012
	s_lshl_b32 s50, s43, 5
	s_ashr_i32 s51, s50, 31
	v_mov_b64_e32 v[68:69], s[24:25]
	v_mad_i64_i32 v[64:65], s[52:53], v156, s82, v[68:69]
	s_lshl_b64 s[50:51], s[50:51], 1
	v_lshl_add_u64 v[64:65], v[64:65], 0, s[50:51]
	v_lshl_add_u64 v[70:71], v[64:65], 0, v[154:155]
	v_mul_f32_e32 v66, v62, v180
	v_mul_f32_e32 v67, v63, v180
	v_mul_f32_e32 v64, v60, v180
	v_mul_f32_e32 v65, v61, v180
	v_mul_f32_e32 v72, v58, v180
	v_mul_f32_e32 v73, v59, v180
	v_cvt_pk_bf16_f32 v64, v64, v65
	v_cvt_pk_bf16_f32 v65, v66, v67
	v_mul_f32_e32 v66, v56, v180
	v_mul_f32_e32 v67, v57, v180
	s_nop 0
	v_cvt_pk_bf16_f32 v66, v66, v67
	v_cvt_pk_bf16_f32 v67, v72, v73
	global_store_dwordx4 v[70:71], v[64:67], off
	v_mul_f32_e32 v72, v50, v178
	v_mul_f32_e32 v73, v51, v178
	s_nop 0
	v_mad_i64_i32 v[64:65], s[52:53], v160, s82, v[68:69]
	v_lshl_add_u64 v[64:65], v[64:65], 0, s[50:51]
	v_lshl_add_u64 v[70:71], v[64:65], 0, v[154:155]
	v_mul_f32_e32 v66, v54, v178
	v_mul_f32_e32 v67, v55, v178
	v_mul_f32_e32 v64, v52, v178
	v_mul_f32_e32 v65, v53, v178
	s_nop 0
	v_cvt_pk_bf16_f32 v64, v64, v65
	v_cvt_pk_bf16_f32 v65, v66, v67
	v_mul_f32_e32 v66, v48, v178
	v_mul_f32_e32 v67, v49, v178
	s_nop 0
	v_cvt_pk_bf16_f32 v66, v66, v67
	v_cvt_pk_bf16_f32 v67, v72, v73
	global_store_dwordx4 v[70:71], v[64:67], off
	v_mul_f32_e32 v72, v42, v176
	v_mul_f32_e32 v73, v43, v176
	s_nop 0
	v_mad_i64_i32 v[64:65], s[52:53], v162, s82, v[68:69]
	v_lshl_add_u64 v[64:65], v[64:65], 0, s[50:51]
	v_lshl_add_u64 v[70:71], v[64:65], 0, v[154:155]
	v_mul_f32_e32 v66, v46, v176
	v_mul_f32_e32 v67, v47, v176
	v_mul_f32_e32 v64, v44, v176
	v_mul_f32_e32 v65, v45, v176
	s_nop 0
	v_cvt_pk_bf16_f32 v64, v64, v65
	v_cvt_pk_bf16_f32 v65, v66, v67
	v_mul_f32_e32 v66, v40, v176
	v_mul_f32_e32 v67, v41, v176
	s_nop 0
	v_cvt_pk_bf16_f32 v66, v66, v67
	v_cvt_pk_bf16_f32 v67, v72, v73
	global_store_dwordx4 v[70:71], v[64:67], off
	v_mul_f32_e32 v72, v34, v172
	v_mul_f32_e32 v73, v35, v172
	s_nop 0
	v_mad_i64_i32 v[64:65], s[52:53], v158, s82, v[68:69]
	v_lshl_add_u64 v[64:65], v[64:65], 0, s[50:51]
	v_lshl_add_u64 v[70:71], v[64:65], 0, v[154:155]
	v_mul_f32_e32 v66, v38, v172
; #define ROWS8 _Pragma("unroll") for (int ai = 0; ai < 2; ++ai) _Pragma("unroll") for (int m = 0; m < 4; ++m) if (ai == 0 || !hf)
; #define PK8(v0, v1) ({ const u32x2 h0_ = pk4(v0), h1_ = pk4(v1); (u32x4){h0_.x, h0_.y, h1_.x, h1_.y}; })
;     DI void operator()(const Acc& acc, const Unit& u, int wr, int wc, int fr, int fq) const {
;     ...
;                         ROWS8 { const int r = row0 + ai * HALF + m * 16; const float rs = rsv[ai][m] * QSCALE;
;                             bf16_t* dst = WSB(OFF_Q) + (size_t)r * 3072 + g32 * 32 + 8 * fq; *(u32x4*)(dst) = PK8(acc[ai][bj][m][0] * rs, acc[ai][bj][m][1] * rs); }
;                     } else {
;                         const int j0 = 16 * (g32 & 1) + 4 * fq;
; #pragma unroll
;                         for (int ai = 0; ai < 2; ++ai) if (ai == 0 || !hf) {
;                             f32x4 c4[4], s4[4];
; #pragma unroll
;                             for (int m = 0; m < 4; ++m) { const int pos = (row0 + ai * HALF + m * 16) & (SEQ - 1); c4[m] = *(const f32x4*)(cs + pos * 32 + j0); s4[m] = *(const f32x4*)(cs + 4096 * 32 + pos * 32 + j0); }
	v_mul_f32_e32 v67, v39, v172
	v_mul_f32_e32 v64, v36, v172
	v_mul_f32_e32 v65, v37, v172
	s_nop 0
	v_cvt_pk_bf16_f32 v64, v64, v65
	v_cvt_pk_bf16_f32 v65, v66, v67
	v_mul_f32_e32 v66, v32, v172
	v_mul_f32_e32 v67, v33, v172
	s_nop 0
	v_cvt_pk_bf16_f32 v66, v66, v67
	v_cvt_pk_bf16_f32 v67, v72, v73
	global_store_dwordx4 v[70:71], v[64:67], off
	v_mul_f32_e32 v72, v26, v170
	v_mul_f32_e32 v73, v27, v170
	s_nop 0
	v_mad_i64_i32 v[64:65], s[52:53], v161, s82, v[68:69]
	v_lshl_add_u64 v[64:65], v[64:65], 0, s[50:51]
	v_lshl_add_u64 v[70:71], v[64:65], 0, v[154:155]
	v_mul_f32_e32 v66, v30, v170
	v_mul_f32_e32 v67, v31, v170
	v_mul_f32_e32 v64, v28, v170
	v_mul_f32_e32 v65, v29, v170
	s_nop 0
	v_cvt_pk_bf16_f32 v64, v64, v65
	v_cvt_pk_bf16_f32 v65, v66, v67
	v_mul_f32_e32 v66, v24, v170
	v_mul_f32_e32 v67, v25, v170
	s_nop 0
	v_cvt_pk_bf16_f32 v66, v66, v67
	v_cvt_pk_bf16_f32 v67, v72, v73
	global_store_dwordx4 v[70:71], v[64:67], off
	v_mul_f32_e32 v72, v18, v168
	v_mul_f32_e32 v73, v19, v168
	s_nop 0
	v_mad_i64_i32 v[64:65], s[52:53], v163, s82, v[68:69]
	v_lshl_add_u64 v[64:65], v[64:65], 0, s[50:51]
	v_lshl_add_u64 v[70:71], v[64:65], 0, v[154:155]
	v_mul_f32_e32 v66, v22, v168
	v_mul_f32_e32 v67, v23, v168
	v_mul_f32_e32 v64, v20, v168
	v_mul_f32_e32 v65, v21, v168
	s_nop 0
	v_cvt_pk_bf16_f32 v64, v64, v65
	v_cvt_pk_bf16_f32 v65, v66, v67
	v_mul_f32_e32 v66, v16, v168
	v_mul_f32_e32 v67, v17, v168
	s_nop 0
	v_cvt_pk_bf16_f32 v66, v66, v67
	v_cvt_pk_bf16_f32 v67, v72, v73
	global_store_dwordx4 v[70:71], v[64:67], off
	v_mul_f32_e32 v72, v10, v166
	v_mul_f32_e32 v73, v11, v166
	s_nop 0
	v_mad_i64_i32 v[64:65], s[52:53], v159, s82, v[68:69]
	v_lshl_add_u64 v[64:65], v[64:65], 0, s[50:51]
	v_lshl_add_u64 v[70:71], v[64:65], 0, v[154:155]
	v_mul_f32_e32 v66, v14, v166
	v_mul_f32_e32 v67, v15, v166
	v_mul_f32_e32 v64, v12, v166
	v_mul_f32_e32 v65, v13, v166
	s_nop 0
	v_cvt_pk_bf16_f32 v64, v64, v65
	v_cvt_pk_bf16_f32 v65, v66, v67
	v_mul_f32_e32 v66, v8, v166
	v_mul_f32_e32 v67, v9, v166
	s_nop 0
	v_cvt_pk_bf16_f32 v66, v66, v67
	v_cvt_pk_bf16_f32 v67, v72, v73
	global_store_dwordx4 v[70:71], v[64:67], off
	v_mul_f32_e32 v70, v2, v164
	v_mul_f32_e32 v71, v3, v164
	s_nop 0
	v_mad_i64_i32 v[64:65], s[52:53], v157, s82, v[68:69]
	v_lshl_add_u64 v[64:65], v[64:65], 0, s[50:51]
	v_lshl_add_u64 v[68:69], v[64:65], 0, v[154:155]
	v_mul_f32_e32 v66, v6, v164
	v_mul_f32_e32 v67, v7, v164
	v_mul_f32_e32 v64, v4, v164
	v_mul_f32_e32 v65, v5, v164
	s_mov_b64 s[50:51], 0
	v_cvt_pk_bf16_f32 v64, v64, v65
	v_cvt_pk_bf16_f32 v65, v66, v67
	v_mul_f32_e32 v66, v0, v164
	v_mul_f32_e32 v67, v1, v164
	s_nop 0
	v_cvt_pk_bf16_f32 v66, v66, v67
	v_cvt_pk_bf16_f32 v67, v70, v71
	global_store_dwordx4 v[68:69], v[64:67], off
.LBB0_1012:
	s_andn2_b64 vcc, exec, s[50:51]
	s_cbranch_vccnz .LBB0_978
	v_lshl_add_u64 v[68:69], v[142:143], 0, v[136:137]
	v_or_b32_e32 v84, 0x1000, v136
	v_mov_b32_e32 v85, v137
	global_load_dwordx4 v[64:67], v[68:69], off
	s_nop 0
	global_load_dwordx4 v[68:71], v[68:69], off offset:2048
	v_lshl_add_u64 v[76:77], v[140:141], 0, v[136:137]
	v_lshl_add_u64 v[80:81], v[142:143], 0, v[84:85]
	global_load_dwordx4 v[72:75], v[76:77], off
	s_nop 0
	global_load_dwordx4 v[76:79], v[76:77], off offset:2048
	v_lshl_add_u64 v[84:85], v[140:141], 0, v[84:85]
	global_load_dwordx4 v[80:83], v[80:81], off
	v_or_b32_e32 v136, 0x1800, v136
	global_load_dwordx4 v[84:87], v[84:85], off
	v_lshl_add_u64 v[92:93], v[140:141], 0, v[136:137]
	v_lshl_add_u64 v[88:89], v[142:143], 0, v[136:137]
	global_load_dwordx4 v[88:91], v[88:89], off
	s_nop 0
	global_load_dwordx4 v[92:95], v[92:93], off
	s_lshl_b32 s50, s41, 6
	v_mul_f32_e32 v62, v62, v180
	v_mul_f32_e32 v63, v63, v180
	v_mul_f32_e32 v58, v58, v180
	v_mul_f32_e32 v59, v59, v180
	v_mul_f32_e32 v52, v52, v178
	v_mul_f32_e32 v53, v53, v178
	v_mul_f32_e32 v48, v48, v178
	v_mul_f32_e32 v49, v49, v178
	v_mul_f32_e32 v60, v60, v180
	v_mul_f32_e32 v61, v61, v180
	v_mul_f32_e32 v96, v56, v180
	v_mul_f32_e32 v97, v57, v180
	v_mov_b64_e32 v[56:57], s[24:25]
	v_mul_f32_e32 v54, v54, v178
	v_mul_f32_e32 v55, v55, v178
	v_mul_f32_e32 v50, v50, v178
	v_mul_f32_e32 v51, v51, v178
	v_mul_f32_e32 v42, v42, v176
	v_mul_f32_e32 v43, v43, v176
	v_mul_f32_e32 v40, v40, v176
	v_mul_f32_e32 v41, v41, v176
	s_ashr_i32 s51, s50, 31
	v_mul_f32_e32 v46, v46, v176
	v_mul_f32_e32 v47, v47, v176
	v_mul_f32_e32 v44, v44, v176
	v_mul_f32_e32 v45, v45, v176
	v_mad_i64_i32 v[98:99], s[52:53], v156, s82, v[56:57]
	v_mad_i64_i32 v[102:103], s[52:53], v162, s82, v[56:57]
	s_lshl_b64 s[50:51], s[50:51], 1
	v_mad_i64_i32 v[100:101], s[52:53], v160, s82, v[56:57]
	v_lshl_add_u64 v[98:99], v[98:99], 0, s[50:51]
	v_lshl_add_u64 v[102:103], v[102:103], 0, s[50:51]
	v_lshl_add_u64 v[100:101], v[100:101], 0, s[50:51]
	v_lshl_add_u64 v[98:99], v[98:99], 0, v[174:175]
	v_lshl_add_u64 v[102:103], v[102:103], 0, v[174:175]
	v_mul_f32_e32 v34, v34, v172
	v_mul_f32_e32 v35, v35, v172
	v_mul_f32_e32 v32, v32, v172
	v_mul_f32_e32 v33, v33, v172
	v_lshl_add_u64 v[100:101], v[100:101], 0, v[174:175]
	v_mul_f32_e32 v38, v38, v172
	v_mul_f32_e32 v39, v39, v172
	v_mul_f32_e32 v36, v36, v172
	v_mul_f32_e32 v37, v37, v172
	v_lshlrev_b32_e32 v136, 2, v165
	v_mul_f32_e32 v26, v26, v170
	v_mul_f32_e32 v27, v27, v170
	v_mul_f32_e32 v24, v24, v170
	v_mul_f32_e32 v25, v25, v170
	v_mul_f32_e32 v18, v18, v168
	v_mul_f32_e32 v19, v19, v168
	v_mul_f32_e32 v16, v16, v168
	v_mul_f32_e32 v17, v17, v168
	v_mul_f32_e32 v30, v30, v170
	v_mul_f32_e32 v31, v31, v170
	v_mul_f32_e32 v28, v28, v170
	v_mul_f32_e32 v29, v29, v170
	v_mul_f32_e32 v22, v22, v168
	v_mul_f32_e32 v23, v23, v168
	v_mul_f32_e32 v20, v20, v168
	v_mul_f32_e32 v21, v21, v168
	v_mul_f32_e32 v10, v10, v166
	v_mul_f32_e32 v11, v11, v166
	v_mul_f32_e32 v8, v8, v166
	v_mul_f32_e32 v9, v9, v166
	v_mul_f32_e32 v14, v14, v166
	v_mul_f32_e32 v15, v15, v166
	v_mul_f32_e32 v12, v12, v166
	v_mul_f32_e32 v13, v13, v166
	v_mul_f32_e32 v2, v2, v164
	v_mul_f32_e32 v3, v3, v164
	v_mul_f32_e32 v0, v0, v164
	v_mul_f32_e32 v1, v1, v164
	v_mul_f32_e32 v6, v6, v164
	v_mul_f32_e32 v7, v7, v164
	v_mul_f32_e32 v4, v4, v164
	v_mul_f32_e32 v5, v5, v164
	s_waitcnt vmcnt(0)
; DI u32x2 pk4(f32x4 v) { u32x2 r; r.x = pk2(v[0], v[1]); r.y = pk2(v[2], v[3]); return r; }
;     DI void operator()(const Acc& acc, const Unit& u, int wr, int wc, int fr, int fq) const {
;     ...
; #pragma unroll
;                             for (int m = 0; m < 4; ++m) { const int r = row0 + ai * HALF + m * 16; const float rs = rsv[ai][m] * QSCALE;
;                                 const f32x4 v0 = acc[ai][bj][m][0] * rs, v1 = acc[ai][bj][m][1] * rs;
;                                 bf16_t* dst = WSB(OFF_Q) + (size_t)r * 3072 + g64 * 64 + j0;
;                                 *(u32x2*)(dst) = pk4(v0 * c4[m] - v1 * s4[m]); *(u32x2*)(dst + 32) = pk4(v1 * c4[m] + v0 * s4[m]); }
	v_mul_f32_e32 v104, v58, v66
	v_mul_f32_e32 v105, v59, v67
	v_mul_f32_e32 v66, v62, v66
	v_mul_f32_e32 v67, v63, v67
	v_mul_f32_e32 v110, v48, v68
	v_mul_f32_e32 v111, v49, v69
	v_mul_f32_e32 v68, v52, v68
	v_mul_f32_e32 v69, v53, v69
	v_mul_f32_e32 v106, v96, v64
	v_mul_f32_e32 v107, v97, v65
	v_mul_f32_e32 v64, v60, v64
	v_mul_f32_e32 v65, v61, v65
	v_mul_f32_e32 v108, v50, v70
	v_mul_f32_e32 v109, v51, v71
	v_mul_f32_e32 v70, v54, v70
	v_mul_f32_e32 v71, v55, v71
	v_fma_f32 v58, v58, v74, v66
	v_fma_f32 v59, v59, v75, v67
	v_fma_f32 v48, v48, v76, v68
	v_fma_f32 v49, v49, v77, v69
	v_mul_f32_e32 v66, v42, v82
	v_mul_f32_e32 v67, v43, v83
	v_mul_f32_e32 v68, v40, v80
	v_mul_f32_e32 v69, v41, v81
	v_fma_f32 v62, v62, v74, -v104
	v_fma_f32 v63, v63, v75, -v105
	v_fma_f32 v60, v60, v72, -v106
	v_fma_f32 v61, v61, v73, -v107
	v_fma_f32 v64, v96, v72, v64
	v_fma_f32 v65, v97, v73, v65
	v_fma_f32 v50, v50, v78, v70
	v_fma_f32 v51, v51, v79, v71
	v_mul_f32_e32 v70, v46, v82
	v_mul_f32_e32 v71, v47, v83
	v_mul_f32_e32 v72, v44, v80
	v_mul_f32_e32 v73, v45, v81
	v_fma_f32 v46, v46, v86, -v66
	v_fma_f32 v47, v47, v87, -v67
	v_fma_f32 v44, v44, v84, -v68
	v_fma_f32 v45, v45, v85, -v69
	v_fma_f32 v54, v54, v78, -v108
	v_fma_f32 v55, v55, v79, -v109
	v_fma_f32 v52, v52, v76, -v110
	v_fma_f32 v53, v53, v77, -v111
	v_cvt_pk_bf16_f32 v60, v60, v61
	v_cvt_pk_bf16_f32 v61, v62, v63
	v_fma_f32 v42, v42, v86, v70
	v_fma_f32 v43, v43, v87, v71
	v_fma_f32 v40, v40, v84, v72
	v_fma_f32 v41, v41, v85, v73
	v_cvt_pk_bf16_f32 v44, v44, v45
	v_cvt_pk_bf16_f32 v45, v46, v47
	v_cvt_pk_bf16_f32 v62, v64, v65
	v_cvt_pk_bf16_f32 v63, v58, v59
	v_cvt_pk_bf16_f32 v52, v52, v53
	v_cvt_pk_bf16_f32 v53, v54, v55
	v_cvt_pk_bf16_f32 v48, v48, v49
	v_cvt_pk_bf16_f32 v49, v50, v51
	global_store_dwordx2 v[98:99], v[60:61], off
	global_store_dwordx2 v[98:99], v[62:63], off offset:64
	global_store_dwordx2 v[100:101], v[52:53], off
	global_store_dwordx2 v[100:101], v[48:49], off offset:64
	v_cvt_pk_bf16_f32 v40, v40, v41
	v_cvt_pk_bf16_f32 v41, v42, v43
	global_store_dwordx2 v[102:103], v[44:45], off
	global_store_dwordx2 v[102:103], v[40:41], off offset:64
	v_mul_f32_e32 v42, v34, v90
	v_mul_f32_e32 v43, v35, v91
	v_mul_f32_e32 v44, v32, v88
	v_mul_f32_e32 v45, v33, v89
	v_mad_i64_i32 v[40:41], s[52:53], v158, s82, v[56:57]
	v_fma_f32 v42, v38, v94, -v42
	v_fma_f32 v43, v39, v95, -v43
	v_fma_f32 v44, v36, v92, -v44
	v_fma_f32 v45, v37, v93, -v45
	v_mul_f32_e32 v38, v38, v90
	v_mul_f32_e32 v39, v39, v91
	v_mul_f32_e32 v36, v36, v88
	v_mul_f32_e32 v37, v37, v89
	v_lshl_add_u64 v[40:41], v[40:41], 0, s[50:51]
	v_fma_f32 v34, v34, v94, v38
	v_fma_f32 v35, v35, v95, v39
	v_fma_f32 v32, v32, v92, v36
	v_fma_f32 v33, v33, v93, v37
	v_lshl_add_u64 v[40:41], v[40:41], 0, v[174:175]
	v_cvt_pk_bf16_f32 v44, v44, v45
	v_cvt_pk_bf16_f32 v45, v42, v43
	v_cvt_pk_bf16_f32 v32, v32, v33
	v_cvt_pk_bf16_f32 v33, v34, v35
	global_store_dwordx2 v[40:41], v[44:45], off
	global_store_dwordx2 v[40:41], v[32:33], off offset:64
	v_lshl_add_u64 v[36:37], v[142:143], 0, v[136:137]
	global_load_dwordx4 v[32:35], v[36:37], off
	s_nop 0
	global_load_dwordx4 v[36:39], v[36:37], off offset:2048
	v_lshl_add_u64 v[44:45], v[140:141], 0, v[136:137]
	global_load_dwordx4 v[40:43], v[44:45], off
	s_nop 0
	global_load_dwordx4 v[44:47], v[44:45], off offset:2048
	v_mov_b32_e32 v53, v137
	v_or_b32_e32 v52, 0x1000, v136
	v_lshl_add_u64 v[48:49], v[142:143], 0, v[52:53]
	global_load_dwordx4 v[48:51], v[48:49], off
	v_lshl_add_u64 v[52:53], v[140:141], 0, v[52:53]
	global_load_dwordx4 v[52:55], v[52:53], off
	v_or_b32_e32 v136, 0x1800, v136
	v_lshl_add_u64 v[58:59], v[142:143], 0, v[136:137]
	global_load_dwordx4 v[58:61], v[58:59], off
	v_lshl_add_u64 v[62:63], v[140:141], 0, v[136:137]
	global_load_dwordx4 v[62:65], v[62:63], off
	v_mad_i64_i32 v[66:67], s[52:53], v161, s82, v[56:57]
	v_mad_i64_i32 v[68:69], s[52:53], v163, s82, v[56:57]
	v_lshl_add_u64 v[66:67], v[66:67], 0, s[50:51]
	v_lshl_add_u64 v[68:69], v[68:69], 0, s[50:51]
	v_lshl_add_u64 v[66:67], v[66:67], 0, v[174:175]
	v_lshl_add_u64 v[68:69], v[68:69], 0, v[174:175]
	s_waitcnt vmcnt(0)
; DI u32x2 pk4(f32x4 v) { u32x2 r; r.x = pk2(v[0], v[1]); r.y = pk2(v[2], v[3]); return r; }
;     DI void operator()(const Acc& acc, const Unit& u, int wr, int wc, int fr, int fq) const {
;     ...
; #pragma unroll
;                             for (int m = 0; m < 4; ++m) { const int r = row0 + ai * HALF + m * 16; const float rs = rsv[ai][m] * QSCALE;
;                                 const f32x4 v0 = acc[ai][bj][m][0] * rs, v1 = acc[ai][bj][m][1] * rs;
;                                 bf16_t* dst = WSB(OFF_Q) + (size_t)r * 3072 + g64 * 64 + j0;
;                                 *(u32x2*)(dst) = pk4(v0 * c4[m] - v1 * s4[m]); *(u32x2*)(dst + 32) = pk4(v1 * c4[m] + v0 * s4[m]); }
	v_mul_f32_e32 v70, v26, v34
	v_mul_f32_e32 v71, v27, v35
	v_mul_f32_e32 v72, v24, v32
	v_mul_f32_e32 v73, v25, v33
	v_mul_f32_e32 v74, v18, v38
	v_mul_f32_e32 v75, v19, v39
	v_mul_f32_e32 v76, v16, v36
	v_mul_f32_e32 v77, v17, v37
	v_mul_f32_e32 v34, v30, v34
	v_mul_f32_e32 v35, v31, v35
	v_mul_f32_e32 v32, v28, v32
	v_mul_f32_e32 v33, v29, v33
	v_mul_f32_e32 v38, v22, v38
	v_mul_f32_e32 v39, v23, v39
	v_mul_f32_e32 v36, v20, v36
	v_mul_f32_e32 v37, v21, v37
	v_fma_f32 v30, v30, v42, -v70
	v_fma_f32 v31, v31, v43, -v71
	v_fma_f32 v28, v28, v40, -v72
	v_fma_f32 v29, v29, v41, -v73
	v_fma_f32 v22, v22, v46, -v74
	v_fma_f32 v23, v23, v47, -v75
	v_fma_f32 v20, v20, v44, -v76
	v_fma_f32 v21, v21, v45, -v77
	v_fma_f32 v26, v26, v42, v34
	v_fma_f32 v27, v27, v43, v35
	v_fma_f32 v24, v24, v40, v32
	v_fma_f32 v25, v25, v41, v33
	v_fma_f32 v18, v18, v46, v38
	v_fma_f32 v19, v19, v47, v39
	v_fma_f32 v16, v16, v44, v36
	v_fma_f32 v17, v17, v45, v37
	v_cvt_pk_bf16_f32 v28, v28, v29
	v_cvt_pk_bf16_f32 v29, v30, v31
	v_cvt_pk_bf16_f32 v20, v20, v21
	v_cvt_pk_bf16_f32 v21, v22, v23
	v_cvt_pk_bf16_f32 v24, v24, v25
	v_cvt_pk_bf16_f32 v25, v26, v27
	v_cvt_pk_bf16_f32 v16, v16, v17
	v_cvt_pk_bf16_f32 v17, v18, v19
	global_store_dwordx2 v[66:67], v[28:29], off
	global_store_dwordx2 v[66:67], v[24:25], off offset:64
	global_store_dwordx2 v[68:69], v[20:21], off
	global_store_dwordx2 v[68:69], v[16:17], off offset:64
	v_mul_f32_e32 v18, v10, v50
	v_mul_f32_e32 v19, v11, v51
	v_mul_f32_e32 v20, v8, v48
	v_mul_f32_e32 v21, v9, v49
	v_mad_i64_i32 v[16:17], s[52:53], v159, s82, v[56:57]
	v_fma_f32 v18, v14, v54, -v18
	v_fma_f32 v19, v15, v55, -v19
	v_fma_f32 v20, v12, v52, -v20
	v_fma_f32 v21, v13, v53, -v21
	v_mul_f32_e32 v14, v14, v50
	v_mul_f32_e32 v15, v15, v51
	v_mul_f32_e32 v12, v12, v48
	v_mul_f32_e32 v13, v13, v49
	v_lshl_add_u64 v[16:17], v[16:17], 0, s[50:51]
	v_fma_f32 v10, v10, v54, v14
	v_fma_f32 v11, v11, v55, v15
	v_fma_f32 v8, v8, v52, v12
	v_fma_f32 v9, v9, v53, v13
	v_lshl_add_u64 v[16:17], v[16:17], 0, v[174:175]
	v_cvt_pk_bf16_f32 v8, v8, v9
	v_cvt_pk_bf16_f32 v9, v10, v11
	v_mul_f32_e32 v10, v2, v60
	v_mul_f32_e32 v11, v3, v61
	v_mul_f32_e32 v12, v0, v58
	v_mul_f32_e32 v13, v1, v59
	global_store_dwordx2 v[16:17], v[8:9], off offset:64
	v_mad_i64_i32 v[8:9], s[52:53], v157, s82, v[56:57]
	v_fma_f32 v10, v6, v64, -v10
	v_fma_f32 v11, v7, v65, -v11
	v_fma_f32 v12, v4, v62, -v12
	v_fma_f32 v13, v5, v63, -v13
	v_mul_f32_e32 v6, v6, v60
	v_mul_f32_e32 v7, v7, v61
	v_mul_f32_e32 v4, v4, v58
	v_mul_f32_e32 v5, v5, v59
	v_lshl_add_u64 v[8:9], v[8:9], 0, s[50:51]
	v_fma_f32 v2, v2, v64, v6
	v_fma_f32 v3, v3, v65, v7
	v_fma_f32 v0, v0, v62, v4
	v_fma_f32 v1, v1, v63, v5
	v_cvt_pk_bf16_f32 v20, v20, v21
	v_cvt_pk_bf16_f32 v21, v18, v19
	v_lshl_add_u64 v[8:9], v[8:9], 0, v[174:175]
	v_cvt_pk_bf16_f32 v12, v12, v13
	v_cvt_pk_bf16_f32 v13, v10, v11
	v_cvt_pk_bf16_f32 v0, v0, v1
	v_cvt_pk_bf16_f32 v1, v2, v3
	global_store_dwordx2 v[16:17], v[20:21], off
	global_store_dwordx2 v[8:9], v[12:13], off
	global_store_dwordx2 v[8:9], v[0:1], off offset:64
	s_branch .LBB0_978

; #define LAS __attribute__((address_space(3)))
; DI u32x2 pk4(f32x4 v) { u32x2 r; r.x = pk2(v[0], v[1]); r.y = pk2(v[2], v[3]); return r; }
; DI float shfl_xor_l(float v, int lane, int m) { return __int_as_float(__builtin_amdgcn_ds_bpermute((lane ^ m) << 2, __float_as_int(v))); }
; DI void attn_unit(LAS unsigned char* lds, int wid, int b, int h, int qb) {
;     ...
;     const float lt = lrow + shfl_xor_l(lrow, lane, 32), inv = 1.f / lt;
;     LAS unsigned char* pt_ = lds + ABUF + wid * (32 * 272);
; #pragma unroll
;     for (int dt = 0; dt < 4; ++dt)
; #pragma unroll
;         for (int blk = 0; blk < 4; ++blk) { const f32x4 v = {o[dt][4 * blk] * inv, o[dt][4 * blk + 1] * inv, o[dt][4 * blk + 2] * inv, o[dt][4 * blk + 3] * inv};
;             *(LAS u32x2*)(pt_ + n * 272 + (32 * dt + 8 * blk + 4 * g) * 2) = pk4(v); }
;     asm volatile("" ::: "memory");
;     bf16_t* od = WSB(OFF_O) + ((size_t)b * SEQ + q0 + (lane >> 4)) * 2048 + h * 128 + (lane & 15) * 8;
; #pragma unroll
;     for (int j = 0; j < 8; ++j) { const u32x4 w = *(const LAS u32x4*)(pt_ + (4 * j + (lane >> 4)) * 272 + (lane & 15) * 16); *(u32x4*)(od + (size_t)(4 * j) * 2048) = w; }
;     asm volatile("" ::: "memory");
.LBB0_1077:
	ds_bpermute_b32 v0, v189, v185
	s_waitcnt lgkmcnt(0)
	s_barrier
	s_mov_b32 s25, s5
	v_add_f32_e32 v0, v185, v0
	v_div_scale_f32 v2, s[18:19], v0, v0, 1.0
	v_rcp_f32_e32 v3, v2
	v_div_scale_f32 v4, vcc, 1.0, v0, 1.0
	s_add_i32 s55, s55, s7
	v_fma_f32 v5, -v2, v3, 1.0
	v_fmac_f32_e32 v3, v5, v3
	v_mul_f32_e32 v5, v4, v3
	v_fma_f32 v6, -v2, v5, v4
	v_fmac_f32_e32 v5, v6, v3
	v_fma_f32 v2, -v2, v5, v4
	v_div_fmas_f32 v2, v2, v3, v5
	v_div_fixup_f32 v0, v2, v0, 1.0
	v_mul_u32_u24_e32 v2, 0x110, v202
	v_add3_u32 v8, s30, v2, v188
	v_mul_f32_e32 v2, v64, v0
	v_mul_f32_e32 v3, v65, v0
	v_mul_f32_e32 v4, v66, v0
	v_mul_f32_e32 v5, v67, v0
	v_cvt_pk_bf16_f32 v2, v2, v3
	v_cvt_pk_bf16_f32 v3, v4, v5
	v_mul_f32_e32 v4, v68, v0
	v_mul_f32_e32 v5, v69, v0
	v_mul_f32_e32 v6, v70, v0
	v_mul_f32_e32 v7, v71, v0
	v_cvt_pk_bf16_f32 v4, v4, v5
	v_cvt_pk_bf16_f32 v5, v6, v7
	v_add_u32_e32 v8, 0xa800, v8
	ds_write2_b64 v8, v[2:3], v[4:5] offset1:2
	v_mul_f32_e32 v2, v72, v0
	v_mul_f32_e32 v3, v73, v0
	v_mul_f32_e32 v4, v74, v0
	v_mul_f32_e32 v5, v75, v0
	v_cvt_pk_bf16_f32 v2, v2, v3
	v_cvt_pk_bf16_f32 v3, v4, v5
	v_mul_f32_e32 v4, v76, v0
	v_mul_f32_e32 v5, v77, v0
	v_mul_f32_e32 v6, v78, v0
	v_mul_f32_e32 v7, v79, v0
	v_cvt_pk_bf16_f32 v4, v4, v5
	v_cvt_pk_bf16_f32 v5, v6, v7
	ds_write2_b64 v8, v[2:3], v[4:5] offset0:4 offset1:6
	v_mul_f32_e32 v2, v48, v0
	v_mul_f32_e32 v3, v49, v0
	v_mul_f32_e32 v4, v50, v0
	v_mul_f32_e32 v5, v51, v0
	v_cvt_pk_bf16_f32 v2, v2, v3
	v_cvt_pk_bf16_f32 v3, v4, v5
	v_mul_f32_e32 v4, v52, v0
	v_mul_f32_e32 v5, v53, v0
	v_mul_f32_e32 v6, v54, v0
	v_mul_f32_e32 v7, v55, v0
	v_cvt_pk_bf16_f32 v4, v4, v5
	v_cvt_pk_bf16_f32 v5, v6, v7
	ds_write2_b64 v8, v[2:3], v[4:5] offset0:8 offset1:10
	v_mul_f32_e32 v2, v56, v0
	v_mul_f32_e32 v3, v57, v0
	v_mul_f32_e32 v4, v58, v0
	v_mul_f32_e32 v5, v59, v0
	v_cvt_pk_bf16_f32 v2, v2, v3
	v_cvt_pk_bf16_f32 v3, v4, v5
	v_mul_f32_e32 v4, v60, v0
	v_mul_f32_e32 v5, v61, v0
	v_mul_f32_e32 v6, v62, v0
	v_mul_f32_e32 v7, v63, v0
	v_cvt_pk_bf16_f32 v4, v4, v5
	v_cvt_pk_bf16_f32 v5, v6, v7
	ds_write2_b64 v8, v[2:3], v[4:5] offset0:12 offset1:14
	v_mul_f32_e32 v2, v32, v0
	v_mul_f32_e32 v3, v33, v0
	v_mul_f32_e32 v4, v34, v0
	v_mul_f32_e32 v5, v35, v0
	v_cvt_pk_bf16_f32 v2, v2, v3
	v_cvt_pk_bf16_f32 v3, v4, v5
	v_mul_f32_e32 v4, v36, v0
	v_mul_f32_e32 v5, v37, v0
	v_mul_f32_e32 v6, v38, v0
	v_mul_f32_e32 v7, v39, v0
	v_cvt_pk_bf16_f32 v4, v4, v5
	v_cvt_pk_bf16_f32 v5, v6, v7
	ds_write2_b64 v8, v[2:3], v[4:5] offset0:16 offset1:18
	v_mul_f32_e32 v2, v40, v0
	v_mul_f32_e32 v3, v41, v0
	v_mul_f32_e32 v4, v42, v0
	v_mul_f32_e32 v5, v43, v0
	v_cvt_pk_bf16_f32 v2, v2, v3
	v_cvt_pk_bf16_f32 v3, v4, v5
	v_mul_f32_e32 v4, v44, v0
	v_mul_f32_e32 v5, v45, v0
	v_mul_f32_e32 v6, v46, v0
	v_mul_f32_e32 v7, v47, v0
	v_cvt_pk_bf16_f32 v4, v4, v5
	v_cvt_pk_bf16_f32 v5, v6, v7
	ds_write2_b64 v8, v[2:3], v[4:5] offset0:20 offset1:22
	v_mul_f32_e32 v2, v16, v0
	v_mul_f32_e32 v3, v17, v0
	v_mul_f32_e32 v4, v18, v0
	v_mul_f32_e32 v5, v19, v0
	v_cvt_pk_bf16_f32 v2, v2, v3
	v_cvt_pk_bf16_f32 v3, v4, v5
	v_mul_f32_e32 v4, v20, v0
	v_mul_f32_e32 v5, v21, v0
	v_mul_f32_e32 v6, v22, v0
	v_mul_f32_e32 v7, v23, v0
	v_cvt_pk_bf16_f32 v4, v4, v5
	v_cvt_pk_bf16_f32 v5, v6, v7
	ds_write2_b64 v8, v[2:3], v[4:5] offset0:24 offset1:26
	v_mul_f32_e32 v2, v24, v0
	v_mul_f32_e32 v3, v25, v0
	v_mul_f32_e32 v4, v26, v0
	v_mul_f32_e32 v5, v27, v0
	v_cvt_pk_bf16_f32 v2, v2, v3
	v_cvt_pk_bf16_f32 v3, v4, v5
	v_mul_f32_e32 v4, v28, v0
	v_mul_f32_e32 v5, v29, v0
	v_mul_f32_e32 v6, v30, v0
	v_mul_f32_e32 v7, v31, v0
	v_cvt_pk_bf16_f32 v4, v4, v5
	v_cvt_pk_bf16_f32 v5, v6, v7
	ds_write2_b64 v8, v[2:3], v[4:5] offset0:28 offset1:30
	v_ashrrev_i32_e32 v2, 4, v187
	v_ashrrev_i32_e32 v3, 31, v2
	v_lshl_add_u64 v[4:5], s[16:17], 0, v[2:3]
	v_lshlrev_b64 v[4:5], 12, v[4:5]
	v_lshl_add_u64 v[4:5], s[26:27], 0, v[4:5]
	v_lshl_add_u64 v[4:5], v[4:5], 0, s[24:25]
	v_lshlrev_b32_e32 v0, 1, v186
	v_lshl_add_u64 v[10:11], v[4:5], 0, v[0:1]
	v_mul_lo_u32 v0, v2, s46
	v_add3_u32 v0, s30, v184, v0
	ds_read_b128 v[2:5], v0 offset:43008
	ds_read_b128 v[6:9], v0 offset:44096
	v_add_co_u32_e32 v12, vcc, s47, v10
	s_add_i32 s31, s31, s36
	s_nop 0
	v_addc_co_u32_e32 v13, vcc, 0, v11, vcc
	s_waitcnt lgkmcnt(1)
	global_store_dwordx4 v[12:13], v[2:5], off
	s_cmpk_gt_i32 s55, 0xff
	s_nop 0
	v_add_co_u32_e32 v2, vcc, s48, v10
	s_nop 1
	v_addc_co_u32_e32 v3, vcc, 0, v11, vcc
	s_waitcnt lgkmcnt(0)
	global_store_dwordx4 v[2:3], v[6:9], off
	ds_read_b128 v[2:5], v0 offset:45184
	ds_read_b128 v[6:9], v0 offset:46272
	v_add_co_u32_e32 v12, vcc, s49, v10
	s_nop 1
	v_addc_co_u32_e32 v13, vcc, 0, v11, vcc
	s_waitcnt lgkmcnt(1)
	global_store_dwordx4 v[12:13], v[2:5], off
	s_nop 1
	v_add_co_u32_e32 v2, vcc, s50, v10
	s_nop 1
	v_addc_co_u32_e32 v3, vcc, 0, v11, vcc
	s_waitcnt lgkmcnt(0)
	global_store_dwordx4 v[2:3], v[6:9], off
	ds_read_b128 v[2:5], v0 offset:47360
	ds_read_b128 v[6:9], v0 offset:48448
	v_add_co_u32_e32 v12, vcc, s51, v10
	s_nop 1
	v_addc_co_u32_e32 v13, vcc, 0, v11, vcc
	s_waitcnt lgkmcnt(1)
	global_store_dwordx4 v[12:13], v[2:5], off
	s_nop 1
	v_add_co_u32_e32 v2, vcc, s52, v10
	s_nop 1
	v_addc_co_u32_e32 v3, vcc, 0, v11, vcc
	s_waitcnt lgkmcnt(0)
	global_store_dwordx4 v[2:3], v[6:9], off
	ds_read_b128 v[2:5], v0 offset:49536
	ds_read_b128 v[6:9], v0 offset:50624
	v_add_co_u32_e32 v12, vcc, 0x15118000, v10
	s_nop 1
	v_addc_co_u32_e32 v13, vcc, 0, v11, vcc
	s_waitcnt lgkmcnt(1)
	global_store_dwordx4 v[12:13], v[2:5], off
	s_nop 1
	v_add_co_u32_e32 v2, vcc, 0x1511c000, v10
	s_nop 1
	v_addc_co_u32_e32 v3, vcc, 0, v11, vcc
	s_waitcnt lgkmcnt(0)
	global_store_dwordx4 v[2:3], v[6:9], off
	s_cbranch_scc1 .LBB0_1101

; #define LAS __attribute__((address_space(3)))
; DI float shfl_xor_l(float v, int lane, int m) { return __int_as_float(__builtin_amdgcn_ds_bpermute((lane ^ m) << 2, __float_as_int(v))); }
; #define A_LOAD(kt) do { const size_t ko = (size_t)(kt) * 64; st0 = *(const u32x4*)(kn_src + ko * 2048); st1 = *(const u32x4*)(kn_src + (ko + 32) * 2048); \
;         st2 = *(const u32x4*)(kr_src + ko * 64); st3 = *(const u32x4*)(v_src + ko); st4 = *(const u32x4*)(v_src + ko + (size_t)64 * 8192); } while (0)
; #define VLD(dst, j, dt) do { LAS unsigned char* va_ = vb + (32 * (dt) + n) * VROW + (16 * (j) + 4 * g) * 2; const u32x2 lo_ = *(const LAS u32x2*)(va_), hi_ = *(const LAS u32x2*)(va_ + 16); dst = (u32x4){lo_.x, lo_.y, hi_.x, hi_.y}; } while (0)
; DI void attn_unit(LAS unsigned char* lds, int wid, int b, int h, int qb) {
;     ...
;     for (int kt = 0; kt < nkt; ++kt) {
;         const int buf = kt & 1;
;         if (kt + 1 < nkt) A_LOAD(kt + 1);
;         if (kt <= cq) {
;             LAS unsigned char* kb = lds + buf * ABUF; LAS unsigned char* vb = kb + KBYTES;
;             f32x16 s0, s1;
; #pragma unroll
;             for (int i = 0; i < 16; ++i) { s0[i] = 0.f; s1[i] = 0.f; }
;     ...
;             bf16x8 ka[3][2];
;             ka[0][0] = KLD(0, 0); ka[0][1] = KLD(0, 1); ka[1][0] = KLD(1, 0); ka[1][1] = KLD(1, 1);
; #pragma unroll
;             for (int ks = 0; ks < 12; ++ks) {
;                 if (ks + 2 < 12) { ka[(ks + 2) % 3][0] = KLD(ks + 2, 0); ka[(ks + 2) % 3][1] = KLD(ks + 2, 1); }
;                 s0 = __builtin_amdgcn_mfma_f32_32x32x16_bf16(ka[ks % 3][0], qf[ks], s0, 0, 0, 0); s1 = __builtin_amdgcn_mfma_f32_32x32x16_bf16(ka[ks % 3][1], qf[ks], s1, 0, 0, 0);
;                 __builtin_amdgcn_sched_barrier(0); }
;             u32x4 vf[2][4];
; #pragma unroll
;             for (int dt = 0; dt < 4; ++dt) VLD(vf[0][dt], 0, dt);
;             float mx = s0[0];
; #pragma unroll
;             for (int i = 1; i < 16; ++i) mx = fmaxf(mx, s0[i]);
; #pragma unroll
;             for (int i = 0; i < 16; ++i) mx = fmaxf(mx, s1[i]);
;             mx = fmaxf(mx, shfl_xor_l(mx, lane, 32));
;             const float mnew = fmaxf(mrow, mx), alpha = __builtin_amdgcn_exp2f(mrow - mnew); mrow = mnew;
.LBB0_1079:
	v_lshl_add_u64 v[66:67], s[24:25], 0, v[194:195]
	v_add_co_u32_e32 v68, vcc, 0x11140000, v66
	s_and_b32 s65, s64, 1
	s_nop 0
	v_addc_co_u32_e32 v69, vcc, 0, v67, vcc
	v_add_co_u32_e32 v66, vcc, 0x11160000, v66
	s_cmp_gt_u32 s64, s62
	s_nop 0
	v_addc_co_u32_e32 v67, vcc, 0, v67, vcc
	global_load_dwordx4 v[146:149], v[68:69], off
	global_load_dwordx4 v[150:153], v[66:67], off
	v_lshl_add_u64 v[68:69], s[24:25], 0, v[190:191]
	v_add_co_u32_e32 v70, vcc, 0x13100000, v68
	v_lshl_add_u64 v[66:67], s[24:25], 0, v[192:193]
	s_nop 0
	v_addc_co_u32_e32 v71, vcc, 0, v69, vcc
	global_load_dwordx4 v[154:157], v[66:67], off
	global_load_dwordx4 v[158:161], v[70:71], off offset:128
	v_add_co_u32_e32 v66, vcc, 0x13200000, v68
	s_nop 1
	v_addc_co_u32_e32 v67, vcc, 0, v69, vcc
	global_load_dwordx4 v[162:165], v[66:67], off offset:128
	s_cbranch_scc1 .LBB0_1083
	s_mul_i32 s66, s65, 0xa800
	s_add_i32 s66, s66, 0
	v_add3_u32 v171, s66, v199, v202
	ds_read_b128 v[66:69], v171
	ds_read_b128 v[166:169], v171 offset:32
	ds_read_b128 v[82:85], v171 offset:12800
	ds_read_b128 v[172:175], v171 offset:64
	ds_read_b128 v[176:179], v171 offset:12832
	ds_read_b128 v[204:207], v171 offset:12864
	s_waitcnt lgkmcnt(3)
	v_mfma_f32_32x32x16_bf16 v[82:97], v[82:85], v[142:145], 0
	v_mfma_f32_32x32x16_bf16 v[66:81], v[66:69], v[142:145], 0
	v_mfma_f32_32x32x16_bf16 v[66:81], v[166:169], v[138:141], v[66:81]
	ds_read_b128 v[166:169], v171 offset:96
	ds_read_b128 v[208:211], v171 offset:12896
	s_waitcnt lgkmcnt(3)
	v_mfma_f32_32x32x16_bf16 v[82:97], v[176:179], v[138:141], v[82:97]
	v_mfma_f32_32x32x16_bf16 v[66:81], v[172:175], v[134:137], v[66:81]
	ds_read_b128 v[172:175], v171 offset:128
	ds_read_b128 v[176:179], v171 offset:12928
	s_waitcnt lgkmcnt(4)
	v_mfma_f32_32x32x16_bf16 v[82:97], v[204:207], v[134:137], v[82:97]
	s_waitcnt lgkmcnt(3)
	v_mfma_f32_32x32x16_bf16 v[66:81], v[166:169], v[130:133], v[66:81]
	ds_read_b128 v[166:169], v171 offset:160
	ds_read_b128 v[204:207], v171 offset:12960
	s_waitcnt lgkmcnt(4)
	v_mfma_f32_32x32x16_bf16 v[82:97], v[208:211], v[130:133], v[82:97]
	s_waitcnt lgkmcnt(3)
	v_mfma_f32_32x32x16_bf16 v[66:81], v[172:175], v[126:129], v[66:81]
	ds_read_b128 v[172:175], v171 offset:192
	ds_read_b128 v[208:211], v171 offset:12992
	s_waitcnt lgkmcnt(4)
	v_mfma_f32_32x32x16_bf16 v[82:97], v[176:179], v[126:129], v[82:97]
	s_waitcnt lgkmcnt(3)
	v_mfma_f32_32x32x16_bf16 v[66:81], v[166:169], v[122:125], v[66:81]
	ds_read_b128 v[166:169], v171 offset:224
	ds_read_b128 v[176:179], v171 offset:13024
	s_waitcnt lgkmcnt(4)
	v_mfma_f32_32x32x16_bf16 v[82:97], v[204:207], v[122:125], v[82:97]
	s_waitcnt lgkmcnt(3)
	v_mfma_f32_32x32x16_bf16 v[66:81], v[172:175], v[118:121], v[66:81]
	ds_read_b128 v[172:175], v171 offset:256
	ds_read_b128 v[204:207], v171 offset:13056
	s_waitcnt lgkmcnt(4)
	v_mfma_f32_32x32x16_bf16 v[82:97], v[208:211], v[118:121], v[82:97]
	s_waitcnt lgkmcnt(3)
	v_mfma_f32_32x32x16_bf16 v[66:81], v[166:169], v[114:117], v[66:81]
	ds_read_b128 v[166:169], v171 offset:288
	ds_read_b128 v[208:211], v171 offset:13088
	s_waitcnt lgkmcnt(4)
	v_mfma_f32_32x32x16_bf16 v[82:97], v[176:179], v[114:117], v[82:97]
	s_waitcnt lgkmcnt(3)
	v_mfma_f32_32x32x16_bf16 v[66:81], v[172:175], v[110:113], v[66:81]
	ds_read_b128 v[172:175], v171 offset:320
	ds_read_b128 v[176:179], v171 offset:13120
	s_waitcnt lgkmcnt(4)
	v_mfma_f32_32x32x16_bf16 v[82:97], v[204:207], v[110:113], v[82:97]
	s_waitcnt lgkmcnt(3)
	v_mfma_f32_32x32x16_bf16 v[66:81], v[166:169], v[106:109], v[66:81]
	ds_read_b128 v[166:169], v171 offset:352
	ds_read_b128 v[212:215], v171 offset:13152
	s_waitcnt lgkmcnt(4)
	v_mfma_f32_32x32x16_bf16 v[82:97], v[208:211], v[106:109], v[82:97]
	s_waitcnt lgkmcnt(3)
	v_mfma_f32_32x32x16_bf16 v[66:81], v[172:175], v[102:105], v[66:81]
	s_waitcnt lgkmcnt(2)
	v_mfma_f32_32x32x16_bf16 v[82:97], v[176:179], v[102:105], v[82:97]
	s_waitcnt lgkmcnt(1)
	v_mfma_f32_32x32x16_bf16 v[66:81], v[166:169], v[98:101], v[66:81]
	v_add_u32_e32 v171, s66, v184
	v_add_u32_e32 v171, v171, v189
	v_add_u32_e32 v204, 0x6000, v171
	v_add_u32_e32 v205, 0x7000, v171
	v_add_u32_e32 v206, 0x8000, v171
	v_add_u32_e32 v207, 0x9000, v171
	ds_read2_b64 v[166:169], v204 offset0:128 offset1:130
	s_nop 4
	v_max_f32_e32 v172, v67, v67
	v_max_f32_e32 v173, v66, v66
	v_max_f32_e32 v172, v173, v172
	s_waitcnt lgkmcnt(1)
	v_mfma_f32_32x32x16_bf16 v[82:97], v[212:215], v[98:101], v[82:97]
	v_max3_f32 v172, v172, v68, v69
	v_max3_f32 v172, v172, v70, v71
	v_max3_f32 v172, v172, v72, v73
	v_max3_f32 v172, v172, v74, v75
	v_max3_f32 v172, v172, v76, v77
	v_max3_f32 v172, v172, v78, v79
	v_max3_f32 v172, v172, v80, v81
	s_nop 4
	v_max3_f32 v172, v172, v82, v83
	v_max3_f32 v172, v172, v84, v85
	v_max3_f32 v172, v172, v86, v87
	v_max3_f32 v172, v172, v88, v89
	v_max3_f32 v172, v172, v90, v91
	v_max3_f32 v172, v172, v92, v93
	v_max3_f32 v172, v172, v94, v95
	v_max3_f32 v172, v172, v96, v97
	ds_bpermute_b32 v173, v185, v172
	ds_read2_b64 v[178:181], v205 offset0:160 offset1:162
	ds_read2_b64 v[174:177], v206 offset0:192 offset1:194
	s_waitcnt lgkmcnt(2)
	v_max3_f32 v203, v170, v172, v173
	v_mov_b32_e32 v236, v170
	v_sub_f32_e32 v170, v170, v203
	v_cmp_gt_f32_e32 vcc, 0xc1000000, v170
	v_exp_f32_e32 v196, v170
	ds_read2_b64 v[170:173], v207 offset0:224 offset1:226
	s_cbranch_vccz .Lthr_0_keep
; DI void attn_unit(LAS unsigned char* lds, int wid, int b, int h, int qb) {
;     ...
;             if (__builtin_amdgcn_ballot_w64(alpha != 1.f) != 0ull) {
; #pragma unroll
;                 for (int dt = 0; dt < 4; ++dt)
; #pragma unroll
;                     for (int i = 0; i < 16; ++i) o[dt][i] *= alpha;
;             }
	v_mul_f32_e32 v64, v64, v196
	v_mul_f32_e32 v65, v65, v196
	v_mul_f32_e32 v62, v62, v196
	v_mul_f32_e32 v63, v63, v196
	v_mul_f32_e32 v60, v60, v196
	v_mul_f32_e32 v61, v61, v196
	v_mul_f32_e32 v58, v58, v196
	v_mul_f32_e32 v59, v59, v196
	v_mul_f32_e32 v56, v56, v196
	v_mul_f32_e32 v57, v57, v196
	v_mul_f32_e32 v54, v54, v196
	v_mul_f32_e32 v55, v55, v196
	v_mul_f32_e32 v52, v52, v196
	v_mul_f32_e32 v53, v53, v196
	v_mul_f32_e32 v50, v50, v196
	v_mul_f32_e32 v51, v51, v196
	v_mul_f32_e32 v48, v48, v196
	v_mul_f32_e32 v49, v49, v196
	v_mul_f32_e32 v46, v46, v196
	v_mul_f32_e32 v47, v47, v196
	v_mul_f32_e32 v44, v44, v196
	v_mul_f32_e32 v45, v45, v196
	v_mul_f32_e32 v42, v42, v196
	v_mul_f32_e32 v43, v43, v196
	v_mul_f32_e32 v40, v40, v196
	v_mul_f32_e32 v41, v41, v196
	v_mul_f32_e32 v38, v38, v196
	v_mul_f32_e32 v39, v39, v196
	v_mul_f32_e32 v36, v36, v196
	v_mul_f32_e32 v37, v37, v196
	v_mul_f32_e32 v34, v34, v196
	v_mul_f32_e32 v35, v35, v196
	v_mul_f32_e32 v32, v32, v196
	v_mul_f32_e32 v33, v33, v196
	v_mul_f32_e32 v30, v30, v196
	v_mul_f32_e32 v31, v31, v196
	v_mul_f32_e32 v28, v28, v196
	v_mul_f32_e32 v29, v29, v196
	v_mul_f32_e32 v26, v26, v196
	v_mul_f32_e32 v27, v27, v196
	v_mul_f32_e32 v24, v24, v196
	v_mul_f32_e32 v25, v25, v196
	v_mul_f32_e32 v22, v22, v196
	v_mul_f32_e32 v23, v23, v196
	v_mul_f32_e32 v20, v20, v196
	v_mul_f32_e32 v21, v21, v196
	v_mul_f32_e32 v18, v18, v196
	v_mul_f32_e32 v19, v19, v196
	v_mul_f32_e32 v16, v16, v196
	v_mul_f32_e32 v17, v17, v196
	v_mul_f32_e32 v14, v14, v196
	v_mul_f32_e32 v15, v15, v196
	v_mul_f32_e32 v12, v12, v196
	v_mul_f32_e32 v13, v13, v196
	v_mul_f32_e32 v10, v10, v196
	v_mul_f32_e32 v11, v11, v196
	v_mul_f32_e32 v8, v8, v196
	v_mul_f32_e32 v9, v9, v196
	v_mul_f32_e32 v6, v6, v196
	v_mul_f32_e32 v7, v7, v196
	v_mul_f32_e32 v4, v4, v196
	v_mul_f32_e32 v5, v5, v196
	v_mul_f32_e32 v2, v2, v196
	v_mul_f32_e32 v3, v3, v196

; #define LAS __attribute__((address_space(3)))
; DI float shfl_xor_l(float v, int lane, int m) { return __int_as_float(__builtin_amdgcn_ds_bpermute((lane ^ m) << 2, __float_as_int(v))); }
; #define VLD(dst, j, dt) do { LAS unsigned char* va_ = vb + (32 * (dt) + n) * VROW + (16 * (j) + 4 * g) * 2; const u32x2 lo_ = *(const LAS u32x2*)(va_), hi_ = *(const LAS u32x2*)(va_ + 16); dst = (u32x4){lo_.x, lo_.y, hi_.x, hi_.y}; } while (0)
; DI void attn_unit(LAS unsigned char* lds, int wid, int b, int h, int qb) {
;     ...
;         if (kt <= cq) {
;             LAS unsigned char* kb = lds + buf * ABUF; LAS unsigned char* vb = kb + KBYTES;
;             f32x16 s0, s1;
; #pragma unroll
;             for (int i = 0; i < 16; ++i) { s0[i] = 0.f; s1[i] = 0.f; }
;     ...
;             bf16x8 ka[3][2];
;             ka[0][0] = KLD(0, 0); ka[0][1] = KLD(0, 1); ka[1][0] = KLD(1, 0); ka[1][1] = KLD(1, 1);
; #pragma unroll
;             for (int ks = 0; ks < 12; ++ks) {
;                 if (ks + 2 < 12) { ka[(ks + 2) % 3][0] = KLD(ks + 2, 0); ka[(ks + 2) % 3][1] = KLD(ks + 2, 1); }
;                 s0 = __builtin_amdgcn_mfma_f32_32x32x16_bf16(ka[ks % 3][0], qf[ks], s0, 0, 0, 0); s1 = __builtin_amdgcn_mfma_f32_32x32x16_bf16(ka[ks % 3][1], qf[ks], s1, 0, 0, 0);
;                 __builtin_amdgcn_sched_barrier(0); }
;             u32x4 vf[2][4];
; #pragma unroll
;             for (int dt = 0; dt < 4; ++dt) VLD(vf[0][dt], 0, dt);
;             float mx = s0[0];
; #pragma unroll
;             for (int i = 1; i < 16; ++i) mx = fmaxf(mx, s0[i]);
; #pragma unroll
;             for (int i = 0; i < 16; ++i) mx = fmaxf(mx, s1[i]);
;             mx = fmaxf(mx, shfl_xor_l(mx, lane, 32));
;             const float mnew = fmaxf(mrow, mx), alpha = __builtin_amdgcn_exp2f(mrow - mnew); mrow = mnew;
;             float ls = 0.f;
; #pragma unroll
;             for (int i = 0; i < 16; ++i) { s0[i] = __builtin_amdgcn_exp2f(s0[i] - mnew); s1[i] = __builtin_amdgcn_exp2f(s1[i] - mnew); ls += s0[i] + s1[i]; }
;             lrow = lrow * alpha + ls;
;             if (__builtin_amdgcn_ballot_w64(alpha != 1.f) != 0ull) {
; #pragma unroll
;                 for (int dt = 0; dt < 4; ++dt)
; #pragma unroll
;                     for (int i = 0; i < 16; ++i) o[dt][i] *= alpha;
;             }
.LBB0_1086:
	s_or_b32 s61, s61, 2
	s_cmp_ge_u32 s61, s62
	s_cbranch_scc1 .LBB0_1090
	s_bitcmp1_b32 s63, 0
	s_cselect_b32 s61, 0xa800, 0
	s_add_i32 s61, s61, 0
	v_add3_u32 v162, s61, v199, v202
	ds_read_b128 v[66:69], v162
	ds_read_b128 v[146:149], v162 offset:32
	ds_read_b128 v[82:85], v162 offset:12800
	ds_read_b128 v[150:153], v162 offset:64
	ds_read_b128 v[154:157], v162 offset:12832
	ds_read_b128 v[158:161], v162 offset:12864
	s_waitcnt lgkmcnt(3)
	v_mfma_f32_32x32x16_bf16 v[82:97], v[82:85], v[142:145], 0
	v_mfma_f32_32x32x16_bf16 v[66:81], v[66:69], v[142:145], 0
	v_mfma_f32_32x32x16_bf16 v[66:81], v[146:149], v[138:141], v[66:81]
	ds_read_b128 v[142:145], v162 offset:96
	ds_read_b128 v[146:149], v162 offset:12896
	s_waitcnt lgkmcnt(3)
	v_mfma_f32_32x32x16_bf16 v[82:97], v[154:157], v[138:141], v[82:97]
	v_mfma_f32_32x32x16_bf16 v[66:81], v[150:153], v[134:137], v[66:81]
	ds_read_b128 v[138:141], v162 offset:128
	ds_read_b128 v[150:153], v162 offset:12928
	s_waitcnt lgkmcnt(4)
	v_mfma_f32_32x32x16_bf16 v[82:97], v[158:161], v[134:137], v[82:97]
	s_waitcnt lgkmcnt(3)
	v_mfma_f32_32x32x16_bf16 v[66:81], v[142:145], v[130:133], v[66:81]
	ds_read_b128 v[134:137], v162 offset:160
	ds_read_b128 v[142:145], v162 offset:12960
	s_waitcnt lgkmcnt(4)
	v_mfma_f32_32x32x16_bf16 v[82:97], v[146:149], v[130:133], v[82:97]
	s_waitcnt lgkmcnt(3)
	v_mfma_f32_32x32x16_bf16 v[66:81], v[138:141], v[126:129], v[66:81]
	ds_read_b128 v[130:133], v162 offset:192
	ds_read_b128 v[138:141], v162 offset:12992
	s_waitcnt lgkmcnt(4)
	v_mfma_f32_32x32x16_bf16 v[82:97], v[150:153], v[126:129], v[82:97]
	s_waitcnt lgkmcnt(3)
	v_mfma_f32_32x32x16_bf16 v[66:81], v[134:137], v[122:125], v[66:81]
	ds_read_b128 v[126:129], v162 offset:224
	ds_read_b128 v[134:137], v162 offset:13024
	s_waitcnt lgkmcnt(4)
	v_mfma_f32_32x32x16_bf16 v[82:97], v[142:145], v[122:125], v[82:97]
	s_waitcnt lgkmcnt(3)
	v_mfma_f32_32x32x16_bf16 v[66:81], v[130:133], v[118:121], v[66:81]
	ds_read_b128 v[122:125], v162 offset:256
	ds_read_b128 v[130:133], v162 offset:13056
	s_waitcnt lgkmcnt(4)
	v_mfma_f32_32x32x16_bf16 v[82:97], v[138:141], v[118:121], v[82:97]
	s_waitcnt lgkmcnt(3)
	v_mfma_f32_32x32x16_bf16 v[66:81], v[126:129], v[114:117], v[66:81]
	ds_read_b128 v[118:121], v162 offset:288
	ds_read_b128 v[126:129], v162 offset:13088
	s_waitcnt lgkmcnt(4)
	v_mfma_f32_32x32x16_bf16 v[82:97], v[134:137], v[114:117], v[82:97]
	s_waitcnt lgkmcnt(3)
	v_mfma_f32_32x32x16_bf16 v[66:81], v[122:125], v[110:113], v[66:81]
	ds_read_b128 v[114:117], v162 offset:320
	ds_read_b128 v[122:125], v162 offset:13120
	s_waitcnt lgkmcnt(4)
	v_mfma_f32_32x32x16_bf16 v[82:97], v[130:133], v[110:113], v[82:97]
	s_waitcnt lgkmcnt(3)
	v_mfma_f32_32x32x16_bf16 v[66:81], v[118:121], v[106:109], v[66:81]
	ds_read_b128 v[110:113], v162 offset:352
	ds_read_b128 v[118:121], v162 offset:13152
	s_waitcnt lgkmcnt(4)
	v_mfma_f32_32x32x16_bf16 v[82:97], v[126:129], v[106:109], v[82:97]
	s_waitcnt lgkmcnt(3)
	v_mfma_f32_32x32x16_bf16 v[66:81], v[114:117], v[102:105], v[66:81]
	s_waitcnt lgkmcnt(2)
	v_mfma_f32_32x32x16_bf16 v[82:97], v[122:125], v[102:105], v[82:97]
	s_waitcnt lgkmcnt(1)
	v_mfma_f32_32x32x16_bf16 v[66:81], v[110:113], v[98:101], v[66:81]
	v_add_u32_e32 v102, s61, v184
	v_add_u32_e32 v122, v102, v189
	v_add_u32_e32 v115, 0x6000, v122
	v_add_u32_e32 v116, 0x7000, v122
	v_add_u32_e32 v117, 0x8000, v122
	ds_read2_b64 v[102:105], v115 offset0:128 offset1:130
	ds_read2_b64 v[110:113], v116 offset0:160 offset1:162
	s_nop 4
	v_max_f32_e32 v106, v67, v67
	v_max_f32_e32 v107, v66, v66
	v_max_f32_e32 v106, v107, v106
	s_waitcnt lgkmcnt(2)
	v_mfma_f32_32x32x16_bf16 v[82:97], v[118:121], v[98:101], v[82:97]
	v_max3_f32 v106, v106, v68, v69
	v_max3_f32 v106, v106, v70, v71
	v_max3_f32 v106, v106, v72, v73
	v_max3_f32 v106, v106, v74, v75
	v_max3_f32 v106, v106, v76, v77
	v_max3_f32 v106, v106, v78, v79
	v_max3_f32 v106, v106, v80, v81
	s_nop 4
	v_max3_f32 v98, v106, v82, v83
	v_max3_f32 v98, v98, v84, v85
	v_max3_f32 v98, v98, v86, v87
	v_max3_f32 v98, v98, v88, v89
	v_max3_f32 v98, v98, v90, v91
	v_max3_f32 v98, v98, v92, v93
	v_max3_f32 v98, v98, v94, v95
	v_max3_f32 v98, v98, v96, v97
	ds_bpermute_b32 v99, v185, v98
	v_add_u32_e32 v118, 0x9000, v122
	ds_read2_b64 v[106:109], v117 offset0:192 offset1:194
	s_waitcnt lgkmcnt(1)
	v_max3_f32 v119, v203, v98, v99
	v_mov_b32_e32 v236, v203
	v_sub_f32_e32 v98, v203, v119
	v_cmp_gt_f32_e32 vcc, 0xc1000000, v98
	v_exp_f32_e32 v114, v98
	ds_read2_b64 v[98:101], v118 offset0:224 offset1:226
	s_cbranch_vccz .Lthr_1_keep
	v_mul_f32_e32 v64, v64, v114
	v_mul_f32_e32 v65, v65, v114
	v_mul_f32_e32 v62, v62, v114
	v_mul_f32_e32 v63, v63, v114
	v_mul_f32_e32 v60, v60, v114
	v_mul_f32_e32 v61, v61, v114
	v_mul_f32_e32 v58, v58, v114
	v_mul_f32_e32 v59, v59, v114
	v_mul_f32_e32 v56, v56, v114
	v_mul_f32_e32 v57, v57, v114
	v_mul_f32_e32 v54, v54, v114
	v_mul_f32_e32 v55, v55, v114
	v_mul_f32_e32 v52, v52, v114
	v_mul_f32_e32 v53, v53, v114
	v_mul_f32_e32 v50, v50, v114
	v_mul_f32_e32 v51, v51, v114
	v_mul_f32_e32 v48, v48, v114
	v_mul_f32_e32 v49, v49, v114
	v_mul_f32_e32 v46, v46, v114
	v_mul_f32_e32 v47, v47, v114
	v_mul_f32_e32 v44, v44, v114
	v_mul_f32_e32 v45, v45, v114
	v_mul_f32_e32 v42, v42, v114
	v_mul_f32_e32 v43, v43, v114
	v_mul_f32_e32 v40, v40, v114
	v_mul_f32_e32 v41, v41, v114
	v_mul_f32_e32 v38, v38, v114
	v_mul_f32_e32 v39, v39, v114
	v_mul_f32_e32 v36, v36, v114
	v_mul_f32_e32 v37, v37, v114
	v_mul_f32_e32 v34, v34, v114
	v_mul_f32_e32 v35, v35, v114
	v_mul_f32_e32 v32, v32, v114
	v_mul_f32_e32 v33, v33, v114
	v_mul_f32_e32 v30, v30, v114
	v_mul_f32_e32 v31, v31, v114
	v_mul_f32_e32 v28, v28, v114
	v_mul_f32_e32 v29, v29, v114
	v_mul_f32_e32 v26, v26, v114
	v_mul_f32_e32 v27, v27, v114
	v_mul_f32_e32 v24, v24, v114
	v_mul_f32_e32 v25, v25, v114
	v_mul_f32_e32 v22, v22, v114
	v_mul_f32_e32 v23, v23, v114
	v_mul_f32_e32 v20, v20, v114
	v_mul_f32_e32 v21, v21, v114
	v_mul_f32_e32 v18, v18, v114
	v_mul_f32_e32 v19, v19, v114
	v_mul_f32_e32 v16, v16, v114
	v_mul_f32_e32 v17, v17, v114
	v_mul_f32_e32 v14, v14, v114
	v_mul_f32_e32 v15, v15, v114
	v_mul_f32_e32 v12, v12, v114
	v_mul_f32_e32 v13, v13, v114
	v_mul_f32_e32 v10, v10, v114
	v_mul_f32_e32 v11, v11, v114
	v_mul_f32_e32 v8, v8, v114
	v_mul_f32_e32 v9, v9, v114
	v_mul_f32_e32 v6, v6, v114
	v_mul_f32_e32 v7, v7, v114
	v_mul_f32_e32 v4, v4, v114
	v_mul_f32_e32 v5, v5, v114
	v_mul_f32_e32 v2, v2, v114
	v_mul_f32_e32 v3, v3, v114

; #define LAS __attribute__((address_space(3)))
; DI u32x2 pk4(f32x4 v) { u32x2 r; r.x = pk2(v[0], v[1]); r.y = pk2(v[2], v[3]); return r; }
; DI float shfl_xor_l(float v, int lane, int m) { return __int_as_float(__builtin_amdgcn_ds_bpermute((lane ^ m) << 2, __float_as_int(v))); }
; DI void attn_unit(LAS unsigned char* lds, int wid, int b, int h, int qb) {
;     ...
;     const float lt = lrow + shfl_xor_l(lrow, lane, 32), inv = 1.f / lt;
;     LAS unsigned char* pt_ = lds + ABUF + wid * (32 * 272);
; #pragma unroll
;     for (int dt = 0; dt < 4; ++dt)
; #pragma unroll
;         for (int blk = 0; blk < 4; ++blk) { const f32x4 v = {o[dt][4 * blk] * inv, o[dt][4 * blk + 1] * inv, o[dt][4 * blk + 2] * inv, o[dt][4 * blk + 3] * inv};
;             *(LAS u32x2*)(pt_ + n * 272 + (32 * dt + 8 * blk + 4 * g) * 2) = pk4(v); }
;     asm volatile("" ::: "memory");
;     bf16_t* od = WSB(OFF_O) + ((size_t)b * SEQ + q0 + (lane >> 4)) * 2048 + h * 128 + (lane & 15) * 8;
; #pragma unroll
;     for (int j = 0; j < 8; ++j) { const u32x4 w = *(const LAS u32x4*)(pt_ + (4 * j + (lane >> 4)) * 272 + (lane & 15) * 16); *(u32x4*)(od + (size_t)(4 * j) * 2048) = w; }
.LBB0_1090:
	ds_bpermute_b32 v66, v185, v187
	s_waitcnt lgkmcnt(0)
	s_barrier
	v_mov_b32_e32 v185, v1
	v_add_f32_e32 v66, v187, v66
	v_div_scale_f32 v67, s[62:63], v66, v66, 1.0
	v_rcp_f32_e32 v68, v67
	v_div_scale_f32 v69, vcc, 1.0, v66, 1.0
	v_mov_b32_e32 v187, v201
	v_fma_f32 v70, -v67, v68, 1.0
	v_fmac_f32_e32 v68, v70, v68
	v_mul_f32_e32 v70, v69, v68
	v_fma_f32 v71, -v67, v70, v69
	v_fmac_f32_e32 v70, v71, v68
	v_fma_f32 v67, -v67, v70, v69
	v_div_fmas_f32 v67, v67, v68, v70
	v_div_fixup_f32 v66, v67, v66, 1.0
	v_mul_u32_u24_e32 v67, 0x110, v197
	v_add3_u32 v67, s30, v67, v184
	v_mul_f32_e32 v2, v2, v66
	v_mul_f32_e32 v3, v3, v66
	v_mul_f32_e32 v4, v4, v66
	v_mul_f32_e32 v5, v5, v66
	v_mul_f32_e32 v50, v50, v66
	v_mul_f32_e32 v51, v51, v66
	v_mul_f32_e32 v52, v52, v66
	v_mul_f32_e32 v53, v53, v66
	v_cvt_pk_bf16_f32 v2, v2, v3
	v_cvt_pk_bf16_f32 v3, v4, v5
	v_mul_f32_e32 v4, v6, v66
	v_mul_f32_e32 v5, v7, v66
	v_mul_f32_e32 v6, v8, v66
	v_mul_f32_e32 v7, v9, v66
	v_cvt_pk_bf16_f32 v50, v50, v51
	v_cvt_pk_bf16_f32 v51, v52, v53
	v_mul_f32_e32 v52, v54, v66
	v_mul_f32_e32 v53, v55, v66
	v_mul_f32_e32 v54, v56, v66
	v_mul_f32_e32 v55, v57, v66
	v_add_u32_e32 v56, 0xa800, v67
	v_cvt_pk_bf16_f32 v4, v4, v5
	v_cvt_pk_bf16_f32 v5, v6, v7
	ds_write2_b64 v56, v[2:3], v[4:5] offset0:24 offset1:26
	v_mul_f32_e32 v2, v10, v66
	v_mul_f32_e32 v3, v11, v66
	v_mul_f32_e32 v4, v12, v66
	v_mul_f32_e32 v5, v13, v66
	v_mul_f32_e32 v34, v34, v66
	v_mul_f32_e32 v35, v35, v66
	v_mul_f32_e32 v36, v36, v66
	v_mul_f32_e32 v37, v37, v66
	v_mul_f32_e32 v18, v18, v66
	v_mul_f32_e32 v19, v19, v66
	v_mul_f32_e32 v20, v20, v66
	v_mul_f32_e32 v21, v21, v66
	v_cvt_pk_bf16_f32 v2, v2, v3
	v_cvt_pk_bf16_f32 v3, v4, v5
	v_mul_f32_e32 v4, v14, v66
	v_mul_f32_e32 v5, v15, v66
	v_mul_f32_e32 v6, v16, v66
	v_mul_f32_e32 v7, v17, v66
	v_cvt_pk_bf16_f32 v34, v34, v35
	v_cvt_pk_bf16_f32 v35, v36, v37
	v_mul_f32_e32 v36, v38, v66
	v_mul_f32_e32 v37, v39, v66
	v_mul_f32_e32 v38, v40, v66
	v_mul_f32_e32 v39, v41, v66
	v_cvt_pk_bf16_f32 v18, v18, v19
	v_cvt_pk_bf16_f32 v19, v20, v21
	v_mul_f32_e32 v20, v22, v66
	v_mul_f32_e32 v21, v23, v66
	v_mul_f32_e32 v22, v24, v66
	v_mul_f32_e32 v23, v25, v66
	v_cvt_pk_bf16_f32 v4, v4, v5
	v_cvt_pk_bf16_f32 v5, v6, v7
	v_cvt_pk_bf16_f32 v52, v52, v53
	v_cvt_pk_bf16_f32 v53, v54, v55
	v_cvt_pk_bf16_f32 v36, v36, v37
	v_cvt_pk_bf16_f32 v37, v38, v39
	v_cvt_pk_bf16_f32 v20, v20, v21
	v_cvt_pk_bf16_f32 v21, v22, v23
	ds_write2_b64 v56, v[2:3], v[4:5] offset0:28 offset1:30
	v_ashrrev_i32_e32 v2, 4, v183
	ds_write2_b64 v56, v[50:51], v[52:53] offset1:2
	v_mul_f32_e32 v50, v58, v66
	v_mul_f32_e32 v51, v59, v66
	v_mul_f32_e32 v52, v60, v66
	v_mul_f32_e32 v53, v61, v66
	ds_write2_b64 v56, v[34:35], v[36:37] offset0:8 offset1:10
	v_mul_f32_e32 v34, v42, v66
	v_mul_f32_e32 v35, v43, v66
	v_mul_f32_e32 v36, v44, v66
	v_mul_f32_e32 v37, v45, v66
	ds_write2_b64 v56, v[18:19], v[20:21] offset0:16 offset1:18
	v_mul_f32_e32 v18, v26, v66
	v_mul_f32_e32 v19, v27, v66
	v_mul_f32_e32 v20, v28, v66
	v_mul_f32_e32 v21, v29, v66
	v_ashrrev_i32_e32 v3, 31, v2
	v_cvt_pk_bf16_f32 v50, v50, v51
	v_cvt_pk_bf16_f32 v51, v52, v53
	v_mul_f32_e32 v52, v62, v66
	v_mul_f32_e32 v53, v63, v66
	v_mul_f32_e32 v54, v64, v66
	v_mul_f32_e32 v55, v65, v66
	v_cvt_pk_bf16_f32 v34, v34, v35
	v_cvt_pk_bf16_f32 v35, v36, v37
	v_mul_f32_e32 v36, v46, v66
	v_mul_f32_e32 v37, v47, v66
	v_mul_f32_e32 v38, v48, v66
	v_mul_f32_e32 v39, v49, v66
	v_cvt_pk_bf16_f32 v18, v18, v19
	v_cvt_pk_bf16_f32 v19, v20, v21
	v_mul_f32_e32 v20, v30, v66
	v_mul_f32_e32 v21, v31, v66
	v_mul_f32_e32 v22, v32, v66
	v_mul_f32_e32 v23, v33, v66
	v_lshl_add_u64 v[4:5], s[26:27], 0, v[2:3]
	v_cvt_pk_bf16_f32 v52, v52, v53
	v_cvt_pk_bf16_f32 v53, v54, v55
	v_cvt_pk_bf16_f32 v36, v36, v37
	v_cvt_pk_bf16_f32 v37, v38, v39
	v_cvt_pk_bf16_f32 v20, v20, v21
	v_cvt_pk_bf16_f32 v21, v22, v23
	v_lshlrev_b64 v[4:5], 12, v[4:5]
	ds_write2_b64 v56, v[50:51], v[52:53] offset0:4 offset1:6
	ds_write2_b64 v56, v[34:35], v[36:37] offset0:12 offset1:14
	ds_write2_b64 v56, v[18:19], v[20:21] offset0:20 offset1:22
	v_lshl_add_u64 v[4:5], s[24:25], 0, v[4:5]
	s_lshl_b32 s24, s4, 1
	s_mov_b32 s25, s5
	v_mul_lo_u32 v2, v2, s46
	v_lshl_add_u64 v[4:5], v[4:5], 0, s[24:25]
	v_lshlrev_b32_e32 v6, 1, v182
	v_mov_b32_e32 v7, v1
	v_add3_u32 v0, s30, v0, v2
	v_lshl_add_u64 v[10:11], v[4:5], 0, v[6:7]
	ds_read_b128 v[2:5], v0 offset:43008
	ds_read_b128 v[6:9], v0 offset:44096
	v_add_co_u32_e32 v12, vcc, s47, v10
	s_mov_b64 s[26:27], s[0:1]
	s_nop 0
	v_addc_co_u32_e32 v13, vcc, 0, v11, vcc
	s_waitcnt lgkmcnt(1)
	global_store_dwordx4 v[12:13], v[2:5], off
	v_mov_b32_e32 v172, 0xff800000
	s_nop 0
	v_add_co_u32_e32 v2, vcc, s48, v10
	s_nop 1
	v_addc_co_u32_e32 v3, vcc, 0, v11, vcc
	s_waitcnt lgkmcnt(0)
	global_store_dwordx4 v[2:3], v[6:9], off
	ds_read_b128 v[2:5], v0 offset:45184
	ds_read_b128 v[6:9], v0 offset:46272
	v_add_co_u32_e32 v12, vcc, s49, v10
	s_nop 1
	v_addc_co_u32_e32 v13, vcc, 0, v11, vcc
	s_waitcnt lgkmcnt(1)
	global_store_dwordx4 v[12:13], v[2:5], off
	s_nop 1
	v_add_co_u32_e32 v2, vcc, s50, v10
	s_nop 1
	v_addc_co_u32_e32 v3, vcc, 0, v11, vcc
	s_waitcnt lgkmcnt(0)
	global_store_dwordx4 v[2:3], v[6:9], off
	ds_read_b128 v[2:5], v0 offset:47360
	ds_read_b128 v[6:9], v0 offset:48448
	v_add_co_u32_e32 v12, vcc, s51, v10
	s_nop 1
	v_addc_co_u32_e32 v13, vcc, 0, v11, vcc
	s_waitcnt lgkmcnt(1)
	global_store_dwordx4 v[12:13], v[2:5], off
	s_nop 1
	v_add_co_u32_e32 v2, vcc, s52, v10
	s_nop 1
	v_addc_co_u32_e32 v3, vcc, 0, v11, vcc
	s_waitcnt lgkmcnt(0)
; DI CP* kparams() { CP* kp = (CP*)__builtin_amdgcn_kernarg_segment_ptr(); asm volatile("" : "+s"(kp)); return kp; }
; DI int lane_id() { int l = __builtin_amdgcn_mbcnt_hi(-1, __builtin_amdgcn_mbcnt_lo(-1, 0)); asm volatile("" : "+v"(l)); return l; }
; #define A_LOAD(kt) do { const size_t ko = (size_t)(kt) * 64; st0 = *(const u32x4*)(kn_src + ko * 2048); st1 = *(const u32x4*)(kn_src + (ko + 32) * 2048); \
;         st2 = *(const u32x4*)(kr_src + ko * 64); st3 = *(const u32x4*)(v_src + ko); st4 = *(const u32x4*)(v_src + ko + (size_t)64 * 8192); } while (0)
; DI void attn_unit(LAS unsigned char* lds, int wid, int b, int h, int qb) {
;     CP& p = *kparams();
;     const int lane = lane_id(), tid = wid * 64 + lane, n = lane & 31, g = lane >> 5;
;     const int q0 = qb * 256 + wid * 32, cq = q0 >> 6, nkt = 4 * qb + 4;
;     const size_t tokq = (size_t)b * SEQ + q0 + n;
;     const bf16_t* Q = WSB(OFF_Q); const bf16_t* KN = WSB(OFF_KN); const bf16_t* KR = WSB(OFF_KR); const bf16_t* VT = WSB(OFF_VT2);
;     bf16x8 qf[12];
; #pragma unroll
;     for (int ks = 0; ks < 12; ++ks) qf[ks] = *(const bf16x8*)(Q + tokq * 3072 + h * 192 + ks * 16 + g * 8);
;     f32x16 o[4];
; #pragma unroll
;     for (int dt = 0; dt < 4; ++dt)
; #pragma unroll
;         for (int i = 0; i < 16; ++i) o[dt][i] = 0.f;
;     float mrow = -__builtin_inff(), lrow = 0.f;
;     const int krow = tid >> 4, kc16 = tid & 15, rrow = tid >> 3, rc8 = tid & 7;
;     const bf16_t* kn_src = KN + ((size_t)b * SEQ + krow) * 2048 + h * 128 + kc16 * 8;
;     const bf16_t* kr_src = KR + ((size_t)b * SEQ + rrow) * 64 + rc8 * 8;
;     const bf16_t* v_src = VT + ((size_t)h * 128 + rrow) * 8192 + (size_t)b * SEQ + rc8 * 8;
;     const int kn_dst = krow * KROW + kc16 * 16, kr_dst = rrow * KROW + 256 + rc8 * 16, v_dst = KBYTES + rrow * VROW + rc8 * 16;
;     u32x4 st0, st1, st2, st3, st4;
;     ...
;     A_LOAD(0); A_WRITE(0); __syncthreads();
	global_store_dwordx4 v[2:3], v[6:9], off
	ds_read_b128 v[2:5], v0 offset:49536
	ds_read_b128 v[6:9], v0 offset:50624
	v_add_co_u32_e32 v12, vcc, s53, v10
	s_nop 1
	v_addc_co_u32_e32 v13, vcc, 0, v11, vcc
	s_waitcnt lgkmcnt(1)
	global_store_dwordx4 v[12:13], v[2:5], off
	s_nop 1
	v_add_co_u32_e32 v2, vcc, s54, v10
	s_nop 1
	v_addc_co_u32_e32 v3, vcc, 0, v11, vcc
	s_waitcnt lgkmcnt(0)
	global_store_dwordx4 v[2:3], v[6:9], off
	s_load_dwordx2 s[26:27], s[26:27], 0xa8
	v_add_u32_e32 v0, s28, v187
	v_ashrrev_i32_e32 v24, 3, v0
	v_ashrrev_i32_e32 v25, 31, v24
	v_ashrrev_i32_e32 v22, 4, v0
	v_lshl_add_u64 v[4:5], s[16:17], 0, v[24:25]
	v_ashrrev_i32_e32 v23, 31, v22
	v_lshlrev_b64 v[4:5], 7, v[4:5]
	v_lshlrev_b32_e32 v0, 4, v187
	v_lshl_add_u64 v[2:3], s[16:17], 0, v[22:23]
	s_waitcnt lgkmcnt(0)
	v_lshl_add_u64 v[4:5], s[26:27], 0, v[4:5]
	v_and_b32_e32 v0, 0x70, v0
	v_lshlrev_b64 v[2:3], 12, v[2:3]
	v_lshl_add_u64 v[10:11], v[4:5], 0, v[0:1]
	v_lshl_add_u64 v[4:5], v[24:25], 0, s[4:5]
	v_and_b32_e32 v30, 15, v187
	v_lshl_add_u64 v[2:3], s[26:27], 0, v[2:3]
	v_lshlrev_b64 v[4:5], 14, v[4:5]
	v_lshl_add_u64 v[2:3], v[2:3], 0, s[24:25]
	v_lshlrev_b32_e32 v184, 4, v30
	v_lshl_add_u64 v[4:5], s[26:27], 0, v[4:5]
	v_lshl_add_u64 v[2:3], v[2:3], 0, v[184:185]
	v_lshl_add_u64 v[4:5], s[16:17], 1, v[4:5]
	v_lshl_add_u64 v[18:19], v[4:5], 0, v[0:1]
	v_add_co_u32_e32 v4, vcc, s40, v2
	s_and_b32 s4, s57, 7
	s_nop 0
	v_addc_co_u32_e32 v5, vcc, 0, v3, vcc
	v_add_co_u32_e32 v6, vcc, s41, v2
	s_lshl_b32 s4, s4, 2
	s_lshl_b32 s25, s56, 8
	v_addc_co_u32_e32 v7, vcc, 0, v3, vcc
	s_or_b32 s4, s4, 3
	s_add_i32 s25, s25, s29
	v_add_co_u32_e32 v10, vcc, s42, v10
	v_and_b32_e32 v202, 31, v187
	s_add_u32 s16, s16, s25
	v_addc_co_u32_e32 v11, vcc, 0, v11, vcc
	v_or_b32_e32 v28, s16, v202
	v_mov_b64_e32 v[26:27], s[26:27]
	v_add_co_u32_e32 v14, vcc, s43, v18
	v_ashrrev_i32_e32 v31, 5, v187
	s_addc_u32 s17, s17, 0
	v_mad_u64_u32 v[26:27], s[62:63], v28, s37, v[26:27]
	v_addc_co_u32_e32 v15, vcc, 0, v19, vcc
	v_mad_i32_i24 v27, s17, v200, v27
	s_lshl_b32 s62, s58, 1
	s_mov_b32 s63, s5
	v_lshlrev_b32_e32 v188, 3, v31
	v_add_co_u32_e32 v18, vcc, s44, v18
	v_lshl_add_u64 v[26:27], v[26:27], 0, s[62:63]
	v_ashrrev_i32_e32 v189, 31, v188
	global_load_dwordx4 v[2:5], v[4:5], off
	s_nop 0
	global_load_dwordx4 v[6:9], v[6:7], off
	v_addc_co_u32_e32 v19, vcc, 0, v19, vcc
	v_lshl_add_u64 v[26:27], v[188:189], 1, v[26:27]
	global_load_dwordx4 v[10:13], v[10:11], off
	v_lshl_add_u64 v[28:29], v[26:27], 0, s[8:9]
	v_add_co_u32_e32 v26, vcc, s38, v26
	global_load_dwordx4 v[14:17], v[14:15], off
	s_nop 0
	v_addc_co_u32_e32 v27, vcc, 0, v27, vcc
	global_load_dwordx4 v[18:21], v[18:19], off
	s_nop 0
	global_load_dwordx4 v[152:155], v[28:29], off offset:32
	global_load_dwordx4 v[148:151], v[28:29], off offset:64
	global_load_dwordx4 v[144:147], v[28:29], off offset:96
	global_load_dwordx4 v[140:143], v[28:29], off offset:128
	global_load_dwordx4 v[136:139], v[28:29], off offset:160
	global_load_dwordx4 v[132:135], v[28:29], off offset:192
	global_load_dwordx4 v[128:131], v[28:29], off offset:224
	global_load_dwordx4 v[124:127], v[28:29], off offset:256
	global_load_dwordx4 v[120:123], v[28:29], off offset:288
	global_load_dwordx4 v[116:119], v[28:29], off offset:320
	global_load_dwordx4 v[156:159], v[26:27], off
	global_load_dwordx4 v[112:115], v[28:29], off offset:352
	v_mad_u64_u32 v[190:191], s[62:63], v22, s39, v[184:185]
	v_add_u32_e32 v26, 0, v190
	v_mad_u64_u32 v[192:193], s[62:63], v24, s39, v[0:1]
	s_waitcnt vmcnt(16)
	ds_write_b128 v26, v[2:5]
	s_waitcnt vmcnt(15)
	ds_write_b128 v26, v[6:9] offset:12800
	v_add_u32_e32 v2, 0, v192
	v_mul_lo_u32 v3, v24, s45
	s_lshr_b32 s25, s25, 6
	s_waitcnt vmcnt(14)
	ds_write_b128 v2, v[10:13] offset:256
	v_add_u32_e32 v2, v2, v3
	v_add_u32_e32 v203, v192, v3
	v_add_u32_e32 v3, 0x6400, v2
	v_add_u32_e32 v2, 0x8600, v2
	s_add_u32 s18, s18, s59
	s_waitcnt vmcnt(13)
	ds_write2_b64 v3, v[14:15], v[16:17] offset1:1
	s_waitcnt vmcnt(12)
	ds_write2_b64 v2, v[18:19], v[20:21] offset1:1
	v_lshlrev_b32_e32 v2, 2, v187
	v_xor_b32_e32 v189, 0x80, v2
	v_lshlrev_b64 v[2:3], 14, v[24:25]
	s_addc_u32 s19, s19, 0
	v_lshl_add_u64 v[2:3], s[18:19], 0, v[2:3]
	v_lshl_add_u64 v[194:195], v[2:3], 0, v[0:1]
	v_lshlrev_b64 v[2:3], 7, v[24:25]
	v_lshl_add_u64 v[2:3], s[20:21], 0, v[2:3]
	s_add_u32 s18, s60, s22
	v_lshl_add_u64 v[196:197], v[2:3], 0, v[0:1]
	v_lshlrev_b64 v[2:3], 12, v[22:23]
	s_addc_u32 s19, 0, s23
	v_lshl_add_u64 v[2:3], s[18:19], 0, v[2:3]
	v_mov_b32_e32 v14, v1
	v_mov_b32_e32 v15, v1
	v_lshlrev_b32_e32 v186, 3, v30
	v_lshlrev_b32_e32 v204, 4, v31
	v_lshl_add_u64 v[198:199], v[2:3], 0, v[184:185]
	v_mov_b32_e32 v0, v1
	v_mov_b32_e32 v2, v1
	v_mov_b32_e32 v3, v1
	v_mov_b32_e32 v4, v1
	v_mov_b32_e32 v5, v1
	v_mov_b32_e32 v6, v1
	v_mov_b32_e32 v7, v1
	v_mov_b32_e32 v8, v1
	v_mov_b32_e32 v9, v1
	v_mov_b32_e32 v10, v1
	v_mov_b32_e32 v11, v1
	v_mov_b32_e32 v12, v1
	v_mov_b32_e32 v13, v1
	v_mov_b64_e32 v[30:31], v[14:15]
	v_mov_b64_e32 v[46:47], v[14:15]
	v_mov_b64_e32 v[62:63], v[14:15]
	v_mov_b64_e32 v[78:79], v[14:15]
	s_mov_b32 s57, 0
	v_mul_u32_u24_e32 v193, 0x190, v202
	v_mul_u32_u24_e32 v191, 0x88, v202
	v_mov_b32_e32 v185, 0
	v_mov_b64_e32 v[28:29], v[12:13]
	v_mov_b64_e32 v[26:27], v[10:11]
	v_mov_b64_e32 v[24:25], v[8:9]
	v_mov_b64_e32 v[22:23], v[6:7]
	v_mov_b64_e32 v[20:21], v[4:5]
	v_mov_b64_e32 v[18:19], v[2:3]
	v_mov_b64_e32 v[16:17], v[0:1]
	v_mov_b64_e32 v[44:45], v[12:13]
	v_mov_b64_e32 v[42:43], v[10:11]
	v_mov_b64_e32 v[40:41], v[8:9]
	v_mov_b64_e32 v[38:39], v[6:7]
	v_mov_b64_e32 v[36:37], v[4:5]
	v_mov_b64_e32 v[34:35], v[2:3]
	v_mov_b64_e32 v[32:33], v[0:1]
	v_mov_b64_e32 v[60:61], v[12:13]
	v_mov_b64_e32 v[58:59], v[10:11]
	v_mov_b64_e32 v[56:57], v[8:9]
	v_mov_b64_e32 v[54:55], v[6:7]
	v_mov_b64_e32 v[52:53], v[4:5]
	v_mov_b64_e32 v[50:51], v[2:3]
	v_mov_b64_e32 v[48:49], v[0:1]
	v_mov_b64_e32 v[76:77], v[12:13]
	v_mov_b64_e32 v[74:75], v[10:11]
	v_mov_b64_e32 v[72:73], v[8:9]
	v_mov_b64_e32 v[70:71], v[6:7]
	v_mov_b64_e32 v[68:69], v[4:5]
	v_mov_b64_e32 v[66:67], v[2:3]
	v_mov_b64_e32 v[64:65], v[0:1]
	s_waitcnt lgkmcnt(0)
	s_barrier
; #define LAS __attribute__((address_space(3)))
; DI float shfl_xor_l(float v, int lane, int m) { return __int_as_float(__builtin_amdgcn_ds_bpermute((lane ^ m) << 2, __float_as_int(v))); }
; #define VLD(dst, j, dt) do { LAS unsigned char* va_ = vb + (32 * (dt) + n) * VROW + (16 * (j) + 4 * g) * 2; const u32x2 lo_ = *(const LAS u32x2*)(va_), hi_ = *(const LAS u32x2*)(va_ + 16); dst = (u32x4){lo_.x, lo_.y, hi_.x, hi_.y}; } while (0)
; DI void attn_unit(LAS unsigned char* lds, int wid, int b, int h, int qb) {
;     ...
;     for (int kt = 0; kt < nkt; ++kt) {
;         const int buf = kt & 1;
;         if (kt + 1 < nkt) A_LOAD(kt + 1);
;         if (kt <= cq) {
;             LAS unsigned char* kb = lds + buf * ABUF; LAS unsigned char* vb = kb + KBYTES;
;             f32x16 s0, s1;
; #pragma unroll
;             for (int i = 0; i < 16; ++i) { s0[i] = 0.f; s1[i] = 0.f; }
;     ...
;             bf16x8 ka[3][2];
;             ka[0][0] = KLD(0, 0); ka[0][1] = KLD(0, 1); ka[1][0] = KLD(1, 0); ka[1][1] = KLD(1, 1);
; #pragma unroll
;             for (int ks = 0; ks < 12; ++ks) {
;                 if (ks + 2 < 12) { ka[(ks + 2) % 3][0] = KLD(ks + 2, 0); ka[(ks + 2) % 3][1] = KLD(ks + 2, 1); }
;                 s0 = __builtin_amdgcn_mfma_f32_32x32x16_bf16(ka[ks % 3][0], qf[ks], s0, 0, 0, 0); s1 = __builtin_amdgcn_mfma_f32_32x32x16_bf16(ka[ks % 3][1], qf[ks], s1, 0, 0, 0);
;                 __builtin_amdgcn_sched_barrier(0); }
;             u32x4 vf[2][4];
; #pragma unroll
;             for (int dt = 0; dt < 4; ++dt) VLD(vf[0][dt], 0, dt);
;             float mx = s0[0];
; #pragma unroll
;             for (int i = 1; i < 16; ++i) mx = fmaxf(mx, s0[i]);
; #pragma unroll
;             for (int i = 0; i < 16; ++i) mx = fmaxf(mx, s1[i]);
;             mx = fmaxf(mx, shfl_xor_l(mx, lane, 32));
;             const float mnew = fmaxf(mrow, mx), alpha = __builtin_amdgcn_exp2f(mrow - mnew); mrow = mnew;
;             float ls = 0.f;
; #pragma unroll
;             for (int i = 0; i < 16; ++i) { s0[i] = __builtin_amdgcn_exp2f(s0[i] - mnew); s1[i] = __builtin_amdgcn_exp2f(s1[i] - mnew); ls += s0[i] + s1[i]; }
;             lrow = lrow * alpha + ls;
;             if (__builtin_amdgcn_ballot_w64(alpha != 1.f) != 0ull) {
; #pragma unroll
;                 for (int dt = 0; dt < 4; ++dt)
; #pragma unroll
;                     for (int i = 0; i < 16; ++i) o[dt][i] *= alpha;
;             }
.LBB0_1091:
	v_lshl_add_u64 v[2:3], s[26:27], 0, v[198:199]
	v_add_co_u32_e32 v4, vcc, 0x11140000, v2
	v_lshl_add_u64 v[14:15], s[26:27], 0, v[194:195]
	s_nop 0
	v_addc_co_u32_e32 v5, vcc, 0, v3, vcc
	v_add_co_u32_e32 v6, vcc, 0x11160000, v2
	v_lshl_add_u64 v[10:11], s[26:27], 0, v[196:197]
	s_nop 0
	v_addc_co_u32_e32 v7, vcc, 0, v3, vcc
	v_add_co_u32_e32 v80, vcc, 0x13100000, v14
	global_load_dwordx4 v[2:5], v[4:5], off
	s_nop 0
	global_load_dwordx4 v[6:9], v[6:7], off
	v_addc_co_u32_e32 v81, vcc, 0, v15, vcc
	v_add_co_u32_e32 v14, vcc, 0x13200000, v14
	global_load_dwordx4 v[10:13], v[10:11], off
	s_nop 0
	global_load_dwordx4 v[160:163], v[80:81], off offset:128
	v_addc_co_u32_e32 v15, vcc, 0, v15, vcc
	global_load_dwordx4 v[164:167], v[14:15], off offset:128
	s_and_b32 s18, s57, 1
	s_cmp_gt_u32 s57, s25
	s_cbranch_scc1 .LBB0_1095
	s_mul_i32 s19, s18, 0xa800
	s_add_i32 s19, s19, 0
	v_add3_u32 v0, s19, v193, v204
	ds_read_b128 v[80:83], v0
	ds_read_b128 v[168:171], v0 offset:32
	ds_read_b128 v[96:99], v0 offset:12800
	ds_read_b128 v[174:177], v0 offset:64
	ds_read_b128 v[178:181], v0 offset:12832
	ds_read_b128 v[206:209], v0 offset:12864
	s_waitcnt vmcnt(6) lgkmcnt(3)
	v_mfma_f32_32x32x16_bf16 v[96:111], v[96:99], v[156:159], 0
	v_mfma_f32_32x32x16_bf16 v[80:95], v[80:83], v[156:159], 0
	v_mfma_f32_32x32x16_bf16 v[80:95], v[168:171], v[152:155], v[80:95]
	ds_read_b128 v[168:171], v0 offset:96
	ds_read_b128 v[210:213], v0 offset:12896
	s_waitcnt lgkmcnt(3)
	v_mfma_f32_32x32x16_bf16 v[96:111], v[178:181], v[152:155], v[96:111]
	v_mfma_f32_32x32x16_bf16 v[80:95], v[174:177], v[148:151], v[80:95]
	ds_read_b128 v[174:177], v0 offset:128
	ds_read_b128 v[178:181], v0 offset:12928
	s_waitcnt lgkmcnt(4)
	v_mfma_f32_32x32x16_bf16 v[96:111], v[206:209], v[148:151], v[96:111]
	s_waitcnt lgkmcnt(3)
	v_mfma_f32_32x32x16_bf16 v[80:95], v[168:171], v[144:147], v[80:95]
	ds_read_b128 v[168:171], v0 offset:160
	ds_read_b128 v[206:209], v0 offset:12960
	s_waitcnt lgkmcnt(4)
	v_mfma_f32_32x32x16_bf16 v[96:111], v[210:213], v[144:147], v[96:111]
	s_waitcnt lgkmcnt(3)
	v_mfma_f32_32x32x16_bf16 v[80:95], v[174:177], v[140:143], v[80:95]
	ds_read_b128 v[174:177], v0 offset:192
	ds_read_b128 v[210:213], v0 offset:12992
	s_waitcnt lgkmcnt(4)
	v_mfma_f32_32x32x16_bf16 v[96:111], v[178:181], v[140:143], v[96:111]
	s_waitcnt lgkmcnt(3)
	v_mfma_f32_32x32x16_bf16 v[80:95], v[168:171], v[136:139], v[80:95]
	ds_read_b128 v[168:171], v0 offset:224
	ds_read_b128 v[178:181], v0 offset:13024
	s_waitcnt lgkmcnt(4)
	v_mfma_f32_32x32x16_bf16 v[96:111], v[206:209], v[136:139], v[96:111]
	s_waitcnt lgkmcnt(3)
	v_mfma_f32_32x32x16_bf16 v[80:95], v[174:177], v[132:135], v[80:95]
	ds_read_b128 v[174:177], v0 offset:256
	ds_read_b128 v[206:209], v0 offset:13056
	s_waitcnt lgkmcnt(4)
	v_mfma_f32_32x32x16_bf16 v[96:111], v[210:213], v[132:135], v[96:111]
	s_waitcnt lgkmcnt(3)
	v_mfma_f32_32x32x16_bf16 v[80:95], v[168:171], v[128:131], v[80:95]
	ds_read_b128 v[168:171], v0 offset:288
	ds_read_b128 v[210:213], v0 offset:13088
	s_waitcnt lgkmcnt(4)
	v_mfma_f32_32x32x16_bf16 v[96:111], v[178:181], v[128:131], v[96:111]
	s_waitcnt lgkmcnt(3)
	v_mfma_f32_32x32x16_bf16 v[80:95], v[174:177], v[124:127], v[80:95]
	ds_read_b128 v[174:177], v0 offset:320
	ds_read_b128 v[178:181], v0 offset:13120
	s_waitcnt lgkmcnt(4)
	v_mfma_f32_32x32x16_bf16 v[96:111], v[206:209], v[124:127], v[96:111]
	s_waitcnt lgkmcnt(3)
	v_mfma_f32_32x32x16_bf16 v[80:95], v[168:171], v[120:123], v[80:95]
	ds_read_b128 v[168:171], v0 offset:352
	ds_read_b128 v[206:209], v0 offset:13152
	s_waitcnt lgkmcnt(4)
	v_mfma_f32_32x32x16_bf16 v[96:111], v[210:213], v[120:123], v[96:111]
	s_waitcnt lgkmcnt(3)
	v_mfma_f32_32x32x16_bf16 v[80:95], v[174:177], v[116:119], v[80:95]
	s_waitcnt lgkmcnt(2)
	v_mfma_f32_32x32x16_bf16 v[96:111], v[178:181], v[116:119], v[96:111]
	s_waitcnt vmcnt(5) lgkmcnt(1)
	v_mfma_f32_32x32x16_bf16 v[80:95], v[168:171], v[112:115], v[80:95]
	v_add_u32_e32 v0, s19, v188
	v_add_u32_e32 v173, v0, v191
	v_add_u32_e32 v15, 0x6000, v173
	v_add_u32_e32 v205, 0x7000, v173
	ds_read2_b64 v[168:171], v15 offset0:128 offset1:130
	ds_read2_b64 v[180:183], v205 offset0:160 offset1:162
	s_nop 5
	v_max_f32_e32 v0, v81, v81
	v_max_f32_e32 v14, v80, v80
	v_max_f32_e32 v0, v14, v0
	s_waitcnt lgkmcnt(2)
	v_mfma_f32_32x32x16_bf16 v[96:111], v[206:209], v[112:115], v[96:111]
	v_max3_f32 v0, v0, v82, v83
	v_max3_f32 v0, v0, v84, v85
	v_max3_f32 v0, v0, v86, v87
	v_max3_f32 v0, v0, v88, v89
	v_max3_f32 v0, v0, v90, v91
	v_max3_f32 v0, v0, v92, v93
	v_max3_f32 v0, v0, v94, v95
	s_nop 4
	v_max3_f32 v0, v0, v96, v97
	v_max3_f32 v0, v0, v98, v99
	v_max3_f32 v0, v0, v100, v101
	v_max3_f32 v0, v0, v102, v103
	v_max3_f32 v0, v0, v104, v105
	v_max3_f32 v0, v0, v106, v107
	v_max3_f32 v0, v0, v108, v109
	v_max3_f32 v0, v0, v110, v111
	ds_bpermute_b32 v14, v189, v0
	v_add_u32_e32 v206, 0x8000, v173
	v_add_u32_e32 v207, 0x9000, v173
	ds_read2_b64 v[176:179], v206 offset0:192 offset1:194
	s_waitcnt lgkmcnt(1)
	v_max3_f32 v14, v172, v0, v14
	v_mov_b32_e32 v236, v172
	v_sub_f32_e32 v0, v172, v14
	v_cmp_gt_f32_e32 vcc, 0xc1000000, v0
	v_exp_f32_e32 v0, v0
	ds_read2_b64 v[172:175], v207 offset0:224 offset1:226
	s_cbranch_vccz .Lthr_2_keep
	v_mul_f32_e32 v78, v78, v0
	v_mul_f32_e32 v79, v79, v0
	v_mul_f32_e32 v76, v76, v0
	v_mul_f32_e32 v77, v77, v0
	v_mul_f32_e32 v74, v74, v0
	v_mul_f32_e32 v75, v75, v0
	v_mul_f32_e32 v72, v72, v0
	v_mul_f32_e32 v73, v73, v0
	v_mul_f32_e32 v70, v70, v0
	v_mul_f32_e32 v71, v71, v0
	v_mul_f32_e32 v68, v68, v0
	v_mul_f32_e32 v69, v69, v0
	v_mul_f32_e32 v66, v66, v0
	v_mul_f32_e32 v67, v67, v0
	v_mul_f32_e32 v64, v64, v0
	v_mul_f32_e32 v65, v65, v0
	v_mul_f32_e32 v62, v62, v0
	v_mul_f32_e32 v63, v63, v0
	v_mul_f32_e32 v60, v60, v0
	v_mul_f32_e32 v61, v61, v0
	v_mul_f32_e32 v58, v58, v0
	v_mul_f32_e32 v59, v59, v0
	v_mul_f32_e32 v56, v56, v0
	v_mul_f32_e32 v57, v57, v0
	v_mul_f32_e32 v54, v54, v0
	v_mul_f32_e32 v55, v55, v0
	v_mul_f32_e32 v52, v52, v0
	v_mul_f32_e32 v53, v53, v0
	v_mul_f32_e32 v50, v50, v0
	v_mul_f32_e32 v51, v51, v0
	v_mul_f32_e32 v48, v48, v0
	v_mul_f32_e32 v49, v49, v0
	v_mul_f32_e32 v46, v46, v0
	v_mul_f32_e32 v47, v47, v0
	v_mul_f32_e32 v44, v44, v0
	v_mul_f32_e32 v45, v45, v0
	v_mul_f32_e32 v42, v42, v0
	v_mul_f32_e32 v43, v43, v0
	v_mul_f32_e32 v40, v40, v0
	v_mul_f32_e32 v41, v41, v0
	v_mul_f32_e32 v38, v38, v0
	v_mul_f32_e32 v39, v39, v0
	v_mul_f32_e32 v36, v36, v0
	v_mul_f32_e32 v37, v37, v0
	v_mul_f32_e32 v34, v34, v0
	v_mul_f32_e32 v35, v35, v0
	v_mul_f32_e32 v32, v32, v0
	v_mul_f32_e32 v33, v33, v0
	v_mul_f32_e32 v30, v30, v0
	v_mul_f32_e32 v31, v31, v0
	v_mul_f32_e32 v28, v28, v0
	v_mul_f32_e32 v29, v29, v0
	v_mul_f32_e32 v26, v26, v0
	v_mul_f32_e32 v27, v27, v0
	v_mul_f32_e32 v24, v24, v0
	v_mul_f32_e32 v25, v25, v0
	v_mul_f32_e32 v22, v22, v0
	v_mul_f32_e32 v23, v23, v0
	v_mul_f32_e32 v20, v20, v0
	v_mul_f32_e32 v21, v21, v0
	v_mul_f32_e32 v18, v18, v0
	v_mul_f32_e32 v19, v19, v0
	v_mul_f32_e32 v16, v16, v0
	v_mul_f32_e32 v17, v17, v0

; #define LAS __attribute__((address_space(3)))
; DI float shfl_xor_l(float v, int lane, int m) { return __int_as_float(__builtin_amdgcn_ds_bpermute((lane ^ m) << 2, __float_as_int(v))); }
; #define VLD(dst, j, dt) do { LAS unsigned char* va_ = vb + (32 * (dt) + n) * VROW + (16 * (j) + 4 * g) * 2; const u32x2 lo_ = *(const LAS u32x2*)(va_), hi_ = *(const LAS u32x2*)(va_ + 16); dst = (u32x4){lo_.x, lo_.y, hi_.x, hi_.y}; } while (0)
; DI void attn_unit(LAS unsigned char* lds, int wid, int b, int h, int qb) {
;     ...
;         if (kt <= cq) {
;             LAS unsigned char* kb = lds + buf * ABUF; LAS unsigned char* vb = kb + KBYTES;
;             f32x16 s0, s1;
; #pragma unroll
;             for (int i = 0; i < 16; ++i) { s0[i] = 0.f; s1[i] = 0.f; }
;     ...
;             bf16x8 ka[3][2];
;             ka[0][0] = KLD(0, 0); ka[0][1] = KLD(0, 1); ka[1][0] = KLD(1, 0); ka[1][1] = KLD(1, 1);
; #pragma unroll
;             for (int ks = 0; ks < 12; ++ks) {
;                 if (ks + 2 < 12) { ka[(ks + 2) % 3][0] = KLD(ks + 2, 0); ka[(ks + 2) % 3][1] = KLD(ks + 2, 1); }
;                 s0 = __builtin_amdgcn_mfma_f32_32x32x16_bf16(ka[ks % 3][0], qf[ks], s0, 0, 0, 0); s1 = __builtin_amdgcn_mfma_f32_32x32x16_bf16(ka[ks % 3][1], qf[ks], s1, 0, 0, 0);
;                 __builtin_amdgcn_sched_barrier(0); }
;             u32x4 vf[2][4];
; #pragma unroll
;             for (int dt = 0; dt < 4; ++dt) VLD(vf[0][dt], 0, dt);
;             float mx = s0[0];
; #pragma unroll
;             for (int i = 1; i < 16; ++i) mx = fmaxf(mx, s0[i]);
; #pragma unroll
;             for (int i = 0; i < 16; ++i) mx = fmaxf(mx, s1[i]);
;             mx = fmaxf(mx, shfl_xor_l(mx, lane, 32));
;             const float mnew = fmaxf(mrow, mx), alpha = __builtin_amdgcn_exp2f(mrow - mnew); mrow = mnew;
;             float ls = 0.f;
; #pragma unroll
;             for (int i = 0; i < 16; ++i) { s0[i] = __builtin_amdgcn_exp2f(s0[i] - mnew); s1[i] = __builtin_amdgcn_exp2f(s1[i] - mnew); ls += s0[i] + s1[i]; }
;             lrow = lrow * alpha + ls;
;             if (__builtin_amdgcn_ballot_w64(alpha != 1.f) != 0ull) {
; #pragma unroll
;                 for (int dt = 0; dt < 4; ++dt)
; #pragma unroll
;                     for (int i = 0; i < 16; ++i) o[dt][i] *= alpha;
;             }
.LBB0_1098:
	s_lshl_b32 s18, s56, 2
	s_or_b32 s18, s18, 2
	s_cmp_ge_u32 s18, s25
	s_cbranch_scc1 .LBB0_1077
	s_bitcmp1_b32 s4, 0
	s_cselect_b32 s4, 0xa800, 0
	s_add_i32 s4, s4, 0
	v_add3_u32 v0, s4, v193, v204
	ds_read_b128 v[2:5], v0
	ds_read_b128 v[6:9], v0 offset:32
	s_waitcnt lgkmcnt(1)
	v_mfma_f32_32x32x16_bf16 v[80:95], v[2:5], v[156:159], 0
	ds_read_b128 v[2:5], v0 offset:12800
	ds_read_b128 v[10:13], v0 offset:64
	ds_read_b128 v[160:163], v0 offset:12832
	ds_read_b128 v[164:167], v0 offset:12864
	s_waitcnt lgkmcnt(3)
	v_mfma_f32_32x32x16_bf16 v[96:111], v[2:5], v[156:159], 0
	v_mfma_f32_32x32x16_bf16 v[80:95], v[6:9], v[152:155], v[80:95]
	ds_read_b128 v[2:5], v0 offset:96
	ds_read_b128 v[6:9], v0 offset:12896
	s_waitcnt lgkmcnt(3)
	v_mfma_f32_32x32x16_bf16 v[96:111], v[160:163], v[152:155], v[96:111]
	v_mfma_f32_32x32x16_bf16 v[80:95], v[10:13], v[148:151], v[80:95]
	ds_read_b128 v[10:13], v0 offset:128
	ds_read_b128 v[152:155], v0 offset:12928
	s_waitcnt lgkmcnt(4)
	v_mfma_f32_32x32x16_bf16 v[96:111], v[164:167], v[148:151], v[96:111]
	s_waitcnt lgkmcnt(3)
	v_mfma_f32_32x32x16_bf16 v[80:95], v[2:5], v[144:147], v[80:95]
	ds_read_b128 v[2:5], v0 offset:160
	ds_read_b128 v[148:151], v0 offset:12960
	s_waitcnt lgkmcnt(4)
	v_mfma_f32_32x32x16_bf16 v[96:111], v[6:9], v[144:147], v[96:111]
	s_waitcnt lgkmcnt(3)
	v_mfma_f32_32x32x16_bf16 v[80:95], v[10:13], v[140:143], v[80:95]
	ds_read_b128 v[6:9], v0 offset:192
	ds_read_b128 v[10:13], v0 offset:12992
	s_waitcnt lgkmcnt(4)
	v_mfma_f32_32x32x16_bf16 v[96:111], v[152:155], v[140:143], v[96:111]
	s_waitcnt lgkmcnt(3)
	v_mfma_f32_32x32x16_bf16 v[80:95], v[2:5], v[136:139], v[80:95]
	ds_read_b128 v[2:5], v0 offset:224
	ds_read_b128 v[140:143], v0 offset:13024
	s_waitcnt lgkmcnt(4)
	v_mfma_f32_32x32x16_bf16 v[96:111], v[148:151], v[136:139], v[96:111]
	s_waitcnt lgkmcnt(3)
	v_mfma_f32_32x32x16_bf16 v[80:95], v[6:9], v[132:135], v[80:95]
	ds_read_b128 v[6:9], v0 offset:256
	ds_read_b128 v[136:139], v0 offset:13056
	s_waitcnt lgkmcnt(4)
	v_mfma_f32_32x32x16_bf16 v[96:111], v[10:13], v[132:135], v[96:111]
	s_waitcnt lgkmcnt(3)
	v_mfma_f32_32x32x16_bf16 v[80:95], v[2:5], v[128:131], v[80:95]
	ds_read_b128 v[2:5], v0 offset:288
	ds_read_b128 v[10:13], v0 offset:13088
	s_waitcnt lgkmcnt(4)
	v_mfma_f32_32x32x16_bf16 v[96:111], v[140:143], v[128:131], v[96:111]
	s_waitcnt lgkmcnt(3)
	v_mfma_f32_32x32x16_bf16 v[80:95], v[6:9], v[124:127], v[80:95]
	ds_read_b128 v[6:9], v0 offset:320
	ds_read_b128 v[128:131], v0 offset:13120
	s_waitcnt lgkmcnt(4)
	v_mfma_f32_32x32x16_bf16 v[96:111], v[136:139], v[124:127], v[96:111]
	s_waitcnt lgkmcnt(3)
	v_mfma_f32_32x32x16_bf16 v[80:95], v[2:5], v[120:123], v[80:95]
	ds_read_b128 v[2:5], v0 offset:352
	ds_read_b128 v[124:127], v0 offset:13152
	s_waitcnt lgkmcnt(4)
	v_mfma_f32_32x32x16_bf16 v[96:111], v[10:13], v[120:123], v[96:111]
	s_waitcnt lgkmcnt(3)
	v_mfma_f32_32x32x16_bf16 v[80:95], v[6:9], v[116:119], v[80:95]
	s_waitcnt lgkmcnt(2)
	v_mfma_f32_32x32x16_bf16 v[96:111], v[128:131], v[116:119], v[96:111]
	s_waitcnt lgkmcnt(1)
	v_mfma_f32_32x32x16_bf16 v[80:95], v[2:5], v[112:115], v[80:95]
	v_add_u32_e32 v0, s4, v188
	v_add_u32_e32 v6, v0, v191
	v_add_u32_e32 v15, 0x6000, v6
	v_add_u32_e32 v116, 0x7000, v6
	v_add_u32_e32 v117, 0x8000, v6
	ds_read2_b64 v[2:5], v15 offset0:128 offset1:130
	ds_read2_b64 v[10:13], v117 offset0:192 offset1:194
	s_nop 4
	v_max_f32_e32 v0, v81, v81
	v_max_f32_e32 v7, v80, v80
	v_max_f32_e32 v0, v7, v0
	s_waitcnt lgkmcnt(2)
	v_mfma_f32_32x32x16_bf16 v[96:111], v[124:127], v[112:115], v[96:111]
	v_max3_f32 v0, v0, v82, v83
	v_max3_f32 v0, v0, v84, v85
	v_max3_f32 v0, v0, v86, v87
	v_max3_f32 v0, v0, v88, v89
	v_max3_f32 v0, v0, v90, v91
	v_max3_f32 v0, v0, v92, v93
	v_max3_f32 v0, v0, v94, v95
	s_nop 4
	v_max3_f32 v0, v0, v96, v97
	v_max3_f32 v0, v0, v98, v99
	v_max3_f32 v0, v0, v100, v101
	v_max3_f32 v0, v0, v102, v103
	v_max3_f32 v0, v0, v104, v105
	v_max3_f32 v0, v0, v106, v107
	v_max3_f32 v0, v0, v108, v109
	v_max3_f32 v0, v0, v110, v111
	ds_bpermute_b32 v7, v189, v0
	ds_read2_b64 v[112:115], v116 offset0:160 offset1:162
	s_waitcnt lgkmcnt(1)
	v_max3_f32 v118, v14, v0, v7
	v_mov_b32_e32 v236, v14
	v_sub_f32_e32 v0, v14, v118
	v_cmp_gt_f32_e32 vcc, 0xc1000000, v0
	v_add_u32_e32 v14, 0x9000, v6
	v_exp_f32_e32 v0, v0
	ds_read2_b64 v[6:9], v14 offset0:224 offset1:226
	s_cbranch_vccz .Lthr_3_keep
	v_mul_f32_e32 v78, v78, v0
	v_mul_f32_e32 v79, v79, v0
	v_mul_f32_e32 v76, v76, v0
	v_mul_f32_e32 v77, v77, v0
	v_mul_f32_e32 v74, v74, v0
	v_mul_f32_e32 v75, v75, v0
	v_mul_f32_e32 v72, v72, v0
	v_mul_f32_e32 v73, v73, v0
	v_mul_f32_e32 v70, v70, v0
	v_mul_f32_e32 v71, v71, v0
	v_mul_f32_e32 v68, v68, v0
	v_mul_f32_e32 v69, v69, v0
	v_mul_f32_e32 v66, v66, v0
	v_mul_f32_e32 v67, v67, v0
	v_mul_f32_e32 v64, v64, v0
	v_mul_f32_e32 v65, v65, v0
	v_mul_f32_e32 v62, v62, v0
	v_mul_f32_e32 v63, v63, v0
	v_mul_f32_e32 v60, v60, v0
	v_mul_f32_e32 v61, v61, v0
	v_mul_f32_e32 v58, v58, v0
	v_mul_f32_e32 v59, v59, v0
	v_mul_f32_e32 v56, v56, v0
	v_mul_f32_e32 v57, v57, v0
	v_mul_f32_e32 v54, v54, v0
	v_mul_f32_e32 v55, v55, v0
	v_mul_f32_e32 v52, v52, v0
	v_mul_f32_e32 v53, v53, v0
	v_mul_f32_e32 v50, v50, v0
	v_mul_f32_e32 v51, v51, v0
	v_mul_f32_e32 v48, v48, v0
	v_mul_f32_e32 v49, v49, v0
	v_mul_f32_e32 v46, v46, v0
	v_mul_f32_e32 v47, v47, v0
	v_mul_f32_e32 v44, v44, v0
	v_mul_f32_e32 v45, v45, v0
	v_mul_f32_e32 v42, v42, v0
	v_mul_f32_e32 v43, v43, v0
	v_mul_f32_e32 v40, v40, v0
	v_mul_f32_e32 v41, v41, v0
	v_mul_f32_e32 v38, v38, v0
	v_mul_f32_e32 v39, v39, v0
	v_mul_f32_e32 v36, v36, v0
	v_mul_f32_e32 v37, v37, v0
	v_mul_f32_e32 v34, v34, v0
	v_mul_f32_e32 v35, v35, v0
	v_mul_f32_e32 v32, v32, v0
	v_mul_f32_e32 v33, v33, v0
	v_mul_f32_e32 v30, v30, v0
	v_mul_f32_e32 v31, v31, v0
	v_mul_f32_e32 v28, v28, v0
	v_mul_f32_e32 v29, v29, v0
	v_mul_f32_e32 v26, v26, v0
	v_mul_f32_e32 v27, v27, v0
	v_mul_f32_e32 v24, v24, v0
	v_mul_f32_e32 v25, v25, v0
	v_mul_f32_e32 v22, v22, v0
	v_mul_f32_e32 v23, v23, v0
	v_mul_f32_e32 v20, v20, v0
	v_mul_f32_e32 v21, v21, v0
	v_mul_f32_e32 v18, v18, v0
	v_mul_f32_e32 v19, v19, v0
	v_mul_f32_e32 v16, v16, v0
	v_mul_f32_e32 v17, v17, v0
	s_branch .LBB0_1076

; #define PG8_STAGE(bufoff, gbase, voff) do { _Pragma("unroll") for (int _i = 0; _i < 2; ++_i) \
;         __builtin_amdgcn_global_load_lds((const unsigned*)((const char*)(gbase) + (voff)[_i]), (LAS unsigned*)(lds + (bufoff) + ldsw + _i * 8192), 16, 0, 0); } while (0)
; #define PG8_LDA(dst, b, h) do { _Pragma("unroll") for (int m = 0; m < 4; ++m) _Pragma("unroll") for (int k = 0; k < 2; ++k) dst[m][k] = *(const LAS bf16x8*)(lds + PG8_SA(b, h) + aoff + m * 2048 + k * 1024); } while (0)
; #define PG8_LDB(dst, b, h) do { _Pragma("unroll") for (int n = 0; n < 2; ++n) _Pragma("unroll") for (int k = 0; k < 2; ++k) dst[n][k] = *(const LAS bf16x8*)(lds + PG8_SB(b, h) + boff + n * 2048 + k * 1024); } while (0)
; #define PG8_MMA(ai, bj, At, Bt) do { __builtin_amdgcn_s_setprio(1); _Pragma("unroll") for (int m = 0; m < 4; ++m) _Pragma("unroll") for (int n = 0; n < 2; ++n) _Pragma("unroll") for (int k = 0; k < 2; ++k) \
;         acc[ai][bj][m][n] = __builtin_amdgcn_mfma_f32_16x16x32_bf16(Bt[n][k], At[m][k], acc[ai][bj][m][n], 0, 0, 0); __builtin_amdgcn_s_setprio(0); } while (0)
; #define PG8_WAIT_L(n) asm volatile("s_waitcnt lgkmcnt(" #n ")" ::: "memory")
; #define PG8_BAR __builtin_amdgcn_s_barrier()
; #define PG8_SCHED __builtin_amdgcn_sched_barrier(0)
; template <class Epi>
; DI void gemm_phase(LAS unsigned char* lds, int wid, int K, int lda, int ldb, bool bperm, const Sched3& S, const Epi& E) {
;     ...
;         for (int t = 0; t < nt; t += 2) {
;             const bool last = (t == nt - 2);
;             const char* a1 = cA + (size_t)(t + 1) * kstep;
;             const char* a2 = last ? nA : cA + (size_t)(t + 2) * kstep; const char* b2 = last ? nB : cB + (size_t)(t + 2) * kstep;
;             const char* a3 = a2 + kstep; const char* b3 = b2 + kstep; const size_t h2 = last ? nhA : hA;
;             PG8_LDB(B0, 0, 0); PG8_SCHED; PG8_LDA(At, 0, 0); PG8_STAGE(PG8_SA(1, 1), a1 + hA, voffA);
;             PG8_WAIT_L(8); PG8_BAR; PG8_WAIT_L(0); PG8_MMA(0, 0, At, B0); PG8_BAR; PG8_SCHED;
;             PG8_LDB(B1, 0, 1); PG8_STAGE(PG8_SB(0, 0), b2, voffB);
;             PG8_BAR; PG8_WAIT_L(0); PG8_MMA(0, 1, At, B1); PG8_BAR;
;             PG8_LDA(At, 0, 1); PG8_STAGE(PG8_SA(0, 0), a2, voffA);
;             PG8_BAR; PG8_WAIT_L(0); if (full) PG8_MMA(1, 0, At, B0); PG8_BAR; PG8_SCHED;
.LBB0_1176:
	ds_read_b128 v[128:131], v185
	ds_read_b128 v[132:135], v185 offset:1024
	ds_read_b128 v[136:139], v185 offset:2048
	ds_read_b128 v[140:143], v185 offset:3072
	s_add_u32 s38, s36, 0xfff80080
	s_addc_u32 s39, s37, -1
	s_cmp_eq_u32 s27, 28
	s_cselect_b32 s41, s29, s39
	s_cselect_b32 s40, s28, s38
	s_cselect_b32 s39, s31, s21
	s_cselect_b32 s38, s30, s19
	v_lshl_add_u64 v[178:179], s[36:37], 0, v[156:157]
	s_add_i32 m0, s48, 0xc000
	ds_read_b128 v[144:147], v186
	ds_read_b128 v[148:151], v186 offset:1024
	ds_read_b128 v[162:165], v186 offset:2048
	ds_read_b128 v[166:169], v186 offset:3072
	ds_read_b128 v[170:173], v186 offset:4096
	ds_read_b128 v[174:177], v186 offset:5120
	ds_read_b128 v[188:191], v186 offset:6144
	ds_read_b128 v[192:195], v186 offset:7168
	global_load_lds_dwordx4 v[178:179], off
	v_lshl_add_u64 v[178:179], s[36:37], 0, v[158:159]
	s_add_i32 m0, s48, 0xe000
	s_nop 0
	global_load_lds_dwordx4 v[178:179], off
	s_waitcnt lgkmcnt(8)
	s_barrier
	s_waitcnt lgkmcnt(0)
	s_setprio 1
	s_waitcnt lgkmcnt(0)
	v_mfma_f32_16x16x32_bf16 v[124:127], v[128:131], v[144:147], v[124:127]
	v_mfma_f32_16x16x32_bf16 v[120:123], v[136:139], v[144:147], v[120:123]
	v_mfma_f32_16x16x32_bf16 v[108:111], v[128:131], v[162:165], v[108:111]
	v_mfma_f32_16x16x32_bf16 v[104:107], v[136:139], v[162:165], v[104:107]
	v_mfma_f32_16x16x32_bf16 v[92:95], v[128:131], v[170:173], v[92:95]
	v_mfma_f32_16x16x32_bf16 v[88:91], v[136:139], v[170:173], v[88:91]
	v_mfma_f32_16x16x32_bf16 v[76:79], v[128:131], v[188:191], v[76:79]
	v_mfma_f32_16x16x32_bf16 v[72:75], v[136:139], v[188:191], v[72:75]
	v_mfma_f32_16x16x32_bf16 v[124:127], v[132:135], v[148:151], v[124:127]
	v_mfma_f32_16x16x32_bf16 v[120:123], v[140:143], v[148:151], v[120:123]
	v_mfma_f32_16x16x32_bf16 v[108:111], v[132:135], v[166:169], v[108:111]
	v_mfma_f32_16x16x32_bf16 v[104:107], v[140:143], v[166:169], v[104:107]
	v_mfma_f32_16x16x32_bf16 v[92:95], v[132:135], v[174:177], v[92:95]
	v_mfma_f32_16x16x32_bf16 v[88:91], v[140:143], v[174:177], v[88:91]
	v_mfma_f32_16x16x32_bf16 v[76:79], v[132:135], v[192:195], v[76:79]
	v_mfma_f32_16x16x32_bf16 v[72:75], v[140:143], v[192:195], v[72:75]
	s_setprio 0
	s_barrier
	s_add_i32 s61, s57, s47
	v_lshl_add_u64 v[178:179], s[38:39], 0, v[152:153]
	s_mov_b32 m0, s61
	ds_read_b128 v[196:199], v187
	ds_read_b128 v[200:203], v187 offset:1024
	ds_read_b128 v[204:207], v187 offset:2048
	ds_read_b128 v[208:211], v187 offset:3072
	global_load_lds_dwordx4 v[178:179], off
	v_lshl_add_u64 v[212:213], s[38:39], 0, v[154:155]
	s_add_i32 m0, s61, 0x2000
	s_nop 0
	global_load_lds_dwordx4 v[212:213], off
	s_barrier
	s_waitcnt lgkmcnt(0)
	s_setprio 1
	s_waitcnt lgkmcnt(0)
	v_mfma_f32_16x16x32_bf16 v[116:119], v[196:199], v[144:147], v[116:119]
	v_mfma_f32_16x16x32_bf16 v[112:115], v[204:207], v[144:147], v[112:115]
	v_mfma_f32_16x16x32_bf16 v[100:103], v[196:199], v[162:165], v[100:103]
	v_mfma_f32_16x16x32_bf16 v[96:99], v[204:207], v[162:165], v[96:99]
	v_mfma_f32_16x16x32_bf16 v[84:87], v[196:199], v[170:173], v[84:87]
	v_mfma_f32_16x16x32_bf16 v[80:83], v[204:207], v[170:173], v[80:83]
	v_mfma_f32_16x16x32_bf16 v[68:71], v[196:199], v[188:191], v[68:71]
	v_mfma_f32_16x16x32_bf16 v[64:67], v[204:207], v[188:191], v[64:67]
	v_mfma_f32_16x16x32_bf16 v[116:119], v[200:203], v[148:151], v[116:119]
	v_mfma_f32_16x16x32_bf16 v[112:115], v[208:211], v[148:151], v[112:115]
	v_mfma_f32_16x16x32_bf16 v[100:103], v[200:203], v[166:169], v[100:103]
	v_mfma_f32_16x16x32_bf16 v[96:99], v[208:211], v[166:169], v[96:99]
	v_mfma_f32_16x16x32_bf16 v[84:87], v[200:203], v[174:177], v[84:87]
	v_mfma_f32_16x16x32_bf16 v[80:83], v[208:211], v[174:177], v[80:83]
	v_mfma_f32_16x16x32_bf16 v[68:71], v[200:203], v[192:195], v[68:71]
	v_mfma_f32_16x16x32_bf16 v[64:67], v[208:211], v[192:195], v[64:67]
	s_setprio 0
	s_mov_b32 m0, s48
	v_lshl_add_u64 v[214:215], s[40:41], 0, v[152:153]
	s_barrier
	ds_read_b128 v[144:147], v186 offset:16384
	ds_read_b128 v[148:151], v186 offset:17408
	ds_read_b128 v[162:165], v186 offset:18432
	ds_read_b128 v[166:169], v186 offset:19456
	ds_read_b128 v[170:173], v186 offset:20480
	ds_read_b128 v[174:177], v186 offset:21504
	ds_read_b128 v[188:191], v186 offset:22528
	ds_read_b128 v[192:195], v186 offset:23552
	global_load_lds_dwordx4 v[214:215], off
	v_lshl_add_u64 v[216:217], s[40:41], 0, v[154:155]
	s_mov_b32 m0, s49
	s_nop 0
	global_load_lds_dwordx4 v[216:217], off
	s_barrier
	s_waitcnt lgkmcnt(0)
	s_setprio 1
	s_waitcnt lgkmcnt(0)
	v_mfma_f32_16x16x32_bf16 v[60:63], v[128:131], v[144:147], v[60:63]
	v_mfma_f32_16x16x32_bf16 v[56:59], v[136:139], v[144:147], v[56:59]
	v_mfma_f32_16x16x32_bf16 v[44:47], v[128:131], v[162:165], v[44:47]
	v_mfma_f32_16x16x32_bf16 v[40:43], v[136:139], v[162:165], v[40:43]
	v_mfma_f32_16x16x32_bf16 v[28:31], v[128:131], v[170:173], v[28:31]
	v_mfma_f32_16x16x32_bf16 v[24:27], v[136:139], v[170:173], v[24:27]
	v_mfma_f32_16x16x32_bf16 v[12:15], v[128:131], v[188:191], v[12:15]
	v_mfma_f32_16x16x32_bf16 v[8:11], v[136:139], v[188:191], v[8:11]
	v_mfma_f32_16x16x32_bf16 v[60:63], v[132:135], v[148:151], v[60:63]
	v_mfma_f32_16x16x32_bf16 v[56:59], v[140:143], v[148:151], v[56:59]
	v_mfma_f32_16x16x32_bf16 v[44:47], v[132:135], v[166:169], v[44:47]
	v_mfma_f32_16x16x32_bf16 v[40:43], v[140:143], v[166:169], v[40:43]
	v_mfma_f32_16x16x32_bf16 v[28:31], v[132:135], v[174:177], v[28:31]
	v_mfma_f32_16x16x32_bf16 v[24:27], v[140:143], v[174:177], v[24:27]
	v_mfma_f32_16x16x32_bf16 v[12:15], v[132:135], v[192:195], v[12:15]
	v_mfma_f32_16x16x32_bf16 v[8:11], v[140:143], v[192:195], v[8:11]
	s_setprio 0
	s_barrier
; #define PG8_STAGE(bufoff, gbase, voff) do { _Pragma("unroll") for (int _i = 0; _i < 2; ++_i) \
;         __builtin_amdgcn_global_load_lds((const unsigned*)((const char*)(gbase) + (voff)[_i]), (LAS unsigned*)(lds + (bufoff) + ldsw + _i * 8192), 16, 0, 0); } while (0)
; #define PG8_LDA(dst, b, h) do { _Pragma("unroll") for (int m = 0; m < 4; ++m) _Pragma("unroll") for (int k = 0; k < 2; ++k) dst[m][k] = *(const LAS bf16x8*)(lds + PG8_SA(b, h) + aoff + m * 2048 + k * 1024); } while (0)
; #define PG8_LDB(dst, b, h) do { _Pragma("unroll") for (int n = 0; n < 2; ++n) _Pragma("unroll") for (int k = 0; k < 2; ++k) dst[n][k] = *(const LAS bf16x8*)(lds + PG8_SB(b, h) + boff + n * 2048 + k * 1024); } while (0)
; #define PG8_MMA(ai, bj, At, Bt) do { __builtin_amdgcn_s_setprio(1); _Pragma("unroll") for (int m = 0; m < 4; ++m) _Pragma("unroll") for (int n = 0; n < 2; ++n) _Pragma("unroll") for (int k = 0; k < 2; ++k) \
;         acc[ai][bj][m][n] = __builtin_amdgcn_mfma_f32_16x16x32_bf16(Bt[n][k], At[m][k], acc[ai][bj][m][n], 0, 0, 0); __builtin_amdgcn_s_setprio(0); } while (0)
; #define PG8_WAIT_V(n) asm volatile("s_waitcnt vmcnt(" #n ")" ::: "memory")
; #define PG8_WAIT_L(n) asm volatile("s_waitcnt lgkmcnt(" #n ")" ::: "memory")
; #define PG8_BAR __builtin_amdgcn_s_barrier()
; #define PG8_SCHED __builtin_amdgcn_sched_barrier(0)
; template <class Epi>
; DI void gemm_phase(LAS unsigned char* lds, int wid, int K, int lda, int ldb, bool bperm, const Sched3& S, const Epi& E) {
;     ...
;             PG8_STAGE(PG8_SB(0, 1), b2 + hstepB, voffB);
;             PG8_WAIT_V(6); PG8_BAR; if (full) PG8_MMA(1, 1, At, B1); PG8_BAR;
;             PG8_LDB(B0, 1, 0); PG8_SCHED; PG8_LDA(At, 1, 0); PG8_STAGE(PG8_SA(0, 1), a2 + h2, voffA);
;             PG8_WAIT_L(8); PG8_BAR; PG8_WAIT_L(0); PG8_MMA(0, 0, At, B0); PG8_BAR; PG8_SCHED;
;             PG8_LDB(B1, 1, 1); PG8_STAGE(PG8_SB(1, 0), b3, voffB);
;             PG8_BAR; PG8_WAIT_L(0); PG8_MMA(0, 1, At, B1); PG8_BAR;
;             PG8_LDA(At, 1, 1); PG8_STAGE(PG8_SA(1, 0), a3, voffA);
;             PG8_BAR; PG8_WAIT_L(0); if (full) PG8_MMA(1, 0, At, B0); PG8_BAR; PG8_SCHED;
;             PG8_STAGE(PG8_SB(1, 1), b3 + hstepB, voffB);
;             PG8_WAIT_V(6); PG8_BAR; if (full) PG8_MMA(1, 1, At, B1); PG8_BAR;
	s_add_u32 s62, s38, 0x80000
	s_addc_u32 s63, s39, 0
	s_add_i32 s61, s58, s47
	v_lshl_add_u64 v[128:129], s[62:63], 0, v[152:153]
	s_mov_b32 m0, s61
	s_nop 0
	global_load_lds_dwordx4 v[128:129], off
	v_lshl_add_u64 v[128:129], s[62:63], 0, v[154:155]
	s_add_i32 m0, s61, 0x2000
	s_nop 0
	global_load_lds_dwordx4 v[128:129], off
	s_waitcnt vmcnt(6)
	s_barrier
	s_setprio 1
	v_mfma_f32_16x16x32_bf16 v[52:55], v[196:199], v[144:147], v[52:55]
	v_mfma_f32_16x16x32_bf16 v[48:51], v[204:207], v[144:147], v[48:51]
	v_mfma_f32_16x16x32_bf16 v[36:39], v[196:199], v[162:165], v[36:39]
	v_mfma_f32_16x16x32_bf16 v[32:35], v[204:207], v[162:165], v[32:35]
	v_mfma_f32_16x16x32_bf16 v[20:23], v[196:199], v[170:173], v[20:23]
	v_mfma_f32_16x16x32_bf16 v[16:19], v[204:207], v[170:173], v[16:19]
	v_mfma_f32_16x16x32_bf16 v[4:7], v[196:199], v[188:191], v[4:7]
	v_mfma_f32_16x16x32_bf16 v[0:3], v[204:207], v[188:191], v[0:3]
	v_mfma_f32_16x16x32_bf16 v[52:55], v[200:203], v[148:151], v[52:55]
	v_mfma_f32_16x16x32_bf16 v[48:51], v[208:211], v[148:151], v[48:51]
	v_mfma_f32_16x16x32_bf16 v[36:39], v[200:203], v[166:169], v[36:39]
	v_mfma_f32_16x16x32_bf16 v[32:35], v[208:211], v[166:169], v[32:35]
	v_mfma_f32_16x16x32_bf16 v[20:23], v[200:203], v[174:177], v[20:23]
	v_mfma_f32_16x16x32_bf16 v[16:19], v[208:211], v[174:177], v[16:19]
	v_mfma_f32_16x16x32_bf16 v[4:7], v[200:203], v[192:195], v[4:7]
	v_mfma_f32_16x16x32_bf16 v[0:3], v[208:211], v[192:195], v[0:3]
	s_setprio 0
	s_add_i32 s61, 0, 0x18000
	v_add_u32_e32 v140, s61, v181
	s_barrier
	ds_read_b128 v[128:131], v140
	ds_read_b128 v[132:135], v140 offset:1024
	ds_read_b128 v[136:139], v140 offset:2048
	ds_read_b128 v[140:143], v140 offset:3072
	s_add_u32 s40, s40, 0x80000
	s_addc_u32 s41, s41, 0
	s_mov_b32 m0, s50
	v_lshl_add_u64 v[196:197], s[40:41], 0, v[152:153]
	ds_read_b128 v[144:147], v186 offset:32768
	ds_read_b128 v[148:151], v186 offset:33792
	ds_read_b128 v[162:165], v186 offset:34816
	ds_read_b128 v[166:169], v186 offset:35840
	ds_read_b128 v[170:173], v186 offset:36864
	ds_read_b128 v[174:177], v186 offset:37888
	ds_read_b128 v[188:191], v186 offset:38912
	ds_read_b128 v[192:195], v186 offset:39936
	global_load_lds_dwordx4 v[196:197], off
	v_lshl_add_u64 v[196:197], s[40:41], 0, v[154:155]
	s_mov_b32 m0, s51
	s_nop 0
	global_load_lds_dwordx4 v[196:197], off
	s_waitcnt lgkmcnt(8)
	s_barrier
	s_waitcnt lgkmcnt(0)
	s_setprio 1
	s_waitcnt lgkmcnt(0)
	v_mfma_f32_16x16x32_bf16 v[124:127], v[128:131], v[144:147], v[124:127]
	v_mfma_f32_16x16x32_bf16 v[120:123], v[136:139], v[144:147], v[120:123]
	v_mfma_f32_16x16x32_bf16 v[108:111], v[128:131], v[162:165], v[108:111]
	v_mfma_f32_16x16x32_bf16 v[104:107], v[136:139], v[162:165], v[104:107]
	v_mfma_f32_16x16x32_bf16 v[92:95], v[128:131], v[170:173], v[92:95]
	v_mfma_f32_16x16x32_bf16 v[88:91], v[136:139], v[170:173], v[88:91]
	v_mfma_f32_16x16x32_bf16 v[76:79], v[128:131], v[188:191], v[76:79]
	v_mfma_f32_16x16x32_bf16 v[72:75], v[136:139], v[188:191], v[72:75]
	v_mfma_f32_16x16x32_bf16 v[124:127], v[132:135], v[148:151], v[124:127]
	v_mfma_f32_16x16x32_bf16 v[120:123], v[140:143], v[148:151], v[120:123]
	v_mfma_f32_16x16x32_bf16 v[108:111], v[132:135], v[166:169], v[108:111]
	v_mfma_f32_16x16x32_bf16 v[104:107], v[140:143], v[166:169], v[104:107]
	v_mfma_f32_16x16x32_bf16 v[92:95], v[132:135], v[174:177], v[92:95]
	v_mfma_f32_16x16x32_bf16 v[88:91], v[140:143], v[174:177], v[88:91]
	v_mfma_f32_16x16x32_bf16 v[76:79], v[132:135], v[192:195], v[76:79]
	v_mfma_f32_16x16x32_bf16 v[72:75], v[140:143], v[192:195], v[72:75]
	s_setprio 0
	s_barrier
	s_add_i32 s40, 0, 0x1c000
	s_add_i32 s41, s61, s47
	v_add_u32_e32 v208, s40, v181
	v_lshl_add_u64 v[178:179], v[178:179], 0, s[12:13]
	s_mov_b32 m0, s41
	ds_read_b128 v[196:199], v208
	ds_read_b128 v[200:203], v208 offset:1024
	ds_read_b128 v[204:207], v208 offset:2048
	ds_read_b128 v[208:211], v208 offset:3072
	global_load_lds_dwordx4 v[178:179], off
	v_lshl_add_u64 v[178:179], v[212:213], 0, s[12:13]
	s_add_i32 m0, s41, 0x2000
	s_nop 0
	global_load_lds_dwordx4 v[178:179], off
	s_barrier
	s_waitcnt lgkmcnt(0)
	s_setprio 1
	s_waitcnt lgkmcnt(0)
	v_mfma_f32_16x16x32_bf16 v[116:119], v[196:199], v[144:147], v[116:119]
	v_mfma_f32_16x16x32_bf16 v[112:115], v[204:207], v[144:147], v[112:115]
	v_mfma_f32_16x16x32_bf16 v[100:103], v[196:199], v[162:165], v[100:103]
	v_mfma_f32_16x16x32_bf16 v[96:99], v[204:207], v[162:165], v[96:99]
	v_mfma_f32_16x16x32_bf16 v[84:87], v[196:199], v[170:173], v[84:87]
	v_mfma_f32_16x16x32_bf16 v[80:83], v[204:207], v[170:173], v[80:83]
	v_mfma_f32_16x16x32_bf16 v[68:71], v[196:199], v[188:191], v[68:71]
	v_mfma_f32_16x16x32_bf16 v[64:67], v[204:207], v[188:191], v[64:67]
	v_mfma_f32_16x16x32_bf16 v[116:119], v[200:203], v[148:151], v[116:119]
	v_mfma_f32_16x16x32_bf16 v[112:115], v[208:211], v[148:151], v[112:115]
	v_mfma_f32_16x16x32_bf16 v[100:103], v[200:203], v[166:169], v[100:103]
	v_mfma_f32_16x16x32_bf16 v[96:99], v[208:211], v[166:169], v[96:99]
	v_mfma_f32_16x16x32_bf16 v[84:87], v[200:203], v[174:177], v[84:87]
	v_mfma_f32_16x16x32_bf16 v[80:83], v[208:211], v[174:177], v[80:83]
	v_mfma_f32_16x16x32_bf16 v[68:71], v[200:203], v[192:195], v[68:71]
	v_mfma_f32_16x16x32_bf16 v[64:67], v[208:211], v[192:195], v[64:67]
	s_setprio 0
	s_mov_b32 m0, s53
	v_lshl_add_u64 v[178:179], v[214:215], 0, s[12:13]
	s_barrier
	ds_read_b128 v[144:147], v186 offset:49152
	ds_read_b128 v[148:151], v186 offset:50176
	ds_read_b128 v[162:165], v186 offset:51200
	ds_read_b128 v[166:169], v186 offset:52224
	ds_read_b128 v[170:173], v186 offset:53248
	ds_read_b128 v[174:177], v186 offset:54272
	ds_read_b128 v[188:191], v186 offset:55296
	ds_read_b128 v[192:195], v186 offset:56320
	global_load_lds_dwordx4 v[178:179], off
	v_lshl_add_u64 v[178:179], v[216:217], 0, s[12:13]
	s_mov_b32 m0, s54
	s_nop 0
	global_load_lds_dwordx4 v[178:179], off
	s_barrier
; DI u32x2 pk4(f32x4 v) { u32x2 r; r.x = pk2(v[0], v[1]); r.y = pk2(v[2], v[3]); return r; }
; DI float bf_lo(unsigned w) { return __uint_as_float(w << 16); }
; DI float bf_hi(unsigned w) { return __uint_as_float(w & 0xffff0000u); }
; #define PG8_LDA(dst, b, h) do { _Pragma("unroll") for (int m = 0; m < 4; ++m) _Pragma("unroll") for (int k = 0; k < 2; ++k) dst[m][k] = *(const LAS bf16x8*)(lds + PG8_SA(b, h) + aoff + m * 2048 + k * 1024); } while (0)
; template <class Epi>
; DI void gemm_phase(LAS unsigned char* lds, int wid, int K, int lda, int ldb, bool bperm, const Sched3& S, const Epi& E) {
;     ...
;             PG8_LDA(At, 1, 1); PG8_STAGE(PG8_SA(1, 0), a3, voffA);
;             PG8_BAR; PG8_WAIT_L(0); if (full) PG8_MMA(1, 0, At, B0); PG8_BAR; PG8_SCHED;
;             PG8_STAGE(PG8_SB(1, 1), b3 + hstepB, voffB);
;             PG8_WAIT_V(6); PG8_BAR; if (full) PG8_MMA(1, 1, At, B1); PG8_BAR;
;         }
;     DI void operator()(const Acc& acc, const Unit& u, int wr, int wc, int fr, int fq) const {
;     ...
;                 for (int m = 0; m < 4; ++m) { const size_t o = (size_t)(row0 + ai * HALF + m * 16) * 2048 + colp;
;                     if (PH == 4) { COLS4 xo[m][bj][n] = *(const f32x4*)(p.x + o + bj * HALF + n * 4); }
;                     else {
; #pragma unroll
;                         for (int bj = 0; bj < 2; ++bj) { const u32x4 w = *(const u32x4*)(WSB(OFF_XB) + o + bj * HALF);
;                             xo[m][bj][0] = (f32x4){bf_lo(w.x), bf_hi(w.x), bf_lo(w.y), bf_hi(w.y)}; xo[m][bj][1] = (f32x4){bf_lo(w.z), bf_hi(w.z), bf_lo(w.w), bf_hi(w.w)}; } } }
; #pragma unroll
;                 for (int m = 0; m < 4; ++m) { const int r = row0 + ai * HALF + m * 16; const size_t o = (size_t)r * 2048 + colp; float part = 0.f;
; #pragma unroll
;                     for (int bj = 0; bj < 2; ++bj) { const f32x4 x0 = xo[m][bj][0] + acc[ai][bj][m][0], x1 = xo[m][bj][1] + acc[ai][bj][m][1];
;                         const u32x2 h0 = pk4(x0), h1 = pk4(x1);
;                         *(u32x4*)(WSB(OFF_XB) + o + bj * HALF) = (u32x4){h0.x, h0.y, h1.x, h1.y};
;                         part += x0[0] * x0[0] + x0[1] * x0[1] + x0[2] * x0[2] + x0[3] * x0[3] + x1[0] * x1[0] + x1[1] * x1[1] + x1[2] * x1[2] + x1[3] * x1[3]; }
;                     part += __shfl_xor(part, 16); part += __shfl_xor(part, 32);
;                     if (fq == 0) unsafeAtomicAdd(ssq + r, part);
	s_waitcnt lgkmcnt(0)
	s_setprio 1
	s_waitcnt lgkmcnt(0)
	v_mfma_f32_16x16x32_bf16 v[60:63], v[128:131], v[144:147], v[60:63]
	v_mfma_f32_16x16x32_bf16 v[56:59], v[136:139], v[144:147], v[56:59]
	v_mfma_f32_16x16x32_bf16 v[44:47], v[128:131], v[162:165], v[44:47]
	v_mfma_f32_16x16x32_bf16 v[40:43], v[136:139], v[162:165], v[40:43]
	v_mfma_f32_16x16x32_bf16 v[28:31], v[128:131], v[170:173], v[28:31]
	v_mfma_f32_16x16x32_bf16 v[24:27], v[136:139], v[170:173], v[24:27]
	v_mfma_f32_16x16x32_bf16 v[12:15], v[128:131], v[188:191], v[12:15]
	v_mfma_f32_16x16x32_bf16 v[8:11], v[136:139], v[188:191], v[8:11]
	v_mfma_f32_16x16x32_bf16 v[60:63], v[132:135], v[148:151], v[60:63]
	v_mfma_f32_16x16x32_bf16 v[56:59], v[140:143], v[148:151], v[56:59]
	v_mfma_f32_16x16x32_bf16 v[44:47], v[132:135], v[166:169], v[44:47]
	v_mfma_f32_16x16x32_bf16 v[40:43], v[140:143], v[166:169], v[40:43]
	v_mfma_f32_16x16x32_bf16 v[28:31], v[132:135], v[174:177], v[28:31]
	v_mfma_f32_16x16x32_bf16 v[24:27], v[140:143], v[174:177], v[24:27]
	v_mfma_f32_16x16x32_bf16 v[12:15], v[132:135], v[192:195], v[12:15]
	v_mfma_f32_16x16x32_bf16 v[8:11], v[140:143], v[192:195], v[8:11]
	s_setprio 0
	s_barrier
	s_add_u32 s38, s38, 0x80080
	s_addc_u32 s39, s39, 0
	s_add_i32 s40, s40, s47
	v_lshl_add_u64 v[128:129], s[38:39], 0, v[152:153]
	s_mov_b32 m0, s40
	s_nop 0
	global_load_lds_dwordx4 v[128:129], off
	v_lshl_add_u64 v[128:129], s[38:39], 0, v[154:155]
	s_add_i32 m0, s40, 0x2000
	s_nop 0
	global_load_lds_dwordx4 v[128:129], off
	s_waitcnt vmcnt(6)
	s_barrier
	s_setprio 1
	v_mfma_f32_16x16x32_bf16 v[52:55], v[196:199], v[144:147], v[52:55]
	v_mfma_f32_16x16x32_bf16 v[48:51], v[204:207], v[144:147], v[48:51]
	v_mfma_f32_16x16x32_bf16 v[36:39], v[196:199], v[162:165], v[36:39]
	v_mfma_f32_16x16x32_bf16 v[32:35], v[204:207], v[162:165], v[32:35]
	v_mfma_f32_16x16x32_bf16 v[20:23], v[196:199], v[170:173], v[20:23]
	v_mfma_f32_16x16x32_bf16 v[16:19], v[204:207], v[170:173], v[16:19]
	v_mfma_f32_16x16x32_bf16 v[4:7], v[196:199], v[188:191], v[4:7]
	v_mfma_f32_16x16x32_bf16 v[0:3], v[204:207], v[188:191], v[0:3]
	v_mfma_f32_16x16x32_bf16 v[52:55], v[200:203], v[148:151], v[52:55]
	v_mfma_f32_16x16x32_bf16 v[48:51], v[208:211], v[148:151], v[48:51]
	v_mfma_f32_16x16x32_bf16 v[36:39], v[200:203], v[166:169], v[36:39]
	v_mfma_f32_16x16x32_bf16 v[32:35], v[208:211], v[166:169], v[32:35]
	v_mfma_f32_16x16x32_bf16 v[20:23], v[200:203], v[174:177], v[20:23]
	v_mfma_f32_16x16x32_bf16 v[16:19], v[208:211], v[174:177], v[16:19]
	v_mfma_f32_16x16x32_bf16 v[4:7], v[200:203], v[192:195], v[4:7]
	v_mfma_f32_16x16x32_bf16 v[0:3], v[208:211], v[192:195], v[0:3]
	s_setprio 0
	s_add_i32 s27, s27, 2
	s_add_u32 s36, s36, 0x100
	s_addc_u32 s37, s37, 0
	s_add_u32 s19, s19, 0x100
	s_addc_u32 s21, s21, 0
	s_cmp_gt_u32 s27, 29
	s_barrier
	s_cbranch_scc0 .LBB0_1176
	v_lshl_add_u32 v128, s60, 8, v182
	v_lshl_add_u32 v166, s26, 8, v180
	v_ashrrev_i32_e32 v129, 31, v128
	v_lshlrev_b64 v[162:163], 1, v[128:129]
	v_ashrrev_i32_e32 v167, 31, v166
	v_lshl_add_u64 v[164:165], s[16:17], 0, v[162:163]
	v_lshlrev_b64 v[196:197], 12, v[166:167]
	v_lshl_add_u64 v[128:129], v[164:165], 0, v[196:197]
	global_load_dwordx4 v[188:191], v[128:129], off
	global_load_dwordx4 v[192:195], v[128:129], off offset:256
	v_or_b32_e32 v176, 16, v166
	v_or_b32_e32 v172, 32, v166
	v_or_b32_e32 v168, 48, v166
	v_ashrrev_i32_e32 v177, 31, v176
	v_ashrrev_i32_e32 v173, 31, v172
	v_ashrrev_i32_e32 v169, 31, v168
	v_lshlrev_b64 v[178:179], 12, v[176:177]
	v_lshlrev_b64 v[174:175], 12, v[172:173]
	v_lshlrev_b64 v[170:171], 12, v[168:169]
	v_lshl_add_u64 v[128:129], v[164:165], 0, v[178:179]
	v_lshl_add_u64 v[130:131], v[164:165], 0, v[174:175]
	v_lshl_add_u64 v[198:199], v[164:165], 0, v[170:171]
	global_load_dwordx4 v[148:151], v[128:129], off
	global_load_dwordx4 v[144:147], v[128:129], off offset:256
	global_load_dwordx4 v[140:143], v[130:131], off
	global_load_dwordx4 v[136:139], v[130:131], off offset:256
	global_load_dwordx4 v[132:135], v[198:199], off
	s_nop 0
	global_load_dwordx4 v[128:131], v[198:199], off offset:256
	v_lshl_add_u64 v[198:199], s[16:17], 0, v[196:197]
	v_lshl_add_u64 v[198:199], v[198:199], 0, v[162:163]
	v_lshl_add_u64 v[196:197], s[10:11], 0, v[196:197]
	v_lshl_add_u64 v[196:197], v[196:197], 0, v[162:163]
	s_waitcnt vmcnt(0)
	v_lshlrev_b32_e32 v200, 16, v188
	v_and_b32_e32 v201, 0xffff0000, v188
	v_lshlrev_b32_e32 v188, 16, v189
	v_and_b32_e32 v189, 0xffff0000, v189
	v_lshlrev_b32_e32 v204, 16, v192
	v_and_b32_e32 v205, 0xffff0000, v192
	v_lshlrev_b32_e32 v192, 16, v193
	v_and_b32_e32 v193, 0xffff0000, v193
	v_lshlrev_b32_e32 v206, 16, v194
	v_and_b32_e32 v207, 0xffff0000, v194
	v_add_f32_e32 v126, v126, v188
	v_add_f32_e32 v127, v127, v189
	v_add_f32_e32 v124, v124, v200
	v_add_f32_e32 v125, v125, v201
	v_add_f32_e32 v188, v116, v204
	v_add_f32_e32 v189, v117, v205
	v_add_f32_e32 v118, v118, v192
	v_add_f32_e32 v119, v119, v193
	v_add_f32_e32 v192, v112, v206
	v_add_f32_e32 v193, v113, v207
	v_cvt_pk_bf16_f32 v112, v124, v125
	v_mul_f32_e32 v117, v125, v125
	v_mul_f32_e32 v125, v189, v189
	v_fmac_f32_e32 v117, v124, v124
	v_fmac_f32_e32 v125, v188, v188
	v_lshlrev_b32_e32 v202, 16, v190
	v_and_b32_e32 v203, 0xffff0000, v190
	v_fmac_f32_e32 v117, v126, v126
	v_fmac_f32_e32 v125, v118, v118
	v_add_f32_e32 v120, v120, v202
	v_add_f32_e32 v121, v121, v203
	v_fmac_f32_e32 v117, v127, v127
	v_fmac_f32_e32 v125, v119, v119
	v_lshlrev_b32_e32 v190, 16, v191
	v_and_b32_e32 v191, 0xffff0000, v191
	v_lshlrev_b32_e32 v194, 16, v195
	v_and_b32_e32 v195, 0xffff0000, v195
	v_fmac_f32_e32 v117, v120, v120
	v_fmac_f32_e32 v125, v192, v192
	v_add_f32_e32 v122, v122, v190
	v_add_f32_e32 v123, v123, v191
	v_add_f32_e32 v190, v114, v194
	v_add_f32_e32 v191, v115, v195
	v_fmac_f32_e32 v117, v121, v121
	v_fmac_f32_e32 v125, v193, v193
	v_fmac_f32_e32 v117, v122, v122
	v_fmac_f32_e32 v125, v190, v190
	v_fmac_f32_e32 v117, v123, v123
	v_fmac_f32_e32 v125, v191, v191
	v_cvt_pk_bf16_f32 v114, v120, v121
	v_add_f32_e32 v120, v117, v125
	ds_bpermute_b32 v121, v183, v120
	v_cvt_pk_bf16_f32 v113, v126, v127
	v_cvt_pk_bf16_f32 v115, v122, v123
	global_store_dwordx4 v[198:199], v[112:115], off sc1
	v_cvt_pk_bf16_f32 v116, v188, v189
	v_cvt_pk_bf16_f32 v117, v118, v119
	s_waitcnt lgkmcnt(0)
	v_add_f32_e32 v112, v120, v121
	ds_bpermute_b32 v113, v184, v112
	v_add_co_u32_e32 v114, vcc, s59, v196
	v_cvt_pk_bf16_f32 v118, v192, v193
	v_cvt_pk_bf16_f32 v119, v190, v191
	v_addc_co_u32_e32 v115, vcc, 0, v197, vcc
	global_store_dwordx4 v[114:115], v[116:119], off offset:256 sc1
	s_and_saveexec_b64 s[26:27], s[2:3]
	s_cbranch_execz .LBB0_1179
	s_waitcnt lgkmcnt(0)
	v_add_f32_e32 v114, v112, v113
	v_lshl_add_u64 v[112:113], v[166:167], 2, s[14:15]
	global_atomic_add_f32 v[112:113], v114, off
; DI u32x2 pk4(f32x4 v) { u32x2 r; r.x = pk2(v[0], v[1]); r.y = pk2(v[2], v[3]); return r; }
;     DI void operator()(const Acc& acc, const Unit& u, int wr, int wc, int fr, int fq) const {
;     ...
;                 for (int m = 0; m < 4; ++m) { const int r = row0 + ai * HALF + m * 16; const size_t o = (size_t)r * 2048 + colp; float part = 0.f;
; #pragma unroll
;                     for (int bj = 0; bj < 2; ++bj) { const f32x4 x0 = xo[m][bj][0] + acc[ai][bj][m][0], x1 = xo[m][bj][1] + acc[ai][bj][m][1];
;                         const u32x2 h0 = pk4(x0), h1 = pk4(x1);
;                         *(u32x4*)(WSB(OFF_XB) + o + bj * HALF) = (u32x4){h0.x, h0.y, h1.x, h1.y};
;                         part += x0[0] * x0[0] + x0[1] * x0[1] + x0[2] * x0[2] + x0[3] * x0[3] + x1[0] * x1[0] + x1[1] * x1[1] + x1[2] * x1[2] + x1[3] * x1[3]; }
;                     part += __shfl_xor(part, 16); part += __shfl_xor(part, 32);
;                     if (fq == 0) unsafeAtomicAdd(ssq + r, part);
.LBB0_1179:
	s_or_b64 exec, exec, s[26:27]
	v_lshlrev_b32_e32 v112, 16, v148
	s_waitcnt lgkmcnt(0)
	v_and_b32_e32 v113, 0xffff0000, v148
	v_lshlrev_b32_e32 v114, 16, v149
	v_and_b32_e32 v115, 0xffff0000, v149
	v_lshlrev_b32_e32 v116, 16, v150
	v_and_b32_e32 v117, 0xffff0000, v150
	v_lshlrev_b32_e32 v118, 16, v151
	v_and_b32_e32 v119, 0xffff0000, v151
	v_lshlrev_b32_e32 v120, 16, v144
	v_and_b32_e32 v121, 0xffff0000, v144
	v_add_f32_e32 v110, v110, v114
	v_add_f32_e32 v111, v111, v115
	v_add_f32_e32 v108, v108, v112
	v_add_f32_e32 v109, v109, v113
	v_add_f32_e32 v112, v106, v118
	v_add_f32_e32 v113, v107, v119
	v_add_f32_e32 v114, v104, v116
	v_add_f32_e32 v115, v105, v117
	v_lshl_add_u64 v[116:117], s[16:17], 0, v[178:179]
	v_lshlrev_b32_e32 v126, 16, v147
	v_and_b32_e32 v127, 0xffff0000, v147
	v_cvt_pk_bf16_f32 v104, v108, v109
	v_cvt_pk_bf16_f32 v105, v110, v111
	v_cvt_pk_bf16_f32 v106, v114, v115
	v_cvt_pk_bf16_f32 v107, v112, v113
	v_lshl_add_u64 v[116:117], v[116:117], 0, v[162:163]
	v_add_f32_e32 v100, v100, v120
	v_add_f32_e32 v101, v101, v121
	v_lshlrev_b32_e32 v122, 16, v145
	v_and_b32_e32 v123, 0xffff0000, v145
	global_store_dwordx4 v[116:117], v[104:107], off sc1
	v_add_f32_e32 v102, v102, v122
	v_add_f32_e32 v103, v103, v123
	v_lshlrev_b32_e32 v124, 16, v146
	v_mul_f32_e32 v106, v109, v109
	v_add_f32_e32 v104, v98, v126
	v_add_f32_e32 v105, v99, v127
	v_cvt_pk_bf16_f32 v98, v100, v101
	v_mul_f32_e32 v101, v101, v101
	v_fmac_f32_e32 v106, v108, v108
	v_fmac_f32_e32 v101, v100, v100
	v_and_b32_e32 v125, 0xffff0000, v146
	v_fmac_f32_e32 v106, v110, v110
	v_fmac_f32_e32 v101, v102, v102
	v_fmac_f32_e32 v106, v111, v111
	v_add_f32_e32 v96, v96, v124
	v_add_f32_e32 v97, v97, v125
	v_fmac_f32_e32 v101, v103, v103
	v_fmac_f32_e32 v106, v114, v114
	v_fmac_f32_e32 v101, v96, v96
	v_fmac_f32_e32 v106, v115, v115
	v_fmac_f32_e32 v101, v97, v97
	v_fmac_f32_e32 v106, v112, v112
	v_fmac_f32_e32 v101, v104, v104
	v_fmac_f32_e32 v106, v113, v113
	v_fmac_f32_e32 v101, v105, v105
	v_add_f32_e32 v106, v106, v101
	ds_bpermute_b32 v107, v183, v106
	v_cvt_pk_bf16_f32 v100, v96, v97
	v_lshl_add_u64 v[96:97], s[10:11], 0, v[178:179]
	v_cvt_pk_bf16_f32 v99, v102, v103
	v_lshl_add_u64 v[102:103], v[96:97], 0, v[162:163]
	s_waitcnt lgkmcnt(0)
	v_add_f32_e32 v96, v106, v107
	ds_bpermute_b32 v97, v184, v96
	v_add_co_u32_e32 v102, vcc, s59, v102
	v_cvt_pk_bf16_f32 v101, v104, v105
	s_nop 0
	v_addc_co_u32_e32 v103, vcc, 0, v103, vcc
	global_store_dwordx4 v[102:103], v[98:101], off offset:256 sc1
	s_and_saveexec_b64 s[26:27], s[2:3]
	s_cbranch_execz .LBB0_1181
	s_waitcnt lgkmcnt(0)
	v_add_f32_e32 v98, v96, v97
	v_lshl_add_u64 v[96:97], v[176:177], 2, s[14:15]
	global_atomic_add_f32 v[96:97], v98, off
.LBB0_1181:
	s_or_b64 exec, exec, s[26:27]
	v_lshlrev_b32_e32 v96, 16, v140
	s_waitcnt lgkmcnt(0)
	v_and_b32_e32 v97, 0xffff0000, v140
	v_lshlrev_b32_e32 v98, 16, v141
	v_and_b32_e32 v99, 0xffff0000, v141
	v_lshlrev_b32_e32 v100, 16, v142
	v_and_b32_e32 v101, 0xffff0000, v142
	v_lshlrev_b32_e32 v102, 16, v143
	v_and_b32_e32 v103, 0xffff0000, v143
	v_lshlrev_b32_e32 v104, 16, v136
	v_and_b32_e32 v105, 0xffff0000, v136
	v_add_f32_e32 v94, v94, v98
	v_add_f32_e32 v95, v95, v99
	v_add_f32_e32 v92, v92, v96
	v_add_f32_e32 v93, v93, v97
	v_add_f32_e32 v96, v90, v102
	v_add_f32_e32 v97, v91, v103
	v_add_f32_e32 v98, v88, v100
	v_add_f32_e32 v99, v89, v101
	v_lshl_add_u64 v[100:101], s[16:17], 0, v[174:175]
	v_lshlrev_b32_e32 v110, 16, v139
	v_and_b32_e32 v111, 0xffff0000, v139
	v_cvt_pk_bf16_f32 v88, v92, v93
	v_cvt_pk_bf16_f32 v89, v94, v95
	v_cvt_pk_bf16_f32 v90, v98, v99
	v_cvt_pk_bf16_f32 v91, v96, v97
	v_lshl_add_u64 v[100:101], v[100:101], 0, v[162:163]
	v_add_f32_e32 v84, v84, v104
	v_add_f32_e32 v85, v85, v105
	v_lshlrev_b32_e32 v106, 16, v137
	v_and_b32_e32 v107, 0xffff0000, v137
	global_store_dwordx4 v[100:101], v[88:91], off sc1
	v_add_f32_e32 v86, v86, v106
	v_add_f32_e32 v87, v87, v107
	v_lshlrev_b32_e32 v108, 16, v138
	v_mul_f32_e32 v90, v93, v93
	v_add_f32_e32 v88, v82, v110
	v_add_f32_e32 v89, v83, v111
	v_cvt_pk_bf16_f32 v82, v84, v85
	v_mul_f32_e32 v85, v85, v85
	v_fmac_f32_e32 v90, v92, v92
	v_fmac_f32_e32 v85, v84, v84
	v_and_b32_e32 v109, 0xffff0000, v138
	v_fmac_f32_e32 v90, v94, v94
	v_fmac_f32_e32 v85, v86, v86
	v_fmac_f32_e32 v90, v95, v95
	v_add_f32_e32 v80, v80, v108
	v_add_f32_e32 v81, v81, v109
	v_fmac_f32_e32 v85, v87, v87
	v_fmac_f32_e32 v90, v98, v98
	v_fmac_f32_e32 v85, v80, v80
	v_fmac_f32_e32 v90, v99, v99
	v_fmac_f32_e32 v85, v81, v81
	v_fmac_f32_e32 v90, v96, v96
	v_fmac_f32_e32 v85, v88, v88
	v_fmac_f32_e32 v90, v97, v97
	v_fmac_f32_e32 v85, v89, v89
	v_add_f32_e32 v90, v90, v85
	ds_bpermute_b32 v91, v183, v90
	v_cvt_pk_bf16_f32 v84, v80, v81
	v_lshl_add_u64 v[80:81], s[10:11], 0, v[174:175]
	v_cvt_pk_bf16_f32 v83, v86, v87
	v_lshl_add_u64 v[86:87], v[80:81], 0, v[162:163]
	s_waitcnt lgkmcnt(0)
	v_add_f32_e32 v80, v90, v91
	ds_bpermute_b32 v81, v184, v80
	v_add_co_u32_e32 v86, vcc, s59, v86
	v_cvt_pk_bf16_f32 v85, v88, v89
	s_nop 0
	v_addc_co_u32_e32 v87, vcc, 0, v87, vcc
	global_store_dwordx4 v[86:87], v[82:85], off offset:256 sc1
	s_and_saveexec_b64 s[26:27], s[2:3]
	s_cbranch_execz .LBB0_1183
	s_waitcnt lgkmcnt(0)
	v_add_f32_e32 v82, v80, v81
	v_lshl_add_u64 v[80:81], v[172:173], 2, s[14:15]
	global_atomic_add_f32 v[80:81], v82, off
; DI u32x2 pk4(f32x4 v) { u32x2 r; r.x = pk2(v[0], v[1]); r.y = pk2(v[2], v[3]); return r; }
; DI float bf_lo(unsigned w) { return __uint_as_float(w << 16); }
; DI float bf_hi(unsigned w) { return __uint_as_float(w & 0xffff0000u); }
; #define COLS4 _Pragma("unroll") for (int bj = 0; bj < 2; ++bj) _Pragma("unroll") for (int n = 0; n < 2; ++n)
;     DI void operator()(const Acc& acc, const Unit& u, int wr, int wc, int fr, int fq) const {
;     ...
;                 for (int m = 0; m < 4; ++m) { const size_t o = (size_t)(row0 + ai * HALF + m * 16) * 2048 + colp;
;                     if (PH == 4) { COLS4 xo[m][bj][n] = *(const f32x4*)(p.x + o + bj * HALF + n * 4); }
;                     else {
; #pragma unroll
;                         for (int bj = 0; bj < 2; ++bj) { const u32x4 w = *(const u32x4*)(WSB(OFF_XB) + o + bj * HALF);
;                             xo[m][bj][0] = (f32x4){bf_lo(w.x), bf_hi(w.x), bf_lo(w.y), bf_hi(w.y)}; xo[m][bj][1] = (f32x4){bf_lo(w.z), bf_hi(w.z), bf_lo(w.w), bf_hi(w.w)}; } } }
; #pragma unroll
;                 for (int m = 0; m < 4; ++m) { const int r = row0 + ai * HALF + m * 16; const size_t o = (size_t)r * 2048 + colp; float part = 0.f;
; #pragma unroll
;                     for (int bj = 0; bj < 2; ++bj) { const f32x4 x0 = xo[m][bj][0] + acc[ai][bj][m][0], x1 = xo[m][bj][1] + acc[ai][bj][m][1];
;                         const u32x2 h0 = pk4(x0), h1 = pk4(x1);
;                         *(u32x4*)(WSB(OFF_XB) + o + bj * HALF) = (u32x4){h0.x, h0.y, h1.x, h1.y};
;                         part += x0[0] * x0[0] + x0[1] * x0[1] + x0[2] * x0[2] + x0[3] * x0[3] + x1[0] * x1[0] + x1[1] * x1[1] + x1[2] * x1[2] + x1[3] * x1[3]; }
;                     part += __shfl_xor(part, 16); part += __shfl_xor(part, 32);
;                     if (fq == 0) unsafeAtomicAdd(ssq + r, part);
.LBB0_1183:
	s_or_b64 exec, exec, s[26:27]
	v_lshlrev_b32_e32 v80, 16, v132
	s_waitcnt lgkmcnt(0)
	v_and_b32_e32 v81, 0xffff0000, v132
	v_lshlrev_b32_e32 v82, 16, v133
	v_and_b32_e32 v83, 0xffff0000, v133
	v_lshlrev_b32_e32 v84, 16, v134
	v_and_b32_e32 v85, 0xffff0000, v134
	v_lshlrev_b32_e32 v86, 16, v135
	v_and_b32_e32 v87, 0xffff0000, v135
	v_lshlrev_b32_e32 v88, 16, v128
	v_and_b32_e32 v89, 0xffff0000, v128
	v_add_f32_e32 v78, v78, v82
	v_add_f32_e32 v79, v79, v83
	v_add_f32_e32 v76, v76, v80
	v_add_f32_e32 v77, v77, v81
	v_add_f32_e32 v80, v74, v86
	v_add_f32_e32 v81, v75, v87
	v_add_f32_e32 v82, v72, v84
	v_add_f32_e32 v83, v73, v85
	v_lshl_add_u64 v[84:85], s[16:17], 0, v[170:171]
	v_lshlrev_b32_e32 v94, 16, v131
	v_and_b32_e32 v95, 0xffff0000, v131
	v_cvt_pk_bf16_f32 v72, v76, v77
	v_cvt_pk_bf16_f32 v73, v78, v79
	v_cvt_pk_bf16_f32 v74, v82, v83
	v_cvt_pk_bf16_f32 v75, v80, v81
	v_lshl_add_u64 v[84:85], v[84:85], 0, v[162:163]
	v_add_f32_e32 v68, v68, v88
	v_add_f32_e32 v69, v69, v89
	v_lshlrev_b32_e32 v90, 16, v129
	v_and_b32_e32 v91, 0xffff0000, v129
	global_store_dwordx4 v[84:85], v[72:75], off sc1
	v_add_f32_e32 v70, v70, v90
	v_add_f32_e32 v71, v71, v91
	v_lshlrev_b32_e32 v92, 16, v130
	v_mul_f32_e32 v74, v77, v77
	v_add_f32_e32 v72, v66, v94
	v_add_f32_e32 v73, v67, v95
	v_cvt_pk_bf16_f32 v66, v68, v69
	v_mul_f32_e32 v69, v69, v69
	v_fmac_f32_e32 v74, v76, v76
	v_fmac_f32_e32 v69, v68, v68
	v_and_b32_e32 v93, 0xffff0000, v130
	v_fmac_f32_e32 v74, v78, v78
	v_fmac_f32_e32 v69, v70, v70
	v_fmac_f32_e32 v74, v79, v79
	v_add_f32_e32 v64, v64, v92
	v_add_f32_e32 v65, v65, v93
	v_fmac_f32_e32 v69, v71, v71
	v_fmac_f32_e32 v74, v82, v82
	v_fmac_f32_e32 v69, v64, v64
	v_fmac_f32_e32 v74, v83, v83
	v_fmac_f32_e32 v69, v65, v65
	v_fmac_f32_e32 v74, v80, v80
	v_fmac_f32_e32 v69, v72, v72
	v_fmac_f32_e32 v74, v81, v81
	v_fmac_f32_e32 v69, v73, v73
	v_add_f32_e32 v74, v74, v69
	ds_bpermute_b32 v75, v183, v74
	v_cvt_pk_bf16_f32 v68, v64, v65
	v_lshl_add_u64 v[64:65], s[10:11], 0, v[170:171]
	v_cvt_pk_bf16_f32 v67, v70, v71
	v_lshl_add_u64 v[70:71], v[64:65], 0, v[162:163]
	s_waitcnt lgkmcnt(0)
	v_add_f32_e32 v64, v74, v75
	ds_bpermute_b32 v65, v184, v64
	v_add_co_u32_e32 v70, vcc, s59, v70
	v_cvt_pk_bf16_f32 v69, v72, v73
	s_nop 0
	v_addc_co_u32_e32 v71, vcc, 0, v71, vcc
	global_store_dwordx4 v[70:71], v[66:69], off offset:256 sc1
	s_and_saveexec_b64 s[26:27], s[2:3]
	s_cbranch_execz .LBB0_1185
	s_waitcnt lgkmcnt(0)
	v_add_f32_e32 v66, v64, v65
	v_lshl_add_u64 v[64:65], v[168:169], 2, s[14:15]
	global_atomic_add_f32 v[64:65], v66, off
.LBB0_1185:
	s_or_b64 exec, exec, s[26:27]
	v_add_u32_e32 v100, 0x80, v166
	v_ashrrev_i32_e32 v101, 31, v100
	v_lshlrev_b64 v[110:111], 12, v[100:101]
	s_waitcnt lgkmcnt(0)
	v_lshl_add_u64 v[64:65], v[164:165], 0, v[110:111]
	global_load_dwordx4 v[102:105], v[64:65], off
	global_load_dwordx4 v[106:109], v[64:65], off offset:256
	v_add_u32_e32 v96, 0x90, v166
	v_add_u32_e32 v92, 0xa0, v166
	v_add_u32_e32 v88, 0xb0, v166
	v_ashrrev_i32_e32 v97, 31, v96
	v_ashrrev_i32_e32 v93, 31, v92
	v_ashrrev_i32_e32 v89, 31, v88
	v_lshlrev_b64 v[98:99], 12, v[96:97]
	v_lshlrev_b64 v[94:95], 12, v[92:93]
	v_lshlrev_b64 v[90:91], 12, v[88:89]
	v_lshl_add_u64 v[64:65], v[164:165], 0, v[98:99]
	v_lshl_add_u64 v[66:67], v[164:165], 0, v[94:95]
	v_lshl_add_u64 v[112:113], v[164:165], 0, v[90:91]
	global_load_dwordx4 v[84:87], v[64:65], off
	global_load_dwordx4 v[80:83], v[64:65], off offset:256
	global_load_dwordx4 v[76:79], v[66:67], off
	global_load_dwordx4 v[72:75], v[66:67], off offset:256
	global_load_dwordx4 v[68:71], v[112:113], off
	s_nop 0
	global_load_dwordx4 v[64:67], v[112:113], off offset:256
	v_lshl_add_u64 v[112:113], s[16:17], 0, v[110:111]
	v_lshl_add_u64 v[112:113], v[112:113], 0, v[162:163]
	v_lshl_add_u64 v[110:111], s[10:11], 0, v[110:111]
	v_lshl_add_u64 v[110:111], v[110:111], 0, v[162:163]
	s_waitcnt vmcnt(7)
	v_lshlrev_b32_e32 v114, 16, v102
	v_and_b32_e32 v115, 0xffff0000, v102
	v_lshlrev_b32_e32 v102, 16, v103
	v_and_b32_e32 v103, 0xffff0000, v103
	s_waitcnt vmcnt(6)
	v_lshlrev_b32_e32 v118, 16, v106
	v_and_b32_e32 v119, 0xffff0000, v106
	v_lshlrev_b32_e32 v106, 16, v107
	v_and_b32_e32 v107, 0xffff0000, v107
	v_lshlrev_b32_e32 v120, 16, v108
	v_and_b32_e32 v121, 0xffff0000, v108
	v_add_f32_e32 v62, v62, v102
	v_add_f32_e32 v63, v63, v103
	v_add_f32_e32 v60, v60, v114
	v_add_f32_e32 v61, v61, v115
	v_add_f32_e32 v102, v52, v118
	v_add_f32_e32 v103, v53, v119
	v_add_f32_e32 v54, v54, v106
	v_add_f32_e32 v55, v55, v107
	v_add_f32_e32 v106, v48, v120
	v_add_f32_e32 v107, v49, v121
	v_cvt_pk_bf16_f32 v48, v60, v61
	v_mul_f32_e32 v53, v61, v61
	v_mul_f32_e32 v61, v103, v103
	v_fmac_f32_e32 v53, v60, v60
	v_fmac_f32_e32 v61, v102, v102
	v_lshlrev_b32_e32 v116, 16, v104
	v_and_b32_e32 v117, 0xffff0000, v104
	v_fmac_f32_e32 v53, v62, v62
	v_fmac_f32_e32 v61, v54, v54
	v_add_f32_e32 v56, v56, v116
	v_add_f32_e32 v57, v57, v117
	v_fmac_f32_e32 v53, v63, v63
	v_fmac_f32_e32 v61, v55, v55
	v_lshlrev_b32_e32 v104, 16, v105
	v_and_b32_e32 v105, 0xffff0000, v105
	v_lshlrev_b32_e32 v108, 16, v109
	v_and_b32_e32 v109, 0xffff0000, v109
	v_fmac_f32_e32 v53, v56, v56
	v_fmac_f32_e32 v61, v106, v106
	v_add_f32_e32 v58, v58, v104
	v_add_f32_e32 v59, v59, v105
	v_add_f32_e32 v104, v50, v108
	v_add_f32_e32 v105, v51, v109
	v_fmac_f32_e32 v53, v57, v57
	v_fmac_f32_e32 v61, v107, v107
	v_fmac_f32_e32 v53, v58, v58
	v_fmac_f32_e32 v61, v104, v104
	v_fmac_f32_e32 v53, v59, v59
	v_fmac_f32_e32 v61, v105, v105
	v_cvt_pk_bf16_f32 v50, v56, v57
	v_add_f32_e32 v56, v53, v61
	ds_bpermute_b32 v57, v183, v56
	v_cvt_pk_bf16_f32 v49, v62, v63
	v_cvt_pk_bf16_f32 v51, v58, v59
	global_store_dwordx4 v[112:113], v[48:51], off sc1
	v_cvt_pk_bf16_f32 v52, v102, v103
	v_cvt_pk_bf16_f32 v53, v54, v55
	s_waitcnt lgkmcnt(0)
	v_add_f32_e32 v48, v56, v57
	ds_bpermute_b32 v49, v184, v48
	v_add_co_u32_e32 v50, vcc, s59, v110
	v_cvt_pk_bf16_f32 v54, v106, v107
	v_cvt_pk_bf16_f32 v55, v104, v105
	v_addc_co_u32_e32 v51, vcc, 0, v111, vcc
	global_store_dwordx4 v[50:51], v[52:55], off offset:256 sc1
	s_and_saveexec_b64 s[26:27], s[2:3]
	s_cbranch_execz .LBB0_1187
	s_waitcnt lgkmcnt(0)
	v_add_f32_e32 v50, v48, v49
	v_lshl_add_u64 v[48:49], v[100:101], 2, s[14:15]
	global_atomic_add_f32 v[48:49], v50, off
; DI u32x2 pk4(f32x4 v) { u32x2 r; r.x = pk2(v[0], v[1]); r.y = pk2(v[2], v[3]); return r; }
;     DI void operator()(const Acc& acc, const Unit& u, int wr, int wc, int fr, int fq) const {
;     ...
;                 for (int m = 0; m < 4; ++m) { const int r = row0 + ai * HALF + m * 16; const size_t o = (size_t)r * 2048 + colp; float part = 0.f;
; #pragma unroll
;                     for (int bj = 0; bj < 2; ++bj) { const f32x4 x0 = xo[m][bj][0] + acc[ai][bj][m][0], x1 = xo[m][bj][1] + acc[ai][bj][m][1];
;                         const u32x2 h0 = pk4(x0), h1 = pk4(x1);
;                         *(u32x4*)(WSB(OFF_XB) + o + bj * HALF) = (u32x4){h0.x, h0.y, h1.x, h1.y};
;                         part += x0[0] * x0[0] + x0[1] * x0[1] + x0[2] * x0[2] + x0[3] * x0[3] + x1[0] * x1[0] + x1[1] * x1[1] + x1[2] * x1[2] + x1[3] * x1[3]; }
;                     part += __shfl_xor(part, 16); part += __shfl_xor(part, 32);
;                     if (fq == 0) unsafeAtomicAdd(ssq + r, part);
.LBB0_1187:
	s_or_b64 exec, exec, s[26:27]
	s_waitcnt vmcnt(7)
	v_lshlrev_b32_e32 v48, 16, v84
	s_waitcnt lgkmcnt(0)
	v_and_b32_e32 v49, 0xffff0000, v84
	v_lshlrev_b32_e32 v50, 16, v85
	v_and_b32_e32 v51, 0xffff0000, v85
	v_lshlrev_b32_e32 v52, 16, v86
	v_and_b32_e32 v53, 0xffff0000, v86
	v_lshlrev_b32_e32 v54, 16, v87
	v_and_b32_e32 v55, 0xffff0000, v87
	s_waitcnt vmcnt(6)
	v_lshlrev_b32_e32 v56, 16, v80
	v_and_b32_e32 v57, 0xffff0000, v80
	v_add_f32_e32 v46, v46, v50
	v_add_f32_e32 v47, v47, v51
	v_add_f32_e32 v44, v44, v48
	v_add_f32_e32 v45, v45, v49
	v_add_f32_e32 v48, v42, v54
	v_add_f32_e32 v49, v43, v55
	v_add_f32_e32 v50, v40, v52
	v_add_f32_e32 v51, v41, v53
	v_lshl_add_u64 v[52:53], s[16:17], 0, v[98:99]
	v_lshlrev_b32_e32 v62, 16, v83
	v_and_b32_e32 v63, 0xffff0000, v83
	v_cvt_pk_bf16_f32 v40, v44, v45
	v_cvt_pk_bf16_f32 v41, v46, v47
	v_cvt_pk_bf16_f32 v42, v50, v51
	v_cvt_pk_bf16_f32 v43, v48, v49
	v_lshl_add_u64 v[52:53], v[52:53], 0, v[162:163]
	v_add_f32_e32 v36, v36, v56
	v_add_f32_e32 v37, v37, v57
	v_lshlrev_b32_e32 v58, 16, v81
	v_and_b32_e32 v59, 0xffff0000, v81
	global_store_dwordx4 v[52:53], v[40:43], off sc1
	v_add_f32_e32 v38, v38, v58
	v_add_f32_e32 v39, v39, v59
	v_lshlrev_b32_e32 v60, 16, v82
	v_mul_f32_e32 v42, v45, v45
	v_add_f32_e32 v40, v34, v62
	v_add_f32_e32 v41, v35, v63
	v_cvt_pk_bf16_f32 v34, v36, v37
	v_mul_f32_e32 v37, v37, v37
	v_fmac_f32_e32 v42, v44, v44
	v_fmac_f32_e32 v37, v36, v36
	v_and_b32_e32 v61, 0xffff0000, v82
	v_fmac_f32_e32 v42, v46, v46
	v_fmac_f32_e32 v37, v38, v38
	v_fmac_f32_e32 v42, v47, v47
	v_add_f32_e32 v32, v32, v60
	v_add_f32_e32 v33, v33, v61
	v_fmac_f32_e32 v37, v39, v39
	v_fmac_f32_e32 v42, v50, v50
	v_fmac_f32_e32 v37, v32, v32
	v_fmac_f32_e32 v42, v51, v51
	v_fmac_f32_e32 v37, v33, v33
	v_fmac_f32_e32 v42, v48, v48
	v_fmac_f32_e32 v37, v40, v40
	v_fmac_f32_e32 v42, v49, v49
	v_fmac_f32_e32 v37, v41, v41
	v_add_f32_e32 v42, v42, v37
	ds_bpermute_b32 v43, v183, v42
	v_cvt_pk_bf16_f32 v36, v32, v33
	v_lshl_add_u64 v[32:33], s[10:11], 0, v[98:99]
	v_cvt_pk_bf16_f32 v35, v38, v39
	v_lshl_add_u64 v[38:39], v[32:33], 0, v[162:163]
	s_waitcnt lgkmcnt(0)
	v_add_f32_e32 v32, v42, v43
	ds_bpermute_b32 v33, v184, v32
	v_add_co_u32_e32 v38, vcc, s59, v38
	v_cvt_pk_bf16_f32 v37, v40, v41
	s_nop 0
	v_addc_co_u32_e32 v39, vcc, 0, v39, vcc
	global_store_dwordx4 v[38:39], v[34:37], off offset:256 sc1
	s_and_saveexec_b64 s[26:27], s[2:3]
	s_cbranch_execz .LBB0_1189
	s_waitcnt lgkmcnt(0)
	v_add_f32_e32 v34, v32, v33
	v_lshl_add_u64 v[32:33], v[96:97], 2, s[14:15]
	global_atomic_add_f32 v[32:33], v34, off
; DI u32x2 pk4(f32x4 v) { u32x2 r; r.x = pk2(v[0], v[1]); r.y = pk2(v[2], v[3]); return r; }
;     DI void operator()(const Acc& acc, const Unit& u, int wr, int wc, int fr, int fq) const {
;     ...
;                 for (int m = 0; m < 4; ++m) { const int r = row0 + ai * HALF + m * 16; const size_t o = (size_t)r * 2048 + colp; float part = 0.f;
; #pragma unroll
;                     for (int bj = 0; bj < 2; ++bj) { const f32x4 x0 = xo[m][bj][0] + acc[ai][bj][m][0], x1 = xo[m][bj][1] + acc[ai][bj][m][1];
;                         const u32x2 h0 = pk4(x0), h1 = pk4(x1);
;                         *(u32x4*)(WSB(OFF_XB) + o + bj * HALF) = (u32x4){h0.x, h0.y, h1.x, h1.y};
;                         part += x0[0] * x0[0] + x0[1] * x0[1] + x0[2] * x0[2] + x0[3] * x0[3] + x1[0] * x1[0] + x1[1] * x1[1] + x1[2] * x1[2] + x1[3] * x1[3]; }
;                     part += __shfl_xor(part, 16); part += __shfl_xor(part, 32);
;                     if (fq == 0) unsafeAtomicAdd(ssq + r, part);
.LBB0_1189:
	s_or_b64 exec, exec, s[26:27]
	s_waitcnt vmcnt(7)
	v_lshlrev_b32_e32 v32, 16, v76
	s_waitcnt lgkmcnt(0)
	v_and_b32_e32 v33, 0xffff0000, v76
	v_lshlrev_b32_e32 v34, 16, v77
	v_and_b32_e32 v35, 0xffff0000, v77
	v_lshlrev_b32_e32 v36, 16, v78
	v_and_b32_e32 v37, 0xffff0000, v78
	v_lshlrev_b32_e32 v38, 16, v79
	v_and_b32_e32 v39, 0xffff0000, v79
	s_waitcnt vmcnt(6)
	v_lshlrev_b32_e32 v40, 16, v72
	v_and_b32_e32 v41, 0xffff0000, v72
	v_add_f32_e32 v30, v30, v34
	v_add_f32_e32 v31, v31, v35
	v_add_f32_e32 v28, v28, v32
	v_add_f32_e32 v29, v29, v33
	v_add_f32_e32 v32, v26, v38
	v_add_f32_e32 v33, v27, v39
	v_add_f32_e32 v34, v24, v36
	v_add_f32_e32 v35, v25, v37
	v_lshl_add_u64 v[36:37], s[16:17], 0, v[94:95]
	v_lshlrev_b32_e32 v46, 16, v75
	v_and_b32_e32 v47, 0xffff0000, v75
	v_cvt_pk_bf16_f32 v24, v28, v29
	v_cvt_pk_bf16_f32 v25, v30, v31
	v_cvt_pk_bf16_f32 v26, v34, v35
	v_cvt_pk_bf16_f32 v27, v32, v33
	v_lshl_add_u64 v[36:37], v[36:37], 0, v[162:163]
	v_add_f32_e32 v20, v20, v40
	v_add_f32_e32 v21, v21, v41
	v_lshlrev_b32_e32 v42, 16, v73
	v_and_b32_e32 v43, 0xffff0000, v73
	global_store_dwordx4 v[36:37], v[24:27], off sc1
	v_add_f32_e32 v22, v22, v42
	v_add_f32_e32 v23, v23, v43
	v_lshlrev_b32_e32 v44, 16, v74
	v_mul_f32_e32 v26, v29, v29
	v_add_f32_e32 v24, v18, v46
	v_add_f32_e32 v25, v19, v47
	v_cvt_pk_bf16_f32 v18, v20, v21
	v_mul_f32_e32 v21, v21, v21
	v_fmac_f32_e32 v26, v28, v28
	v_fmac_f32_e32 v21, v20, v20
	v_and_b32_e32 v45, 0xffff0000, v74
	v_fmac_f32_e32 v26, v30, v30
	v_fmac_f32_e32 v21, v22, v22
	v_fmac_f32_e32 v26, v31, v31
	v_add_f32_e32 v16, v16, v44
	v_add_f32_e32 v17, v17, v45
	v_fmac_f32_e32 v21, v23, v23
	v_fmac_f32_e32 v26, v34, v34
	v_fmac_f32_e32 v21, v16, v16
	v_fmac_f32_e32 v26, v35, v35
	v_fmac_f32_e32 v21, v17, v17
	v_fmac_f32_e32 v26, v32, v32
	v_fmac_f32_e32 v21, v24, v24
	v_fmac_f32_e32 v26, v33, v33
	v_fmac_f32_e32 v21, v25, v25
	v_add_f32_e32 v26, v26, v21
	ds_bpermute_b32 v27, v183, v26
	v_cvt_pk_bf16_f32 v20, v16, v17
	v_lshl_add_u64 v[16:17], s[10:11], 0, v[94:95]
	v_cvt_pk_bf16_f32 v19, v22, v23
	v_lshl_add_u64 v[22:23], v[16:17], 0, v[162:163]
	s_waitcnt lgkmcnt(0)
	v_add_f32_e32 v16, v26, v27
	ds_bpermute_b32 v17, v184, v16
	v_add_co_u32_e32 v22, vcc, s59, v22
	v_cvt_pk_bf16_f32 v21, v24, v25
	s_nop 0
	v_addc_co_u32_e32 v23, vcc, 0, v23, vcc
	global_store_dwordx4 v[22:23], v[18:21], off offset:256 sc1
	s_and_saveexec_b64 s[26:27], s[2:3]
	s_cbranch_execz .LBB0_1191
	s_waitcnt lgkmcnt(0)
	v_add_f32_e32 v18, v16, v17
	v_lshl_add_u64 v[16:17], v[92:93], 2, s[14:15]
	global_atomic_add_f32 v[16:17], v18, off
.LBB0_1191:
	s_or_b64 exec, exec, s[26:27]
	s_waitcnt vmcnt(7)
	v_lshlrev_b32_e32 v16, 16, v68
	s_waitcnt lgkmcnt(0)
	v_and_b32_e32 v17, 0xffff0000, v68
	v_lshlrev_b32_e32 v18, 16, v69
	v_and_b32_e32 v19, 0xffff0000, v69
	v_lshlrev_b32_e32 v20, 16, v70
	v_and_b32_e32 v21, 0xffff0000, v70
	v_lshlrev_b32_e32 v22, 16, v71
	v_and_b32_e32 v23, 0xffff0000, v71
	s_waitcnt vmcnt(6)
	v_lshlrev_b32_e32 v24, 16, v64
	v_and_b32_e32 v25, 0xffff0000, v64
	v_add_f32_e32 v14, v14, v18
	v_add_f32_e32 v15, v15, v19
	v_add_f32_e32 v12, v12, v16
	v_add_f32_e32 v13, v13, v17
	v_add_f32_e32 v16, v10, v22
	v_add_f32_e32 v17, v11, v23
	v_add_f32_e32 v18, v8, v20
	v_add_f32_e32 v19, v9, v21
	v_lshl_add_u64 v[20:21], s[16:17], 0, v[90:91]
	v_lshlrev_b32_e32 v30, 16, v67
	v_and_b32_e32 v31, 0xffff0000, v67
	v_cvt_pk_bf16_f32 v8, v12, v13
	v_cvt_pk_bf16_f32 v9, v14, v15
	v_cvt_pk_bf16_f32 v10, v18, v19
	v_cvt_pk_bf16_f32 v11, v16, v17
	v_lshl_add_u64 v[20:21], v[20:21], 0, v[162:163]
	v_add_f32_e32 v4, v4, v24
	v_add_f32_e32 v5, v5, v25
	v_lshlrev_b32_e32 v26, 16, v65
	v_and_b32_e32 v27, 0xffff0000, v65
	global_store_dwordx4 v[20:21], v[8:11], off sc1
	v_add_f32_e32 v6, v6, v26
	v_add_f32_e32 v7, v7, v27
	v_lshlrev_b32_e32 v28, 16, v66
	v_mul_f32_e32 v10, v13, v13
	v_add_f32_e32 v8, v2, v30
	v_add_f32_e32 v9, v3, v31
	v_cvt_pk_bf16_f32 v2, v4, v5
	v_mul_f32_e32 v5, v5, v5
	v_fmac_f32_e32 v10, v12, v12
	v_fmac_f32_e32 v5, v4, v4
	v_and_b32_e32 v29, 0xffff0000, v66
	v_fmac_f32_e32 v10, v14, v14
	v_fmac_f32_e32 v5, v6, v6
	v_fmac_f32_e32 v10, v15, v15
	v_add_f32_e32 v0, v0, v28
	v_add_f32_e32 v1, v1, v29
	v_fmac_f32_e32 v5, v7, v7
	v_fmac_f32_e32 v10, v18, v18
	v_fmac_f32_e32 v5, v0, v0
	v_fmac_f32_e32 v10, v19, v19
	v_fmac_f32_e32 v5, v1, v1
	v_fmac_f32_e32 v10, v16, v16
	v_fmac_f32_e32 v5, v8, v8
	v_fmac_f32_e32 v10, v17, v17
	v_fmac_f32_e32 v5, v9, v9
	v_add_f32_e32 v10, v10, v5
	ds_bpermute_b32 v11, v183, v10
	v_cvt_pk_bf16_f32 v4, v0, v1
	v_lshl_add_u64 v[0:1], s[10:11], 0, v[90:91]
	v_cvt_pk_bf16_f32 v3, v6, v7
	v_lshl_add_u64 v[6:7], v[0:1], 0, v[162:163]
	s_waitcnt lgkmcnt(0)
	v_add_f32_e32 v0, v10, v11
	ds_bpermute_b32 v1, v184, v0
	v_add_co_u32_e32 v6, vcc, s59, v6
	v_cvt_pk_bf16_f32 v5, v8, v9
	s_nop 0
	v_addc_co_u32_e32 v7, vcc, 0, v7, vcc
	global_store_dwordx4 v[6:7], v[2:5], off offset:256 sc1
	s_and_saveexec_b64 s[26:27], s[2:3]
	s_cbranch_execz .LBB0_1168
	s_waitcnt lgkmcnt(0)
	v_add_f32_e32 v2, v0, v1
	v_lshl_add_u64 v[0:1], v[88:89], 2, s[14:15]
	global_atomic_add_f32 v[0:1], v2, off
	s_branch .LBB0_1168

; DI float bf_lo(unsigned w) { return __uint_as_float(w << 16); }
; DI float bf_hi(unsigned w) { return __uint_as_float(w & 0xffff0000u); }
; DI float rstd_of(float ssq, float inv_n) { return __builtin_amdgcn_rsqf(ssq * inv_n + 1e-6f); }
; DI void phase_final(CP& p, int wid) {
;     ...
;     for (int it = blockIdx.x; it < 1024; it += gridDim.x) {
;         const int row = it * 8 + wid; const float rs = rstd_of(SSQ(7)[row], 1.f / 2048.f);
;         const u32x4* xr = (const u32x4*)(WSB(OFF_XB) + (size_t)row * 2048); f32x4* orow = (f32x4*)(p.out + (size_t)row * 2048); const f32x4* gf = (const f32x4*)p.g_final;
; #pragma unroll
;         for (int i = 0; i < 4; ++i) { const u32x4 w = xr[i * 64 + lane]; const int c = (i * 64 + lane) * 2;
;             const f32x4 a = {bf_lo(w.x), bf_hi(w.x), bf_lo(w.y), bf_hi(w.y)}, b = {bf_lo(w.z), bf_hi(w.z), bf_lo(w.w), bf_hi(w.w)};
;             orow[c] = a * rs * gf[c]; orow[c + 1] = b * rs * gf[c + 1]; }
;     }
.LBB0_1419:
	s_ashr_i32 s1, s0, 31
	s_lshl_b64 s[2:3], s[0:1], 2
	s_add_u32 s2, s4, s2
	s_addc_u32 s3, s5, s3
	global_load_dword v32, v18, s[2:3]
	s_lshl_b64 s[2:3], s[0:1], 13
	s_add_u32 s2, s8, s2
	s_addc_u32 s3, s9, s3
	s_lshl_b64 s[12:13], s[0:1], 12
	v_lshl_add_u64 v[28:29], v[16:17], 0, s[12:13]
	global_load_dwordx4 v[20:23], v[28:29], off
	global_load_dwordx4 v[72:75], v[28:29], off offset:1024
	global_load_dwordx4 v[76:79], v[28:29], off offset:2048
	global_load_dwordx4 v[80:83], v[28:29], off offset:3072
	s_add_i32 s6, s6, s7
	s_add_i32 s0, s0, s10
	s_waitcnt vmcnt(4)
	v_fmamk_f32 v32, v32, 0x3a000000, v19
	v_rsq_f32_e32 v32, v32
	v_lshl_add_u64 v[30:31], v[0:1], 4, s[2:3]
	s_waitcnt vmcnt(3)
	v_lshlrev_b32_e32 v34, 16, v20
	v_and_b32_e32 v35, 0xffff0000, v20
	v_lshlrev_b32_e32 v36, 16, v21
	v_and_b32_e32 v37, 0xffff0000, v21
	v_mul_f32_e32 v34, v32, v34
	v_mul_f32_e32 v35, v32, v35
	v_mul_f32_e32 v36, v32, v36
	v_mul_f32_e32 v37, v32, v37
	v_mul_f32_e32 v84, v40, v34
	v_mul_f32_e32 v85, v41, v35
	v_mul_f32_e32 v86, v42, v36
	v_mul_f32_e32 v87, v43, v37
	global_store_dwordx4 v[30:31], v[84:87], off
	v_lshlrev_b32_e32 v34, 16, v22
	v_and_b32_e32 v35, 0xffff0000, v22
	v_lshlrev_b32_e32 v36, 16, v23
	v_and_b32_e32 v37, 0xffff0000, v23
	v_mul_f32_e32 v34, v32, v34
	v_mul_f32_e32 v35, v32, v35
	v_mul_f32_e32 v36, v32, v36
	v_mul_f32_e32 v37, v32, v37
	v_mul_f32_e32 v88, v44, v34
	v_mul_f32_e32 v89, v45, v35
	v_mul_f32_e32 v90, v46, v36
	v_mul_f32_e32 v91, v47, v37
	global_store_dwordx4 v[30:31], v[88:91], off offset:16
	v_lshl_add_u64 v[30:31], v[4:5], 4, s[2:3]
	s_waitcnt vmcnt(4)
	v_lshlrev_b32_e32 v34, 16, v72
	v_and_b32_e32 v35, 0xffff0000, v72
	v_lshlrev_b32_e32 v36, 16, v73
	v_and_b32_e32 v37, 0xffff0000, v73
	v_mul_f32_e32 v34, v32, v34
	v_mul_f32_e32 v35, v32, v35
	v_mul_f32_e32 v36, v32, v36
	v_mul_f32_e32 v37, v32, v37
	v_mul_f32_e32 v84, v48, v34
	v_mul_f32_e32 v85, v49, v35
	v_mul_f32_e32 v86, v50, v36
	v_mul_f32_e32 v87, v51, v37
	global_store_dwordx4 v[30:31], v[84:87], off
	v_lshlrev_b32_e32 v34, 16, v74
	v_and_b32_e32 v35, 0xffff0000, v74
	v_lshlrev_b32_e32 v36, 16, v75
	v_and_b32_e32 v37, 0xffff0000, v75
	v_mul_f32_e32 v34, v32, v34
	v_mul_f32_e32 v35, v32, v35
	v_mul_f32_e32 v36, v32, v36
	v_mul_f32_e32 v37, v32, v37
	v_mul_f32_e32 v88, v52, v34
	v_mul_f32_e32 v89, v53, v35
	v_mul_f32_e32 v90, v54, v36
	v_mul_f32_e32 v91, v55, v37
	global_store_dwordx4 v[30:31], v[88:91], off offset:16
	v_lshl_add_u64 v[30:31], v[8:9], 4, s[2:3]
	s_waitcnt vmcnt(5)
	v_lshlrev_b32_e32 v34, 16, v76
	v_and_b32_e32 v35, 0xffff0000, v76
	v_lshlrev_b32_e32 v36, 16, v77
	v_and_b32_e32 v37, 0xffff0000, v77
	v_mul_f32_e32 v34, v32, v34
	v_mul_f32_e32 v35, v32, v35
	v_mul_f32_e32 v36, v32, v36
	v_mul_f32_e32 v37, v32, v37
	v_mul_f32_e32 v84, v56, v34
	v_mul_f32_e32 v85, v57, v35
	v_mul_f32_e32 v86, v58, v36
	v_mul_f32_e32 v87, v59, v37
	global_store_dwordx4 v[30:31], v[84:87], off
	v_lshlrev_b32_e32 v34, 16, v78
	v_and_b32_e32 v35, 0xffff0000, v78
	v_lshlrev_b32_e32 v36, 16, v79
	v_and_b32_e32 v37, 0xffff0000, v79
	v_mul_f32_e32 v34, v32, v34
	v_mul_f32_e32 v35, v32, v35
	v_mul_f32_e32 v36, v32, v36
	v_mul_f32_e32 v37, v32, v37
	v_mul_f32_e32 v88, v60, v34
	v_mul_f32_e32 v89, v61, v35
	v_mul_f32_e32 v90, v62, v36
	v_mul_f32_e32 v91, v63, v37
	global_store_dwordx4 v[30:31], v[88:91], off offset:16
	v_lshl_add_u64 v[30:31], v[12:13], 4, s[2:3]
	s_waitcnt vmcnt(6)
	v_lshlrev_b32_e32 v34, 16, v80
	v_and_b32_e32 v35, 0xffff0000, v80
	v_lshlrev_b32_e32 v36, 16, v81
	v_and_b32_e32 v37, 0xffff0000, v81
	v_mul_f32_e32 v34, v32, v34
	v_mul_f32_e32 v35, v32, v35
	v_mul_f32_e32 v36, v32, v36
	v_mul_f32_e32 v37, v32, v37
	v_mul_f32_e32 v84, v64, v34
	v_mul_f32_e32 v85, v65, v35
	v_mul_f32_e32 v86, v66, v36
	v_mul_f32_e32 v87, v67, v37
	global_store_dwordx4 v[30:31], v[84:87], off
	v_lshlrev_b32_e32 v34, 16, v82
	v_and_b32_e32 v35, 0xffff0000, v82
	v_lshlrev_b32_e32 v36, 16, v83
	v_and_b32_e32 v37, 0xffff0000, v83
	v_mul_f32_e32 v34, v32, v34
	v_mul_f32_e32 v35, v32, v35
	v_mul_f32_e32 v36, v32, v36
	v_mul_f32_e32 v37, v32, v37
	v_mul_f32_e32 v88, v68, v34
	v_mul_f32_e32 v89, v69, v35
	v_mul_f32_e32 v90, v70, v36
	v_mul_f32_e32 v91, v71, v37
	global_store_dwordx4 v[30:31], v[88:91], off offset:16
	s_cmpk_lt_i32 s6, 0x400
	s_cbranch_scc1 .LBB0_1419
